# dil loop two-stage software pipeline: next group's 4 dependent QK MFMAs interleaved into this group's exp block, second score register set, K/V register sets cut from 3 to 2
# speedup vs baseline: 1.0035x; 1.0035x over previous
; #define LAS __attribute__((address_space(3)))
; #define GAS __attribute__((address_space(1)))
; __device__ __forceinline__ void dil_unit(LAS unsigned char* lds, bf16_t* proj, int seq, int hd, int T0, int rho) {
;     int tid_ = threadIdx.x; asm volatile("" : "+v"(tid_));
;     const int tid = tid_, lane = tid & 63, r32 = lane & 31, hi = lane >> 5, wid = __builtin_amdgcn_readfirstlane(tid >> 6);
;     bf16_t* base = proj + (size_t)seq * SEQ * NIN;
;     LAS unsigned char* wbuf = lds + wid * 4096;
;     const LAS unsigned char* vp = wbuf + ((lane >> 4) & 1) * 32 + (lane & 3) * 8 + (4 * hi + ((lane & 15) >> 2)) * 64;
;     const int P0 = T0 + rho;
;     bf16x8 qr[4];
; #pragma unroll
;     for (int ks = 0; ks < 4; ++ks) qr[ks] = *(const GAS bf16x8*)(base + (size_t)(P0 + 16 * r32) * NIN + PC_LQ + hd * 64 + 16 * ks + 8 * hi);
;     f32x16 o0 = {}, o1 = {}; float l = 0.f;
;     const bool bound = (T0 < 1024) || (T0 >= 15360);
.LBB0_554:
	s_lshr_b32 s82, s33, 8
	s_mul_i32 s82, s82, 13
	s_add_i32 s82, s82, s33
	s_ashr_i32 s2, s33, 6
	s_mul_hi_i32 s7, s2, 0x2aaaaaab
	s_lshl_b32 s3, s82, 8
	s_lshr_b32 s8, s7, 31
	s_and_b32 s6, s3, 0x3e00
	s_lshl_b32 s3, s82, 3
	s_add_i32 s7, s7, s8
	s_and_b32 s3, s3, 8
	s_mul_i32 s8, s7, 6
	s_add_i32 s3, s3, s64
	s_sub_i32 s8, s2, s8
	s_mul_hi_i32 s2, s7, 0x6000000
	s_mul_i32 s7, s7, 0x6000000
	v_mov_b32_e32 v2, v154
	s_add_u32 s56, s48, s7
	s_addc_u32 s57, s49, s2
	v_and_b32_e32 v105, 31, v2
	s_add_i32 s76, s3, s6
	v_lshl_add_u32 v3, v105, 4, s76
	v_mov_b64_e32 v[0:1], s[56:57]
	s_lshl_b32 s58, s8, 6
	v_bfe_u32 v106, v2, 5, 1
	v_mad_u64_u32 v[0:1], s[2:3], v3, s65, v[0:1]
	s_ashr_i32 s59, s58, 31
	v_lshl_add_u64 v[0:1], s[58:59], 1, v[0:1]
	v_lshlrev_b32_e32 v80, 4, v106
	v_lshl_add_u64 v[0:1], v[0:1], 0, v[80:81]
	global_load_dwordx4 v[48:51], v[0:1], off offset:1280
	global_load_dwordx4 v[52:55], v[0:1], off offset:1312
	global_load_dwordx4 v[56:59], v[0:1], off offset:1344
	global_load_dwordx4 v[60:63], v[0:1], off offset:1376
	v_readfirstlane_b32 s2, v2
	s_lshl_b32 s2, s2, 6
	s_and_b32 s2, s2, 0xfffff000
	v_lshlrev_b32_e32 v0, 1, v2
	v_lshlrev_b32_e32 v104, 3, v2
	v_lshlrev_b32_e32 v107, 2, v106
	v_lshrrev_b32_e32 v1, 2, v2
	v_and_b32_e32 v103, 63, v2
	v_and_b32_e32 v0, 32, v0
	v_and_b32_e32 v98, 24, v104
	v_and_or_b32 v1, v1, 3, v107
	s_add_i32 s77, s2, 0
	v_lshlrev_b32_e32 v108, 6, v1
	v_lshlrev_b32_e32 v1, 3, v106
	v_add3_u32 v109, s77, v0, v98
	s_addk_i32 s6, 0xc400
	v_lshrrev_b32_e32 v110, 2, v103
	v_lshlrev_b32_e32 v0, 4, v103
	s_mov_b64 s[2:3], -1
	s_cmp_gt_u32 s6, 0xffffc7ff
	v_lshlrev_b32_e32 v100, 1, v98
	s_mul_i32 s6, s8, 0x1c00
	v_lshlrev_b32_e32 v82, 1, v1
	v_or_b32_e32 v111, 16, v110
	v_add_u32_e32 v112, s77, v0
	s_cbranch_scc0 .LBB0_558
	s_movk_i32 s100, 0x1800
	s_add_i32 s101, s6, 0x15c00
	s_lshl_b32 s90, s58, 1
	s_add_u32 s82, s56, s90
	s_addc_u32 s83, s57, 0
	s_add_u32 s82, s82, 0x1200
	s_addc_u32 s83, s83, 0
	s_sub_i32 s90, s76, 64
	s_mul_i32 s90, s90, 0x1800
	s_add_u32 s84, s82, s90
	s_addc_u32 s85, s83, 0
	s_sub_i32 s90, s76, 256
	s_mul_i32 s90, s90, 0x1800
	s_add_u32 s86, s82, s90
	s_addc_u32 s87, s83, 0
	s_sub_i32 s90, s76, 1024
	s_mul_i32 s90, s90, 0x1800
	s_add_u32 s88, s82, s90
	s_addc_u32 s89, s83, 0
	v_lshlrev_b32_e32 v153, 1, v98
	v_mad_u32_u24 v80, v105, s100, v82
	v_mad_u32_u24 v100, v110, s100, v153
	v_add_u32_e32 v149, 0x18000, v100
	v_lshlrev_b32_e32 v83, 2, v105
	v_mad_u32_u24 v83, v83, s100, v82
	v_lshlrev_b32_e32 v101, 2, v110
	v_mad_u32_u24 v101, v101, s100, v153
	v_add_u32_e32 v150, 0x60000, v101
	v_lshlrev_b32_e32 v99, 4, v105
	v_mad_u32_u24 v99, v99, s100, v82
	v_lshlrev_b32_e32 v148, 4, v110
	v_mad_u32_u24 v148, v148, s100, v153
	v_add_u32_e32 v151, 0x180000, v148
	v_lshrrev_b32_e32 v249, 3, v103
	v_and_b32_e32 v250, 7, v103
	v_lshlrev_b32_e32 v250, 4, v250
	v_add_u32_e32 v235, 0, v249
	v_mad_u32_u24 v235, v235, s100, v250
	v_add_u32_e32 v236, 8, v249
	v_mad_u32_u24 v236, v236, s100, v250
	v_add_u32_e32 v237, 16, v249
	v_mad_u32_u24 v237, v237, s100, v250
	v_add_u32_e32 v238, 24, v249
	v_mad_u32_u24 v238, v238, s100, v250
	v_add_u32_e32 v239, 0, v249
	v_lshlrev_b32_e32 v239, 2, v239
	v_mad_u32_u24 v239, v239, s100, v250
	v_add_u32_e32 v240, 8, v249
	v_lshlrev_b32_e32 v240, 2, v240
	v_mad_u32_u24 v240, v240, s100, v250
	v_add_u32_e32 v241, 16, v249
	v_lshlrev_b32_e32 v241, 2, v241
	v_mad_u32_u24 v241, v241, s100, v250
	v_add_u32_e32 v242, 24, v249
	v_lshlrev_b32_e32 v242, 2, v242
	v_mad_u32_u24 v242, v242, s100, v250
	v_add_u32_e32 v243, 0, v249
	v_lshlrev_b32_e32 v243, 4, v243
	v_mad_u32_u24 v243, v243, s100, v250
	v_add_u32_e32 v244, 8, v249
	v_lshlrev_b32_e32 v244, 4, v244
	v_mad_u32_u24 v244, v244, s100, v250
	v_add_u32_e32 v245, 16, v249
	v_lshlrev_b32_e32 v245, 4, v245
	v_mad_u32_u24 v245, v245, s100, v250
	v_add_u32_e32 v246, 24, v249
	v_lshlrev_b32_e32 v246, 4, v246
	v_mad_u32_u24 v246, v246, s100, v250
	v_and_b32_e32 v247, 7, v249
	v_lshlrev_b32_e32 v247, 4, v247
	v_xor_b32_e32 v247, v247, v112
	v_and_b32_e32 v153, 7, v105
	v_or_b32_e32 v248, 0, v106
	v_xor_b32_e32 v248, v248, v153
	v_lshlrev_b32_e32 v248, 4, v248
	v_lshl_add_u32 v248, v105, 7, v248
	v_add_u32_e32 v248, s77, v248
	v_or_b32_e32 v249, 2, v106
	v_xor_b32_e32 v249, v249, v153
	v_lshlrev_b32_e32 v249, 4, v249
	v_lshl_add_u32 v249, v105, 7, v249
	v_add_u32_e32 v249, s77, v249
	v_or_b32_e32 v250, 4, v106
	v_xor_b32_e32 v250, v250, v153
	v_lshlrev_b32_e32 v250, 4, v250
	v_lshl_add_u32 v250, v105, 7, v250
	v_add_u32_e32 v250, s77, v250
	v_or_b32_e32 v251, 6, v106
	v_xor_b32_e32 v251, v251, v153
	v_lshlrev_b32_e32 v251, 4, v251
	v_lshl_add_u32 v251, v105, 7, v251
	v_add_u32_e32 v251, s77, v251
	v_lshlrev_b32_e32 v153, 1, v98
	v_mul_u32_u24_e32 v228, 17, v105
	v_sub_u32_e32 v228, v107, v228
	s_mul_i32 s90, s58, 153
	s_lshr_b32 s90, s90, 1
	s_add_i32 s90, s90, 34876
	v_lshl_add_u32 v228, v228, 2, s90
	v_lshlrev_b32_e32 v229, 2, v105
	v_sub_u32_e32 v229, v107, v229
	s_add_i32 s90, s101, 5104
	v_lshl_add_u32 v229, v229, 2, s90
	v_sub_u32_e32 v230, v107, v105
	s_add_i32 s90, s101, 6364
	v_lshl_add_u32 v230, v230, 2, s90
	v_add_u32_e32 v231, v109, v108
	v_mov_b64_e32 v[232:233], 0
	v_mov_b64_e32 v[0:1], 0
	v_mov_b64_e32 v[2:3], 0
	v_mov_b64_e32 v[4:5], 0
	v_mov_b64_e32 v[6:7], 0
	v_mov_b64_e32 v[8:9], 0
	v_mov_b64_e32 v[10:11], 0
	v_mov_b64_e32 v[12:13], 0
	v_mov_b64_e32 v[14:15], 0
	v_mov_b64_e32 v[16:17], 0
	v_mov_b64_e32 v[18:19], 0
	v_mov_b64_e32 v[20:21], 0
	v_mov_b64_e32 v[22:23], 0
	v_mov_b64_e32 v[24:25], 0
	v_mov_b64_e32 v[26:27], 0
	v_mov_b64_e32 v[28:29], 0
	v_mov_b64_e32 v[30:31], 0
	global_load_dwordx4 v[116:119], v235, s[84:85]
	global_load_dwordx4 v[120:123], v236, s[84:85]
	global_load_dwordx4 v[124:127], v237, s[84:85]
	global_load_dwordx4 v[128:131], v238, s[84:85]
	global_load_dwordx4 v[132:135], v100, s[84:85] offset:768
	global_load_dwordx4 v[136:139], v149, s[84:85] offset:768
	global_load_dwordx4 v[140:143], v100, s[84:85] offset:832
	global_load_dwordx4 v[144:147], v149, s[84:85] offset:832
	s_add_u32 s84, s84, 0x30000
	s_addc_u32 s85, s85, 0
	global_load_dwordx4 v[156:159], v235, s[84:85]
	global_load_dwordx4 v[160:163], v236, s[84:85]
	global_load_dwordx4 v[164:167], v237, s[84:85]
	global_load_dwordx4 v[168:171], v238, s[84:85]
	global_load_dwordx4 v[172:175], v100, s[84:85] offset:768
	global_load_dwordx4 v[176:179], v149, s[84:85] offset:768
	global_load_dwordx4 v[180:183], v100, s[84:85] offset:832
	global_load_dwordx4 v[184:187], v149, s[84:85] offset:832
	s_add_u32 s84, s84, 0x30000
	s_addc_u32 s85, s85, 0
	v_mov_b32_e32 v115, v228
	ds_read2_b32 v[32:33], v115 offset0:0 offset1:1
	ds_read2_b32 v[34:35], v115 offset0:2 offset1:3
	ds_read2_b32 v[36:37], v115 offset0:8 offset1:9
	ds_read2_b32 v[38:39], v115 offset0:10 offset1:11
	ds_read2_b32 v[40:41], v115 offset0:17 offset1:18
	ds_read2_b32 v[42:43], v115 offset0:19 offset1:20
	ds_read2_b32 v[44:45], v115 offset0:25 offset1:26
	ds_read2_b32 v[46:47], v115 offset0:27 offset1:28
	s_waitcnt vmcnt(8)
	ds_write_b128 v247, v[116:119]
	ds_write_b128 v247, v[120:123] offset:1024
	ds_write_b128 v247, v[124:127] offset:2048
	ds_write_b128 v247, v[128:131] offset:3072
	ds_read_b128 v[116:119], v248
	ds_read_b128 v[120:123], v249
	ds_read_b128 v[124:127], v250
	ds_read_b128 v[128:131], v251
	ds_write_b128 v112, v[132:135]
	ds_write_b128 v112, v[136:139] offset:1024
	ds_write_b128 v112, v[140:143] offset:2048
	ds_write_b128 v112, v[144:147] offset:3072
	s_waitcnt lgkmcnt(4)
	v_mfma_f32_32x32x16_bf16 v[32:47], v[116:119], v[48:51], v[32:47]
	v_mfma_f32_32x32x16_bf16 v[32:47], v[120:123], v[52:55], v[32:47]
	v_mfma_f32_32x32x16_bf16 v[32:47], v[124:127], v[56:59], v[32:47]
	v_mfma_f32_32x32x16_bf16 v[32:47], v[128:131], v[60:63], v[32:47]
	ds_read2_b32 v[188:189], v115 offset0:34 offset1:35
	ds_read2_b32 v[190:191], v115 offset0:36 offset1:37
	ds_read2_b32 v[192:193], v115 offset0:42 offset1:43
	ds_read2_b32 v[194:195], v115 offset0:44 offset1:45
	ds_read2_b32 v[196:197], v115 offset0:51 offset1:52
	ds_read2_b32 v[198:199], v115 offset0:53 offset1:54
	ds_read2_b32 v[200:201], v115 offset0:59 offset1:60
	ds_read2_b32 v[202:203], v115 offset0:61 offset1:62
	global_load_dwordx4 v[116:119], v235, s[84:85]
	global_load_dwordx4 v[120:123], v236, s[84:85]
	global_load_dwordx4 v[124:127], v237, s[84:85]
	global_load_dwordx4 v[128:131], v238, s[84:85]
	global_load_dwordx4 v[132:135], v100, s[84:85] offset:768
	global_load_dwordx4 v[136:139], v149, s[84:85] offset:768
	global_load_dwordx4 v[140:143], v100, s[84:85] offset:832
	global_load_dwordx4 v[144:147], v149, s[84:85] offset:832
	s_add_u32 s84, s84, 0x30000
	s_addc_u32 s85, s85, 0
	ds_read_b64_tr_b16 v[72:73], v231
	ds_read_b64_tr_b16 v[74:75], v231 offset:512
	ds_read_b64_tr_b16 v[76:77], v231 offset:2048
	ds_read_b64_tr_b16 v[78:79], v231 offset:2560
	ds_read_b64_tr_b16 v[220:221], v231 offset:1024
	ds_read_b64_tr_b16 v[222:223], v231 offset:1536
	ds_read_b64_tr_b16 v[224:225], v231 offset:3072
	ds_read_b64_tr_b16 v[226:227], v231 offset:3584
	s_waitcnt vmcnt(8)
	ds_write_b128 v247, v[156:159]
	ds_write_b128 v247, v[160:163] offset:1024
	ds_write_b128 v247, v[164:167] offset:2048
	ds_write_b128 v247, v[168:171] offset:3072
	ds_read_b128 v[156:159], v248
	ds_read_b128 v[160:163], v249
	ds_read_b128 v[164:167], v250
	ds_read_b128 v[168:171], v251
	ds_write_b128 v112, v[172:175]
	ds_write_b128 v112, v[176:179] offset:1024
	ds_write_b128 v112, v[180:183] offset:2048
	ds_write_b128 v112, v[184:187] offset:3072
	s_waitcnt lgkmcnt(4)
	v_mfma_f32_32x32x16_bf16 v[188:203], v[156:159], v[48:51], v[188:203]
	v_exp_f32_e32 v32, v32
	v_exp_f32_e32 v33, v33
	v_exp_f32_e32 v34, v34
	v_exp_f32_e32 v35, v35
	v_mfma_f32_32x32x16_bf16 v[188:203], v[160:163], v[52:55], v[188:203]
	v_exp_f32_e32 v36, v36
	v_exp_f32_e32 v37, v37
	v_exp_f32_e32 v38, v38
	v_exp_f32_e32 v39, v39
	v_mfma_f32_32x32x16_bf16 v[188:203], v[164:167], v[56:59], v[188:203]
	v_exp_f32_e32 v40, v40
	v_exp_f32_e32 v41, v41
	v_exp_f32_e32 v42, v42
	v_exp_f32_e32 v43, v43
	v_mfma_f32_32x32x16_bf16 v[188:203], v[168:171], v[60:63], v[188:203]
	v_exp_f32_e32 v44, v44
	v_exp_f32_e32 v45, v45
	v_exp_f32_e32 v46, v46
	v_exp_f32_e32 v47, v47
	v_cvt_pk_bf16_f32 v64, v32, v33
	v_cvt_pk_bf16_f32 v65, v34, v35
	v_cvt_pk_bf16_f32 v66, v36, v37
	v_cvt_pk_bf16_f32 v67, v38, v39
	v_cvt_pk_bf16_f32 v68, v40, v41
	v_cvt_pk_bf16_f32 v69, v42, v43
	v_cvt_pk_bf16_f32 v70, v44, v45
	v_cvt_pk_bf16_f32 v71, v46, v47
	v_pk_add_f32 v[232:233], v[232:233], v[32:33]
	v_pk_add_f32 v[232:233], v[232:233], v[34:35]
	v_pk_add_f32 v[232:233], v[232:233], v[36:37]
	v_pk_add_f32 v[232:233], v[232:233], v[38:39]
	v_pk_add_f32 v[232:233], v[232:233], v[40:41]
	v_pk_add_f32 v[232:233], v[232:233], v[42:43]
	v_pk_add_f32 v[232:233], v[232:233], v[44:45]
	v_pk_add_f32 v[232:233], v[232:233], v[46:47]
	ds_read2_b32 v[32:33], v115 offset0:68 offset1:69
	ds_read2_b32 v[34:35], v115 offset0:70 offset1:71
	ds_read2_b32 v[36:37], v115 offset0:76 offset1:77
	ds_read2_b32 v[38:39], v115 offset0:78 offset1:79
	ds_read2_b32 v[40:41], v115 offset0:85 offset1:86
	ds_read2_b32 v[42:43], v115 offset0:87 offset1:88
	ds_read2_b32 v[44:45], v115 offset0:93 offset1:94
	ds_read2_b32 v[46:47], v115 offset0:95 offset1:96
	v_mfma_f32_32x32x16_bf16 v[0:15], v[64:67], v[72:75], v[0:15]
	v_mfma_f32_32x32x16_bf16 v[16:31], v[64:67], v[76:79], v[16:31]
	v_mfma_f32_32x32x16_bf16 v[0:15], v[68:71], v[220:223], v[0:15]
	v_mfma_f32_32x32x16_bf16 v[16:31], v[68:71], v[224:227], v[16:31]
	global_load_dwordx4 v[156:159], v235, s[84:85]
	global_load_dwordx4 v[160:163], v236, s[84:85]
	global_load_dwordx4 v[164:167], v237, s[84:85]
	global_load_dwordx4 v[168:171], v238, s[84:85]
	global_load_dwordx4 v[172:175], v100, s[84:85] offset:768
	global_load_dwordx4 v[176:179], v149, s[84:85] offset:768
	global_load_dwordx4 v[180:183], v100, s[84:85] offset:832
	global_load_dwordx4 v[184:187], v149, s[84:85] offset:832
	s_add_u32 s84, s84, 0x30000
	s_addc_u32 s85, s85, 0
	ds_read_b64_tr_b16 v[72:73], v231
	ds_read_b64_tr_b16 v[74:75], v231 offset:512
	ds_read_b64_tr_b16 v[76:77], v231 offset:2048
	ds_read_b64_tr_b16 v[78:79], v231 offset:2560
	ds_read_b64_tr_b16 v[220:221], v231 offset:1024
	ds_read_b64_tr_b16 v[222:223], v231 offset:1536
	ds_read_b64_tr_b16 v[224:225], v231 offset:3072
	ds_read_b64_tr_b16 v[226:227], v231 offset:3584
	s_waitcnt vmcnt(8)
	ds_write_b128 v247, v[116:119]
	ds_write_b128 v247, v[120:123] offset:1024
	ds_write_b128 v247, v[124:127] offset:2048
	ds_write_b128 v247, v[128:131] offset:3072
	ds_read_b128 v[116:119], v248
	ds_read_b128 v[120:123], v249
	ds_read_b128 v[124:127], v250
	ds_read_b128 v[128:131], v251
	ds_write_b128 v112, v[132:135]
	ds_write_b128 v112, v[136:139] offset:1024
	ds_write_b128 v112, v[140:143] offset:2048
	ds_write_b128 v112, v[144:147] offset:3072
	s_waitcnt lgkmcnt(4)
	v_mfma_f32_32x32x16_bf16 v[32:47], v[116:119], v[48:51], v[32:47]
	v_exp_f32_e32 v188, v188
	v_exp_f32_e32 v189, v189
	v_exp_f32_e32 v190, v190
	v_exp_f32_e32 v191, v191
	v_mfma_f32_32x32x16_bf16 v[32:47], v[120:123], v[52:55], v[32:47]
	v_exp_f32_e32 v192, v192
	v_exp_f32_e32 v193, v193
	v_exp_f32_e32 v194, v194
	v_exp_f32_e32 v195, v195
	v_mfma_f32_32x32x16_bf16 v[32:47], v[124:127], v[56:59], v[32:47]
	v_exp_f32_e32 v196, v196
	v_exp_f32_e32 v197, v197
	v_exp_f32_e32 v198, v198
	v_exp_f32_e32 v199, v199
	v_mfma_f32_32x32x16_bf16 v[32:47], v[128:131], v[60:63], v[32:47]
	v_exp_f32_e32 v200, v200
	v_exp_f32_e32 v201, v201
	v_exp_f32_e32 v202, v202
	v_exp_f32_e32 v203, v203
	v_cvt_pk_bf16_f32 v64, v188, v189
	v_cvt_pk_bf16_f32 v65, v190, v191
	v_cvt_pk_bf16_f32 v66, v192, v193
	v_cvt_pk_bf16_f32 v67, v194, v195
	v_cvt_pk_bf16_f32 v68, v196, v197
	v_cvt_pk_bf16_f32 v69, v198, v199
	v_cvt_pk_bf16_f32 v70, v200, v201
	v_cvt_pk_bf16_f32 v71, v202, v203
	v_pk_add_f32 v[232:233], v[232:233], v[188:189]
	v_pk_add_f32 v[232:233], v[232:233], v[190:191]
	v_pk_add_f32 v[232:233], v[232:233], v[192:193]
	v_pk_add_f32 v[232:233], v[232:233], v[194:195]
	v_pk_add_f32 v[232:233], v[232:233], v[196:197]
	v_pk_add_f32 v[232:233], v[232:233], v[198:199]
	v_pk_add_f32 v[232:233], v[232:233], v[200:201]
	v_pk_add_f32 v[232:233], v[232:233], v[202:203]
	ds_read2_b32 v[188:189], v115 offset0:102 offset1:103
	ds_read2_b32 v[190:191], v115 offset0:104 offset1:105
	ds_read2_b32 v[192:193], v115 offset0:110 offset1:111
	ds_read2_b32 v[194:195], v115 offset0:112 offset1:113
	ds_read2_b32 v[196:197], v115 offset0:119 offset1:120
	ds_read2_b32 v[198:199], v115 offset0:121 offset1:122
	ds_read2_b32 v[200:201], v115 offset0:127 offset1:128
	ds_read2_b32 v[202:203], v115 offset0:129 offset1:130
	v_mfma_f32_32x32x16_bf16 v[0:15], v[64:67], v[72:75], v[0:15]
	v_mfma_f32_32x32x16_bf16 v[16:31], v[64:67], v[76:79], v[16:31]
	v_mfma_f32_32x32x16_bf16 v[0:15], v[68:71], v[220:223], v[0:15]
	v_mfma_f32_32x32x16_bf16 v[16:31], v[68:71], v[224:227], v[16:31]
	global_load_dwordx4 v[116:119], v235, s[84:85]
	global_load_dwordx4 v[120:123], v236, s[84:85]
	global_load_dwordx4 v[124:127], v237, s[84:85]
	global_load_dwordx4 v[128:131], v238, s[84:85]
	global_load_dwordx4 v[132:135], v100, s[84:85] offset:768
	global_load_dwordx4 v[136:139], v149, s[84:85] offset:768
	global_load_dwordx4 v[140:143], v100, s[84:85] offset:832
	global_load_dwordx4 v[144:147], v149, s[84:85] offset:832
	s_add_u32 s84, s84, 0x30000
	s_addc_u32 s85, s85, 0
	ds_read_b64_tr_b16 v[72:73], v231
	ds_read_b64_tr_b16 v[74:75], v231 offset:512
	ds_read_b64_tr_b16 v[76:77], v231 offset:2048
	ds_read_b64_tr_b16 v[78:79], v231 offset:2560
	ds_read_b64_tr_b16 v[220:221], v231 offset:1024
	ds_read_b64_tr_b16 v[222:223], v231 offset:1536
	ds_read_b64_tr_b16 v[224:225], v231 offset:3072
	ds_read_b64_tr_b16 v[226:227], v231 offset:3584
	s_waitcnt vmcnt(8)
	ds_write_b128 v247, v[156:159]
	ds_write_b128 v247, v[160:163] offset:1024
	ds_write_b128 v247, v[164:167] offset:2048
	ds_write_b128 v247, v[168:171] offset:3072
	ds_read_b128 v[156:159], v248
	ds_read_b128 v[160:163], v249
	ds_read_b128 v[164:167], v250
	ds_read_b128 v[168:171], v251
	ds_write_b128 v112, v[172:175]
	ds_write_b128 v112, v[176:179] offset:1024
	ds_write_b128 v112, v[180:183] offset:2048
	ds_write_b128 v112, v[184:187] offset:3072
	s_waitcnt lgkmcnt(4)
	v_mfma_f32_32x32x16_bf16 v[188:203], v[156:159], v[48:51], v[188:203]
	v_exp_f32_e32 v32, v32
	v_exp_f32_e32 v33, v33
	v_exp_f32_e32 v34, v34
	v_exp_f32_e32 v35, v35
	v_mfma_f32_32x32x16_bf16 v[188:203], v[160:163], v[52:55], v[188:203]
	v_exp_f32_e32 v36, v36
	v_exp_f32_e32 v37, v37
	v_exp_f32_e32 v38, v38
	v_exp_f32_e32 v39, v39
	v_mfma_f32_32x32x16_bf16 v[188:203], v[164:167], v[56:59], v[188:203]
	v_exp_f32_e32 v40, v40
	v_exp_f32_e32 v41, v41
	v_exp_f32_e32 v42, v42
	v_exp_f32_e32 v43, v43
	v_mfma_f32_32x32x16_bf16 v[188:203], v[168:171], v[60:63], v[188:203]
	v_exp_f32_e32 v44, v44
	v_exp_f32_e32 v45, v45
	v_exp_f32_e32 v46, v46
	v_exp_f32_e32 v47, v47
	v_cvt_pk_bf16_f32 v64, v32, v33
	v_cvt_pk_bf16_f32 v65, v34, v35
	v_cvt_pk_bf16_f32 v66, v36, v37
	v_cvt_pk_bf16_f32 v67, v38, v39
	v_cvt_pk_bf16_f32 v68, v40, v41
	v_cvt_pk_bf16_f32 v69, v42, v43
	v_cvt_pk_bf16_f32 v70, v44, v45
	v_cvt_pk_bf16_f32 v71, v46, v47
	v_pk_add_f32 v[232:233], v[232:233], v[32:33]
	v_pk_add_f32 v[232:233], v[232:233], v[34:35]
	v_pk_add_f32 v[232:233], v[232:233], v[36:37]
	v_pk_add_f32 v[232:233], v[232:233], v[38:39]
	v_pk_add_f32 v[232:233], v[232:233], v[40:41]
	v_pk_add_f32 v[232:233], v[232:233], v[42:43]
	v_pk_add_f32 v[232:233], v[232:233], v[44:45]
	v_pk_add_f32 v[232:233], v[232:233], v[46:47]
	ds_read2_b32 v[32:33], v115 offset0:136 offset1:137
	ds_read2_b32 v[34:35], v115 offset0:138 offset1:139
	ds_read2_b32 v[36:37], v115 offset0:144 offset1:145
	ds_read2_b32 v[38:39], v115 offset0:146 offset1:147
	ds_read2_b32 v[40:41], v115 offset0:153 offset1:154
	ds_read2_b32 v[42:43], v115 offset0:155 offset1:156
	ds_read2_b32 v[44:45], v115 offset0:161 offset1:162
	ds_read2_b32 v[46:47], v115 offset0:163 offset1:164
	v_mfma_f32_32x32x16_bf16 v[0:15], v[64:67], v[72:75], v[0:15]
	v_mfma_f32_32x32x16_bf16 v[16:31], v[64:67], v[76:79], v[16:31]
	v_mfma_f32_32x32x16_bf16 v[0:15], v[68:71], v[220:223], v[0:15]
	v_mfma_f32_32x32x16_bf16 v[16:31], v[68:71], v[224:227], v[16:31]
	global_load_dwordx4 v[156:159], v235, s[84:85]
	global_load_dwordx4 v[160:163], v236, s[84:85]
	global_load_dwordx4 v[164:167], v237, s[84:85]
	global_load_dwordx4 v[168:171], v238, s[84:85]
	global_load_dwordx4 v[172:175], v100, s[84:85] offset:768
	global_load_dwordx4 v[176:179], v149, s[84:85] offset:768
	global_load_dwordx4 v[180:183], v100, s[84:85] offset:832
	global_load_dwordx4 v[184:187], v149, s[84:85] offset:832
	s_add_u32 s84, s84, 0x30000
	s_addc_u32 s85, s85, 0
	ds_read_b64_tr_b16 v[72:73], v231
	ds_read_b64_tr_b16 v[74:75], v231 offset:512
	ds_read_b64_tr_b16 v[76:77], v231 offset:2048
	ds_read_b64_tr_b16 v[78:79], v231 offset:2560
	ds_read_b64_tr_b16 v[220:221], v231 offset:1024
	ds_read_b64_tr_b16 v[222:223], v231 offset:1536
	ds_read_b64_tr_b16 v[224:225], v231 offset:3072
	ds_read_b64_tr_b16 v[226:227], v231 offset:3584
	s_waitcnt vmcnt(8)
	ds_write_b128 v247, v[116:119]
	ds_write_b128 v247, v[120:123] offset:1024
	ds_write_b128 v247, v[124:127] offset:2048
	ds_write_b128 v247, v[128:131] offset:3072
	ds_read_b128 v[116:119], v248
	ds_read_b128 v[120:123], v249
	ds_read_b128 v[124:127], v250
	ds_read_b128 v[128:131], v251
	ds_write_b128 v112, v[132:135]
	ds_write_b128 v112, v[136:139] offset:1024
	ds_write_b128 v112, v[140:143] offset:2048
	ds_write_b128 v112, v[144:147] offset:3072
	s_waitcnt lgkmcnt(4)
	v_mfma_f32_32x32x16_bf16 v[32:47], v[116:119], v[48:51], v[32:47]
	v_exp_f32_e32 v188, v188
	v_exp_f32_e32 v189, v189
	v_exp_f32_e32 v190, v190
	v_exp_f32_e32 v191, v191
	v_mfma_f32_32x32x16_bf16 v[32:47], v[120:123], v[52:55], v[32:47]
	v_exp_f32_e32 v192, v192
	v_exp_f32_e32 v193, v193
	v_exp_f32_e32 v194, v194
	v_exp_f32_e32 v195, v195
	v_mfma_f32_32x32x16_bf16 v[32:47], v[124:127], v[56:59], v[32:47]
	v_exp_f32_e32 v196, v196
	v_exp_f32_e32 v197, v197
	v_exp_f32_e32 v198, v198
	v_exp_f32_e32 v199, v199
	v_mfma_f32_32x32x16_bf16 v[32:47], v[128:131], v[60:63], v[32:47]
	v_exp_f32_e32 v200, v200
	v_exp_f32_e32 v201, v201
	v_exp_f32_e32 v202, v202
	v_exp_f32_e32 v203, v203
	v_cvt_pk_bf16_f32 v64, v188, v189
	v_cvt_pk_bf16_f32 v65, v190, v191
	v_cvt_pk_bf16_f32 v66, v192, v193
	v_cvt_pk_bf16_f32 v67, v194, v195
	v_cvt_pk_bf16_f32 v68, v196, v197
	v_cvt_pk_bf16_f32 v69, v198, v199
	v_cvt_pk_bf16_f32 v70, v200, v201
	v_cvt_pk_bf16_f32 v71, v202, v203
	v_pk_add_f32 v[232:233], v[232:233], v[188:189]
	v_pk_add_f32 v[232:233], v[232:233], v[190:191]
	v_pk_add_f32 v[232:233], v[232:233], v[192:193]
	v_pk_add_f32 v[232:233], v[232:233], v[194:195]
	v_pk_add_f32 v[232:233], v[232:233], v[196:197]
	v_pk_add_f32 v[232:233], v[232:233], v[198:199]
	v_pk_add_f32 v[232:233], v[232:233], v[200:201]
	v_pk_add_f32 v[232:233], v[232:233], v[202:203]
	ds_read2_b32 v[188:189], v115 offset0:170 offset1:171
	ds_read2_b32 v[190:191], v115 offset0:172 offset1:173
	ds_read2_b32 v[192:193], v115 offset0:178 offset1:179
	ds_read2_b32 v[194:195], v115 offset0:180 offset1:181
	ds_read2_b32 v[196:197], v115 offset0:187 offset1:188
	ds_read2_b32 v[198:199], v115 offset0:189 offset1:190
	ds_read2_b32 v[200:201], v115 offset0:195 offset1:196
	ds_read2_b32 v[202:203], v115 offset0:197 offset1:198
	v_mfma_f32_32x32x16_bf16 v[0:15], v[64:67], v[72:75], v[0:15]
	v_mfma_f32_32x32x16_bf16 v[16:31], v[64:67], v[76:79], v[16:31]
	v_mfma_f32_32x32x16_bf16 v[0:15], v[68:71], v[220:223], v[0:15]
	v_mfma_f32_32x32x16_bf16 v[16:31], v[68:71], v[224:227], v[16:31]
	global_load_dwordx4 v[116:119], v235, s[84:85]
	global_load_dwordx4 v[120:123], v236, s[84:85]
	global_load_dwordx4 v[124:127], v237, s[84:85]
	global_load_dwordx4 v[128:131], v238, s[84:85]
	global_load_dwordx4 v[132:135], v100, s[84:85] offset:768
	global_load_dwordx4 v[136:139], v149, s[84:85] offset:768
	global_load_dwordx4 v[140:143], v100, s[84:85] offset:832
	global_load_dwordx4 v[144:147], v149, s[84:85] offset:832
	s_add_u32 s84, s84, 0x30000
	s_addc_u32 s85, s85, 0
	ds_read_b64_tr_b16 v[72:73], v231
	ds_read_b64_tr_b16 v[74:75], v231 offset:512
	ds_read_b64_tr_b16 v[76:77], v231 offset:2048
	ds_read_b64_tr_b16 v[78:79], v231 offset:2560
	ds_read_b64_tr_b16 v[220:221], v231 offset:1024
	ds_read_b64_tr_b16 v[222:223], v231 offset:1536
	ds_read_b64_tr_b16 v[224:225], v231 offset:3072
	ds_read_b64_tr_b16 v[226:227], v231 offset:3584
	s_waitcnt vmcnt(8)
	ds_write_b128 v247, v[156:159]
	ds_write_b128 v247, v[160:163] offset:1024
	ds_write_b128 v247, v[164:167] offset:2048
	ds_write_b128 v247, v[168:171] offset:3072
	ds_read_b128 v[156:159], v248
	ds_read_b128 v[160:163], v249
	ds_read_b128 v[164:167], v250
	ds_read_b128 v[168:171], v251
	ds_write_b128 v112, v[172:175]
	ds_write_b128 v112, v[176:179] offset:1024
	ds_write_b128 v112, v[180:183] offset:2048
	ds_write_b128 v112, v[184:187] offset:3072
	s_waitcnt lgkmcnt(4)
	v_mfma_f32_32x32x16_bf16 v[188:203], v[156:159], v[48:51], v[188:203]
	v_exp_f32_e32 v32, v32
	v_exp_f32_e32 v33, v33
	v_exp_f32_e32 v34, v34
	v_exp_f32_e32 v35, v35
	v_mfma_f32_32x32x16_bf16 v[188:203], v[160:163], v[52:55], v[188:203]
	v_exp_f32_e32 v36, v36
	v_exp_f32_e32 v37, v37
	v_exp_f32_e32 v38, v38
	v_exp_f32_e32 v39, v39
	v_mfma_f32_32x32x16_bf16 v[188:203], v[164:167], v[56:59], v[188:203]
	v_exp_f32_e32 v40, v40
	v_exp_f32_e32 v41, v41
	v_exp_f32_e32 v42, v42
	v_exp_f32_e32 v43, v43
	v_mfma_f32_32x32x16_bf16 v[188:203], v[168:171], v[60:63], v[188:203]
	v_exp_f32_e32 v44, v44
	v_exp_f32_e32 v45, v45
	v_exp_f32_e32 v46, v46
	v_exp_f32_e32 v47, v47
	v_cvt_pk_bf16_f32 v64, v32, v33
	v_cvt_pk_bf16_f32 v65, v34, v35
	v_cvt_pk_bf16_f32 v66, v36, v37
	v_cvt_pk_bf16_f32 v67, v38, v39
	v_cvt_pk_bf16_f32 v68, v40, v41
	v_cvt_pk_bf16_f32 v69, v42, v43
	v_cvt_pk_bf16_f32 v70, v44, v45
	v_cvt_pk_bf16_f32 v71, v46, v47
	v_pk_add_f32 v[232:233], v[232:233], v[32:33]
	v_pk_add_f32 v[232:233], v[232:233], v[34:35]
	v_pk_add_f32 v[232:233], v[232:233], v[36:37]
	v_pk_add_f32 v[232:233], v[232:233], v[38:39]
	v_pk_add_f32 v[232:233], v[232:233], v[40:41]
	v_pk_add_f32 v[232:233], v[232:233], v[42:43]
	v_pk_add_f32 v[232:233], v[232:233], v[44:45]
	v_pk_add_f32 v[232:233], v[232:233], v[46:47]
	ds_read2_b32 v[32:33], v115 offset0:204 offset1:205
	ds_read2_b32 v[34:35], v115 offset0:206 offset1:207
	ds_read2_b32 v[36:37], v115 offset0:212 offset1:213
	ds_read2_b32 v[38:39], v115 offset0:214 offset1:215
	ds_read2_b32 v[40:41], v115 offset0:221 offset1:222
	ds_read2_b32 v[42:43], v115 offset0:223 offset1:224
	ds_read2_b32 v[44:45], v115 offset0:229 offset1:230
	ds_read2_b32 v[46:47], v115 offset0:231 offset1:232
	v_mfma_f32_32x32x16_bf16 v[0:15], v[64:67], v[72:75], v[0:15]
	v_mfma_f32_32x32x16_bf16 v[16:31], v[64:67], v[76:79], v[16:31]
	v_mfma_f32_32x32x16_bf16 v[0:15], v[68:71], v[220:223], v[0:15]
	v_mfma_f32_32x32x16_bf16 v[16:31], v[68:71], v[224:227], v[16:31]
	global_load_dwordx4 v[156:159], v235, s[84:85]
	global_load_dwordx4 v[160:163], v236, s[84:85]
	global_load_dwordx4 v[164:167], v237, s[84:85]
	global_load_dwordx4 v[168:171], v238, s[84:85]
	global_load_dwordx4 v[172:175], v100, s[84:85] offset:768
	global_load_dwordx4 v[176:179], v149, s[84:85] offset:768
	global_load_dwordx4 v[180:183], v100, s[84:85] offset:832
	global_load_dwordx4 v[184:187], v149, s[84:85] offset:832
	s_add_u32 s84, s84, 0x30000
	s_addc_u32 s85, s85, 0
	ds_read_b64_tr_b16 v[72:73], v231
	ds_read_b64_tr_b16 v[74:75], v231 offset:512
	ds_read_b64_tr_b16 v[76:77], v231 offset:2048
	ds_read_b64_tr_b16 v[78:79], v231 offset:2560
	ds_read_b64_tr_b16 v[220:221], v231 offset:1024
	ds_read_b64_tr_b16 v[222:223], v231 offset:1536
	ds_read_b64_tr_b16 v[224:225], v231 offset:3072
	ds_read_b64_tr_b16 v[226:227], v231 offset:3584
	s_waitcnt vmcnt(8)
	ds_write_b128 v247, v[116:119]
	ds_write_b128 v247, v[120:123] offset:1024
	ds_write_b128 v247, v[124:127] offset:2048
	ds_write_b128 v247, v[128:131] offset:3072
	ds_read_b128 v[116:119], v248
	ds_read_b128 v[120:123], v249
	ds_read_b128 v[124:127], v250
	ds_read_b128 v[128:131], v251
	ds_write_b128 v112, v[132:135]
	ds_write_b128 v112, v[136:139] offset:1024
	ds_write_b128 v112, v[140:143] offset:2048
	ds_write_b128 v112, v[144:147] offset:3072
	s_waitcnt lgkmcnt(4)
	v_mfma_f32_32x32x16_bf16 v[32:47], v[116:119], v[48:51], v[32:47]
	v_exp_f32_e32 v188, v188
	v_exp_f32_e32 v189, v189
	v_exp_f32_e32 v190, v190
	v_exp_f32_e32 v191, v191
	v_mfma_f32_32x32x16_bf16 v[32:47], v[120:123], v[52:55], v[32:47]
	v_exp_f32_e32 v192, v192
	v_exp_f32_e32 v193, v193
	v_exp_f32_e32 v194, v194
	v_exp_f32_e32 v195, v195
	v_mfma_f32_32x32x16_bf16 v[32:47], v[124:127], v[56:59], v[32:47]
	v_exp_f32_e32 v196, v196
	v_exp_f32_e32 v197, v197
	v_exp_f32_e32 v198, v198
	v_exp_f32_e32 v199, v199
	v_mfma_f32_32x32x16_bf16 v[32:47], v[128:131], v[60:63], v[32:47]
	v_exp_f32_e32 v200, v200
	v_exp_f32_e32 v201, v201
	v_exp_f32_e32 v202, v202
	v_exp_f32_e32 v203, v203
	v_cvt_pk_bf16_f32 v64, v188, v189
	v_cvt_pk_bf16_f32 v65, v190, v191
	v_cvt_pk_bf16_f32 v66, v192, v193
	v_cvt_pk_bf16_f32 v67, v194, v195
	v_cvt_pk_bf16_f32 v68, v196, v197
	v_cvt_pk_bf16_f32 v69, v198, v199
	v_cvt_pk_bf16_f32 v70, v200, v201
	v_cvt_pk_bf16_f32 v71, v202, v203
	v_pk_add_f32 v[232:233], v[232:233], v[188:189]
	v_pk_add_f32 v[232:233], v[232:233], v[190:191]
	v_pk_add_f32 v[232:233], v[232:233], v[192:193]
	v_pk_add_f32 v[232:233], v[232:233], v[194:195]
	v_pk_add_f32 v[232:233], v[232:233], v[196:197]
	v_pk_add_f32 v[232:233], v[232:233], v[198:199]
	v_pk_add_f32 v[232:233], v[232:233], v[200:201]
	v_pk_add_f32 v[232:233], v[232:233], v[202:203]
	v_add_u32_e32 v115, 952, v115
	ds_read2_b32 v[188:189], v115 offset0:0 offset1:1
	ds_read2_b32 v[190:191], v115 offset0:2 offset1:3
	ds_read2_b32 v[192:193], v115 offset0:8 offset1:9
	ds_read2_b32 v[194:195], v115 offset0:10 offset1:11
	ds_read2_b32 v[196:197], v115 offset0:17 offset1:18
	ds_read2_b32 v[198:199], v115 offset0:19 offset1:20
	ds_read2_b32 v[200:201], v115 offset0:25 offset1:26
	ds_read2_b32 v[202:203], v115 offset0:27 offset1:28
	v_mfma_f32_32x32x16_bf16 v[0:15], v[64:67], v[72:75], v[0:15]
	v_mfma_f32_32x32x16_bf16 v[16:31], v[64:67], v[76:79], v[16:31]
	v_mfma_f32_32x32x16_bf16 v[0:15], v[68:71], v[220:223], v[0:15]
	v_mfma_f32_32x32x16_bf16 v[16:31], v[68:71], v[224:227], v[16:31]
	global_load_dwordx4 v[116:119], v235, s[84:85]
	global_load_dwordx4 v[120:123], v236, s[84:85]
	global_load_dwordx4 v[124:127], v237, s[84:85]
	global_load_dwordx4 v[128:131], v238, s[84:85]
	global_load_dwordx4 v[132:135], v100, s[84:85] offset:768
	global_load_dwordx4 v[136:139], v149, s[84:85] offset:768
	global_load_dwordx4 v[140:143], v100, s[84:85] offset:832
	global_load_dwordx4 v[144:147], v149, s[84:85] offset:832
	s_add_u32 s84, s84, 0x30000
	s_addc_u32 s85, s85, 0
	ds_read_b64_tr_b16 v[72:73], v231
	ds_read_b64_tr_b16 v[74:75], v231 offset:512
	ds_read_b64_tr_b16 v[76:77], v231 offset:2048
	ds_read_b64_tr_b16 v[78:79], v231 offset:2560
	ds_read_b64_tr_b16 v[220:221], v231 offset:1024
	ds_read_b64_tr_b16 v[222:223], v231 offset:1536
	ds_read_b64_tr_b16 v[224:225], v231 offset:3072
	ds_read_b64_tr_b16 v[226:227], v231 offset:3584
	s_waitcnt vmcnt(8)
	ds_write_b128 v247, v[156:159]
	ds_write_b128 v247, v[160:163] offset:1024
	ds_write_b128 v247, v[164:167] offset:2048
	ds_write_b128 v247, v[168:171] offset:3072
	ds_read_b128 v[156:159], v248
	ds_read_b128 v[160:163], v249
	ds_read_b128 v[164:167], v250
	ds_read_b128 v[168:171], v251
	ds_write_b128 v112, v[172:175]
	ds_write_b128 v112, v[176:179] offset:1024
	ds_write_b128 v112, v[180:183] offset:2048
	ds_write_b128 v112, v[184:187] offset:3072
	s_waitcnt lgkmcnt(4)
	v_mfma_f32_32x32x16_bf16 v[188:203], v[156:159], v[48:51], v[188:203]
	v_exp_f32_e32 v32, v32
	v_exp_f32_e32 v33, v33
	v_exp_f32_e32 v34, v34
	v_exp_f32_e32 v35, v35
	v_mfma_f32_32x32x16_bf16 v[188:203], v[160:163], v[52:55], v[188:203]
	v_exp_f32_e32 v36, v36
	v_exp_f32_e32 v37, v37
	v_exp_f32_e32 v38, v38
	v_exp_f32_e32 v39, v39
	v_mfma_f32_32x32x16_bf16 v[188:203], v[164:167], v[56:59], v[188:203]
	v_exp_f32_e32 v40, v40
	v_exp_f32_e32 v41, v41
	v_exp_f32_e32 v42, v42
	v_exp_f32_e32 v43, v43
	v_mfma_f32_32x32x16_bf16 v[188:203], v[168:171], v[60:63], v[188:203]
	v_exp_f32_e32 v44, v44
	v_exp_f32_e32 v45, v45
	v_exp_f32_e32 v46, v46
	v_exp_f32_e32 v47, v47
	v_cvt_pk_bf16_f32 v64, v32, v33
	v_cvt_pk_bf16_f32 v65, v34, v35
	v_cvt_pk_bf16_f32 v66, v36, v37
	v_cvt_pk_bf16_f32 v67, v38, v39
	v_cvt_pk_bf16_f32 v68, v40, v41
	v_cvt_pk_bf16_f32 v69, v42, v43
	v_cvt_pk_bf16_f32 v70, v44, v45
	v_cvt_pk_bf16_f32 v71, v46, v47
	v_pk_add_f32 v[232:233], v[232:233], v[32:33]
	v_pk_add_f32 v[232:233], v[232:233], v[34:35]
	v_pk_add_f32 v[232:233], v[232:233], v[36:37]
	v_pk_add_f32 v[232:233], v[232:233], v[38:39]
	v_pk_add_f32 v[232:233], v[232:233], v[40:41]
	v_pk_add_f32 v[232:233], v[232:233], v[42:43]
	v_pk_add_f32 v[232:233], v[232:233], v[44:45]
	v_pk_add_f32 v[232:233], v[232:233], v[46:47]
	ds_read2_b32 v[32:33], v115 offset0:34 offset1:35
	ds_read2_b32 v[34:35], v115 offset0:36 offset1:37
	ds_read2_b32 v[36:37], v115 offset0:42 offset1:43
	ds_read2_b32 v[38:39], v115 offset0:44 offset1:45
	ds_read2_b32 v[40:41], v115 offset0:51 offset1:52
	ds_read2_b32 v[42:43], v115 offset0:53 offset1:54
	ds_read2_b32 v[44:45], v115 offset0:59 offset1:60
	ds_read2_b32 v[46:47], v115 offset0:61 offset1:62
	v_mfma_f32_32x32x16_bf16 v[0:15], v[64:67], v[72:75], v[0:15]
	v_mfma_f32_32x32x16_bf16 v[16:31], v[64:67], v[76:79], v[16:31]
	v_mfma_f32_32x32x16_bf16 v[0:15], v[68:71], v[220:223], v[0:15]
	v_mfma_f32_32x32x16_bf16 v[16:31], v[68:71], v[224:227], v[16:31]
	global_load_dwordx4 v[156:159], v235, s[84:85]
	global_load_dwordx4 v[160:163], v236, s[84:85]
	global_load_dwordx4 v[164:167], v237, s[84:85]
	global_load_dwordx4 v[168:171], v238, s[84:85]
	global_load_dwordx4 v[172:175], v100, s[84:85] offset:768
	global_load_dwordx4 v[176:179], v149, s[84:85] offset:768
	global_load_dwordx4 v[180:183], v100, s[84:85] offset:832
	global_load_dwordx4 v[184:187], v149, s[84:85] offset:832
	s_add_u32 s84, s84, 0x30000
	s_addc_u32 s85, s85, 0
	ds_read_b64_tr_b16 v[72:73], v231
	ds_read_b64_tr_b16 v[74:75], v231 offset:512
	ds_read_b64_tr_b16 v[76:77], v231 offset:2048
	ds_read_b64_tr_b16 v[78:79], v231 offset:2560
	ds_read_b64_tr_b16 v[220:221], v231 offset:1024
	ds_read_b64_tr_b16 v[222:223], v231 offset:1536
	ds_read_b64_tr_b16 v[224:225], v231 offset:3072
	ds_read_b64_tr_b16 v[226:227], v231 offset:3584
	s_waitcnt vmcnt(8)
	ds_write_b128 v247, v[116:119]
	ds_write_b128 v247, v[120:123] offset:1024
	ds_write_b128 v247, v[124:127] offset:2048
	ds_write_b128 v247, v[128:131] offset:3072
	ds_read_b128 v[116:119], v248
	ds_read_b128 v[120:123], v249
	ds_read_b128 v[124:127], v250
	ds_read_b128 v[128:131], v251
	ds_write_b128 v112, v[132:135]
	ds_write_b128 v112, v[136:139] offset:1024
	ds_write_b128 v112, v[140:143] offset:2048
	ds_write_b128 v112, v[144:147] offset:3072
	s_waitcnt lgkmcnt(4)
	v_mfma_f32_32x32x16_bf16 v[32:47], v[116:119], v[48:51], v[32:47]
	v_exp_f32_e32 v188, v188
	v_exp_f32_e32 v189, v189
	v_exp_f32_e32 v190, v190
	v_exp_f32_e32 v191, v191
	v_mfma_f32_32x32x16_bf16 v[32:47], v[120:123], v[52:55], v[32:47]
	v_exp_f32_e32 v192, v192
	v_exp_f32_e32 v193, v193
	v_exp_f32_e32 v194, v194
	v_exp_f32_e32 v195, v195
	v_mfma_f32_32x32x16_bf16 v[32:47], v[124:127], v[56:59], v[32:47]
	v_exp_f32_e32 v196, v196
	v_exp_f32_e32 v197, v197
	v_exp_f32_e32 v198, v198
	v_exp_f32_e32 v199, v199
	v_mfma_f32_32x32x16_bf16 v[32:47], v[128:131], v[60:63], v[32:47]
	v_exp_f32_e32 v200, v200
	v_exp_f32_e32 v201, v201
	v_exp_f32_e32 v202, v202
	v_exp_f32_e32 v203, v203
	v_cvt_pk_bf16_f32 v64, v188, v189
	v_cvt_pk_bf16_f32 v65, v190, v191
	v_cvt_pk_bf16_f32 v66, v192, v193
	v_cvt_pk_bf16_f32 v67, v194, v195
	v_cvt_pk_bf16_f32 v68, v196, v197
	v_cvt_pk_bf16_f32 v69, v198, v199
	v_cvt_pk_bf16_f32 v70, v200, v201
	v_cvt_pk_bf16_f32 v71, v202, v203
	v_pk_add_f32 v[232:233], v[232:233], v[188:189]
	v_pk_add_f32 v[232:233], v[232:233], v[190:191]
	v_pk_add_f32 v[232:233], v[232:233], v[192:193]
	v_pk_add_f32 v[232:233], v[232:233], v[194:195]
	v_pk_add_f32 v[232:233], v[232:233], v[196:197]
	v_pk_add_f32 v[232:233], v[232:233], v[198:199]
	v_pk_add_f32 v[232:233], v[232:233], v[200:201]
	v_pk_add_f32 v[232:233], v[232:233], v[202:203]
	ds_read2_b32 v[188:189], v115 offset0:68 offset1:69
	ds_read2_b32 v[190:191], v115 offset0:70 offset1:71
	ds_read2_b32 v[192:193], v115 offset0:76 offset1:77
	ds_read2_b32 v[194:195], v115 offset0:78 offset1:79
	ds_read2_b32 v[196:197], v115 offset0:85 offset1:86
	ds_read2_b32 v[198:199], v115 offset0:87 offset1:88
	ds_read2_b32 v[200:201], v115 offset0:93 offset1:94
	ds_read2_b32 v[202:203], v115 offset0:95 offset1:96
	v_mfma_f32_32x32x16_bf16 v[0:15], v[64:67], v[72:75], v[0:15]
	v_mfma_f32_32x32x16_bf16 v[16:31], v[64:67], v[76:79], v[16:31]
	v_mfma_f32_32x32x16_bf16 v[0:15], v[68:71], v[220:223], v[0:15]
	v_mfma_f32_32x32x16_bf16 v[16:31], v[68:71], v[224:227], v[16:31]
	global_load_dwordx4 v[116:119], v235, s[84:85]
	global_load_dwordx4 v[120:123], v236, s[84:85]
	global_load_dwordx4 v[124:127], v237, s[84:85]
	global_load_dwordx4 v[128:131], v238, s[84:85]
	global_load_dwordx4 v[132:135], v100, s[84:85] offset:768
	global_load_dwordx4 v[136:139], v149, s[84:85] offset:768
	global_load_dwordx4 v[140:143], v100, s[84:85] offset:832
	global_load_dwordx4 v[144:147], v149, s[84:85] offset:832
	s_add_u32 s84, s84, 0x30000
	s_addc_u32 s85, s85, 0
	ds_read_b64_tr_b16 v[72:73], v231
	ds_read_b64_tr_b16 v[74:75], v231 offset:512
	ds_read_b64_tr_b16 v[76:77], v231 offset:2048
	ds_read_b64_tr_b16 v[78:79], v231 offset:2560
	ds_read_b64_tr_b16 v[220:221], v231 offset:1024
	ds_read_b64_tr_b16 v[222:223], v231 offset:1536
	ds_read_b64_tr_b16 v[224:225], v231 offset:3072
	ds_read_b64_tr_b16 v[226:227], v231 offset:3584
	s_waitcnt vmcnt(8)
	ds_write_b128 v247, v[156:159]
	ds_write_b128 v247, v[160:163] offset:1024
	ds_write_b128 v247, v[164:167] offset:2048
	ds_write_b128 v247, v[168:171] offset:3072
	ds_read_b128 v[156:159], v248
	ds_read_b128 v[160:163], v249
	ds_read_b128 v[164:167], v250
	ds_read_b128 v[168:171], v251
	ds_write_b128 v112, v[172:175]
	ds_write_b128 v112, v[176:179] offset:1024
	ds_write_b128 v112, v[180:183] offset:2048
	ds_write_b128 v112, v[184:187] offset:3072
	s_waitcnt lgkmcnt(4)
	v_mfma_f32_32x32x16_bf16 v[188:203], v[156:159], v[48:51], v[188:203]
	v_exp_f32_e32 v32, v32
	v_exp_f32_e32 v33, v33
	v_exp_f32_e32 v34, v34
	v_exp_f32_e32 v35, v35
	v_mfma_f32_32x32x16_bf16 v[188:203], v[160:163], v[52:55], v[188:203]
	v_exp_f32_e32 v36, v36
	v_exp_f32_e32 v37, v37
	v_exp_f32_e32 v38, v38
	v_exp_f32_e32 v39, v39
	v_mfma_f32_32x32x16_bf16 v[188:203], v[164:167], v[56:59], v[188:203]
	v_exp_f32_e32 v40, v40
	v_exp_f32_e32 v41, v41
	v_exp_f32_e32 v42, v42
	v_exp_f32_e32 v43, v43
	v_mfma_f32_32x32x16_bf16 v[188:203], v[168:171], v[60:63], v[188:203]
	v_exp_f32_e32 v44, v44
	v_exp_f32_e32 v45, v45
	v_exp_f32_e32 v46, v46
	v_exp_f32_e32 v47, v47
	v_cvt_pk_bf16_f32 v64, v32, v33
	v_cvt_pk_bf16_f32 v65, v34, v35
	v_cvt_pk_bf16_f32 v66, v36, v37
	v_cvt_pk_bf16_f32 v67, v38, v39
	v_cvt_pk_bf16_f32 v68, v40, v41
	v_cvt_pk_bf16_f32 v69, v42, v43
	v_cvt_pk_bf16_f32 v70, v44, v45
	v_cvt_pk_bf16_f32 v71, v46, v47
	v_pk_add_f32 v[232:233], v[232:233], v[32:33]
	v_pk_add_f32 v[232:233], v[232:233], v[34:35]
	v_pk_add_f32 v[232:233], v[232:233], v[36:37]
	v_pk_add_f32 v[232:233], v[232:233], v[38:39]
	v_pk_add_f32 v[232:233], v[232:233], v[40:41]
	v_pk_add_f32 v[232:233], v[232:233], v[42:43]
	v_pk_add_f32 v[232:233], v[232:233], v[44:45]
	v_pk_add_f32 v[232:233], v[232:233], v[46:47]
	ds_read2_b32 v[32:33], v115 offset0:102 offset1:103
	ds_read2_b32 v[34:35], v115 offset0:104 offset1:105
	ds_read2_b32 v[36:37], v115 offset0:110 offset1:111
	ds_read2_b32 v[38:39], v115 offset0:112 offset1:113
	ds_read2_b32 v[40:41], v115 offset0:119 offset1:120
	ds_read2_b32 v[42:43], v115 offset0:121 offset1:122
	ds_read2_b32 v[44:45], v115 offset0:127 offset1:128
	ds_read2_b32 v[46:47], v115 offset0:129 offset1:130
	v_mfma_f32_32x32x16_bf16 v[0:15], v[64:67], v[72:75], v[0:15]
	v_mfma_f32_32x32x16_bf16 v[16:31], v[64:67], v[76:79], v[16:31]
	v_mfma_f32_32x32x16_bf16 v[0:15], v[68:71], v[220:223], v[0:15]
	v_mfma_f32_32x32x16_bf16 v[16:31], v[68:71], v[224:227], v[16:31]
	global_load_dwordx4 v[156:159], v235, s[84:85]
	global_load_dwordx4 v[160:163], v236, s[84:85]
	global_load_dwordx4 v[164:167], v237, s[84:85]
	global_load_dwordx4 v[168:171], v238, s[84:85]
	global_load_dwordx4 v[172:175], v100, s[84:85] offset:768
	global_load_dwordx4 v[176:179], v149, s[84:85] offset:768
	global_load_dwordx4 v[180:183], v100, s[84:85] offset:832
	global_load_dwordx4 v[184:187], v149, s[84:85] offset:832
	s_add_u32 s84, s84, 0x30000
	s_addc_u32 s85, s85, 0
	ds_read_b64_tr_b16 v[72:73], v231
	ds_read_b64_tr_b16 v[74:75], v231 offset:512
	ds_read_b64_tr_b16 v[76:77], v231 offset:2048
	ds_read_b64_tr_b16 v[78:79], v231 offset:2560
	ds_read_b64_tr_b16 v[220:221], v231 offset:1024
	ds_read_b64_tr_b16 v[222:223], v231 offset:1536
	ds_read_b64_tr_b16 v[224:225], v231 offset:3072
	ds_read_b64_tr_b16 v[226:227], v231 offset:3584
	s_waitcnt vmcnt(8)
	ds_write_b128 v247, v[116:119]
	ds_write_b128 v247, v[120:123] offset:1024
	ds_write_b128 v247, v[124:127] offset:2048
	ds_write_b128 v247, v[128:131] offset:3072
	ds_read_b128 v[116:119], v248
	ds_read_b128 v[120:123], v249
	ds_read_b128 v[124:127], v250
	ds_read_b128 v[128:131], v251
	ds_write_b128 v112, v[132:135]
	ds_write_b128 v112, v[136:139] offset:1024
	ds_write_b128 v112, v[140:143] offset:2048
	ds_write_b128 v112, v[144:147] offset:3072
	s_waitcnt lgkmcnt(4)
	v_mfma_f32_32x32x16_bf16 v[32:47], v[116:119], v[48:51], v[32:47]
	v_exp_f32_e32 v188, v188
	v_exp_f32_e32 v189, v189
	v_exp_f32_e32 v190, v190
	v_exp_f32_e32 v191, v191
	v_mfma_f32_32x32x16_bf16 v[32:47], v[120:123], v[52:55], v[32:47]
	v_exp_f32_e32 v192, v192
	v_exp_f32_e32 v193, v193
	v_exp_f32_e32 v194, v194
	v_exp_f32_e32 v195, v195
	v_mfma_f32_32x32x16_bf16 v[32:47], v[124:127], v[56:59], v[32:47]
	v_exp_f32_e32 v196, v196
	v_exp_f32_e32 v197, v197
	v_exp_f32_e32 v198, v198
	v_exp_f32_e32 v199, v199
	v_mfma_f32_32x32x16_bf16 v[32:47], v[128:131], v[60:63], v[32:47]
	v_exp_f32_e32 v200, v200
	v_exp_f32_e32 v201, v201
	v_exp_f32_e32 v202, v202
	v_exp_f32_e32 v203, v203
	v_cvt_pk_bf16_f32 v64, v188, v189
	v_cvt_pk_bf16_f32 v65, v190, v191
	v_cvt_pk_bf16_f32 v66, v192, v193
	v_cvt_pk_bf16_f32 v67, v194, v195
	v_cvt_pk_bf16_f32 v68, v196, v197
	v_cvt_pk_bf16_f32 v69, v198, v199
	v_cvt_pk_bf16_f32 v70, v200, v201
	v_cvt_pk_bf16_f32 v71, v202, v203
	v_pk_add_f32 v[232:233], v[232:233], v[188:189]
	v_pk_add_f32 v[232:233], v[232:233], v[190:191]
	v_pk_add_f32 v[232:233], v[232:233], v[192:193]
	v_pk_add_f32 v[232:233], v[232:233], v[194:195]
	v_pk_add_f32 v[232:233], v[232:233], v[196:197]
	v_pk_add_f32 v[232:233], v[232:233], v[198:199]
	v_pk_add_f32 v[232:233], v[232:233], v[200:201]
	v_pk_add_f32 v[232:233], v[232:233], v[202:203]
	ds_read2_b32 v[188:189], v115 offset0:136 offset1:137
	ds_read2_b32 v[190:191], v115 offset0:138 offset1:139
	ds_read2_b32 v[192:193], v115 offset0:144 offset1:145
	ds_read2_b32 v[194:195], v115 offset0:146 offset1:147
	ds_read2_b32 v[196:197], v115 offset0:153 offset1:154
	ds_read2_b32 v[198:199], v115 offset0:155 offset1:156
	ds_read2_b32 v[200:201], v115 offset0:161 offset1:162
	ds_read2_b32 v[202:203], v115 offset0:163 offset1:164
	v_mfma_f32_32x32x16_bf16 v[0:15], v[64:67], v[72:75], v[0:15]
	v_mfma_f32_32x32x16_bf16 v[16:31], v[64:67], v[76:79], v[16:31]
	v_mfma_f32_32x32x16_bf16 v[0:15], v[68:71], v[220:223], v[0:15]
	v_mfma_f32_32x32x16_bf16 v[16:31], v[68:71], v[224:227], v[16:31]
	global_load_dwordx4 v[116:119], v235, s[84:85]
	global_load_dwordx4 v[120:123], v236, s[84:85]
	global_load_dwordx4 v[124:127], v237, s[84:85]
	global_load_dwordx4 v[128:131], v238, s[84:85]
	global_load_dwordx4 v[132:135], v100, s[84:85] offset:768
	global_load_dwordx4 v[136:139], v149, s[84:85] offset:768
	global_load_dwordx4 v[140:143], v100, s[84:85] offset:832
	global_load_dwordx4 v[144:147], v149, s[84:85] offset:832
	s_add_u32 s84, s84, 0x30000
	s_addc_u32 s85, s85, 0
	ds_read_b64_tr_b16 v[72:73], v231
	ds_read_b64_tr_b16 v[74:75], v231 offset:512
	ds_read_b64_tr_b16 v[76:77], v231 offset:2048
	ds_read_b64_tr_b16 v[78:79], v231 offset:2560
	ds_read_b64_tr_b16 v[220:221], v231 offset:1024
	ds_read_b64_tr_b16 v[222:223], v231 offset:1536
	ds_read_b64_tr_b16 v[224:225], v231 offset:3072
	ds_read_b64_tr_b16 v[226:227], v231 offset:3584
	s_waitcnt vmcnt(8)
	ds_write_b128 v247, v[156:159]
	ds_write_b128 v247, v[160:163] offset:1024
	ds_write_b128 v247, v[164:167] offset:2048
	ds_write_b128 v247, v[168:171] offset:3072
	ds_read_b128 v[156:159], v248
	ds_read_b128 v[160:163], v249
	ds_read_b128 v[164:167], v250
	ds_read_b128 v[168:171], v251
	ds_write_b128 v112, v[172:175]
	ds_write_b128 v112, v[176:179] offset:1024
	ds_write_b128 v112, v[180:183] offset:2048
	ds_write_b128 v112, v[184:187] offset:3072
	s_waitcnt lgkmcnt(4)
	v_mfma_f32_32x32x16_bf16 v[188:203], v[156:159], v[48:51], v[188:203]
	v_exp_f32_e32 v32, v32
	v_exp_f32_e32 v33, v33
	v_exp_f32_e32 v34, v34
	v_exp_f32_e32 v35, v35
	v_mfma_f32_32x32x16_bf16 v[188:203], v[160:163], v[52:55], v[188:203]
	v_exp_f32_e32 v36, v36
	v_exp_f32_e32 v37, v37
	v_exp_f32_e32 v38, v38
	v_exp_f32_e32 v39, v39
	v_mfma_f32_32x32x16_bf16 v[188:203], v[164:167], v[56:59], v[188:203]
	v_exp_f32_e32 v40, v40
	v_exp_f32_e32 v41, v41
	v_exp_f32_e32 v42, v42
	v_exp_f32_e32 v43, v43
	v_mfma_f32_32x32x16_bf16 v[188:203], v[168:171], v[60:63], v[188:203]
	v_exp_f32_e32 v44, v44
	v_exp_f32_e32 v45, v45
	v_exp_f32_e32 v46, v46
	v_exp_f32_e32 v47, v47
	v_cvt_pk_bf16_f32 v64, v32, v33
	v_cvt_pk_bf16_f32 v65, v34, v35
	v_cvt_pk_bf16_f32 v66, v36, v37
	v_cvt_pk_bf16_f32 v67, v38, v39
	v_cvt_pk_bf16_f32 v68, v40, v41
	v_cvt_pk_bf16_f32 v69, v42, v43
	v_cvt_pk_bf16_f32 v70, v44, v45
	v_cvt_pk_bf16_f32 v71, v46, v47
	v_pk_add_f32 v[232:233], v[232:233], v[32:33]
	v_pk_add_f32 v[232:233], v[232:233], v[34:35]
	v_pk_add_f32 v[232:233], v[232:233], v[36:37]
	v_pk_add_f32 v[232:233], v[232:233], v[38:39]
	v_pk_add_f32 v[232:233], v[232:233], v[40:41]
	v_pk_add_f32 v[232:233], v[232:233], v[42:43]
	v_pk_add_f32 v[232:233], v[232:233], v[44:45]
	v_pk_add_f32 v[232:233], v[232:233], v[46:47]
	ds_read2_b32 v[32:33], v115 offset0:170 offset1:171
	ds_read2_b32 v[34:35], v115 offset0:172 offset1:173
	ds_read2_b32 v[36:37], v115 offset0:178 offset1:179
	ds_read2_b32 v[38:39], v115 offset0:180 offset1:181
	ds_read2_b32 v[40:41], v115 offset0:187 offset1:188
	ds_read2_b32 v[42:43], v115 offset0:189 offset1:190
	ds_read2_b32 v[44:45], v115 offset0:195 offset1:196
	ds_read2_b32 v[46:47], v115 offset0:197 offset1:198
	v_mfma_f32_32x32x16_bf16 v[0:15], v[64:67], v[72:75], v[0:15]
	v_mfma_f32_32x32x16_bf16 v[16:31], v[64:67], v[76:79], v[16:31]
	v_mfma_f32_32x32x16_bf16 v[0:15], v[68:71], v[220:223], v[0:15]
	v_mfma_f32_32x32x16_bf16 v[16:31], v[68:71], v[224:227], v[16:31]
	global_load_dwordx4 v[156:159], v235, s[84:85]
	global_load_dwordx4 v[160:163], v236, s[84:85]
	global_load_dwordx4 v[164:167], v237, s[84:85]
	global_load_dwordx4 v[168:171], v238, s[84:85]
	global_load_dwordx4 v[172:175], v100, s[84:85] offset:768
	global_load_dwordx4 v[176:179], v149, s[84:85] offset:768
	global_load_dwordx4 v[180:183], v100, s[84:85] offset:832
	global_load_dwordx4 v[184:187], v149, s[84:85] offset:832
	s_add_u32 s84, s84, 0x30000
	s_addc_u32 s85, s85, 0
	ds_read_b64_tr_b16 v[72:73], v231
	ds_read_b64_tr_b16 v[74:75], v231 offset:512
	ds_read_b64_tr_b16 v[76:77], v231 offset:2048
	ds_read_b64_tr_b16 v[78:79], v231 offset:2560
	ds_read_b64_tr_b16 v[220:221], v231 offset:1024
	ds_read_b64_tr_b16 v[222:223], v231 offset:1536
	ds_read_b64_tr_b16 v[224:225], v231 offset:3072
	ds_read_b64_tr_b16 v[226:227], v231 offset:3584
	s_waitcnt vmcnt(8)
	ds_write_b128 v247, v[116:119]
	ds_write_b128 v247, v[120:123] offset:1024
	ds_write_b128 v247, v[124:127] offset:2048
	ds_write_b128 v247, v[128:131] offset:3072
	ds_read_b128 v[116:119], v248
	ds_read_b128 v[120:123], v249
	ds_read_b128 v[124:127], v250
	ds_read_b128 v[128:131], v251
	ds_write_b128 v112, v[132:135]
	ds_write_b128 v112, v[136:139] offset:1024
	ds_write_b128 v112, v[140:143] offset:2048
	ds_write_b128 v112, v[144:147] offset:3072
	s_waitcnt lgkmcnt(4)
	v_mfma_f32_32x32x16_bf16 v[32:47], v[116:119], v[48:51], v[32:47]
	v_exp_f32_e32 v188, v188
	v_exp_f32_e32 v189, v189
	v_exp_f32_e32 v190, v190
	v_exp_f32_e32 v191, v191
	v_mfma_f32_32x32x16_bf16 v[32:47], v[120:123], v[52:55], v[32:47]
	v_exp_f32_e32 v192, v192
	v_exp_f32_e32 v193, v193
	v_exp_f32_e32 v194, v194
	v_exp_f32_e32 v195, v195
	v_mfma_f32_32x32x16_bf16 v[32:47], v[124:127], v[56:59], v[32:47]
	v_exp_f32_e32 v196, v196
	v_exp_f32_e32 v197, v197
	v_exp_f32_e32 v198, v198
	v_exp_f32_e32 v199, v199
	v_mfma_f32_32x32x16_bf16 v[32:47], v[128:131], v[60:63], v[32:47]
	v_exp_f32_e32 v200, v200
	v_exp_f32_e32 v201, v201
	v_exp_f32_e32 v202, v202
	v_exp_f32_e32 v203, v203
	v_cvt_pk_bf16_f32 v64, v188, v189
	v_cvt_pk_bf16_f32 v65, v190, v191
	v_cvt_pk_bf16_f32 v66, v192, v193
	v_cvt_pk_bf16_f32 v67, v194, v195
	v_cvt_pk_bf16_f32 v68, v196, v197
	v_cvt_pk_bf16_f32 v69, v198, v199
	v_cvt_pk_bf16_f32 v70, v200, v201
	v_cvt_pk_bf16_f32 v71, v202, v203
	v_pk_add_f32 v[232:233], v[232:233], v[188:189]
	v_pk_add_f32 v[232:233], v[232:233], v[190:191]
	v_pk_add_f32 v[232:233], v[232:233], v[192:193]
	v_pk_add_f32 v[232:233], v[232:233], v[194:195]
	v_pk_add_f32 v[232:233], v[232:233], v[196:197]
	v_pk_add_f32 v[232:233], v[232:233], v[198:199]
	v_pk_add_f32 v[232:233], v[232:233], v[200:201]
	v_pk_add_f32 v[232:233], v[232:233], v[202:203]
	ds_read2_b32 v[188:189], v115 offset0:204 offset1:205
	ds_read2_b32 v[190:191], v115 offset0:206 offset1:207
	ds_read2_b32 v[192:193], v115 offset0:212 offset1:213
	ds_read2_b32 v[194:195], v115 offset0:214 offset1:215
	ds_read2_b32 v[196:197], v115 offset0:221 offset1:222
	ds_read2_b32 v[198:199], v115 offset0:223 offset1:224
	ds_read2_b32 v[200:201], v115 offset0:229 offset1:230
	ds_read2_b32 v[202:203], v115 offset0:231 offset1:232
	v_mfma_f32_32x32x16_bf16 v[0:15], v[64:67], v[72:75], v[0:15]
	v_mfma_f32_32x32x16_bf16 v[16:31], v[64:67], v[76:79], v[16:31]
	v_mfma_f32_32x32x16_bf16 v[0:15], v[68:71], v[220:223], v[0:15]
	v_mfma_f32_32x32x16_bf16 v[16:31], v[68:71], v[224:227], v[16:31]
	global_load_dwordx4 v[116:119], v235, s[84:85]
	global_load_dwordx4 v[120:123], v236, s[84:85]
	global_load_dwordx4 v[124:127], v237, s[84:85]
	global_load_dwordx4 v[128:131], v238, s[84:85]
	global_load_dwordx4 v[132:135], v100, s[84:85] offset:768
	global_load_dwordx4 v[136:139], v149, s[84:85] offset:768
	global_load_dwordx4 v[140:143], v100, s[84:85] offset:832
	global_load_dwordx4 v[144:147], v149, s[84:85] offset:832
	s_add_u32 s84, s84, 0x30000
	s_addc_u32 s85, s85, 0
	ds_read_b64_tr_b16 v[72:73], v231
	ds_read_b64_tr_b16 v[74:75], v231 offset:512
	ds_read_b64_tr_b16 v[76:77], v231 offset:2048
	ds_read_b64_tr_b16 v[78:79], v231 offset:2560
	ds_read_b64_tr_b16 v[220:221], v231 offset:1024
	ds_read_b64_tr_b16 v[222:223], v231 offset:1536
	ds_read_b64_tr_b16 v[224:225], v231 offset:3072
	ds_read_b64_tr_b16 v[226:227], v231 offset:3584
	s_waitcnt vmcnt(8)
	ds_write_b128 v247, v[156:159]
	ds_write_b128 v247, v[160:163] offset:1024
	ds_write_b128 v247, v[164:167] offset:2048
	ds_write_b128 v247, v[168:171] offset:3072
	ds_read_b128 v[156:159], v248
	ds_read_b128 v[160:163], v249
	ds_read_b128 v[164:167], v250
	ds_read_b128 v[168:171], v251
	ds_write_b128 v112, v[172:175]
	ds_write_b128 v112, v[176:179] offset:1024
	ds_write_b128 v112, v[180:183] offset:2048
	ds_write_b128 v112, v[184:187] offset:3072
	s_waitcnt lgkmcnt(4)
	v_mfma_f32_32x32x16_bf16 v[188:203], v[156:159], v[48:51], v[188:203]
	v_exp_f32_e32 v32, v32
	v_exp_f32_e32 v33, v33
	v_exp_f32_e32 v34, v34
	v_exp_f32_e32 v35, v35
	v_mfma_f32_32x32x16_bf16 v[188:203], v[160:163], v[52:55], v[188:203]
	v_exp_f32_e32 v36, v36
	v_exp_f32_e32 v37, v37
	v_exp_f32_e32 v38, v38
	v_exp_f32_e32 v39, v39
	v_mfma_f32_32x32x16_bf16 v[188:203], v[164:167], v[56:59], v[188:203]
	v_exp_f32_e32 v40, v40
	v_exp_f32_e32 v41, v41
	v_exp_f32_e32 v42, v42
	v_exp_f32_e32 v43, v43
	v_mfma_f32_32x32x16_bf16 v[188:203], v[168:171], v[60:63], v[188:203]
	v_exp_f32_e32 v44, v44
	v_exp_f32_e32 v45, v45
	v_exp_f32_e32 v46, v46
	v_exp_f32_e32 v47, v47
	v_cvt_pk_bf16_f32 v64, v32, v33
	v_cvt_pk_bf16_f32 v65, v34, v35
	v_cvt_pk_bf16_f32 v66, v36, v37
	v_cvt_pk_bf16_f32 v67, v38, v39
	v_cvt_pk_bf16_f32 v68, v40, v41
	v_cvt_pk_bf16_f32 v69, v42, v43
	v_cvt_pk_bf16_f32 v70, v44, v45
	v_cvt_pk_bf16_f32 v71, v46, v47
	v_pk_add_f32 v[232:233], v[232:233], v[32:33]
	v_pk_add_f32 v[232:233], v[232:233], v[34:35]
	v_pk_add_f32 v[232:233], v[232:233], v[36:37]
	v_pk_add_f32 v[232:233], v[232:233], v[38:39]
	v_pk_add_f32 v[232:233], v[232:233], v[40:41]
	v_pk_add_f32 v[232:233], v[232:233], v[42:43]
	v_pk_add_f32 v[232:233], v[232:233], v[44:45]
	v_pk_add_f32 v[232:233], v[232:233], v[46:47]
	v_add_u32_e32 v115, 952, v115
	ds_read2_b32 v[32:33], v115 offset0:0 offset1:1
	ds_read2_b32 v[34:35], v115 offset0:2 offset1:3
	ds_read2_b32 v[36:37], v115 offset0:8 offset1:9
	ds_read2_b32 v[38:39], v115 offset0:10 offset1:11
	ds_read2_b32 v[40:41], v115 offset0:17 offset1:18
	ds_read2_b32 v[42:43], v115 offset0:19 offset1:20
	ds_read2_b32 v[44:45], v115 offset0:25 offset1:26
	ds_read2_b32 v[46:47], v115 offset0:27 offset1:28
	v_mfma_f32_32x32x16_bf16 v[0:15], v[64:67], v[72:75], v[0:15]
	v_mfma_f32_32x32x16_bf16 v[16:31], v[64:67], v[76:79], v[16:31]
	v_mfma_f32_32x32x16_bf16 v[0:15], v[68:71], v[220:223], v[0:15]
	v_mfma_f32_32x32x16_bf16 v[16:31], v[68:71], v[224:227], v[16:31]
	global_load_dwordx4 v[156:159], v235, s[84:85]
	global_load_dwordx4 v[160:163], v236, s[84:85]
	global_load_dwordx4 v[164:167], v237, s[84:85]
	global_load_dwordx4 v[168:171], v238, s[84:85]
	global_load_dwordx4 v[172:175], v100, s[84:85] offset:768
	global_load_dwordx4 v[176:179], v149, s[84:85] offset:768
	global_load_dwordx4 v[180:183], v100, s[84:85] offset:832
	global_load_dwordx4 v[184:187], v149, s[84:85] offset:832
	s_add_u32 s84, s84, 0x30000
	s_addc_u32 s85, s85, 0
	ds_read_b64_tr_b16 v[72:73], v231
	ds_read_b64_tr_b16 v[74:75], v231 offset:512
	ds_read_b64_tr_b16 v[76:77], v231 offset:2048
	ds_read_b64_tr_b16 v[78:79], v231 offset:2560
	ds_read_b64_tr_b16 v[220:221], v231 offset:1024
	ds_read_b64_tr_b16 v[222:223], v231 offset:1536
	ds_read_b64_tr_b16 v[224:225], v231 offset:3072
	ds_read_b64_tr_b16 v[226:227], v231 offset:3584
	s_waitcnt vmcnt(8)
	ds_write_b128 v247, v[116:119]
	ds_write_b128 v247, v[120:123] offset:1024
	ds_write_b128 v247, v[124:127] offset:2048
	ds_write_b128 v247, v[128:131] offset:3072
	ds_read_b128 v[116:119], v248
	ds_read_b128 v[120:123], v249
	ds_read_b128 v[124:127], v250
	ds_read_b128 v[128:131], v251
	ds_write_b128 v112, v[132:135]
	ds_write_b128 v112, v[136:139] offset:1024
	ds_write_b128 v112, v[140:143] offset:2048
	ds_write_b128 v112, v[144:147] offset:3072
	s_waitcnt lgkmcnt(4)
	v_mfma_f32_32x32x16_bf16 v[32:47], v[116:119], v[48:51], v[32:47]
	v_exp_f32_e32 v188, v188
	v_exp_f32_e32 v189, v189
	v_exp_f32_e32 v190, v190
	v_exp_f32_e32 v191, v191
	v_mfma_f32_32x32x16_bf16 v[32:47], v[120:123], v[52:55], v[32:47]
	v_exp_f32_e32 v192, v192
	v_exp_f32_e32 v193, v193
	v_exp_f32_e32 v194, v194
	v_exp_f32_e32 v195, v195
	v_mfma_f32_32x32x16_bf16 v[32:47], v[124:127], v[56:59], v[32:47]
	v_exp_f32_e32 v196, v196
	v_exp_f32_e32 v197, v197
	v_exp_f32_e32 v198, v198
	v_exp_f32_e32 v199, v199
	v_mfma_f32_32x32x16_bf16 v[32:47], v[128:131], v[60:63], v[32:47]
	v_exp_f32_e32 v200, v200
	v_exp_f32_e32 v201, v201
	v_exp_f32_e32 v202, v202
	v_exp_f32_e32 v203, v203
	v_cvt_pk_bf16_f32 v64, v188, v189
	v_cvt_pk_bf16_f32 v65, v190, v191
	v_cvt_pk_bf16_f32 v66, v192, v193
	v_cvt_pk_bf16_f32 v67, v194, v195
	v_cvt_pk_bf16_f32 v68, v196, v197
	v_cvt_pk_bf16_f32 v69, v198, v199
	v_cvt_pk_bf16_f32 v70, v200, v201
	v_cvt_pk_bf16_f32 v71, v202, v203
	v_pk_add_f32 v[232:233], v[232:233], v[188:189]
	v_pk_add_f32 v[232:233], v[232:233], v[190:191]
	v_pk_add_f32 v[232:233], v[232:233], v[192:193]
	v_pk_add_f32 v[232:233], v[232:233], v[194:195]
	v_pk_add_f32 v[232:233], v[232:233], v[196:197]
	v_pk_add_f32 v[232:233], v[232:233], v[198:199]
	v_pk_add_f32 v[232:233], v[232:233], v[200:201]
	v_pk_add_f32 v[232:233], v[232:233], v[202:203]
	ds_read2_b32 v[188:189], v115 offset0:34 offset1:35
	ds_read2_b32 v[190:191], v115 offset0:36 offset1:37
	ds_read2_b32 v[192:193], v115 offset0:42 offset1:43
	ds_read2_b32 v[194:195], v115 offset0:44 offset1:45
	ds_read2_b32 v[196:197], v115 offset0:51 offset1:52
	ds_read2_b32 v[198:199], v115 offset0:53 offset1:54
	ds_read2_b32 v[200:201], v115 offset0:59 offset1:60
	ds_read2_b32 v[202:203], v115 offset0:61 offset1:62
	v_mfma_f32_32x32x16_bf16 v[0:15], v[64:67], v[72:75], v[0:15]
	v_mfma_f32_32x32x16_bf16 v[16:31], v[64:67], v[76:79], v[16:31]
	v_mfma_f32_32x32x16_bf16 v[0:15], v[68:71], v[220:223], v[0:15]
	v_mfma_f32_32x32x16_bf16 v[16:31], v[68:71], v[224:227], v[16:31]
	global_load_dwordx4 v[116:119], v235, s[84:85]
	global_load_dwordx4 v[120:123], v236, s[84:85]
	global_load_dwordx4 v[124:127], v237, s[84:85]
	global_load_dwordx4 v[128:131], v238, s[84:85]
	global_load_dwordx4 v[132:135], v100, s[84:85] offset:768
	global_load_dwordx4 v[136:139], v149, s[84:85] offset:768
	global_load_dwordx4 v[140:143], v100, s[84:85] offset:832
	global_load_dwordx4 v[144:147], v149, s[84:85] offset:832
	s_add_u32 s84, s84, 0x30000
	s_addc_u32 s85, s85, 0
	ds_read_b64_tr_b16 v[72:73], v231
	ds_read_b64_tr_b16 v[74:75], v231 offset:512
	ds_read_b64_tr_b16 v[76:77], v231 offset:2048
	ds_read_b64_tr_b16 v[78:79], v231 offset:2560
	ds_read_b64_tr_b16 v[220:221], v231 offset:1024
	ds_read_b64_tr_b16 v[222:223], v231 offset:1536
	ds_read_b64_tr_b16 v[224:225], v231 offset:3072
	ds_read_b64_tr_b16 v[226:227], v231 offset:3584
	s_waitcnt vmcnt(8)
	ds_write_b128 v247, v[156:159]
	ds_write_b128 v247, v[160:163] offset:1024
	ds_write_b128 v247, v[164:167] offset:2048
	ds_write_b128 v247, v[168:171] offset:3072
	ds_read_b128 v[156:159], v248
	ds_read_b128 v[160:163], v249
	ds_read_b128 v[164:167], v250
	ds_read_b128 v[168:171], v251
	ds_write_b128 v112, v[172:175]
	ds_write_b128 v112, v[176:179] offset:1024
	ds_write_b128 v112, v[180:183] offset:2048
	ds_write_b128 v112, v[184:187] offset:3072
	s_waitcnt lgkmcnt(4)
	v_mfma_f32_32x32x16_bf16 v[188:203], v[156:159], v[48:51], v[188:203]
	v_exp_f32_e32 v32, v32
	v_exp_f32_e32 v33, v33
	v_exp_f32_e32 v34, v34
	v_exp_f32_e32 v35, v35
	v_mfma_f32_32x32x16_bf16 v[188:203], v[160:163], v[52:55], v[188:203]
	v_exp_f32_e32 v36, v36
	v_exp_f32_e32 v37, v37
	v_exp_f32_e32 v38, v38
	v_exp_f32_e32 v39, v39
	v_mfma_f32_32x32x16_bf16 v[188:203], v[164:167], v[56:59], v[188:203]
	v_exp_f32_e32 v40, v40
	v_exp_f32_e32 v41, v41
	v_exp_f32_e32 v42, v42
	v_exp_f32_e32 v43, v43
	v_mfma_f32_32x32x16_bf16 v[188:203], v[168:171], v[60:63], v[188:203]
	v_exp_f32_e32 v44, v44
	v_exp_f32_e32 v45, v45
	v_exp_f32_e32 v46, v46
	v_exp_f32_e32 v47, v47
	v_cvt_pk_bf16_f32 v64, v32, v33
	v_cvt_pk_bf16_f32 v65, v34, v35
	v_cvt_pk_bf16_f32 v66, v36, v37
	v_cvt_pk_bf16_f32 v67, v38, v39
	v_cvt_pk_bf16_f32 v68, v40, v41
	v_cvt_pk_bf16_f32 v69, v42, v43
	v_cvt_pk_bf16_f32 v70, v44, v45
	v_cvt_pk_bf16_f32 v71, v46, v47
	v_pk_add_f32 v[232:233], v[232:233], v[32:33]
	v_pk_add_f32 v[232:233], v[232:233], v[34:35]
	v_pk_add_f32 v[232:233], v[232:233], v[36:37]
	v_pk_add_f32 v[232:233], v[232:233], v[38:39]
	v_pk_add_f32 v[232:233], v[232:233], v[40:41]
	v_pk_add_f32 v[232:233], v[232:233], v[42:43]
	v_pk_add_f32 v[232:233], v[232:233], v[44:45]
	v_pk_add_f32 v[232:233], v[232:233], v[46:47]
	ds_read2_b32 v[32:33], v115 offset0:68 offset1:69
	ds_read2_b32 v[34:35], v115 offset0:70 offset1:71
	ds_read2_b32 v[36:37], v115 offset0:76 offset1:77
	ds_read2_b32 v[38:39], v115 offset0:78 offset1:79
	ds_read2_b32 v[40:41], v115 offset0:85 offset1:86
	ds_read2_b32 v[42:43], v115 offset0:87 offset1:88
	ds_read2_b32 v[44:45], v115 offset0:93 offset1:94
	ds_read2_b32 v[46:47], v115 offset0:95 offset1:96
	v_mfma_f32_32x32x16_bf16 v[0:15], v[64:67], v[72:75], v[0:15]
	v_mfma_f32_32x32x16_bf16 v[16:31], v[64:67], v[76:79], v[16:31]
	v_mfma_f32_32x32x16_bf16 v[0:15], v[68:71], v[220:223], v[0:15]
	v_mfma_f32_32x32x16_bf16 v[16:31], v[68:71], v[224:227], v[16:31]
	global_load_dwordx4 v[156:159], v235, s[84:85]
	global_load_dwordx4 v[160:163], v236, s[84:85]
	global_load_dwordx4 v[164:167], v237, s[84:85]
	global_load_dwordx4 v[168:171], v238, s[84:85]
	global_load_dwordx4 v[172:175], v100, s[84:85] offset:768
	global_load_dwordx4 v[176:179], v149, s[84:85] offset:768
	global_load_dwordx4 v[180:183], v100, s[84:85] offset:832
	global_load_dwordx4 v[184:187], v149, s[84:85] offset:832
	s_add_u32 s84, s84, 0x30000
	s_addc_u32 s85, s85, 0
	ds_read_b64_tr_b16 v[72:73], v231
	ds_read_b64_tr_b16 v[74:75], v231 offset:512
	ds_read_b64_tr_b16 v[76:77], v231 offset:2048
	ds_read_b64_tr_b16 v[78:79], v231 offset:2560
	ds_read_b64_tr_b16 v[220:221], v231 offset:1024
	ds_read_b64_tr_b16 v[222:223], v231 offset:1536
	ds_read_b64_tr_b16 v[224:225], v231 offset:3072
	ds_read_b64_tr_b16 v[226:227], v231 offset:3584
	s_waitcnt vmcnt(8)
	ds_write_b128 v247, v[116:119]
	ds_write_b128 v247, v[120:123] offset:1024
	ds_write_b128 v247, v[124:127] offset:2048
	ds_write_b128 v247, v[128:131] offset:3072
	ds_read_b128 v[116:119], v248
	ds_read_b128 v[120:123], v249
	ds_read_b128 v[124:127], v250
	ds_read_b128 v[128:131], v251
	ds_write_b128 v112, v[132:135]
	ds_write_b128 v112, v[136:139] offset:1024
	ds_write_b128 v112, v[140:143] offset:2048
	ds_write_b128 v112, v[144:147] offset:3072
	s_waitcnt lgkmcnt(4)
	v_mfma_f32_32x32x16_bf16 v[32:47], v[116:119], v[48:51], v[32:47]
	v_exp_f32_e32 v188, v188
	v_exp_f32_e32 v189, v189
	v_exp_f32_e32 v190, v190
	v_exp_f32_e32 v191, v191
	v_mfma_f32_32x32x16_bf16 v[32:47], v[120:123], v[52:55], v[32:47]
	v_exp_f32_e32 v192, v192
	v_exp_f32_e32 v193, v193
	v_exp_f32_e32 v194, v194
	v_exp_f32_e32 v195, v195
	v_mfma_f32_32x32x16_bf16 v[32:47], v[124:127], v[56:59], v[32:47]
	v_exp_f32_e32 v196, v196
	v_exp_f32_e32 v197, v197
	v_exp_f32_e32 v198, v198
	v_exp_f32_e32 v199, v199
	v_mfma_f32_32x32x16_bf16 v[32:47], v[128:131], v[60:63], v[32:47]
	v_exp_f32_e32 v200, v200
	v_exp_f32_e32 v201, v201
	v_exp_f32_e32 v202, v202
	v_exp_f32_e32 v203, v203
	v_cvt_pk_bf16_f32 v64, v188, v189
	v_cvt_pk_bf16_f32 v65, v190, v191
	v_cvt_pk_bf16_f32 v66, v192, v193
	v_cvt_pk_bf16_f32 v67, v194, v195
	v_cvt_pk_bf16_f32 v68, v196, v197
	v_cvt_pk_bf16_f32 v69, v198, v199
	v_cvt_pk_bf16_f32 v70, v200, v201
	v_cvt_pk_bf16_f32 v71, v202, v203
	v_pk_add_f32 v[232:233], v[232:233], v[188:189]
	v_pk_add_f32 v[232:233], v[232:233], v[190:191]
	v_pk_add_f32 v[232:233], v[232:233], v[192:193]
	v_pk_add_f32 v[232:233], v[232:233], v[194:195]
	v_pk_add_f32 v[232:233], v[232:233], v[196:197]
	v_pk_add_f32 v[232:233], v[232:233], v[198:199]
	v_pk_add_f32 v[232:233], v[232:233], v[200:201]
	v_pk_add_f32 v[232:233], v[232:233], v[202:203]
	ds_read2_b32 v[188:189], v115 offset0:102 offset1:103
	ds_read2_b32 v[190:191], v115 offset0:104 offset1:105
	ds_read2_b32 v[192:193], v115 offset0:110 offset1:111
	ds_read2_b32 v[194:195], v115 offset0:112 offset1:113
	ds_read2_b32 v[196:197], v115 offset0:119 offset1:120
	ds_read2_b32 v[198:199], v115 offset0:121 offset1:122
	ds_read2_b32 v[200:201], v115 offset0:127 offset1:128
	ds_read2_b32 v[202:203], v115 offset0:129 offset1:130
	v_mfma_f32_32x32x16_bf16 v[0:15], v[64:67], v[72:75], v[0:15]
	v_mfma_f32_32x32x16_bf16 v[16:31], v[64:67], v[76:79], v[16:31]
	v_mfma_f32_32x32x16_bf16 v[0:15], v[68:71], v[220:223], v[0:15]
	v_mfma_f32_32x32x16_bf16 v[16:31], v[68:71], v[224:227], v[16:31]
	global_load_dwordx4 v[116:119], v235, s[84:85]
	global_load_dwordx4 v[120:123], v236, s[84:85]
	global_load_dwordx4 v[124:127], v237, s[84:85]
	global_load_dwordx4 v[128:131], v238, s[84:85]
	global_load_dwordx4 v[132:135], v100, s[84:85] offset:768
	global_load_dwordx4 v[136:139], v149, s[84:85] offset:768
	global_load_dwordx4 v[140:143], v100, s[84:85] offset:832
	global_load_dwordx4 v[144:147], v149, s[84:85] offset:832
	s_add_u32 s84, s84, 0x30000
	s_addc_u32 s85, s85, 0
	ds_read_b64_tr_b16 v[72:73], v231
	ds_read_b64_tr_b16 v[74:75], v231 offset:512
	ds_read_b64_tr_b16 v[76:77], v231 offset:2048
	ds_read_b64_tr_b16 v[78:79], v231 offset:2560
	ds_read_b64_tr_b16 v[220:221], v231 offset:1024
	ds_read_b64_tr_b16 v[222:223], v231 offset:1536
	ds_read_b64_tr_b16 v[224:225], v231 offset:3072
	ds_read_b64_tr_b16 v[226:227], v231 offset:3584
	s_waitcnt vmcnt(8)
	ds_write_b128 v247, v[156:159]
	ds_write_b128 v247, v[160:163] offset:1024
	ds_write_b128 v247, v[164:167] offset:2048
	ds_write_b128 v247, v[168:171] offset:3072
	ds_read_b128 v[156:159], v248
	ds_read_b128 v[160:163], v249
	ds_read_b128 v[164:167], v250
	ds_read_b128 v[168:171], v251
	ds_write_b128 v112, v[172:175]
	ds_write_b128 v112, v[176:179] offset:1024
	ds_write_b128 v112, v[180:183] offset:2048
	ds_write_b128 v112, v[184:187] offset:3072
	s_waitcnt lgkmcnt(4)
	v_mfma_f32_32x32x16_bf16 v[188:203], v[156:159], v[48:51], v[188:203]
	v_exp_f32_e32 v32, v32
	v_exp_f32_e32 v33, v33
	v_exp_f32_e32 v34, v34
	v_exp_f32_e32 v35, v35
	v_mfma_f32_32x32x16_bf16 v[188:203], v[160:163], v[52:55], v[188:203]
	v_exp_f32_e32 v36, v36
	v_exp_f32_e32 v37, v37
	v_exp_f32_e32 v38, v38
	v_exp_f32_e32 v39, v39
	v_mfma_f32_32x32x16_bf16 v[188:203], v[164:167], v[56:59], v[188:203]
	v_exp_f32_e32 v40, v40
	v_exp_f32_e32 v41, v41
	v_exp_f32_e32 v42, v42
	v_exp_f32_e32 v43, v43
	v_mfma_f32_32x32x16_bf16 v[188:203], v[168:171], v[60:63], v[188:203]
	v_exp_f32_e32 v44, v44
	v_exp_f32_e32 v45, v45
	v_exp_f32_e32 v46, v46
	v_exp_f32_e32 v47, v47
	v_cvt_pk_bf16_f32 v64, v32, v33
	v_cvt_pk_bf16_f32 v65, v34, v35
	v_cvt_pk_bf16_f32 v66, v36, v37
	v_cvt_pk_bf16_f32 v67, v38, v39
	v_cvt_pk_bf16_f32 v68, v40, v41
	v_cvt_pk_bf16_f32 v69, v42, v43
	v_cvt_pk_bf16_f32 v70, v44, v45
	v_cvt_pk_bf16_f32 v71, v46, v47
	v_pk_add_f32 v[232:233], v[232:233], v[32:33]
	v_pk_add_f32 v[232:233], v[232:233], v[34:35]
	v_pk_add_f32 v[232:233], v[232:233], v[36:37]
	v_pk_add_f32 v[232:233], v[232:233], v[38:39]
	v_pk_add_f32 v[232:233], v[232:233], v[40:41]
	v_pk_add_f32 v[232:233], v[232:233], v[42:43]
	v_pk_add_f32 v[232:233], v[232:233], v[44:45]
	v_pk_add_f32 v[232:233], v[232:233], v[46:47]
	ds_read2_b32 v[32:33], v115 offset0:136 offset1:137
	ds_read2_b32 v[34:35], v115 offset0:138 offset1:139
	ds_read2_b32 v[36:37], v115 offset0:144 offset1:145
	ds_read2_b32 v[38:39], v115 offset0:146 offset1:147
	ds_read2_b32 v[40:41], v115 offset0:153 offset1:154
	ds_read2_b32 v[42:43], v115 offset0:155 offset1:156
	ds_read2_b32 v[44:45], v115 offset0:161 offset1:162
	ds_read2_b32 v[46:47], v115 offset0:163 offset1:164
	v_mfma_f32_32x32x16_bf16 v[0:15], v[64:67], v[72:75], v[0:15]
	v_mfma_f32_32x32x16_bf16 v[16:31], v[64:67], v[76:79], v[16:31]
	v_mfma_f32_32x32x16_bf16 v[0:15], v[68:71], v[220:223], v[0:15]
	v_mfma_f32_32x32x16_bf16 v[16:31], v[68:71], v[224:227], v[16:31]
	global_load_dwordx4 v[156:159], v235, s[84:85]
	global_load_dwordx4 v[160:163], v236, s[84:85]
	global_load_dwordx4 v[164:167], v237, s[84:85]
	global_load_dwordx4 v[168:171], v238, s[84:85]
	global_load_dwordx4 v[172:175], v100, s[84:85] offset:768
	global_load_dwordx4 v[176:179], v149, s[84:85] offset:768
	global_load_dwordx4 v[180:183], v100, s[84:85] offset:832
	global_load_dwordx4 v[184:187], v149, s[84:85] offset:832
	ds_read_b64_tr_b16 v[72:73], v231
	ds_read_b64_tr_b16 v[74:75], v231 offset:512
	ds_read_b64_tr_b16 v[76:77], v231 offset:2048
	ds_read_b64_tr_b16 v[78:79], v231 offset:2560
	ds_read_b64_tr_b16 v[220:221], v231 offset:1024
	ds_read_b64_tr_b16 v[222:223], v231 offset:1536
	ds_read_b64_tr_b16 v[224:225], v231 offset:3072
	ds_read_b64_tr_b16 v[226:227], v231 offset:3584
	s_waitcnt vmcnt(8)
	ds_write_b128 v247, v[116:119]
	ds_write_b128 v247, v[120:123] offset:1024
	ds_write_b128 v247, v[124:127] offset:2048
	ds_write_b128 v247, v[128:131] offset:3072
	ds_read_b128 v[116:119], v248
	ds_read_b128 v[120:123], v249
	ds_read_b128 v[124:127], v250
	ds_read_b128 v[128:131], v251
	ds_write_b128 v112, v[132:135]
	ds_write_b128 v112, v[136:139] offset:1024
	ds_write_b128 v112, v[140:143] offset:2048
	ds_write_b128 v112, v[144:147] offset:3072
	s_waitcnt lgkmcnt(4)
	v_mfma_f32_32x32x16_bf16 v[32:47], v[116:119], v[48:51], v[32:47]
	v_exp_f32_e32 v188, v188
	v_exp_f32_e32 v189, v189
	v_exp_f32_e32 v190, v190
	v_exp_f32_e32 v191, v191
	v_mfma_f32_32x32x16_bf16 v[32:47], v[120:123], v[52:55], v[32:47]
	v_exp_f32_e32 v192, v192
	v_exp_f32_e32 v193, v193
	v_exp_f32_e32 v194, v194
	v_exp_f32_e32 v195, v195
	v_mfma_f32_32x32x16_bf16 v[32:47], v[124:127], v[56:59], v[32:47]
	v_exp_f32_e32 v196, v196
	v_exp_f32_e32 v197, v197
	v_exp_f32_e32 v198, v198
	v_exp_f32_e32 v199, v199
	v_mfma_f32_32x32x16_bf16 v[32:47], v[128:131], v[60:63], v[32:47]
	v_exp_f32_e32 v200, v200
	v_exp_f32_e32 v201, v201
	v_exp_f32_e32 v202, v202
	v_exp_f32_e32 v203, v203
	v_cvt_pk_bf16_f32 v64, v188, v189
	v_cvt_pk_bf16_f32 v65, v190, v191
	v_cvt_pk_bf16_f32 v66, v192, v193
	v_cvt_pk_bf16_f32 v67, v194, v195
	v_cvt_pk_bf16_f32 v68, v196, v197
	v_cvt_pk_bf16_f32 v69, v198, v199
	v_cvt_pk_bf16_f32 v70, v200, v201
	v_cvt_pk_bf16_f32 v71, v202, v203
	v_pk_add_f32 v[232:233], v[232:233], v[188:189]
	v_pk_add_f32 v[232:233], v[232:233], v[190:191]
	v_pk_add_f32 v[232:233], v[232:233], v[192:193]
	v_pk_add_f32 v[232:233], v[232:233], v[194:195]
	v_pk_add_f32 v[232:233], v[232:233], v[196:197]
	v_pk_add_f32 v[232:233], v[232:233], v[198:199]
	v_pk_add_f32 v[232:233], v[232:233], v[200:201]
	v_pk_add_f32 v[232:233], v[232:233], v[202:203]
	ds_read2_b32 v[188:189], v115 offset0:170 offset1:171
	ds_read2_b32 v[190:191], v115 offset0:172 offset1:173
	ds_read2_b32 v[192:193], v115 offset0:178 offset1:179
	ds_read2_b32 v[194:195], v115 offset0:180 offset1:181
	ds_read2_b32 v[196:197], v115 offset0:187 offset1:188
	ds_read2_b32 v[198:199], v115 offset0:189 offset1:190
	ds_read2_b32 v[200:201], v115 offset0:195 offset1:196
	ds_read2_b32 v[202:203], v115 offset0:197 offset1:198
	v_mfma_f32_32x32x16_bf16 v[0:15], v[64:67], v[72:75], v[0:15]
	v_mfma_f32_32x32x16_bf16 v[16:31], v[64:67], v[76:79], v[16:31]
	v_mfma_f32_32x32x16_bf16 v[0:15], v[68:71], v[220:223], v[0:15]
	v_mfma_f32_32x32x16_bf16 v[16:31], v[68:71], v[224:227], v[16:31]
	global_load_dwordx4 v[116:119], v239, s[86:87]
	global_load_dwordx4 v[120:123], v240, s[86:87]
	global_load_dwordx4 v[124:127], v241, s[86:87]
	global_load_dwordx4 v[128:131], v242, s[86:87]
	global_load_dwordx4 v[132:135], v101, s[86:87] offset:768
	global_load_dwordx4 v[136:139], v150, s[86:87] offset:768
	global_load_dwordx4 v[140:143], v101, s[86:87] offset:832
	global_load_dwordx4 v[144:147], v150, s[86:87] offset:832
	s_add_u32 s86, s86, 0xc0000
	s_addc_u32 s87, s87, 0
	ds_read_b64_tr_b16 v[72:73], v231
	ds_read_b64_tr_b16 v[74:75], v231 offset:512
	ds_read_b64_tr_b16 v[76:77], v231 offset:2048
	ds_read_b64_tr_b16 v[78:79], v231 offset:2560
	ds_read_b64_tr_b16 v[220:221], v231 offset:1024
	ds_read_b64_tr_b16 v[222:223], v231 offset:1536
	ds_read_b64_tr_b16 v[224:225], v231 offset:3072
	ds_read_b64_tr_b16 v[226:227], v231 offset:3584
	s_waitcnt vmcnt(8)
	ds_write_b128 v247, v[156:159]
	ds_write_b128 v247, v[160:163] offset:1024
	ds_write_b128 v247, v[164:167] offset:2048
	ds_write_b128 v247, v[168:171] offset:3072
	ds_read_b128 v[156:159], v248
	ds_read_b128 v[160:163], v249
	ds_read_b128 v[164:167], v250
	ds_read_b128 v[168:171], v251
	ds_write_b128 v112, v[172:175]
	ds_write_b128 v112, v[176:179] offset:1024
	ds_write_b128 v112, v[180:183] offset:2048
	ds_write_b128 v112, v[184:187] offset:3072
	s_waitcnt lgkmcnt(4)
	v_mfma_f32_32x32x16_bf16 v[188:203], v[156:159], v[48:51], v[188:203]
	v_exp_f32_e32 v32, v32
	v_exp_f32_e32 v33, v33
	v_exp_f32_e32 v34, v34
	v_exp_f32_e32 v35, v35
	v_mfma_f32_32x32x16_bf16 v[188:203], v[160:163], v[52:55], v[188:203]
	v_exp_f32_e32 v36, v36
	v_exp_f32_e32 v37, v37
	v_exp_f32_e32 v38, v38
	v_exp_f32_e32 v39, v39
	v_mfma_f32_32x32x16_bf16 v[188:203], v[164:167], v[56:59], v[188:203]
	v_exp_f32_e32 v40, v40
	v_exp_f32_e32 v41, v41
	v_exp_f32_e32 v42, v42
	v_exp_f32_e32 v43, v43
	v_mfma_f32_32x32x16_bf16 v[188:203], v[168:171], v[60:63], v[188:203]
	v_exp_f32_e32 v44, v44
	v_exp_f32_e32 v45, v45
	v_exp_f32_e32 v46, v46
	v_exp_f32_e32 v47, v47
	v_cvt_pk_bf16_f32 v64, v32, v33
	v_cvt_pk_bf16_f32 v65, v34, v35
	v_cvt_pk_bf16_f32 v66, v36, v37
	v_cvt_pk_bf16_f32 v67, v38, v39
	v_cvt_pk_bf16_f32 v68, v40, v41
	v_cvt_pk_bf16_f32 v69, v42, v43
	v_cvt_pk_bf16_f32 v70, v44, v45
	v_cvt_pk_bf16_f32 v71, v46, v47
	v_pk_add_f32 v[232:233], v[232:233], v[32:33]
	v_pk_add_f32 v[232:233], v[232:233], v[34:35]
	v_pk_add_f32 v[232:233], v[232:233], v[36:37]
	v_pk_add_f32 v[232:233], v[232:233], v[38:39]
	v_pk_add_f32 v[232:233], v[232:233], v[40:41]
	v_pk_add_f32 v[232:233], v[232:233], v[42:43]
	v_pk_add_f32 v[232:233], v[232:233], v[44:45]
	v_pk_add_f32 v[232:233], v[232:233], v[46:47]
	v_mov_b32_e32 v115, v229
	ds_read2_b32 v[32:33], v115 offset0:0 offset1:1
	ds_read2_b32 v[34:35], v115 offset0:2 offset1:3
	ds_read2_b32 v[36:37], v115 offset0:8 offset1:9
	ds_read2_b32 v[38:39], v115 offset0:10 offset1:11
	ds_read2_b32 v[40:41], v115 offset0:16 offset1:17
	ds_read2_b32 v[42:43], v115 offset0:18 offset1:19
	ds_read2_b32 v[44:45], v115 offset0:24 offset1:25
	ds_read2_b32 v[46:47], v115 offset0:26 offset1:27
	v_mfma_f32_32x32x16_bf16 v[0:15], v[64:67], v[72:75], v[0:15]
	v_mfma_f32_32x32x16_bf16 v[16:31], v[64:67], v[76:79], v[16:31]
	v_mfma_f32_32x32x16_bf16 v[0:15], v[68:71], v[220:223], v[0:15]
	v_mfma_f32_32x32x16_bf16 v[16:31], v[68:71], v[224:227], v[16:31]
	global_load_dwordx4 v[156:159], v239, s[86:87]
	global_load_dwordx4 v[160:163], v240, s[86:87]
	global_load_dwordx4 v[164:167], v241, s[86:87]
	global_load_dwordx4 v[168:171], v242, s[86:87]
	global_load_dwordx4 v[172:175], v101, s[86:87] offset:768
	global_load_dwordx4 v[176:179], v150, s[86:87] offset:768
	global_load_dwordx4 v[180:183], v101, s[86:87] offset:832
	global_load_dwordx4 v[184:187], v150, s[86:87] offset:832
	s_add_u32 s86, s86, 0xc0000
	s_addc_u32 s87, s87, 0
	ds_read_b64_tr_b16 v[72:73], v231
	ds_read_b64_tr_b16 v[74:75], v231 offset:512
	ds_read_b64_tr_b16 v[76:77], v231 offset:2048
	ds_read_b64_tr_b16 v[78:79], v231 offset:2560
	ds_read_b64_tr_b16 v[220:221], v231 offset:1024
	ds_read_b64_tr_b16 v[222:223], v231 offset:1536
	ds_read_b64_tr_b16 v[224:225], v231 offset:3072
	ds_read_b64_tr_b16 v[226:227], v231 offset:3584
	s_waitcnt vmcnt(8)
	ds_write_b128 v247, v[116:119]
	ds_write_b128 v247, v[120:123] offset:1024
	ds_write_b128 v247, v[124:127] offset:2048
	ds_write_b128 v247, v[128:131] offset:3072
	ds_read_b128 v[116:119], v248
	ds_read_b128 v[120:123], v249
	ds_read_b128 v[124:127], v250
	ds_read_b128 v[128:131], v251
	ds_write_b128 v112, v[132:135]
	ds_write_b128 v112, v[136:139] offset:1024
	ds_write_b128 v112, v[140:143] offset:2048
	ds_write_b128 v112, v[144:147] offset:3072
	s_waitcnt lgkmcnt(4)
	v_mfma_f32_32x32x16_bf16 v[32:47], v[116:119], v[48:51], v[32:47]
	v_exp_f32_e32 v188, v188
	v_exp_f32_e32 v189, v189
	v_exp_f32_e32 v190, v190
	v_exp_f32_e32 v191, v191
	v_mfma_f32_32x32x16_bf16 v[32:47], v[120:123], v[52:55], v[32:47]
	v_exp_f32_e32 v192, v192
	v_exp_f32_e32 v193, v193
	v_exp_f32_e32 v194, v194
	v_exp_f32_e32 v195, v195
	v_mfma_f32_32x32x16_bf16 v[32:47], v[124:127], v[56:59], v[32:47]
	v_exp_f32_e32 v196, v196
	v_exp_f32_e32 v197, v197
	v_exp_f32_e32 v198, v198
	v_exp_f32_e32 v199, v199
	v_mfma_f32_32x32x16_bf16 v[32:47], v[128:131], v[60:63], v[32:47]
	v_exp_f32_e32 v200, v200
	v_exp_f32_e32 v201, v201
	v_exp_f32_e32 v202, v202
	v_exp_f32_e32 v203, v203
	v_cvt_pk_bf16_f32 v64, v188, v189
	v_cvt_pk_bf16_f32 v65, v190, v191
	v_cvt_pk_bf16_f32 v66, v192, v193
	v_cvt_pk_bf16_f32 v67, v194, v195
	v_cvt_pk_bf16_f32 v68, v196, v197
	v_cvt_pk_bf16_f32 v69, v198, v199
	v_cvt_pk_bf16_f32 v70, v200, v201
	v_cvt_pk_bf16_f32 v71, v202, v203
	v_pk_add_f32 v[232:233], v[232:233], v[188:189]
	v_pk_add_f32 v[232:233], v[232:233], v[190:191]
	v_pk_add_f32 v[232:233], v[232:233], v[192:193]
	v_pk_add_f32 v[232:233], v[232:233], v[194:195]
	v_pk_add_f32 v[232:233], v[232:233], v[196:197]
	v_pk_add_f32 v[232:233], v[232:233], v[198:199]
	v_pk_add_f32 v[232:233], v[232:233], v[200:201]
	v_pk_add_f32 v[232:233], v[232:233], v[202:203]
	ds_read2_b32 v[188:189], v115 offset0:32 offset1:33
	ds_read2_b32 v[190:191], v115 offset0:34 offset1:35
	ds_read2_b32 v[192:193], v115 offset0:40 offset1:41
	ds_read2_b32 v[194:195], v115 offset0:42 offset1:43
	ds_read2_b32 v[196:197], v115 offset0:48 offset1:49
	ds_read2_b32 v[198:199], v115 offset0:50 offset1:51
	ds_read2_b32 v[200:201], v115 offset0:56 offset1:57
	ds_read2_b32 v[202:203], v115 offset0:58 offset1:59
	v_mfma_f32_32x32x16_bf16 v[0:15], v[64:67], v[72:75], v[0:15]
	v_mfma_f32_32x32x16_bf16 v[16:31], v[64:67], v[76:79], v[16:31]
	v_mfma_f32_32x32x16_bf16 v[0:15], v[68:71], v[220:223], v[0:15]
	v_mfma_f32_32x32x16_bf16 v[16:31], v[68:71], v[224:227], v[16:31]
	global_load_dwordx4 v[116:119], v239, s[86:87]
	global_load_dwordx4 v[120:123], v240, s[86:87]
	global_load_dwordx4 v[124:127], v241, s[86:87]
	global_load_dwordx4 v[128:131], v242, s[86:87]
	global_load_dwordx4 v[132:135], v101, s[86:87] offset:768
	global_load_dwordx4 v[136:139], v150, s[86:87] offset:768
	global_load_dwordx4 v[140:143], v101, s[86:87] offset:832
	global_load_dwordx4 v[144:147], v150, s[86:87] offset:832
	s_add_u32 s86, s86, 0xc0000
	s_addc_u32 s87, s87, 0
	ds_read_b64_tr_b16 v[72:73], v231
	ds_read_b64_tr_b16 v[74:75], v231 offset:512
	ds_read_b64_tr_b16 v[76:77], v231 offset:2048
	ds_read_b64_tr_b16 v[78:79], v231 offset:2560
	ds_read_b64_tr_b16 v[220:221], v231 offset:1024
	ds_read_b64_tr_b16 v[222:223], v231 offset:1536
	ds_read_b64_tr_b16 v[224:225], v231 offset:3072
	ds_read_b64_tr_b16 v[226:227], v231 offset:3584
	s_waitcnt vmcnt(8)
	ds_write_b128 v247, v[156:159]
	ds_write_b128 v247, v[160:163] offset:1024
	ds_write_b128 v247, v[164:167] offset:2048
	ds_write_b128 v247, v[168:171] offset:3072
	ds_read_b128 v[156:159], v248
	ds_read_b128 v[160:163], v249
	ds_read_b128 v[164:167], v250
	ds_read_b128 v[168:171], v251
	ds_write_b128 v112, v[172:175]
	ds_write_b128 v112, v[176:179] offset:1024
	ds_write_b128 v112, v[180:183] offset:2048
	ds_write_b128 v112, v[184:187] offset:3072
	s_waitcnt lgkmcnt(4)
	v_mfma_f32_32x32x16_bf16 v[188:203], v[156:159], v[48:51], v[188:203]
	v_exp_f32_e32 v32, v32
	v_exp_f32_e32 v33, v33
	v_exp_f32_e32 v34, v34
	v_exp_f32_e32 v35, v35
	v_mfma_f32_32x32x16_bf16 v[188:203], v[160:163], v[52:55], v[188:203]
	v_exp_f32_e32 v36, v36
	v_exp_f32_e32 v37, v37
	v_exp_f32_e32 v38, v38
	v_exp_f32_e32 v39, v39
	v_mfma_f32_32x32x16_bf16 v[188:203], v[164:167], v[56:59], v[188:203]
	v_exp_f32_e32 v40, v40
	v_exp_f32_e32 v41, v41
	v_exp_f32_e32 v42, v42
	v_exp_f32_e32 v43, v43
	v_mfma_f32_32x32x16_bf16 v[188:203], v[168:171], v[60:63], v[188:203]
	v_exp_f32_e32 v44, v44
	v_exp_f32_e32 v45, v45
	v_exp_f32_e32 v46, v46
	v_exp_f32_e32 v47, v47
	v_cvt_pk_bf16_f32 v64, v32, v33
	v_cvt_pk_bf16_f32 v65, v34, v35
	v_cvt_pk_bf16_f32 v66, v36, v37
	v_cvt_pk_bf16_f32 v67, v38, v39
	v_cvt_pk_bf16_f32 v68, v40, v41
	v_cvt_pk_bf16_f32 v69, v42, v43
	v_cvt_pk_bf16_f32 v70, v44, v45
	v_cvt_pk_bf16_f32 v71, v46, v47
	v_pk_add_f32 v[232:233], v[232:233], v[32:33]
	v_pk_add_f32 v[232:233], v[232:233], v[34:35]
	v_pk_add_f32 v[232:233], v[232:233], v[36:37]
	v_pk_add_f32 v[232:233], v[232:233], v[38:39]
	v_pk_add_f32 v[232:233], v[232:233], v[40:41]
	v_pk_add_f32 v[232:233], v[232:233], v[42:43]
	v_pk_add_f32 v[232:233], v[232:233], v[44:45]
	v_pk_add_f32 v[232:233], v[232:233], v[46:47]
	ds_read2_b32 v[32:33], v115 offset0:64 offset1:65
	ds_read2_b32 v[34:35], v115 offset0:66 offset1:67
	ds_read2_b32 v[36:37], v115 offset0:72 offset1:73
	ds_read2_b32 v[38:39], v115 offset0:74 offset1:75
	ds_read2_b32 v[40:41], v115 offset0:80 offset1:81
	ds_read2_b32 v[42:43], v115 offset0:82 offset1:83
	ds_read2_b32 v[44:45], v115 offset0:88 offset1:89
	ds_read2_b32 v[46:47], v115 offset0:90 offset1:91
	v_mfma_f32_32x32x16_bf16 v[0:15], v[64:67], v[72:75], v[0:15]
	v_mfma_f32_32x32x16_bf16 v[16:31], v[64:67], v[76:79], v[16:31]
	v_mfma_f32_32x32x16_bf16 v[0:15], v[68:71], v[220:223], v[0:15]
	v_mfma_f32_32x32x16_bf16 v[16:31], v[68:71], v[224:227], v[16:31]
	global_load_dwordx4 v[156:159], v239, s[86:87]
	global_load_dwordx4 v[160:163], v240, s[86:87]
	global_load_dwordx4 v[164:167], v241, s[86:87]
	global_load_dwordx4 v[168:171], v242, s[86:87]
	global_load_dwordx4 v[172:175], v101, s[86:87] offset:768
	global_load_dwordx4 v[176:179], v150, s[86:87] offset:768
	global_load_dwordx4 v[180:183], v101, s[86:87] offset:832
	global_load_dwordx4 v[184:187], v150, s[86:87] offset:832
	s_add_u32 s86, s86, 0xc0000
	s_addc_u32 s87, s87, 0
	ds_read_b64_tr_b16 v[72:73], v231
	ds_read_b64_tr_b16 v[74:75], v231 offset:512
	ds_read_b64_tr_b16 v[76:77], v231 offset:2048
	ds_read_b64_tr_b16 v[78:79], v231 offset:2560
	ds_read_b64_tr_b16 v[220:221], v231 offset:1024
	ds_read_b64_tr_b16 v[222:223], v231 offset:1536
	ds_read_b64_tr_b16 v[224:225], v231 offset:3072
	ds_read_b64_tr_b16 v[226:227], v231 offset:3584
	s_waitcnt vmcnt(8)
	ds_write_b128 v247, v[116:119]
	ds_write_b128 v247, v[120:123] offset:1024
	ds_write_b128 v247, v[124:127] offset:2048
	ds_write_b128 v247, v[128:131] offset:3072
	ds_read_b128 v[116:119], v248
	ds_read_b128 v[120:123], v249
	ds_read_b128 v[124:127], v250
	ds_read_b128 v[128:131], v251
	ds_write_b128 v112, v[132:135]
	ds_write_b128 v112, v[136:139] offset:1024
	ds_write_b128 v112, v[140:143] offset:2048
	ds_write_b128 v112, v[144:147] offset:3072
	s_waitcnt lgkmcnt(4)
	v_mfma_f32_32x32x16_bf16 v[32:47], v[116:119], v[48:51], v[32:47]
	v_exp_f32_e32 v188, v188
	v_exp_f32_e32 v189, v189
	v_exp_f32_e32 v190, v190
	v_exp_f32_e32 v191, v191
	v_mfma_f32_32x32x16_bf16 v[32:47], v[120:123], v[52:55], v[32:47]
	v_exp_f32_e32 v192, v192
	v_exp_f32_e32 v193, v193
	v_exp_f32_e32 v194, v194
	v_exp_f32_e32 v195, v195
	v_mfma_f32_32x32x16_bf16 v[32:47], v[124:127], v[56:59], v[32:47]
	v_exp_f32_e32 v196, v196
	v_exp_f32_e32 v197, v197
	v_exp_f32_e32 v198, v198
	v_exp_f32_e32 v199, v199
	v_mfma_f32_32x32x16_bf16 v[32:47], v[128:131], v[60:63], v[32:47]
	v_exp_f32_e32 v200, v200
	v_exp_f32_e32 v201, v201
	v_exp_f32_e32 v202, v202
	v_exp_f32_e32 v203, v203
	v_cvt_pk_bf16_f32 v64, v188, v189
	v_cvt_pk_bf16_f32 v65, v190, v191
	v_cvt_pk_bf16_f32 v66, v192, v193
	v_cvt_pk_bf16_f32 v67, v194, v195
	v_cvt_pk_bf16_f32 v68, v196, v197
	v_cvt_pk_bf16_f32 v69, v198, v199
	v_cvt_pk_bf16_f32 v70, v200, v201
	v_cvt_pk_bf16_f32 v71, v202, v203
	v_pk_add_f32 v[232:233], v[232:233], v[188:189]
	v_pk_add_f32 v[232:233], v[232:233], v[190:191]
	v_pk_add_f32 v[232:233], v[232:233], v[192:193]
	v_pk_add_f32 v[232:233], v[232:233], v[194:195]
	v_pk_add_f32 v[232:233], v[232:233], v[196:197]
	v_pk_add_f32 v[232:233], v[232:233], v[198:199]
	v_pk_add_f32 v[232:233], v[232:233], v[200:201]
	v_pk_add_f32 v[232:233], v[232:233], v[202:203]
	ds_read2_b32 v[188:189], v115 offset0:96 offset1:97
	ds_read2_b32 v[190:191], v115 offset0:98 offset1:99
	ds_read2_b32 v[192:193], v115 offset0:104 offset1:105
	ds_read2_b32 v[194:195], v115 offset0:106 offset1:107
	ds_read2_b32 v[196:197], v115 offset0:112 offset1:113
	ds_read2_b32 v[198:199], v115 offset0:114 offset1:115
	ds_read2_b32 v[200:201], v115 offset0:120 offset1:121
	ds_read2_b32 v[202:203], v115 offset0:122 offset1:123
	v_mfma_f32_32x32x16_bf16 v[0:15], v[64:67], v[72:75], v[0:15]
	v_mfma_f32_32x32x16_bf16 v[16:31], v[64:67], v[76:79], v[16:31]
	v_mfma_f32_32x32x16_bf16 v[0:15], v[68:71], v[220:223], v[0:15]
	v_mfma_f32_32x32x16_bf16 v[16:31], v[68:71], v[224:227], v[16:31]
	global_load_dwordx4 v[116:119], v239, s[86:87]
	global_load_dwordx4 v[120:123], v240, s[86:87]
	global_load_dwordx4 v[124:127], v241, s[86:87]
	global_load_dwordx4 v[128:131], v242, s[86:87]
	global_load_dwordx4 v[132:135], v101, s[86:87] offset:768
	global_load_dwordx4 v[136:139], v150, s[86:87] offset:768
	global_load_dwordx4 v[140:143], v101, s[86:87] offset:832
	global_load_dwordx4 v[144:147], v150, s[86:87] offset:832
	s_add_u32 s86, s86, 0xc0000
	s_addc_u32 s87, s87, 0
	ds_read_b64_tr_b16 v[72:73], v231
	ds_read_b64_tr_b16 v[74:75], v231 offset:512
	ds_read_b64_tr_b16 v[76:77], v231 offset:2048
	ds_read_b64_tr_b16 v[78:79], v231 offset:2560
	ds_read_b64_tr_b16 v[220:221], v231 offset:1024
	ds_read_b64_tr_b16 v[222:223], v231 offset:1536
	ds_read_b64_tr_b16 v[224:225], v231 offset:3072
	ds_read_b64_tr_b16 v[226:227], v231 offset:3584
	s_waitcnt vmcnt(8)
	ds_write_b128 v247, v[156:159]
	ds_write_b128 v247, v[160:163] offset:1024
	ds_write_b128 v247, v[164:167] offset:2048
	ds_write_b128 v247, v[168:171] offset:3072
	ds_read_b128 v[156:159], v248
	ds_read_b128 v[160:163], v249
	ds_read_b128 v[164:167], v250
	ds_read_b128 v[168:171], v251
	ds_write_b128 v112, v[172:175]
	ds_write_b128 v112, v[176:179] offset:1024
	ds_write_b128 v112, v[180:183] offset:2048
	ds_write_b128 v112, v[184:187] offset:3072
	s_waitcnt lgkmcnt(4)
	v_mfma_f32_32x32x16_bf16 v[188:203], v[156:159], v[48:51], v[188:203]
	v_exp_f32_e32 v32, v32
	v_exp_f32_e32 v33, v33
	v_exp_f32_e32 v34, v34
	v_exp_f32_e32 v35, v35
	v_mfma_f32_32x32x16_bf16 v[188:203], v[160:163], v[52:55], v[188:203]
	v_exp_f32_e32 v36, v36
	v_exp_f32_e32 v37, v37
	v_exp_f32_e32 v38, v38
	v_exp_f32_e32 v39, v39
	v_mfma_f32_32x32x16_bf16 v[188:203], v[164:167], v[56:59], v[188:203]
	v_exp_f32_e32 v40, v40
	v_exp_f32_e32 v41, v41
	v_exp_f32_e32 v42, v42
	v_exp_f32_e32 v43, v43
	v_mfma_f32_32x32x16_bf16 v[188:203], v[168:171], v[60:63], v[188:203]
	v_exp_f32_e32 v44, v44
	v_exp_f32_e32 v45, v45
	v_exp_f32_e32 v46, v46
	v_exp_f32_e32 v47, v47
	v_cvt_pk_bf16_f32 v64, v32, v33
	v_cvt_pk_bf16_f32 v65, v34, v35
	v_cvt_pk_bf16_f32 v66, v36, v37
	v_cvt_pk_bf16_f32 v67, v38, v39
	v_cvt_pk_bf16_f32 v68, v40, v41
	v_cvt_pk_bf16_f32 v69, v42, v43
	v_cvt_pk_bf16_f32 v70, v44, v45
	v_cvt_pk_bf16_f32 v71, v46, v47
	v_pk_add_f32 v[232:233], v[232:233], v[32:33]
	v_pk_add_f32 v[232:233], v[232:233], v[34:35]
	v_pk_add_f32 v[232:233], v[232:233], v[36:37]
	v_pk_add_f32 v[232:233], v[232:233], v[38:39]
	v_pk_add_f32 v[232:233], v[232:233], v[40:41]
	v_pk_add_f32 v[232:233], v[232:233], v[42:43]
	v_pk_add_f32 v[232:233], v[232:233], v[44:45]
	v_pk_add_f32 v[232:233], v[232:233], v[46:47]
	ds_read2_b32 v[32:33], v115 offset0:128 offset1:129
	ds_read2_b32 v[34:35], v115 offset0:130 offset1:131
	ds_read2_b32 v[36:37], v115 offset0:136 offset1:137
	ds_read2_b32 v[38:39], v115 offset0:138 offset1:139
	ds_read2_b32 v[40:41], v115 offset0:144 offset1:145
	ds_read2_b32 v[42:43], v115 offset0:146 offset1:147
	ds_read2_b32 v[44:45], v115 offset0:152 offset1:153
	ds_read2_b32 v[46:47], v115 offset0:154 offset1:155
	v_mfma_f32_32x32x16_bf16 v[0:15], v[64:67], v[72:75], v[0:15]
	v_mfma_f32_32x32x16_bf16 v[16:31], v[64:67], v[76:79], v[16:31]
	v_mfma_f32_32x32x16_bf16 v[0:15], v[68:71], v[220:223], v[0:15]
	v_mfma_f32_32x32x16_bf16 v[16:31], v[68:71], v[224:227], v[16:31]
	global_load_dwordx4 v[156:159], v239, s[86:87]
	global_load_dwordx4 v[160:163], v240, s[86:87]
	global_load_dwordx4 v[164:167], v241, s[86:87]
	global_load_dwordx4 v[168:171], v242, s[86:87]
	global_load_dwordx4 v[172:175], v101, s[86:87] offset:768
	global_load_dwordx4 v[176:179], v150, s[86:87] offset:768
	global_load_dwordx4 v[180:183], v101, s[86:87] offset:832
	global_load_dwordx4 v[184:187], v150, s[86:87] offset:832
	s_add_u32 s86, s86, 0xc0000
	s_addc_u32 s87, s87, 0
	ds_read_b64_tr_b16 v[72:73], v231
	ds_read_b64_tr_b16 v[74:75], v231 offset:512
	ds_read_b64_tr_b16 v[76:77], v231 offset:2048
	ds_read_b64_tr_b16 v[78:79], v231 offset:2560
	ds_read_b64_tr_b16 v[220:221], v231 offset:1024
	ds_read_b64_tr_b16 v[222:223], v231 offset:1536
	ds_read_b64_tr_b16 v[224:225], v231 offset:3072
	ds_read_b64_tr_b16 v[226:227], v231 offset:3584
	s_waitcnt vmcnt(8)
	ds_write_b128 v247, v[116:119]
	ds_write_b128 v247, v[120:123] offset:1024
	ds_write_b128 v247, v[124:127] offset:2048
	ds_write_b128 v247, v[128:131] offset:3072
	ds_read_b128 v[116:119], v248
	ds_read_b128 v[120:123], v249
	ds_read_b128 v[124:127], v250
	ds_read_b128 v[128:131], v251
	ds_write_b128 v112, v[132:135]
	ds_write_b128 v112, v[136:139] offset:1024
	ds_write_b128 v112, v[140:143] offset:2048
	ds_write_b128 v112, v[144:147] offset:3072
	s_waitcnt lgkmcnt(4)
	v_mfma_f32_32x32x16_bf16 v[32:47], v[116:119], v[48:51], v[32:47]
	v_exp_f32_e32 v188, v188
	v_exp_f32_e32 v189, v189
	v_exp_f32_e32 v190, v190
	v_exp_f32_e32 v191, v191
	v_mfma_f32_32x32x16_bf16 v[32:47], v[120:123], v[52:55], v[32:47]
	v_exp_f32_e32 v192, v192
	v_exp_f32_e32 v193, v193
	v_exp_f32_e32 v194, v194
	v_exp_f32_e32 v195, v195
	v_mfma_f32_32x32x16_bf16 v[32:47], v[124:127], v[56:59], v[32:47]
	v_exp_f32_e32 v196, v196
	v_exp_f32_e32 v197, v197
	v_exp_f32_e32 v198, v198
	v_exp_f32_e32 v199, v199
	v_mfma_f32_32x32x16_bf16 v[32:47], v[128:131], v[60:63], v[32:47]
	v_exp_f32_e32 v200, v200
	v_exp_f32_e32 v201, v201
	v_exp_f32_e32 v202, v202
	v_exp_f32_e32 v203, v203
	v_cvt_pk_bf16_f32 v64, v188, v189
	v_cvt_pk_bf16_f32 v65, v190, v191
	v_cvt_pk_bf16_f32 v66, v192, v193
	v_cvt_pk_bf16_f32 v67, v194, v195
	v_cvt_pk_bf16_f32 v68, v196, v197
	v_cvt_pk_bf16_f32 v69, v198, v199
	v_cvt_pk_bf16_f32 v70, v200, v201
	v_cvt_pk_bf16_f32 v71, v202, v203
	v_pk_add_f32 v[232:233], v[232:233], v[188:189]
	v_pk_add_f32 v[232:233], v[232:233], v[190:191]
	v_pk_add_f32 v[232:233], v[232:233], v[192:193]
	v_pk_add_f32 v[232:233], v[232:233], v[194:195]
	v_pk_add_f32 v[232:233], v[232:233], v[196:197]
	v_pk_add_f32 v[232:233], v[232:233], v[198:199]
	v_pk_add_f32 v[232:233], v[232:233], v[200:201]
	v_pk_add_f32 v[232:233], v[232:233], v[202:203]
	ds_read2_b32 v[188:189], v115 offset0:160 offset1:161
	ds_read2_b32 v[190:191], v115 offset0:162 offset1:163
	ds_read2_b32 v[192:193], v115 offset0:168 offset1:169
	ds_read2_b32 v[194:195], v115 offset0:170 offset1:171
	ds_read2_b32 v[196:197], v115 offset0:176 offset1:177
	ds_read2_b32 v[198:199], v115 offset0:178 offset1:179
	ds_read2_b32 v[200:201], v115 offset0:184 offset1:185
	ds_read2_b32 v[202:203], v115 offset0:186 offset1:187
	v_mfma_f32_32x32x16_bf16 v[0:15], v[64:67], v[72:75], v[0:15]
	v_mfma_f32_32x32x16_bf16 v[16:31], v[64:67], v[76:79], v[16:31]
	v_mfma_f32_32x32x16_bf16 v[0:15], v[68:71], v[220:223], v[0:15]
	v_mfma_f32_32x32x16_bf16 v[16:31], v[68:71], v[224:227], v[16:31]
	global_load_dwordx4 v[116:119], v239, s[86:87]
	global_load_dwordx4 v[120:123], v240, s[86:87]
	global_load_dwordx4 v[124:127], v241, s[86:87]
	global_load_dwordx4 v[128:131], v242, s[86:87]
	global_load_dwordx4 v[132:135], v101, s[86:87] offset:768
	global_load_dwordx4 v[136:139], v150, s[86:87] offset:768
	global_load_dwordx4 v[140:143], v101, s[86:87] offset:832
	global_load_dwordx4 v[144:147], v150, s[86:87] offset:832
	s_add_u32 s86, s86, 0xc0000
	s_addc_u32 s87, s87, 0
	ds_read_b64_tr_b16 v[72:73], v231
	ds_read_b64_tr_b16 v[74:75], v231 offset:512
	ds_read_b64_tr_b16 v[76:77], v231 offset:2048
	ds_read_b64_tr_b16 v[78:79], v231 offset:2560
	ds_read_b64_tr_b16 v[220:221], v231 offset:1024
	ds_read_b64_tr_b16 v[222:223], v231 offset:1536
	ds_read_b64_tr_b16 v[224:225], v231 offset:3072
	ds_read_b64_tr_b16 v[226:227], v231 offset:3584
	s_waitcnt vmcnt(8)
	ds_write_b128 v247, v[156:159]
	ds_write_b128 v247, v[160:163] offset:1024
	ds_write_b128 v247, v[164:167] offset:2048
	ds_write_b128 v247, v[168:171] offset:3072
	ds_read_b128 v[156:159], v248
	ds_read_b128 v[160:163], v249
	ds_read_b128 v[164:167], v250
	ds_read_b128 v[168:171], v251
	ds_write_b128 v112, v[172:175]
	ds_write_b128 v112, v[176:179] offset:1024
	ds_write_b128 v112, v[180:183] offset:2048
	ds_write_b128 v112, v[184:187] offset:3072
	s_waitcnt lgkmcnt(4)
	v_mfma_f32_32x32x16_bf16 v[188:203], v[156:159], v[48:51], v[188:203]
	v_exp_f32_e32 v32, v32
	v_exp_f32_e32 v33, v33
	v_exp_f32_e32 v34, v34
	v_exp_f32_e32 v35, v35
	v_mfma_f32_32x32x16_bf16 v[188:203], v[160:163], v[52:55], v[188:203]
	v_exp_f32_e32 v36, v36
	v_exp_f32_e32 v37, v37
	v_exp_f32_e32 v38, v38
	v_exp_f32_e32 v39, v39
	v_mfma_f32_32x32x16_bf16 v[188:203], v[164:167], v[56:59], v[188:203]
	v_exp_f32_e32 v40, v40
	v_exp_f32_e32 v41, v41
	v_exp_f32_e32 v42, v42
	v_exp_f32_e32 v43, v43
	v_mfma_f32_32x32x16_bf16 v[188:203], v[168:171], v[60:63], v[188:203]
	v_exp_f32_e32 v44, v44
	v_exp_f32_e32 v45, v45
	v_exp_f32_e32 v46, v46
	v_exp_f32_e32 v47, v47
	v_cvt_pk_bf16_f32 v64, v32, v33
	v_cvt_pk_bf16_f32 v65, v34, v35
	v_cvt_pk_bf16_f32 v66, v36, v37
	v_cvt_pk_bf16_f32 v67, v38, v39
	v_cvt_pk_bf16_f32 v68, v40, v41
	v_cvt_pk_bf16_f32 v69, v42, v43
	v_cvt_pk_bf16_f32 v70, v44, v45
	v_cvt_pk_bf16_f32 v71, v46, v47
	v_pk_add_f32 v[232:233], v[232:233], v[32:33]
	v_pk_add_f32 v[232:233], v[232:233], v[34:35]
	v_pk_add_f32 v[232:233], v[232:233], v[36:37]
	v_pk_add_f32 v[232:233], v[232:233], v[38:39]
	v_pk_add_f32 v[232:233], v[232:233], v[40:41]
	v_pk_add_f32 v[232:233], v[232:233], v[42:43]
	v_pk_add_f32 v[232:233], v[232:233], v[44:45]
	v_pk_add_f32 v[232:233], v[232:233], v[46:47]
	ds_read2_b32 v[32:33], v115 offset0:192 offset1:193
	ds_read2_b32 v[34:35], v115 offset0:194 offset1:195
	ds_read2_b32 v[36:37], v115 offset0:200 offset1:201
	ds_read2_b32 v[38:39], v115 offset0:202 offset1:203
	ds_read2_b32 v[40:41], v115 offset0:208 offset1:209
	ds_read2_b32 v[42:43], v115 offset0:210 offset1:211
	ds_read2_b32 v[44:45], v115 offset0:216 offset1:217
	ds_read2_b32 v[46:47], v115 offset0:218 offset1:219
	v_mfma_f32_32x32x16_bf16 v[0:15], v[64:67], v[72:75], v[0:15]
	v_mfma_f32_32x32x16_bf16 v[16:31], v[64:67], v[76:79], v[16:31]
	v_mfma_f32_32x32x16_bf16 v[0:15], v[68:71], v[220:223], v[0:15]
	v_mfma_f32_32x32x16_bf16 v[16:31], v[68:71], v[224:227], v[16:31]
	global_load_dwordx4 v[156:159], v239, s[86:87]
	global_load_dwordx4 v[160:163], v240, s[86:87]
	global_load_dwordx4 v[164:167], v241, s[86:87]
	global_load_dwordx4 v[168:171], v242, s[86:87]
	global_load_dwordx4 v[172:175], v101, s[86:87] offset:768
	global_load_dwordx4 v[176:179], v150, s[86:87] offset:768
	global_load_dwordx4 v[180:183], v101, s[86:87] offset:832
	global_load_dwordx4 v[184:187], v150, s[86:87] offset:832
	ds_read_b64_tr_b16 v[72:73], v231
	ds_read_b64_tr_b16 v[74:75], v231 offset:512
	ds_read_b64_tr_b16 v[76:77], v231 offset:2048
	ds_read_b64_tr_b16 v[78:79], v231 offset:2560
	ds_read_b64_tr_b16 v[220:221], v231 offset:1024
	ds_read_b64_tr_b16 v[222:223], v231 offset:1536
	ds_read_b64_tr_b16 v[224:225], v231 offset:3072
	ds_read_b64_tr_b16 v[226:227], v231 offset:3584
	s_waitcnt vmcnt(8)
	ds_write_b128 v247, v[116:119]
	ds_write_b128 v247, v[120:123] offset:1024
	ds_write_b128 v247, v[124:127] offset:2048
	ds_write_b128 v247, v[128:131] offset:3072
	ds_read_b128 v[116:119], v248
	ds_read_b128 v[120:123], v249
	ds_read_b128 v[124:127], v250
	ds_read_b128 v[128:131], v251
	ds_write_b128 v112, v[132:135]
	ds_write_b128 v112, v[136:139] offset:1024
	ds_write_b128 v112, v[140:143] offset:2048
	ds_write_b128 v112, v[144:147] offset:3072
	s_waitcnt lgkmcnt(4)
	v_mfma_f32_32x32x16_bf16 v[32:47], v[116:119], v[48:51], v[32:47]
	v_exp_f32_e32 v188, v188
	v_exp_f32_e32 v189, v189
	v_exp_f32_e32 v190, v190
	v_exp_f32_e32 v191, v191
	v_mfma_f32_32x32x16_bf16 v[32:47], v[120:123], v[52:55], v[32:47]
	v_exp_f32_e32 v192, v192
	v_exp_f32_e32 v193, v193
	v_exp_f32_e32 v194, v194
	v_exp_f32_e32 v195, v195
	v_mfma_f32_32x32x16_bf16 v[32:47], v[124:127], v[56:59], v[32:47]
	v_exp_f32_e32 v196, v196
	v_exp_f32_e32 v197, v197
	v_exp_f32_e32 v198, v198
	v_exp_f32_e32 v199, v199
	v_mfma_f32_32x32x16_bf16 v[32:47], v[128:131], v[60:63], v[32:47]
	v_exp_f32_e32 v200, v200
	v_exp_f32_e32 v201, v201
	v_exp_f32_e32 v202, v202
	v_exp_f32_e32 v203, v203
	v_cvt_pk_bf16_f32 v64, v188, v189
	v_cvt_pk_bf16_f32 v65, v190, v191
	v_cvt_pk_bf16_f32 v66, v192, v193
	v_cvt_pk_bf16_f32 v67, v194, v195
	v_cvt_pk_bf16_f32 v68, v196, v197
	v_cvt_pk_bf16_f32 v69, v198, v199
	v_cvt_pk_bf16_f32 v70, v200, v201
	v_cvt_pk_bf16_f32 v71, v202, v203
	v_pk_add_f32 v[232:233], v[232:233], v[188:189]
	v_pk_add_f32 v[232:233], v[232:233], v[190:191]
	v_pk_add_f32 v[232:233], v[232:233], v[192:193]
	v_pk_add_f32 v[232:233], v[232:233], v[194:195]
	v_pk_add_f32 v[232:233], v[232:233], v[196:197]
	v_pk_add_f32 v[232:233], v[232:233], v[198:199]
	v_pk_add_f32 v[232:233], v[232:233], v[200:201]
	v_pk_add_f32 v[232:233], v[232:233], v[202:203]
	ds_read2_b32 v[188:189], v115 offset0:224 offset1:225
	ds_read2_b32 v[190:191], v115 offset0:226 offset1:227
	ds_read2_b32 v[192:193], v115 offset0:232 offset1:233
	ds_read2_b32 v[194:195], v115 offset0:234 offset1:235
	ds_read2_b32 v[196:197], v115 offset0:240 offset1:241
	ds_read2_b32 v[198:199], v115 offset0:242 offset1:243
	ds_read2_b32 v[200:201], v115 offset0:248 offset1:249
	ds_read2_b32 v[202:203], v115 offset0:250 offset1:251
	v_mfma_f32_32x32x16_bf16 v[0:15], v[64:67], v[72:75], v[0:15]
	v_mfma_f32_32x32x16_bf16 v[16:31], v[64:67], v[76:79], v[16:31]
	v_mfma_f32_32x32x16_bf16 v[0:15], v[68:71], v[220:223], v[0:15]
	v_mfma_f32_32x32x16_bf16 v[16:31], v[68:71], v[224:227], v[16:31]
	global_load_dwordx4 v[116:119], v243, s[88:89]
	global_load_dwordx4 v[120:123], v244, s[88:89]
	global_load_dwordx4 v[124:127], v245, s[88:89]
	global_load_dwordx4 v[128:131], v246, s[88:89]
	global_load_dwordx4 v[132:135], v148, s[88:89] offset:768
	global_load_dwordx4 v[136:139], v151, s[88:89] offset:768
	global_load_dwordx4 v[140:143], v148, s[88:89] offset:832
	global_load_dwordx4 v[144:147], v151, s[88:89] offset:832
	s_add_u32 s88, s88, 0x300000
	s_addc_u32 s89, s89, 0
	ds_read_b64_tr_b16 v[72:73], v231
	ds_read_b64_tr_b16 v[74:75], v231 offset:512
	ds_read_b64_tr_b16 v[76:77], v231 offset:2048
	ds_read_b64_tr_b16 v[78:79], v231 offset:2560
	ds_read_b64_tr_b16 v[220:221], v231 offset:1024
	ds_read_b64_tr_b16 v[222:223], v231 offset:1536
	ds_read_b64_tr_b16 v[224:225], v231 offset:3072
	ds_read_b64_tr_b16 v[226:227], v231 offset:3584
	s_waitcnt vmcnt(8)
	ds_write_b128 v247, v[156:159]
	ds_write_b128 v247, v[160:163] offset:1024
	ds_write_b128 v247, v[164:167] offset:2048
	ds_write_b128 v247, v[168:171] offset:3072
	ds_read_b128 v[156:159], v248
	ds_read_b128 v[160:163], v249
	ds_read_b128 v[164:167], v250
	ds_read_b128 v[168:171], v251
	ds_write_b128 v112, v[172:175]
	ds_write_b128 v112, v[176:179] offset:1024
	ds_write_b128 v112, v[180:183] offset:2048
	ds_write_b128 v112, v[184:187] offset:3072
	s_waitcnt lgkmcnt(4)
	v_mfma_f32_32x32x16_bf16 v[188:203], v[156:159], v[48:51], v[188:203]
	v_exp_f32_e32 v32, v32
	v_exp_f32_e32 v33, v33
	v_exp_f32_e32 v34, v34
	v_exp_f32_e32 v35, v35
	v_mfma_f32_32x32x16_bf16 v[188:203], v[160:163], v[52:55], v[188:203]
	v_exp_f32_e32 v36, v36
	v_exp_f32_e32 v37, v37
	v_exp_f32_e32 v38, v38
	v_exp_f32_e32 v39, v39
	v_mfma_f32_32x32x16_bf16 v[188:203], v[164:167], v[56:59], v[188:203]
	v_exp_f32_e32 v40, v40
	v_exp_f32_e32 v41, v41
	v_exp_f32_e32 v42, v42
	v_exp_f32_e32 v43, v43
	v_mfma_f32_32x32x16_bf16 v[188:203], v[168:171], v[60:63], v[188:203]
	v_exp_f32_e32 v44, v44
	v_exp_f32_e32 v45, v45
	v_exp_f32_e32 v46, v46
	v_exp_f32_e32 v47, v47
	v_cvt_pk_bf16_f32 v64, v32, v33
	v_cvt_pk_bf16_f32 v65, v34, v35
	v_cvt_pk_bf16_f32 v66, v36, v37
	v_cvt_pk_bf16_f32 v67, v38, v39
	v_cvt_pk_bf16_f32 v68, v40, v41
	v_cvt_pk_bf16_f32 v69, v42, v43
	v_cvt_pk_bf16_f32 v70, v44, v45
	v_cvt_pk_bf16_f32 v71, v46, v47
	v_pk_add_f32 v[232:233], v[232:233], v[32:33]
	v_pk_add_f32 v[232:233], v[232:233], v[34:35]
	v_pk_add_f32 v[232:233], v[232:233], v[36:37]
	v_pk_add_f32 v[232:233], v[232:233], v[38:39]
	v_pk_add_f32 v[232:233], v[232:233], v[40:41]
	v_pk_add_f32 v[232:233], v[232:233], v[42:43]
	v_pk_add_f32 v[232:233], v[232:233], v[44:45]
	v_pk_add_f32 v[232:233], v[232:233], v[46:47]
	v_mov_b32_e32 v115, v230
	ds_read2_b32 v[32:33], v115 offset0:0 offset1:1
	ds_read2_b32 v[34:35], v115 offset0:2 offset1:3
	ds_read2_b32 v[36:37], v115 offset0:8 offset1:9
	ds_read2_b32 v[38:39], v115 offset0:10 offset1:11
	ds_read2_b32 v[40:41], v115 offset0:16 offset1:17
	ds_read2_b32 v[42:43], v115 offset0:18 offset1:19
	ds_read2_b32 v[44:45], v115 offset0:24 offset1:25
	ds_read2_b32 v[46:47], v115 offset0:26 offset1:27
	v_mfma_f32_32x32x16_bf16 v[0:15], v[64:67], v[72:75], v[0:15]
	v_mfma_f32_32x32x16_bf16 v[16:31], v[64:67], v[76:79], v[16:31]
	v_mfma_f32_32x32x16_bf16 v[0:15], v[68:71], v[220:223], v[0:15]
	v_mfma_f32_32x32x16_bf16 v[16:31], v[68:71], v[224:227], v[16:31]
	global_load_dwordx4 v[156:159], v243, s[88:89]
	global_load_dwordx4 v[160:163], v244, s[88:89]
	global_load_dwordx4 v[164:167], v245, s[88:89]
	global_load_dwordx4 v[168:171], v246, s[88:89]
	global_load_dwordx4 v[172:175], v148, s[88:89] offset:768
	global_load_dwordx4 v[176:179], v151, s[88:89] offset:768
	global_load_dwordx4 v[180:183], v148, s[88:89] offset:832
	global_load_dwordx4 v[184:187], v151, s[88:89] offset:832
	s_add_u32 s88, s88, 0x300000
	s_addc_u32 s89, s89, 0
	ds_read_b64_tr_b16 v[72:73], v231
	ds_read_b64_tr_b16 v[74:75], v231 offset:512
	ds_read_b64_tr_b16 v[76:77], v231 offset:2048
	ds_read_b64_tr_b16 v[78:79], v231 offset:2560
	ds_read_b64_tr_b16 v[220:221], v231 offset:1024
	ds_read_b64_tr_b16 v[222:223], v231 offset:1536
	ds_read_b64_tr_b16 v[224:225], v231 offset:3072
	ds_read_b64_tr_b16 v[226:227], v231 offset:3584
	s_waitcnt vmcnt(8)
	ds_write_b128 v247, v[116:119]
	ds_write_b128 v247, v[120:123] offset:1024
	ds_write_b128 v247, v[124:127] offset:2048
	ds_write_b128 v247, v[128:131] offset:3072
	ds_read_b128 v[116:119], v248
	ds_read_b128 v[120:123], v249
	ds_read_b128 v[124:127], v250
	ds_read_b128 v[128:131], v251
	ds_write_b128 v112, v[132:135]
	ds_write_b128 v112, v[136:139] offset:1024
	ds_write_b128 v112, v[140:143] offset:2048
	ds_write_b128 v112, v[144:147] offset:3072
	s_waitcnt lgkmcnt(4)
	v_mfma_f32_32x32x16_bf16 v[32:47], v[116:119], v[48:51], v[32:47]
	v_exp_f32_e32 v188, v188
	v_exp_f32_e32 v189, v189
	v_exp_f32_e32 v190, v190
	v_exp_f32_e32 v191, v191
	v_mfma_f32_32x32x16_bf16 v[32:47], v[120:123], v[52:55], v[32:47]
	v_exp_f32_e32 v192, v192
	v_exp_f32_e32 v193, v193
	v_exp_f32_e32 v194, v194
	v_exp_f32_e32 v195, v195
	v_mfma_f32_32x32x16_bf16 v[32:47], v[124:127], v[56:59], v[32:47]
	v_exp_f32_e32 v196, v196
	v_exp_f32_e32 v197, v197
	v_exp_f32_e32 v198, v198
	v_exp_f32_e32 v199, v199
	v_mfma_f32_32x32x16_bf16 v[32:47], v[128:131], v[60:63], v[32:47]
	v_exp_f32_e32 v200, v200
	v_exp_f32_e32 v201, v201
	v_exp_f32_e32 v202, v202
	v_exp_f32_e32 v203, v203
	v_cvt_pk_bf16_f32 v64, v188, v189
	v_cvt_pk_bf16_f32 v65, v190, v191
	v_cvt_pk_bf16_f32 v66, v192, v193
	v_cvt_pk_bf16_f32 v67, v194, v195
	v_cvt_pk_bf16_f32 v68, v196, v197
	v_cvt_pk_bf16_f32 v69, v198, v199
	v_cvt_pk_bf16_f32 v70, v200, v201
	v_cvt_pk_bf16_f32 v71, v202, v203
	v_pk_add_f32 v[232:233], v[232:233], v[188:189]
	v_pk_add_f32 v[232:233], v[232:233], v[190:191]
	v_pk_add_f32 v[232:233], v[232:233], v[192:193]
	v_pk_add_f32 v[232:233], v[232:233], v[194:195]
	v_pk_add_f32 v[232:233], v[232:233], v[196:197]
	v_pk_add_f32 v[232:233], v[232:233], v[198:199]
	v_pk_add_f32 v[232:233], v[232:233], v[200:201]
	v_pk_add_f32 v[232:233], v[232:233], v[202:203]
	ds_read2_b32 v[188:189], v115 offset0:32 offset1:33
	ds_read2_b32 v[190:191], v115 offset0:34 offset1:35
	ds_read2_b32 v[192:193], v115 offset0:40 offset1:41
	ds_read2_b32 v[194:195], v115 offset0:42 offset1:43
	ds_read2_b32 v[196:197], v115 offset0:48 offset1:49
	ds_read2_b32 v[198:199], v115 offset0:50 offset1:51
	ds_read2_b32 v[200:201], v115 offset0:56 offset1:57
	ds_read2_b32 v[202:203], v115 offset0:58 offset1:59
	v_mfma_f32_32x32x16_bf16 v[0:15], v[64:67], v[72:75], v[0:15]
	v_mfma_f32_32x32x16_bf16 v[16:31], v[64:67], v[76:79], v[16:31]
	v_mfma_f32_32x32x16_bf16 v[0:15], v[68:71], v[220:223], v[0:15]
	v_mfma_f32_32x32x16_bf16 v[16:31], v[68:71], v[224:227], v[16:31]
	global_load_dwordx4 v[116:119], v243, s[88:89]
	global_load_dwordx4 v[120:123], v244, s[88:89]
	global_load_dwordx4 v[124:127], v245, s[88:89]
	global_load_dwordx4 v[128:131], v246, s[88:89]
	global_load_dwordx4 v[132:135], v148, s[88:89] offset:768
	global_load_dwordx4 v[136:139], v151, s[88:89] offset:768
	global_load_dwordx4 v[140:143], v148, s[88:89] offset:832
	global_load_dwordx4 v[144:147], v151, s[88:89] offset:832
	s_add_u32 s88, s88, 0x300000
	s_addc_u32 s89, s89, 0
	ds_read_b64_tr_b16 v[72:73], v231
	ds_read_b64_tr_b16 v[74:75], v231 offset:512
	ds_read_b64_tr_b16 v[76:77], v231 offset:2048
	ds_read_b64_tr_b16 v[78:79], v231 offset:2560
	ds_read_b64_tr_b16 v[220:221], v231 offset:1024
	ds_read_b64_tr_b16 v[222:223], v231 offset:1536
	ds_read_b64_tr_b16 v[224:225], v231 offset:3072
	ds_read_b64_tr_b16 v[226:227], v231 offset:3584
	s_waitcnt vmcnt(8)
	ds_write_b128 v247, v[156:159]
	ds_write_b128 v247, v[160:163] offset:1024
	ds_write_b128 v247, v[164:167] offset:2048
	ds_write_b128 v247, v[168:171] offset:3072
	ds_read_b128 v[156:159], v248
	ds_read_b128 v[160:163], v249
	ds_read_b128 v[164:167], v250
	ds_read_b128 v[168:171], v251
	ds_write_b128 v112, v[172:175]
	ds_write_b128 v112, v[176:179] offset:1024
	ds_write_b128 v112, v[180:183] offset:2048
	ds_write_b128 v112, v[184:187] offset:3072
	s_waitcnt lgkmcnt(4)
	v_mfma_f32_32x32x16_bf16 v[188:203], v[156:159], v[48:51], v[188:203]
	v_exp_f32_e32 v32, v32
	v_exp_f32_e32 v33, v33
	v_exp_f32_e32 v34, v34
	v_exp_f32_e32 v35, v35
	v_mfma_f32_32x32x16_bf16 v[188:203], v[160:163], v[52:55], v[188:203]
	v_exp_f32_e32 v36, v36
	v_exp_f32_e32 v37, v37
	v_exp_f32_e32 v38, v38
	v_exp_f32_e32 v39, v39
	v_mfma_f32_32x32x16_bf16 v[188:203], v[164:167], v[56:59], v[188:203]
	v_exp_f32_e32 v40, v40
	v_exp_f32_e32 v41, v41
	v_exp_f32_e32 v42, v42
	v_exp_f32_e32 v43, v43
	v_mfma_f32_32x32x16_bf16 v[188:203], v[168:171], v[60:63], v[188:203]
	v_exp_f32_e32 v44, v44
	v_exp_f32_e32 v45, v45
	v_exp_f32_e32 v46, v46
	v_exp_f32_e32 v47, v47
	v_cvt_pk_bf16_f32 v64, v32, v33
	v_cvt_pk_bf16_f32 v65, v34, v35
	v_cvt_pk_bf16_f32 v66, v36, v37
	v_cvt_pk_bf16_f32 v67, v38, v39
	v_cvt_pk_bf16_f32 v68, v40, v41
	v_cvt_pk_bf16_f32 v69, v42, v43
	v_cvt_pk_bf16_f32 v70, v44, v45
	v_cvt_pk_bf16_f32 v71, v46, v47
	v_pk_add_f32 v[232:233], v[232:233], v[32:33]
	v_pk_add_f32 v[232:233], v[232:233], v[34:35]
	v_pk_add_f32 v[232:233], v[232:233], v[36:37]
	v_pk_add_f32 v[232:233], v[232:233], v[38:39]
	v_pk_add_f32 v[232:233], v[232:233], v[40:41]
	v_pk_add_f32 v[232:233], v[232:233], v[42:43]
	v_pk_add_f32 v[232:233], v[232:233], v[44:45]
	v_pk_add_f32 v[232:233], v[232:233], v[46:47]
	ds_read2_b32 v[32:33], v115 offset0:64 offset1:65
	ds_read2_b32 v[34:35], v115 offset0:66 offset1:67
	ds_read2_b32 v[36:37], v115 offset0:72 offset1:73
	ds_read2_b32 v[38:39], v115 offset0:74 offset1:75
	ds_read2_b32 v[40:41], v115 offset0:80 offset1:81
	ds_read2_b32 v[42:43], v115 offset0:82 offset1:83
	ds_read2_b32 v[44:45], v115 offset0:88 offset1:89
	ds_read2_b32 v[46:47], v115 offset0:90 offset1:91
	v_mfma_f32_32x32x16_bf16 v[0:15], v[64:67], v[72:75], v[0:15]
	v_mfma_f32_32x32x16_bf16 v[16:31], v[64:67], v[76:79], v[16:31]
	v_mfma_f32_32x32x16_bf16 v[0:15], v[68:71], v[220:223], v[0:15]
	v_mfma_f32_32x32x16_bf16 v[16:31], v[68:71], v[224:227], v[16:31]
	global_load_dwordx4 v[156:159], v243, s[88:89]
	global_load_dwordx4 v[160:163], v244, s[88:89]
	global_load_dwordx4 v[164:167], v245, s[88:89]
	global_load_dwordx4 v[168:171], v246, s[88:89]
	global_load_dwordx4 v[172:175], v148, s[88:89] offset:768
	global_load_dwordx4 v[176:179], v151, s[88:89] offset:768
	global_load_dwordx4 v[180:183], v148, s[88:89] offset:832
	global_load_dwordx4 v[184:187], v151, s[88:89] offset:832
	s_add_u32 s88, s88, 0x300000
	s_addc_u32 s89, s89, 0
	ds_read_b64_tr_b16 v[72:73], v231
	ds_read_b64_tr_b16 v[74:75], v231 offset:512
	ds_read_b64_tr_b16 v[76:77], v231 offset:2048
	ds_read_b64_tr_b16 v[78:79], v231 offset:2560
	ds_read_b64_tr_b16 v[220:221], v231 offset:1024
	ds_read_b64_tr_b16 v[222:223], v231 offset:1536
	ds_read_b64_tr_b16 v[224:225], v231 offset:3072
	ds_read_b64_tr_b16 v[226:227], v231 offset:3584
	s_waitcnt vmcnt(8)
	ds_write_b128 v247, v[116:119]
	ds_write_b128 v247, v[120:123] offset:1024
	ds_write_b128 v247, v[124:127] offset:2048
	ds_write_b128 v247, v[128:131] offset:3072
	ds_read_b128 v[116:119], v248
	ds_read_b128 v[120:123], v249
	ds_read_b128 v[124:127], v250
	ds_read_b128 v[128:131], v251
	ds_write_b128 v112, v[132:135]
	ds_write_b128 v112, v[136:139] offset:1024
	ds_write_b128 v112, v[140:143] offset:2048
	ds_write_b128 v112, v[144:147] offset:3072
	s_waitcnt lgkmcnt(4)
	v_mfma_f32_32x32x16_bf16 v[32:47], v[116:119], v[48:51], v[32:47]
	v_exp_f32_e32 v188, v188
	v_exp_f32_e32 v189, v189
	v_exp_f32_e32 v190, v190
	v_exp_f32_e32 v191, v191
	v_mfma_f32_32x32x16_bf16 v[32:47], v[120:123], v[52:55], v[32:47]
	v_exp_f32_e32 v192, v192
	v_exp_f32_e32 v193, v193
	v_exp_f32_e32 v194, v194
	v_exp_f32_e32 v195, v195
	v_mfma_f32_32x32x16_bf16 v[32:47], v[124:127], v[56:59], v[32:47]
	v_exp_f32_e32 v196, v196
	v_exp_f32_e32 v197, v197
	v_exp_f32_e32 v198, v198
	v_exp_f32_e32 v199, v199
	v_mfma_f32_32x32x16_bf16 v[32:47], v[128:131], v[60:63], v[32:47]
	v_exp_f32_e32 v200, v200
	v_exp_f32_e32 v201, v201
	v_exp_f32_e32 v202, v202
	v_exp_f32_e32 v203, v203
	v_cvt_pk_bf16_f32 v64, v188, v189
	v_cvt_pk_bf16_f32 v65, v190, v191
	v_cvt_pk_bf16_f32 v66, v192, v193
	v_cvt_pk_bf16_f32 v67, v194, v195
	v_cvt_pk_bf16_f32 v68, v196, v197
	v_cvt_pk_bf16_f32 v69, v198, v199
	v_cvt_pk_bf16_f32 v70, v200, v201
	v_cvt_pk_bf16_f32 v71, v202, v203
	v_pk_add_f32 v[232:233], v[232:233], v[188:189]
	v_pk_add_f32 v[232:233], v[232:233], v[190:191]
	v_pk_add_f32 v[232:233], v[232:233], v[192:193]
	v_pk_add_f32 v[232:233], v[232:233], v[194:195]
	v_pk_add_f32 v[232:233], v[232:233], v[196:197]
	v_pk_add_f32 v[232:233], v[232:233], v[198:199]
	v_pk_add_f32 v[232:233], v[232:233], v[200:201]
	v_pk_add_f32 v[232:233], v[232:233], v[202:203]
	ds_read2_b32 v[188:189], v115 offset0:96 offset1:97
	ds_read2_b32 v[190:191], v115 offset0:98 offset1:99
	ds_read2_b32 v[192:193], v115 offset0:104 offset1:105
	ds_read2_b32 v[194:195], v115 offset0:106 offset1:107
	ds_read2_b32 v[196:197], v115 offset0:112 offset1:113
	ds_read2_b32 v[198:199], v115 offset0:114 offset1:115
	ds_read2_b32 v[200:201], v115 offset0:120 offset1:121
	ds_read2_b32 v[202:203], v115 offset0:122 offset1:123
	v_mfma_f32_32x32x16_bf16 v[0:15], v[64:67], v[72:75], v[0:15]
	v_mfma_f32_32x32x16_bf16 v[16:31], v[64:67], v[76:79], v[16:31]
	v_mfma_f32_32x32x16_bf16 v[0:15], v[68:71], v[220:223], v[0:15]
	v_mfma_f32_32x32x16_bf16 v[16:31], v[68:71], v[224:227], v[16:31]
	global_load_dwordx4 v[116:119], v243, s[88:89]
	global_load_dwordx4 v[120:123], v244, s[88:89]
	global_load_dwordx4 v[124:127], v245, s[88:89]
	global_load_dwordx4 v[128:131], v246, s[88:89]
	global_load_dwordx4 v[132:135], v148, s[88:89] offset:768
	global_load_dwordx4 v[136:139], v151, s[88:89] offset:768
	global_load_dwordx4 v[140:143], v148, s[88:89] offset:832
	global_load_dwordx4 v[144:147], v151, s[88:89] offset:832
	ds_read_b64_tr_b16 v[72:73], v231
	ds_read_b64_tr_b16 v[74:75], v231 offset:512
	ds_read_b64_tr_b16 v[76:77], v231 offset:2048
	ds_read_b64_tr_b16 v[78:79], v231 offset:2560
	ds_read_b64_tr_b16 v[220:221], v231 offset:1024
	ds_read_b64_tr_b16 v[222:223], v231 offset:1536
	ds_read_b64_tr_b16 v[224:225], v231 offset:3072
	ds_read_b64_tr_b16 v[226:227], v231 offset:3584
	s_waitcnt vmcnt(8)
	ds_write_b128 v247, v[156:159]
	ds_write_b128 v247, v[160:163] offset:1024
	ds_write_b128 v247, v[164:167] offset:2048
	ds_write_b128 v247, v[168:171] offset:3072
	ds_read_b128 v[156:159], v248
	ds_read_b128 v[160:163], v249
	ds_read_b128 v[164:167], v250
	ds_read_b128 v[168:171], v251
	ds_write_b128 v112, v[172:175]
	ds_write_b128 v112, v[176:179] offset:1024
	ds_write_b128 v112, v[180:183] offset:2048
	ds_write_b128 v112, v[184:187] offset:3072
	s_waitcnt lgkmcnt(4)
	v_mfma_f32_32x32x16_bf16 v[188:203], v[156:159], v[48:51], v[188:203]
	v_exp_f32_e32 v32, v32
	v_exp_f32_e32 v33, v33
	v_exp_f32_e32 v34, v34
	v_exp_f32_e32 v35, v35
	v_mfma_f32_32x32x16_bf16 v[188:203], v[160:163], v[52:55], v[188:203]
	v_exp_f32_e32 v36, v36
	v_exp_f32_e32 v37, v37
	v_exp_f32_e32 v38, v38
	v_exp_f32_e32 v39, v39
	v_mfma_f32_32x32x16_bf16 v[188:203], v[164:167], v[56:59], v[188:203]
	v_exp_f32_e32 v40, v40
	v_exp_f32_e32 v41, v41
	v_exp_f32_e32 v42, v42
	v_exp_f32_e32 v43, v43
	v_mfma_f32_32x32x16_bf16 v[188:203], v[168:171], v[60:63], v[188:203]
	v_exp_f32_e32 v44, v44
	v_exp_f32_e32 v45, v45
	v_exp_f32_e32 v46, v46
	v_exp_f32_e32 v47, v47
	v_cvt_pk_bf16_f32 v64, v32, v33
	v_cvt_pk_bf16_f32 v65, v34, v35
	v_cvt_pk_bf16_f32 v66, v36, v37
	v_cvt_pk_bf16_f32 v67, v38, v39
	v_cvt_pk_bf16_f32 v68, v40, v41
	v_cvt_pk_bf16_f32 v69, v42, v43
	v_cvt_pk_bf16_f32 v70, v44, v45
	v_cvt_pk_bf16_f32 v71, v46, v47
	v_pk_add_f32 v[232:233], v[232:233], v[32:33]
	v_pk_add_f32 v[232:233], v[232:233], v[34:35]
	v_pk_add_f32 v[232:233], v[232:233], v[36:37]
	v_pk_add_f32 v[232:233], v[232:233], v[38:39]
	v_pk_add_f32 v[232:233], v[232:233], v[40:41]
	v_pk_add_f32 v[232:233], v[232:233], v[42:43]
	v_pk_add_f32 v[232:233], v[232:233], v[44:45]
	v_pk_add_f32 v[232:233], v[232:233], v[46:47]
	ds_read2_b32 v[32:33], v115 offset0:128 offset1:129
	ds_read2_b32 v[34:35], v115 offset0:130 offset1:131
	ds_read2_b32 v[36:37], v115 offset0:136 offset1:137
	ds_read2_b32 v[38:39], v115 offset0:138 offset1:139
	ds_read2_b32 v[40:41], v115 offset0:144 offset1:145
	ds_read2_b32 v[42:43], v115 offset0:146 offset1:147
	ds_read2_b32 v[44:45], v115 offset0:152 offset1:153
	ds_read2_b32 v[46:47], v115 offset0:154 offset1:155
	v_mfma_f32_32x32x16_bf16 v[0:15], v[64:67], v[72:75], v[0:15]
	v_mfma_f32_32x32x16_bf16 v[16:31], v[64:67], v[76:79], v[16:31]
	v_mfma_f32_32x32x16_bf16 v[0:15], v[68:71], v[220:223], v[0:15]
	v_mfma_f32_32x32x16_bf16 v[16:31], v[68:71], v[224:227], v[16:31]
	ds_read_b64_tr_b16 v[72:73], v231
	ds_read_b64_tr_b16 v[74:75], v231 offset:512
	ds_read_b64_tr_b16 v[76:77], v231 offset:2048
	ds_read_b64_tr_b16 v[78:79], v231 offset:2560
	ds_read_b64_tr_b16 v[220:221], v231 offset:1024
	ds_read_b64_tr_b16 v[222:223], v231 offset:1536
	ds_read_b64_tr_b16 v[224:225], v231 offset:3072
	ds_read_b64_tr_b16 v[226:227], v231 offset:3584
	s_waitcnt vmcnt(0)
; __device__ __forceinline__ int crow(int r, int hi) { return (r & 3) + 8 * (r >> 2) + 4 * hi; }
; __device__ __forceinline__ void dil_unit(LAS unsigned char* lds, bf16_t* proj, int seq, int hd, int T0, int rho) {
;     ...
;     l += __shfl_xor(l, 32);
; #pragma unroll
;     for (int rr = 0; rr < 16; ++rr) {
;         const int j = crow(rr, hi);
;         const float il = __builtin_amdgcn_rcpf(__shfl(l, j));
	ds_write_b128 v247, v[116:119]
	ds_write_b128 v247, v[120:123] offset:1024
	ds_write_b128 v247, v[124:127] offset:2048
	ds_write_b128 v247, v[128:131] offset:3072
	ds_read_b128 v[116:119], v248
	ds_read_b128 v[120:123], v249
	ds_read_b128 v[124:127], v250
	ds_read_b128 v[128:131], v251
	ds_write_b128 v112, v[132:135]
	ds_write_b128 v112, v[136:139] offset:1024
	ds_write_b128 v112, v[140:143] offset:2048
	ds_write_b128 v112, v[144:147] offset:3072
	s_waitcnt lgkmcnt(4)
	v_mfma_f32_32x32x16_bf16 v[32:47], v[116:119], v[48:51], v[32:47]
	v_exp_f32_e32 v188, v188
	v_exp_f32_e32 v189, v189
	v_exp_f32_e32 v190, v190
	v_exp_f32_e32 v191, v191
	v_mfma_f32_32x32x16_bf16 v[32:47], v[120:123], v[52:55], v[32:47]
	v_exp_f32_e32 v192, v192
	v_exp_f32_e32 v193, v193
	v_exp_f32_e32 v194, v194
	v_exp_f32_e32 v195, v195
	v_mfma_f32_32x32x16_bf16 v[32:47], v[124:127], v[56:59], v[32:47]
	v_exp_f32_e32 v196, v196
	v_exp_f32_e32 v197, v197
	v_exp_f32_e32 v198, v198
	v_exp_f32_e32 v199, v199
	v_mfma_f32_32x32x16_bf16 v[32:47], v[128:131], v[60:63], v[32:47]
	v_exp_f32_e32 v200, v200
	v_exp_f32_e32 v201, v201
	v_exp_f32_e32 v202, v202
	v_exp_f32_e32 v203, v203
	v_cvt_pk_bf16_f32 v64, v188, v189
	v_cvt_pk_bf16_f32 v65, v190, v191
	v_cvt_pk_bf16_f32 v66, v192, v193
	v_cvt_pk_bf16_f32 v67, v194, v195
	v_cvt_pk_bf16_f32 v68, v196, v197
	v_cvt_pk_bf16_f32 v69, v198, v199
	v_cvt_pk_bf16_f32 v70, v200, v201
	v_cvt_pk_bf16_f32 v71, v202, v203
	v_pk_add_f32 v[232:233], v[232:233], v[188:189]
	v_pk_add_f32 v[232:233], v[232:233], v[190:191]
	v_pk_add_f32 v[232:233], v[232:233], v[192:193]
	v_pk_add_f32 v[232:233], v[232:233], v[194:195]
	v_pk_add_f32 v[232:233], v[232:233], v[196:197]
	v_pk_add_f32 v[232:233], v[232:233], v[198:199]
	v_pk_add_f32 v[232:233], v[232:233], v[200:201]
	v_pk_add_f32 v[232:233], v[232:233], v[202:203]
	v_mfma_f32_32x32x16_bf16 v[0:15], v[64:67], v[72:75], v[0:15]
	v_mfma_f32_32x32x16_bf16 v[16:31], v[64:67], v[76:79], v[16:31]
	v_mfma_f32_32x32x16_bf16 v[0:15], v[68:71], v[220:223], v[0:15]
	v_mfma_f32_32x32x16_bf16 v[16:31], v[68:71], v[224:227], v[16:31]
	ds_read_b64_tr_b16 v[72:73], v231
	ds_read_b64_tr_b16 v[74:75], v231 offset:512
	ds_read_b64_tr_b16 v[76:77], v231 offset:2048
	ds_read_b64_tr_b16 v[78:79], v231 offset:2560
	ds_read_b64_tr_b16 v[220:221], v231 offset:1024
	ds_read_b64_tr_b16 v[222:223], v231 offset:1536
	ds_read_b64_tr_b16 v[224:225], v231 offset:3072
	ds_read_b64_tr_b16 v[226:227], v231 offset:3584
	s_waitcnt lgkmcnt(0)
	v_exp_f32_e32 v32, v32
	v_exp_f32_e32 v33, v33
	v_exp_f32_e32 v34, v34
	v_exp_f32_e32 v35, v35
	v_exp_f32_e32 v36, v36
	v_exp_f32_e32 v37, v37
	v_exp_f32_e32 v38, v38
	v_exp_f32_e32 v39, v39
	v_exp_f32_e32 v40, v40
	v_exp_f32_e32 v41, v41
	v_exp_f32_e32 v42, v42
	v_exp_f32_e32 v43, v43
	v_exp_f32_e32 v44, v44
	v_exp_f32_e32 v45, v45
	v_exp_f32_e32 v46, v46
	v_exp_f32_e32 v47, v47
	v_cvt_pk_bf16_f32 v64, v32, v33
	v_cvt_pk_bf16_f32 v65, v34, v35
	v_cvt_pk_bf16_f32 v66, v36, v37
	v_cvt_pk_bf16_f32 v67, v38, v39
	v_cvt_pk_bf16_f32 v68, v40, v41
	v_cvt_pk_bf16_f32 v69, v42, v43
	v_cvt_pk_bf16_f32 v70, v44, v45
	v_cvt_pk_bf16_f32 v71, v46, v47
	v_pk_add_f32 v[232:233], v[232:233], v[32:33]
	v_pk_add_f32 v[232:233], v[232:233], v[34:35]
	v_pk_add_f32 v[232:233], v[232:233], v[36:37]
	v_pk_add_f32 v[232:233], v[232:233], v[38:39]
	v_pk_add_f32 v[232:233], v[232:233], v[40:41]
	v_pk_add_f32 v[232:233], v[232:233], v[42:43]
	v_pk_add_f32 v[232:233], v[232:233], v[44:45]
	v_pk_add_f32 v[232:233], v[232:233], v[46:47]
	v_mfma_f32_32x32x16_bf16 v[0:15], v[64:67], v[72:75], v[0:15]
	v_mfma_f32_32x32x16_bf16 v[16:31], v[64:67], v[76:79], v[16:31]
	v_mfma_f32_32x32x16_bf16 v[0:15], v[68:71], v[220:223], v[0:15]
	v_mfma_f32_32x32x16_bf16 v[16:31], v[68:71], v[224:227], v[16:31]
	v_add_f32_e32 v113, v232, v233
	v_or_b32_e32 v114, 1, v107
	v_or_b32_e32 v97, 2, v107
	v_or_b32_e32 v96, 3, v107
	v_or_b32_e32 v95, 8, v107
	v_or_b32_e32 v94, 9, v107
	v_or_b32_e32 v93, 10, v107
	v_or_b32_e32 v92, 11, v107
	v_or_b32_e32 v91, 16, v107
	v_or_b32_e32 v90, 17, v107
	v_or_b32_e32 v89, 18, v107
	v_or_b32_e32 v88, 19, v107
	v_or_b32_e32 v87, 24, v107
	v_or_b32_e32 v86, 25, v107
	v_or_b32_e32 v85, 26, v107
	v_or_b32_e32 v84, 27, v107
	s_nop 11
	s_branch .LBB0_553
; #define LAS __attribute__((address_space(3)))
; #define GAS __attribute__((address_space(1)))
; __device__ __forceinline__ void dil_unit(LAS unsigned char* lds, bf16_t* proj, int seq, int hd, int T0, int rho) {
;     ...
;     const int tid = tid_, lane = tid & 63, r32 = lane & 31, hi = lane >> 5, wid = __builtin_amdgcn_readfirstlane(tid >> 6);
;     bf16_t* base = proj + (size_t)seq * SEQ * NIN;
;     LAS unsigned char* wbuf = lds + wid * 4096;
;     const LAS unsigned char* vp = wbuf + ((lane >> 4) & 1) * 32 + (lane & 3) * 8 + (4 * hi + ((lane & 15) >> 2)) * 64;
;     const int P0 = T0 + rho;
;     bf16x8 qr[4];
; #pragma unroll
;     for (int ks = 0; ks < 4; ++ks) qr[ks] = *(const GAS bf16x8*)(base + (size_t)(P0 + 16 * r32) * NIN + PC_LQ + hd * 64 + 16 * ks + 8 * hi);
;     f32x16 o0 = {}, o1 = {}; float l = 0.f;
;     const bool bound = (T0 < 1024) || (T0 >= 15360);
.LBB0_558:
	s_movk_i32 s100, 0x1800
	s_add_i32 s101, s6, 0x15c00
	s_lshl_b32 s90, s58, 1
	s_add_u32 s82, s56, s90
	s_addc_u32 s83, s57, 0
	s_add_u32 s82, s82, 0x1200
	s_addc_u32 s83, s83, 0
	s_sub_i32 s90, s76, 64
	s_mul_i32 s90, s90, 0x1800
	s_add_u32 s84, s82, s90
	s_addc_u32 s85, s83, 0
	s_sub_i32 s90, s76, 256
	s_mul_i32 s90, s90, 0x1800
	s_add_u32 s86, s82, s90
	s_addc_u32 s87, s83, 0
	s_sub_i32 s90, s76, 1024
	s_mul_i32 s90, s90, 0x1800
	s_add_u32 s88, s82, s90
	s_addc_u32 s89, s83, 0
	v_lshlrev_b32_e32 v153, 1, v98
	v_mad_u32_u24 v80, v105, s100, v82
	v_mad_u32_u24 v100, v110, s100, v153
	v_add_u32_e32 v149, 0x18000, v100
	v_lshlrev_b32_e32 v83, 2, v105
	v_mad_u32_u24 v83, v83, s100, v82
	v_lshlrev_b32_e32 v101, 2, v110
	v_mad_u32_u24 v101, v101, s100, v153
	v_add_u32_e32 v150, 0x60000, v101
	v_lshlrev_b32_e32 v99, 4, v105
	v_mad_u32_u24 v99, v99, s100, v82
	v_lshlrev_b32_e32 v148, 4, v110
	v_mad_u32_u24 v148, v148, s100, v153
	v_add_u32_e32 v151, 0x180000, v148
	v_lshrrev_b32_e32 v249, 3, v103
	v_and_b32_e32 v250, 7, v103
	v_lshlrev_b32_e32 v250, 4, v250
	v_add_u32_e32 v235, 0, v249
	v_add_u32_e32 v236, 8, v249
	v_add_u32_e32 v237, 16, v249
	v_add_u32_e32 v238, 24, v249
	v_add_u32_e32 v239, 0, v249
	v_lshlrev_b32_e32 v239, 2, v239
	v_add_u32_e32 v240, 8, v249
	v_lshlrev_b32_e32 v240, 2, v240
	v_add_u32_e32 v241, 16, v249
	v_lshlrev_b32_e32 v241, 2, v241
	v_add_u32_e32 v242, 24, v249
	v_lshlrev_b32_e32 v242, 2, v242
	v_add_u32_e32 v243, 0, v249
	v_lshlrev_b32_e32 v243, 4, v243
	v_add_u32_e32 v244, 8, v249
	v_lshlrev_b32_e32 v244, 4, v244
	v_add_u32_e32 v245, 16, v249
	v_lshlrev_b32_e32 v245, 4, v245
	v_add_u32_e32 v246, 24, v249
	v_lshlrev_b32_e32 v246, 4, v246
	v_mov_b32_e32 v252, v250
	v_mov_b32_e32 v100, v110
	v_add_u32_e32 v149, 16, v100
	v_lshlrev_b32_e32 v101, 2, v110
	v_add_u32_e32 v150, 64, v101
	v_lshlrev_b32_e32 v148, 4, v110
	v_add_u32_e32 v151, 256, v148
	s_mov_b32 s98, 0x4000
	s_mov_b32 s99, 0x3fff
	v_and_b32_e32 v247, 7, v249
	v_lshlrev_b32_e32 v247, 4, v247
	v_xor_b32_e32 v247, v247, v112
	v_and_b32_e32 v153, 7, v105
	v_or_b32_e32 v248, 0, v106
	v_xor_b32_e32 v248, v248, v153
	v_lshlrev_b32_e32 v248, 4, v248
	v_lshl_add_u32 v248, v105, 7, v248
	v_add_u32_e32 v248, s77, v248
	v_or_b32_e32 v249, 2, v106
	v_xor_b32_e32 v249, v249, v153
	v_lshlrev_b32_e32 v249, 4, v249
	v_lshl_add_u32 v249, v105, 7, v249
	v_add_u32_e32 v249, s77, v249
	v_or_b32_e32 v250, 4, v106
	v_xor_b32_e32 v250, v250, v153
	v_lshlrev_b32_e32 v250, 4, v250
	v_lshl_add_u32 v250, v105, 7, v250
	v_add_u32_e32 v250, s77, v250
	v_or_b32_e32 v251, 6, v106
	v_xor_b32_e32 v251, v251, v153
	v_lshlrev_b32_e32 v251, 4, v251
	v_lshl_add_u32 v251, v105, 7, v251
	v_add_u32_e32 v251, s77, v251
	v_lshlrev_b32_e32 v153, 1, v98
	v_mul_u32_u24_e32 v228, 17, v105
	v_sub_u32_e32 v228, v107, v228
	s_mul_i32 s90, s58, 153
	s_lshr_b32 s90, s90, 1
	s_add_i32 s90, s90, 34876
	v_lshl_add_u32 v228, v228, 2, s90
	v_lshlrev_b32_e32 v229, 2, v105
	v_sub_u32_e32 v229, v107, v229
	s_add_i32 s90, s101, 5104
	v_lshl_add_u32 v229, v229, 2, s90
	v_sub_u32_e32 v230, v107, v105
	s_add_i32 s90, s101, 6364
	v_lshl_add_u32 v230, v230, 2, s90
	v_add_u32_e32 v231, v109, v108
	v_mov_b64_e32 v[232:233], 0
	v_mov_b64_e32 v[0:1], 0
	v_mov_b64_e32 v[2:3], 0
	v_mov_b64_e32 v[4:5], 0
	v_mov_b64_e32 v[6:7], 0
	v_mov_b64_e32 v[8:9], 0
	v_mov_b64_e32 v[10:11], 0
	v_mov_b64_e32 v[12:13], 0
	v_mov_b64_e32 v[14:15], 0
	v_mov_b64_e32 v[16:17], 0
	v_mov_b64_e32 v[18:19], 0
	v_mov_b64_e32 v[20:21], 0
	v_mov_b64_e32 v[22:23], 0
	v_mov_b64_e32 v[24:25], 0
	v_mov_b64_e32 v[26:27], 0
	v_mov_b64_e32 v[28:29], 0
	v_mov_b64_e32 v[30:31], 0
	s_add_i32 s90, s76, -64
	v_add_u32_e32 v80, s90, v235
	v_add_u32_e32 v83, s90, v236
	v_add_u32_e32 v99, s90, v237
	v_add_u32_e32 v253, s90, v238
	v_add_u32_e32 v254, s90, v100
	v_add_u32_e32 v255, s90, v149
	v_med3_i32 v80, v80, 0, s99
	v_med3_i32 v83, v83, 0, s99
	v_med3_i32 v99, v99, 0, s99
	v_med3_i32 v253, v253, 0, s99
	v_med3_i32 v254, v254, 0, s99
	v_med3_i32 v255, v255, 0, s99
	v_mad_u32_u24 v80, v80, s100, v252
	v_mad_u32_u24 v83, v83, s100, v252
	v_mad_u32_u24 v99, v99, s100, v252
	v_mad_u32_u24 v253, v253, s100, v252
	v_mad_u32_u24 v254, v254, s100, v153
	v_mad_u32_u24 v255, v255, s100, v153
	global_load_dwordx4 v[116:119], v80, s[82:83]
	global_load_dwordx4 v[120:123], v83, s[82:83]
	global_load_dwordx4 v[124:127], v99, s[82:83]
	global_load_dwordx4 v[128:131], v253, s[82:83]
	global_load_dwordx4 v[132:135], v254, s[82:83] offset:768
	global_load_dwordx4 v[136:139], v255, s[82:83] offset:768
	global_load_dwordx4 v[140:143], v254, s[82:83] offset:832
	global_load_dwordx4 v[144:147], v255, s[82:83] offset:832
	s_add_i32 s90, s76, -32
	v_add_u32_e32 v80, s90, v235
	v_add_u32_e32 v83, s90, v236
	v_add_u32_e32 v99, s90, v237
	v_add_u32_e32 v253, s90, v238
	v_add_u32_e32 v254, s90, v100
	v_add_u32_e32 v255, s90, v149
	v_med3_i32 v80, v80, 0, s99
	v_med3_i32 v83, v83, 0, s99
	v_med3_i32 v99, v99, 0, s99
	v_med3_i32 v253, v253, 0, s99
	v_med3_i32 v254, v254, 0, s99
	v_med3_i32 v255, v255, 0, s99
	v_mad_u32_u24 v80, v80, s100, v252
	v_mad_u32_u24 v83, v83, s100, v252
	v_mad_u32_u24 v99, v99, s100, v252
	v_mad_u32_u24 v253, v253, s100, v252
	v_mad_u32_u24 v254, v254, s100, v153
	v_mad_u32_u24 v255, v255, s100, v153
	global_load_dwordx4 v[156:159], v80, s[82:83]
	global_load_dwordx4 v[160:163], v83, s[82:83]
	global_load_dwordx4 v[164:167], v99, s[82:83]
	global_load_dwordx4 v[168:171], v253, s[82:83]
	global_load_dwordx4 v[172:175], v254, s[82:83] offset:768
	global_load_dwordx4 v[176:179], v255, s[82:83] offset:768
	global_load_dwordx4 v[180:183], v254, s[82:83] offset:832
	global_load_dwordx4 v[184:187], v255, s[82:83] offset:832
	v_mov_b32_e32 v115, v228
	ds_read2_b32 v[32:33], v115 offset0:0 offset1:1
	ds_read2_b32 v[34:35], v115 offset0:2 offset1:3
	ds_read2_b32 v[36:37], v115 offset0:8 offset1:9
	ds_read2_b32 v[38:39], v115 offset0:10 offset1:11
	ds_read2_b32 v[40:41], v115 offset0:17 offset1:18
	ds_read2_b32 v[42:43], v115 offset0:19 offset1:20
	ds_read2_b32 v[44:45], v115 offset0:25 offset1:26
	ds_read2_b32 v[46:47], v115 offset0:27 offset1:28
	s_waitcnt vmcnt(8)
	ds_write_b128 v247, v[116:119]
	ds_write_b128 v247, v[120:123] offset:1024
	ds_write_b128 v247, v[124:127] offset:2048
	ds_write_b128 v247, v[128:131] offset:3072
	ds_read_b128 v[116:119], v248
	ds_read_b128 v[120:123], v249
	ds_read_b128 v[124:127], v250
	ds_read_b128 v[128:131], v251
	ds_write_b128 v112, v[132:135]
	ds_write_b128 v112, v[136:139] offset:1024
	ds_write_b128 v112, v[140:143] offset:2048
	ds_write_b128 v112, v[144:147] offset:3072
	s_waitcnt lgkmcnt(4)
	v_mfma_f32_32x32x16_bf16 v[32:47], v[116:119], v[48:51], v[32:47]
	v_mfma_f32_32x32x16_bf16 v[32:47], v[120:123], v[52:55], v[32:47]
	v_mfma_f32_32x32x16_bf16 v[32:47], v[124:127], v[56:59], v[32:47]
	v_mfma_f32_32x32x16_bf16 v[32:47], v[128:131], v[60:63], v[32:47]
	ds_read2_b32 v[188:189], v115 offset0:34 offset1:35
	ds_read2_b32 v[190:191], v115 offset0:36 offset1:37
	ds_read2_b32 v[192:193], v115 offset0:42 offset1:43
	ds_read2_b32 v[194:195], v115 offset0:44 offset1:45
	ds_read2_b32 v[196:197], v115 offset0:51 offset1:52
	ds_read2_b32 v[198:199], v115 offset0:53 offset1:54
	ds_read2_b32 v[200:201], v115 offset0:59 offset1:60
	ds_read2_b32 v[202:203], v115 offset0:61 offset1:62
	s_add_i32 s90, s76, 0
	v_add_u32_e32 v80, s90, v235
	v_add_u32_e32 v83, s90, v236
	v_add_u32_e32 v99, s90, v237
	v_add_u32_e32 v253, s90, v238
	v_add_u32_e32 v254, s90, v100
	v_add_u32_e32 v255, s90, v149
	v_med3_i32 v80, v80, 0, s99
	v_med3_i32 v83, v83, 0, s99
	v_med3_i32 v99, v99, 0, s99
	v_med3_i32 v253, v253, 0, s99
	v_med3_i32 v254, v254, 0, s99
	v_med3_i32 v255, v255, 0, s99
	v_mad_u32_u24 v80, v80, s100, v252
	v_mad_u32_u24 v83, v83, s100, v252
	v_mad_u32_u24 v99, v99, s100, v252
	v_mad_u32_u24 v253, v253, s100, v252
	v_mad_u32_u24 v254, v254, s100, v153
	v_mad_u32_u24 v255, v255, s100, v153
	global_load_dwordx4 v[116:119], v80, s[82:83]
	global_load_dwordx4 v[120:123], v83, s[82:83]
	global_load_dwordx4 v[124:127], v99, s[82:83]
	global_load_dwordx4 v[128:131], v253, s[82:83]
	global_load_dwordx4 v[132:135], v254, s[82:83] offset:768
	global_load_dwordx4 v[136:139], v255, s[82:83] offset:768
	global_load_dwordx4 v[140:143], v254, s[82:83] offset:832
	global_load_dwordx4 v[144:147], v255, s[82:83] offset:832
	ds_read_b64_tr_b16 v[72:73], v231
	ds_read_b64_tr_b16 v[74:75], v231 offset:512
	ds_read_b64_tr_b16 v[76:77], v231 offset:2048
	ds_read_b64_tr_b16 v[78:79], v231 offset:2560
	ds_read_b64_tr_b16 v[220:221], v231 offset:1024
	ds_read_b64_tr_b16 v[222:223], v231 offset:1536
	ds_read_b64_tr_b16 v[224:225], v231 offset:3072
	ds_read_b64_tr_b16 v[226:227], v231 offset:3584
	s_waitcnt vmcnt(8)
	ds_write_b128 v247, v[156:159]
	ds_write_b128 v247, v[160:163] offset:1024
	ds_write_b128 v247, v[164:167] offset:2048
	ds_write_b128 v247, v[168:171] offset:3072
	ds_read_b128 v[156:159], v248
	ds_read_b128 v[160:163], v249
	ds_read_b128 v[164:167], v250
	ds_read_b128 v[168:171], v251
	ds_write_b128 v112, v[172:175]
	ds_write_b128 v112, v[176:179] offset:1024
	ds_write_b128 v112, v[180:183] offset:2048
	ds_write_b128 v112, v[184:187] offset:3072
	s_waitcnt lgkmcnt(4)
	v_mfma_f32_32x32x16_bf16 v[188:203], v[156:159], v[48:51], v[188:203]
	v_exp_f32_e32 v32, v32
	v_exp_f32_e32 v33, v33
	v_exp_f32_e32 v34, v34
	v_exp_f32_e32 v35, v35
	v_mfma_f32_32x32x16_bf16 v[188:203], v[160:163], v[52:55], v[188:203]
	v_exp_f32_e32 v36, v36
	v_exp_f32_e32 v37, v37
	v_exp_f32_e32 v38, v38
	v_exp_f32_e32 v39, v39
	v_mfma_f32_32x32x16_bf16 v[188:203], v[164:167], v[56:59], v[188:203]
	v_exp_f32_e32 v40, v40
	v_exp_f32_e32 v41, v41
	v_exp_f32_e32 v42, v42
	v_exp_f32_e32 v43, v43
	v_mfma_f32_32x32x16_bf16 v[188:203], v[168:171], v[60:63], v[188:203]
	v_exp_f32_e32 v44, v44
	v_exp_f32_e32 v45, v45
	v_exp_f32_e32 v46, v46
	v_exp_f32_e32 v47, v47
	s_add_i32 s90, s76, -64
	v_add_u32_e32 v84, s90, v107
	v_add_u32_e32 v85, 0, v84
	v_add_u32_e32 v86, 1, v84
	v_add_u32_e32 v87, 2, v84
	v_add_u32_e32 v88, 3, v84
	v_cmp_gt_u32_e64 s[30:31], s98, v85
	v_cmp_gt_u32_e64 s[36:37], s98, v86
	v_cmp_gt_u32_e64 s[78:79], s98, v87
	v_cmp_gt_u32_e64 s[50:51], s98, v88
	v_cndmask_b32_e64 v32, 0, v32, s[30:31]
	v_add_u32_e32 v85, 8, v84
	v_cmp_gt_u32_e64 s[30:31], s98, v85
	v_cndmask_b32_e64 v33, 0, v33, s[36:37]
	v_add_u32_e32 v86, 9, v84
	v_cmp_gt_u32_e64 s[36:37], s98, v86
	v_cndmask_b32_e64 v34, 0, v34, s[78:79]
	v_add_u32_e32 v87, 10, v84
	v_cmp_gt_u32_e64 s[78:79], s98, v87
	v_cndmask_b32_e64 v35, 0, v35, s[50:51]
	v_add_u32_e32 v88, 11, v84
	v_cmp_gt_u32_e64 s[50:51], s98, v88
	v_cndmask_b32_e64 v36, 0, v36, s[30:31]
	v_add_u32_e32 v85, 16, v84
	v_cmp_gt_u32_e64 s[30:31], s98, v85
	v_cndmask_b32_e64 v37, 0, v37, s[36:37]
	v_add_u32_e32 v86, 17, v84
	v_cmp_gt_u32_e64 s[36:37], s98, v86
	v_cndmask_b32_e64 v38, 0, v38, s[78:79]
	v_add_u32_e32 v87, 18, v84
	v_cmp_gt_u32_e64 s[78:79], s98, v87
	v_cndmask_b32_e64 v39, 0, v39, s[50:51]
	v_add_u32_e32 v88, 19, v84
	v_cmp_gt_u32_e64 s[50:51], s98, v88
	v_cndmask_b32_e64 v40, 0, v40, s[30:31]
	v_add_u32_e32 v85, 24, v84
	v_cmp_gt_u32_e64 s[30:31], s98, v85
	v_cndmask_b32_e64 v41, 0, v41, s[36:37]
	v_add_u32_e32 v86, 25, v84
	v_cmp_gt_u32_e64 s[36:37], s98, v86
	v_cndmask_b32_e64 v42, 0, v42, s[78:79]
	v_add_u32_e32 v87, 26, v84
	v_cmp_gt_u32_e64 s[78:79], s98, v87
	v_cndmask_b32_e64 v43, 0, v43, s[50:51]
	v_add_u32_e32 v88, 27, v84
	v_cmp_gt_u32_e64 s[50:51], s98, v88
	v_nop
	v_cndmask_b32_e64 v44, 0, v44, s[30:31]
	v_cndmask_b32_e64 v45, 0, v45, s[36:37]
	v_cndmask_b32_e64 v46, 0, v46, s[78:79]
	v_cndmask_b32_e64 v47, 0, v47, s[50:51]
	v_cvt_pk_bf16_f32 v64, v32, v33
	v_cvt_pk_bf16_f32 v65, v34, v35
	v_cvt_pk_bf16_f32 v66, v36, v37
	v_cvt_pk_bf16_f32 v67, v38, v39
	v_cvt_pk_bf16_f32 v68, v40, v41
	v_cvt_pk_bf16_f32 v69, v42, v43
	v_cvt_pk_bf16_f32 v70, v44, v45
	v_cvt_pk_bf16_f32 v71, v46, v47
	v_pk_add_f32 v[232:233], v[232:233], v[32:33]
	v_pk_add_f32 v[232:233], v[232:233], v[34:35]
	v_pk_add_f32 v[232:233], v[232:233], v[36:37]
	v_pk_add_f32 v[232:233], v[232:233], v[38:39]
	v_pk_add_f32 v[232:233], v[232:233], v[40:41]
	v_pk_add_f32 v[232:233], v[232:233], v[42:43]
	v_pk_add_f32 v[232:233], v[232:233], v[44:45]
	v_pk_add_f32 v[232:233], v[232:233], v[46:47]
	ds_read2_b32 v[32:33], v115 offset0:68 offset1:69
	ds_read2_b32 v[34:35], v115 offset0:70 offset1:71
	ds_read2_b32 v[36:37], v115 offset0:76 offset1:77
	ds_read2_b32 v[38:39], v115 offset0:78 offset1:79
	ds_read2_b32 v[40:41], v115 offset0:85 offset1:86
	ds_read2_b32 v[42:43], v115 offset0:87 offset1:88
	ds_read2_b32 v[44:45], v115 offset0:93 offset1:94
	ds_read2_b32 v[46:47], v115 offset0:95 offset1:96
	v_mfma_f32_32x32x16_bf16 v[0:15], v[64:67], v[72:75], v[0:15]
	v_mfma_f32_32x32x16_bf16 v[16:31], v[64:67], v[76:79], v[16:31]
	v_mfma_f32_32x32x16_bf16 v[0:15], v[68:71], v[220:223], v[0:15]
	v_mfma_f32_32x32x16_bf16 v[16:31], v[68:71], v[224:227], v[16:31]
	s_add_i32 s90, s76, 32
	v_add_u32_e32 v80, s90, v235
	v_add_u32_e32 v83, s90, v236
	v_add_u32_e32 v99, s90, v237
	v_add_u32_e32 v253, s90, v238
	v_add_u32_e32 v254, s90, v100
	v_add_u32_e32 v255, s90, v149
	v_med3_i32 v80, v80, 0, s99
	v_med3_i32 v83, v83, 0, s99
	v_med3_i32 v99, v99, 0, s99
	v_med3_i32 v253, v253, 0, s99
	v_med3_i32 v254, v254, 0, s99
	v_med3_i32 v255, v255, 0, s99
	v_mad_u32_u24 v80, v80, s100, v252
	v_mad_u32_u24 v83, v83, s100, v252
	v_mad_u32_u24 v99, v99, s100, v252
	v_mad_u32_u24 v253, v253, s100, v252
	v_mad_u32_u24 v254, v254, s100, v153
	v_mad_u32_u24 v255, v255, s100, v153
	global_load_dwordx4 v[156:159], v80, s[82:83]
	global_load_dwordx4 v[160:163], v83, s[82:83]
	global_load_dwordx4 v[164:167], v99, s[82:83]
	global_load_dwordx4 v[168:171], v253, s[82:83]
	global_load_dwordx4 v[172:175], v254, s[82:83] offset:768
	global_load_dwordx4 v[176:179], v255, s[82:83] offset:768
	global_load_dwordx4 v[180:183], v254, s[82:83] offset:832
	global_load_dwordx4 v[184:187], v255, s[82:83] offset:832
	ds_read_b64_tr_b16 v[72:73], v231
	ds_read_b64_tr_b16 v[74:75], v231 offset:512
	ds_read_b64_tr_b16 v[76:77], v231 offset:2048
	ds_read_b64_tr_b16 v[78:79], v231 offset:2560
	ds_read_b64_tr_b16 v[220:221], v231 offset:1024
	ds_read_b64_tr_b16 v[222:223], v231 offset:1536
	ds_read_b64_tr_b16 v[224:225], v231 offset:3072
	ds_read_b64_tr_b16 v[226:227], v231 offset:3584
	s_waitcnt vmcnt(8)
	ds_write_b128 v247, v[116:119]
	ds_write_b128 v247, v[120:123] offset:1024
	ds_write_b128 v247, v[124:127] offset:2048
	ds_write_b128 v247, v[128:131] offset:3072
	ds_read_b128 v[116:119], v248
	ds_read_b128 v[120:123], v249
	ds_read_b128 v[124:127], v250
	ds_read_b128 v[128:131], v251
	ds_write_b128 v112, v[132:135]
	ds_write_b128 v112, v[136:139] offset:1024
	ds_write_b128 v112, v[140:143] offset:2048
	ds_write_b128 v112, v[144:147] offset:3072
	s_waitcnt lgkmcnt(4)
	v_mfma_f32_32x32x16_bf16 v[32:47], v[116:119], v[48:51], v[32:47]
	v_exp_f32_e32 v188, v188
	v_exp_f32_e32 v189, v189
	v_exp_f32_e32 v190, v190
	v_exp_f32_e32 v191, v191
	v_mfma_f32_32x32x16_bf16 v[32:47], v[120:123], v[52:55], v[32:47]
	v_exp_f32_e32 v192, v192
	v_exp_f32_e32 v193, v193
	v_exp_f32_e32 v194, v194
	v_exp_f32_e32 v195, v195
	v_mfma_f32_32x32x16_bf16 v[32:47], v[124:127], v[56:59], v[32:47]
	v_exp_f32_e32 v196, v196
	v_exp_f32_e32 v197, v197
	v_exp_f32_e32 v198, v198
	v_exp_f32_e32 v199, v199
	v_mfma_f32_32x32x16_bf16 v[32:47], v[128:131], v[60:63], v[32:47]
	v_exp_f32_e32 v200, v200
	v_exp_f32_e32 v201, v201
	v_exp_f32_e32 v202, v202
	v_exp_f32_e32 v203, v203
	s_add_i32 s90, s76, -32
	v_add_u32_e32 v84, s90, v107
	v_add_u32_e32 v85, 0, v84
	v_add_u32_e32 v86, 1, v84
	v_add_u32_e32 v87, 2, v84
	v_add_u32_e32 v88, 3, v84
	v_cmp_gt_u32_e64 s[30:31], s98, v85
	v_cmp_gt_u32_e64 s[36:37], s98, v86
	v_cmp_gt_u32_e64 s[78:79], s98, v87
	v_cmp_gt_u32_e64 s[50:51], s98, v88
	v_cndmask_b32_e64 v188, 0, v188, s[30:31]
	v_add_u32_e32 v85, 8, v84
	v_cmp_gt_u32_e64 s[30:31], s98, v85
	v_cndmask_b32_e64 v189, 0, v189, s[36:37]
	v_add_u32_e32 v86, 9, v84
	v_cmp_gt_u32_e64 s[36:37], s98, v86
	v_cndmask_b32_e64 v190, 0, v190, s[78:79]
	v_add_u32_e32 v87, 10, v84
	v_cmp_gt_u32_e64 s[78:79], s98, v87
	v_cndmask_b32_e64 v191, 0, v191, s[50:51]
	v_add_u32_e32 v88, 11, v84
	v_cmp_gt_u32_e64 s[50:51], s98, v88
	v_cndmask_b32_e64 v192, 0, v192, s[30:31]
	v_add_u32_e32 v85, 16, v84
	v_cmp_gt_u32_e64 s[30:31], s98, v85
	v_cndmask_b32_e64 v193, 0, v193, s[36:37]
	v_add_u32_e32 v86, 17, v84
	v_cmp_gt_u32_e64 s[36:37], s98, v86
	v_cndmask_b32_e64 v194, 0, v194, s[78:79]
	v_add_u32_e32 v87, 18, v84
	v_cmp_gt_u32_e64 s[78:79], s98, v87
	v_cndmask_b32_e64 v195, 0, v195, s[50:51]
	v_add_u32_e32 v88, 19, v84
	v_cmp_gt_u32_e64 s[50:51], s98, v88
	v_cndmask_b32_e64 v196, 0, v196, s[30:31]
	v_add_u32_e32 v85, 24, v84
	v_cmp_gt_u32_e64 s[30:31], s98, v85
	v_cndmask_b32_e64 v197, 0, v197, s[36:37]
	v_add_u32_e32 v86, 25, v84
	v_cmp_gt_u32_e64 s[36:37], s98, v86
	v_cndmask_b32_e64 v198, 0, v198, s[78:79]
	v_add_u32_e32 v87, 26, v84
	v_cmp_gt_u32_e64 s[78:79], s98, v87
	v_cndmask_b32_e64 v199, 0, v199, s[50:51]
	v_add_u32_e32 v88, 27, v84
	v_cmp_gt_u32_e64 s[50:51], s98, v88
	v_nop
	v_cndmask_b32_e64 v200, 0, v200, s[30:31]
	v_cndmask_b32_e64 v201, 0, v201, s[36:37]
	v_cndmask_b32_e64 v202, 0, v202, s[78:79]
	v_cndmask_b32_e64 v203, 0, v203, s[50:51]
	v_cvt_pk_bf16_f32 v64, v188, v189
	v_cvt_pk_bf16_f32 v65, v190, v191
	v_cvt_pk_bf16_f32 v66, v192, v193
	v_cvt_pk_bf16_f32 v67, v194, v195
	v_cvt_pk_bf16_f32 v68, v196, v197
	v_cvt_pk_bf16_f32 v69, v198, v199
	v_cvt_pk_bf16_f32 v70, v200, v201
	v_cvt_pk_bf16_f32 v71, v202, v203
	v_pk_add_f32 v[232:233], v[232:233], v[188:189]
	v_pk_add_f32 v[232:233], v[232:233], v[190:191]
	v_pk_add_f32 v[232:233], v[232:233], v[192:193]
	v_pk_add_f32 v[232:233], v[232:233], v[194:195]
	v_pk_add_f32 v[232:233], v[232:233], v[196:197]
	v_pk_add_f32 v[232:233], v[232:233], v[198:199]
	v_pk_add_f32 v[232:233], v[232:233], v[200:201]
	v_pk_add_f32 v[232:233], v[232:233], v[202:203]
	ds_read2_b32 v[188:189], v115 offset0:102 offset1:103
	ds_read2_b32 v[190:191], v115 offset0:104 offset1:105
	ds_read2_b32 v[192:193], v115 offset0:110 offset1:111
	ds_read2_b32 v[194:195], v115 offset0:112 offset1:113
	ds_read2_b32 v[196:197], v115 offset0:119 offset1:120
	ds_read2_b32 v[198:199], v115 offset0:121 offset1:122
	ds_read2_b32 v[200:201], v115 offset0:127 offset1:128
	ds_read2_b32 v[202:203], v115 offset0:129 offset1:130
	v_mfma_f32_32x32x16_bf16 v[0:15], v[64:67], v[72:75], v[0:15]
	v_mfma_f32_32x32x16_bf16 v[16:31], v[64:67], v[76:79], v[16:31]
	v_mfma_f32_32x32x16_bf16 v[0:15], v[68:71], v[220:223], v[0:15]
	v_mfma_f32_32x32x16_bf16 v[16:31], v[68:71], v[224:227], v[16:31]
	s_add_i32 s90, s76, 64
	v_add_u32_e32 v80, s90, v235
	v_add_u32_e32 v83, s90, v236
	v_add_u32_e32 v99, s90, v237
	v_add_u32_e32 v253, s90, v238
	v_add_u32_e32 v254, s90, v100
	v_add_u32_e32 v255, s90, v149
	v_med3_i32 v80, v80, 0, s99
	v_med3_i32 v83, v83, 0, s99
	v_med3_i32 v99, v99, 0, s99
	v_med3_i32 v253, v253, 0, s99
	v_med3_i32 v254, v254, 0, s99
	v_med3_i32 v255, v255, 0, s99
	v_mad_u32_u24 v80, v80, s100, v252
	v_mad_u32_u24 v83, v83, s100, v252
	v_mad_u32_u24 v99, v99, s100, v252
	v_mad_u32_u24 v253, v253, s100, v252
	v_mad_u32_u24 v254, v254, s100, v153
	v_mad_u32_u24 v255, v255, s100, v153
	global_load_dwordx4 v[116:119], v80, s[82:83]
	global_load_dwordx4 v[120:123], v83, s[82:83]
	global_load_dwordx4 v[124:127], v99, s[82:83]
	global_load_dwordx4 v[128:131], v253, s[82:83]
	global_load_dwordx4 v[132:135], v254, s[82:83] offset:768
	global_load_dwordx4 v[136:139], v255, s[82:83] offset:768
	global_load_dwordx4 v[140:143], v254, s[82:83] offset:832
	global_load_dwordx4 v[144:147], v255, s[82:83] offset:832
	ds_read_b64_tr_b16 v[72:73], v231
	ds_read_b64_tr_b16 v[74:75], v231 offset:512
	ds_read_b64_tr_b16 v[76:77], v231 offset:2048
	ds_read_b64_tr_b16 v[78:79], v231 offset:2560
	ds_read_b64_tr_b16 v[220:221], v231 offset:1024
	ds_read_b64_tr_b16 v[222:223], v231 offset:1536
	ds_read_b64_tr_b16 v[224:225], v231 offset:3072
	ds_read_b64_tr_b16 v[226:227], v231 offset:3584
	s_waitcnt vmcnt(8)
	ds_write_b128 v247, v[156:159]
	ds_write_b128 v247, v[160:163] offset:1024
	ds_write_b128 v247, v[164:167] offset:2048
	ds_write_b128 v247, v[168:171] offset:3072
	ds_read_b128 v[156:159], v248
	ds_read_b128 v[160:163], v249
	ds_read_b128 v[164:167], v250
	ds_read_b128 v[168:171], v251
	ds_write_b128 v112, v[172:175]
	ds_write_b128 v112, v[176:179] offset:1024
	ds_write_b128 v112, v[180:183] offset:2048
	ds_write_b128 v112, v[184:187] offset:3072
	s_waitcnt lgkmcnt(4)
	v_mfma_f32_32x32x16_bf16 v[188:203], v[156:159], v[48:51], v[188:203]
	v_exp_f32_e32 v32, v32
	v_exp_f32_e32 v33, v33
	v_exp_f32_e32 v34, v34
	v_exp_f32_e32 v35, v35
	v_mfma_f32_32x32x16_bf16 v[188:203], v[160:163], v[52:55], v[188:203]
	v_exp_f32_e32 v36, v36
	v_exp_f32_e32 v37, v37
	v_exp_f32_e32 v38, v38
	v_exp_f32_e32 v39, v39
	v_mfma_f32_32x32x16_bf16 v[188:203], v[164:167], v[56:59], v[188:203]
	v_exp_f32_e32 v40, v40
	v_exp_f32_e32 v41, v41
	v_exp_f32_e32 v42, v42
	v_exp_f32_e32 v43, v43
	v_mfma_f32_32x32x16_bf16 v[188:203], v[168:171], v[60:63], v[188:203]
	v_exp_f32_e32 v44, v44
	v_exp_f32_e32 v45, v45
	v_exp_f32_e32 v46, v46
	v_exp_f32_e32 v47, v47
	s_add_i32 s90, s76, 0
	v_add_u32_e32 v84, s90, v107
	v_add_u32_e32 v85, 0, v84
	v_add_u32_e32 v86, 1, v84
	v_add_u32_e32 v87, 2, v84
	v_add_u32_e32 v88, 3, v84
	v_cmp_gt_u32_e64 s[30:31], s98, v85
	v_cmp_gt_u32_e64 s[36:37], s98, v86
	v_cmp_gt_u32_e64 s[78:79], s98, v87
	v_cmp_gt_u32_e64 s[50:51], s98, v88
	v_cndmask_b32_e64 v32, 0, v32, s[30:31]
	v_add_u32_e32 v85, 8, v84
	v_cmp_gt_u32_e64 s[30:31], s98, v85
	v_cndmask_b32_e64 v33, 0, v33, s[36:37]
	v_add_u32_e32 v86, 9, v84
	v_cmp_gt_u32_e64 s[36:37], s98, v86
	v_cndmask_b32_e64 v34, 0, v34, s[78:79]
	v_add_u32_e32 v87, 10, v84
	v_cmp_gt_u32_e64 s[78:79], s98, v87
	v_cndmask_b32_e64 v35, 0, v35, s[50:51]
	v_add_u32_e32 v88, 11, v84
	v_cmp_gt_u32_e64 s[50:51], s98, v88
	v_cndmask_b32_e64 v36, 0, v36, s[30:31]
	v_add_u32_e32 v85, 16, v84
	v_cmp_gt_u32_e64 s[30:31], s98, v85
	v_cndmask_b32_e64 v37, 0, v37, s[36:37]
	v_add_u32_e32 v86, 17, v84
	v_cmp_gt_u32_e64 s[36:37], s98, v86
	v_cndmask_b32_e64 v38, 0, v38, s[78:79]
	v_add_u32_e32 v87, 18, v84
	v_cmp_gt_u32_e64 s[78:79], s98, v87
	v_cndmask_b32_e64 v39, 0, v39, s[50:51]
	v_add_u32_e32 v88, 19, v84
	v_cmp_gt_u32_e64 s[50:51], s98, v88
	v_cndmask_b32_e64 v40, 0, v40, s[30:31]
	v_add_u32_e32 v85, 24, v84
	v_cmp_gt_u32_e64 s[30:31], s98, v85
	v_cndmask_b32_e64 v41, 0, v41, s[36:37]
	v_add_u32_e32 v86, 25, v84
	v_cmp_gt_u32_e64 s[36:37], s98, v86
	v_cndmask_b32_e64 v42, 0, v42, s[78:79]
	v_add_u32_e32 v87, 26, v84
	v_cmp_gt_u32_e64 s[78:79], s98, v87
	v_cndmask_b32_e64 v43, 0, v43, s[50:51]
	v_add_u32_e32 v88, 27, v84
	v_cmp_gt_u32_e64 s[50:51], s98, v88
	v_nop
	v_cndmask_b32_e64 v44, 0, v44, s[30:31]
	v_cndmask_b32_e64 v45, 0, v45, s[36:37]
	v_cndmask_b32_e64 v46, 0, v46, s[78:79]
	v_cndmask_b32_e64 v47, 0, v47, s[50:51]
	v_cvt_pk_bf16_f32 v64, v32, v33
	v_cvt_pk_bf16_f32 v65, v34, v35
	v_cvt_pk_bf16_f32 v66, v36, v37
	v_cvt_pk_bf16_f32 v67, v38, v39
	v_cvt_pk_bf16_f32 v68, v40, v41
	v_cvt_pk_bf16_f32 v69, v42, v43
	v_cvt_pk_bf16_f32 v70, v44, v45
	v_cvt_pk_bf16_f32 v71, v46, v47
	v_pk_add_f32 v[232:233], v[232:233], v[32:33]
	v_pk_add_f32 v[232:233], v[232:233], v[34:35]
	v_pk_add_f32 v[232:233], v[232:233], v[36:37]
	v_pk_add_f32 v[232:233], v[232:233], v[38:39]
	v_pk_add_f32 v[232:233], v[232:233], v[40:41]
	v_pk_add_f32 v[232:233], v[232:233], v[42:43]
	v_pk_add_f32 v[232:233], v[232:233], v[44:45]
	v_pk_add_f32 v[232:233], v[232:233], v[46:47]
	ds_read2_b32 v[32:33], v115 offset0:136 offset1:137
	ds_read2_b32 v[34:35], v115 offset0:138 offset1:139
	ds_read2_b32 v[36:37], v115 offset0:144 offset1:145
	ds_read2_b32 v[38:39], v115 offset0:146 offset1:147
	ds_read2_b32 v[40:41], v115 offset0:153 offset1:154
	ds_read2_b32 v[42:43], v115 offset0:155 offset1:156
	ds_read2_b32 v[44:45], v115 offset0:161 offset1:162
	ds_read2_b32 v[46:47], v115 offset0:163 offset1:164
	v_mfma_f32_32x32x16_bf16 v[0:15], v[64:67], v[72:75], v[0:15]
	v_mfma_f32_32x32x16_bf16 v[16:31], v[64:67], v[76:79], v[16:31]
	v_mfma_f32_32x32x16_bf16 v[0:15], v[68:71], v[220:223], v[0:15]
	v_mfma_f32_32x32x16_bf16 v[16:31], v[68:71], v[224:227], v[16:31]
	s_add_i32 s90, s76, 96
	v_add_u32_e32 v80, s90, v235
	v_add_u32_e32 v83, s90, v236
	v_add_u32_e32 v99, s90, v237
	v_add_u32_e32 v253, s90, v238
	v_add_u32_e32 v254, s90, v100
	v_add_u32_e32 v255, s90, v149
	v_med3_i32 v80, v80, 0, s99
	v_med3_i32 v83, v83, 0, s99
	v_med3_i32 v99, v99, 0, s99
	v_med3_i32 v253, v253, 0, s99
	v_med3_i32 v254, v254, 0, s99
	v_med3_i32 v255, v255, 0, s99
	v_mad_u32_u24 v80, v80, s100, v252
	v_mad_u32_u24 v83, v83, s100, v252
	v_mad_u32_u24 v99, v99, s100, v252
	v_mad_u32_u24 v253, v253, s100, v252
	v_mad_u32_u24 v254, v254, s100, v153
	v_mad_u32_u24 v255, v255, s100, v153
	global_load_dwordx4 v[156:159], v80, s[82:83]
	global_load_dwordx4 v[160:163], v83, s[82:83]
	global_load_dwordx4 v[164:167], v99, s[82:83]
	global_load_dwordx4 v[168:171], v253, s[82:83]
	global_load_dwordx4 v[172:175], v254, s[82:83] offset:768
	global_load_dwordx4 v[176:179], v255, s[82:83] offset:768
	global_load_dwordx4 v[180:183], v254, s[82:83] offset:832
	global_load_dwordx4 v[184:187], v255, s[82:83] offset:832
	ds_read_b64_tr_b16 v[72:73], v231
	ds_read_b64_tr_b16 v[74:75], v231 offset:512
	ds_read_b64_tr_b16 v[76:77], v231 offset:2048
	ds_read_b64_tr_b16 v[78:79], v231 offset:2560
	ds_read_b64_tr_b16 v[220:221], v231 offset:1024
	ds_read_b64_tr_b16 v[222:223], v231 offset:1536
	ds_read_b64_tr_b16 v[224:225], v231 offset:3072
	ds_read_b64_tr_b16 v[226:227], v231 offset:3584
	s_waitcnt vmcnt(8)
	ds_write_b128 v247, v[116:119]
	ds_write_b128 v247, v[120:123] offset:1024
	ds_write_b128 v247, v[124:127] offset:2048
	ds_write_b128 v247, v[128:131] offset:3072
	ds_read_b128 v[116:119], v248
	ds_read_b128 v[120:123], v249
	ds_read_b128 v[124:127], v250
	ds_read_b128 v[128:131], v251
	ds_write_b128 v112, v[132:135]
	ds_write_b128 v112, v[136:139] offset:1024
	ds_write_b128 v112, v[140:143] offset:2048
	ds_write_b128 v112, v[144:147] offset:3072
	s_waitcnt lgkmcnt(4)
	v_mfma_f32_32x32x16_bf16 v[32:47], v[116:119], v[48:51], v[32:47]
	v_exp_f32_e32 v188, v188
	v_exp_f32_e32 v189, v189
	v_exp_f32_e32 v190, v190
	v_exp_f32_e32 v191, v191
	v_mfma_f32_32x32x16_bf16 v[32:47], v[120:123], v[52:55], v[32:47]
	v_exp_f32_e32 v192, v192
	v_exp_f32_e32 v193, v193
	v_exp_f32_e32 v194, v194
	v_exp_f32_e32 v195, v195
	v_mfma_f32_32x32x16_bf16 v[32:47], v[124:127], v[56:59], v[32:47]
	v_exp_f32_e32 v196, v196
	v_exp_f32_e32 v197, v197
	v_exp_f32_e32 v198, v198
	v_exp_f32_e32 v199, v199
	v_mfma_f32_32x32x16_bf16 v[32:47], v[128:131], v[60:63], v[32:47]
	v_exp_f32_e32 v200, v200
	v_exp_f32_e32 v201, v201
	v_exp_f32_e32 v202, v202
	v_exp_f32_e32 v203, v203
	s_add_i32 s90, s76, 32
	v_add_u32_e32 v84, s90, v107
	v_add_u32_e32 v85, 0, v84
	v_add_u32_e32 v86, 1, v84
	v_add_u32_e32 v87, 2, v84
	v_add_u32_e32 v88, 3, v84
	v_cmp_gt_u32_e64 s[30:31], s98, v85
	v_cmp_gt_u32_e64 s[36:37], s98, v86
	v_cmp_gt_u32_e64 s[78:79], s98, v87
	v_cmp_gt_u32_e64 s[50:51], s98, v88
	v_cndmask_b32_e64 v188, 0, v188, s[30:31]
	v_add_u32_e32 v85, 8, v84
	v_cmp_gt_u32_e64 s[30:31], s98, v85
	v_cndmask_b32_e64 v189, 0, v189, s[36:37]
	v_add_u32_e32 v86, 9, v84
	v_cmp_gt_u32_e64 s[36:37], s98, v86
	v_cndmask_b32_e64 v190, 0, v190, s[78:79]
	v_add_u32_e32 v87, 10, v84
	v_cmp_gt_u32_e64 s[78:79], s98, v87
	v_cndmask_b32_e64 v191, 0, v191, s[50:51]
	v_add_u32_e32 v88, 11, v84
	v_cmp_gt_u32_e64 s[50:51], s98, v88
	v_cndmask_b32_e64 v192, 0, v192, s[30:31]
	v_add_u32_e32 v85, 16, v84
	v_cmp_gt_u32_e64 s[30:31], s98, v85
	v_cndmask_b32_e64 v193, 0, v193, s[36:37]
	v_add_u32_e32 v86, 17, v84
	v_cmp_gt_u32_e64 s[36:37], s98, v86
	v_cndmask_b32_e64 v194, 0, v194, s[78:79]
	v_add_u32_e32 v87, 18, v84
	v_cmp_gt_u32_e64 s[78:79], s98, v87
	v_cndmask_b32_e64 v195, 0, v195, s[50:51]
	v_add_u32_e32 v88, 19, v84
	v_cmp_gt_u32_e64 s[50:51], s98, v88
	v_cndmask_b32_e64 v196, 0, v196, s[30:31]
	v_add_u32_e32 v85, 24, v84
	v_cmp_gt_u32_e64 s[30:31], s98, v85
	v_cndmask_b32_e64 v197, 0, v197, s[36:37]
	v_add_u32_e32 v86, 25, v84
	v_cmp_gt_u32_e64 s[36:37], s98, v86
	v_cndmask_b32_e64 v198, 0, v198, s[78:79]
	v_add_u32_e32 v87, 26, v84
	v_cmp_gt_u32_e64 s[78:79], s98, v87
	v_cndmask_b32_e64 v199, 0, v199, s[50:51]
	v_add_u32_e32 v88, 27, v84
	v_cmp_gt_u32_e64 s[50:51], s98, v88
	v_nop
	v_cndmask_b32_e64 v200, 0, v200, s[30:31]
	v_cndmask_b32_e64 v201, 0, v201, s[36:37]
	v_cndmask_b32_e64 v202, 0, v202, s[78:79]
	v_cndmask_b32_e64 v203, 0, v203, s[50:51]
	v_cvt_pk_bf16_f32 v64, v188, v189
	v_cvt_pk_bf16_f32 v65, v190, v191
	v_cvt_pk_bf16_f32 v66, v192, v193
	v_cvt_pk_bf16_f32 v67, v194, v195
	v_cvt_pk_bf16_f32 v68, v196, v197
	v_cvt_pk_bf16_f32 v69, v198, v199
	v_cvt_pk_bf16_f32 v70, v200, v201
	v_cvt_pk_bf16_f32 v71, v202, v203
	v_pk_add_f32 v[232:233], v[232:233], v[188:189]
	v_pk_add_f32 v[232:233], v[232:233], v[190:191]
	v_pk_add_f32 v[232:233], v[232:233], v[192:193]
	v_pk_add_f32 v[232:233], v[232:233], v[194:195]
	v_pk_add_f32 v[232:233], v[232:233], v[196:197]
	v_pk_add_f32 v[232:233], v[232:233], v[198:199]
	v_pk_add_f32 v[232:233], v[232:233], v[200:201]
	v_pk_add_f32 v[232:233], v[232:233], v[202:203]
	ds_read2_b32 v[188:189], v115 offset0:170 offset1:171
	ds_read2_b32 v[190:191], v115 offset0:172 offset1:173
	ds_read2_b32 v[192:193], v115 offset0:178 offset1:179
	ds_read2_b32 v[194:195], v115 offset0:180 offset1:181
	ds_read2_b32 v[196:197], v115 offset0:187 offset1:188
	ds_read2_b32 v[198:199], v115 offset0:189 offset1:190
	ds_read2_b32 v[200:201], v115 offset0:195 offset1:196
	ds_read2_b32 v[202:203], v115 offset0:197 offset1:198
	v_mfma_f32_32x32x16_bf16 v[0:15], v[64:67], v[72:75], v[0:15]
	v_mfma_f32_32x32x16_bf16 v[16:31], v[64:67], v[76:79], v[16:31]
	v_mfma_f32_32x32x16_bf16 v[0:15], v[68:71], v[220:223], v[0:15]
	v_mfma_f32_32x32x16_bf16 v[16:31], v[68:71], v[224:227], v[16:31]
	s_add_i32 s90, s76, 128
	v_add_u32_e32 v80, s90, v235
	v_add_u32_e32 v83, s90, v236
	v_add_u32_e32 v99, s90, v237
	v_add_u32_e32 v253, s90, v238
	v_add_u32_e32 v254, s90, v100
	v_add_u32_e32 v255, s90, v149
	v_med3_i32 v80, v80, 0, s99
	v_med3_i32 v83, v83, 0, s99
	v_med3_i32 v99, v99, 0, s99
	v_med3_i32 v253, v253, 0, s99
	v_med3_i32 v254, v254, 0, s99
	v_med3_i32 v255, v255, 0, s99
	v_mad_u32_u24 v80, v80, s100, v252
	v_mad_u32_u24 v83, v83, s100, v252
	v_mad_u32_u24 v99, v99, s100, v252
	v_mad_u32_u24 v253, v253, s100, v252
	v_mad_u32_u24 v254, v254, s100, v153
	v_mad_u32_u24 v255, v255, s100, v153
	global_load_dwordx4 v[116:119], v80, s[82:83]
	global_load_dwordx4 v[120:123], v83, s[82:83]
	global_load_dwordx4 v[124:127], v99, s[82:83]
	global_load_dwordx4 v[128:131], v253, s[82:83]
	global_load_dwordx4 v[132:135], v254, s[82:83] offset:768
	global_load_dwordx4 v[136:139], v255, s[82:83] offset:768
	global_load_dwordx4 v[140:143], v254, s[82:83] offset:832
	global_load_dwordx4 v[144:147], v255, s[82:83] offset:832
	ds_read_b64_tr_b16 v[72:73], v231
	ds_read_b64_tr_b16 v[74:75], v231 offset:512
	ds_read_b64_tr_b16 v[76:77], v231 offset:2048
	ds_read_b64_tr_b16 v[78:79], v231 offset:2560
	ds_read_b64_tr_b16 v[220:221], v231 offset:1024
	ds_read_b64_tr_b16 v[222:223], v231 offset:1536
	ds_read_b64_tr_b16 v[224:225], v231 offset:3072
	ds_read_b64_tr_b16 v[226:227], v231 offset:3584
	s_waitcnt vmcnt(8)
	ds_write_b128 v247, v[156:159]
	ds_write_b128 v247, v[160:163] offset:1024
	ds_write_b128 v247, v[164:167] offset:2048
	ds_write_b128 v247, v[168:171] offset:3072
	ds_read_b128 v[156:159], v248
	ds_read_b128 v[160:163], v249
	ds_read_b128 v[164:167], v250
	ds_read_b128 v[168:171], v251
	ds_write_b128 v112, v[172:175]
	ds_write_b128 v112, v[176:179] offset:1024
	ds_write_b128 v112, v[180:183] offset:2048
	ds_write_b128 v112, v[184:187] offset:3072
	s_waitcnt lgkmcnt(4)
	v_mfma_f32_32x32x16_bf16 v[188:203], v[156:159], v[48:51], v[188:203]
	v_exp_f32_e32 v32, v32
	v_exp_f32_e32 v33, v33
	v_exp_f32_e32 v34, v34
	v_exp_f32_e32 v35, v35
	v_mfma_f32_32x32x16_bf16 v[188:203], v[160:163], v[52:55], v[188:203]
	v_exp_f32_e32 v36, v36
	v_exp_f32_e32 v37, v37
	v_exp_f32_e32 v38, v38
	v_exp_f32_e32 v39, v39
	v_mfma_f32_32x32x16_bf16 v[188:203], v[164:167], v[56:59], v[188:203]
	v_exp_f32_e32 v40, v40
	v_exp_f32_e32 v41, v41
	v_exp_f32_e32 v42, v42
	v_exp_f32_e32 v43, v43
	v_mfma_f32_32x32x16_bf16 v[188:203], v[168:171], v[60:63], v[188:203]
	v_exp_f32_e32 v44, v44
	v_exp_f32_e32 v45, v45
	v_exp_f32_e32 v46, v46
	v_exp_f32_e32 v47, v47
	s_add_i32 s90, s76, 64
	v_add_u32_e32 v84, s90, v107
	v_add_u32_e32 v85, 0, v84
	v_add_u32_e32 v86, 1, v84
	v_add_u32_e32 v87, 2, v84
	v_add_u32_e32 v88, 3, v84
	v_cmp_gt_u32_e64 s[30:31], s98, v85
	v_cmp_gt_u32_e64 s[36:37], s98, v86
	v_cmp_gt_u32_e64 s[78:79], s98, v87
	v_cmp_gt_u32_e64 s[50:51], s98, v88
	v_cndmask_b32_e64 v32, 0, v32, s[30:31]
	v_add_u32_e32 v85, 8, v84
	v_cmp_gt_u32_e64 s[30:31], s98, v85
	v_cndmask_b32_e64 v33, 0, v33, s[36:37]
	v_add_u32_e32 v86, 9, v84
	v_cmp_gt_u32_e64 s[36:37], s98, v86
	v_cndmask_b32_e64 v34, 0, v34, s[78:79]
	v_add_u32_e32 v87, 10, v84
	v_cmp_gt_u32_e64 s[78:79], s98, v87
	v_cndmask_b32_e64 v35, 0, v35, s[50:51]
	v_add_u32_e32 v88, 11, v84
	v_cmp_gt_u32_e64 s[50:51], s98, v88
	v_cndmask_b32_e64 v36, 0, v36, s[30:31]
	v_add_u32_e32 v85, 16, v84
	v_cmp_gt_u32_e64 s[30:31], s98, v85
	v_cndmask_b32_e64 v37, 0, v37, s[36:37]
	v_add_u32_e32 v86, 17, v84
	v_cmp_gt_u32_e64 s[36:37], s98, v86
	v_cndmask_b32_e64 v38, 0, v38, s[78:79]
	v_add_u32_e32 v87, 18, v84
	v_cmp_gt_u32_e64 s[78:79], s98, v87
	v_cndmask_b32_e64 v39, 0, v39, s[50:51]
	v_add_u32_e32 v88, 19, v84
	v_cmp_gt_u32_e64 s[50:51], s98, v88
	v_cndmask_b32_e64 v40, 0, v40, s[30:31]
	v_add_u32_e32 v85, 24, v84
	v_cmp_gt_u32_e64 s[30:31], s98, v85
	v_cndmask_b32_e64 v41, 0, v41, s[36:37]
	v_add_u32_e32 v86, 25, v84
	v_cmp_gt_u32_e64 s[36:37], s98, v86
	v_cndmask_b32_e64 v42, 0, v42, s[78:79]
	v_add_u32_e32 v87, 26, v84
	v_cmp_gt_u32_e64 s[78:79], s98, v87
	v_cndmask_b32_e64 v43, 0, v43, s[50:51]
	v_add_u32_e32 v88, 27, v84
	v_cmp_gt_u32_e64 s[50:51], s98, v88
	v_nop
	v_cndmask_b32_e64 v44, 0, v44, s[30:31]
	v_cndmask_b32_e64 v45, 0, v45, s[36:37]
	v_cndmask_b32_e64 v46, 0, v46, s[78:79]
	v_cndmask_b32_e64 v47, 0, v47, s[50:51]
	v_cvt_pk_bf16_f32 v64, v32, v33
	v_cvt_pk_bf16_f32 v65, v34, v35
	v_cvt_pk_bf16_f32 v66, v36, v37
	v_cvt_pk_bf16_f32 v67, v38, v39
	v_cvt_pk_bf16_f32 v68, v40, v41
	v_cvt_pk_bf16_f32 v69, v42, v43
	v_cvt_pk_bf16_f32 v70, v44, v45
	v_cvt_pk_bf16_f32 v71, v46, v47
	v_pk_add_f32 v[232:233], v[232:233], v[32:33]
	v_pk_add_f32 v[232:233], v[232:233], v[34:35]
	v_pk_add_f32 v[232:233], v[232:233], v[36:37]
	v_pk_add_f32 v[232:233], v[232:233], v[38:39]
	v_pk_add_f32 v[232:233], v[232:233], v[40:41]
	v_pk_add_f32 v[232:233], v[232:233], v[42:43]
	v_pk_add_f32 v[232:233], v[232:233], v[44:45]
	v_pk_add_f32 v[232:233], v[232:233], v[46:47]
	ds_read2_b32 v[32:33], v115 offset0:204 offset1:205
	ds_read2_b32 v[34:35], v115 offset0:206 offset1:207
	ds_read2_b32 v[36:37], v115 offset0:212 offset1:213
	ds_read2_b32 v[38:39], v115 offset0:214 offset1:215
	ds_read2_b32 v[40:41], v115 offset0:221 offset1:222
	ds_read2_b32 v[42:43], v115 offset0:223 offset1:224
	ds_read2_b32 v[44:45], v115 offset0:229 offset1:230
	ds_read2_b32 v[46:47], v115 offset0:231 offset1:232
	v_mfma_f32_32x32x16_bf16 v[0:15], v[64:67], v[72:75], v[0:15]
	v_mfma_f32_32x32x16_bf16 v[16:31], v[64:67], v[76:79], v[16:31]
	v_mfma_f32_32x32x16_bf16 v[0:15], v[68:71], v[220:223], v[0:15]
	v_mfma_f32_32x32x16_bf16 v[16:31], v[68:71], v[224:227], v[16:31]
	s_add_i32 s90, s76, 160
	v_add_u32_e32 v80, s90, v235
	v_add_u32_e32 v83, s90, v236
	v_add_u32_e32 v99, s90, v237
	v_add_u32_e32 v253, s90, v238
	v_add_u32_e32 v254, s90, v100
	v_add_u32_e32 v255, s90, v149
	v_med3_i32 v80, v80, 0, s99
	v_med3_i32 v83, v83, 0, s99
	v_med3_i32 v99, v99, 0, s99
	v_med3_i32 v253, v253, 0, s99
	v_med3_i32 v254, v254, 0, s99
	v_med3_i32 v255, v255, 0, s99
	v_mad_u32_u24 v80, v80, s100, v252
	v_mad_u32_u24 v83, v83, s100, v252
	v_mad_u32_u24 v99, v99, s100, v252
	v_mad_u32_u24 v253, v253, s100, v252
	v_mad_u32_u24 v254, v254, s100, v153
	v_mad_u32_u24 v255, v255, s100, v153
	global_load_dwordx4 v[156:159], v80, s[82:83]
	global_load_dwordx4 v[160:163], v83, s[82:83]
	global_load_dwordx4 v[164:167], v99, s[82:83]
	global_load_dwordx4 v[168:171], v253, s[82:83]
	global_load_dwordx4 v[172:175], v254, s[82:83] offset:768
	global_load_dwordx4 v[176:179], v255, s[82:83] offset:768
	global_load_dwordx4 v[180:183], v254, s[82:83] offset:832
	global_load_dwordx4 v[184:187], v255, s[82:83] offset:832
	ds_read_b64_tr_b16 v[72:73], v231
	ds_read_b64_tr_b16 v[74:75], v231 offset:512
	ds_read_b64_tr_b16 v[76:77], v231 offset:2048
	ds_read_b64_tr_b16 v[78:79], v231 offset:2560
	ds_read_b64_tr_b16 v[220:221], v231 offset:1024
	ds_read_b64_tr_b16 v[222:223], v231 offset:1536
	ds_read_b64_tr_b16 v[224:225], v231 offset:3072
	ds_read_b64_tr_b16 v[226:227], v231 offset:3584
	s_waitcnt vmcnt(8)
	ds_write_b128 v247, v[116:119]
	ds_write_b128 v247, v[120:123] offset:1024
	ds_write_b128 v247, v[124:127] offset:2048
	ds_write_b128 v247, v[128:131] offset:3072
	ds_read_b128 v[116:119], v248
	ds_read_b128 v[120:123], v249
	ds_read_b128 v[124:127], v250
	ds_read_b128 v[128:131], v251
	ds_write_b128 v112, v[132:135]
	ds_write_b128 v112, v[136:139] offset:1024
	ds_write_b128 v112, v[140:143] offset:2048
	ds_write_b128 v112, v[144:147] offset:3072
	s_waitcnt lgkmcnt(4)
	v_mfma_f32_32x32x16_bf16 v[32:47], v[116:119], v[48:51], v[32:47]
	v_exp_f32_e32 v188, v188
	v_exp_f32_e32 v189, v189
	v_exp_f32_e32 v190, v190
	v_exp_f32_e32 v191, v191
	v_mfma_f32_32x32x16_bf16 v[32:47], v[120:123], v[52:55], v[32:47]
	v_exp_f32_e32 v192, v192
	v_exp_f32_e32 v193, v193
	v_exp_f32_e32 v194, v194
	v_exp_f32_e32 v195, v195
	v_mfma_f32_32x32x16_bf16 v[32:47], v[124:127], v[56:59], v[32:47]
	v_exp_f32_e32 v196, v196
	v_exp_f32_e32 v197, v197
	v_exp_f32_e32 v198, v198
	v_exp_f32_e32 v199, v199
	v_mfma_f32_32x32x16_bf16 v[32:47], v[128:131], v[60:63], v[32:47]
	v_exp_f32_e32 v200, v200
	v_exp_f32_e32 v201, v201
	v_exp_f32_e32 v202, v202
	v_exp_f32_e32 v203, v203
	s_add_i32 s90, s76, 96
	v_add_u32_e32 v84, s90, v107
	v_add_u32_e32 v85, 0, v84
	v_add_u32_e32 v86, 1, v84
	v_add_u32_e32 v87, 2, v84
	v_add_u32_e32 v88, 3, v84
	v_cmp_gt_u32_e64 s[30:31], s98, v85
	v_cmp_gt_u32_e64 s[36:37], s98, v86
	v_cmp_gt_u32_e64 s[78:79], s98, v87
	v_cmp_gt_u32_e64 s[50:51], s98, v88
	v_cndmask_b32_e64 v188, 0, v188, s[30:31]
	v_add_u32_e32 v85, 8, v84
	v_cmp_gt_u32_e64 s[30:31], s98, v85
	v_cndmask_b32_e64 v189, 0, v189, s[36:37]
	v_add_u32_e32 v86, 9, v84
	v_cmp_gt_u32_e64 s[36:37], s98, v86
	v_cndmask_b32_e64 v190, 0, v190, s[78:79]
	v_add_u32_e32 v87, 10, v84
	v_cmp_gt_u32_e64 s[78:79], s98, v87
	v_cndmask_b32_e64 v191, 0, v191, s[50:51]
	v_add_u32_e32 v88, 11, v84
	v_cmp_gt_u32_e64 s[50:51], s98, v88
	v_cndmask_b32_e64 v192, 0, v192, s[30:31]
	v_add_u32_e32 v85, 16, v84
	v_cmp_gt_u32_e64 s[30:31], s98, v85
	v_cndmask_b32_e64 v193, 0, v193, s[36:37]
	v_add_u32_e32 v86, 17, v84
	v_cmp_gt_u32_e64 s[36:37], s98, v86
	v_cndmask_b32_e64 v194, 0, v194, s[78:79]
	v_add_u32_e32 v87, 18, v84
	v_cmp_gt_u32_e64 s[78:79], s98, v87
	v_cndmask_b32_e64 v195, 0, v195, s[50:51]
	v_add_u32_e32 v88, 19, v84
	v_cmp_gt_u32_e64 s[50:51], s98, v88
	v_cndmask_b32_e64 v196, 0, v196, s[30:31]
	v_add_u32_e32 v85, 24, v84
	v_cmp_gt_u32_e64 s[30:31], s98, v85
	v_cndmask_b32_e64 v197, 0, v197, s[36:37]
	v_add_u32_e32 v86, 25, v84
	v_cmp_gt_u32_e64 s[36:37], s98, v86
	v_cndmask_b32_e64 v198, 0, v198, s[78:79]
	v_add_u32_e32 v87, 26, v84
	v_cmp_gt_u32_e64 s[78:79], s98, v87
	v_cndmask_b32_e64 v199, 0, v199, s[50:51]
	v_add_u32_e32 v88, 27, v84
	v_cmp_gt_u32_e64 s[50:51], s98, v88
	v_nop
	v_cndmask_b32_e64 v200, 0, v200, s[30:31]
	v_cndmask_b32_e64 v201, 0, v201, s[36:37]
	v_cndmask_b32_e64 v202, 0, v202, s[78:79]
	v_cndmask_b32_e64 v203, 0, v203, s[50:51]
	v_cvt_pk_bf16_f32 v64, v188, v189
	v_cvt_pk_bf16_f32 v65, v190, v191
	v_cvt_pk_bf16_f32 v66, v192, v193
	v_cvt_pk_bf16_f32 v67, v194, v195
	v_cvt_pk_bf16_f32 v68, v196, v197
	v_cvt_pk_bf16_f32 v69, v198, v199
	v_cvt_pk_bf16_f32 v70, v200, v201
	v_cvt_pk_bf16_f32 v71, v202, v203
	v_pk_add_f32 v[232:233], v[232:233], v[188:189]
	v_pk_add_f32 v[232:233], v[232:233], v[190:191]
	v_pk_add_f32 v[232:233], v[232:233], v[192:193]
	v_pk_add_f32 v[232:233], v[232:233], v[194:195]
	v_pk_add_f32 v[232:233], v[232:233], v[196:197]
	v_pk_add_f32 v[232:233], v[232:233], v[198:199]
	v_pk_add_f32 v[232:233], v[232:233], v[200:201]
	v_pk_add_f32 v[232:233], v[232:233], v[202:203]
	v_add_u32_e32 v115, 952, v115
	ds_read2_b32 v[188:189], v115 offset0:0 offset1:1
	ds_read2_b32 v[190:191], v115 offset0:2 offset1:3
	ds_read2_b32 v[192:193], v115 offset0:8 offset1:9
	ds_read2_b32 v[194:195], v115 offset0:10 offset1:11
	ds_read2_b32 v[196:197], v115 offset0:17 offset1:18
	ds_read2_b32 v[198:199], v115 offset0:19 offset1:20
	ds_read2_b32 v[200:201], v115 offset0:25 offset1:26
	ds_read2_b32 v[202:203], v115 offset0:27 offset1:28
	v_mfma_f32_32x32x16_bf16 v[0:15], v[64:67], v[72:75], v[0:15]
	v_mfma_f32_32x32x16_bf16 v[16:31], v[64:67], v[76:79], v[16:31]
	v_mfma_f32_32x32x16_bf16 v[0:15], v[68:71], v[220:223], v[0:15]
	v_mfma_f32_32x32x16_bf16 v[16:31], v[68:71], v[224:227], v[16:31]
	s_add_i32 s90, s76, 192
	v_add_u32_e32 v80, s90, v235
	v_add_u32_e32 v83, s90, v236
	v_add_u32_e32 v99, s90, v237
	v_add_u32_e32 v253, s90, v238
	v_add_u32_e32 v254, s90, v100
	v_add_u32_e32 v255, s90, v149
	v_med3_i32 v80, v80, 0, s99
	v_med3_i32 v83, v83, 0, s99
	v_med3_i32 v99, v99, 0, s99
	v_med3_i32 v253, v253, 0, s99
	v_med3_i32 v254, v254, 0, s99
	v_med3_i32 v255, v255, 0, s99
	v_mad_u32_u24 v80, v80, s100, v252
	v_mad_u32_u24 v83, v83, s100, v252
	v_mad_u32_u24 v99, v99, s100, v252
	v_mad_u32_u24 v253, v253, s100, v252
	v_mad_u32_u24 v254, v254, s100, v153
	v_mad_u32_u24 v255, v255, s100, v153
	global_load_dwordx4 v[116:119], v80, s[82:83]
	global_load_dwordx4 v[120:123], v83, s[82:83]
	global_load_dwordx4 v[124:127], v99, s[82:83]
	global_load_dwordx4 v[128:131], v253, s[82:83]
	global_load_dwordx4 v[132:135], v254, s[82:83] offset:768
	global_load_dwordx4 v[136:139], v255, s[82:83] offset:768
	global_load_dwordx4 v[140:143], v254, s[82:83] offset:832
	global_load_dwordx4 v[144:147], v255, s[82:83] offset:832
	ds_read_b64_tr_b16 v[72:73], v231
	ds_read_b64_tr_b16 v[74:75], v231 offset:512
	ds_read_b64_tr_b16 v[76:77], v231 offset:2048
	ds_read_b64_tr_b16 v[78:79], v231 offset:2560
	ds_read_b64_tr_b16 v[220:221], v231 offset:1024
	ds_read_b64_tr_b16 v[222:223], v231 offset:1536
	ds_read_b64_tr_b16 v[224:225], v231 offset:3072
	ds_read_b64_tr_b16 v[226:227], v231 offset:3584
	s_waitcnt vmcnt(8)
	ds_write_b128 v247, v[156:159]
	ds_write_b128 v247, v[160:163] offset:1024
	ds_write_b128 v247, v[164:167] offset:2048
	ds_write_b128 v247, v[168:171] offset:3072
	ds_read_b128 v[156:159], v248
	ds_read_b128 v[160:163], v249
	ds_read_b128 v[164:167], v250
	ds_read_b128 v[168:171], v251
	ds_write_b128 v112, v[172:175]
	ds_write_b128 v112, v[176:179] offset:1024
	ds_write_b128 v112, v[180:183] offset:2048
	ds_write_b128 v112, v[184:187] offset:3072
	s_waitcnt lgkmcnt(4)
	v_mfma_f32_32x32x16_bf16 v[188:203], v[156:159], v[48:51], v[188:203]
	v_exp_f32_e32 v32, v32
	v_exp_f32_e32 v33, v33
	v_exp_f32_e32 v34, v34
	v_exp_f32_e32 v35, v35
	v_mfma_f32_32x32x16_bf16 v[188:203], v[160:163], v[52:55], v[188:203]
	v_exp_f32_e32 v36, v36
	v_exp_f32_e32 v37, v37
	v_exp_f32_e32 v38, v38
	v_exp_f32_e32 v39, v39
	v_mfma_f32_32x32x16_bf16 v[188:203], v[164:167], v[56:59], v[188:203]
	v_exp_f32_e32 v40, v40
	v_exp_f32_e32 v41, v41
	v_exp_f32_e32 v42, v42
	v_exp_f32_e32 v43, v43
	v_mfma_f32_32x32x16_bf16 v[188:203], v[168:171], v[60:63], v[188:203]
	v_exp_f32_e32 v44, v44
	v_exp_f32_e32 v45, v45
	v_exp_f32_e32 v46, v46
	v_exp_f32_e32 v47, v47
	s_add_i32 s90, s76, 128
	v_add_u32_e32 v84, s90, v107
	v_add_u32_e32 v85, 0, v84
	v_add_u32_e32 v86, 1, v84
	v_add_u32_e32 v87, 2, v84
	v_add_u32_e32 v88, 3, v84
	v_cmp_gt_u32_e64 s[30:31], s98, v85
	v_cmp_gt_u32_e64 s[36:37], s98, v86
	v_cmp_gt_u32_e64 s[78:79], s98, v87
	v_cmp_gt_u32_e64 s[50:51], s98, v88
	v_cndmask_b32_e64 v32, 0, v32, s[30:31]
	v_add_u32_e32 v85, 8, v84
	v_cmp_gt_u32_e64 s[30:31], s98, v85
	v_cndmask_b32_e64 v33, 0, v33, s[36:37]
	v_add_u32_e32 v86, 9, v84
	v_cmp_gt_u32_e64 s[36:37], s98, v86
	v_cndmask_b32_e64 v34, 0, v34, s[78:79]
	v_add_u32_e32 v87, 10, v84
	v_cmp_gt_u32_e64 s[78:79], s98, v87
	v_cndmask_b32_e64 v35, 0, v35, s[50:51]
	v_add_u32_e32 v88, 11, v84
	v_cmp_gt_u32_e64 s[50:51], s98, v88
	v_cndmask_b32_e64 v36, 0, v36, s[30:31]
	v_add_u32_e32 v85, 16, v84
	v_cmp_gt_u32_e64 s[30:31], s98, v85
	v_cndmask_b32_e64 v37, 0, v37, s[36:37]
	v_add_u32_e32 v86, 17, v84
	v_cmp_gt_u32_e64 s[36:37], s98, v86
	v_cndmask_b32_e64 v38, 0, v38, s[78:79]
	v_add_u32_e32 v87, 18, v84
	v_cmp_gt_u32_e64 s[78:79], s98, v87
	v_cndmask_b32_e64 v39, 0, v39, s[50:51]
	v_add_u32_e32 v88, 19, v84
	v_cmp_gt_u32_e64 s[50:51], s98, v88
	v_cndmask_b32_e64 v40, 0, v40, s[30:31]
	v_add_u32_e32 v85, 24, v84
	v_cmp_gt_u32_e64 s[30:31], s98, v85
	v_cndmask_b32_e64 v41, 0, v41, s[36:37]
	v_add_u32_e32 v86, 25, v84
	v_cmp_gt_u32_e64 s[36:37], s98, v86
	v_cndmask_b32_e64 v42, 0, v42, s[78:79]
	v_add_u32_e32 v87, 26, v84
	v_cmp_gt_u32_e64 s[78:79], s98, v87
	v_cndmask_b32_e64 v43, 0, v43, s[50:51]
	v_add_u32_e32 v88, 27, v84
	v_cmp_gt_u32_e64 s[50:51], s98, v88
	v_nop
	v_cndmask_b32_e64 v44, 0, v44, s[30:31]
	v_cndmask_b32_e64 v45, 0, v45, s[36:37]
	v_cndmask_b32_e64 v46, 0, v46, s[78:79]
	v_cndmask_b32_e64 v47, 0, v47, s[50:51]
	v_cvt_pk_bf16_f32 v64, v32, v33
	v_cvt_pk_bf16_f32 v65, v34, v35
	v_cvt_pk_bf16_f32 v66, v36, v37
	v_cvt_pk_bf16_f32 v67, v38, v39
	v_cvt_pk_bf16_f32 v68, v40, v41
	v_cvt_pk_bf16_f32 v69, v42, v43
	v_cvt_pk_bf16_f32 v70, v44, v45
	v_cvt_pk_bf16_f32 v71, v46, v47
	v_pk_add_f32 v[232:233], v[232:233], v[32:33]
	v_pk_add_f32 v[232:233], v[232:233], v[34:35]
	v_pk_add_f32 v[232:233], v[232:233], v[36:37]
	v_pk_add_f32 v[232:233], v[232:233], v[38:39]
	v_pk_add_f32 v[232:233], v[232:233], v[40:41]
	v_pk_add_f32 v[232:233], v[232:233], v[42:43]
	v_pk_add_f32 v[232:233], v[232:233], v[44:45]
	v_pk_add_f32 v[232:233], v[232:233], v[46:47]
	ds_read2_b32 v[32:33], v115 offset0:34 offset1:35
	ds_read2_b32 v[34:35], v115 offset0:36 offset1:37
	ds_read2_b32 v[36:37], v115 offset0:42 offset1:43
	ds_read2_b32 v[38:39], v115 offset0:44 offset1:45
	ds_read2_b32 v[40:41], v115 offset0:51 offset1:52
	ds_read2_b32 v[42:43], v115 offset0:53 offset1:54
	ds_read2_b32 v[44:45], v115 offset0:59 offset1:60
	ds_read2_b32 v[46:47], v115 offset0:61 offset1:62
	v_mfma_f32_32x32x16_bf16 v[0:15], v[64:67], v[72:75], v[0:15]
	v_mfma_f32_32x32x16_bf16 v[16:31], v[64:67], v[76:79], v[16:31]
	v_mfma_f32_32x32x16_bf16 v[0:15], v[68:71], v[220:223], v[0:15]
	v_mfma_f32_32x32x16_bf16 v[16:31], v[68:71], v[224:227], v[16:31]
	s_add_i32 s90, s76, 224
	v_add_u32_e32 v80, s90, v235
	v_add_u32_e32 v83, s90, v236
	v_add_u32_e32 v99, s90, v237
	v_add_u32_e32 v253, s90, v238
	v_add_u32_e32 v254, s90, v100
	v_add_u32_e32 v255, s90, v149
	v_med3_i32 v80, v80, 0, s99
	v_med3_i32 v83, v83, 0, s99
	v_med3_i32 v99, v99, 0, s99
	v_med3_i32 v253, v253, 0, s99
	v_med3_i32 v254, v254, 0, s99
	v_med3_i32 v255, v255, 0, s99
	v_mad_u32_u24 v80, v80, s100, v252
	v_mad_u32_u24 v83, v83, s100, v252
	v_mad_u32_u24 v99, v99, s100, v252
	v_mad_u32_u24 v253, v253, s100, v252
	v_mad_u32_u24 v254, v254, s100, v153
	v_mad_u32_u24 v255, v255, s100, v153
	global_load_dwordx4 v[156:159], v80, s[82:83]
	global_load_dwordx4 v[160:163], v83, s[82:83]
	global_load_dwordx4 v[164:167], v99, s[82:83]
	global_load_dwordx4 v[168:171], v253, s[82:83]
	global_load_dwordx4 v[172:175], v254, s[82:83] offset:768
	global_load_dwordx4 v[176:179], v255, s[82:83] offset:768
	global_load_dwordx4 v[180:183], v254, s[82:83] offset:832
	global_load_dwordx4 v[184:187], v255, s[82:83] offset:832
	ds_read_b64_tr_b16 v[72:73], v231
	ds_read_b64_tr_b16 v[74:75], v231 offset:512
	ds_read_b64_tr_b16 v[76:77], v231 offset:2048
	ds_read_b64_tr_b16 v[78:79], v231 offset:2560
	ds_read_b64_tr_b16 v[220:221], v231 offset:1024
	ds_read_b64_tr_b16 v[222:223], v231 offset:1536
	ds_read_b64_tr_b16 v[224:225], v231 offset:3072
	ds_read_b64_tr_b16 v[226:227], v231 offset:3584
	s_waitcnt vmcnt(8)
	ds_write_b128 v247, v[116:119]
	ds_write_b128 v247, v[120:123] offset:1024
	ds_write_b128 v247, v[124:127] offset:2048
	ds_write_b128 v247, v[128:131] offset:3072
	ds_read_b128 v[116:119], v248
	ds_read_b128 v[120:123], v249
	ds_read_b128 v[124:127], v250
	ds_read_b128 v[128:131], v251
	ds_write_b128 v112, v[132:135]
	ds_write_b128 v112, v[136:139] offset:1024
	ds_write_b128 v112, v[140:143] offset:2048
	ds_write_b128 v112, v[144:147] offset:3072
	s_waitcnt lgkmcnt(4)
	v_mfma_f32_32x32x16_bf16 v[32:47], v[116:119], v[48:51], v[32:47]
	v_exp_f32_e32 v188, v188
	v_exp_f32_e32 v189, v189
	v_exp_f32_e32 v190, v190
	v_exp_f32_e32 v191, v191
	v_mfma_f32_32x32x16_bf16 v[32:47], v[120:123], v[52:55], v[32:47]
	v_exp_f32_e32 v192, v192
	v_exp_f32_e32 v193, v193
	v_exp_f32_e32 v194, v194
	v_exp_f32_e32 v195, v195
	v_mfma_f32_32x32x16_bf16 v[32:47], v[124:127], v[56:59], v[32:47]
	v_exp_f32_e32 v196, v196
	v_exp_f32_e32 v197, v197
	v_exp_f32_e32 v198, v198
	v_exp_f32_e32 v199, v199
	v_mfma_f32_32x32x16_bf16 v[32:47], v[128:131], v[60:63], v[32:47]
	v_exp_f32_e32 v200, v200
	v_exp_f32_e32 v201, v201
	v_exp_f32_e32 v202, v202
	v_exp_f32_e32 v203, v203
	s_add_i32 s90, s76, 160
	v_add_u32_e32 v84, s90, v107
	v_add_u32_e32 v85, 0, v84
	v_add_u32_e32 v86, 1, v84
	v_add_u32_e32 v87, 2, v84
	v_add_u32_e32 v88, 3, v84
	v_cmp_gt_u32_e64 s[30:31], s98, v85
	v_cmp_gt_u32_e64 s[36:37], s98, v86
	v_cmp_gt_u32_e64 s[78:79], s98, v87
	v_cmp_gt_u32_e64 s[50:51], s98, v88
	v_cndmask_b32_e64 v188, 0, v188, s[30:31]
	v_add_u32_e32 v85, 8, v84
	v_cmp_gt_u32_e64 s[30:31], s98, v85
	v_cndmask_b32_e64 v189, 0, v189, s[36:37]
	v_add_u32_e32 v86, 9, v84
	v_cmp_gt_u32_e64 s[36:37], s98, v86
	v_cndmask_b32_e64 v190, 0, v190, s[78:79]
	v_add_u32_e32 v87, 10, v84
	v_cmp_gt_u32_e64 s[78:79], s98, v87
	v_cndmask_b32_e64 v191, 0, v191, s[50:51]
	v_add_u32_e32 v88, 11, v84
	v_cmp_gt_u32_e64 s[50:51], s98, v88
	v_cndmask_b32_e64 v192, 0, v192, s[30:31]
	v_add_u32_e32 v85, 16, v84
	v_cmp_gt_u32_e64 s[30:31], s98, v85
	v_cndmask_b32_e64 v193, 0, v193, s[36:37]
	v_add_u32_e32 v86, 17, v84
	v_cmp_gt_u32_e64 s[36:37], s98, v86
	v_cndmask_b32_e64 v194, 0, v194, s[78:79]
	v_add_u32_e32 v87, 18, v84
	v_cmp_gt_u32_e64 s[78:79], s98, v87
	v_cndmask_b32_e64 v195, 0, v195, s[50:51]
	v_add_u32_e32 v88, 19, v84
	v_cmp_gt_u32_e64 s[50:51], s98, v88
	v_cndmask_b32_e64 v196, 0, v196, s[30:31]
	v_add_u32_e32 v85, 24, v84
	v_cmp_gt_u32_e64 s[30:31], s98, v85
	v_cndmask_b32_e64 v197, 0, v197, s[36:37]
	v_add_u32_e32 v86, 25, v84
	v_cmp_gt_u32_e64 s[36:37], s98, v86
	v_cndmask_b32_e64 v198, 0, v198, s[78:79]
	v_add_u32_e32 v87, 26, v84
	v_cmp_gt_u32_e64 s[78:79], s98, v87
	v_cndmask_b32_e64 v199, 0, v199, s[50:51]
	v_add_u32_e32 v88, 27, v84
	v_cmp_gt_u32_e64 s[50:51], s98, v88
	v_nop
	v_cndmask_b32_e64 v200, 0, v200, s[30:31]
	v_cndmask_b32_e64 v201, 0, v201, s[36:37]
	v_cndmask_b32_e64 v202, 0, v202, s[78:79]
	v_cndmask_b32_e64 v203, 0, v203, s[50:51]
	v_cvt_pk_bf16_f32 v64, v188, v189
	v_cvt_pk_bf16_f32 v65, v190, v191
	v_cvt_pk_bf16_f32 v66, v192, v193
	v_cvt_pk_bf16_f32 v67, v194, v195
	v_cvt_pk_bf16_f32 v68, v196, v197
	v_cvt_pk_bf16_f32 v69, v198, v199
	v_cvt_pk_bf16_f32 v70, v200, v201
	v_cvt_pk_bf16_f32 v71, v202, v203
	v_pk_add_f32 v[232:233], v[232:233], v[188:189]
	v_pk_add_f32 v[232:233], v[232:233], v[190:191]
	v_pk_add_f32 v[232:233], v[232:233], v[192:193]
	v_pk_add_f32 v[232:233], v[232:233], v[194:195]
	v_pk_add_f32 v[232:233], v[232:233], v[196:197]
	v_pk_add_f32 v[232:233], v[232:233], v[198:199]
	v_pk_add_f32 v[232:233], v[232:233], v[200:201]
	v_pk_add_f32 v[232:233], v[232:233], v[202:203]
	ds_read2_b32 v[188:189], v115 offset0:68 offset1:69
	ds_read2_b32 v[190:191], v115 offset0:70 offset1:71
	ds_read2_b32 v[192:193], v115 offset0:76 offset1:77
	ds_read2_b32 v[194:195], v115 offset0:78 offset1:79
	ds_read2_b32 v[196:197], v115 offset0:85 offset1:86
	ds_read2_b32 v[198:199], v115 offset0:87 offset1:88
	ds_read2_b32 v[200:201], v115 offset0:93 offset1:94
	ds_read2_b32 v[202:203], v115 offset0:95 offset1:96
	v_mfma_f32_32x32x16_bf16 v[0:15], v[64:67], v[72:75], v[0:15]
	v_mfma_f32_32x32x16_bf16 v[16:31], v[64:67], v[76:79], v[16:31]
	v_mfma_f32_32x32x16_bf16 v[0:15], v[68:71], v[220:223], v[0:15]
	v_mfma_f32_32x32x16_bf16 v[16:31], v[68:71], v[224:227], v[16:31]
	s_add_i32 s90, s76, 256
	v_add_u32_e32 v80, s90, v235
	v_add_u32_e32 v83, s90, v236
	v_add_u32_e32 v99, s90, v237
	v_add_u32_e32 v253, s90, v238
	v_add_u32_e32 v254, s90, v100
	v_add_u32_e32 v255, s90, v149
	v_med3_i32 v80, v80, 0, s99
	v_med3_i32 v83, v83, 0, s99
	v_med3_i32 v99, v99, 0, s99
	v_med3_i32 v253, v253, 0, s99
	v_med3_i32 v254, v254, 0, s99
	v_med3_i32 v255, v255, 0, s99
	v_mad_u32_u24 v80, v80, s100, v252
	v_mad_u32_u24 v83, v83, s100, v252
	v_mad_u32_u24 v99, v99, s100, v252
	v_mad_u32_u24 v253, v253, s100, v252
	v_mad_u32_u24 v254, v254, s100, v153
	v_mad_u32_u24 v255, v255, s100, v153
	global_load_dwordx4 v[116:119], v80, s[82:83]
	global_load_dwordx4 v[120:123], v83, s[82:83]
	global_load_dwordx4 v[124:127], v99, s[82:83]
	global_load_dwordx4 v[128:131], v253, s[82:83]
	global_load_dwordx4 v[132:135], v254, s[82:83] offset:768
	global_load_dwordx4 v[136:139], v255, s[82:83] offset:768
	global_load_dwordx4 v[140:143], v254, s[82:83] offset:832
	global_load_dwordx4 v[144:147], v255, s[82:83] offset:832
	ds_read_b64_tr_b16 v[72:73], v231
	ds_read_b64_tr_b16 v[74:75], v231 offset:512
	ds_read_b64_tr_b16 v[76:77], v231 offset:2048
	ds_read_b64_tr_b16 v[78:79], v231 offset:2560
	ds_read_b64_tr_b16 v[220:221], v231 offset:1024
	ds_read_b64_tr_b16 v[222:223], v231 offset:1536
	ds_read_b64_tr_b16 v[224:225], v231 offset:3072
	ds_read_b64_tr_b16 v[226:227], v231 offset:3584
	s_waitcnt vmcnt(8)
	ds_write_b128 v247, v[156:159]
	ds_write_b128 v247, v[160:163] offset:1024
	ds_write_b128 v247, v[164:167] offset:2048
	ds_write_b128 v247, v[168:171] offset:3072
	ds_read_b128 v[156:159], v248
	ds_read_b128 v[160:163], v249
	ds_read_b128 v[164:167], v250
	ds_read_b128 v[168:171], v251
	ds_write_b128 v112, v[172:175]
	ds_write_b128 v112, v[176:179] offset:1024
	ds_write_b128 v112, v[180:183] offset:2048
	ds_write_b128 v112, v[184:187] offset:3072
	s_waitcnt lgkmcnt(4)
	v_mfma_f32_32x32x16_bf16 v[188:203], v[156:159], v[48:51], v[188:203]
	v_exp_f32_e32 v32, v32
	v_exp_f32_e32 v33, v33
	v_exp_f32_e32 v34, v34
	v_exp_f32_e32 v35, v35
	v_mfma_f32_32x32x16_bf16 v[188:203], v[160:163], v[52:55], v[188:203]
	v_exp_f32_e32 v36, v36
	v_exp_f32_e32 v37, v37
	v_exp_f32_e32 v38, v38
	v_exp_f32_e32 v39, v39
	v_mfma_f32_32x32x16_bf16 v[188:203], v[164:167], v[56:59], v[188:203]
	v_exp_f32_e32 v40, v40
	v_exp_f32_e32 v41, v41
	v_exp_f32_e32 v42, v42
	v_exp_f32_e32 v43, v43
	v_mfma_f32_32x32x16_bf16 v[188:203], v[168:171], v[60:63], v[188:203]
	v_exp_f32_e32 v44, v44
	v_exp_f32_e32 v45, v45
	v_exp_f32_e32 v46, v46
	v_exp_f32_e32 v47, v47
	s_add_i32 s90, s76, 192
	v_add_u32_e32 v84, s90, v107
	v_add_u32_e32 v85, 0, v84
	v_add_u32_e32 v86, 1, v84
	v_add_u32_e32 v87, 2, v84
	v_add_u32_e32 v88, 3, v84
	v_cmp_gt_u32_e64 s[30:31], s98, v85
	v_cmp_gt_u32_e64 s[36:37], s98, v86
	v_cmp_gt_u32_e64 s[78:79], s98, v87
	v_cmp_gt_u32_e64 s[50:51], s98, v88
	v_cndmask_b32_e64 v32, 0, v32, s[30:31]
	v_add_u32_e32 v85, 8, v84
	v_cmp_gt_u32_e64 s[30:31], s98, v85
	v_cndmask_b32_e64 v33, 0, v33, s[36:37]
	v_add_u32_e32 v86, 9, v84
	v_cmp_gt_u32_e64 s[36:37], s98, v86
	v_cndmask_b32_e64 v34, 0, v34, s[78:79]
	v_add_u32_e32 v87, 10, v84
	v_cmp_gt_u32_e64 s[78:79], s98, v87
	v_cndmask_b32_e64 v35, 0, v35, s[50:51]
	v_add_u32_e32 v88, 11, v84
	v_cmp_gt_u32_e64 s[50:51], s98, v88
	v_cndmask_b32_e64 v36, 0, v36, s[30:31]
	v_add_u32_e32 v85, 16, v84
	v_cmp_gt_u32_e64 s[30:31], s98, v85
	v_cndmask_b32_e64 v37, 0, v37, s[36:37]
	v_add_u32_e32 v86, 17, v84
	v_cmp_gt_u32_e64 s[36:37], s98, v86
	v_cndmask_b32_e64 v38, 0, v38, s[78:79]
	v_add_u32_e32 v87, 18, v84
	v_cmp_gt_u32_e64 s[78:79], s98, v87
	v_cndmask_b32_e64 v39, 0, v39, s[50:51]
	v_add_u32_e32 v88, 19, v84
	v_cmp_gt_u32_e64 s[50:51], s98, v88
	v_cndmask_b32_e64 v40, 0, v40, s[30:31]
	v_add_u32_e32 v85, 24, v84
	v_cmp_gt_u32_e64 s[30:31], s98, v85
	v_cndmask_b32_e64 v41, 0, v41, s[36:37]
	v_add_u32_e32 v86, 25, v84
	v_cmp_gt_u32_e64 s[36:37], s98, v86
	v_cndmask_b32_e64 v42, 0, v42, s[78:79]
	v_add_u32_e32 v87, 26, v84
	v_cmp_gt_u32_e64 s[78:79], s98, v87
	v_cndmask_b32_e64 v43, 0, v43, s[50:51]
	v_add_u32_e32 v88, 27, v84
	v_cmp_gt_u32_e64 s[50:51], s98, v88
	v_nop
	v_cndmask_b32_e64 v44, 0, v44, s[30:31]
	v_cndmask_b32_e64 v45, 0, v45, s[36:37]
	v_cndmask_b32_e64 v46, 0, v46, s[78:79]
	v_cndmask_b32_e64 v47, 0, v47, s[50:51]
	v_cvt_pk_bf16_f32 v64, v32, v33
	v_cvt_pk_bf16_f32 v65, v34, v35
	v_cvt_pk_bf16_f32 v66, v36, v37
	v_cvt_pk_bf16_f32 v67, v38, v39
	v_cvt_pk_bf16_f32 v68, v40, v41
	v_cvt_pk_bf16_f32 v69, v42, v43
	v_cvt_pk_bf16_f32 v70, v44, v45
	v_cvt_pk_bf16_f32 v71, v46, v47
	v_pk_add_f32 v[232:233], v[232:233], v[32:33]
	v_pk_add_f32 v[232:233], v[232:233], v[34:35]
	v_pk_add_f32 v[232:233], v[232:233], v[36:37]
	v_pk_add_f32 v[232:233], v[232:233], v[38:39]
	v_pk_add_f32 v[232:233], v[232:233], v[40:41]
	v_pk_add_f32 v[232:233], v[232:233], v[42:43]
	v_pk_add_f32 v[232:233], v[232:233], v[44:45]
	v_pk_add_f32 v[232:233], v[232:233], v[46:47]
	ds_read2_b32 v[32:33], v115 offset0:102 offset1:103
	ds_read2_b32 v[34:35], v115 offset0:104 offset1:105
	ds_read2_b32 v[36:37], v115 offset0:110 offset1:111
	ds_read2_b32 v[38:39], v115 offset0:112 offset1:113
	ds_read2_b32 v[40:41], v115 offset0:119 offset1:120
	ds_read2_b32 v[42:43], v115 offset0:121 offset1:122
	ds_read2_b32 v[44:45], v115 offset0:127 offset1:128
	ds_read2_b32 v[46:47], v115 offset0:129 offset1:130
	v_mfma_f32_32x32x16_bf16 v[0:15], v[64:67], v[72:75], v[0:15]
	v_mfma_f32_32x32x16_bf16 v[16:31], v[64:67], v[76:79], v[16:31]
	v_mfma_f32_32x32x16_bf16 v[0:15], v[68:71], v[220:223], v[0:15]
	v_mfma_f32_32x32x16_bf16 v[16:31], v[68:71], v[224:227], v[16:31]
	s_add_i32 s90, s76, 288
	v_add_u32_e32 v80, s90, v235
	v_add_u32_e32 v83, s90, v236
	v_add_u32_e32 v99, s90, v237
	v_add_u32_e32 v253, s90, v238
	v_add_u32_e32 v254, s90, v100
	v_add_u32_e32 v255, s90, v149
	v_med3_i32 v80, v80, 0, s99
	v_med3_i32 v83, v83, 0, s99
	v_med3_i32 v99, v99, 0, s99
	v_med3_i32 v253, v253, 0, s99
	v_med3_i32 v254, v254, 0, s99
	v_med3_i32 v255, v255, 0, s99
	v_mad_u32_u24 v80, v80, s100, v252
	v_mad_u32_u24 v83, v83, s100, v252
	v_mad_u32_u24 v99, v99, s100, v252
	v_mad_u32_u24 v253, v253, s100, v252
	v_mad_u32_u24 v254, v254, s100, v153
	v_mad_u32_u24 v255, v255, s100, v153
	global_load_dwordx4 v[156:159], v80, s[82:83]
	global_load_dwordx4 v[160:163], v83, s[82:83]
	global_load_dwordx4 v[164:167], v99, s[82:83]
	global_load_dwordx4 v[168:171], v253, s[82:83]
	global_load_dwordx4 v[172:175], v254, s[82:83] offset:768
	global_load_dwordx4 v[176:179], v255, s[82:83] offset:768
	global_load_dwordx4 v[180:183], v254, s[82:83] offset:832
	global_load_dwordx4 v[184:187], v255, s[82:83] offset:832
	ds_read_b64_tr_b16 v[72:73], v231
	ds_read_b64_tr_b16 v[74:75], v231 offset:512
	ds_read_b64_tr_b16 v[76:77], v231 offset:2048
	ds_read_b64_tr_b16 v[78:79], v231 offset:2560
	ds_read_b64_tr_b16 v[220:221], v231 offset:1024
	ds_read_b64_tr_b16 v[222:223], v231 offset:1536
	ds_read_b64_tr_b16 v[224:225], v231 offset:3072
	ds_read_b64_tr_b16 v[226:227], v231 offset:3584
	s_waitcnt vmcnt(8)
	ds_write_b128 v247, v[116:119]
	ds_write_b128 v247, v[120:123] offset:1024
	ds_write_b128 v247, v[124:127] offset:2048
	ds_write_b128 v247, v[128:131] offset:3072
	ds_read_b128 v[116:119], v248
	ds_read_b128 v[120:123], v249
	ds_read_b128 v[124:127], v250
	ds_read_b128 v[128:131], v251
	ds_write_b128 v112, v[132:135]
	ds_write_b128 v112, v[136:139] offset:1024
	ds_write_b128 v112, v[140:143] offset:2048
	ds_write_b128 v112, v[144:147] offset:3072
	s_waitcnt lgkmcnt(4)
	v_mfma_f32_32x32x16_bf16 v[32:47], v[116:119], v[48:51], v[32:47]
	v_exp_f32_e32 v188, v188
	v_exp_f32_e32 v189, v189
	v_exp_f32_e32 v190, v190
	v_exp_f32_e32 v191, v191
	v_mfma_f32_32x32x16_bf16 v[32:47], v[120:123], v[52:55], v[32:47]
	v_exp_f32_e32 v192, v192
	v_exp_f32_e32 v193, v193
	v_exp_f32_e32 v194, v194
	v_exp_f32_e32 v195, v195
	v_mfma_f32_32x32x16_bf16 v[32:47], v[124:127], v[56:59], v[32:47]
	v_exp_f32_e32 v196, v196
	v_exp_f32_e32 v197, v197
	v_exp_f32_e32 v198, v198
	v_exp_f32_e32 v199, v199
	v_mfma_f32_32x32x16_bf16 v[32:47], v[128:131], v[60:63], v[32:47]
	v_exp_f32_e32 v200, v200
	v_exp_f32_e32 v201, v201
	v_exp_f32_e32 v202, v202
	v_exp_f32_e32 v203, v203
	s_add_i32 s90, s76, 224
	v_add_u32_e32 v84, s90, v107
	v_add_u32_e32 v85, 0, v84
	v_add_u32_e32 v86, 1, v84
	v_add_u32_e32 v87, 2, v84
	v_add_u32_e32 v88, 3, v84
	v_cmp_gt_u32_e64 s[30:31], s98, v85
	v_cmp_gt_u32_e64 s[36:37], s98, v86
	v_cmp_gt_u32_e64 s[78:79], s98, v87
	v_cmp_gt_u32_e64 s[50:51], s98, v88
	v_cndmask_b32_e64 v188, 0, v188, s[30:31]
	v_add_u32_e32 v85, 8, v84
	v_cmp_gt_u32_e64 s[30:31], s98, v85
	v_cndmask_b32_e64 v189, 0, v189, s[36:37]
	v_add_u32_e32 v86, 9, v84
	v_cmp_gt_u32_e64 s[36:37], s98, v86
	v_cndmask_b32_e64 v190, 0, v190, s[78:79]
	v_add_u32_e32 v87, 10, v84
	v_cmp_gt_u32_e64 s[78:79], s98, v87
	v_cndmask_b32_e64 v191, 0, v191, s[50:51]
	v_add_u32_e32 v88, 11, v84
	v_cmp_gt_u32_e64 s[50:51], s98, v88
	v_cndmask_b32_e64 v192, 0, v192, s[30:31]
	v_add_u32_e32 v85, 16, v84
	v_cmp_gt_u32_e64 s[30:31], s98, v85
	v_cndmask_b32_e64 v193, 0, v193, s[36:37]
	v_add_u32_e32 v86, 17, v84
	v_cmp_gt_u32_e64 s[36:37], s98, v86
	v_cndmask_b32_e64 v194, 0, v194, s[78:79]
	v_add_u32_e32 v87, 18, v84
	v_cmp_gt_u32_e64 s[78:79], s98, v87
	v_cndmask_b32_e64 v195, 0, v195, s[50:51]
	v_add_u32_e32 v88, 19, v84
	v_cmp_gt_u32_e64 s[50:51], s98, v88
	v_cndmask_b32_e64 v196, 0, v196, s[30:31]
	v_add_u32_e32 v85, 24, v84
	v_cmp_gt_u32_e64 s[30:31], s98, v85
	v_cndmask_b32_e64 v197, 0, v197, s[36:37]
	v_add_u32_e32 v86, 25, v84
	v_cmp_gt_u32_e64 s[36:37], s98, v86
	v_cndmask_b32_e64 v198, 0, v198, s[78:79]
	v_add_u32_e32 v87, 26, v84
	v_cmp_gt_u32_e64 s[78:79], s98, v87
	v_cndmask_b32_e64 v199, 0, v199, s[50:51]
	v_add_u32_e32 v88, 27, v84
	v_cmp_gt_u32_e64 s[50:51], s98, v88
	v_nop
	v_cndmask_b32_e64 v200, 0, v200, s[30:31]
	v_cndmask_b32_e64 v201, 0, v201, s[36:37]
	v_cndmask_b32_e64 v202, 0, v202, s[78:79]
	v_cndmask_b32_e64 v203, 0, v203, s[50:51]
	v_cvt_pk_bf16_f32 v64, v188, v189
	v_cvt_pk_bf16_f32 v65, v190, v191
	v_cvt_pk_bf16_f32 v66, v192, v193
	v_cvt_pk_bf16_f32 v67, v194, v195
	v_cvt_pk_bf16_f32 v68, v196, v197
	v_cvt_pk_bf16_f32 v69, v198, v199
	v_cvt_pk_bf16_f32 v70, v200, v201
	v_cvt_pk_bf16_f32 v71, v202, v203
	v_pk_add_f32 v[232:233], v[232:233], v[188:189]
	v_pk_add_f32 v[232:233], v[232:233], v[190:191]
	v_pk_add_f32 v[232:233], v[232:233], v[192:193]
	v_pk_add_f32 v[232:233], v[232:233], v[194:195]
	v_pk_add_f32 v[232:233], v[232:233], v[196:197]
	v_pk_add_f32 v[232:233], v[232:233], v[198:199]
	v_pk_add_f32 v[232:233], v[232:233], v[200:201]
	v_pk_add_f32 v[232:233], v[232:233], v[202:203]
	ds_read2_b32 v[188:189], v115 offset0:136 offset1:137
	ds_read2_b32 v[190:191], v115 offset0:138 offset1:139
	ds_read2_b32 v[192:193], v115 offset0:144 offset1:145
	ds_read2_b32 v[194:195], v115 offset0:146 offset1:147
	ds_read2_b32 v[196:197], v115 offset0:153 offset1:154
	ds_read2_b32 v[198:199], v115 offset0:155 offset1:156
	ds_read2_b32 v[200:201], v115 offset0:161 offset1:162
	ds_read2_b32 v[202:203], v115 offset0:163 offset1:164
	v_mfma_f32_32x32x16_bf16 v[0:15], v[64:67], v[72:75], v[0:15]
	v_mfma_f32_32x32x16_bf16 v[16:31], v[64:67], v[76:79], v[16:31]
	v_mfma_f32_32x32x16_bf16 v[0:15], v[68:71], v[220:223], v[0:15]
	v_mfma_f32_32x32x16_bf16 v[16:31], v[68:71], v[224:227], v[16:31]
	s_add_i32 s90, s76, 320
	v_add_u32_e32 v80, s90, v235
	v_add_u32_e32 v83, s90, v236
	v_add_u32_e32 v99, s90, v237
	v_add_u32_e32 v253, s90, v238
	v_add_u32_e32 v254, s90, v100
	v_add_u32_e32 v255, s90, v149
	v_med3_i32 v80, v80, 0, s99
	v_med3_i32 v83, v83, 0, s99
	v_med3_i32 v99, v99, 0, s99
	v_med3_i32 v253, v253, 0, s99
	v_med3_i32 v254, v254, 0, s99
	v_med3_i32 v255, v255, 0, s99
	v_mad_u32_u24 v80, v80, s100, v252
	v_mad_u32_u24 v83, v83, s100, v252
	v_mad_u32_u24 v99, v99, s100, v252
	v_mad_u32_u24 v253, v253, s100, v252
	v_mad_u32_u24 v254, v254, s100, v153
	v_mad_u32_u24 v255, v255, s100, v153
	global_load_dwordx4 v[116:119], v80, s[82:83]
	global_load_dwordx4 v[120:123], v83, s[82:83]
	global_load_dwordx4 v[124:127], v99, s[82:83]
	global_load_dwordx4 v[128:131], v253, s[82:83]
	global_load_dwordx4 v[132:135], v254, s[82:83] offset:768
	global_load_dwordx4 v[136:139], v255, s[82:83] offset:768
	global_load_dwordx4 v[140:143], v254, s[82:83] offset:832
	global_load_dwordx4 v[144:147], v255, s[82:83] offset:832
	ds_read_b64_tr_b16 v[72:73], v231
	ds_read_b64_tr_b16 v[74:75], v231 offset:512
	ds_read_b64_tr_b16 v[76:77], v231 offset:2048
	ds_read_b64_tr_b16 v[78:79], v231 offset:2560
	ds_read_b64_tr_b16 v[220:221], v231 offset:1024
	ds_read_b64_tr_b16 v[222:223], v231 offset:1536
	ds_read_b64_tr_b16 v[224:225], v231 offset:3072
	ds_read_b64_tr_b16 v[226:227], v231 offset:3584
	s_waitcnt vmcnt(8)
	ds_write_b128 v247, v[156:159]
	ds_write_b128 v247, v[160:163] offset:1024
	ds_write_b128 v247, v[164:167] offset:2048
	ds_write_b128 v247, v[168:171] offset:3072
	ds_read_b128 v[156:159], v248
	ds_read_b128 v[160:163], v249
	ds_read_b128 v[164:167], v250
	ds_read_b128 v[168:171], v251
	ds_write_b128 v112, v[172:175]
	ds_write_b128 v112, v[176:179] offset:1024
	ds_write_b128 v112, v[180:183] offset:2048
	ds_write_b128 v112, v[184:187] offset:3072
	s_waitcnt lgkmcnt(4)
	v_mfma_f32_32x32x16_bf16 v[188:203], v[156:159], v[48:51], v[188:203]
	v_exp_f32_e32 v32, v32
	v_exp_f32_e32 v33, v33
	v_exp_f32_e32 v34, v34
	v_exp_f32_e32 v35, v35
	v_mfma_f32_32x32x16_bf16 v[188:203], v[160:163], v[52:55], v[188:203]
	v_exp_f32_e32 v36, v36
	v_exp_f32_e32 v37, v37
	v_exp_f32_e32 v38, v38
	v_exp_f32_e32 v39, v39
	v_mfma_f32_32x32x16_bf16 v[188:203], v[164:167], v[56:59], v[188:203]
	v_exp_f32_e32 v40, v40
	v_exp_f32_e32 v41, v41
	v_exp_f32_e32 v42, v42
	v_exp_f32_e32 v43, v43
	v_mfma_f32_32x32x16_bf16 v[188:203], v[168:171], v[60:63], v[188:203]
	v_exp_f32_e32 v44, v44
	v_exp_f32_e32 v45, v45
	v_exp_f32_e32 v46, v46
	v_exp_f32_e32 v47, v47
	s_add_i32 s90, s76, 256
	v_add_u32_e32 v84, s90, v107
	v_add_u32_e32 v85, 0, v84
	v_add_u32_e32 v86, 1, v84
	v_add_u32_e32 v87, 2, v84
	v_add_u32_e32 v88, 3, v84
	v_cmp_gt_u32_e64 s[30:31], s98, v85
	v_cmp_gt_u32_e64 s[36:37], s98, v86
	v_cmp_gt_u32_e64 s[78:79], s98, v87
	v_cmp_gt_u32_e64 s[50:51], s98, v88
	v_cndmask_b32_e64 v32, 0, v32, s[30:31]
	v_add_u32_e32 v85, 8, v84
	v_cmp_gt_u32_e64 s[30:31], s98, v85
	v_cndmask_b32_e64 v33, 0, v33, s[36:37]
	v_add_u32_e32 v86, 9, v84
	v_cmp_gt_u32_e64 s[36:37], s98, v86
	v_cndmask_b32_e64 v34, 0, v34, s[78:79]
	v_add_u32_e32 v87, 10, v84
	v_cmp_gt_u32_e64 s[78:79], s98, v87
	v_cndmask_b32_e64 v35, 0, v35, s[50:51]
	v_add_u32_e32 v88, 11, v84
	v_cmp_gt_u32_e64 s[50:51], s98, v88
	v_cndmask_b32_e64 v36, 0, v36, s[30:31]
	v_add_u32_e32 v85, 16, v84
	v_cmp_gt_u32_e64 s[30:31], s98, v85
	v_cndmask_b32_e64 v37, 0, v37, s[36:37]
	v_add_u32_e32 v86, 17, v84
	v_cmp_gt_u32_e64 s[36:37], s98, v86
	v_cndmask_b32_e64 v38, 0, v38, s[78:79]
	v_add_u32_e32 v87, 18, v84
	v_cmp_gt_u32_e64 s[78:79], s98, v87
	v_cndmask_b32_e64 v39, 0, v39, s[50:51]
	v_add_u32_e32 v88, 19, v84
	v_cmp_gt_u32_e64 s[50:51], s98, v88
	v_cndmask_b32_e64 v40, 0, v40, s[30:31]
	v_add_u32_e32 v85, 24, v84
	v_cmp_gt_u32_e64 s[30:31], s98, v85
	v_cndmask_b32_e64 v41, 0, v41, s[36:37]
	v_add_u32_e32 v86, 25, v84
	v_cmp_gt_u32_e64 s[36:37], s98, v86
	v_cndmask_b32_e64 v42, 0, v42, s[78:79]
	v_add_u32_e32 v87, 26, v84
	v_cmp_gt_u32_e64 s[78:79], s98, v87
	v_cndmask_b32_e64 v43, 0, v43, s[50:51]
	v_add_u32_e32 v88, 27, v84
	v_cmp_gt_u32_e64 s[50:51], s98, v88
	v_nop
	v_cndmask_b32_e64 v44, 0, v44, s[30:31]
	v_cndmask_b32_e64 v45, 0, v45, s[36:37]
	v_cndmask_b32_e64 v46, 0, v46, s[78:79]
	v_cndmask_b32_e64 v47, 0, v47, s[50:51]
	v_cvt_pk_bf16_f32 v64, v32, v33
	v_cvt_pk_bf16_f32 v65, v34, v35
	v_cvt_pk_bf16_f32 v66, v36, v37
	v_cvt_pk_bf16_f32 v67, v38, v39
	v_cvt_pk_bf16_f32 v68, v40, v41
	v_cvt_pk_bf16_f32 v69, v42, v43
	v_cvt_pk_bf16_f32 v70, v44, v45
	v_cvt_pk_bf16_f32 v71, v46, v47
	v_pk_add_f32 v[232:233], v[232:233], v[32:33]
	v_pk_add_f32 v[232:233], v[232:233], v[34:35]
	v_pk_add_f32 v[232:233], v[232:233], v[36:37]
	v_pk_add_f32 v[232:233], v[232:233], v[38:39]
	v_pk_add_f32 v[232:233], v[232:233], v[40:41]
	v_pk_add_f32 v[232:233], v[232:233], v[42:43]
	v_pk_add_f32 v[232:233], v[232:233], v[44:45]
	v_pk_add_f32 v[232:233], v[232:233], v[46:47]
	ds_read2_b32 v[32:33], v115 offset0:170 offset1:171
	ds_read2_b32 v[34:35], v115 offset0:172 offset1:173
	ds_read2_b32 v[36:37], v115 offset0:178 offset1:179
	ds_read2_b32 v[38:39], v115 offset0:180 offset1:181
	ds_read2_b32 v[40:41], v115 offset0:187 offset1:188
	ds_read2_b32 v[42:43], v115 offset0:189 offset1:190
	ds_read2_b32 v[44:45], v115 offset0:195 offset1:196
	ds_read2_b32 v[46:47], v115 offset0:197 offset1:198
	v_mfma_f32_32x32x16_bf16 v[0:15], v[64:67], v[72:75], v[0:15]
	v_mfma_f32_32x32x16_bf16 v[16:31], v[64:67], v[76:79], v[16:31]
	v_mfma_f32_32x32x16_bf16 v[0:15], v[68:71], v[220:223], v[0:15]
	v_mfma_f32_32x32x16_bf16 v[16:31], v[68:71], v[224:227], v[16:31]
	s_add_i32 s90, s76, 352
	v_add_u32_e32 v80, s90, v235
	v_add_u32_e32 v83, s90, v236
	v_add_u32_e32 v99, s90, v237
	v_add_u32_e32 v253, s90, v238
	v_add_u32_e32 v254, s90, v100
	v_add_u32_e32 v255, s90, v149
	v_med3_i32 v80, v80, 0, s99
	v_med3_i32 v83, v83, 0, s99
	v_med3_i32 v99, v99, 0, s99
	v_med3_i32 v253, v253, 0, s99
	v_med3_i32 v254, v254, 0, s99
	v_med3_i32 v255, v255, 0, s99
	v_mad_u32_u24 v80, v80, s100, v252
	v_mad_u32_u24 v83, v83, s100, v252
	v_mad_u32_u24 v99, v99, s100, v252
	v_mad_u32_u24 v253, v253, s100, v252
	v_mad_u32_u24 v254, v254, s100, v153
	v_mad_u32_u24 v255, v255, s100, v153
	global_load_dwordx4 v[156:159], v80, s[82:83]
	global_load_dwordx4 v[160:163], v83, s[82:83]
	global_load_dwordx4 v[164:167], v99, s[82:83]
	global_load_dwordx4 v[168:171], v253, s[82:83]
	global_load_dwordx4 v[172:175], v254, s[82:83] offset:768
	global_load_dwordx4 v[176:179], v255, s[82:83] offset:768
	global_load_dwordx4 v[180:183], v254, s[82:83] offset:832
	global_load_dwordx4 v[184:187], v255, s[82:83] offset:832
	ds_read_b64_tr_b16 v[72:73], v231
	ds_read_b64_tr_b16 v[74:75], v231 offset:512
	ds_read_b64_tr_b16 v[76:77], v231 offset:2048
	ds_read_b64_tr_b16 v[78:79], v231 offset:2560
	ds_read_b64_tr_b16 v[220:221], v231 offset:1024
	ds_read_b64_tr_b16 v[222:223], v231 offset:1536
	ds_read_b64_tr_b16 v[224:225], v231 offset:3072
	ds_read_b64_tr_b16 v[226:227], v231 offset:3584
	s_waitcnt vmcnt(8)
	ds_write_b128 v247, v[116:119]
	ds_write_b128 v247, v[120:123] offset:1024
	ds_write_b128 v247, v[124:127] offset:2048
	ds_write_b128 v247, v[128:131] offset:3072
	ds_read_b128 v[116:119], v248
	ds_read_b128 v[120:123], v249
	ds_read_b128 v[124:127], v250
	ds_read_b128 v[128:131], v251
	ds_write_b128 v112, v[132:135]
	ds_write_b128 v112, v[136:139] offset:1024
	ds_write_b128 v112, v[140:143] offset:2048
	ds_write_b128 v112, v[144:147] offset:3072
	s_waitcnt lgkmcnt(4)
	v_mfma_f32_32x32x16_bf16 v[32:47], v[116:119], v[48:51], v[32:47]
	v_exp_f32_e32 v188, v188
	v_exp_f32_e32 v189, v189
	v_exp_f32_e32 v190, v190
	v_exp_f32_e32 v191, v191
	v_mfma_f32_32x32x16_bf16 v[32:47], v[120:123], v[52:55], v[32:47]
	v_exp_f32_e32 v192, v192
	v_exp_f32_e32 v193, v193
	v_exp_f32_e32 v194, v194
	v_exp_f32_e32 v195, v195
	v_mfma_f32_32x32x16_bf16 v[32:47], v[124:127], v[56:59], v[32:47]
	v_exp_f32_e32 v196, v196
	v_exp_f32_e32 v197, v197
	v_exp_f32_e32 v198, v198
	v_exp_f32_e32 v199, v199
	v_mfma_f32_32x32x16_bf16 v[32:47], v[128:131], v[60:63], v[32:47]
	v_exp_f32_e32 v200, v200
	v_exp_f32_e32 v201, v201
	v_exp_f32_e32 v202, v202
	v_exp_f32_e32 v203, v203
	s_add_i32 s90, s76, 288
	v_add_u32_e32 v84, s90, v107
	v_add_u32_e32 v85, 0, v84
	v_add_u32_e32 v86, 1, v84
	v_add_u32_e32 v87, 2, v84
	v_add_u32_e32 v88, 3, v84
	v_cmp_gt_u32_e64 s[30:31], s98, v85
	v_cmp_gt_u32_e64 s[36:37], s98, v86
	v_cmp_gt_u32_e64 s[78:79], s98, v87
	v_cmp_gt_u32_e64 s[50:51], s98, v88
	v_cndmask_b32_e64 v188, 0, v188, s[30:31]
	v_add_u32_e32 v85, 8, v84
	v_cmp_gt_u32_e64 s[30:31], s98, v85
	v_cndmask_b32_e64 v189, 0, v189, s[36:37]
	v_add_u32_e32 v86, 9, v84
	v_cmp_gt_u32_e64 s[36:37], s98, v86
	v_cndmask_b32_e64 v190, 0, v190, s[78:79]
	v_add_u32_e32 v87, 10, v84
	v_cmp_gt_u32_e64 s[78:79], s98, v87
	v_cndmask_b32_e64 v191, 0, v191, s[50:51]
	v_add_u32_e32 v88, 11, v84
	v_cmp_gt_u32_e64 s[50:51], s98, v88
	v_cndmask_b32_e64 v192, 0, v192, s[30:31]
	v_add_u32_e32 v85, 16, v84
	v_cmp_gt_u32_e64 s[30:31], s98, v85
	v_cndmask_b32_e64 v193, 0, v193, s[36:37]
	v_add_u32_e32 v86, 17, v84
	v_cmp_gt_u32_e64 s[36:37], s98, v86
	v_cndmask_b32_e64 v194, 0, v194, s[78:79]
	v_add_u32_e32 v87, 18, v84
	v_cmp_gt_u32_e64 s[78:79], s98, v87
	v_cndmask_b32_e64 v195, 0, v195, s[50:51]
	v_add_u32_e32 v88, 19, v84
	v_cmp_gt_u32_e64 s[50:51], s98, v88
	v_cndmask_b32_e64 v196, 0, v196, s[30:31]
	v_add_u32_e32 v85, 24, v84
	v_cmp_gt_u32_e64 s[30:31], s98, v85
	v_cndmask_b32_e64 v197, 0, v197, s[36:37]
	v_add_u32_e32 v86, 25, v84
	v_cmp_gt_u32_e64 s[36:37], s98, v86
	v_cndmask_b32_e64 v198, 0, v198, s[78:79]
	v_add_u32_e32 v87, 26, v84
	v_cmp_gt_u32_e64 s[78:79], s98, v87
	v_cndmask_b32_e64 v199, 0, v199, s[50:51]
	v_add_u32_e32 v88, 27, v84
	v_cmp_gt_u32_e64 s[50:51], s98, v88
	v_nop
	v_cndmask_b32_e64 v200, 0, v200, s[30:31]
	v_cndmask_b32_e64 v201, 0, v201, s[36:37]
	v_cndmask_b32_e64 v202, 0, v202, s[78:79]
	v_cndmask_b32_e64 v203, 0, v203, s[50:51]
	v_cvt_pk_bf16_f32 v64, v188, v189
	v_cvt_pk_bf16_f32 v65, v190, v191
	v_cvt_pk_bf16_f32 v66, v192, v193
	v_cvt_pk_bf16_f32 v67, v194, v195
	v_cvt_pk_bf16_f32 v68, v196, v197
	v_cvt_pk_bf16_f32 v69, v198, v199
	v_cvt_pk_bf16_f32 v70, v200, v201
	v_cvt_pk_bf16_f32 v71, v202, v203
	v_pk_add_f32 v[232:233], v[232:233], v[188:189]
	v_pk_add_f32 v[232:233], v[232:233], v[190:191]
	v_pk_add_f32 v[232:233], v[232:233], v[192:193]
	v_pk_add_f32 v[232:233], v[232:233], v[194:195]
	v_pk_add_f32 v[232:233], v[232:233], v[196:197]
	v_pk_add_f32 v[232:233], v[232:233], v[198:199]
	v_pk_add_f32 v[232:233], v[232:233], v[200:201]
	v_pk_add_f32 v[232:233], v[232:233], v[202:203]
	ds_read2_b32 v[188:189], v115 offset0:204 offset1:205
	ds_read2_b32 v[190:191], v115 offset0:206 offset1:207
	ds_read2_b32 v[192:193], v115 offset0:212 offset1:213
	ds_read2_b32 v[194:195], v115 offset0:214 offset1:215
	ds_read2_b32 v[196:197], v115 offset0:221 offset1:222
	ds_read2_b32 v[198:199], v115 offset0:223 offset1:224
	ds_read2_b32 v[200:201], v115 offset0:229 offset1:230
	ds_read2_b32 v[202:203], v115 offset0:231 offset1:232
	v_mfma_f32_32x32x16_bf16 v[0:15], v[64:67], v[72:75], v[0:15]
	v_mfma_f32_32x32x16_bf16 v[16:31], v[64:67], v[76:79], v[16:31]
	v_mfma_f32_32x32x16_bf16 v[0:15], v[68:71], v[220:223], v[0:15]
	v_mfma_f32_32x32x16_bf16 v[16:31], v[68:71], v[224:227], v[16:31]
	s_add_i32 s90, s76, 384
	v_add_u32_e32 v80, s90, v235
	v_add_u32_e32 v83, s90, v236
	v_add_u32_e32 v99, s90, v237
	v_add_u32_e32 v253, s90, v238
	v_add_u32_e32 v254, s90, v100
	v_add_u32_e32 v255, s90, v149
	v_med3_i32 v80, v80, 0, s99
	v_med3_i32 v83, v83, 0, s99
	v_med3_i32 v99, v99, 0, s99
	v_med3_i32 v253, v253, 0, s99
	v_med3_i32 v254, v254, 0, s99
	v_med3_i32 v255, v255, 0, s99
	v_mad_u32_u24 v80, v80, s100, v252
	v_mad_u32_u24 v83, v83, s100, v252
	v_mad_u32_u24 v99, v99, s100, v252
	v_mad_u32_u24 v253, v253, s100, v252
	v_mad_u32_u24 v254, v254, s100, v153
	v_mad_u32_u24 v255, v255, s100, v153
	global_load_dwordx4 v[116:119], v80, s[82:83]
	global_load_dwordx4 v[120:123], v83, s[82:83]
	global_load_dwordx4 v[124:127], v99, s[82:83]
	global_load_dwordx4 v[128:131], v253, s[82:83]
	global_load_dwordx4 v[132:135], v254, s[82:83] offset:768
	global_load_dwordx4 v[136:139], v255, s[82:83] offset:768
	global_load_dwordx4 v[140:143], v254, s[82:83] offset:832
	global_load_dwordx4 v[144:147], v255, s[82:83] offset:832
	ds_read_b64_tr_b16 v[72:73], v231
	ds_read_b64_tr_b16 v[74:75], v231 offset:512
	ds_read_b64_tr_b16 v[76:77], v231 offset:2048
	ds_read_b64_tr_b16 v[78:79], v231 offset:2560
	ds_read_b64_tr_b16 v[220:221], v231 offset:1024
	ds_read_b64_tr_b16 v[222:223], v231 offset:1536
	ds_read_b64_tr_b16 v[224:225], v231 offset:3072
	ds_read_b64_tr_b16 v[226:227], v231 offset:3584
	s_waitcnt vmcnt(8)
	ds_write_b128 v247, v[156:159]
	ds_write_b128 v247, v[160:163] offset:1024
	ds_write_b128 v247, v[164:167] offset:2048
	ds_write_b128 v247, v[168:171] offset:3072
	ds_read_b128 v[156:159], v248
	ds_read_b128 v[160:163], v249
	ds_read_b128 v[164:167], v250
	ds_read_b128 v[168:171], v251
	ds_write_b128 v112, v[172:175]
	ds_write_b128 v112, v[176:179] offset:1024
	ds_write_b128 v112, v[180:183] offset:2048
	ds_write_b128 v112, v[184:187] offset:3072
	s_waitcnt lgkmcnt(4)
	v_mfma_f32_32x32x16_bf16 v[188:203], v[156:159], v[48:51], v[188:203]
	v_exp_f32_e32 v32, v32
	v_exp_f32_e32 v33, v33
	v_exp_f32_e32 v34, v34
	v_exp_f32_e32 v35, v35
	v_mfma_f32_32x32x16_bf16 v[188:203], v[160:163], v[52:55], v[188:203]
	v_exp_f32_e32 v36, v36
	v_exp_f32_e32 v37, v37
	v_exp_f32_e32 v38, v38
	v_exp_f32_e32 v39, v39
	v_mfma_f32_32x32x16_bf16 v[188:203], v[164:167], v[56:59], v[188:203]
	v_exp_f32_e32 v40, v40
	v_exp_f32_e32 v41, v41
	v_exp_f32_e32 v42, v42
	v_exp_f32_e32 v43, v43
	v_mfma_f32_32x32x16_bf16 v[188:203], v[168:171], v[60:63], v[188:203]
	v_exp_f32_e32 v44, v44
	v_exp_f32_e32 v45, v45
	v_exp_f32_e32 v46, v46
	v_exp_f32_e32 v47, v47
	s_add_i32 s90, s76, 320
	v_add_u32_e32 v84, s90, v107
	v_add_u32_e32 v85, 0, v84
	v_add_u32_e32 v86, 1, v84
	v_add_u32_e32 v87, 2, v84
	v_add_u32_e32 v88, 3, v84
	v_cmp_gt_u32_e64 s[30:31], s98, v85
	v_cmp_gt_u32_e64 s[36:37], s98, v86
	v_cmp_gt_u32_e64 s[78:79], s98, v87
	v_cmp_gt_u32_e64 s[50:51], s98, v88
	v_cndmask_b32_e64 v32, 0, v32, s[30:31]
	v_add_u32_e32 v85, 8, v84
	v_cmp_gt_u32_e64 s[30:31], s98, v85
	v_cndmask_b32_e64 v33, 0, v33, s[36:37]
	v_add_u32_e32 v86, 9, v84
	v_cmp_gt_u32_e64 s[36:37], s98, v86
	v_cndmask_b32_e64 v34, 0, v34, s[78:79]
	v_add_u32_e32 v87, 10, v84
	v_cmp_gt_u32_e64 s[78:79], s98, v87
	v_cndmask_b32_e64 v35, 0, v35, s[50:51]
	v_add_u32_e32 v88, 11, v84
	v_cmp_gt_u32_e64 s[50:51], s98, v88
	v_cndmask_b32_e64 v36, 0, v36, s[30:31]
	v_add_u32_e32 v85, 16, v84
	v_cmp_gt_u32_e64 s[30:31], s98, v85
	v_cndmask_b32_e64 v37, 0, v37, s[36:37]
	v_add_u32_e32 v86, 17, v84
	v_cmp_gt_u32_e64 s[36:37], s98, v86
	v_cndmask_b32_e64 v38, 0, v38, s[78:79]
	v_add_u32_e32 v87, 18, v84
	v_cmp_gt_u32_e64 s[78:79], s98, v87
	v_cndmask_b32_e64 v39, 0, v39, s[50:51]
	v_add_u32_e32 v88, 19, v84
	v_cmp_gt_u32_e64 s[50:51], s98, v88
	v_cndmask_b32_e64 v40, 0, v40, s[30:31]
	v_add_u32_e32 v85, 24, v84
	v_cmp_gt_u32_e64 s[30:31], s98, v85
	v_cndmask_b32_e64 v41, 0, v41, s[36:37]
	v_add_u32_e32 v86, 25, v84
	v_cmp_gt_u32_e64 s[36:37], s98, v86
	v_cndmask_b32_e64 v42, 0, v42, s[78:79]
	v_add_u32_e32 v87, 26, v84
	v_cmp_gt_u32_e64 s[78:79], s98, v87
	v_cndmask_b32_e64 v43, 0, v43, s[50:51]
	v_add_u32_e32 v88, 27, v84
	v_cmp_gt_u32_e64 s[50:51], s98, v88
	v_nop
	v_cndmask_b32_e64 v44, 0, v44, s[30:31]
	v_cndmask_b32_e64 v45, 0, v45, s[36:37]
	v_cndmask_b32_e64 v46, 0, v46, s[78:79]
	v_cndmask_b32_e64 v47, 0, v47, s[50:51]
	v_cvt_pk_bf16_f32 v64, v32, v33
	v_cvt_pk_bf16_f32 v65, v34, v35
	v_cvt_pk_bf16_f32 v66, v36, v37
	v_cvt_pk_bf16_f32 v67, v38, v39
	v_cvt_pk_bf16_f32 v68, v40, v41
	v_cvt_pk_bf16_f32 v69, v42, v43
	v_cvt_pk_bf16_f32 v70, v44, v45
	v_cvt_pk_bf16_f32 v71, v46, v47
	v_pk_add_f32 v[232:233], v[232:233], v[32:33]
	v_pk_add_f32 v[232:233], v[232:233], v[34:35]
	v_pk_add_f32 v[232:233], v[232:233], v[36:37]
	v_pk_add_f32 v[232:233], v[232:233], v[38:39]
	v_pk_add_f32 v[232:233], v[232:233], v[40:41]
	v_pk_add_f32 v[232:233], v[232:233], v[42:43]
	v_pk_add_f32 v[232:233], v[232:233], v[44:45]
	v_pk_add_f32 v[232:233], v[232:233], v[46:47]
	v_add_u32_e32 v115, 952, v115
	ds_read2_b32 v[32:33], v115 offset0:0 offset1:1
	ds_read2_b32 v[34:35], v115 offset0:2 offset1:3
	ds_read2_b32 v[36:37], v115 offset0:8 offset1:9
	ds_read2_b32 v[38:39], v115 offset0:10 offset1:11
	ds_read2_b32 v[40:41], v115 offset0:17 offset1:18
	ds_read2_b32 v[42:43], v115 offset0:19 offset1:20
	ds_read2_b32 v[44:45], v115 offset0:25 offset1:26
	ds_read2_b32 v[46:47], v115 offset0:27 offset1:28
	v_mfma_f32_32x32x16_bf16 v[0:15], v[64:67], v[72:75], v[0:15]
	v_mfma_f32_32x32x16_bf16 v[16:31], v[64:67], v[76:79], v[16:31]
	v_mfma_f32_32x32x16_bf16 v[0:15], v[68:71], v[220:223], v[0:15]
	v_mfma_f32_32x32x16_bf16 v[16:31], v[68:71], v[224:227], v[16:31]
	s_add_i32 s90, s76, 416
	v_add_u32_e32 v80, s90, v235
	v_add_u32_e32 v83, s90, v236
	v_add_u32_e32 v99, s90, v237
	v_add_u32_e32 v253, s90, v238
	v_add_u32_e32 v254, s90, v100
	v_add_u32_e32 v255, s90, v149
	v_med3_i32 v80, v80, 0, s99
	v_med3_i32 v83, v83, 0, s99
	v_med3_i32 v99, v99, 0, s99
	v_med3_i32 v253, v253, 0, s99
	v_med3_i32 v254, v254, 0, s99
	v_med3_i32 v255, v255, 0, s99
	v_mad_u32_u24 v80, v80, s100, v252
	v_mad_u32_u24 v83, v83, s100, v252
	v_mad_u32_u24 v99, v99, s100, v252
	v_mad_u32_u24 v253, v253, s100, v252
	v_mad_u32_u24 v254, v254, s100, v153
	v_mad_u32_u24 v255, v255, s100, v153
	global_load_dwordx4 v[156:159], v80, s[82:83]
	global_load_dwordx4 v[160:163], v83, s[82:83]
	global_load_dwordx4 v[164:167], v99, s[82:83]
	global_load_dwordx4 v[168:171], v253, s[82:83]
	global_load_dwordx4 v[172:175], v254, s[82:83] offset:768
	global_load_dwordx4 v[176:179], v255, s[82:83] offset:768
	global_load_dwordx4 v[180:183], v254, s[82:83] offset:832
	global_load_dwordx4 v[184:187], v255, s[82:83] offset:832
	ds_read_b64_tr_b16 v[72:73], v231
	ds_read_b64_tr_b16 v[74:75], v231 offset:512
	ds_read_b64_tr_b16 v[76:77], v231 offset:2048
	ds_read_b64_tr_b16 v[78:79], v231 offset:2560
	ds_read_b64_tr_b16 v[220:221], v231 offset:1024
	ds_read_b64_tr_b16 v[222:223], v231 offset:1536
	ds_read_b64_tr_b16 v[224:225], v231 offset:3072
	ds_read_b64_tr_b16 v[226:227], v231 offset:3584
	s_waitcnt vmcnt(8)
	ds_write_b128 v247, v[116:119]
	ds_write_b128 v247, v[120:123] offset:1024
	ds_write_b128 v247, v[124:127] offset:2048
	ds_write_b128 v247, v[128:131] offset:3072
	ds_read_b128 v[116:119], v248
	ds_read_b128 v[120:123], v249
	ds_read_b128 v[124:127], v250
	ds_read_b128 v[128:131], v251
	ds_write_b128 v112, v[132:135]
	ds_write_b128 v112, v[136:139] offset:1024
	ds_write_b128 v112, v[140:143] offset:2048
	ds_write_b128 v112, v[144:147] offset:3072
	s_waitcnt lgkmcnt(4)
	v_mfma_f32_32x32x16_bf16 v[32:47], v[116:119], v[48:51], v[32:47]
	v_exp_f32_e32 v188, v188
	v_exp_f32_e32 v189, v189
	v_exp_f32_e32 v190, v190
	v_exp_f32_e32 v191, v191
	v_mfma_f32_32x32x16_bf16 v[32:47], v[120:123], v[52:55], v[32:47]
	v_exp_f32_e32 v192, v192
	v_exp_f32_e32 v193, v193
	v_exp_f32_e32 v194, v194
	v_exp_f32_e32 v195, v195
	v_mfma_f32_32x32x16_bf16 v[32:47], v[124:127], v[56:59], v[32:47]
	v_exp_f32_e32 v196, v196
	v_exp_f32_e32 v197, v197
	v_exp_f32_e32 v198, v198
	v_exp_f32_e32 v199, v199
	v_mfma_f32_32x32x16_bf16 v[32:47], v[128:131], v[60:63], v[32:47]
	v_exp_f32_e32 v200, v200
	v_exp_f32_e32 v201, v201
	v_exp_f32_e32 v202, v202
	v_exp_f32_e32 v203, v203
	s_add_i32 s90, s76, 352
	v_add_u32_e32 v84, s90, v107
	v_add_u32_e32 v85, 0, v84
	v_add_u32_e32 v86, 1, v84
	v_add_u32_e32 v87, 2, v84
	v_add_u32_e32 v88, 3, v84
	v_cmp_gt_u32_e64 s[30:31], s98, v85
	v_cmp_gt_u32_e64 s[36:37], s98, v86
	v_cmp_gt_u32_e64 s[78:79], s98, v87
	v_cmp_gt_u32_e64 s[50:51], s98, v88
	v_cndmask_b32_e64 v188, 0, v188, s[30:31]
	v_add_u32_e32 v85, 8, v84
	v_cmp_gt_u32_e64 s[30:31], s98, v85
	v_cndmask_b32_e64 v189, 0, v189, s[36:37]
	v_add_u32_e32 v86, 9, v84
	v_cmp_gt_u32_e64 s[36:37], s98, v86
	v_cndmask_b32_e64 v190, 0, v190, s[78:79]
	v_add_u32_e32 v87, 10, v84
	v_cmp_gt_u32_e64 s[78:79], s98, v87
	v_cndmask_b32_e64 v191, 0, v191, s[50:51]
	v_add_u32_e32 v88, 11, v84
	v_cmp_gt_u32_e64 s[50:51], s98, v88
	v_cndmask_b32_e64 v192, 0, v192, s[30:31]
	v_add_u32_e32 v85, 16, v84
	v_cmp_gt_u32_e64 s[30:31], s98, v85
	v_cndmask_b32_e64 v193, 0, v193, s[36:37]
	v_add_u32_e32 v86, 17, v84
	v_cmp_gt_u32_e64 s[36:37], s98, v86
	v_cndmask_b32_e64 v194, 0, v194, s[78:79]
	v_add_u32_e32 v87, 18, v84
	v_cmp_gt_u32_e64 s[78:79], s98, v87
	v_cndmask_b32_e64 v195, 0, v195, s[50:51]
	v_add_u32_e32 v88, 19, v84
	v_cmp_gt_u32_e64 s[50:51], s98, v88
	v_cndmask_b32_e64 v196, 0, v196, s[30:31]
	v_add_u32_e32 v85, 24, v84
	v_cmp_gt_u32_e64 s[30:31], s98, v85
	v_cndmask_b32_e64 v197, 0, v197, s[36:37]
	v_add_u32_e32 v86, 25, v84
	v_cmp_gt_u32_e64 s[36:37], s98, v86
	v_cndmask_b32_e64 v198, 0, v198, s[78:79]
	v_add_u32_e32 v87, 26, v84
	v_cmp_gt_u32_e64 s[78:79], s98, v87
	v_cndmask_b32_e64 v199, 0, v199, s[50:51]
	v_add_u32_e32 v88, 27, v84
	v_cmp_gt_u32_e64 s[50:51], s98, v88
	v_nop
	v_cndmask_b32_e64 v200, 0, v200, s[30:31]
	v_cndmask_b32_e64 v201, 0, v201, s[36:37]
	v_cndmask_b32_e64 v202, 0, v202, s[78:79]
	v_cndmask_b32_e64 v203, 0, v203, s[50:51]
	v_cvt_pk_bf16_f32 v64, v188, v189
	v_cvt_pk_bf16_f32 v65, v190, v191
	v_cvt_pk_bf16_f32 v66, v192, v193
	v_cvt_pk_bf16_f32 v67, v194, v195
	v_cvt_pk_bf16_f32 v68, v196, v197
	v_cvt_pk_bf16_f32 v69, v198, v199
	v_cvt_pk_bf16_f32 v70, v200, v201
	v_cvt_pk_bf16_f32 v71, v202, v203
	v_pk_add_f32 v[232:233], v[232:233], v[188:189]
	v_pk_add_f32 v[232:233], v[232:233], v[190:191]
	v_pk_add_f32 v[232:233], v[232:233], v[192:193]
	v_pk_add_f32 v[232:233], v[232:233], v[194:195]
	v_pk_add_f32 v[232:233], v[232:233], v[196:197]
	v_pk_add_f32 v[232:233], v[232:233], v[198:199]
	v_pk_add_f32 v[232:233], v[232:233], v[200:201]
	v_pk_add_f32 v[232:233], v[232:233], v[202:203]
	ds_read2_b32 v[188:189], v115 offset0:34 offset1:35
	ds_read2_b32 v[190:191], v115 offset0:36 offset1:37
	ds_read2_b32 v[192:193], v115 offset0:42 offset1:43
	ds_read2_b32 v[194:195], v115 offset0:44 offset1:45
	ds_read2_b32 v[196:197], v115 offset0:51 offset1:52
	ds_read2_b32 v[198:199], v115 offset0:53 offset1:54
	ds_read2_b32 v[200:201], v115 offset0:59 offset1:60
	ds_read2_b32 v[202:203], v115 offset0:61 offset1:62
	v_mfma_f32_32x32x16_bf16 v[0:15], v[64:67], v[72:75], v[0:15]
	v_mfma_f32_32x32x16_bf16 v[16:31], v[64:67], v[76:79], v[16:31]
	v_mfma_f32_32x32x16_bf16 v[0:15], v[68:71], v[220:223], v[0:15]
	v_mfma_f32_32x32x16_bf16 v[16:31], v[68:71], v[224:227], v[16:31]
	s_add_i32 s90, s76, 448
	v_add_u32_e32 v80, s90, v235
	v_add_u32_e32 v83, s90, v236
	v_add_u32_e32 v99, s90, v237
	v_add_u32_e32 v253, s90, v238
	v_add_u32_e32 v254, s90, v100
	v_add_u32_e32 v255, s90, v149
	v_med3_i32 v80, v80, 0, s99
	v_med3_i32 v83, v83, 0, s99
	v_med3_i32 v99, v99, 0, s99
	v_med3_i32 v253, v253, 0, s99
	v_med3_i32 v254, v254, 0, s99
	v_med3_i32 v255, v255, 0, s99
	v_mad_u32_u24 v80, v80, s100, v252
	v_mad_u32_u24 v83, v83, s100, v252
	v_mad_u32_u24 v99, v99, s100, v252
	v_mad_u32_u24 v253, v253, s100, v252
	v_mad_u32_u24 v254, v254, s100, v153
	v_mad_u32_u24 v255, v255, s100, v153
	global_load_dwordx4 v[116:119], v80, s[82:83]
	global_load_dwordx4 v[120:123], v83, s[82:83]
	global_load_dwordx4 v[124:127], v99, s[82:83]
	global_load_dwordx4 v[128:131], v253, s[82:83]
	global_load_dwordx4 v[132:135], v254, s[82:83] offset:768
	global_load_dwordx4 v[136:139], v255, s[82:83] offset:768
	global_load_dwordx4 v[140:143], v254, s[82:83] offset:832
	global_load_dwordx4 v[144:147], v255, s[82:83] offset:832
	ds_read_b64_tr_b16 v[72:73], v231
	ds_read_b64_tr_b16 v[74:75], v231 offset:512
	ds_read_b64_tr_b16 v[76:77], v231 offset:2048
	ds_read_b64_tr_b16 v[78:79], v231 offset:2560
	ds_read_b64_tr_b16 v[220:221], v231 offset:1024
	ds_read_b64_tr_b16 v[222:223], v231 offset:1536
	ds_read_b64_tr_b16 v[224:225], v231 offset:3072
	ds_read_b64_tr_b16 v[226:227], v231 offset:3584
	s_waitcnt vmcnt(8)
	ds_write_b128 v247, v[156:159]
	ds_write_b128 v247, v[160:163] offset:1024
	ds_write_b128 v247, v[164:167] offset:2048
	ds_write_b128 v247, v[168:171] offset:3072
	ds_read_b128 v[156:159], v248
	ds_read_b128 v[160:163], v249
	ds_read_b128 v[164:167], v250
	ds_read_b128 v[168:171], v251
	ds_write_b128 v112, v[172:175]
	ds_write_b128 v112, v[176:179] offset:1024
	ds_write_b128 v112, v[180:183] offset:2048
	ds_write_b128 v112, v[184:187] offset:3072
	s_waitcnt lgkmcnt(4)
	v_mfma_f32_32x32x16_bf16 v[188:203], v[156:159], v[48:51], v[188:203]
	v_exp_f32_e32 v32, v32
	v_exp_f32_e32 v33, v33
	v_exp_f32_e32 v34, v34
	v_exp_f32_e32 v35, v35
	v_mfma_f32_32x32x16_bf16 v[188:203], v[160:163], v[52:55], v[188:203]
	v_exp_f32_e32 v36, v36
	v_exp_f32_e32 v37, v37
	v_exp_f32_e32 v38, v38
	v_exp_f32_e32 v39, v39
	v_mfma_f32_32x32x16_bf16 v[188:203], v[164:167], v[56:59], v[188:203]
	v_exp_f32_e32 v40, v40
	v_exp_f32_e32 v41, v41
	v_exp_f32_e32 v42, v42
	v_exp_f32_e32 v43, v43
	v_mfma_f32_32x32x16_bf16 v[188:203], v[168:171], v[60:63], v[188:203]
	v_exp_f32_e32 v44, v44
	v_exp_f32_e32 v45, v45
	v_exp_f32_e32 v46, v46
	v_exp_f32_e32 v47, v47
	s_add_i32 s90, s76, 384
	v_add_u32_e32 v84, s90, v107
	v_add_u32_e32 v85, 0, v84
	v_add_u32_e32 v86, 1, v84
	v_add_u32_e32 v87, 2, v84
	v_add_u32_e32 v88, 3, v84
	v_cmp_gt_u32_e64 s[30:31], s98, v85
	v_cmp_gt_u32_e64 s[36:37], s98, v86
	v_cmp_gt_u32_e64 s[78:79], s98, v87
	v_cmp_gt_u32_e64 s[50:51], s98, v88
	v_cndmask_b32_e64 v32, 0, v32, s[30:31]
	v_add_u32_e32 v85, 8, v84
	v_cmp_gt_u32_e64 s[30:31], s98, v85
	v_cndmask_b32_e64 v33, 0, v33, s[36:37]
	v_add_u32_e32 v86, 9, v84
	v_cmp_gt_u32_e64 s[36:37], s98, v86
	v_cndmask_b32_e64 v34, 0, v34, s[78:79]
	v_add_u32_e32 v87, 10, v84
	v_cmp_gt_u32_e64 s[78:79], s98, v87
	v_cndmask_b32_e64 v35, 0, v35, s[50:51]
	v_add_u32_e32 v88, 11, v84
	v_cmp_gt_u32_e64 s[50:51], s98, v88
	v_cndmask_b32_e64 v36, 0, v36, s[30:31]
	v_add_u32_e32 v85, 16, v84
	v_cmp_gt_u32_e64 s[30:31], s98, v85
	v_cndmask_b32_e64 v37, 0, v37, s[36:37]
	v_add_u32_e32 v86, 17, v84
	v_cmp_gt_u32_e64 s[36:37], s98, v86
	v_cndmask_b32_e64 v38, 0, v38, s[78:79]
	v_add_u32_e32 v87, 18, v84
	v_cmp_gt_u32_e64 s[78:79], s98, v87
	v_cndmask_b32_e64 v39, 0, v39, s[50:51]
	v_add_u32_e32 v88, 19, v84
	v_cmp_gt_u32_e64 s[50:51], s98, v88
	v_cndmask_b32_e64 v40, 0, v40, s[30:31]
	v_add_u32_e32 v85, 24, v84
	v_cmp_gt_u32_e64 s[30:31], s98, v85
	v_cndmask_b32_e64 v41, 0, v41, s[36:37]
	v_add_u32_e32 v86, 25, v84
	v_cmp_gt_u32_e64 s[36:37], s98, v86
	v_cndmask_b32_e64 v42, 0, v42, s[78:79]
	v_add_u32_e32 v87, 26, v84
	v_cmp_gt_u32_e64 s[78:79], s98, v87
	v_cndmask_b32_e64 v43, 0, v43, s[50:51]
	v_add_u32_e32 v88, 27, v84
	v_cmp_gt_u32_e64 s[50:51], s98, v88
	v_nop
	v_cndmask_b32_e64 v44, 0, v44, s[30:31]
	v_cndmask_b32_e64 v45, 0, v45, s[36:37]
	v_cndmask_b32_e64 v46, 0, v46, s[78:79]
	v_cndmask_b32_e64 v47, 0, v47, s[50:51]
	v_cvt_pk_bf16_f32 v64, v32, v33
	v_cvt_pk_bf16_f32 v65, v34, v35
	v_cvt_pk_bf16_f32 v66, v36, v37
	v_cvt_pk_bf16_f32 v67, v38, v39
	v_cvt_pk_bf16_f32 v68, v40, v41
	v_cvt_pk_bf16_f32 v69, v42, v43
	v_cvt_pk_bf16_f32 v70, v44, v45
	v_cvt_pk_bf16_f32 v71, v46, v47
	v_pk_add_f32 v[232:233], v[232:233], v[32:33]
	v_pk_add_f32 v[232:233], v[232:233], v[34:35]
	v_pk_add_f32 v[232:233], v[232:233], v[36:37]
	v_pk_add_f32 v[232:233], v[232:233], v[38:39]
	v_pk_add_f32 v[232:233], v[232:233], v[40:41]
	v_pk_add_f32 v[232:233], v[232:233], v[42:43]
	v_pk_add_f32 v[232:233], v[232:233], v[44:45]
	v_pk_add_f32 v[232:233], v[232:233], v[46:47]
	ds_read2_b32 v[32:33], v115 offset0:68 offset1:69
	ds_read2_b32 v[34:35], v115 offset0:70 offset1:71
	ds_read2_b32 v[36:37], v115 offset0:76 offset1:77
	ds_read2_b32 v[38:39], v115 offset0:78 offset1:79
	ds_read2_b32 v[40:41], v115 offset0:85 offset1:86
	ds_read2_b32 v[42:43], v115 offset0:87 offset1:88
	ds_read2_b32 v[44:45], v115 offset0:93 offset1:94
	ds_read2_b32 v[46:47], v115 offset0:95 offset1:96
	v_mfma_f32_32x32x16_bf16 v[0:15], v[64:67], v[72:75], v[0:15]
	v_mfma_f32_32x32x16_bf16 v[16:31], v[64:67], v[76:79], v[16:31]
	v_mfma_f32_32x32x16_bf16 v[0:15], v[68:71], v[220:223], v[0:15]
	v_mfma_f32_32x32x16_bf16 v[16:31], v[68:71], v[224:227], v[16:31]
	s_add_i32 s90, s76, 480
	v_add_u32_e32 v80, s90, v235
	v_add_u32_e32 v83, s90, v236
	v_add_u32_e32 v99, s90, v237
	v_add_u32_e32 v253, s90, v238
	v_add_u32_e32 v254, s90, v100
	v_add_u32_e32 v255, s90, v149
	v_med3_i32 v80, v80, 0, s99
	v_med3_i32 v83, v83, 0, s99
	v_med3_i32 v99, v99, 0, s99
	v_med3_i32 v253, v253, 0, s99
	v_med3_i32 v254, v254, 0, s99
	v_med3_i32 v255, v255, 0, s99
	v_mad_u32_u24 v80, v80, s100, v252
	v_mad_u32_u24 v83, v83, s100, v252
	v_mad_u32_u24 v99, v99, s100, v252
	v_mad_u32_u24 v253, v253, s100, v252
	v_mad_u32_u24 v254, v254, s100, v153
	v_mad_u32_u24 v255, v255, s100, v153
	global_load_dwordx4 v[156:159], v80, s[82:83]
	global_load_dwordx4 v[160:163], v83, s[82:83]
	global_load_dwordx4 v[164:167], v99, s[82:83]
	global_load_dwordx4 v[168:171], v253, s[82:83]
	global_load_dwordx4 v[172:175], v254, s[82:83] offset:768
	global_load_dwordx4 v[176:179], v255, s[82:83] offset:768
	global_load_dwordx4 v[180:183], v254, s[82:83] offset:832
	global_load_dwordx4 v[184:187], v255, s[82:83] offset:832
	ds_read_b64_tr_b16 v[72:73], v231
	ds_read_b64_tr_b16 v[74:75], v231 offset:512
	ds_read_b64_tr_b16 v[76:77], v231 offset:2048
	ds_read_b64_tr_b16 v[78:79], v231 offset:2560
	ds_read_b64_tr_b16 v[220:221], v231 offset:1024
	ds_read_b64_tr_b16 v[222:223], v231 offset:1536
	ds_read_b64_tr_b16 v[224:225], v231 offset:3072
	ds_read_b64_tr_b16 v[226:227], v231 offset:3584
	s_waitcnt vmcnt(8)
	ds_write_b128 v247, v[116:119]
	ds_write_b128 v247, v[120:123] offset:1024
	ds_write_b128 v247, v[124:127] offset:2048
	ds_write_b128 v247, v[128:131] offset:3072
	ds_read_b128 v[116:119], v248
	ds_read_b128 v[120:123], v249
	ds_read_b128 v[124:127], v250
	ds_read_b128 v[128:131], v251
	ds_write_b128 v112, v[132:135]
	ds_write_b128 v112, v[136:139] offset:1024
	ds_write_b128 v112, v[140:143] offset:2048
	ds_write_b128 v112, v[144:147] offset:3072
	s_waitcnt lgkmcnt(4)
	v_mfma_f32_32x32x16_bf16 v[32:47], v[116:119], v[48:51], v[32:47]
	v_exp_f32_e32 v188, v188
	v_exp_f32_e32 v189, v189
	v_exp_f32_e32 v190, v190
	v_exp_f32_e32 v191, v191
	v_mfma_f32_32x32x16_bf16 v[32:47], v[120:123], v[52:55], v[32:47]
	v_exp_f32_e32 v192, v192
	v_exp_f32_e32 v193, v193
	v_exp_f32_e32 v194, v194
	v_exp_f32_e32 v195, v195
	v_mfma_f32_32x32x16_bf16 v[32:47], v[124:127], v[56:59], v[32:47]
	v_exp_f32_e32 v196, v196
	v_exp_f32_e32 v197, v197
	v_exp_f32_e32 v198, v198
	v_exp_f32_e32 v199, v199
	v_mfma_f32_32x32x16_bf16 v[32:47], v[128:131], v[60:63], v[32:47]
	v_exp_f32_e32 v200, v200
	v_exp_f32_e32 v201, v201
	v_exp_f32_e32 v202, v202
	v_exp_f32_e32 v203, v203
	s_add_i32 s90, s76, 416
	v_add_u32_e32 v84, s90, v107
	v_add_u32_e32 v85, 0, v84
	v_add_u32_e32 v86, 1, v84
	v_add_u32_e32 v87, 2, v84
	v_add_u32_e32 v88, 3, v84
	v_cmp_gt_u32_e64 s[30:31], s98, v85
	v_cmp_gt_u32_e64 s[36:37], s98, v86
	v_cmp_gt_u32_e64 s[78:79], s98, v87
	v_cmp_gt_u32_e64 s[50:51], s98, v88
	v_cndmask_b32_e64 v188, 0, v188, s[30:31]
	v_add_u32_e32 v85, 8, v84
	v_cmp_gt_u32_e64 s[30:31], s98, v85
	v_cndmask_b32_e64 v189, 0, v189, s[36:37]
	v_add_u32_e32 v86, 9, v84
	v_cmp_gt_u32_e64 s[36:37], s98, v86
	v_cndmask_b32_e64 v190, 0, v190, s[78:79]
	v_add_u32_e32 v87, 10, v84
	v_cmp_gt_u32_e64 s[78:79], s98, v87
	v_cndmask_b32_e64 v191, 0, v191, s[50:51]
	v_add_u32_e32 v88, 11, v84
	v_cmp_gt_u32_e64 s[50:51], s98, v88
	v_cndmask_b32_e64 v192, 0, v192, s[30:31]
	v_add_u32_e32 v85, 16, v84
	v_cmp_gt_u32_e64 s[30:31], s98, v85
	v_cndmask_b32_e64 v193, 0, v193, s[36:37]
	v_add_u32_e32 v86, 17, v84
	v_cmp_gt_u32_e64 s[36:37], s98, v86
	v_cndmask_b32_e64 v194, 0, v194, s[78:79]
	v_add_u32_e32 v87, 18, v84
	v_cmp_gt_u32_e64 s[78:79], s98, v87
	v_cndmask_b32_e64 v195, 0, v195, s[50:51]
	v_add_u32_e32 v88, 19, v84
	v_cmp_gt_u32_e64 s[50:51], s98, v88
	v_cndmask_b32_e64 v196, 0, v196, s[30:31]
	v_add_u32_e32 v85, 24, v84
	v_cmp_gt_u32_e64 s[30:31], s98, v85
	v_cndmask_b32_e64 v197, 0, v197, s[36:37]
	v_add_u32_e32 v86, 25, v84
	v_cmp_gt_u32_e64 s[36:37], s98, v86
	v_cndmask_b32_e64 v198, 0, v198, s[78:79]
	v_add_u32_e32 v87, 26, v84
	v_cmp_gt_u32_e64 s[78:79], s98, v87
	v_cndmask_b32_e64 v199, 0, v199, s[50:51]
	v_add_u32_e32 v88, 27, v84
	v_cmp_gt_u32_e64 s[50:51], s98, v88
	v_nop
	v_cndmask_b32_e64 v200, 0, v200, s[30:31]
	v_cndmask_b32_e64 v201, 0, v201, s[36:37]
	v_cndmask_b32_e64 v202, 0, v202, s[78:79]
	v_cndmask_b32_e64 v203, 0, v203, s[50:51]
	v_cvt_pk_bf16_f32 v64, v188, v189
	v_cvt_pk_bf16_f32 v65, v190, v191
	v_cvt_pk_bf16_f32 v66, v192, v193
	v_cvt_pk_bf16_f32 v67, v194, v195
	v_cvt_pk_bf16_f32 v68, v196, v197
	v_cvt_pk_bf16_f32 v69, v198, v199
	v_cvt_pk_bf16_f32 v70, v200, v201
	v_cvt_pk_bf16_f32 v71, v202, v203
	v_pk_add_f32 v[232:233], v[232:233], v[188:189]
	v_pk_add_f32 v[232:233], v[232:233], v[190:191]
	v_pk_add_f32 v[232:233], v[232:233], v[192:193]
	v_pk_add_f32 v[232:233], v[232:233], v[194:195]
	v_pk_add_f32 v[232:233], v[232:233], v[196:197]
	v_pk_add_f32 v[232:233], v[232:233], v[198:199]
	v_pk_add_f32 v[232:233], v[232:233], v[200:201]
	v_pk_add_f32 v[232:233], v[232:233], v[202:203]
	ds_read2_b32 v[188:189], v115 offset0:102 offset1:103
	ds_read2_b32 v[190:191], v115 offset0:104 offset1:105
	ds_read2_b32 v[192:193], v115 offset0:110 offset1:111
	ds_read2_b32 v[194:195], v115 offset0:112 offset1:113
	ds_read2_b32 v[196:197], v115 offset0:119 offset1:120
	ds_read2_b32 v[198:199], v115 offset0:121 offset1:122
	ds_read2_b32 v[200:201], v115 offset0:127 offset1:128
	ds_read2_b32 v[202:203], v115 offset0:129 offset1:130
	v_mfma_f32_32x32x16_bf16 v[0:15], v[64:67], v[72:75], v[0:15]
	v_mfma_f32_32x32x16_bf16 v[16:31], v[64:67], v[76:79], v[16:31]
	v_mfma_f32_32x32x16_bf16 v[0:15], v[68:71], v[220:223], v[0:15]
	v_mfma_f32_32x32x16_bf16 v[16:31], v[68:71], v[224:227], v[16:31]
	s_add_i32 s90, s76, 512
	v_add_u32_e32 v80, s90, v235
	v_add_u32_e32 v83, s90, v236
	v_add_u32_e32 v99, s90, v237
	v_add_u32_e32 v253, s90, v238
	v_add_u32_e32 v254, s90, v100
	v_add_u32_e32 v255, s90, v149
	v_med3_i32 v80, v80, 0, s99
	v_med3_i32 v83, v83, 0, s99
	v_med3_i32 v99, v99, 0, s99
	v_med3_i32 v253, v253, 0, s99
	v_med3_i32 v254, v254, 0, s99
	v_med3_i32 v255, v255, 0, s99
	v_mad_u32_u24 v80, v80, s100, v252
	v_mad_u32_u24 v83, v83, s100, v252
	v_mad_u32_u24 v99, v99, s100, v252
	v_mad_u32_u24 v253, v253, s100, v252
	v_mad_u32_u24 v254, v254, s100, v153
	v_mad_u32_u24 v255, v255, s100, v153
	global_load_dwordx4 v[116:119], v80, s[82:83]
	global_load_dwordx4 v[120:123], v83, s[82:83]
	global_load_dwordx4 v[124:127], v99, s[82:83]
	global_load_dwordx4 v[128:131], v253, s[82:83]
	global_load_dwordx4 v[132:135], v254, s[82:83] offset:768
	global_load_dwordx4 v[136:139], v255, s[82:83] offset:768
	global_load_dwordx4 v[140:143], v254, s[82:83] offset:832
	global_load_dwordx4 v[144:147], v255, s[82:83] offset:832
	ds_read_b64_tr_b16 v[72:73], v231
	ds_read_b64_tr_b16 v[74:75], v231 offset:512
	ds_read_b64_tr_b16 v[76:77], v231 offset:2048
	ds_read_b64_tr_b16 v[78:79], v231 offset:2560
	ds_read_b64_tr_b16 v[220:221], v231 offset:1024
	ds_read_b64_tr_b16 v[222:223], v231 offset:1536
	ds_read_b64_tr_b16 v[224:225], v231 offset:3072
	ds_read_b64_tr_b16 v[226:227], v231 offset:3584
	s_waitcnt vmcnt(8)
	ds_write_b128 v247, v[156:159]
	ds_write_b128 v247, v[160:163] offset:1024
	ds_write_b128 v247, v[164:167] offset:2048
	ds_write_b128 v247, v[168:171] offset:3072
	ds_read_b128 v[156:159], v248
	ds_read_b128 v[160:163], v249
	ds_read_b128 v[164:167], v250
	ds_read_b128 v[168:171], v251
	ds_write_b128 v112, v[172:175]
	ds_write_b128 v112, v[176:179] offset:1024
	ds_write_b128 v112, v[180:183] offset:2048
	ds_write_b128 v112, v[184:187] offset:3072
	s_waitcnt lgkmcnt(4)
	v_mfma_f32_32x32x16_bf16 v[188:203], v[156:159], v[48:51], v[188:203]
	v_exp_f32_e32 v32, v32
	v_exp_f32_e32 v33, v33
	v_exp_f32_e32 v34, v34
	v_exp_f32_e32 v35, v35
	v_mfma_f32_32x32x16_bf16 v[188:203], v[160:163], v[52:55], v[188:203]
	v_exp_f32_e32 v36, v36
	v_exp_f32_e32 v37, v37
	v_exp_f32_e32 v38, v38
	v_exp_f32_e32 v39, v39
	v_mfma_f32_32x32x16_bf16 v[188:203], v[164:167], v[56:59], v[188:203]
	v_exp_f32_e32 v40, v40
	v_exp_f32_e32 v41, v41
	v_exp_f32_e32 v42, v42
	v_exp_f32_e32 v43, v43
	v_mfma_f32_32x32x16_bf16 v[188:203], v[168:171], v[60:63], v[188:203]
	v_exp_f32_e32 v44, v44
	v_exp_f32_e32 v45, v45
	v_exp_f32_e32 v46, v46
	v_exp_f32_e32 v47, v47
	s_add_i32 s90, s76, 448
	v_add_u32_e32 v84, s90, v107
	v_add_u32_e32 v85, 0, v84
	v_add_u32_e32 v86, 1, v84
	v_add_u32_e32 v87, 2, v84
	v_add_u32_e32 v88, 3, v84
	v_cmp_gt_u32_e64 s[30:31], s98, v85
	v_cmp_gt_u32_e64 s[36:37], s98, v86
	v_cmp_gt_u32_e64 s[78:79], s98, v87
	v_cmp_gt_u32_e64 s[50:51], s98, v88
	v_cndmask_b32_e64 v32, 0, v32, s[30:31]
	v_add_u32_e32 v85, 8, v84
	v_cmp_gt_u32_e64 s[30:31], s98, v85
	v_cndmask_b32_e64 v33, 0, v33, s[36:37]
	v_add_u32_e32 v86, 9, v84
	v_cmp_gt_u32_e64 s[36:37], s98, v86
	v_cndmask_b32_e64 v34, 0, v34, s[78:79]
	v_add_u32_e32 v87, 10, v84
	v_cmp_gt_u32_e64 s[78:79], s98, v87
	v_cndmask_b32_e64 v35, 0, v35, s[50:51]
	v_add_u32_e32 v88, 11, v84
	v_cmp_gt_u32_e64 s[50:51], s98, v88
	v_cndmask_b32_e64 v36, 0, v36, s[30:31]
	v_add_u32_e32 v85, 16, v84
	v_cmp_gt_u32_e64 s[30:31], s98, v85
	v_cndmask_b32_e64 v37, 0, v37, s[36:37]
	v_add_u32_e32 v86, 17, v84
	v_cmp_gt_u32_e64 s[36:37], s98, v86
	v_cndmask_b32_e64 v38, 0, v38, s[78:79]
	v_add_u32_e32 v87, 18, v84
	v_cmp_gt_u32_e64 s[78:79], s98, v87
	v_cndmask_b32_e64 v39, 0, v39, s[50:51]
	v_add_u32_e32 v88, 19, v84
	v_cmp_gt_u32_e64 s[50:51], s98, v88
	v_cndmask_b32_e64 v40, 0, v40, s[30:31]
	v_add_u32_e32 v85, 24, v84
	v_cmp_gt_u32_e64 s[30:31], s98, v85
	v_cndmask_b32_e64 v41, 0, v41, s[36:37]
	v_add_u32_e32 v86, 25, v84
	v_cmp_gt_u32_e64 s[36:37], s98, v86
	v_cndmask_b32_e64 v42, 0, v42, s[78:79]
	v_add_u32_e32 v87, 26, v84
	v_cmp_gt_u32_e64 s[78:79], s98, v87
	v_cndmask_b32_e64 v43, 0, v43, s[50:51]
	v_add_u32_e32 v88, 27, v84
	v_cmp_gt_u32_e64 s[50:51], s98, v88
	v_nop
	v_cndmask_b32_e64 v44, 0, v44, s[30:31]
	v_cndmask_b32_e64 v45, 0, v45, s[36:37]
	v_cndmask_b32_e64 v46, 0, v46, s[78:79]
	v_cndmask_b32_e64 v47, 0, v47, s[50:51]
	v_cvt_pk_bf16_f32 v64, v32, v33
	v_cvt_pk_bf16_f32 v65, v34, v35
	v_cvt_pk_bf16_f32 v66, v36, v37
	v_cvt_pk_bf16_f32 v67, v38, v39
	v_cvt_pk_bf16_f32 v68, v40, v41
	v_cvt_pk_bf16_f32 v69, v42, v43
	v_cvt_pk_bf16_f32 v70, v44, v45
	v_cvt_pk_bf16_f32 v71, v46, v47
	v_pk_add_f32 v[232:233], v[232:233], v[32:33]
	v_pk_add_f32 v[232:233], v[232:233], v[34:35]
	v_pk_add_f32 v[232:233], v[232:233], v[36:37]
	v_pk_add_f32 v[232:233], v[232:233], v[38:39]
	v_pk_add_f32 v[232:233], v[232:233], v[40:41]
	v_pk_add_f32 v[232:233], v[232:233], v[42:43]
	v_pk_add_f32 v[232:233], v[232:233], v[44:45]
	v_pk_add_f32 v[232:233], v[232:233], v[46:47]
	ds_read2_b32 v[32:33], v115 offset0:136 offset1:137
	ds_read2_b32 v[34:35], v115 offset0:138 offset1:139
	ds_read2_b32 v[36:37], v115 offset0:144 offset1:145
	ds_read2_b32 v[38:39], v115 offset0:146 offset1:147
	ds_read2_b32 v[40:41], v115 offset0:153 offset1:154
	ds_read2_b32 v[42:43], v115 offset0:155 offset1:156
	ds_read2_b32 v[44:45], v115 offset0:161 offset1:162
	ds_read2_b32 v[46:47], v115 offset0:163 offset1:164
	v_mfma_f32_32x32x16_bf16 v[0:15], v[64:67], v[72:75], v[0:15]
	v_mfma_f32_32x32x16_bf16 v[16:31], v[64:67], v[76:79], v[16:31]
	v_mfma_f32_32x32x16_bf16 v[0:15], v[68:71], v[220:223], v[0:15]
	v_mfma_f32_32x32x16_bf16 v[16:31], v[68:71], v[224:227], v[16:31]
	s_add_i32 s90, s76, 544
	v_add_u32_e32 v80, s90, v235
	v_add_u32_e32 v83, s90, v236
	v_add_u32_e32 v99, s90, v237
	v_add_u32_e32 v253, s90, v238
	v_add_u32_e32 v254, s90, v100
	v_add_u32_e32 v255, s90, v149
	v_med3_i32 v80, v80, 0, s99
	v_med3_i32 v83, v83, 0, s99
	v_med3_i32 v99, v99, 0, s99
	v_med3_i32 v253, v253, 0, s99
	v_med3_i32 v254, v254, 0, s99
	v_med3_i32 v255, v255, 0, s99
	v_mad_u32_u24 v80, v80, s100, v252
	v_mad_u32_u24 v83, v83, s100, v252
	v_mad_u32_u24 v99, v99, s100, v252
	v_mad_u32_u24 v253, v253, s100, v252
	v_mad_u32_u24 v254, v254, s100, v153
	v_mad_u32_u24 v255, v255, s100, v153
	global_load_dwordx4 v[156:159], v80, s[82:83]
	global_load_dwordx4 v[160:163], v83, s[82:83]
	global_load_dwordx4 v[164:167], v99, s[82:83]
	global_load_dwordx4 v[168:171], v253, s[82:83]
	global_load_dwordx4 v[172:175], v254, s[82:83] offset:768
	global_load_dwordx4 v[176:179], v255, s[82:83] offset:768
	global_load_dwordx4 v[180:183], v254, s[82:83] offset:832
	global_load_dwordx4 v[184:187], v255, s[82:83] offset:832
	ds_read_b64_tr_b16 v[72:73], v231
	ds_read_b64_tr_b16 v[74:75], v231 offset:512
	ds_read_b64_tr_b16 v[76:77], v231 offset:2048
	ds_read_b64_tr_b16 v[78:79], v231 offset:2560
	ds_read_b64_tr_b16 v[220:221], v231 offset:1024
	ds_read_b64_tr_b16 v[222:223], v231 offset:1536
	ds_read_b64_tr_b16 v[224:225], v231 offset:3072
	ds_read_b64_tr_b16 v[226:227], v231 offset:3584
	s_waitcnt vmcnt(8)
	ds_write_b128 v247, v[116:119]
	ds_write_b128 v247, v[120:123] offset:1024
	ds_write_b128 v247, v[124:127] offset:2048
	ds_write_b128 v247, v[128:131] offset:3072
	ds_read_b128 v[116:119], v248
	ds_read_b128 v[120:123], v249
	ds_read_b128 v[124:127], v250
	ds_read_b128 v[128:131], v251
	ds_write_b128 v112, v[132:135]
	ds_write_b128 v112, v[136:139] offset:1024
	ds_write_b128 v112, v[140:143] offset:2048
	ds_write_b128 v112, v[144:147] offset:3072
	s_waitcnt lgkmcnt(4)
	v_mfma_f32_32x32x16_bf16 v[32:47], v[116:119], v[48:51], v[32:47]
	v_exp_f32_e32 v188, v188
	v_exp_f32_e32 v189, v189
	v_exp_f32_e32 v190, v190
	v_exp_f32_e32 v191, v191
	v_mfma_f32_32x32x16_bf16 v[32:47], v[120:123], v[52:55], v[32:47]
	v_exp_f32_e32 v192, v192
	v_exp_f32_e32 v193, v193
	v_exp_f32_e32 v194, v194
	v_exp_f32_e32 v195, v195
	v_mfma_f32_32x32x16_bf16 v[32:47], v[124:127], v[56:59], v[32:47]
	v_exp_f32_e32 v196, v196
	v_exp_f32_e32 v197, v197
	v_exp_f32_e32 v198, v198
	v_exp_f32_e32 v199, v199
	v_mfma_f32_32x32x16_bf16 v[32:47], v[128:131], v[60:63], v[32:47]
	v_exp_f32_e32 v200, v200
	v_exp_f32_e32 v201, v201
	v_exp_f32_e32 v202, v202
	v_exp_f32_e32 v203, v203
	s_add_i32 s90, s76, 480
	v_add_u32_e32 v84, s90, v107
	v_add_u32_e32 v85, 0, v84
	v_add_u32_e32 v86, 1, v84
	v_add_u32_e32 v87, 2, v84
	v_add_u32_e32 v88, 3, v84
	v_cmp_gt_u32_e64 s[30:31], s98, v85
	v_cmp_gt_u32_e64 s[36:37], s98, v86
	v_cmp_gt_u32_e64 s[78:79], s98, v87
	v_cmp_gt_u32_e64 s[50:51], s98, v88
	v_cndmask_b32_e64 v188, 0, v188, s[30:31]
	v_add_u32_e32 v85, 8, v84
	v_cmp_gt_u32_e64 s[30:31], s98, v85
	v_cndmask_b32_e64 v189, 0, v189, s[36:37]
	v_add_u32_e32 v86, 9, v84
	v_cmp_gt_u32_e64 s[36:37], s98, v86
	v_cndmask_b32_e64 v190, 0, v190, s[78:79]
	v_add_u32_e32 v87, 10, v84
	v_cmp_gt_u32_e64 s[78:79], s98, v87
	v_cndmask_b32_e64 v191, 0, v191, s[50:51]
	v_add_u32_e32 v88, 11, v84
	v_cmp_gt_u32_e64 s[50:51], s98, v88
	v_cndmask_b32_e64 v192, 0, v192, s[30:31]
	v_add_u32_e32 v85, 16, v84
	v_cmp_gt_u32_e64 s[30:31], s98, v85
	v_cndmask_b32_e64 v193, 0, v193, s[36:37]
	v_add_u32_e32 v86, 17, v84
	v_cmp_gt_u32_e64 s[36:37], s98, v86
	v_cndmask_b32_e64 v194, 0, v194, s[78:79]
	v_add_u32_e32 v87, 18, v84
	v_cmp_gt_u32_e64 s[78:79], s98, v87
	v_cndmask_b32_e64 v195, 0, v195, s[50:51]
	v_add_u32_e32 v88, 19, v84
	v_cmp_gt_u32_e64 s[50:51], s98, v88
	v_cndmask_b32_e64 v196, 0, v196, s[30:31]
	v_add_u32_e32 v85, 24, v84
	v_cmp_gt_u32_e64 s[30:31], s98, v85
	v_cndmask_b32_e64 v197, 0, v197, s[36:37]
	v_add_u32_e32 v86, 25, v84
	v_cmp_gt_u32_e64 s[36:37], s98, v86
	v_cndmask_b32_e64 v198, 0, v198, s[78:79]
	v_add_u32_e32 v87, 26, v84
	v_cmp_gt_u32_e64 s[78:79], s98, v87
	v_cndmask_b32_e64 v199, 0, v199, s[50:51]
	v_add_u32_e32 v88, 27, v84
	v_cmp_gt_u32_e64 s[50:51], s98, v88
	v_nop
	v_cndmask_b32_e64 v200, 0, v200, s[30:31]
	v_cndmask_b32_e64 v201, 0, v201, s[36:37]
	v_cndmask_b32_e64 v202, 0, v202, s[78:79]
	v_cndmask_b32_e64 v203, 0, v203, s[50:51]
	v_cvt_pk_bf16_f32 v64, v188, v189
	v_cvt_pk_bf16_f32 v65, v190, v191
	v_cvt_pk_bf16_f32 v66, v192, v193
	v_cvt_pk_bf16_f32 v67, v194, v195
	v_cvt_pk_bf16_f32 v68, v196, v197
	v_cvt_pk_bf16_f32 v69, v198, v199
	v_cvt_pk_bf16_f32 v70, v200, v201
	v_cvt_pk_bf16_f32 v71, v202, v203
	v_pk_add_f32 v[232:233], v[232:233], v[188:189]
	v_pk_add_f32 v[232:233], v[232:233], v[190:191]
	v_pk_add_f32 v[232:233], v[232:233], v[192:193]
	v_pk_add_f32 v[232:233], v[232:233], v[194:195]
	v_pk_add_f32 v[232:233], v[232:233], v[196:197]
	v_pk_add_f32 v[232:233], v[232:233], v[198:199]
	v_pk_add_f32 v[232:233], v[232:233], v[200:201]
	v_pk_add_f32 v[232:233], v[232:233], v[202:203]
	ds_read2_b32 v[188:189], v115 offset0:170 offset1:171
	ds_read2_b32 v[190:191], v115 offset0:172 offset1:173
	ds_read2_b32 v[192:193], v115 offset0:178 offset1:179
	ds_read2_b32 v[194:195], v115 offset0:180 offset1:181
	ds_read2_b32 v[196:197], v115 offset0:187 offset1:188
	ds_read2_b32 v[198:199], v115 offset0:189 offset1:190
	ds_read2_b32 v[200:201], v115 offset0:195 offset1:196
	ds_read2_b32 v[202:203], v115 offset0:197 offset1:198
	v_mfma_f32_32x32x16_bf16 v[0:15], v[64:67], v[72:75], v[0:15]
	v_mfma_f32_32x32x16_bf16 v[16:31], v[64:67], v[76:79], v[16:31]
	v_mfma_f32_32x32x16_bf16 v[0:15], v[68:71], v[220:223], v[0:15]
	v_mfma_f32_32x32x16_bf16 v[16:31], v[68:71], v[224:227], v[16:31]
	s_add_i32 s90, s76, -256
	v_add_u32_e32 v80, s90, v239
	v_add_u32_e32 v83, s90, v240
	v_add_u32_e32 v99, s90, v241
	v_add_u32_e32 v253, s90, v242
	v_add_u32_e32 v254, s90, v101
	v_add_u32_e32 v255, s90, v150
	v_med3_i32 v80, v80, 0, s99
	v_med3_i32 v83, v83, 0, s99
	v_med3_i32 v99, v99, 0, s99
	v_med3_i32 v253, v253, 0, s99
	v_med3_i32 v254, v254, 0, s99
	v_med3_i32 v255, v255, 0, s99
	v_mad_u32_u24 v80, v80, s100, v252
	v_mad_u32_u24 v83, v83, s100, v252
	v_mad_u32_u24 v99, v99, s100, v252
	v_mad_u32_u24 v253, v253, s100, v252
	v_mad_u32_u24 v254, v254, s100, v153
	v_mad_u32_u24 v255, v255, s100, v153
	global_load_dwordx4 v[116:119], v80, s[82:83]
	global_load_dwordx4 v[120:123], v83, s[82:83]
	global_load_dwordx4 v[124:127], v99, s[82:83]
	global_load_dwordx4 v[128:131], v253, s[82:83]
	global_load_dwordx4 v[132:135], v254, s[82:83] offset:768
	global_load_dwordx4 v[136:139], v255, s[82:83] offset:768
	global_load_dwordx4 v[140:143], v254, s[82:83] offset:832
	global_load_dwordx4 v[144:147], v255, s[82:83] offset:832
	ds_read_b64_tr_b16 v[72:73], v231
	ds_read_b64_tr_b16 v[74:75], v231 offset:512
	ds_read_b64_tr_b16 v[76:77], v231 offset:2048
	ds_read_b64_tr_b16 v[78:79], v231 offset:2560
	ds_read_b64_tr_b16 v[220:221], v231 offset:1024
	ds_read_b64_tr_b16 v[222:223], v231 offset:1536
	ds_read_b64_tr_b16 v[224:225], v231 offset:3072
	ds_read_b64_tr_b16 v[226:227], v231 offset:3584
	s_waitcnt vmcnt(8)
	ds_write_b128 v247, v[156:159]
	ds_write_b128 v247, v[160:163] offset:1024
	ds_write_b128 v247, v[164:167] offset:2048
	ds_write_b128 v247, v[168:171] offset:3072
	ds_read_b128 v[156:159], v248
	ds_read_b128 v[160:163], v249
	ds_read_b128 v[164:167], v250
	ds_read_b128 v[168:171], v251
	ds_write_b128 v112, v[172:175]
	ds_write_b128 v112, v[176:179] offset:1024
	ds_write_b128 v112, v[180:183] offset:2048
	ds_write_b128 v112, v[184:187] offset:3072
	s_waitcnt lgkmcnt(4)
	v_mfma_f32_32x32x16_bf16 v[188:203], v[156:159], v[48:51], v[188:203]
	v_exp_f32_e32 v32, v32
	v_exp_f32_e32 v33, v33
	v_exp_f32_e32 v34, v34
	v_exp_f32_e32 v35, v35
	v_mfma_f32_32x32x16_bf16 v[188:203], v[160:163], v[52:55], v[188:203]
	v_exp_f32_e32 v36, v36
	v_exp_f32_e32 v37, v37
	v_exp_f32_e32 v38, v38
	v_exp_f32_e32 v39, v39
	v_mfma_f32_32x32x16_bf16 v[188:203], v[164:167], v[56:59], v[188:203]
	v_exp_f32_e32 v40, v40
	v_exp_f32_e32 v41, v41
	v_exp_f32_e32 v42, v42
	v_exp_f32_e32 v43, v43
	v_mfma_f32_32x32x16_bf16 v[188:203], v[168:171], v[60:63], v[188:203]
	v_exp_f32_e32 v44, v44
	v_exp_f32_e32 v45, v45
	v_exp_f32_e32 v46, v46
	v_exp_f32_e32 v47, v47
	s_add_i32 s90, s76, 512
	v_add_u32_e32 v84, s90, v107
	v_add_u32_e32 v85, 0, v84
	v_add_u32_e32 v86, 1, v84
	v_add_u32_e32 v87, 2, v84
	v_add_u32_e32 v88, 3, v84
	v_cmp_gt_u32_e64 s[30:31], s98, v85
	v_cmp_gt_u32_e64 s[36:37], s98, v86
	v_cmp_gt_u32_e64 s[78:79], s98, v87
	v_cmp_gt_u32_e64 s[50:51], s98, v88
	v_cndmask_b32_e64 v32, 0, v32, s[30:31]
	v_add_u32_e32 v85, 8, v84
	v_cmp_gt_u32_e64 s[30:31], s98, v85
	v_cndmask_b32_e64 v33, 0, v33, s[36:37]
	v_add_u32_e32 v86, 9, v84
	v_cmp_gt_u32_e64 s[36:37], s98, v86
	v_cndmask_b32_e64 v34, 0, v34, s[78:79]
	v_add_u32_e32 v87, 10, v84
	v_cmp_gt_u32_e64 s[78:79], s98, v87
	v_cndmask_b32_e64 v35, 0, v35, s[50:51]
	v_add_u32_e32 v88, 11, v84
	v_cmp_gt_u32_e64 s[50:51], s98, v88
	v_cndmask_b32_e64 v36, 0, v36, s[30:31]
	v_add_u32_e32 v85, 16, v84
	v_cmp_gt_u32_e64 s[30:31], s98, v85
	v_cndmask_b32_e64 v37, 0, v37, s[36:37]
	v_add_u32_e32 v86, 17, v84
	v_cmp_gt_u32_e64 s[36:37], s98, v86
	v_cndmask_b32_e64 v38, 0, v38, s[78:79]
	v_add_u32_e32 v87, 18, v84
	v_cmp_gt_u32_e64 s[78:79], s98, v87
	v_cndmask_b32_e64 v39, 0, v39, s[50:51]
	v_add_u32_e32 v88, 19, v84
	v_cmp_gt_u32_e64 s[50:51], s98, v88
	v_cndmask_b32_e64 v40, 0, v40, s[30:31]
	v_add_u32_e32 v85, 24, v84
	v_cmp_gt_u32_e64 s[30:31], s98, v85
	v_cndmask_b32_e64 v41, 0, v41, s[36:37]
	v_add_u32_e32 v86, 25, v84
	v_cmp_gt_u32_e64 s[36:37], s98, v86
	v_cndmask_b32_e64 v42, 0, v42, s[78:79]
	v_add_u32_e32 v87, 26, v84
	v_cmp_gt_u32_e64 s[78:79], s98, v87
	v_cndmask_b32_e64 v43, 0, v43, s[50:51]
	v_add_u32_e32 v88, 27, v84
	v_cmp_gt_u32_e64 s[50:51], s98, v88
	v_nop
	v_cndmask_b32_e64 v44, 0, v44, s[30:31]
	v_cndmask_b32_e64 v45, 0, v45, s[36:37]
	v_cndmask_b32_e64 v46, 0, v46, s[78:79]
	v_cndmask_b32_e64 v47, 0, v47, s[50:51]
	v_cvt_pk_bf16_f32 v64, v32, v33
	v_cvt_pk_bf16_f32 v65, v34, v35
	v_cvt_pk_bf16_f32 v66, v36, v37
	v_cvt_pk_bf16_f32 v67, v38, v39
	v_cvt_pk_bf16_f32 v68, v40, v41
	v_cvt_pk_bf16_f32 v69, v42, v43
	v_cvt_pk_bf16_f32 v70, v44, v45
	v_cvt_pk_bf16_f32 v71, v46, v47
	v_pk_add_f32 v[232:233], v[232:233], v[32:33]
	v_pk_add_f32 v[232:233], v[232:233], v[34:35]
	v_pk_add_f32 v[232:233], v[232:233], v[36:37]
	v_pk_add_f32 v[232:233], v[232:233], v[38:39]
	v_pk_add_f32 v[232:233], v[232:233], v[40:41]
	v_pk_add_f32 v[232:233], v[232:233], v[42:43]
	v_pk_add_f32 v[232:233], v[232:233], v[44:45]
	v_pk_add_f32 v[232:233], v[232:233], v[46:47]
	v_mov_b32_e32 v115, v229
	ds_read2_b32 v[32:33], v115 offset0:0 offset1:1
	ds_read2_b32 v[34:35], v115 offset0:2 offset1:3
	ds_read2_b32 v[36:37], v115 offset0:8 offset1:9
	ds_read2_b32 v[38:39], v115 offset0:10 offset1:11
	ds_read2_b32 v[40:41], v115 offset0:16 offset1:17
	ds_read2_b32 v[42:43], v115 offset0:18 offset1:19
	ds_read2_b32 v[44:45], v115 offset0:24 offset1:25
	ds_read2_b32 v[46:47], v115 offset0:26 offset1:27
	v_mfma_f32_32x32x16_bf16 v[0:15], v[64:67], v[72:75], v[0:15]
	v_mfma_f32_32x32x16_bf16 v[16:31], v[64:67], v[76:79], v[16:31]
	v_mfma_f32_32x32x16_bf16 v[0:15], v[68:71], v[220:223], v[0:15]
	v_mfma_f32_32x32x16_bf16 v[16:31], v[68:71], v[224:227], v[16:31]
	s_add_i32 s90, s76, -128
	v_add_u32_e32 v80, s90, v239
	v_add_u32_e32 v83, s90, v240
	v_add_u32_e32 v99, s90, v241
	v_add_u32_e32 v253, s90, v242
	v_add_u32_e32 v254, s90, v101
	v_add_u32_e32 v255, s90, v150
	v_med3_i32 v80, v80, 0, s99
	v_med3_i32 v83, v83, 0, s99
	v_med3_i32 v99, v99, 0, s99
	v_med3_i32 v253, v253, 0, s99
	v_med3_i32 v254, v254, 0, s99
	v_med3_i32 v255, v255, 0, s99
	v_mad_u32_u24 v80, v80, s100, v252
	v_mad_u32_u24 v83, v83, s100, v252
	v_mad_u32_u24 v99, v99, s100, v252
	v_mad_u32_u24 v253, v253, s100, v252
	v_mad_u32_u24 v254, v254, s100, v153
	v_mad_u32_u24 v255, v255, s100, v153
	global_load_dwordx4 v[156:159], v80, s[82:83]
	global_load_dwordx4 v[160:163], v83, s[82:83]
	global_load_dwordx4 v[164:167], v99, s[82:83]
	global_load_dwordx4 v[168:171], v253, s[82:83]
	global_load_dwordx4 v[172:175], v254, s[82:83] offset:768
	global_load_dwordx4 v[176:179], v255, s[82:83] offset:768
	global_load_dwordx4 v[180:183], v254, s[82:83] offset:832
	global_load_dwordx4 v[184:187], v255, s[82:83] offset:832
	ds_read_b64_tr_b16 v[72:73], v231
	ds_read_b64_tr_b16 v[74:75], v231 offset:512
	ds_read_b64_tr_b16 v[76:77], v231 offset:2048
	ds_read_b64_tr_b16 v[78:79], v231 offset:2560
	ds_read_b64_tr_b16 v[220:221], v231 offset:1024
	ds_read_b64_tr_b16 v[222:223], v231 offset:1536
	ds_read_b64_tr_b16 v[224:225], v231 offset:3072
	ds_read_b64_tr_b16 v[226:227], v231 offset:3584
	s_waitcnt vmcnt(8)
	ds_write_b128 v247, v[116:119]
	ds_write_b128 v247, v[120:123] offset:1024
	ds_write_b128 v247, v[124:127] offset:2048
	ds_write_b128 v247, v[128:131] offset:3072
	ds_read_b128 v[116:119], v248
	ds_read_b128 v[120:123], v249
	ds_read_b128 v[124:127], v250
	ds_read_b128 v[128:131], v251
	ds_write_b128 v112, v[132:135]
	ds_write_b128 v112, v[136:139] offset:1024
	ds_write_b128 v112, v[140:143] offset:2048
	ds_write_b128 v112, v[144:147] offset:3072
	s_waitcnt lgkmcnt(4)
	v_mfma_f32_32x32x16_bf16 v[32:47], v[116:119], v[48:51], v[32:47]
	v_exp_f32_e32 v188, v188
	v_exp_f32_e32 v189, v189
	v_exp_f32_e32 v190, v190
	v_exp_f32_e32 v191, v191
	v_mfma_f32_32x32x16_bf16 v[32:47], v[120:123], v[52:55], v[32:47]
	v_exp_f32_e32 v192, v192
	v_exp_f32_e32 v193, v193
	v_exp_f32_e32 v194, v194
	v_exp_f32_e32 v195, v195
	v_mfma_f32_32x32x16_bf16 v[32:47], v[124:127], v[56:59], v[32:47]
	v_exp_f32_e32 v196, v196
	v_exp_f32_e32 v197, v197
	v_exp_f32_e32 v198, v198
	v_exp_f32_e32 v199, v199
	v_mfma_f32_32x32x16_bf16 v[32:47], v[128:131], v[60:63], v[32:47]
	v_exp_f32_e32 v200, v200
	v_exp_f32_e32 v201, v201
	v_exp_f32_e32 v202, v202
	v_exp_f32_e32 v203, v203
	s_add_i32 s90, s76, 544
	v_add_u32_e32 v84, s90, v107
	v_add_u32_e32 v85, 0, v84
	v_add_u32_e32 v86, 1, v84
	v_add_u32_e32 v87, 2, v84
	v_add_u32_e32 v88, 3, v84
	v_cmp_gt_u32_e64 s[30:31], s98, v85
	v_cmp_gt_u32_e64 s[36:37], s98, v86
	v_cmp_gt_u32_e64 s[78:79], s98, v87
	v_cmp_gt_u32_e64 s[50:51], s98, v88
	v_cndmask_b32_e64 v188, 0, v188, s[30:31]
	v_add_u32_e32 v85, 8, v84
	v_cmp_gt_u32_e64 s[30:31], s98, v85
	v_cndmask_b32_e64 v189, 0, v189, s[36:37]
	v_add_u32_e32 v86, 9, v84
	v_cmp_gt_u32_e64 s[36:37], s98, v86
	v_cndmask_b32_e64 v190, 0, v190, s[78:79]
	v_add_u32_e32 v87, 10, v84
	v_cmp_gt_u32_e64 s[78:79], s98, v87
	v_cndmask_b32_e64 v191, 0, v191, s[50:51]
	v_add_u32_e32 v88, 11, v84
	v_cmp_gt_u32_e64 s[50:51], s98, v88
	v_cndmask_b32_e64 v192, 0, v192, s[30:31]
	v_add_u32_e32 v85, 16, v84
	v_cmp_gt_u32_e64 s[30:31], s98, v85
	v_cndmask_b32_e64 v193, 0, v193, s[36:37]
	v_add_u32_e32 v86, 17, v84
	v_cmp_gt_u32_e64 s[36:37], s98, v86
	v_cndmask_b32_e64 v194, 0, v194, s[78:79]
	v_add_u32_e32 v87, 18, v84
	v_cmp_gt_u32_e64 s[78:79], s98, v87
	v_cndmask_b32_e64 v195, 0, v195, s[50:51]
	v_add_u32_e32 v88, 19, v84
	v_cmp_gt_u32_e64 s[50:51], s98, v88
	v_cndmask_b32_e64 v196, 0, v196, s[30:31]
	v_add_u32_e32 v85, 24, v84
	v_cmp_gt_u32_e64 s[30:31], s98, v85
	v_cndmask_b32_e64 v197, 0, v197, s[36:37]
	v_add_u32_e32 v86, 25, v84
	v_cmp_gt_u32_e64 s[36:37], s98, v86
	v_cndmask_b32_e64 v198, 0, v198, s[78:79]
	v_add_u32_e32 v87, 26, v84
	v_cmp_gt_u32_e64 s[78:79], s98, v87
	v_cndmask_b32_e64 v199, 0, v199, s[50:51]
	v_add_u32_e32 v88, 27, v84
	v_cmp_gt_u32_e64 s[50:51], s98, v88
	v_nop
	v_cndmask_b32_e64 v200, 0, v200, s[30:31]
	v_cndmask_b32_e64 v201, 0, v201, s[36:37]
	v_cndmask_b32_e64 v202, 0, v202, s[78:79]
	v_cndmask_b32_e64 v203, 0, v203, s[50:51]
	v_cvt_pk_bf16_f32 v64, v188, v189
	v_cvt_pk_bf16_f32 v65, v190, v191
	v_cvt_pk_bf16_f32 v66, v192, v193
	v_cvt_pk_bf16_f32 v67, v194, v195
	v_cvt_pk_bf16_f32 v68, v196, v197
	v_cvt_pk_bf16_f32 v69, v198, v199
	v_cvt_pk_bf16_f32 v70, v200, v201
	v_cvt_pk_bf16_f32 v71, v202, v203
	v_pk_add_f32 v[232:233], v[232:233], v[188:189]
	v_pk_add_f32 v[232:233], v[232:233], v[190:191]
	v_pk_add_f32 v[232:233], v[232:233], v[192:193]
	v_pk_add_f32 v[232:233], v[232:233], v[194:195]
	v_pk_add_f32 v[232:233], v[232:233], v[196:197]
	v_pk_add_f32 v[232:233], v[232:233], v[198:199]
	v_pk_add_f32 v[232:233], v[232:233], v[200:201]
	v_pk_add_f32 v[232:233], v[232:233], v[202:203]
	ds_read2_b32 v[188:189], v115 offset0:32 offset1:33
	ds_read2_b32 v[190:191], v115 offset0:34 offset1:35
	ds_read2_b32 v[192:193], v115 offset0:40 offset1:41
	ds_read2_b32 v[194:195], v115 offset0:42 offset1:43
	ds_read2_b32 v[196:197], v115 offset0:48 offset1:49
	ds_read2_b32 v[198:199], v115 offset0:50 offset1:51
	ds_read2_b32 v[200:201], v115 offset0:56 offset1:57
	ds_read2_b32 v[202:203], v115 offset0:58 offset1:59
	v_mfma_f32_32x32x16_bf16 v[0:15], v[64:67], v[72:75], v[0:15]
	v_mfma_f32_32x32x16_bf16 v[16:31], v[64:67], v[76:79], v[16:31]
	v_mfma_f32_32x32x16_bf16 v[0:15], v[68:71], v[220:223], v[0:15]
	v_mfma_f32_32x32x16_bf16 v[16:31], v[68:71], v[224:227], v[16:31]
	s_add_i32 s90, s76, 0
	v_add_u32_e32 v80, s90, v239
	v_add_u32_e32 v83, s90, v240
	v_add_u32_e32 v99, s90, v241
	v_add_u32_e32 v253, s90, v242
	v_add_u32_e32 v254, s90, v101
	v_add_u32_e32 v255, s90, v150
	v_med3_i32 v80, v80, 0, s99
	v_med3_i32 v83, v83, 0, s99
	v_med3_i32 v99, v99, 0, s99
	v_med3_i32 v253, v253, 0, s99
	v_med3_i32 v254, v254, 0, s99
	v_med3_i32 v255, v255, 0, s99
	v_mad_u32_u24 v80, v80, s100, v252
	v_mad_u32_u24 v83, v83, s100, v252
	v_mad_u32_u24 v99, v99, s100, v252
	v_mad_u32_u24 v253, v253, s100, v252
	v_mad_u32_u24 v254, v254, s100, v153
	v_mad_u32_u24 v255, v255, s100, v153
	global_load_dwordx4 v[116:119], v80, s[82:83]
	global_load_dwordx4 v[120:123], v83, s[82:83]
	global_load_dwordx4 v[124:127], v99, s[82:83]
	global_load_dwordx4 v[128:131], v253, s[82:83]
	global_load_dwordx4 v[132:135], v254, s[82:83] offset:768
	global_load_dwordx4 v[136:139], v255, s[82:83] offset:768
	global_load_dwordx4 v[140:143], v254, s[82:83] offset:832
	global_load_dwordx4 v[144:147], v255, s[82:83] offset:832
	ds_read_b64_tr_b16 v[72:73], v231
	ds_read_b64_tr_b16 v[74:75], v231 offset:512
	ds_read_b64_tr_b16 v[76:77], v231 offset:2048
	ds_read_b64_tr_b16 v[78:79], v231 offset:2560
	ds_read_b64_tr_b16 v[220:221], v231 offset:1024
	ds_read_b64_tr_b16 v[222:223], v231 offset:1536
	ds_read_b64_tr_b16 v[224:225], v231 offset:3072
	ds_read_b64_tr_b16 v[226:227], v231 offset:3584
	s_waitcnt vmcnt(8)
	ds_write_b128 v247, v[156:159]
	ds_write_b128 v247, v[160:163] offset:1024
	ds_write_b128 v247, v[164:167] offset:2048
	ds_write_b128 v247, v[168:171] offset:3072
	ds_read_b128 v[156:159], v248
	ds_read_b128 v[160:163], v249
	ds_read_b128 v[164:167], v250
	ds_read_b128 v[168:171], v251
	ds_write_b128 v112, v[172:175]
	ds_write_b128 v112, v[176:179] offset:1024
	ds_write_b128 v112, v[180:183] offset:2048
	ds_write_b128 v112, v[184:187] offset:3072
	s_waitcnt lgkmcnt(4)
	v_mfma_f32_32x32x16_bf16 v[188:203], v[156:159], v[48:51], v[188:203]
	v_exp_f32_e32 v32, v32
	v_exp_f32_e32 v33, v33
	v_exp_f32_e32 v34, v34
	v_exp_f32_e32 v35, v35
	v_mfma_f32_32x32x16_bf16 v[188:203], v[160:163], v[52:55], v[188:203]
	v_exp_f32_e32 v36, v36
	v_exp_f32_e32 v37, v37
	v_exp_f32_e32 v38, v38
	v_exp_f32_e32 v39, v39
	v_mfma_f32_32x32x16_bf16 v[188:203], v[164:167], v[56:59], v[188:203]
	v_exp_f32_e32 v40, v40
	v_exp_f32_e32 v41, v41
	v_exp_f32_e32 v42, v42
	v_exp_f32_e32 v43, v43
	v_mfma_f32_32x32x16_bf16 v[188:203], v[168:171], v[60:63], v[188:203]
	v_exp_f32_e32 v44, v44
	v_exp_f32_e32 v45, v45
	v_exp_f32_e32 v46, v46
	v_exp_f32_e32 v47, v47
	s_add_i32 s90, s76, -256
	v_lshlrev_b32_e32 v84, 2, v107
	v_add_u32_e32 v84, s90, v84
	v_add_u32_e32 v85, 0, v84
	v_add_u32_e32 v86, 4, v84
	v_add_u32_e32 v87, 8, v84
	v_add_u32_e32 v88, 12, v84
	v_cmp_gt_u32_e64 s[30:31], s98, v85
	v_cmp_gt_u32_e64 s[36:37], s98, v86
	v_cmp_gt_u32_e64 s[78:79], s98, v87
	v_cmp_gt_u32_e64 s[50:51], s98, v88
	v_cndmask_b32_e64 v32, 0, v32, s[30:31]
	v_add_u32_e32 v85, 32, v84
	v_cmp_gt_u32_e64 s[30:31], s98, v85
	v_cndmask_b32_e64 v33, 0, v33, s[36:37]
	v_add_u32_e32 v86, 36, v84
	v_cmp_gt_u32_e64 s[36:37], s98, v86
	v_cndmask_b32_e64 v34, 0, v34, s[78:79]
	v_add_u32_e32 v87, 40, v84
	v_cmp_gt_u32_e64 s[78:79], s98, v87
	v_cndmask_b32_e64 v35, 0, v35, s[50:51]
	v_add_u32_e32 v88, 44, v84
	v_cmp_gt_u32_e64 s[50:51], s98, v88
	v_cndmask_b32_e64 v36, 0, v36, s[30:31]
	v_add_u32_e32 v85, 64, v84
	v_cmp_gt_u32_e64 s[30:31], s98, v85
	v_cndmask_b32_e64 v37, 0, v37, s[36:37]
	v_add_u32_e32 v86, 68, v84
	v_cmp_gt_u32_e64 s[36:37], s98, v86
	v_cndmask_b32_e64 v38, 0, v38, s[78:79]
	v_add_u32_e32 v87, 72, v84
	v_cmp_gt_u32_e64 s[78:79], s98, v87
	v_cndmask_b32_e64 v39, 0, v39, s[50:51]
	v_add_u32_e32 v88, 76, v84
	v_cmp_gt_u32_e64 s[50:51], s98, v88
	v_cndmask_b32_e64 v40, 0, v40, s[30:31]
	v_add_u32_e32 v85, 96, v84
	v_cmp_gt_u32_e64 s[30:31], s98, v85
	v_cndmask_b32_e64 v41, 0, v41, s[36:37]
	v_add_u32_e32 v86, 100, v84
	v_cmp_gt_u32_e64 s[36:37], s98, v86
	v_cndmask_b32_e64 v42, 0, v42, s[78:79]
	v_add_u32_e32 v87, 104, v84
	v_cmp_gt_u32_e64 s[78:79], s98, v87
	v_cndmask_b32_e64 v43, 0, v43, s[50:51]
	v_add_u32_e32 v88, 108, v84
	v_cmp_gt_u32_e64 s[50:51], s98, v88
	v_nop
	v_cndmask_b32_e64 v44, 0, v44, s[30:31]
	v_cndmask_b32_e64 v45, 0, v45, s[36:37]
	v_cndmask_b32_e64 v46, 0, v46, s[78:79]
	v_cndmask_b32_e64 v47, 0, v47, s[50:51]
	v_cvt_pk_bf16_f32 v64, v32, v33
	v_cvt_pk_bf16_f32 v65, v34, v35
	v_cvt_pk_bf16_f32 v66, v36, v37
	v_cvt_pk_bf16_f32 v67, v38, v39
	v_cvt_pk_bf16_f32 v68, v40, v41
	v_cvt_pk_bf16_f32 v69, v42, v43
	v_cvt_pk_bf16_f32 v70, v44, v45
	v_cvt_pk_bf16_f32 v71, v46, v47
	v_pk_add_f32 v[232:233], v[232:233], v[32:33]
	v_pk_add_f32 v[232:233], v[232:233], v[34:35]
	v_pk_add_f32 v[232:233], v[232:233], v[36:37]
	v_pk_add_f32 v[232:233], v[232:233], v[38:39]
	v_pk_add_f32 v[232:233], v[232:233], v[40:41]
	v_pk_add_f32 v[232:233], v[232:233], v[42:43]
	v_pk_add_f32 v[232:233], v[232:233], v[44:45]
	v_pk_add_f32 v[232:233], v[232:233], v[46:47]
	ds_read2_b32 v[32:33], v115 offset0:64 offset1:65
	ds_read2_b32 v[34:35], v115 offset0:66 offset1:67
	ds_read2_b32 v[36:37], v115 offset0:72 offset1:73
	ds_read2_b32 v[38:39], v115 offset0:74 offset1:75
	ds_read2_b32 v[40:41], v115 offset0:80 offset1:81
	ds_read2_b32 v[42:43], v115 offset0:82 offset1:83
	ds_read2_b32 v[44:45], v115 offset0:88 offset1:89
	ds_read2_b32 v[46:47], v115 offset0:90 offset1:91
	v_mfma_f32_32x32x16_bf16 v[0:15], v[64:67], v[72:75], v[0:15]
	v_mfma_f32_32x32x16_bf16 v[16:31], v[64:67], v[76:79], v[16:31]
	v_mfma_f32_32x32x16_bf16 v[0:15], v[68:71], v[220:223], v[0:15]
	v_mfma_f32_32x32x16_bf16 v[16:31], v[68:71], v[224:227], v[16:31]
	s_add_i32 s90, s76, 128
	v_add_u32_e32 v80, s90, v239
	v_add_u32_e32 v83, s90, v240
	v_add_u32_e32 v99, s90, v241
	v_add_u32_e32 v253, s90, v242
	v_add_u32_e32 v254, s90, v101
	v_add_u32_e32 v255, s90, v150
	v_med3_i32 v80, v80, 0, s99
	v_med3_i32 v83, v83, 0, s99
	v_med3_i32 v99, v99, 0, s99
	v_med3_i32 v253, v253, 0, s99
	v_med3_i32 v254, v254, 0, s99
	v_med3_i32 v255, v255, 0, s99
	v_mad_u32_u24 v80, v80, s100, v252
	v_mad_u32_u24 v83, v83, s100, v252
	v_mad_u32_u24 v99, v99, s100, v252
	v_mad_u32_u24 v253, v253, s100, v252
	v_mad_u32_u24 v254, v254, s100, v153
	v_mad_u32_u24 v255, v255, s100, v153
	global_load_dwordx4 v[156:159], v80, s[82:83]
	global_load_dwordx4 v[160:163], v83, s[82:83]
	global_load_dwordx4 v[164:167], v99, s[82:83]
	global_load_dwordx4 v[168:171], v253, s[82:83]
	global_load_dwordx4 v[172:175], v254, s[82:83] offset:768
	global_load_dwordx4 v[176:179], v255, s[82:83] offset:768
	global_load_dwordx4 v[180:183], v254, s[82:83] offset:832
	global_load_dwordx4 v[184:187], v255, s[82:83] offset:832
	ds_read_b64_tr_b16 v[72:73], v231
	ds_read_b64_tr_b16 v[74:75], v231 offset:512
	ds_read_b64_tr_b16 v[76:77], v231 offset:2048
	ds_read_b64_tr_b16 v[78:79], v231 offset:2560
	ds_read_b64_tr_b16 v[220:221], v231 offset:1024
	ds_read_b64_tr_b16 v[222:223], v231 offset:1536
	ds_read_b64_tr_b16 v[224:225], v231 offset:3072
	ds_read_b64_tr_b16 v[226:227], v231 offset:3584
	s_waitcnt vmcnt(8)
	ds_write_b128 v247, v[116:119]
	ds_write_b128 v247, v[120:123] offset:1024
	ds_write_b128 v247, v[124:127] offset:2048
	ds_write_b128 v247, v[128:131] offset:3072
	ds_read_b128 v[116:119], v248
	ds_read_b128 v[120:123], v249
	ds_read_b128 v[124:127], v250
	ds_read_b128 v[128:131], v251
	ds_write_b128 v112, v[132:135]
	ds_write_b128 v112, v[136:139] offset:1024
	ds_write_b128 v112, v[140:143] offset:2048
	ds_write_b128 v112, v[144:147] offset:3072
	s_waitcnt lgkmcnt(4)
	v_mfma_f32_32x32x16_bf16 v[32:47], v[116:119], v[48:51], v[32:47]
	v_exp_f32_e32 v188, v188
	v_exp_f32_e32 v189, v189
	v_exp_f32_e32 v190, v190
	v_exp_f32_e32 v191, v191
	v_mfma_f32_32x32x16_bf16 v[32:47], v[120:123], v[52:55], v[32:47]
	v_exp_f32_e32 v192, v192
	v_exp_f32_e32 v193, v193
	v_exp_f32_e32 v194, v194
	v_exp_f32_e32 v195, v195
	v_mfma_f32_32x32x16_bf16 v[32:47], v[124:127], v[56:59], v[32:47]
	v_exp_f32_e32 v196, v196
	v_exp_f32_e32 v197, v197
	v_exp_f32_e32 v198, v198
	v_exp_f32_e32 v199, v199
	v_mfma_f32_32x32x16_bf16 v[32:47], v[128:131], v[60:63], v[32:47]
	v_exp_f32_e32 v200, v200
	v_exp_f32_e32 v201, v201
	v_exp_f32_e32 v202, v202
	v_exp_f32_e32 v203, v203
	s_add_i32 s90, s76, -128
	v_lshlrev_b32_e32 v84, 2, v107
	v_add_u32_e32 v84, s90, v84
	v_add_u32_e32 v85, 0, v84
	v_add_u32_e32 v86, 4, v84
	v_add_u32_e32 v87, 8, v84
	v_add_u32_e32 v88, 12, v84
	v_cmp_gt_u32_e64 s[30:31], s98, v85
	v_cmp_gt_u32_e64 s[36:37], s98, v86
	v_cmp_gt_u32_e64 s[78:79], s98, v87
	v_cmp_gt_u32_e64 s[50:51], s98, v88
	v_cndmask_b32_e64 v188, 0, v188, s[30:31]
	v_add_u32_e32 v85, 32, v84
	v_cmp_gt_u32_e64 s[30:31], s98, v85
	v_cndmask_b32_e64 v189, 0, v189, s[36:37]
	v_add_u32_e32 v86, 36, v84
	v_cmp_gt_u32_e64 s[36:37], s98, v86
	v_cndmask_b32_e64 v190, 0, v190, s[78:79]
	v_add_u32_e32 v87, 40, v84
	v_cmp_gt_u32_e64 s[78:79], s98, v87
	v_cndmask_b32_e64 v191, 0, v191, s[50:51]
	v_add_u32_e32 v88, 44, v84
	v_cmp_gt_u32_e64 s[50:51], s98, v88
	v_cndmask_b32_e64 v192, 0, v192, s[30:31]
	v_add_u32_e32 v85, 64, v84
	v_cmp_gt_u32_e64 s[30:31], s98, v85
	v_cndmask_b32_e64 v193, 0, v193, s[36:37]
	v_add_u32_e32 v86, 68, v84
	v_cmp_gt_u32_e64 s[36:37], s98, v86
	v_cndmask_b32_e64 v194, 0, v194, s[78:79]
	v_add_u32_e32 v87, 72, v84
	v_cmp_gt_u32_e64 s[78:79], s98, v87
	v_cndmask_b32_e64 v195, 0, v195, s[50:51]
	v_add_u32_e32 v88, 76, v84
	v_cmp_gt_u32_e64 s[50:51], s98, v88
	v_cndmask_b32_e64 v196, 0, v196, s[30:31]
	v_add_u32_e32 v85, 96, v84
	v_cmp_gt_u32_e64 s[30:31], s98, v85
	v_cndmask_b32_e64 v197, 0, v197, s[36:37]
	v_add_u32_e32 v86, 100, v84
	v_cmp_gt_u32_e64 s[36:37], s98, v86
	v_cndmask_b32_e64 v198, 0, v198, s[78:79]
	v_add_u32_e32 v87, 104, v84
	v_cmp_gt_u32_e64 s[78:79], s98, v87
	v_cndmask_b32_e64 v199, 0, v199, s[50:51]
	v_add_u32_e32 v88, 108, v84
	v_cmp_gt_u32_e64 s[50:51], s98, v88
	v_nop
	v_cndmask_b32_e64 v200, 0, v200, s[30:31]
	v_cndmask_b32_e64 v201, 0, v201, s[36:37]
	v_cndmask_b32_e64 v202, 0, v202, s[78:79]
	v_cndmask_b32_e64 v203, 0, v203, s[50:51]
	v_cvt_pk_bf16_f32 v64, v188, v189
	v_cvt_pk_bf16_f32 v65, v190, v191
	v_cvt_pk_bf16_f32 v66, v192, v193
	v_cvt_pk_bf16_f32 v67, v194, v195
	v_cvt_pk_bf16_f32 v68, v196, v197
	v_cvt_pk_bf16_f32 v69, v198, v199
	v_cvt_pk_bf16_f32 v70, v200, v201
	v_cvt_pk_bf16_f32 v71, v202, v203
	v_pk_add_f32 v[232:233], v[232:233], v[188:189]
	v_pk_add_f32 v[232:233], v[232:233], v[190:191]
	v_pk_add_f32 v[232:233], v[232:233], v[192:193]
	v_pk_add_f32 v[232:233], v[232:233], v[194:195]
	v_pk_add_f32 v[232:233], v[232:233], v[196:197]
	v_pk_add_f32 v[232:233], v[232:233], v[198:199]
	v_pk_add_f32 v[232:233], v[232:233], v[200:201]
	v_pk_add_f32 v[232:233], v[232:233], v[202:203]
	ds_read2_b32 v[188:189], v115 offset0:96 offset1:97
	ds_read2_b32 v[190:191], v115 offset0:98 offset1:99
	ds_read2_b32 v[192:193], v115 offset0:104 offset1:105
	ds_read2_b32 v[194:195], v115 offset0:106 offset1:107
	ds_read2_b32 v[196:197], v115 offset0:112 offset1:113
	ds_read2_b32 v[198:199], v115 offset0:114 offset1:115
	ds_read2_b32 v[200:201], v115 offset0:120 offset1:121
	ds_read2_b32 v[202:203], v115 offset0:122 offset1:123
	v_mfma_f32_32x32x16_bf16 v[0:15], v[64:67], v[72:75], v[0:15]
	v_mfma_f32_32x32x16_bf16 v[16:31], v[64:67], v[76:79], v[16:31]
	v_mfma_f32_32x32x16_bf16 v[0:15], v[68:71], v[220:223], v[0:15]
	v_mfma_f32_32x32x16_bf16 v[16:31], v[68:71], v[224:227], v[16:31]
	s_add_i32 s90, s76, 256
	v_add_u32_e32 v80, s90, v239
	v_add_u32_e32 v83, s90, v240
	v_add_u32_e32 v99, s90, v241
	v_add_u32_e32 v253, s90, v242
	v_add_u32_e32 v254, s90, v101
	v_add_u32_e32 v255, s90, v150
	v_med3_i32 v80, v80, 0, s99
	v_med3_i32 v83, v83, 0, s99
	v_med3_i32 v99, v99, 0, s99
	v_med3_i32 v253, v253, 0, s99
	v_med3_i32 v254, v254, 0, s99
	v_med3_i32 v255, v255, 0, s99
	v_mad_u32_u24 v80, v80, s100, v252
	v_mad_u32_u24 v83, v83, s100, v252
	v_mad_u32_u24 v99, v99, s100, v252
	v_mad_u32_u24 v253, v253, s100, v252
	v_mad_u32_u24 v254, v254, s100, v153
	v_mad_u32_u24 v255, v255, s100, v153
	global_load_dwordx4 v[116:119], v80, s[82:83]
	global_load_dwordx4 v[120:123], v83, s[82:83]
	global_load_dwordx4 v[124:127], v99, s[82:83]
	global_load_dwordx4 v[128:131], v253, s[82:83]
	global_load_dwordx4 v[132:135], v254, s[82:83] offset:768
	global_load_dwordx4 v[136:139], v255, s[82:83] offset:768
	global_load_dwordx4 v[140:143], v254, s[82:83] offset:832
	global_load_dwordx4 v[144:147], v255, s[82:83] offset:832
	ds_read_b64_tr_b16 v[72:73], v231
	ds_read_b64_tr_b16 v[74:75], v231 offset:512
	ds_read_b64_tr_b16 v[76:77], v231 offset:2048
	ds_read_b64_tr_b16 v[78:79], v231 offset:2560
	ds_read_b64_tr_b16 v[220:221], v231 offset:1024
	ds_read_b64_tr_b16 v[222:223], v231 offset:1536
	ds_read_b64_tr_b16 v[224:225], v231 offset:3072
	ds_read_b64_tr_b16 v[226:227], v231 offset:3584
	s_waitcnt vmcnt(8)
	ds_write_b128 v247, v[156:159]
	ds_write_b128 v247, v[160:163] offset:1024
	ds_write_b128 v247, v[164:167] offset:2048
	ds_write_b128 v247, v[168:171] offset:3072
	ds_read_b128 v[156:159], v248
	ds_read_b128 v[160:163], v249
	ds_read_b128 v[164:167], v250
	ds_read_b128 v[168:171], v251
	ds_write_b128 v112, v[172:175]
	ds_write_b128 v112, v[176:179] offset:1024
	ds_write_b128 v112, v[180:183] offset:2048
	ds_write_b128 v112, v[184:187] offset:3072
	s_waitcnt lgkmcnt(4)
	v_mfma_f32_32x32x16_bf16 v[188:203], v[156:159], v[48:51], v[188:203]
	v_exp_f32_e32 v32, v32
	v_exp_f32_e32 v33, v33
	v_exp_f32_e32 v34, v34
	v_exp_f32_e32 v35, v35
	v_mfma_f32_32x32x16_bf16 v[188:203], v[160:163], v[52:55], v[188:203]
	v_exp_f32_e32 v36, v36
	v_exp_f32_e32 v37, v37
	v_exp_f32_e32 v38, v38
	v_exp_f32_e32 v39, v39
	v_mfma_f32_32x32x16_bf16 v[188:203], v[164:167], v[56:59], v[188:203]
	v_exp_f32_e32 v40, v40
	v_exp_f32_e32 v41, v41
	v_exp_f32_e32 v42, v42
	v_exp_f32_e32 v43, v43
	v_mfma_f32_32x32x16_bf16 v[188:203], v[168:171], v[60:63], v[188:203]
	v_exp_f32_e32 v44, v44
	v_exp_f32_e32 v45, v45
	v_exp_f32_e32 v46, v46
	v_exp_f32_e32 v47, v47
	s_add_i32 s90, s76, 0
	v_lshlrev_b32_e32 v84, 2, v107
	v_add_u32_e32 v84, s90, v84
	v_add_u32_e32 v85, 0, v84
	v_add_u32_e32 v86, 4, v84
	v_add_u32_e32 v87, 8, v84
	v_add_u32_e32 v88, 12, v84
	v_cmp_gt_u32_e64 s[30:31], s98, v85
	v_cmp_gt_u32_e64 s[36:37], s98, v86
	v_cmp_gt_u32_e64 s[78:79], s98, v87
	v_cmp_gt_u32_e64 s[50:51], s98, v88
	v_cndmask_b32_e64 v32, 0, v32, s[30:31]
	v_add_u32_e32 v85, 32, v84
	v_cmp_gt_u32_e64 s[30:31], s98, v85
	v_cndmask_b32_e64 v33, 0, v33, s[36:37]
	v_add_u32_e32 v86, 36, v84
	v_cmp_gt_u32_e64 s[36:37], s98, v86
	v_cndmask_b32_e64 v34, 0, v34, s[78:79]
	v_add_u32_e32 v87, 40, v84
	v_cmp_gt_u32_e64 s[78:79], s98, v87
	v_cndmask_b32_e64 v35, 0, v35, s[50:51]
	v_add_u32_e32 v88, 44, v84
	v_cmp_gt_u32_e64 s[50:51], s98, v88
	v_cndmask_b32_e64 v36, 0, v36, s[30:31]
	v_add_u32_e32 v85, 64, v84
	v_cmp_gt_u32_e64 s[30:31], s98, v85
	v_cndmask_b32_e64 v37, 0, v37, s[36:37]
	v_add_u32_e32 v86, 68, v84
	v_cmp_gt_u32_e64 s[36:37], s98, v86
	v_cndmask_b32_e64 v38, 0, v38, s[78:79]
	v_add_u32_e32 v87, 72, v84
	v_cmp_gt_u32_e64 s[78:79], s98, v87
	v_cndmask_b32_e64 v39, 0, v39, s[50:51]
	v_add_u32_e32 v88, 76, v84
	v_cmp_gt_u32_e64 s[50:51], s98, v88
	v_cndmask_b32_e64 v40, 0, v40, s[30:31]
	v_add_u32_e32 v85, 96, v84
	v_cmp_gt_u32_e64 s[30:31], s98, v85
	v_cndmask_b32_e64 v41, 0, v41, s[36:37]
	v_add_u32_e32 v86, 100, v84
	v_cmp_gt_u32_e64 s[36:37], s98, v86
	v_cndmask_b32_e64 v42, 0, v42, s[78:79]
	v_add_u32_e32 v87, 104, v84
	v_cmp_gt_u32_e64 s[78:79], s98, v87
	v_cndmask_b32_e64 v43, 0, v43, s[50:51]
	v_add_u32_e32 v88, 108, v84
	v_cmp_gt_u32_e64 s[50:51], s98, v88
	v_nop
	v_cndmask_b32_e64 v44, 0, v44, s[30:31]
	v_cndmask_b32_e64 v45, 0, v45, s[36:37]
	v_cndmask_b32_e64 v46, 0, v46, s[78:79]
	v_cndmask_b32_e64 v47, 0, v47, s[50:51]
	v_cvt_pk_bf16_f32 v64, v32, v33
	v_cvt_pk_bf16_f32 v65, v34, v35
	v_cvt_pk_bf16_f32 v66, v36, v37
	v_cvt_pk_bf16_f32 v67, v38, v39
	v_cvt_pk_bf16_f32 v68, v40, v41
	v_cvt_pk_bf16_f32 v69, v42, v43
	v_cvt_pk_bf16_f32 v70, v44, v45
	v_cvt_pk_bf16_f32 v71, v46, v47
	v_pk_add_f32 v[232:233], v[232:233], v[32:33]
	v_pk_add_f32 v[232:233], v[232:233], v[34:35]
	v_pk_add_f32 v[232:233], v[232:233], v[36:37]
	v_pk_add_f32 v[232:233], v[232:233], v[38:39]
	v_pk_add_f32 v[232:233], v[232:233], v[40:41]
	v_pk_add_f32 v[232:233], v[232:233], v[42:43]
	v_pk_add_f32 v[232:233], v[232:233], v[44:45]
	v_pk_add_f32 v[232:233], v[232:233], v[46:47]
	ds_read2_b32 v[32:33], v115 offset0:128 offset1:129
	ds_read2_b32 v[34:35], v115 offset0:130 offset1:131
	ds_read2_b32 v[36:37], v115 offset0:136 offset1:137
	ds_read2_b32 v[38:39], v115 offset0:138 offset1:139
	ds_read2_b32 v[40:41], v115 offset0:144 offset1:145
	ds_read2_b32 v[42:43], v115 offset0:146 offset1:147
	ds_read2_b32 v[44:45], v115 offset0:152 offset1:153
	ds_read2_b32 v[46:47], v115 offset0:154 offset1:155
	v_mfma_f32_32x32x16_bf16 v[0:15], v[64:67], v[72:75], v[0:15]
	v_mfma_f32_32x32x16_bf16 v[16:31], v[64:67], v[76:79], v[16:31]
	v_mfma_f32_32x32x16_bf16 v[0:15], v[68:71], v[220:223], v[0:15]
	v_mfma_f32_32x32x16_bf16 v[16:31], v[68:71], v[224:227], v[16:31]
	s_add_i32 s90, s76, 384
	v_add_u32_e32 v80, s90, v239
	v_add_u32_e32 v83, s90, v240
	v_add_u32_e32 v99, s90, v241
	v_add_u32_e32 v253, s90, v242
	v_add_u32_e32 v254, s90, v101
	v_add_u32_e32 v255, s90, v150
	v_med3_i32 v80, v80, 0, s99
	v_med3_i32 v83, v83, 0, s99
	v_med3_i32 v99, v99, 0, s99
	v_med3_i32 v253, v253, 0, s99
	v_med3_i32 v254, v254, 0, s99
	v_med3_i32 v255, v255, 0, s99
	v_mad_u32_u24 v80, v80, s100, v252
	v_mad_u32_u24 v83, v83, s100, v252
	v_mad_u32_u24 v99, v99, s100, v252
	v_mad_u32_u24 v253, v253, s100, v252
	v_mad_u32_u24 v254, v254, s100, v153
	v_mad_u32_u24 v255, v255, s100, v153
	global_load_dwordx4 v[156:159], v80, s[82:83]
	global_load_dwordx4 v[160:163], v83, s[82:83]
	global_load_dwordx4 v[164:167], v99, s[82:83]
	global_load_dwordx4 v[168:171], v253, s[82:83]
	global_load_dwordx4 v[172:175], v254, s[82:83] offset:768
	global_load_dwordx4 v[176:179], v255, s[82:83] offset:768
	global_load_dwordx4 v[180:183], v254, s[82:83] offset:832
	global_load_dwordx4 v[184:187], v255, s[82:83] offset:832
	ds_read_b64_tr_b16 v[72:73], v231
	ds_read_b64_tr_b16 v[74:75], v231 offset:512
	ds_read_b64_tr_b16 v[76:77], v231 offset:2048
	ds_read_b64_tr_b16 v[78:79], v231 offset:2560
	ds_read_b64_tr_b16 v[220:221], v231 offset:1024
	ds_read_b64_tr_b16 v[222:223], v231 offset:1536
	ds_read_b64_tr_b16 v[224:225], v231 offset:3072
	ds_read_b64_tr_b16 v[226:227], v231 offset:3584
	s_waitcnt vmcnt(8)
	ds_write_b128 v247, v[116:119]
	ds_write_b128 v247, v[120:123] offset:1024
	ds_write_b128 v247, v[124:127] offset:2048
	ds_write_b128 v247, v[128:131] offset:3072
	ds_read_b128 v[116:119], v248
	ds_read_b128 v[120:123], v249
	ds_read_b128 v[124:127], v250
	ds_read_b128 v[128:131], v251
	ds_write_b128 v112, v[132:135]
	ds_write_b128 v112, v[136:139] offset:1024
	ds_write_b128 v112, v[140:143] offset:2048
	ds_write_b128 v112, v[144:147] offset:3072
	s_waitcnt lgkmcnt(4)
	v_mfma_f32_32x32x16_bf16 v[32:47], v[116:119], v[48:51], v[32:47]
	v_exp_f32_e32 v188, v188
	v_exp_f32_e32 v189, v189
	v_exp_f32_e32 v190, v190
	v_exp_f32_e32 v191, v191
	v_mfma_f32_32x32x16_bf16 v[32:47], v[120:123], v[52:55], v[32:47]
	v_exp_f32_e32 v192, v192
	v_exp_f32_e32 v193, v193
	v_exp_f32_e32 v194, v194
	v_exp_f32_e32 v195, v195
	v_mfma_f32_32x32x16_bf16 v[32:47], v[124:127], v[56:59], v[32:47]
	v_exp_f32_e32 v196, v196
	v_exp_f32_e32 v197, v197
	v_exp_f32_e32 v198, v198
	v_exp_f32_e32 v199, v199
	v_mfma_f32_32x32x16_bf16 v[32:47], v[128:131], v[60:63], v[32:47]
	v_exp_f32_e32 v200, v200
	v_exp_f32_e32 v201, v201
	v_exp_f32_e32 v202, v202
	v_exp_f32_e32 v203, v203
	s_add_i32 s90, s76, 128
	v_lshlrev_b32_e32 v84, 2, v107
	v_add_u32_e32 v84, s90, v84
	v_add_u32_e32 v85, 0, v84
	v_add_u32_e32 v86, 4, v84
	v_add_u32_e32 v87, 8, v84
	v_add_u32_e32 v88, 12, v84
	v_cmp_gt_u32_e64 s[30:31], s98, v85
	v_cmp_gt_u32_e64 s[36:37], s98, v86
	v_cmp_gt_u32_e64 s[78:79], s98, v87
	v_cmp_gt_u32_e64 s[50:51], s98, v88
	v_cndmask_b32_e64 v188, 0, v188, s[30:31]
	v_add_u32_e32 v85, 32, v84
	v_cmp_gt_u32_e64 s[30:31], s98, v85
	v_cndmask_b32_e64 v189, 0, v189, s[36:37]
	v_add_u32_e32 v86, 36, v84
	v_cmp_gt_u32_e64 s[36:37], s98, v86
	v_cndmask_b32_e64 v190, 0, v190, s[78:79]
	v_add_u32_e32 v87, 40, v84
	v_cmp_gt_u32_e64 s[78:79], s98, v87
	v_cndmask_b32_e64 v191, 0, v191, s[50:51]
	v_add_u32_e32 v88, 44, v84
	v_cmp_gt_u32_e64 s[50:51], s98, v88
	v_cndmask_b32_e64 v192, 0, v192, s[30:31]
	v_add_u32_e32 v85, 64, v84
	v_cmp_gt_u32_e64 s[30:31], s98, v85
	v_cndmask_b32_e64 v193, 0, v193, s[36:37]
	v_add_u32_e32 v86, 68, v84
	v_cmp_gt_u32_e64 s[36:37], s98, v86
	v_cndmask_b32_e64 v194, 0, v194, s[78:79]
	v_add_u32_e32 v87, 72, v84
	v_cmp_gt_u32_e64 s[78:79], s98, v87
	v_cndmask_b32_e64 v195, 0, v195, s[50:51]
	v_add_u32_e32 v88, 76, v84
	v_cmp_gt_u32_e64 s[50:51], s98, v88
	v_cndmask_b32_e64 v196, 0, v196, s[30:31]
	v_add_u32_e32 v85, 96, v84
	v_cmp_gt_u32_e64 s[30:31], s98, v85
	v_cndmask_b32_e64 v197, 0, v197, s[36:37]
	v_add_u32_e32 v86, 100, v84
	v_cmp_gt_u32_e64 s[36:37], s98, v86
	v_cndmask_b32_e64 v198, 0, v198, s[78:79]
	v_add_u32_e32 v87, 104, v84
	v_cmp_gt_u32_e64 s[78:79], s98, v87
	v_cndmask_b32_e64 v199, 0, v199, s[50:51]
	v_add_u32_e32 v88, 108, v84
	v_cmp_gt_u32_e64 s[50:51], s98, v88
	v_nop
	v_cndmask_b32_e64 v200, 0, v200, s[30:31]
	v_cndmask_b32_e64 v201, 0, v201, s[36:37]
	v_cndmask_b32_e64 v202, 0, v202, s[78:79]
	v_cndmask_b32_e64 v203, 0, v203, s[50:51]
	v_cvt_pk_bf16_f32 v64, v188, v189
	v_cvt_pk_bf16_f32 v65, v190, v191
	v_cvt_pk_bf16_f32 v66, v192, v193
	v_cvt_pk_bf16_f32 v67, v194, v195
	v_cvt_pk_bf16_f32 v68, v196, v197
	v_cvt_pk_bf16_f32 v69, v198, v199
	v_cvt_pk_bf16_f32 v70, v200, v201
	v_cvt_pk_bf16_f32 v71, v202, v203
	v_pk_add_f32 v[232:233], v[232:233], v[188:189]
	v_pk_add_f32 v[232:233], v[232:233], v[190:191]
	v_pk_add_f32 v[232:233], v[232:233], v[192:193]
	v_pk_add_f32 v[232:233], v[232:233], v[194:195]
	v_pk_add_f32 v[232:233], v[232:233], v[196:197]
	v_pk_add_f32 v[232:233], v[232:233], v[198:199]
	v_pk_add_f32 v[232:233], v[232:233], v[200:201]
	v_pk_add_f32 v[232:233], v[232:233], v[202:203]
	ds_read2_b32 v[188:189], v115 offset0:160 offset1:161
	ds_read2_b32 v[190:191], v115 offset0:162 offset1:163
	ds_read2_b32 v[192:193], v115 offset0:168 offset1:169
	ds_read2_b32 v[194:195], v115 offset0:170 offset1:171
	ds_read2_b32 v[196:197], v115 offset0:176 offset1:177
	ds_read2_b32 v[198:199], v115 offset0:178 offset1:179
	ds_read2_b32 v[200:201], v115 offset0:184 offset1:185
	ds_read2_b32 v[202:203], v115 offset0:186 offset1:187
	v_mfma_f32_32x32x16_bf16 v[0:15], v[64:67], v[72:75], v[0:15]
	v_mfma_f32_32x32x16_bf16 v[16:31], v[64:67], v[76:79], v[16:31]
	v_mfma_f32_32x32x16_bf16 v[0:15], v[68:71], v[220:223], v[0:15]
	v_mfma_f32_32x32x16_bf16 v[16:31], v[68:71], v[224:227], v[16:31]
	s_add_i32 s90, s76, 512
	v_add_u32_e32 v80, s90, v239
	v_add_u32_e32 v83, s90, v240
	v_add_u32_e32 v99, s90, v241
	v_add_u32_e32 v253, s90, v242
	v_add_u32_e32 v254, s90, v101
	v_add_u32_e32 v255, s90, v150
	v_med3_i32 v80, v80, 0, s99
	v_med3_i32 v83, v83, 0, s99
	v_med3_i32 v99, v99, 0, s99
	v_med3_i32 v253, v253, 0, s99
	v_med3_i32 v254, v254, 0, s99
	v_med3_i32 v255, v255, 0, s99
	v_mad_u32_u24 v80, v80, s100, v252
	v_mad_u32_u24 v83, v83, s100, v252
	v_mad_u32_u24 v99, v99, s100, v252
	v_mad_u32_u24 v253, v253, s100, v252
	v_mad_u32_u24 v254, v254, s100, v153
	v_mad_u32_u24 v255, v255, s100, v153
	global_load_dwordx4 v[116:119], v80, s[82:83]
	global_load_dwordx4 v[120:123], v83, s[82:83]
	global_load_dwordx4 v[124:127], v99, s[82:83]
	global_load_dwordx4 v[128:131], v253, s[82:83]
	global_load_dwordx4 v[132:135], v254, s[82:83] offset:768
	global_load_dwordx4 v[136:139], v255, s[82:83] offset:768
	global_load_dwordx4 v[140:143], v254, s[82:83] offset:832
	global_load_dwordx4 v[144:147], v255, s[82:83] offset:832
	ds_read_b64_tr_b16 v[72:73], v231
	ds_read_b64_tr_b16 v[74:75], v231 offset:512
	ds_read_b64_tr_b16 v[76:77], v231 offset:2048
	ds_read_b64_tr_b16 v[78:79], v231 offset:2560
	ds_read_b64_tr_b16 v[220:221], v231 offset:1024
	ds_read_b64_tr_b16 v[222:223], v231 offset:1536
	ds_read_b64_tr_b16 v[224:225], v231 offset:3072
	ds_read_b64_tr_b16 v[226:227], v231 offset:3584
	s_waitcnt vmcnt(8)
	ds_write_b128 v247, v[156:159]
	ds_write_b128 v247, v[160:163] offset:1024
	ds_write_b128 v247, v[164:167] offset:2048
	ds_write_b128 v247, v[168:171] offset:3072
	ds_read_b128 v[156:159], v248
	ds_read_b128 v[160:163], v249
	ds_read_b128 v[164:167], v250
	ds_read_b128 v[168:171], v251
	ds_write_b128 v112, v[172:175]
	ds_write_b128 v112, v[176:179] offset:1024
	ds_write_b128 v112, v[180:183] offset:2048
	ds_write_b128 v112, v[184:187] offset:3072
	s_waitcnt lgkmcnt(4)
	v_mfma_f32_32x32x16_bf16 v[188:203], v[156:159], v[48:51], v[188:203]
	v_exp_f32_e32 v32, v32
	v_exp_f32_e32 v33, v33
	v_exp_f32_e32 v34, v34
	v_exp_f32_e32 v35, v35
	v_mfma_f32_32x32x16_bf16 v[188:203], v[160:163], v[52:55], v[188:203]
	v_exp_f32_e32 v36, v36
	v_exp_f32_e32 v37, v37
	v_exp_f32_e32 v38, v38
	v_exp_f32_e32 v39, v39
	v_mfma_f32_32x32x16_bf16 v[188:203], v[164:167], v[56:59], v[188:203]
	v_exp_f32_e32 v40, v40
	v_exp_f32_e32 v41, v41
	v_exp_f32_e32 v42, v42
	v_exp_f32_e32 v43, v43
	v_mfma_f32_32x32x16_bf16 v[188:203], v[168:171], v[60:63], v[188:203]
	v_exp_f32_e32 v44, v44
	v_exp_f32_e32 v45, v45
	v_exp_f32_e32 v46, v46
	v_exp_f32_e32 v47, v47
	s_add_i32 s90, s76, 256
	v_lshlrev_b32_e32 v84, 2, v107
	v_add_u32_e32 v84, s90, v84
	v_add_u32_e32 v85, 0, v84
	v_add_u32_e32 v86, 4, v84
	v_add_u32_e32 v87, 8, v84
	v_add_u32_e32 v88, 12, v84
	v_cmp_gt_u32_e64 s[30:31], s98, v85
	v_cmp_gt_u32_e64 s[36:37], s98, v86
	v_cmp_gt_u32_e64 s[78:79], s98, v87
	v_cmp_gt_u32_e64 s[50:51], s98, v88
	v_cndmask_b32_e64 v32, 0, v32, s[30:31]
	v_add_u32_e32 v85, 32, v84
	v_cmp_gt_u32_e64 s[30:31], s98, v85
	v_cndmask_b32_e64 v33, 0, v33, s[36:37]
	v_add_u32_e32 v86, 36, v84
	v_cmp_gt_u32_e64 s[36:37], s98, v86
	v_cndmask_b32_e64 v34, 0, v34, s[78:79]
	v_add_u32_e32 v87, 40, v84
	v_cmp_gt_u32_e64 s[78:79], s98, v87
	v_cndmask_b32_e64 v35, 0, v35, s[50:51]
	v_add_u32_e32 v88, 44, v84
	v_cmp_gt_u32_e64 s[50:51], s98, v88
	v_cndmask_b32_e64 v36, 0, v36, s[30:31]
	v_add_u32_e32 v85, 64, v84
	v_cmp_gt_u32_e64 s[30:31], s98, v85
	v_cndmask_b32_e64 v37, 0, v37, s[36:37]
	v_add_u32_e32 v86, 68, v84
	v_cmp_gt_u32_e64 s[36:37], s98, v86
	v_cndmask_b32_e64 v38, 0, v38, s[78:79]
	v_add_u32_e32 v87, 72, v84
	v_cmp_gt_u32_e64 s[78:79], s98, v87
	v_cndmask_b32_e64 v39, 0, v39, s[50:51]
	v_add_u32_e32 v88, 76, v84
	v_cmp_gt_u32_e64 s[50:51], s98, v88
	v_cndmask_b32_e64 v40, 0, v40, s[30:31]
	v_add_u32_e32 v85, 96, v84
	v_cmp_gt_u32_e64 s[30:31], s98, v85
	v_cndmask_b32_e64 v41, 0, v41, s[36:37]
	v_add_u32_e32 v86, 100, v84
	v_cmp_gt_u32_e64 s[36:37], s98, v86
	v_cndmask_b32_e64 v42, 0, v42, s[78:79]
	v_add_u32_e32 v87, 104, v84
	v_cmp_gt_u32_e64 s[78:79], s98, v87
	v_cndmask_b32_e64 v43, 0, v43, s[50:51]
	v_add_u32_e32 v88, 108, v84
	v_cmp_gt_u32_e64 s[50:51], s98, v88
	v_nop
	v_cndmask_b32_e64 v44, 0, v44, s[30:31]
	v_cndmask_b32_e64 v45, 0, v45, s[36:37]
	v_cndmask_b32_e64 v46, 0, v46, s[78:79]
	v_cndmask_b32_e64 v47, 0, v47, s[50:51]
	v_cvt_pk_bf16_f32 v64, v32, v33
	v_cvt_pk_bf16_f32 v65, v34, v35
	v_cvt_pk_bf16_f32 v66, v36, v37
	v_cvt_pk_bf16_f32 v67, v38, v39
	v_cvt_pk_bf16_f32 v68, v40, v41
	v_cvt_pk_bf16_f32 v69, v42, v43
	v_cvt_pk_bf16_f32 v70, v44, v45
	v_cvt_pk_bf16_f32 v71, v46, v47
	v_pk_add_f32 v[232:233], v[232:233], v[32:33]
	v_pk_add_f32 v[232:233], v[232:233], v[34:35]
	v_pk_add_f32 v[232:233], v[232:233], v[36:37]
	v_pk_add_f32 v[232:233], v[232:233], v[38:39]
	v_pk_add_f32 v[232:233], v[232:233], v[40:41]
	v_pk_add_f32 v[232:233], v[232:233], v[42:43]
	v_pk_add_f32 v[232:233], v[232:233], v[44:45]
	v_pk_add_f32 v[232:233], v[232:233], v[46:47]
	ds_read2_b32 v[32:33], v115 offset0:192 offset1:193
	ds_read2_b32 v[34:35], v115 offset0:194 offset1:195
	ds_read2_b32 v[36:37], v115 offset0:200 offset1:201
	ds_read2_b32 v[38:39], v115 offset0:202 offset1:203
	ds_read2_b32 v[40:41], v115 offset0:208 offset1:209
	ds_read2_b32 v[42:43], v115 offset0:210 offset1:211
	ds_read2_b32 v[44:45], v115 offset0:216 offset1:217
	ds_read2_b32 v[46:47], v115 offset0:218 offset1:219
	v_mfma_f32_32x32x16_bf16 v[0:15], v[64:67], v[72:75], v[0:15]
	v_mfma_f32_32x32x16_bf16 v[16:31], v[64:67], v[76:79], v[16:31]
	v_mfma_f32_32x32x16_bf16 v[0:15], v[68:71], v[220:223], v[0:15]
	v_mfma_f32_32x32x16_bf16 v[16:31], v[68:71], v[224:227], v[16:31]
	s_add_i32 s90, s76, 640
	v_add_u32_e32 v80, s90, v239
	v_add_u32_e32 v83, s90, v240
	v_add_u32_e32 v99, s90, v241
	v_add_u32_e32 v253, s90, v242
	v_add_u32_e32 v254, s90, v101
	v_add_u32_e32 v255, s90, v150
	v_med3_i32 v80, v80, 0, s99
	v_med3_i32 v83, v83, 0, s99
	v_med3_i32 v99, v99, 0, s99
	v_med3_i32 v253, v253, 0, s99
	v_med3_i32 v254, v254, 0, s99
	v_med3_i32 v255, v255, 0, s99
	v_mad_u32_u24 v80, v80, s100, v252
	v_mad_u32_u24 v83, v83, s100, v252
	v_mad_u32_u24 v99, v99, s100, v252
	v_mad_u32_u24 v253, v253, s100, v252
	v_mad_u32_u24 v254, v254, s100, v153
	v_mad_u32_u24 v255, v255, s100, v153
	global_load_dwordx4 v[156:159], v80, s[82:83]
	global_load_dwordx4 v[160:163], v83, s[82:83]
	global_load_dwordx4 v[164:167], v99, s[82:83]
	global_load_dwordx4 v[168:171], v253, s[82:83]
	global_load_dwordx4 v[172:175], v254, s[82:83] offset:768
	global_load_dwordx4 v[176:179], v255, s[82:83] offset:768
	global_load_dwordx4 v[180:183], v254, s[82:83] offset:832
	global_load_dwordx4 v[184:187], v255, s[82:83] offset:832
	ds_read_b64_tr_b16 v[72:73], v231
	ds_read_b64_tr_b16 v[74:75], v231 offset:512
	ds_read_b64_tr_b16 v[76:77], v231 offset:2048
	ds_read_b64_tr_b16 v[78:79], v231 offset:2560
	ds_read_b64_tr_b16 v[220:221], v231 offset:1024
	ds_read_b64_tr_b16 v[222:223], v231 offset:1536
	ds_read_b64_tr_b16 v[224:225], v231 offset:3072
	ds_read_b64_tr_b16 v[226:227], v231 offset:3584
	s_waitcnt vmcnt(8)
	ds_write_b128 v247, v[116:119]
	ds_write_b128 v247, v[120:123] offset:1024
	ds_write_b128 v247, v[124:127] offset:2048
	ds_write_b128 v247, v[128:131] offset:3072
	ds_read_b128 v[116:119], v248
	ds_read_b128 v[120:123], v249
	ds_read_b128 v[124:127], v250
	ds_read_b128 v[128:131], v251
	ds_write_b128 v112, v[132:135]
	ds_write_b128 v112, v[136:139] offset:1024
	ds_write_b128 v112, v[140:143] offset:2048
	ds_write_b128 v112, v[144:147] offset:3072
	s_waitcnt lgkmcnt(4)
	v_mfma_f32_32x32x16_bf16 v[32:47], v[116:119], v[48:51], v[32:47]
	v_exp_f32_e32 v188, v188
	v_exp_f32_e32 v189, v189
	v_exp_f32_e32 v190, v190
	v_exp_f32_e32 v191, v191
	v_mfma_f32_32x32x16_bf16 v[32:47], v[120:123], v[52:55], v[32:47]
	v_exp_f32_e32 v192, v192
	v_exp_f32_e32 v193, v193
	v_exp_f32_e32 v194, v194
	v_exp_f32_e32 v195, v195
	v_mfma_f32_32x32x16_bf16 v[32:47], v[124:127], v[56:59], v[32:47]
	v_exp_f32_e32 v196, v196
	v_exp_f32_e32 v197, v197
	v_exp_f32_e32 v198, v198
	v_exp_f32_e32 v199, v199
	v_mfma_f32_32x32x16_bf16 v[32:47], v[128:131], v[60:63], v[32:47]
	v_exp_f32_e32 v200, v200
	v_exp_f32_e32 v201, v201
	v_exp_f32_e32 v202, v202
	v_exp_f32_e32 v203, v203
	s_add_i32 s90, s76, 384
	v_lshlrev_b32_e32 v84, 2, v107
	v_add_u32_e32 v84, s90, v84
	v_add_u32_e32 v85, 0, v84
	v_add_u32_e32 v86, 4, v84
	v_add_u32_e32 v87, 8, v84
	v_add_u32_e32 v88, 12, v84
	v_cmp_gt_u32_e64 s[30:31], s98, v85
	v_cmp_gt_u32_e64 s[36:37], s98, v86
	v_cmp_gt_u32_e64 s[78:79], s98, v87
	v_cmp_gt_u32_e64 s[50:51], s98, v88
	v_cndmask_b32_e64 v188, 0, v188, s[30:31]
	v_add_u32_e32 v85, 32, v84
	v_cmp_gt_u32_e64 s[30:31], s98, v85
	v_cndmask_b32_e64 v189, 0, v189, s[36:37]
	v_add_u32_e32 v86, 36, v84
	v_cmp_gt_u32_e64 s[36:37], s98, v86
	v_cndmask_b32_e64 v190, 0, v190, s[78:79]
	v_add_u32_e32 v87, 40, v84
	v_cmp_gt_u32_e64 s[78:79], s98, v87
	v_cndmask_b32_e64 v191, 0, v191, s[50:51]
	v_add_u32_e32 v88, 44, v84
	v_cmp_gt_u32_e64 s[50:51], s98, v88
	v_cndmask_b32_e64 v192, 0, v192, s[30:31]
	v_add_u32_e32 v85, 64, v84
	v_cmp_gt_u32_e64 s[30:31], s98, v85
	v_cndmask_b32_e64 v193, 0, v193, s[36:37]
	v_add_u32_e32 v86, 68, v84
	v_cmp_gt_u32_e64 s[36:37], s98, v86
	v_cndmask_b32_e64 v194, 0, v194, s[78:79]
	v_add_u32_e32 v87, 72, v84
	v_cmp_gt_u32_e64 s[78:79], s98, v87
	v_cndmask_b32_e64 v195, 0, v195, s[50:51]
	v_add_u32_e32 v88, 76, v84
	v_cmp_gt_u32_e64 s[50:51], s98, v88
	v_cndmask_b32_e64 v196, 0, v196, s[30:31]
	v_add_u32_e32 v85, 96, v84
	v_cmp_gt_u32_e64 s[30:31], s98, v85
	v_cndmask_b32_e64 v197, 0, v197, s[36:37]
	v_add_u32_e32 v86, 100, v84
	v_cmp_gt_u32_e64 s[36:37], s98, v86
	v_cndmask_b32_e64 v198, 0, v198, s[78:79]
	v_add_u32_e32 v87, 104, v84
	v_cmp_gt_u32_e64 s[78:79], s98, v87
	v_cndmask_b32_e64 v199, 0, v199, s[50:51]
	v_add_u32_e32 v88, 108, v84
	v_cmp_gt_u32_e64 s[50:51], s98, v88
	v_nop
	v_cndmask_b32_e64 v200, 0, v200, s[30:31]
	v_cndmask_b32_e64 v201, 0, v201, s[36:37]
	v_cndmask_b32_e64 v202, 0, v202, s[78:79]
	v_cndmask_b32_e64 v203, 0, v203, s[50:51]
	v_cvt_pk_bf16_f32 v64, v188, v189
	v_cvt_pk_bf16_f32 v65, v190, v191
	v_cvt_pk_bf16_f32 v66, v192, v193
	v_cvt_pk_bf16_f32 v67, v194, v195
	v_cvt_pk_bf16_f32 v68, v196, v197
	v_cvt_pk_bf16_f32 v69, v198, v199
	v_cvt_pk_bf16_f32 v70, v200, v201
	v_cvt_pk_bf16_f32 v71, v202, v203
	v_pk_add_f32 v[232:233], v[232:233], v[188:189]
	v_pk_add_f32 v[232:233], v[232:233], v[190:191]
	v_pk_add_f32 v[232:233], v[232:233], v[192:193]
	v_pk_add_f32 v[232:233], v[232:233], v[194:195]
	v_pk_add_f32 v[232:233], v[232:233], v[196:197]
	v_pk_add_f32 v[232:233], v[232:233], v[198:199]
	v_pk_add_f32 v[232:233], v[232:233], v[200:201]
	v_pk_add_f32 v[232:233], v[232:233], v[202:203]
	ds_read2_b32 v[188:189], v115 offset0:224 offset1:225
	ds_read2_b32 v[190:191], v115 offset0:226 offset1:227
	ds_read2_b32 v[192:193], v115 offset0:232 offset1:233
	ds_read2_b32 v[194:195], v115 offset0:234 offset1:235
	ds_read2_b32 v[196:197], v115 offset0:240 offset1:241
	ds_read2_b32 v[198:199], v115 offset0:242 offset1:243
	ds_read2_b32 v[200:201], v115 offset0:248 offset1:249
	ds_read2_b32 v[202:203], v115 offset0:250 offset1:251
	v_mfma_f32_32x32x16_bf16 v[0:15], v[64:67], v[72:75], v[0:15]
	v_mfma_f32_32x32x16_bf16 v[16:31], v[64:67], v[76:79], v[16:31]
	v_mfma_f32_32x32x16_bf16 v[0:15], v[68:71], v[220:223], v[0:15]
	v_mfma_f32_32x32x16_bf16 v[16:31], v[68:71], v[224:227], v[16:31]
	s_add_i32 s90, s76, -1024
	v_add_u32_e32 v80, s90, v243
	v_add_u32_e32 v83, s90, v244
	v_add_u32_e32 v99, s90, v245
	v_add_u32_e32 v253, s90, v246
	v_add_u32_e32 v254, s90, v148
	v_add_u32_e32 v255, s90, v151
	v_med3_i32 v80, v80, 0, s99
	v_med3_i32 v83, v83, 0, s99
	v_med3_i32 v99, v99, 0, s99
	v_med3_i32 v253, v253, 0, s99
	v_med3_i32 v254, v254, 0, s99
	v_med3_i32 v255, v255, 0, s99
	v_mad_u32_u24 v80, v80, s100, v252
	v_mad_u32_u24 v83, v83, s100, v252
	v_mad_u32_u24 v99, v99, s100, v252
	v_mad_u32_u24 v253, v253, s100, v252
	v_mad_u32_u24 v254, v254, s100, v153
	v_mad_u32_u24 v255, v255, s100, v153
	global_load_dwordx4 v[116:119], v80, s[82:83]
	global_load_dwordx4 v[120:123], v83, s[82:83]
	global_load_dwordx4 v[124:127], v99, s[82:83]
	global_load_dwordx4 v[128:131], v253, s[82:83]
	global_load_dwordx4 v[132:135], v254, s[82:83] offset:768
	global_load_dwordx4 v[136:139], v255, s[82:83] offset:768
	global_load_dwordx4 v[140:143], v254, s[82:83] offset:832
	global_load_dwordx4 v[144:147], v255, s[82:83] offset:832
	ds_read_b64_tr_b16 v[72:73], v231
	ds_read_b64_tr_b16 v[74:75], v231 offset:512
	ds_read_b64_tr_b16 v[76:77], v231 offset:2048
	ds_read_b64_tr_b16 v[78:79], v231 offset:2560
	ds_read_b64_tr_b16 v[220:221], v231 offset:1024
	ds_read_b64_tr_b16 v[222:223], v231 offset:1536
	ds_read_b64_tr_b16 v[224:225], v231 offset:3072
	ds_read_b64_tr_b16 v[226:227], v231 offset:3584
	s_waitcnt vmcnt(8)
	ds_write_b128 v247, v[156:159]
	ds_write_b128 v247, v[160:163] offset:1024
	ds_write_b128 v247, v[164:167] offset:2048
	ds_write_b128 v247, v[168:171] offset:3072
	ds_read_b128 v[156:159], v248
	ds_read_b128 v[160:163], v249
	ds_read_b128 v[164:167], v250
	ds_read_b128 v[168:171], v251
	ds_write_b128 v112, v[172:175]
	ds_write_b128 v112, v[176:179] offset:1024
	ds_write_b128 v112, v[180:183] offset:2048
	ds_write_b128 v112, v[184:187] offset:3072
	s_waitcnt lgkmcnt(4)
	v_mfma_f32_32x32x16_bf16 v[188:203], v[156:159], v[48:51], v[188:203]
	v_exp_f32_e32 v32, v32
	v_exp_f32_e32 v33, v33
	v_exp_f32_e32 v34, v34
	v_exp_f32_e32 v35, v35
	v_mfma_f32_32x32x16_bf16 v[188:203], v[160:163], v[52:55], v[188:203]
	v_exp_f32_e32 v36, v36
	v_exp_f32_e32 v37, v37
	v_exp_f32_e32 v38, v38
	v_exp_f32_e32 v39, v39
	v_mfma_f32_32x32x16_bf16 v[188:203], v[164:167], v[56:59], v[188:203]
	v_exp_f32_e32 v40, v40
	v_exp_f32_e32 v41, v41
	v_exp_f32_e32 v42, v42
	v_exp_f32_e32 v43, v43
	v_mfma_f32_32x32x16_bf16 v[188:203], v[168:171], v[60:63], v[188:203]
	v_exp_f32_e32 v44, v44
	v_exp_f32_e32 v45, v45
	v_exp_f32_e32 v46, v46
	v_exp_f32_e32 v47, v47
	s_add_i32 s90, s76, 512
	v_lshlrev_b32_e32 v84, 2, v107
	v_add_u32_e32 v84, s90, v84
	v_add_u32_e32 v85, 0, v84
	v_add_u32_e32 v86, 4, v84
	v_add_u32_e32 v87, 8, v84
	v_add_u32_e32 v88, 12, v84
	v_cmp_gt_u32_e64 s[30:31], s98, v85
	v_cmp_gt_u32_e64 s[36:37], s98, v86
	v_cmp_gt_u32_e64 s[78:79], s98, v87
	v_cmp_gt_u32_e64 s[50:51], s98, v88
	v_cndmask_b32_e64 v32, 0, v32, s[30:31]
	v_add_u32_e32 v85, 32, v84
	v_cmp_gt_u32_e64 s[30:31], s98, v85
	v_cndmask_b32_e64 v33, 0, v33, s[36:37]
	v_add_u32_e32 v86, 36, v84
	v_cmp_gt_u32_e64 s[36:37], s98, v86
	v_cndmask_b32_e64 v34, 0, v34, s[78:79]
	v_add_u32_e32 v87, 40, v84
	v_cmp_gt_u32_e64 s[78:79], s98, v87
	v_cndmask_b32_e64 v35, 0, v35, s[50:51]
	v_add_u32_e32 v88, 44, v84
	v_cmp_gt_u32_e64 s[50:51], s98, v88
	v_cndmask_b32_e64 v36, 0, v36, s[30:31]
	v_add_u32_e32 v85, 64, v84
	v_cmp_gt_u32_e64 s[30:31], s98, v85
	v_cndmask_b32_e64 v37, 0, v37, s[36:37]
	v_add_u32_e32 v86, 68, v84
	v_cmp_gt_u32_e64 s[36:37], s98, v86
	v_cndmask_b32_e64 v38, 0, v38, s[78:79]
	v_add_u32_e32 v87, 72, v84
	v_cmp_gt_u32_e64 s[78:79], s98, v87
	v_cndmask_b32_e64 v39, 0, v39, s[50:51]
	v_add_u32_e32 v88, 76, v84
	v_cmp_gt_u32_e64 s[50:51], s98, v88
	v_cndmask_b32_e64 v40, 0, v40, s[30:31]
	v_add_u32_e32 v85, 96, v84
	v_cmp_gt_u32_e64 s[30:31], s98, v85
	v_cndmask_b32_e64 v41, 0, v41, s[36:37]
	v_add_u32_e32 v86, 100, v84
	v_cmp_gt_u32_e64 s[36:37], s98, v86
	v_cndmask_b32_e64 v42, 0, v42, s[78:79]
	v_add_u32_e32 v87, 104, v84
	v_cmp_gt_u32_e64 s[78:79], s98, v87
	v_cndmask_b32_e64 v43, 0, v43, s[50:51]
	v_add_u32_e32 v88, 108, v84
	v_cmp_gt_u32_e64 s[50:51], s98, v88
	v_nop
	v_cndmask_b32_e64 v44, 0, v44, s[30:31]
	v_cndmask_b32_e64 v45, 0, v45, s[36:37]
	v_cndmask_b32_e64 v46, 0, v46, s[78:79]
	v_cndmask_b32_e64 v47, 0, v47, s[50:51]
	v_cvt_pk_bf16_f32 v64, v32, v33
	v_cvt_pk_bf16_f32 v65, v34, v35
	v_cvt_pk_bf16_f32 v66, v36, v37
	v_cvt_pk_bf16_f32 v67, v38, v39
	v_cvt_pk_bf16_f32 v68, v40, v41
	v_cvt_pk_bf16_f32 v69, v42, v43
	v_cvt_pk_bf16_f32 v70, v44, v45
	v_cvt_pk_bf16_f32 v71, v46, v47
	v_pk_add_f32 v[232:233], v[232:233], v[32:33]
	v_pk_add_f32 v[232:233], v[232:233], v[34:35]
	v_pk_add_f32 v[232:233], v[232:233], v[36:37]
	v_pk_add_f32 v[232:233], v[232:233], v[38:39]
	v_pk_add_f32 v[232:233], v[232:233], v[40:41]
	v_pk_add_f32 v[232:233], v[232:233], v[42:43]
	v_pk_add_f32 v[232:233], v[232:233], v[44:45]
	v_pk_add_f32 v[232:233], v[232:233], v[46:47]
	v_mov_b32_e32 v115, v230
	ds_read2_b32 v[32:33], v115 offset0:0 offset1:1
	ds_read2_b32 v[34:35], v115 offset0:2 offset1:3
	ds_read2_b32 v[36:37], v115 offset0:8 offset1:9
	ds_read2_b32 v[38:39], v115 offset0:10 offset1:11
	ds_read2_b32 v[40:41], v115 offset0:16 offset1:17
	ds_read2_b32 v[42:43], v115 offset0:18 offset1:19
	ds_read2_b32 v[44:45], v115 offset0:24 offset1:25
	ds_read2_b32 v[46:47], v115 offset0:26 offset1:27
	v_mfma_f32_32x32x16_bf16 v[0:15], v[64:67], v[72:75], v[0:15]
	v_mfma_f32_32x32x16_bf16 v[16:31], v[64:67], v[76:79], v[16:31]
	v_mfma_f32_32x32x16_bf16 v[0:15], v[68:71], v[220:223], v[0:15]
	v_mfma_f32_32x32x16_bf16 v[16:31], v[68:71], v[224:227], v[16:31]
	s_add_i32 s90, s76, -512
	v_add_u32_e32 v80, s90, v243
	v_add_u32_e32 v83, s90, v244
	v_add_u32_e32 v99, s90, v245
	v_add_u32_e32 v253, s90, v246
	v_add_u32_e32 v254, s90, v148
	v_add_u32_e32 v255, s90, v151
	v_med3_i32 v80, v80, 0, s99
	v_med3_i32 v83, v83, 0, s99
	v_med3_i32 v99, v99, 0, s99
	v_med3_i32 v253, v253, 0, s99
	v_med3_i32 v254, v254, 0, s99
	v_med3_i32 v255, v255, 0, s99
	v_mad_u32_u24 v80, v80, s100, v252
	v_mad_u32_u24 v83, v83, s100, v252
	v_mad_u32_u24 v99, v99, s100, v252
	v_mad_u32_u24 v253, v253, s100, v252
	v_mad_u32_u24 v254, v254, s100, v153
	v_mad_u32_u24 v255, v255, s100, v153
	global_load_dwordx4 v[156:159], v80, s[82:83]
	global_load_dwordx4 v[160:163], v83, s[82:83]
	global_load_dwordx4 v[164:167], v99, s[82:83]
	global_load_dwordx4 v[168:171], v253, s[82:83]
	global_load_dwordx4 v[172:175], v254, s[82:83] offset:768
	global_load_dwordx4 v[176:179], v255, s[82:83] offset:768
	global_load_dwordx4 v[180:183], v254, s[82:83] offset:832
	global_load_dwordx4 v[184:187], v255, s[82:83] offset:832
	ds_read_b64_tr_b16 v[72:73], v231
	ds_read_b64_tr_b16 v[74:75], v231 offset:512
	ds_read_b64_tr_b16 v[76:77], v231 offset:2048
	ds_read_b64_tr_b16 v[78:79], v231 offset:2560
	ds_read_b64_tr_b16 v[220:221], v231 offset:1024
	ds_read_b64_tr_b16 v[222:223], v231 offset:1536
	ds_read_b64_tr_b16 v[224:225], v231 offset:3072
	ds_read_b64_tr_b16 v[226:227], v231 offset:3584
	s_waitcnt vmcnt(8)
	ds_write_b128 v247, v[116:119]
	ds_write_b128 v247, v[120:123] offset:1024
	ds_write_b128 v247, v[124:127] offset:2048
	ds_write_b128 v247, v[128:131] offset:3072
	ds_read_b128 v[116:119], v248
	ds_read_b128 v[120:123], v249
	ds_read_b128 v[124:127], v250
	ds_read_b128 v[128:131], v251
	ds_write_b128 v112, v[132:135]
	ds_write_b128 v112, v[136:139] offset:1024
	ds_write_b128 v112, v[140:143] offset:2048
	ds_write_b128 v112, v[144:147] offset:3072
	s_waitcnt lgkmcnt(4)
	v_mfma_f32_32x32x16_bf16 v[32:47], v[116:119], v[48:51], v[32:47]
	v_exp_f32_e32 v188, v188
	v_exp_f32_e32 v189, v189
	v_exp_f32_e32 v190, v190
	v_exp_f32_e32 v191, v191
	v_mfma_f32_32x32x16_bf16 v[32:47], v[120:123], v[52:55], v[32:47]
	v_exp_f32_e32 v192, v192
	v_exp_f32_e32 v193, v193
	v_exp_f32_e32 v194, v194
	v_exp_f32_e32 v195, v195
	v_mfma_f32_32x32x16_bf16 v[32:47], v[124:127], v[56:59], v[32:47]
	v_exp_f32_e32 v196, v196
	v_exp_f32_e32 v197, v197
	v_exp_f32_e32 v198, v198
	v_exp_f32_e32 v199, v199
	v_mfma_f32_32x32x16_bf16 v[32:47], v[128:131], v[60:63], v[32:47]
	v_exp_f32_e32 v200, v200
	v_exp_f32_e32 v201, v201
	v_exp_f32_e32 v202, v202
	v_exp_f32_e32 v203, v203
	s_add_i32 s90, s76, 640
	v_lshlrev_b32_e32 v84, 2, v107
	v_add_u32_e32 v84, s90, v84
	v_add_u32_e32 v85, 0, v84
	v_add_u32_e32 v86, 4, v84
	v_add_u32_e32 v87, 8, v84
	v_add_u32_e32 v88, 12, v84
	v_cmp_gt_u32_e64 s[30:31], s98, v85
	v_cmp_gt_u32_e64 s[36:37], s98, v86
	v_cmp_gt_u32_e64 s[78:79], s98, v87
	v_cmp_gt_u32_e64 s[50:51], s98, v88
	v_cndmask_b32_e64 v188, 0, v188, s[30:31]
	v_add_u32_e32 v85, 32, v84
	v_cmp_gt_u32_e64 s[30:31], s98, v85
	v_cndmask_b32_e64 v189, 0, v189, s[36:37]
	v_add_u32_e32 v86, 36, v84
	v_cmp_gt_u32_e64 s[36:37], s98, v86
	v_cndmask_b32_e64 v190, 0, v190, s[78:79]
	v_add_u32_e32 v87, 40, v84
	v_cmp_gt_u32_e64 s[78:79], s98, v87
	v_cndmask_b32_e64 v191, 0, v191, s[50:51]
	v_add_u32_e32 v88, 44, v84
	v_cmp_gt_u32_e64 s[50:51], s98, v88
	v_cndmask_b32_e64 v192, 0, v192, s[30:31]
	v_add_u32_e32 v85, 64, v84
	v_cmp_gt_u32_e64 s[30:31], s98, v85
	v_cndmask_b32_e64 v193, 0, v193, s[36:37]
	v_add_u32_e32 v86, 68, v84
	v_cmp_gt_u32_e64 s[36:37], s98, v86
	v_cndmask_b32_e64 v194, 0, v194, s[78:79]
	v_add_u32_e32 v87, 72, v84
	v_cmp_gt_u32_e64 s[78:79], s98, v87
	v_cndmask_b32_e64 v195, 0, v195, s[50:51]
	v_add_u32_e32 v88, 76, v84
	v_cmp_gt_u32_e64 s[50:51], s98, v88
	v_cndmask_b32_e64 v196, 0, v196, s[30:31]
	v_add_u32_e32 v85, 96, v84
	v_cmp_gt_u32_e64 s[30:31], s98, v85
	v_cndmask_b32_e64 v197, 0, v197, s[36:37]
	v_add_u32_e32 v86, 100, v84
	v_cmp_gt_u32_e64 s[36:37], s98, v86
	v_cndmask_b32_e64 v198, 0, v198, s[78:79]
	v_add_u32_e32 v87, 104, v84
	v_cmp_gt_u32_e64 s[78:79], s98, v87
	v_cndmask_b32_e64 v199, 0, v199, s[50:51]
	v_add_u32_e32 v88, 108, v84
	v_cmp_gt_u32_e64 s[50:51], s98, v88
	v_nop
	v_cndmask_b32_e64 v200, 0, v200, s[30:31]
	v_cndmask_b32_e64 v201, 0, v201, s[36:37]
	v_cndmask_b32_e64 v202, 0, v202, s[78:79]
	v_cndmask_b32_e64 v203, 0, v203, s[50:51]
	v_cvt_pk_bf16_f32 v64, v188, v189
	v_cvt_pk_bf16_f32 v65, v190, v191
	v_cvt_pk_bf16_f32 v66, v192, v193
	v_cvt_pk_bf16_f32 v67, v194, v195
	v_cvt_pk_bf16_f32 v68, v196, v197
	v_cvt_pk_bf16_f32 v69, v198, v199
	v_cvt_pk_bf16_f32 v70, v200, v201
	v_cvt_pk_bf16_f32 v71, v202, v203
	v_pk_add_f32 v[232:233], v[232:233], v[188:189]
	v_pk_add_f32 v[232:233], v[232:233], v[190:191]
	v_pk_add_f32 v[232:233], v[232:233], v[192:193]
	v_pk_add_f32 v[232:233], v[232:233], v[194:195]
	v_pk_add_f32 v[232:233], v[232:233], v[196:197]
	v_pk_add_f32 v[232:233], v[232:233], v[198:199]
	v_pk_add_f32 v[232:233], v[232:233], v[200:201]
	v_pk_add_f32 v[232:233], v[232:233], v[202:203]
	ds_read2_b32 v[188:189], v115 offset0:32 offset1:33
	ds_read2_b32 v[190:191], v115 offset0:34 offset1:35
	ds_read2_b32 v[192:193], v115 offset0:40 offset1:41
	ds_read2_b32 v[194:195], v115 offset0:42 offset1:43
	ds_read2_b32 v[196:197], v115 offset0:48 offset1:49
	ds_read2_b32 v[198:199], v115 offset0:50 offset1:51
	ds_read2_b32 v[200:201], v115 offset0:56 offset1:57
	ds_read2_b32 v[202:203], v115 offset0:58 offset1:59
	v_mfma_f32_32x32x16_bf16 v[0:15], v[64:67], v[72:75], v[0:15]
	v_mfma_f32_32x32x16_bf16 v[16:31], v[64:67], v[76:79], v[16:31]
	v_mfma_f32_32x32x16_bf16 v[0:15], v[68:71], v[220:223], v[0:15]
	v_mfma_f32_32x32x16_bf16 v[16:31], v[68:71], v[224:227], v[16:31]
	s_add_i32 s90, s76, 0
	v_add_u32_e32 v80, s90, v243
	v_add_u32_e32 v83, s90, v244
	v_add_u32_e32 v99, s90, v245
	v_add_u32_e32 v253, s90, v246
	v_add_u32_e32 v254, s90, v148
	v_add_u32_e32 v255, s90, v151
	v_med3_i32 v80, v80, 0, s99
	v_med3_i32 v83, v83, 0, s99
	v_med3_i32 v99, v99, 0, s99
	v_med3_i32 v253, v253, 0, s99
	v_med3_i32 v254, v254, 0, s99
	v_med3_i32 v255, v255, 0, s99
	v_mad_u32_u24 v80, v80, s100, v252
	v_mad_u32_u24 v83, v83, s100, v252
	v_mad_u32_u24 v99, v99, s100, v252
	v_mad_u32_u24 v253, v253, s100, v252
	v_mad_u32_u24 v254, v254, s100, v153
	v_mad_u32_u24 v255, v255, s100, v153
	global_load_dwordx4 v[116:119], v80, s[82:83]
	global_load_dwordx4 v[120:123], v83, s[82:83]
	global_load_dwordx4 v[124:127], v99, s[82:83]
	global_load_dwordx4 v[128:131], v253, s[82:83]
	global_load_dwordx4 v[132:135], v254, s[82:83] offset:768
	global_load_dwordx4 v[136:139], v255, s[82:83] offset:768
	global_load_dwordx4 v[140:143], v254, s[82:83] offset:832
	global_load_dwordx4 v[144:147], v255, s[82:83] offset:832
	ds_read_b64_tr_b16 v[72:73], v231
	ds_read_b64_tr_b16 v[74:75], v231 offset:512
	ds_read_b64_tr_b16 v[76:77], v231 offset:2048
	ds_read_b64_tr_b16 v[78:79], v231 offset:2560
	ds_read_b64_tr_b16 v[220:221], v231 offset:1024
	ds_read_b64_tr_b16 v[222:223], v231 offset:1536
	ds_read_b64_tr_b16 v[224:225], v231 offset:3072
	ds_read_b64_tr_b16 v[226:227], v231 offset:3584
	s_waitcnt vmcnt(8)
	ds_write_b128 v247, v[156:159]
	ds_write_b128 v247, v[160:163] offset:1024
	ds_write_b128 v247, v[164:167] offset:2048
	ds_write_b128 v247, v[168:171] offset:3072
	ds_read_b128 v[156:159], v248
	ds_read_b128 v[160:163], v249
	ds_read_b128 v[164:167], v250
	ds_read_b128 v[168:171], v251
	ds_write_b128 v112, v[172:175]
	ds_write_b128 v112, v[176:179] offset:1024
	ds_write_b128 v112, v[180:183] offset:2048
	ds_write_b128 v112, v[184:187] offset:3072
	s_waitcnt lgkmcnt(4)
	v_mfma_f32_32x32x16_bf16 v[188:203], v[156:159], v[48:51], v[188:203]
	v_exp_f32_e32 v32, v32
	v_exp_f32_e32 v33, v33
	v_exp_f32_e32 v34, v34
	v_exp_f32_e32 v35, v35
	v_mfma_f32_32x32x16_bf16 v[188:203], v[160:163], v[52:55], v[188:203]
	v_exp_f32_e32 v36, v36
	v_exp_f32_e32 v37, v37
	v_exp_f32_e32 v38, v38
	v_exp_f32_e32 v39, v39
	v_mfma_f32_32x32x16_bf16 v[188:203], v[164:167], v[56:59], v[188:203]
	v_exp_f32_e32 v40, v40
	v_exp_f32_e32 v41, v41
	v_exp_f32_e32 v42, v42
	v_exp_f32_e32 v43, v43
	v_mfma_f32_32x32x16_bf16 v[188:203], v[168:171], v[60:63], v[188:203]
	v_exp_f32_e32 v44, v44
	v_exp_f32_e32 v45, v45
	v_exp_f32_e32 v46, v46
	v_exp_f32_e32 v47, v47
	s_add_i32 s90, s76, -1024
	v_lshlrev_b32_e32 v84, 4, v107
	v_add_u32_e32 v84, s90, v84
	v_add_u32_e32 v85, 0, v84
	v_add_u32_e32 v86, 16, v84
	v_add_u32_e32 v87, 32, v84
	v_add_u32_e32 v88, 48, v84
	v_cmp_gt_u32_e64 s[30:31], s98, v85
	v_cmp_gt_u32_e64 s[36:37], s98, v86
	v_cmp_gt_u32_e64 s[78:79], s98, v87
	v_cmp_gt_u32_e64 s[50:51], s98, v88
	v_cndmask_b32_e64 v32, 0, v32, s[30:31]
	v_add_u32_e32 v85, 128, v84
	v_cmp_gt_u32_e64 s[30:31], s98, v85
	v_cndmask_b32_e64 v33, 0, v33, s[36:37]
	v_add_u32_e32 v86, 144, v84
	v_cmp_gt_u32_e64 s[36:37], s98, v86
	v_cndmask_b32_e64 v34, 0, v34, s[78:79]
	v_add_u32_e32 v87, 160, v84
	v_cmp_gt_u32_e64 s[78:79], s98, v87
	v_cndmask_b32_e64 v35, 0, v35, s[50:51]
	v_add_u32_e32 v88, 176, v84
	v_cmp_gt_u32_e64 s[50:51], s98, v88
	v_cndmask_b32_e64 v36, 0, v36, s[30:31]
	v_add_u32_e32 v85, 256, v84
	v_cmp_gt_u32_e64 s[30:31], s98, v85
	v_cndmask_b32_e64 v37, 0, v37, s[36:37]
	v_add_u32_e32 v86, 272, v84
	v_cmp_gt_u32_e64 s[36:37], s98, v86
	v_cndmask_b32_e64 v38, 0, v38, s[78:79]
	v_add_u32_e32 v87, 288, v84
	v_cmp_gt_u32_e64 s[78:79], s98, v87
	v_cndmask_b32_e64 v39, 0, v39, s[50:51]
	v_add_u32_e32 v88, 304, v84
	v_cmp_gt_u32_e64 s[50:51], s98, v88
	v_cndmask_b32_e64 v40, 0, v40, s[30:31]
	v_add_u32_e32 v85, 384, v84
	v_cmp_gt_u32_e64 s[30:31], s98, v85
	v_cndmask_b32_e64 v41, 0, v41, s[36:37]
	v_add_u32_e32 v86, 400, v84
	v_cmp_gt_u32_e64 s[36:37], s98, v86
	v_cndmask_b32_e64 v42, 0, v42, s[78:79]
	v_add_u32_e32 v87, 416, v84
	v_cmp_gt_u32_e64 s[78:79], s98, v87
	v_cndmask_b32_e64 v43, 0, v43, s[50:51]
	v_add_u32_e32 v88, 432, v84
	v_cmp_gt_u32_e64 s[50:51], s98, v88
	v_nop
	v_cndmask_b32_e64 v44, 0, v44, s[30:31]
	v_cndmask_b32_e64 v45, 0, v45, s[36:37]
	v_cndmask_b32_e64 v46, 0, v46, s[78:79]
	v_cndmask_b32_e64 v47, 0, v47, s[50:51]
	v_cvt_pk_bf16_f32 v64, v32, v33
	v_cvt_pk_bf16_f32 v65, v34, v35
	v_cvt_pk_bf16_f32 v66, v36, v37
	v_cvt_pk_bf16_f32 v67, v38, v39
	v_cvt_pk_bf16_f32 v68, v40, v41
	v_cvt_pk_bf16_f32 v69, v42, v43
	v_cvt_pk_bf16_f32 v70, v44, v45
	v_cvt_pk_bf16_f32 v71, v46, v47
	v_pk_add_f32 v[232:233], v[232:233], v[32:33]
	v_pk_add_f32 v[232:233], v[232:233], v[34:35]
	v_pk_add_f32 v[232:233], v[232:233], v[36:37]
	v_pk_add_f32 v[232:233], v[232:233], v[38:39]
	v_pk_add_f32 v[232:233], v[232:233], v[40:41]
	v_pk_add_f32 v[232:233], v[232:233], v[42:43]
	v_pk_add_f32 v[232:233], v[232:233], v[44:45]
	v_pk_add_f32 v[232:233], v[232:233], v[46:47]
	ds_read2_b32 v[32:33], v115 offset0:64 offset1:65
	ds_read2_b32 v[34:35], v115 offset0:66 offset1:67
	ds_read2_b32 v[36:37], v115 offset0:72 offset1:73
	ds_read2_b32 v[38:39], v115 offset0:74 offset1:75
	ds_read2_b32 v[40:41], v115 offset0:80 offset1:81
	ds_read2_b32 v[42:43], v115 offset0:82 offset1:83
	ds_read2_b32 v[44:45], v115 offset0:88 offset1:89
	ds_read2_b32 v[46:47], v115 offset0:90 offset1:91
	v_mfma_f32_32x32x16_bf16 v[0:15], v[64:67], v[72:75], v[0:15]
	v_mfma_f32_32x32x16_bf16 v[16:31], v[64:67], v[76:79], v[16:31]
	v_mfma_f32_32x32x16_bf16 v[0:15], v[68:71], v[220:223], v[0:15]
	v_mfma_f32_32x32x16_bf16 v[16:31], v[68:71], v[224:227], v[16:31]
	s_add_i32 s90, s76, 512
	v_add_u32_e32 v80, s90, v243
	v_add_u32_e32 v83, s90, v244
	v_add_u32_e32 v99, s90, v245
	v_add_u32_e32 v253, s90, v246
	v_add_u32_e32 v254, s90, v148
	v_add_u32_e32 v255, s90, v151
	v_med3_i32 v80, v80, 0, s99
	v_med3_i32 v83, v83, 0, s99
	v_med3_i32 v99, v99, 0, s99
	v_med3_i32 v253, v253, 0, s99
	v_med3_i32 v254, v254, 0, s99
	v_med3_i32 v255, v255, 0, s99
	v_mad_u32_u24 v80, v80, s100, v252
	v_mad_u32_u24 v83, v83, s100, v252
	v_mad_u32_u24 v99, v99, s100, v252
	v_mad_u32_u24 v253, v253, s100, v252
	v_mad_u32_u24 v254, v254, s100, v153
	v_mad_u32_u24 v255, v255, s100, v153
	global_load_dwordx4 v[156:159], v80, s[82:83]
	global_load_dwordx4 v[160:163], v83, s[82:83]
	global_load_dwordx4 v[164:167], v99, s[82:83]
	global_load_dwordx4 v[168:171], v253, s[82:83]
	global_load_dwordx4 v[172:175], v254, s[82:83] offset:768
	global_load_dwordx4 v[176:179], v255, s[82:83] offset:768
	global_load_dwordx4 v[180:183], v254, s[82:83] offset:832
	global_load_dwordx4 v[184:187], v255, s[82:83] offset:832
	ds_read_b64_tr_b16 v[72:73], v231
	ds_read_b64_tr_b16 v[74:75], v231 offset:512
	ds_read_b64_tr_b16 v[76:77], v231 offset:2048
	ds_read_b64_tr_b16 v[78:79], v231 offset:2560
	ds_read_b64_tr_b16 v[220:221], v231 offset:1024
	ds_read_b64_tr_b16 v[222:223], v231 offset:1536
	ds_read_b64_tr_b16 v[224:225], v231 offset:3072
	ds_read_b64_tr_b16 v[226:227], v231 offset:3584
	s_waitcnt vmcnt(8)
	ds_write_b128 v247, v[116:119]
	ds_write_b128 v247, v[120:123] offset:1024
	ds_write_b128 v247, v[124:127] offset:2048
	ds_write_b128 v247, v[128:131] offset:3072
	ds_read_b128 v[116:119], v248
	ds_read_b128 v[120:123], v249
	ds_read_b128 v[124:127], v250
	ds_read_b128 v[128:131], v251
	ds_write_b128 v112, v[132:135]
	ds_write_b128 v112, v[136:139] offset:1024
	ds_write_b128 v112, v[140:143] offset:2048
	ds_write_b128 v112, v[144:147] offset:3072
	s_waitcnt lgkmcnt(4)
	v_mfma_f32_32x32x16_bf16 v[32:47], v[116:119], v[48:51], v[32:47]
	v_exp_f32_e32 v188, v188
	v_exp_f32_e32 v189, v189
	v_exp_f32_e32 v190, v190
	v_exp_f32_e32 v191, v191
	v_mfma_f32_32x32x16_bf16 v[32:47], v[120:123], v[52:55], v[32:47]
	v_exp_f32_e32 v192, v192
	v_exp_f32_e32 v193, v193
	v_exp_f32_e32 v194, v194
	v_exp_f32_e32 v195, v195
	v_mfma_f32_32x32x16_bf16 v[32:47], v[124:127], v[56:59], v[32:47]
	v_exp_f32_e32 v196, v196
	v_exp_f32_e32 v197, v197
	v_exp_f32_e32 v198, v198
	v_exp_f32_e32 v199, v199
	v_mfma_f32_32x32x16_bf16 v[32:47], v[128:131], v[60:63], v[32:47]
	v_exp_f32_e32 v200, v200
	v_exp_f32_e32 v201, v201
	v_exp_f32_e32 v202, v202
	v_exp_f32_e32 v203, v203
	s_add_i32 s90, s76, -512
	v_lshlrev_b32_e32 v84, 4, v107
	v_add_u32_e32 v84, s90, v84
	v_add_u32_e32 v85, 0, v84
	v_add_u32_e32 v86, 16, v84
	v_add_u32_e32 v87, 32, v84
	v_add_u32_e32 v88, 48, v84
	v_cmp_gt_u32_e64 s[30:31], s98, v85
	v_cmp_gt_u32_e64 s[36:37], s98, v86
	v_cmp_gt_u32_e64 s[78:79], s98, v87
	v_cmp_gt_u32_e64 s[50:51], s98, v88
	v_cndmask_b32_e64 v188, 0, v188, s[30:31]
	v_add_u32_e32 v85, 128, v84
	v_cmp_gt_u32_e64 s[30:31], s98, v85
	v_cndmask_b32_e64 v189, 0, v189, s[36:37]
	v_add_u32_e32 v86, 144, v84
	v_cmp_gt_u32_e64 s[36:37], s98, v86
	v_cndmask_b32_e64 v190, 0, v190, s[78:79]
	v_add_u32_e32 v87, 160, v84
	v_cmp_gt_u32_e64 s[78:79], s98, v87
	v_cndmask_b32_e64 v191, 0, v191, s[50:51]
	v_add_u32_e32 v88, 176, v84
	v_cmp_gt_u32_e64 s[50:51], s98, v88
	v_cndmask_b32_e64 v192, 0, v192, s[30:31]
	v_add_u32_e32 v85, 256, v84
	v_cmp_gt_u32_e64 s[30:31], s98, v85
	v_cndmask_b32_e64 v193, 0, v193, s[36:37]
	v_add_u32_e32 v86, 272, v84
	v_cmp_gt_u32_e64 s[36:37], s98, v86
	v_cndmask_b32_e64 v194, 0, v194, s[78:79]
	v_add_u32_e32 v87, 288, v84
	v_cmp_gt_u32_e64 s[78:79], s98, v87
	v_cndmask_b32_e64 v195, 0, v195, s[50:51]
	v_add_u32_e32 v88, 304, v84
	v_cmp_gt_u32_e64 s[50:51], s98, v88
	v_cndmask_b32_e64 v196, 0, v196, s[30:31]
	v_add_u32_e32 v85, 384, v84
	v_cmp_gt_u32_e64 s[30:31], s98, v85
	v_cndmask_b32_e64 v197, 0, v197, s[36:37]
	v_add_u32_e32 v86, 400, v84
	v_cmp_gt_u32_e64 s[36:37], s98, v86
	v_cndmask_b32_e64 v198, 0, v198, s[78:79]
	v_add_u32_e32 v87, 416, v84
	v_cmp_gt_u32_e64 s[78:79], s98, v87
	v_cndmask_b32_e64 v199, 0, v199, s[50:51]
	v_add_u32_e32 v88, 432, v84
	v_cmp_gt_u32_e64 s[50:51], s98, v88
	v_nop
	v_cndmask_b32_e64 v200, 0, v200, s[30:31]
	v_cndmask_b32_e64 v201, 0, v201, s[36:37]
	v_cndmask_b32_e64 v202, 0, v202, s[78:79]
	v_cndmask_b32_e64 v203, 0, v203, s[50:51]
	v_cvt_pk_bf16_f32 v64, v188, v189
	v_cvt_pk_bf16_f32 v65, v190, v191
	v_cvt_pk_bf16_f32 v66, v192, v193
	v_cvt_pk_bf16_f32 v67, v194, v195
	v_cvt_pk_bf16_f32 v68, v196, v197
	v_cvt_pk_bf16_f32 v69, v198, v199
	v_cvt_pk_bf16_f32 v70, v200, v201
	v_cvt_pk_bf16_f32 v71, v202, v203
	v_pk_add_f32 v[232:233], v[232:233], v[188:189]
	v_pk_add_f32 v[232:233], v[232:233], v[190:191]
	v_pk_add_f32 v[232:233], v[232:233], v[192:193]
	v_pk_add_f32 v[232:233], v[232:233], v[194:195]
	v_pk_add_f32 v[232:233], v[232:233], v[196:197]
	v_pk_add_f32 v[232:233], v[232:233], v[198:199]
	v_pk_add_f32 v[232:233], v[232:233], v[200:201]
	v_pk_add_f32 v[232:233], v[232:233], v[202:203]
	ds_read2_b32 v[188:189], v115 offset0:96 offset1:97
	ds_read2_b32 v[190:191], v115 offset0:98 offset1:99
	ds_read2_b32 v[192:193], v115 offset0:104 offset1:105
	ds_read2_b32 v[194:195], v115 offset0:106 offset1:107
	ds_read2_b32 v[196:197], v115 offset0:112 offset1:113
	ds_read2_b32 v[198:199], v115 offset0:114 offset1:115
	ds_read2_b32 v[200:201], v115 offset0:120 offset1:121
	ds_read2_b32 v[202:203], v115 offset0:122 offset1:123
	v_mfma_f32_32x32x16_bf16 v[0:15], v[64:67], v[72:75], v[0:15]
	v_mfma_f32_32x32x16_bf16 v[16:31], v[64:67], v[76:79], v[16:31]
	v_mfma_f32_32x32x16_bf16 v[0:15], v[68:71], v[220:223], v[0:15]
	v_mfma_f32_32x32x16_bf16 v[16:31], v[68:71], v[224:227], v[16:31]
	s_add_i32 s90, s76, 1024
	v_add_u32_e32 v80, s90, v243
	v_add_u32_e32 v83, s90, v244
	v_add_u32_e32 v99, s90, v245
	v_add_u32_e32 v253, s90, v246
	v_add_u32_e32 v254, s90, v148
	v_add_u32_e32 v255, s90, v151
	v_med3_i32 v80, v80, 0, s99
	v_med3_i32 v83, v83, 0, s99
	v_med3_i32 v99, v99, 0, s99
	v_med3_i32 v253, v253, 0, s99
	v_med3_i32 v254, v254, 0, s99
	v_med3_i32 v255, v255, 0, s99
	v_mad_u32_u24 v80, v80, s100, v252
	v_mad_u32_u24 v83, v83, s100, v252
	v_mad_u32_u24 v99, v99, s100, v252
	v_mad_u32_u24 v253, v253, s100, v252
	v_mad_u32_u24 v254, v254, s100, v153
	v_mad_u32_u24 v255, v255, s100, v153
	global_load_dwordx4 v[116:119], v80, s[82:83]
	global_load_dwordx4 v[120:123], v83, s[82:83]
	global_load_dwordx4 v[124:127], v99, s[82:83]
	global_load_dwordx4 v[128:131], v253, s[82:83]
	global_load_dwordx4 v[132:135], v254, s[82:83] offset:768
	global_load_dwordx4 v[136:139], v255, s[82:83] offset:768
	global_load_dwordx4 v[140:143], v254, s[82:83] offset:832
	global_load_dwordx4 v[144:147], v255, s[82:83] offset:832
	ds_read_b64_tr_b16 v[72:73], v231
	ds_read_b64_tr_b16 v[74:75], v231 offset:512
	ds_read_b64_tr_b16 v[76:77], v231 offset:2048
	ds_read_b64_tr_b16 v[78:79], v231 offset:2560
	ds_read_b64_tr_b16 v[220:221], v231 offset:1024
	ds_read_b64_tr_b16 v[222:223], v231 offset:1536
	ds_read_b64_tr_b16 v[224:225], v231 offset:3072
	ds_read_b64_tr_b16 v[226:227], v231 offset:3584
	s_waitcnt vmcnt(8)
	ds_write_b128 v247, v[156:159]
	ds_write_b128 v247, v[160:163] offset:1024
	ds_write_b128 v247, v[164:167] offset:2048
	ds_write_b128 v247, v[168:171] offset:3072
	ds_read_b128 v[156:159], v248
	ds_read_b128 v[160:163], v249
	ds_read_b128 v[164:167], v250
	ds_read_b128 v[168:171], v251
	ds_write_b128 v112, v[172:175]
	ds_write_b128 v112, v[176:179] offset:1024
	ds_write_b128 v112, v[180:183] offset:2048
	ds_write_b128 v112, v[184:187] offset:3072
	s_waitcnt lgkmcnt(4)
	v_mfma_f32_32x32x16_bf16 v[188:203], v[156:159], v[48:51], v[188:203]
	v_exp_f32_e32 v32, v32
	v_exp_f32_e32 v33, v33
	v_exp_f32_e32 v34, v34
	v_exp_f32_e32 v35, v35
	v_mfma_f32_32x32x16_bf16 v[188:203], v[160:163], v[52:55], v[188:203]
	v_exp_f32_e32 v36, v36
	v_exp_f32_e32 v37, v37
	v_exp_f32_e32 v38, v38
	v_exp_f32_e32 v39, v39
	v_mfma_f32_32x32x16_bf16 v[188:203], v[164:167], v[56:59], v[188:203]
	v_exp_f32_e32 v40, v40
	v_exp_f32_e32 v41, v41
	v_exp_f32_e32 v42, v42
	v_exp_f32_e32 v43, v43
	v_mfma_f32_32x32x16_bf16 v[188:203], v[168:171], v[60:63], v[188:203]
	v_exp_f32_e32 v44, v44
	v_exp_f32_e32 v45, v45
	v_exp_f32_e32 v46, v46
	v_exp_f32_e32 v47, v47
	s_add_i32 s90, s76, 0
	v_lshlrev_b32_e32 v84, 4, v107
	v_add_u32_e32 v84, s90, v84
	v_add_u32_e32 v85, 0, v84
	v_add_u32_e32 v86, 16, v84
	v_add_u32_e32 v87, 32, v84
	v_add_u32_e32 v88, 48, v84
	v_cmp_gt_u32_e64 s[30:31], s98, v85
	v_cmp_gt_u32_e64 s[36:37], s98, v86
	v_cmp_gt_u32_e64 s[78:79], s98, v87
	v_cmp_gt_u32_e64 s[50:51], s98, v88
	v_cndmask_b32_e64 v32, 0, v32, s[30:31]
	v_add_u32_e32 v85, 128, v84
	v_cmp_gt_u32_e64 s[30:31], s98, v85
	v_cndmask_b32_e64 v33, 0, v33, s[36:37]
	v_add_u32_e32 v86, 144, v84
	v_cmp_gt_u32_e64 s[36:37], s98, v86
	v_cndmask_b32_e64 v34, 0, v34, s[78:79]
	v_add_u32_e32 v87, 160, v84
	v_cmp_gt_u32_e64 s[78:79], s98, v87
	v_cndmask_b32_e64 v35, 0, v35, s[50:51]
	v_add_u32_e32 v88, 176, v84
	v_cmp_gt_u32_e64 s[50:51], s98, v88
	v_cndmask_b32_e64 v36, 0, v36, s[30:31]
	v_add_u32_e32 v85, 256, v84
	v_cmp_gt_u32_e64 s[30:31], s98, v85
	v_cndmask_b32_e64 v37, 0, v37, s[36:37]
	v_add_u32_e32 v86, 272, v84
	v_cmp_gt_u32_e64 s[36:37], s98, v86
	v_cndmask_b32_e64 v38, 0, v38, s[78:79]
	v_add_u32_e32 v87, 288, v84
	v_cmp_gt_u32_e64 s[78:79], s98, v87
	v_cndmask_b32_e64 v39, 0, v39, s[50:51]
	v_add_u32_e32 v88, 304, v84
	v_cmp_gt_u32_e64 s[50:51], s98, v88
	v_cndmask_b32_e64 v40, 0, v40, s[30:31]
	v_add_u32_e32 v85, 384, v84
	v_cmp_gt_u32_e64 s[30:31], s98, v85
	v_cndmask_b32_e64 v41, 0, v41, s[36:37]
	v_add_u32_e32 v86, 400, v84
	v_cmp_gt_u32_e64 s[36:37], s98, v86
	v_cndmask_b32_e64 v42, 0, v42, s[78:79]
	v_add_u32_e32 v87, 416, v84
	v_cmp_gt_u32_e64 s[78:79], s98, v87
	v_cndmask_b32_e64 v43, 0, v43, s[50:51]
	v_add_u32_e32 v88, 432, v84
	v_cmp_gt_u32_e64 s[50:51], s98, v88
	v_nop
	v_cndmask_b32_e64 v44, 0, v44, s[30:31]
	v_cndmask_b32_e64 v45, 0, v45, s[36:37]
	v_cndmask_b32_e64 v46, 0, v46, s[78:79]
	v_cndmask_b32_e64 v47, 0, v47, s[50:51]
	v_cvt_pk_bf16_f32 v64, v32, v33
	v_cvt_pk_bf16_f32 v65, v34, v35
	v_cvt_pk_bf16_f32 v66, v36, v37
	v_cvt_pk_bf16_f32 v67, v38, v39
	v_cvt_pk_bf16_f32 v68, v40, v41
	v_cvt_pk_bf16_f32 v69, v42, v43
	v_cvt_pk_bf16_f32 v70, v44, v45
	v_cvt_pk_bf16_f32 v71, v46, v47
	v_pk_add_f32 v[232:233], v[232:233], v[32:33]
	v_pk_add_f32 v[232:233], v[232:233], v[34:35]
	v_pk_add_f32 v[232:233], v[232:233], v[36:37]
	v_pk_add_f32 v[232:233], v[232:233], v[38:39]
	v_pk_add_f32 v[232:233], v[232:233], v[40:41]
	v_pk_add_f32 v[232:233], v[232:233], v[42:43]
	v_pk_add_f32 v[232:233], v[232:233], v[44:45]
	v_pk_add_f32 v[232:233], v[232:233], v[46:47]
	ds_read2_b32 v[32:33], v115 offset0:128 offset1:129
	ds_read2_b32 v[34:35], v115 offset0:130 offset1:131
	ds_read2_b32 v[36:37], v115 offset0:136 offset1:137
	ds_read2_b32 v[38:39], v115 offset0:138 offset1:139
	ds_read2_b32 v[40:41], v115 offset0:144 offset1:145
	ds_read2_b32 v[42:43], v115 offset0:146 offset1:147
	ds_read2_b32 v[44:45], v115 offset0:152 offset1:153
	ds_read2_b32 v[46:47], v115 offset0:154 offset1:155
	v_mfma_f32_32x32x16_bf16 v[0:15], v[64:67], v[72:75], v[0:15]
	v_mfma_f32_32x32x16_bf16 v[16:31], v[64:67], v[76:79], v[16:31]
	v_mfma_f32_32x32x16_bf16 v[0:15], v[68:71], v[220:223], v[0:15]
	v_mfma_f32_32x32x16_bf16 v[16:31], v[68:71], v[224:227], v[16:31]
	ds_read_b64_tr_b16 v[72:73], v231
	ds_read_b64_tr_b16 v[74:75], v231 offset:512
	ds_read_b64_tr_b16 v[76:77], v231 offset:2048
	ds_read_b64_tr_b16 v[78:79], v231 offset:2560
	ds_read_b64_tr_b16 v[220:221], v231 offset:1024
	ds_read_b64_tr_b16 v[222:223], v231 offset:1536
	ds_read_b64_tr_b16 v[224:225], v231 offset:3072
	ds_read_b64_tr_b16 v[226:227], v231 offset:3584
	s_waitcnt vmcnt(0)
	ds_write_b128 v247, v[116:119]
	ds_write_b128 v247, v[120:123] offset:1024
	ds_write_b128 v247, v[124:127] offset:2048
	ds_write_b128 v247, v[128:131] offset:3072
	ds_read_b128 v[116:119], v248
	ds_read_b128 v[120:123], v249
	ds_read_b128 v[124:127], v250
	ds_read_b128 v[128:131], v251
	ds_write_b128 v112, v[132:135]
	ds_write_b128 v112, v[136:139] offset:1024
	ds_write_b128 v112, v[140:143] offset:2048
	ds_write_b128 v112, v[144:147] offset:3072
	s_waitcnt lgkmcnt(4)
	v_mfma_f32_32x32x16_bf16 v[32:47], v[116:119], v[48:51], v[32:47]
	v_exp_f32_e32 v188, v188
	v_exp_f32_e32 v189, v189
	v_exp_f32_e32 v190, v190
	v_exp_f32_e32 v191, v191
	v_mfma_f32_32x32x16_bf16 v[32:47], v[120:123], v[52:55], v[32:47]
	v_exp_f32_e32 v192, v192
	v_exp_f32_e32 v193, v193
	v_exp_f32_e32 v194, v194
	v_exp_f32_e32 v195, v195
	v_mfma_f32_32x32x16_bf16 v[32:47], v[124:127], v[56:59], v[32:47]
	v_exp_f32_e32 v196, v196
	v_exp_f32_e32 v197, v197
	v_exp_f32_e32 v198, v198
	v_exp_f32_e32 v199, v199
	v_mfma_f32_32x32x16_bf16 v[32:47], v[128:131], v[60:63], v[32:47]
	v_exp_f32_e32 v200, v200
	v_exp_f32_e32 v201, v201
	v_exp_f32_e32 v202, v202
	v_exp_f32_e32 v203, v203
	s_add_i32 s90, s76, 512
	v_lshlrev_b32_e32 v84, 4, v107
	v_add_u32_e32 v84, s90, v84
	v_add_u32_e32 v85, 0, v84
	v_add_u32_e32 v86, 16, v84
	v_add_u32_e32 v87, 32, v84
	v_add_u32_e32 v88, 48, v84
	v_cmp_gt_u32_e64 s[30:31], s98, v85
	v_cmp_gt_u32_e64 s[36:37], s98, v86
	v_cmp_gt_u32_e64 s[78:79], s98, v87
	v_cmp_gt_u32_e64 s[50:51], s98, v88
	v_cndmask_b32_e64 v188, 0, v188, s[30:31]
	v_add_u32_e32 v85, 128, v84
	v_cmp_gt_u32_e64 s[30:31], s98, v85
	v_cndmask_b32_e64 v189, 0, v189, s[36:37]
	v_add_u32_e32 v86, 144, v84
	v_cmp_gt_u32_e64 s[36:37], s98, v86
	v_cndmask_b32_e64 v190, 0, v190, s[78:79]
	v_add_u32_e32 v87, 160, v84
	v_cmp_gt_u32_e64 s[78:79], s98, v87
	v_cndmask_b32_e64 v191, 0, v191, s[50:51]
	v_add_u32_e32 v88, 176, v84
	v_cmp_gt_u32_e64 s[50:51], s98, v88
	v_cndmask_b32_e64 v192, 0, v192, s[30:31]
	v_add_u32_e32 v85, 256, v84
	v_cmp_gt_u32_e64 s[30:31], s98, v85
	v_cndmask_b32_e64 v193, 0, v193, s[36:37]
	v_add_u32_e32 v86, 272, v84
	v_cmp_gt_u32_e64 s[36:37], s98, v86
	v_cndmask_b32_e64 v194, 0, v194, s[78:79]
	v_add_u32_e32 v87, 288, v84
	v_cmp_gt_u32_e64 s[78:79], s98, v87
	v_cndmask_b32_e64 v195, 0, v195, s[50:51]
	v_add_u32_e32 v88, 304, v84
	v_cmp_gt_u32_e64 s[50:51], s98, v88
	v_cndmask_b32_e64 v196, 0, v196, s[30:31]
	v_add_u32_e32 v85, 384, v84
	v_cmp_gt_u32_e64 s[30:31], s98, v85
	v_cndmask_b32_e64 v197, 0, v197, s[36:37]
	v_add_u32_e32 v86, 400, v84
	v_cmp_gt_u32_e64 s[36:37], s98, v86
	v_cndmask_b32_e64 v198, 0, v198, s[78:79]
	v_add_u32_e32 v87, 416, v84
	v_cmp_gt_u32_e64 s[78:79], s98, v87
	v_cndmask_b32_e64 v199, 0, v199, s[50:51]
	v_add_u32_e32 v88, 432, v84
	v_cmp_gt_u32_e64 s[50:51], s98, v88
	v_nop
	v_cndmask_b32_e64 v200, 0, v200, s[30:31]
	v_cndmask_b32_e64 v201, 0, v201, s[36:37]
	v_cndmask_b32_e64 v202, 0, v202, s[78:79]
	v_cndmask_b32_e64 v203, 0, v203, s[50:51]
	v_cvt_pk_bf16_f32 v64, v188, v189
	v_cvt_pk_bf16_f32 v65, v190, v191
	v_cvt_pk_bf16_f32 v66, v192, v193
	v_cvt_pk_bf16_f32 v67, v194, v195
	v_cvt_pk_bf16_f32 v68, v196, v197
	v_cvt_pk_bf16_f32 v69, v198, v199
	v_cvt_pk_bf16_f32 v70, v200, v201
	v_cvt_pk_bf16_f32 v71, v202, v203
	v_pk_add_f32 v[232:233], v[232:233], v[188:189]
	v_pk_add_f32 v[232:233], v[232:233], v[190:191]
	v_pk_add_f32 v[232:233], v[232:233], v[192:193]
	v_pk_add_f32 v[232:233], v[232:233], v[194:195]
	v_pk_add_f32 v[232:233], v[232:233], v[196:197]
	v_pk_add_f32 v[232:233], v[232:233], v[198:199]
	v_pk_add_f32 v[232:233], v[232:233], v[200:201]
	v_pk_add_f32 v[232:233], v[232:233], v[202:203]
	v_mfma_f32_32x32x16_bf16 v[0:15], v[64:67], v[72:75], v[0:15]
	v_mfma_f32_32x32x16_bf16 v[16:31], v[64:67], v[76:79], v[16:31]
	v_mfma_f32_32x32x16_bf16 v[0:15], v[68:71], v[220:223], v[0:15]
	v_mfma_f32_32x32x16_bf16 v[16:31], v[68:71], v[224:227], v[16:31]
	ds_read_b64_tr_b16 v[72:73], v231
	ds_read_b64_tr_b16 v[74:75], v231 offset:512
	ds_read_b64_tr_b16 v[76:77], v231 offset:2048
	ds_read_b64_tr_b16 v[78:79], v231 offset:2560
	ds_read_b64_tr_b16 v[220:221], v231 offset:1024
	ds_read_b64_tr_b16 v[222:223], v231 offset:1536
	ds_read_b64_tr_b16 v[224:225], v231 offset:3072
	ds_read_b64_tr_b16 v[226:227], v231 offset:3584
	s_waitcnt lgkmcnt(0)
; __device__ __forceinline__ int crow(int r, int hi) { return (r & 3) + 8 * (r >> 2) + 4 * hi; }
; __device__ __forceinline__ void dil_unit(LAS unsigned char* lds, bf16_t* proj, int seq, int hd, int T0, int rho) {
;     ...
;     l += __shfl_xor(l, 32);
; #pragma unroll
;     for (int rr = 0; rr < 16; ++rr) {
;         const int j = crow(rr, hi);
;         const float il = __builtin_amdgcn_rcpf(__shfl(l, j));
	v_exp_f32_e32 v32, v32
	v_exp_f32_e32 v33, v33
	v_exp_f32_e32 v34, v34
	v_exp_f32_e32 v35, v35
	v_exp_f32_e32 v36, v36
	v_exp_f32_e32 v37, v37
	v_exp_f32_e32 v38, v38
	v_exp_f32_e32 v39, v39
	v_exp_f32_e32 v40, v40
	v_exp_f32_e32 v41, v41
	v_exp_f32_e32 v42, v42
	v_exp_f32_e32 v43, v43
	v_exp_f32_e32 v44, v44
	v_exp_f32_e32 v45, v45
	v_exp_f32_e32 v46, v46
	v_exp_f32_e32 v47, v47
	s_add_i32 s90, s76, 1024
	v_lshlrev_b32_e32 v84, 4, v107
	v_add_u32_e32 v84, s90, v84
	v_add_u32_e32 v85, 0, v84
	v_add_u32_e32 v86, 16, v84
	v_add_u32_e32 v87, 32, v84
	v_add_u32_e32 v88, 48, v84
	v_cmp_gt_u32_e64 s[30:31], s98, v85
	v_cmp_gt_u32_e64 s[36:37], s98, v86
	v_cmp_gt_u32_e64 s[78:79], s98, v87
	v_cmp_gt_u32_e64 s[50:51], s98, v88
	v_cndmask_b32_e64 v32, 0, v32, s[30:31]
	v_add_u32_e32 v85, 128, v84
	v_cmp_gt_u32_e64 s[30:31], s98, v85
	v_cndmask_b32_e64 v33, 0, v33, s[36:37]
	v_add_u32_e32 v86, 144, v84
	v_cmp_gt_u32_e64 s[36:37], s98, v86
	v_cndmask_b32_e64 v34, 0, v34, s[78:79]
	v_add_u32_e32 v87, 160, v84
	v_cmp_gt_u32_e64 s[78:79], s98, v87
	v_cndmask_b32_e64 v35, 0, v35, s[50:51]
	v_add_u32_e32 v88, 176, v84
	v_cmp_gt_u32_e64 s[50:51], s98, v88
	v_cndmask_b32_e64 v36, 0, v36, s[30:31]
	v_add_u32_e32 v85, 256, v84
	v_cmp_gt_u32_e64 s[30:31], s98, v85
	v_cndmask_b32_e64 v37, 0, v37, s[36:37]
	v_add_u32_e32 v86, 272, v84
	v_cmp_gt_u32_e64 s[36:37], s98, v86
	v_cndmask_b32_e64 v38, 0, v38, s[78:79]
	v_add_u32_e32 v87, 288, v84
	v_cmp_gt_u32_e64 s[78:79], s98, v87
	v_cndmask_b32_e64 v39, 0, v39, s[50:51]
	v_add_u32_e32 v88, 304, v84
	v_cmp_gt_u32_e64 s[50:51], s98, v88
	v_cndmask_b32_e64 v40, 0, v40, s[30:31]
	v_add_u32_e32 v85, 384, v84
	v_cmp_gt_u32_e64 s[30:31], s98, v85
	v_cndmask_b32_e64 v41, 0, v41, s[36:37]
	v_add_u32_e32 v86, 400, v84
	v_cmp_gt_u32_e64 s[36:37], s98, v86
	v_cndmask_b32_e64 v42, 0, v42, s[78:79]
	v_add_u32_e32 v87, 416, v84
	v_cmp_gt_u32_e64 s[78:79], s98, v87
	v_cndmask_b32_e64 v43, 0, v43, s[50:51]
	v_add_u32_e32 v88, 432, v84
	v_cmp_gt_u32_e64 s[50:51], s98, v88
	v_nop
	v_cndmask_b32_e64 v44, 0, v44, s[30:31]
	v_cndmask_b32_e64 v45, 0, v45, s[36:37]
	v_cndmask_b32_e64 v46, 0, v46, s[78:79]
	v_cndmask_b32_e64 v47, 0, v47, s[50:51]
	v_cvt_pk_bf16_f32 v64, v32, v33
	v_cvt_pk_bf16_f32 v65, v34, v35
	v_cvt_pk_bf16_f32 v66, v36, v37
	v_cvt_pk_bf16_f32 v67, v38, v39
	v_cvt_pk_bf16_f32 v68, v40, v41
	v_cvt_pk_bf16_f32 v69, v42, v43
	v_cvt_pk_bf16_f32 v70, v44, v45
	v_cvt_pk_bf16_f32 v71, v46, v47
	v_pk_add_f32 v[232:233], v[232:233], v[32:33]
	v_pk_add_f32 v[232:233], v[232:233], v[34:35]
	v_pk_add_f32 v[232:233], v[232:233], v[36:37]
	v_pk_add_f32 v[232:233], v[232:233], v[38:39]
	v_pk_add_f32 v[232:233], v[232:233], v[40:41]
	v_pk_add_f32 v[232:233], v[232:233], v[42:43]
	v_pk_add_f32 v[232:233], v[232:233], v[44:45]
	v_pk_add_f32 v[232:233], v[232:233], v[46:47]
	v_mfma_f32_32x32x16_bf16 v[0:15], v[64:67], v[72:75], v[0:15]
	v_mfma_f32_32x32x16_bf16 v[16:31], v[64:67], v[76:79], v[16:31]
	v_mfma_f32_32x32x16_bf16 v[0:15], v[68:71], v[220:223], v[0:15]
	v_mfma_f32_32x32x16_bf16 v[16:31], v[68:71], v[224:227], v[16:31]
	v_add_f32_e32 v113, v232, v233
	v_or_b32_e32 v114, 1, v107
	v_or_b32_e32 v97, 2, v107
	v_or_b32_e32 v96, 3, v107
	v_or_b32_e32 v95, 8, v107
	v_or_b32_e32 v94, 9, v107
	v_or_b32_e32 v93, 10, v107
	v_or_b32_e32 v92, 11, v107
	v_or_b32_e32 v91, 16, v107
	v_or_b32_e32 v90, 17, v107
	v_or_b32_e32 v89, 18, v107
	v_or_b32_e32 v88, 19, v107
	v_or_b32_e32 v87, 24, v107
	v_or_b32_e32 v86, 25, v107
	v_or_b32_e32 v85, 26, v107
	v_or_b32_e32 v84, 27, v107
	s_nop 11
	s_branch .LBB0_553

; #define LAS __attribute__((address_space(3)))
; #define GAS __attribute__((address_space(1)))
; __device__ __forceinline__ void dil_unit(LAS unsigned char* lds, bf16_t* proj, int seq, int hd, int T0, int rho) {
;     int tid_ = threadIdx.x; asm volatile("" : "+v"(tid_));
;     const int tid = tid_, lane = tid & 63, r32 = lane & 31, hi = lane >> 5, wid = __builtin_amdgcn_readfirstlane(tid >> 6);
;     bf16_t* base = proj + (size_t)seq * SEQ * NIN;
;     LAS unsigned char* wbuf = lds + wid * 4096;
;     const LAS unsigned char* vp = wbuf + ((lane >> 4) & 1) * 32 + (lane & 3) * 8 + (4 * hi + ((lane & 15) >> 2)) * 64;
;     const int P0 = T0 + rho;
;     bf16x8 qr[4];
; #pragma unroll
;     for (int ks = 0; ks < 4; ++ks) qr[ks] = *(const GAS bf16x8*)(base + (size_t)(P0 + 16 * r32) * NIN + PC_LQ + hd * 64 + 16 * ks + 8 * hi);
;     f32x16 o0 = {}, o1 = {}; float l = 0.f;
;     const bool bound = (T0 < 1024) || (T0 >= 15360);
.LBB0_1266:
	s_lshr_b32 s82, s60, 8
	s_mul_i32 s82, s82, 13
	s_add_i32 s82, s82, s60
	s_ashr_i32 s4, s60, 6
	s_mul_hi_i32 s9, s4, 0x2aaaaaab
	s_lshl_b32 s5, s82, 8
	s_lshr_b32 s10, s9, 31
	s_and_b32 s8, s5, 0x3e00
	s_lshl_b32 s5, s82, 3
	s_add_i32 s9, s9, s10
	s_and_b32 s5, s5, 8
	s_mul_i32 s10, s9, 6
	s_add_i32 s5, s5, s61
	s_sub_i32 s10, s4, s10
	s_mul_hi_i32 s4, s9, 0x6000000
	s_mul_i32 s9, s9, 0x6000000
	v_mov_b32_e32 v2, v154
	s_add_u32 s52, s44, s9
	s_addc_u32 s53, s45, s4
	v_and_b32_e32 v105, 31, v2
	s_add_i32 s67, s5, s8
	v_lshl_add_u32 v3, v105, 4, s67
	v_mov_b64_e32 v[0:1], s[52:53]
	s_lshl_b32 s54, s10, 6
	v_bfe_u32 v106, v2, 5, 1
	v_mad_u64_u32 v[0:1], s[4:5], v3, s62, v[0:1]
	s_ashr_i32 s55, s54, 31
	v_lshl_add_u64 v[0:1], s[54:55], 1, v[0:1]
	v_lshlrev_b32_e32 v80, 4, v106
	v_lshl_add_u64 v[0:1], v[0:1], 0, v[80:81]
	global_load_dwordx4 v[48:51], v[0:1], off offset:1280
	global_load_dwordx4 v[52:55], v[0:1], off offset:1312
	global_load_dwordx4 v[56:59], v[0:1], off offset:1344
	global_load_dwordx4 v[60:63], v[0:1], off offset:1376
	v_readfirstlane_b32 s4, v2
	s_lshl_b32 s4, s4, 6
	s_and_b32 s4, s4, 0xfffff000
	v_lshlrev_b32_e32 v0, 1, v2
	v_lshlrev_b32_e32 v104, 3, v2
	v_lshlrev_b32_e32 v107, 2, v106
	v_lshrrev_b32_e32 v1, 2, v2
	v_and_b32_e32 v103, 63, v2
	v_and_b32_e32 v0, 32, v0
	v_and_b32_e32 v98, 24, v104
	v_and_or_b32 v1, v1, 3, v107
	s_add_i32 s69, s4, 0
	v_lshlrev_b32_e32 v108, 6, v1
	v_lshlrev_b32_e32 v1, 3, v106
	v_add3_u32 v109, s69, v0, v98
	s_addk_i32 s8, 0xc400
	v_lshrrev_b32_e32 v110, 2, v103
	v_lshlrev_b32_e32 v0, 4, v103
	s_mov_b64 s[4:5], -1
	s_cmp_gt_u32 s8, 0xffffc7ff
	v_lshlrev_b32_e32 v100, 1, v98
	s_mul_i32 s8, s10, 0x1c00
	v_lshlrev_b32_e32 v82, 1, v1
	v_or_b32_e32 v111, 16, v110
	v_add_u32_e32 v112, s69, v0
	s_cbranch_scc0 .LBB0_1270
	s_movk_i32 s100, 0x1800
	s_add_i32 s101, s8, 0x15c00
	s_lshl_b32 s90, s54, 1
	s_add_u32 s82, s52, s90
	s_addc_u32 s83, s53, 0
	s_add_u32 s82, s82, 0x1200
	s_addc_u32 s83, s83, 0
	s_sub_i32 s90, s67, 64
	s_mul_i32 s90, s90, 0x1800
	s_add_u32 s84, s82, s90
	s_addc_u32 s85, s83, 0
	s_sub_i32 s90, s67, 256
	s_mul_i32 s90, s90, 0x1800
	s_add_u32 s86, s82, s90
	s_addc_u32 s87, s83, 0
	s_sub_i32 s90, s67, 1024
	s_mul_i32 s90, s90, 0x1800
	s_add_u32 s88, s82, s90
	s_addc_u32 s89, s83, 0
	v_lshlrev_b32_e32 v153, 1, v98
	v_mad_u32_u24 v80, v105, s100, v82
	v_mad_u32_u24 v100, v110, s100, v153
	v_add_u32_e32 v149, 0x18000, v100
	v_lshlrev_b32_e32 v83, 2, v105
	v_mad_u32_u24 v83, v83, s100, v82
	v_lshlrev_b32_e32 v101, 2, v110
	v_mad_u32_u24 v101, v101, s100, v153
	v_add_u32_e32 v150, 0x60000, v101
	v_lshlrev_b32_e32 v99, 4, v105
	v_mad_u32_u24 v99, v99, s100, v82
	v_lshlrev_b32_e32 v148, 4, v110
	v_mad_u32_u24 v148, v148, s100, v153
	v_add_u32_e32 v151, 0x180000, v148
	v_lshrrev_b32_e32 v249, 3, v103
	v_and_b32_e32 v250, 7, v103
	v_lshlrev_b32_e32 v250, 4, v250
	v_add_u32_e32 v235, 0, v249
	v_mad_u32_u24 v235, v235, s100, v250
	v_add_u32_e32 v236, 8, v249
	v_mad_u32_u24 v236, v236, s100, v250
	v_add_u32_e32 v237, 16, v249
	v_mad_u32_u24 v237, v237, s100, v250
	v_add_u32_e32 v238, 24, v249
	v_mad_u32_u24 v238, v238, s100, v250
	v_add_u32_e32 v239, 0, v249
	v_lshlrev_b32_e32 v239, 2, v239
	v_mad_u32_u24 v239, v239, s100, v250
	v_add_u32_e32 v240, 8, v249
	v_lshlrev_b32_e32 v240, 2, v240
	v_mad_u32_u24 v240, v240, s100, v250
	v_add_u32_e32 v241, 16, v249
	v_lshlrev_b32_e32 v241, 2, v241
	v_mad_u32_u24 v241, v241, s100, v250
	v_add_u32_e32 v242, 24, v249
	v_lshlrev_b32_e32 v242, 2, v242
	v_mad_u32_u24 v242, v242, s100, v250
	v_add_u32_e32 v243, 0, v249
	v_lshlrev_b32_e32 v243, 4, v243
	v_mad_u32_u24 v243, v243, s100, v250
	v_add_u32_e32 v244, 8, v249
	v_lshlrev_b32_e32 v244, 4, v244
	v_mad_u32_u24 v244, v244, s100, v250
	v_add_u32_e32 v245, 16, v249
	v_lshlrev_b32_e32 v245, 4, v245
	v_mad_u32_u24 v245, v245, s100, v250
	v_add_u32_e32 v246, 24, v249
	v_lshlrev_b32_e32 v246, 4, v246
	v_mad_u32_u24 v246, v246, s100, v250
	v_and_b32_e32 v247, 7, v249
	v_lshlrev_b32_e32 v247, 4, v247
	v_xor_b32_e32 v247, v247, v112
	v_and_b32_e32 v153, 7, v105
	v_or_b32_e32 v248, 0, v106
	v_xor_b32_e32 v248, v248, v153
	v_lshlrev_b32_e32 v248, 4, v248
	v_lshl_add_u32 v248, v105, 7, v248
	v_add_u32_e32 v248, s69, v248
	v_or_b32_e32 v249, 2, v106
	v_xor_b32_e32 v249, v249, v153
	v_lshlrev_b32_e32 v249, 4, v249
	v_lshl_add_u32 v249, v105, 7, v249
	v_add_u32_e32 v249, s69, v249
	v_or_b32_e32 v250, 4, v106
	v_xor_b32_e32 v250, v250, v153
	v_lshlrev_b32_e32 v250, 4, v250
	v_lshl_add_u32 v250, v105, 7, v250
	v_add_u32_e32 v250, s69, v250
	v_or_b32_e32 v251, 6, v106
	v_xor_b32_e32 v251, v251, v153
	v_lshlrev_b32_e32 v251, 4, v251
	v_lshl_add_u32 v251, v105, 7, v251
	v_add_u32_e32 v251, s69, v251
	v_lshlrev_b32_e32 v153, 1, v98
	v_mul_u32_u24_e32 v228, 17, v105
	v_sub_u32_e32 v228, v107, v228
	s_mul_i32 s90, s54, 153
	s_lshr_b32 s90, s90, 1
	s_add_i32 s90, s90, 34876
	v_lshl_add_u32 v228, v228, 2, s90
	v_lshlrev_b32_e32 v229, 2, v105
	v_sub_u32_e32 v229, v107, v229
	s_add_i32 s90, s101, 5104
	v_lshl_add_u32 v229, v229, 2, s90
	v_sub_u32_e32 v230, v107, v105
	s_add_i32 s90, s101, 6364
	v_lshl_add_u32 v230, v230, 2, s90
	v_add_u32_e32 v231, v109, v108
	v_mov_b64_e32 v[232:233], 0
	v_mov_b64_e32 v[0:1], 0
	v_mov_b64_e32 v[2:3], 0
	v_mov_b64_e32 v[4:5], 0
	v_mov_b64_e32 v[6:7], 0
	v_mov_b64_e32 v[8:9], 0
	v_mov_b64_e32 v[10:11], 0
	v_mov_b64_e32 v[12:13], 0
	v_mov_b64_e32 v[14:15], 0
	v_mov_b64_e32 v[16:17], 0
	v_mov_b64_e32 v[18:19], 0
	v_mov_b64_e32 v[20:21], 0
	v_mov_b64_e32 v[22:23], 0
	v_mov_b64_e32 v[24:25], 0
	v_mov_b64_e32 v[26:27], 0
	v_mov_b64_e32 v[28:29], 0
	v_mov_b64_e32 v[30:31], 0
	global_load_dwordx4 v[116:119], v235, s[84:85]
	global_load_dwordx4 v[120:123], v236, s[84:85]
	global_load_dwordx4 v[124:127], v237, s[84:85]
	global_load_dwordx4 v[128:131], v238, s[84:85]
	global_load_dwordx4 v[132:135], v100, s[84:85] offset:768
	global_load_dwordx4 v[136:139], v149, s[84:85] offset:768
	global_load_dwordx4 v[140:143], v100, s[84:85] offset:832
	global_load_dwordx4 v[144:147], v149, s[84:85] offset:832
	s_add_u32 s84, s84, 0x30000
	s_addc_u32 s85, s85, 0
	global_load_dwordx4 v[156:159], v235, s[84:85]
	global_load_dwordx4 v[160:163], v236, s[84:85]
	global_load_dwordx4 v[164:167], v237, s[84:85]
	global_load_dwordx4 v[168:171], v238, s[84:85]
	global_load_dwordx4 v[172:175], v100, s[84:85] offset:768
	global_load_dwordx4 v[176:179], v149, s[84:85] offset:768
	global_load_dwordx4 v[180:183], v100, s[84:85] offset:832
	global_load_dwordx4 v[184:187], v149, s[84:85] offset:832
	s_add_u32 s84, s84, 0x30000
	s_addc_u32 s85, s85, 0
	v_mov_b32_e32 v115, v228
	ds_read2_b32 v[32:33], v115 offset0:0 offset1:1
	ds_read2_b32 v[34:35], v115 offset0:2 offset1:3
	ds_read2_b32 v[36:37], v115 offset0:8 offset1:9
	ds_read2_b32 v[38:39], v115 offset0:10 offset1:11
	ds_read2_b32 v[40:41], v115 offset0:17 offset1:18
	ds_read2_b32 v[42:43], v115 offset0:19 offset1:20
	ds_read2_b32 v[44:45], v115 offset0:25 offset1:26
	ds_read2_b32 v[46:47], v115 offset0:27 offset1:28
	s_waitcnt vmcnt(8)
	ds_write_b128 v247, v[116:119]
	ds_write_b128 v247, v[120:123] offset:1024
	ds_write_b128 v247, v[124:127] offset:2048
	ds_write_b128 v247, v[128:131] offset:3072
	ds_read_b128 v[116:119], v248
	ds_read_b128 v[120:123], v249
	ds_read_b128 v[124:127], v250
	ds_read_b128 v[128:131], v251
	ds_write_b128 v112, v[132:135]
	ds_write_b128 v112, v[136:139] offset:1024
	ds_write_b128 v112, v[140:143] offset:2048
	ds_write_b128 v112, v[144:147] offset:3072
	s_waitcnt lgkmcnt(4)
	v_mfma_f32_32x32x16_bf16 v[32:47], v[116:119], v[48:51], v[32:47]
	v_mfma_f32_32x32x16_bf16 v[32:47], v[120:123], v[52:55], v[32:47]
	v_mfma_f32_32x32x16_bf16 v[32:47], v[124:127], v[56:59], v[32:47]
	v_mfma_f32_32x32x16_bf16 v[32:47], v[128:131], v[60:63], v[32:47]
	ds_read2_b32 v[188:189], v115 offset0:34 offset1:35
	ds_read2_b32 v[190:191], v115 offset0:36 offset1:37
	ds_read2_b32 v[192:193], v115 offset0:42 offset1:43
	ds_read2_b32 v[194:195], v115 offset0:44 offset1:45
	ds_read2_b32 v[196:197], v115 offset0:51 offset1:52
	ds_read2_b32 v[198:199], v115 offset0:53 offset1:54
	ds_read2_b32 v[200:201], v115 offset0:59 offset1:60
	ds_read2_b32 v[202:203], v115 offset0:61 offset1:62
	global_load_dwordx4 v[116:119], v235, s[84:85]
	global_load_dwordx4 v[120:123], v236, s[84:85]
	global_load_dwordx4 v[124:127], v237, s[84:85]
	global_load_dwordx4 v[128:131], v238, s[84:85]
	global_load_dwordx4 v[132:135], v100, s[84:85] offset:768
	global_load_dwordx4 v[136:139], v149, s[84:85] offset:768
	global_load_dwordx4 v[140:143], v100, s[84:85] offset:832
	global_load_dwordx4 v[144:147], v149, s[84:85] offset:832
	s_add_u32 s84, s84, 0x30000
	s_addc_u32 s85, s85, 0
	ds_read_b64_tr_b16 v[72:73], v231
	ds_read_b64_tr_b16 v[74:75], v231 offset:512
	ds_read_b64_tr_b16 v[76:77], v231 offset:2048
	ds_read_b64_tr_b16 v[78:79], v231 offset:2560
	ds_read_b64_tr_b16 v[220:221], v231 offset:1024
	ds_read_b64_tr_b16 v[222:223], v231 offset:1536
	ds_read_b64_tr_b16 v[224:225], v231 offset:3072
	ds_read_b64_tr_b16 v[226:227], v231 offset:3584
	s_waitcnt vmcnt(8)
	ds_write_b128 v247, v[156:159]
	ds_write_b128 v247, v[160:163] offset:1024
	ds_write_b128 v247, v[164:167] offset:2048
	ds_write_b128 v247, v[168:171] offset:3072
	ds_read_b128 v[156:159], v248
	ds_read_b128 v[160:163], v249
	ds_read_b128 v[164:167], v250
	ds_read_b128 v[168:171], v251
	ds_write_b128 v112, v[172:175]
	ds_write_b128 v112, v[176:179] offset:1024
	ds_write_b128 v112, v[180:183] offset:2048
	ds_write_b128 v112, v[184:187] offset:3072
	s_waitcnt lgkmcnt(4)
	v_mfma_f32_32x32x16_bf16 v[188:203], v[156:159], v[48:51], v[188:203]
	v_exp_f32_e32 v32, v32
	v_exp_f32_e32 v33, v33
	v_exp_f32_e32 v34, v34
	v_exp_f32_e32 v35, v35
	v_mfma_f32_32x32x16_bf16 v[188:203], v[160:163], v[52:55], v[188:203]
	v_exp_f32_e32 v36, v36
	v_exp_f32_e32 v37, v37
	v_exp_f32_e32 v38, v38
	v_exp_f32_e32 v39, v39
	v_mfma_f32_32x32x16_bf16 v[188:203], v[164:167], v[56:59], v[188:203]
	v_exp_f32_e32 v40, v40
	v_exp_f32_e32 v41, v41
	v_exp_f32_e32 v42, v42
	v_exp_f32_e32 v43, v43
	v_mfma_f32_32x32x16_bf16 v[188:203], v[168:171], v[60:63], v[188:203]
	v_exp_f32_e32 v44, v44
	v_exp_f32_e32 v45, v45
	v_exp_f32_e32 v46, v46
	v_exp_f32_e32 v47, v47
	v_cvt_pk_bf16_f32 v64, v32, v33
	v_cvt_pk_bf16_f32 v65, v34, v35
	v_cvt_pk_bf16_f32 v66, v36, v37
	v_cvt_pk_bf16_f32 v67, v38, v39
	v_cvt_pk_bf16_f32 v68, v40, v41
	v_cvt_pk_bf16_f32 v69, v42, v43
	v_cvt_pk_bf16_f32 v70, v44, v45
	v_cvt_pk_bf16_f32 v71, v46, v47
	v_pk_add_f32 v[232:233], v[232:233], v[32:33]
	v_pk_add_f32 v[232:233], v[232:233], v[34:35]
	v_pk_add_f32 v[232:233], v[232:233], v[36:37]
	v_pk_add_f32 v[232:233], v[232:233], v[38:39]
	v_pk_add_f32 v[232:233], v[232:233], v[40:41]
	v_pk_add_f32 v[232:233], v[232:233], v[42:43]
	v_pk_add_f32 v[232:233], v[232:233], v[44:45]
	v_pk_add_f32 v[232:233], v[232:233], v[46:47]
	ds_read2_b32 v[32:33], v115 offset0:68 offset1:69
	ds_read2_b32 v[34:35], v115 offset0:70 offset1:71
	ds_read2_b32 v[36:37], v115 offset0:76 offset1:77
	ds_read2_b32 v[38:39], v115 offset0:78 offset1:79
	ds_read2_b32 v[40:41], v115 offset0:85 offset1:86
	ds_read2_b32 v[42:43], v115 offset0:87 offset1:88
	ds_read2_b32 v[44:45], v115 offset0:93 offset1:94
	ds_read2_b32 v[46:47], v115 offset0:95 offset1:96
	v_mfma_f32_32x32x16_bf16 v[0:15], v[64:67], v[72:75], v[0:15]
	v_mfma_f32_32x32x16_bf16 v[16:31], v[64:67], v[76:79], v[16:31]
	v_mfma_f32_32x32x16_bf16 v[0:15], v[68:71], v[220:223], v[0:15]
	v_mfma_f32_32x32x16_bf16 v[16:31], v[68:71], v[224:227], v[16:31]
	global_load_dwordx4 v[156:159], v235, s[84:85]
	global_load_dwordx4 v[160:163], v236, s[84:85]
	global_load_dwordx4 v[164:167], v237, s[84:85]
	global_load_dwordx4 v[168:171], v238, s[84:85]
	global_load_dwordx4 v[172:175], v100, s[84:85] offset:768
	global_load_dwordx4 v[176:179], v149, s[84:85] offset:768
	global_load_dwordx4 v[180:183], v100, s[84:85] offset:832
	global_load_dwordx4 v[184:187], v149, s[84:85] offset:832
	s_add_u32 s84, s84, 0x30000
	s_addc_u32 s85, s85, 0
	ds_read_b64_tr_b16 v[72:73], v231
	ds_read_b64_tr_b16 v[74:75], v231 offset:512
	ds_read_b64_tr_b16 v[76:77], v231 offset:2048
	ds_read_b64_tr_b16 v[78:79], v231 offset:2560
	ds_read_b64_tr_b16 v[220:221], v231 offset:1024
	ds_read_b64_tr_b16 v[222:223], v231 offset:1536
	ds_read_b64_tr_b16 v[224:225], v231 offset:3072
	ds_read_b64_tr_b16 v[226:227], v231 offset:3584
	s_waitcnt vmcnt(8)
	ds_write_b128 v247, v[116:119]
	ds_write_b128 v247, v[120:123] offset:1024
	ds_write_b128 v247, v[124:127] offset:2048
	ds_write_b128 v247, v[128:131] offset:3072
	ds_read_b128 v[116:119], v248
	ds_read_b128 v[120:123], v249
	ds_read_b128 v[124:127], v250
	ds_read_b128 v[128:131], v251
	ds_write_b128 v112, v[132:135]
	ds_write_b128 v112, v[136:139] offset:1024
	ds_write_b128 v112, v[140:143] offset:2048
	ds_write_b128 v112, v[144:147] offset:3072
	s_waitcnt lgkmcnt(4)
	v_mfma_f32_32x32x16_bf16 v[32:47], v[116:119], v[48:51], v[32:47]
	v_exp_f32_e32 v188, v188
	v_exp_f32_e32 v189, v189
	v_exp_f32_e32 v190, v190
	v_exp_f32_e32 v191, v191
	v_mfma_f32_32x32x16_bf16 v[32:47], v[120:123], v[52:55], v[32:47]
	v_exp_f32_e32 v192, v192
	v_exp_f32_e32 v193, v193
	v_exp_f32_e32 v194, v194
	v_exp_f32_e32 v195, v195
	v_mfma_f32_32x32x16_bf16 v[32:47], v[124:127], v[56:59], v[32:47]
	v_exp_f32_e32 v196, v196
	v_exp_f32_e32 v197, v197
	v_exp_f32_e32 v198, v198
	v_exp_f32_e32 v199, v199
	v_mfma_f32_32x32x16_bf16 v[32:47], v[128:131], v[60:63], v[32:47]
	v_exp_f32_e32 v200, v200
	v_exp_f32_e32 v201, v201
	v_exp_f32_e32 v202, v202
	v_exp_f32_e32 v203, v203
	v_cvt_pk_bf16_f32 v64, v188, v189
	v_cvt_pk_bf16_f32 v65, v190, v191
	v_cvt_pk_bf16_f32 v66, v192, v193
	v_cvt_pk_bf16_f32 v67, v194, v195
	v_cvt_pk_bf16_f32 v68, v196, v197
	v_cvt_pk_bf16_f32 v69, v198, v199
	v_cvt_pk_bf16_f32 v70, v200, v201
	v_cvt_pk_bf16_f32 v71, v202, v203
	v_pk_add_f32 v[232:233], v[232:233], v[188:189]
	v_pk_add_f32 v[232:233], v[232:233], v[190:191]
	v_pk_add_f32 v[232:233], v[232:233], v[192:193]
	v_pk_add_f32 v[232:233], v[232:233], v[194:195]
	v_pk_add_f32 v[232:233], v[232:233], v[196:197]
	v_pk_add_f32 v[232:233], v[232:233], v[198:199]
	v_pk_add_f32 v[232:233], v[232:233], v[200:201]
	v_pk_add_f32 v[232:233], v[232:233], v[202:203]
	ds_read2_b32 v[188:189], v115 offset0:102 offset1:103
	ds_read2_b32 v[190:191], v115 offset0:104 offset1:105
	ds_read2_b32 v[192:193], v115 offset0:110 offset1:111
	ds_read2_b32 v[194:195], v115 offset0:112 offset1:113
	ds_read2_b32 v[196:197], v115 offset0:119 offset1:120
	ds_read2_b32 v[198:199], v115 offset0:121 offset1:122
	ds_read2_b32 v[200:201], v115 offset0:127 offset1:128
	ds_read2_b32 v[202:203], v115 offset0:129 offset1:130
	v_mfma_f32_32x32x16_bf16 v[0:15], v[64:67], v[72:75], v[0:15]
	v_mfma_f32_32x32x16_bf16 v[16:31], v[64:67], v[76:79], v[16:31]
	v_mfma_f32_32x32x16_bf16 v[0:15], v[68:71], v[220:223], v[0:15]
	v_mfma_f32_32x32x16_bf16 v[16:31], v[68:71], v[224:227], v[16:31]
	global_load_dwordx4 v[116:119], v235, s[84:85]
	global_load_dwordx4 v[120:123], v236, s[84:85]
	global_load_dwordx4 v[124:127], v237, s[84:85]
	global_load_dwordx4 v[128:131], v238, s[84:85]
	global_load_dwordx4 v[132:135], v100, s[84:85] offset:768
	global_load_dwordx4 v[136:139], v149, s[84:85] offset:768
	global_load_dwordx4 v[140:143], v100, s[84:85] offset:832
	global_load_dwordx4 v[144:147], v149, s[84:85] offset:832
	s_add_u32 s84, s84, 0x30000
	s_addc_u32 s85, s85, 0
	ds_read_b64_tr_b16 v[72:73], v231
	ds_read_b64_tr_b16 v[74:75], v231 offset:512
	ds_read_b64_tr_b16 v[76:77], v231 offset:2048
	ds_read_b64_tr_b16 v[78:79], v231 offset:2560
	ds_read_b64_tr_b16 v[220:221], v231 offset:1024
	ds_read_b64_tr_b16 v[222:223], v231 offset:1536
	ds_read_b64_tr_b16 v[224:225], v231 offset:3072
	ds_read_b64_tr_b16 v[226:227], v231 offset:3584
	s_waitcnt vmcnt(8)
	ds_write_b128 v247, v[156:159]
	ds_write_b128 v247, v[160:163] offset:1024
	ds_write_b128 v247, v[164:167] offset:2048
	ds_write_b128 v247, v[168:171] offset:3072
	ds_read_b128 v[156:159], v248
	ds_read_b128 v[160:163], v249
	ds_read_b128 v[164:167], v250
	ds_read_b128 v[168:171], v251
	ds_write_b128 v112, v[172:175]
	ds_write_b128 v112, v[176:179] offset:1024
	ds_write_b128 v112, v[180:183] offset:2048
	ds_write_b128 v112, v[184:187] offset:3072
	s_waitcnt lgkmcnt(4)
	v_mfma_f32_32x32x16_bf16 v[188:203], v[156:159], v[48:51], v[188:203]
	v_exp_f32_e32 v32, v32
	v_exp_f32_e32 v33, v33
	v_exp_f32_e32 v34, v34
	v_exp_f32_e32 v35, v35
	v_mfma_f32_32x32x16_bf16 v[188:203], v[160:163], v[52:55], v[188:203]
	v_exp_f32_e32 v36, v36
	v_exp_f32_e32 v37, v37
	v_exp_f32_e32 v38, v38
	v_exp_f32_e32 v39, v39
	v_mfma_f32_32x32x16_bf16 v[188:203], v[164:167], v[56:59], v[188:203]
	v_exp_f32_e32 v40, v40
	v_exp_f32_e32 v41, v41
	v_exp_f32_e32 v42, v42
	v_exp_f32_e32 v43, v43
	v_mfma_f32_32x32x16_bf16 v[188:203], v[168:171], v[60:63], v[188:203]
	v_exp_f32_e32 v44, v44
	v_exp_f32_e32 v45, v45
	v_exp_f32_e32 v46, v46
	v_exp_f32_e32 v47, v47
	v_cvt_pk_bf16_f32 v64, v32, v33
	v_cvt_pk_bf16_f32 v65, v34, v35
	v_cvt_pk_bf16_f32 v66, v36, v37
	v_cvt_pk_bf16_f32 v67, v38, v39
	v_cvt_pk_bf16_f32 v68, v40, v41
	v_cvt_pk_bf16_f32 v69, v42, v43
	v_cvt_pk_bf16_f32 v70, v44, v45
	v_cvt_pk_bf16_f32 v71, v46, v47
	v_pk_add_f32 v[232:233], v[232:233], v[32:33]
	v_pk_add_f32 v[232:233], v[232:233], v[34:35]
	v_pk_add_f32 v[232:233], v[232:233], v[36:37]
	v_pk_add_f32 v[232:233], v[232:233], v[38:39]
	v_pk_add_f32 v[232:233], v[232:233], v[40:41]
	v_pk_add_f32 v[232:233], v[232:233], v[42:43]
	v_pk_add_f32 v[232:233], v[232:233], v[44:45]
	v_pk_add_f32 v[232:233], v[232:233], v[46:47]
	ds_read2_b32 v[32:33], v115 offset0:136 offset1:137
	ds_read2_b32 v[34:35], v115 offset0:138 offset1:139
	ds_read2_b32 v[36:37], v115 offset0:144 offset1:145
	ds_read2_b32 v[38:39], v115 offset0:146 offset1:147
	ds_read2_b32 v[40:41], v115 offset0:153 offset1:154
	ds_read2_b32 v[42:43], v115 offset0:155 offset1:156
	ds_read2_b32 v[44:45], v115 offset0:161 offset1:162
	ds_read2_b32 v[46:47], v115 offset0:163 offset1:164
	v_mfma_f32_32x32x16_bf16 v[0:15], v[64:67], v[72:75], v[0:15]
	v_mfma_f32_32x32x16_bf16 v[16:31], v[64:67], v[76:79], v[16:31]
	v_mfma_f32_32x32x16_bf16 v[0:15], v[68:71], v[220:223], v[0:15]
	v_mfma_f32_32x32x16_bf16 v[16:31], v[68:71], v[224:227], v[16:31]
	global_load_dwordx4 v[156:159], v235, s[84:85]
	global_load_dwordx4 v[160:163], v236, s[84:85]
	global_load_dwordx4 v[164:167], v237, s[84:85]
	global_load_dwordx4 v[168:171], v238, s[84:85]
	global_load_dwordx4 v[172:175], v100, s[84:85] offset:768
	global_load_dwordx4 v[176:179], v149, s[84:85] offset:768
	global_load_dwordx4 v[180:183], v100, s[84:85] offset:832
	global_load_dwordx4 v[184:187], v149, s[84:85] offset:832
	s_add_u32 s84, s84, 0x30000
	s_addc_u32 s85, s85, 0
	ds_read_b64_tr_b16 v[72:73], v231
	ds_read_b64_tr_b16 v[74:75], v231 offset:512
	ds_read_b64_tr_b16 v[76:77], v231 offset:2048
	ds_read_b64_tr_b16 v[78:79], v231 offset:2560
	ds_read_b64_tr_b16 v[220:221], v231 offset:1024
	ds_read_b64_tr_b16 v[222:223], v231 offset:1536
	ds_read_b64_tr_b16 v[224:225], v231 offset:3072
	ds_read_b64_tr_b16 v[226:227], v231 offset:3584
	s_waitcnt vmcnt(8)
	ds_write_b128 v247, v[116:119]
	ds_write_b128 v247, v[120:123] offset:1024
	ds_write_b128 v247, v[124:127] offset:2048
	ds_write_b128 v247, v[128:131] offset:3072
	ds_read_b128 v[116:119], v248
	ds_read_b128 v[120:123], v249
	ds_read_b128 v[124:127], v250
	ds_read_b128 v[128:131], v251
	ds_write_b128 v112, v[132:135]
	ds_write_b128 v112, v[136:139] offset:1024
	ds_write_b128 v112, v[140:143] offset:2048
	ds_write_b128 v112, v[144:147] offset:3072
	s_waitcnt lgkmcnt(4)
	v_mfma_f32_32x32x16_bf16 v[32:47], v[116:119], v[48:51], v[32:47]
	v_exp_f32_e32 v188, v188
	v_exp_f32_e32 v189, v189
	v_exp_f32_e32 v190, v190
	v_exp_f32_e32 v191, v191
	v_mfma_f32_32x32x16_bf16 v[32:47], v[120:123], v[52:55], v[32:47]
	v_exp_f32_e32 v192, v192
	v_exp_f32_e32 v193, v193
	v_exp_f32_e32 v194, v194
	v_exp_f32_e32 v195, v195
	v_mfma_f32_32x32x16_bf16 v[32:47], v[124:127], v[56:59], v[32:47]
	v_exp_f32_e32 v196, v196
	v_exp_f32_e32 v197, v197
	v_exp_f32_e32 v198, v198
	v_exp_f32_e32 v199, v199
	v_mfma_f32_32x32x16_bf16 v[32:47], v[128:131], v[60:63], v[32:47]
	v_exp_f32_e32 v200, v200
	v_exp_f32_e32 v201, v201
	v_exp_f32_e32 v202, v202
	v_exp_f32_e32 v203, v203
	v_cvt_pk_bf16_f32 v64, v188, v189
	v_cvt_pk_bf16_f32 v65, v190, v191
	v_cvt_pk_bf16_f32 v66, v192, v193
	v_cvt_pk_bf16_f32 v67, v194, v195
	v_cvt_pk_bf16_f32 v68, v196, v197
	v_cvt_pk_bf16_f32 v69, v198, v199
	v_cvt_pk_bf16_f32 v70, v200, v201
	v_cvt_pk_bf16_f32 v71, v202, v203
	v_pk_add_f32 v[232:233], v[232:233], v[188:189]
	v_pk_add_f32 v[232:233], v[232:233], v[190:191]
	v_pk_add_f32 v[232:233], v[232:233], v[192:193]
	v_pk_add_f32 v[232:233], v[232:233], v[194:195]
	v_pk_add_f32 v[232:233], v[232:233], v[196:197]
	v_pk_add_f32 v[232:233], v[232:233], v[198:199]
	v_pk_add_f32 v[232:233], v[232:233], v[200:201]
	v_pk_add_f32 v[232:233], v[232:233], v[202:203]
	ds_read2_b32 v[188:189], v115 offset0:170 offset1:171
	ds_read2_b32 v[190:191], v115 offset0:172 offset1:173
	ds_read2_b32 v[192:193], v115 offset0:178 offset1:179
	ds_read2_b32 v[194:195], v115 offset0:180 offset1:181
	ds_read2_b32 v[196:197], v115 offset0:187 offset1:188
	ds_read2_b32 v[198:199], v115 offset0:189 offset1:190
	ds_read2_b32 v[200:201], v115 offset0:195 offset1:196
	ds_read2_b32 v[202:203], v115 offset0:197 offset1:198
	v_mfma_f32_32x32x16_bf16 v[0:15], v[64:67], v[72:75], v[0:15]
	v_mfma_f32_32x32x16_bf16 v[16:31], v[64:67], v[76:79], v[16:31]
	v_mfma_f32_32x32x16_bf16 v[0:15], v[68:71], v[220:223], v[0:15]
	v_mfma_f32_32x32x16_bf16 v[16:31], v[68:71], v[224:227], v[16:31]
	global_load_dwordx4 v[116:119], v235, s[84:85]
	global_load_dwordx4 v[120:123], v236, s[84:85]
	global_load_dwordx4 v[124:127], v237, s[84:85]
	global_load_dwordx4 v[128:131], v238, s[84:85]
	global_load_dwordx4 v[132:135], v100, s[84:85] offset:768
	global_load_dwordx4 v[136:139], v149, s[84:85] offset:768
	global_load_dwordx4 v[140:143], v100, s[84:85] offset:832
	global_load_dwordx4 v[144:147], v149, s[84:85] offset:832
	s_add_u32 s84, s84, 0x30000
	s_addc_u32 s85, s85, 0
	ds_read_b64_tr_b16 v[72:73], v231
	ds_read_b64_tr_b16 v[74:75], v231 offset:512
	ds_read_b64_tr_b16 v[76:77], v231 offset:2048
	ds_read_b64_tr_b16 v[78:79], v231 offset:2560
	ds_read_b64_tr_b16 v[220:221], v231 offset:1024
	ds_read_b64_tr_b16 v[222:223], v231 offset:1536
	ds_read_b64_tr_b16 v[224:225], v231 offset:3072
	ds_read_b64_tr_b16 v[226:227], v231 offset:3584
	s_waitcnt vmcnt(8)
	ds_write_b128 v247, v[156:159]
	ds_write_b128 v247, v[160:163] offset:1024
	ds_write_b128 v247, v[164:167] offset:2048
	ds_write_b128 v247, v[168:171] offset:3072
	ds_read_b128 v[156:159], v248
	ds_read_b128 v[160:163], v249
	ds_read_b128 v[164:167], v250
	ds_read_b128 v[168:171], v251
	ds_write_b128 v112, v[172:175]
	ds_write_b128 v112, v[176:179] offset:1024
	ds_write_b128 v112, v[180:183] offset:2048
	ds_write_b128 v112, v[184:187] offset:3072
	s_waitcnt lgkmcnt(4)
	v_mfma_f32_32x32x16_bf16 v[188:203], v[156:159], v[48:51], v[188:203]
	v_exp_f32_e32 v32, v32
	v_exp_f32_e32 v33, v33
	v_exp_f32_e32 v34, v34
	v_exp_f32_e32 v35, v35
	v_mfma_f32_32x32x16_bf16 v[188:203], v[160:163], v[52:55], v[188:203]
	v_exp_f32_e32 v36, v36
	v_exp_f32_e32 v37, v37
	v_exp_f32_e32 v38, v38
	v_exp_f32_e32 v39, v39
	v_mfma_f32_32x32x16_bf16 v[188:203], v[164:167], v[56:59], v[188:203]
	v_exp_f32_e32 v40, v40
	v_exp_f32_e32 v41, v41
	v_exp_f32_e32 v42, v42
	v_exp_f32_e32 v43, v43
	v_mfma_f32_32x32x16_bf16 v[188:203], v[168:171], v[60:63], v[188:203]
	v_exp_f32_e32 v44, v44
	v_exp_f32_e32 v45, v45
	v_exp_f32_e32 v46, v46
	v_exp_f32_e32 v47, v47
	v_cvt_pk_bf16_f32 v64, v32, v33
	v_cvt_pk_bf16_f32 v65, v34, v35
	v_cvt_pk_bf16_f32 v66, v36, v37
	v_cvt_pk_bf16_f32 v67, v38, v39
	v_cvt_pk_bf16_f32 v68, v40, v41
	v_cvt_pk_bf16_f32 v69, v42, v43
	v_cvt_pk_bf16_f32 v70, v44, v45
	v_cvt_pk_bf16_f32 v71, v46, v47
	v_pk_add_f32 v[232:233], v[232:233], v[32:33]
	v_pk_add_f32 v[232:233], v[232:233], v[34:35]
	v_pk_add_f32 v[232:233], v[232:233], v[36:37]
	v_pk_add_f32 v[232:233], v[232:233], v[38:39]
	v_pk_add_f32 v[232:233], v[232:233], v[40:41]
	v_pk_add_f32 v[232:233], v[232:233], v[42:43]
	v_pk_add_f32 v[232:233], v[232:233], v[44:45]
	v_pk_add_f32 v[232:233], v[232:233], v[46:47]
	ds_read2_b32 v[32:33], v115 offset0:204 offset1:205
	ds_read2_b32 v[34:35], v115 offset0:206 offset1:207
	ds_read2_b32 v[36:37], v115 offset0:212 offset1:213
	ds_read2_b32 v[38:39], v115 offset0:214 offset1:215
	ds_read2_b32 v[40:41], v115 offset0:221 offset1:222
	ds_read2_b32 v[42:43], v115 offset0:223 offset1:224
	ds_read2_b32 v[44:45], v115 offset0:229 offset1:230
	ds_read2_b32 v[46:47], v115 offset0:231 offset1:232
	v_mfma_f32_32x32x16_bf16 v[0:15], v[64:67], v[72:75], v[0:15]
	v_mfma_f32_32x32x16_bf16 v[16:31], v[64:67], v[76:79], v[16:31]
	v_mfma_f32_32x32x16_bf16 v[0:15], v[68:71], v[220:223], v[0:15]
	v_mfma_f32_32x32x16_bf16 v[16:31], v[68:71], v[224:227], v[16:31]
	global_load_dwordx4 v[156:159], v235, s[84:85]
	global_load_dwordx4 v[160:163], v236, s[84:85]
	global_load_dwordx4 v[164:167], v237, s[84:85]
	global_load_dwordx4 v[168:171], v238, s[84:85]
	global_load_dwordx4 v[172:175], v100, s[84:85] offset:768
	global_load_dwordx4 v[176:179], v149, s[84:85] offset:768
	global_load_dwordx4 v[180:183], v100, s[84:85] offset:832
	global_load_dwordx4 v[184:187], v149, s[84:85] offset:832
	s_add_u32 s84, s84, 0x30000
	s_addc_u32 s85, s85, 0
	ds_read_b64_tr_b16 v[72:73], v231
	ds_read_b64_tr_b16 v[74:75], v231 offset:512
	ds_read_b64_tr_b16 v[76:77], v231 offset:2048
	ds_read_b64_tr_b16 v[78:79], v231 offset:2560
	ds_read_b64_tr_b16 v[220:221], v231 offset:1024
	ds_read_b64_tr_b16 v[222:223], v231 offset:1536
	ds_read_b64_tr_b16 v[224:225], v231 offset:3072
	ds_read_b64_tr_b16 v[226:227], v231 offset:3584
	s_waitcnt vmcnt(8)
	ds_write_b128 v247, v[116:119]
	ds_write_b128 v247, v[120:123] offset:1024
	ds_write_b128 v247, v[124:127] offset:2048
	ds_write_b128 v247, v[128:131] offset:3072
	ds_read_b128 v[116:119], v248
	ds_read_b128 v[120:123], v249
	ds_read_b128 v[124:127], v250
	ds_read_b128 v[128:131], v251
	ds_write_b128 v112, v[132:135]
	ds_write_b128 v112, v[136:139] offset:1024
	ds_write_b128 v112, v[140:143] offset:2048
	ds_write_b128 v112, v[144:147] offset:3072
	s_waitcnt lgkmcnt(4)
	v_mfma_f32_32x32x16_bf16 v[32:47], v[116:119], v[48:51], v[32:47]
	v_exp_f32_e32 v188, v188
	v_exp_f32_e32 v189, v189
	v_exp_f32_e32 v190, v190
	v_exp_f32_e32 v191, v191
	v_mfma_f32_32x32x16_bf16 v[32:47], v[120:123], v[52:55], v[32:47]
	v_exp_f32_e32 v192, v192
	v_exp_f32_e32 v193, v193
	v_exp_f32_e32 v194, v194
	v_exp_f32_e32 v195, v195
	v_mfma_f32_32x32x16_bf16 v[32:47], v[124:127], v[56:59], v[32:47]
	v_exp_f32_e32 v196, v196
	v_exp_f32_e32 v197, v197
	v_exp_f32_e32 v198, v198
	v_exp_f32_e32 v199, v199
	v_mfma_f32_32x32x16_bf16 v[32:47], v[128:131], v[60:63], v[32:47]
	v_exp_f32_e32 v200, v200
	v_exp_f32_e32 v201, v201
	v_exp_f32_e32 v202, v202
	v_exp_f32_e32 v203, v203
	v_cvt_pk_bf16_f32 v64, v188, v189
	v_cvt_pk_bf16_f32 v65, v190, v191
	v_cvt_pk_bf16_f32 v66, v192, v193
	v_cvt_pk_bf16_f32 v67, v194, v195
	v_cvt_pk_bf16_f32 v68, v196, v197
	v_cvt_pk_bf16_f32 v69, v198, v199
	v_cvt_pk_bf16_f32 v70, v200, v201
	v_cvt_pk_bf16_f32 v71, v202, v203
	v_pk_add_f32 v[232:233], v[232:233], v[188:189]
	v_pk_add_f32 v[232:233], v[232:233], v[190:191]
	v_pk_add_f32 v[232:233], v[232:233], v[192:193]
	v_pk_add_f32 v[232:233], v[232:233], v[194:195]
	v_pk_add_f32 v[232:233], v[232:233], v[196:197]
	v_pk_add_f32 v[232:233], v[232:233], v[198:199]
	v_pk_add_f32 v[232:233], v[232:233], v[200:201]
	v_pk_add_f32 v[232:233], v[232:233], v[202:203]
	v_add_u32_e32 v115, 952, v115
	ds_read2_b32 v[188:189], v115 offset0:0 offset1:1
	ds_read2_b32 v[190:191], v115 offset0:2 offset1:3
	ds_read2_b32 v[192:193], v115 offset0:8 offset1:9
	ds_read2_b32 v[194:195], v115 offset0:10 offset1:11
	ds_read2_b32 v[196:197], v115 offset0:17 offset1:18
	ds_read2_b32 v[198:199], v115 offset0:19 offset1:20
	ds_read2_b32 v[200:201], v115 offset0:25 offset1:26
	ds_read2_b32 v[202:203], v115 offset0:27 offset1:28
	v_mfma_f32_32x32x16_bf16 v[0:15], v[64:67], v[72:75], v[0:15]
	v_mfma_f32_32x32x16_bf16 v[16:31], v[64:67], v[76:79], v[16:31]
	v_mfma_f32_32x32x16_bf16 v[0:15], v[68:71], v[220:223], v[0:15]
	v_mfma_f32_32x32x16_bf16 v[16:31], v[68:71], v[224:227], v[16:31]
	global_load_dwordx4 v[116:119], v235, s[84:85]
	global_load_dwordx4 v[120:123], v236, s[84:85]
	global_load_dwordx4 v[124:127], v237, s[84:85]
	global_load_dwordx4 v[128:131], v238, s[84:85]
	global_load_dwordx4 v[132:135], v100, s[84:85] offset:768
	global_load_dwordx4 v[136:139], v149, s[84:85] offset:768
	global_load_dwordx4 v[140:143], v100, s[84:85] offset:832
	global_load_dwordx4 v[144:147], v149, s[84:85] offset:832
	s_add_u32 s84, s84, 0x30000
	s_addc_u32 s85, s85, 0
	ds_read_b64_tr_b16 v[72:73], v231
	ds_read_b64_tr_b16 v[74:75], v231 offset:512
	ds_read_b64_tr_b16 v[76:77], v231 offset:2048
	ds_read_b64_tr_b16 v[78:79], v231 offset:2560
	ds_read_b64_tr_b16 v[220:221], v231 offset:1024
	ds_read_b64_tr_b16 v[222:223], v231 offset:1536
	ds_read_b64_tr_b16 v[224:225], v231 offset:3072
	ds_read_b64_tr_b16 v[226:227], v231 offset:3584
	s_waitcnt vmcnt(8)
	ds_write_b128 v247, v[156:159]
	ds_write_b128 v247, v[160:163] offset:1024
	ds_write_b128 v247, v[164:167] offset:2048
	ds_write_b128 v247, v[168:171] offset:3072
	ds_read_b128 v[156:159], v248
	ds_read_b128 v[160:163], v249
	ds_read_b128 v[164:167], v250
	ds_read_b128 v[168:171], v251
	ds_write_b128 v112, v[172:175]
	ds_write_b128 v112, v[176:179] offset:1024
	ds_write_b128 v112, v[180:183] offset:2048
	ds_write_b128 v112, v[184:187] offset:3072
	s_waitcnt lgkmcnt(4)
	v_mfma_f32_32x32x16_bf16 v[188:203], v[156:159], v[48:51], v[188:203]
	v_exp_f32_e32 v32, v32
	v_exp_f32_e32 v33, v33
	v_exp_f32_e32 v34, v34
	v_exp_f32_e32 v35, v35
	v_mfma_f32_32x32x16_bf16 v[188:203], v[160:163], v[52:55], v[188:203]
	v_exp_f32_e32 v36, v36
	v_exp_f32_e32 v37, v37
	v_exp_f32_e32 v38, v38
	v_exp_f32_e32 v39, v39
	v_mfma_f32_32x32x16_bf16 v[188:203], v[164:167], v[56:59], v[188:203]
	v_exp_f32_e32 v40, v40
	v_exp_f32_e32 v41, v41
	v_exp_f32_e32 v42, v42
	v_exp_f32_e32 v43, v43
	v_mfma_f32_32x32x16_bf16 v[188:203], v[168:171], v[60:63], v[188:203]
	v_exp_f32_e32 v44, v44
	v_exp_f32_e32 v45, v45
	v_exp_f32_e32 v46, v46
	v_exp_f32_e32 v47, v47
	v_cvt_pk_bf16_f32 v64, v32, v33
	v_cvt_pk_bf16_f32 v65, v34, v35
	v_cvt_pk_bf16_f32 v66, v36, v37
	v_cvt_pk_bf16_f32 v67, v38, v39
	v_cvt_pk_bf16_f32 v68, v40, v41
	v_cvt_pk_bf16_f32 v69, v42, v43
	v_cvt_pk_bf16_f32 v70, v44, v45
	v_cvt_pk_bf16_f32 v71, v46, v47
	v_pk_add_f32 v[232:233], v[232:233], v[32:33]
	v_pk_add_f32 v[232:233], v[232:233], v[34:35]
	v_pk_add_f32 v[232:233], v[232:233], v[36:37]
	v_pk_add_f32 v[232:233], v[232:233], v[38:39]
	v_pk_add_f32 v[232:233], v[232:233], v[40:41]
	v_pk_add_f32 v[232:233], v[232:233], v[42:43]
	v_pk_add_f32 v[232:233], v[232:233], v[44:45]
	v_pk_add_f32 v[232:233], v[232:233], v[46:47]
	ds_read2_b32 v[32:33], v115 offset0:34 offset1:35
	ds_read2_b32 v[34:35], v115 offset0:36 offset1:37
	ds_read2_b32 v[36:37], v115 offset0:42 offset1:43
	ds_read2_b32 v[38:39], v115 offset0:44 offset1:45
	ds_read2_b32 v[40:41], v115 offset0:51 offset1:52
	ds_read2_b32 v[42:43], v115 offset0:53 offset1:54
	ds_read2_b32 v[44:45], v115 offset0:59 offset1:60
	ds_read2_b32 v[46:47], v115 offset0:61 offset1:62
	v_mfma_f32_32x32x16_bf16 v[0:15], v[64:67], v[72:75], v[0:15]
	v_mfma_f32_32x32x16_bf16 v[16:31], v[64:67], v[76:79], v[16:31]
	v_mfma_f32_32x32x16_bf16 v[0:15], v[68:71], v[220:223], v[0:15]
	v_mfma_f32_32x32x16_bf16 v[16:31], v[68:71], v[224:227], v[16:31]
	global_load_dwordx4 v[156:159], v235, s[84:85]
	global_load_dwordx4 v[160:163], v236, s[84:85]
	global_load_dwordx4 v[164:167], v237, s[84:85]
	global_load_dwordx4 v[168:171], v238, s[84:85]
	global_load_dwordx4 v[172:175], v100, s[84:85] offset:768
	global_load_dwordx4 v[176:179], v149, s[84:85] offset:768
	global_load_dwordx4 v[180:183], v100, s[84:85] offset:832
	global_load_dwordx4 v[184:187], v149, s[84:85] offset:832
	s_add_u32 s84, s84, 0x30000
	s_addc_u32 s85, s85, 0
	ds_read_b64_tr_b16 v[72:73], v231
	ds_read_b64_tr_b16 v[74:75], v231 offset:512
	ds_read_b64_tr_b16 v[76:77], v231 offset:2048
	ds_read_b64_tr_b16 v[78:79], v231 offset:2560
	ds_read_b64_tr_b16 v[220:221], v231 offset:1024
	ds_read_b64_tr_b16 v[222:223], v231 offset:1536
	ds_read_b64_tr_b16 v[224:225], v231 offset:3072
	ds_read_b64_tr_b16 v[226:227], v231 offset:3584
	s_waitcnt vmcnt(8)
	ds_write_b128 v247, v[116:119]
	ds_write_b128 v247, v[120:123] offset:1024
	ds_write_b128 v247, v[124:127] offset:2048
	ds_write_b128 v247, v[128:131] offset:3072
	ds_read_b128 v[116:119], v248
	ds_read_b128 v[120:123], v249
	ds_read_b128 v[124:127], v250
	ds_read_b128 v[128:131], v251
	ds_write_b128 v112, v[132:135]
	ds_write_b128 v112, v[136:139] offset:1024
	ds_write_b128 v112, v[140:143] offset:2048
	ds_write_b128 v112, v[144:147] offset:3072
	s_waitcnt lgkmcnt(4)
	v_mfma_f32_32x32x16_bf16 v[32:47], v[116:119], v[48:51], v[32:47]
	v_exp_f32_e32 v188, v188
	v_exp_f32_e32 v189, v189
	v_exp_f32_e32 v190, v190
	v_exp_f32_e32 v191, v191
	v_mfma_f32_32x32x16_bf16 v[32:47], v[120:123], v[52:55], v[32:47]
	v_exp_f32_e32 v192, v192
	v_exp_f32_e32 v193, v193
	v_exp_f32_e32 v194, v194
	v_exp_f32_e32 v195, v195
	v_mfma_f32_32x32x16_bf16 v[32:47], v[124:127], v[56:59], v[32:47]
	v_exp_f32_e32 v196, v196
	v_exp_f32_e32 v197, v197
	v_exp_f32_e32 v198, v198
	v_exp_f32_e32 v199, v199
	v_mfma_f32_32x32x16_bf16 v[32:47], v[128:131], v[60:63], v[32:47]
	v_exp_f32_e32 v200, v200
	v_exp_f32_e32 v201, v201
	v_exp_f32_e32 v202, v202
	v_exp_f32_e32 v203, v203
	v_cvt_pk_bf16_f32 v64, v188, v189
	v_cvt_pk_bf16_f32 v65, v190, v191
	v_cvt_pk_bf16_f32 v66, v192, v193
	v_cvt_pk_bf16_f32 v67, v194, v195
	v_cvt_pk_bf16_f32 v68, v196, v197
	v_cvt_pk_bf16_f32 v69, v198, v199
	v_cvt_pk_bf16_f32 v70, v200, v201
	v_cvt_pk_bf16_f32 v71, v202, v203
	v_pk_add_f32 v[232:233], v[232:233], v[188:189]
	v_pk_add_f32 v[232:233], v[232:233], v[190:191]
	v_pk_add_f32 v[232:233], v[232:233], v[192:193]
	v_pk_add_f32 v[232:233], v[232:233], v[194:195]
	v_pk_add_f32 v[232:233], v[232:233], v[196:197]
	v_pk_add_f32 v[232:233], v[232:233], v[198:199]
	v_pk_add_f32 v[232:233], v[232:233], v[200:201]
	v_pk_add_f32 v[232:233], v[232:233], v[202:203]
	ds_read2_b32 v[188:189], v115 offset0:68 offset1:69
	ds_read2_b32 v[190:191], v115 offset0:70 offset1:71
	ds_read2_b32 v[192:193], v115 offset0:76 offset1:77
	ds_read2_b32 v[194:195], v115 offset0:78 offset1:79
	ds_read2_b32 v[196:197], v115 offset0:85 offset1:86
	ds_read2_b32 v[198:199], v115 offset0:87 offset1:88
	ds_read2_b32 v[200:201], v115 offset0:93 offset1:94
	ds_read2_b32 v[202:203], v115 offset0:95 offset1:96
	v_mfma_f32_32x32x16_bf16 v[0:15], v[64:67], v[72:75], v[0:15]
	v_mfma_f32_32x32x16_bf16 v[16:31], v[64:67], v[76:79], v[16:31]
	v_mfma_f32_32x32x16_bf16 v[0:15], v[68:71], v[220:223], v[0:15]
	v_mfma_f32_32x32x16_bf16 v[16:31], v[68:71], v[224:227], v[16:31]
	global_load_dwordx4 v[116:119], v235, s[84:85]
	global_load_dwordx4 v[120:123], v236, s[84:85]
	global_load_dwordx4 v[124:127], v237, s[84:85]
	global_load_dwordx4 v[128:131], v238, s[84:85]
	global_load_dwordx4 v[132:135], v100, s[84:85] offset:768
	global_load_dwordx4 v[136:139], v149, s[84:85] offset:768
	global_load_dwordx4 v[140:143], v100, s[84:85] offset:832
	global_load_dwordx4 v[144:147], v149, s[84:85] offset:832
	s_add_u32 s84, s84, 0x30000
	s_addc_u32 s85, s85, 0
	ds_read_b64_tr_b16 v[72:73], v231
	ds_read_b64_tr_b16 v[74:75], v231 offset:512
	ds_read_b64_tr_b16 v[76:77], v231 offset:2048
	ds_read_b64_tr_b16 v[78:79], v231 offset:2560
	ds_read_b64_tr_b16 v[220:221], v231 offset:1024
	ds_read_b64_tr_b16 v[222:223], v231 offset:1536
	ds_read_b64_tr_b16 v[224:225], v231 offset:3072
	ds_read_b64_tr_b16 v[226:227], v231 offset:3584
	s_waitcnt vmcnt(8)
	ds_write_b128 v247, v[156:159]
	ds_write_b128 v247, v[160:163] offset:1024
	ds_write_b128 v247, v[164:167] offset:2048
	ds_write_b128 v247, v[168:171] offset:3072
	ds_read_b128 v[156:159], v248
	ds_read_b128 v[160:163], v249
	ds_read_b128 v[164:167], v250
	ds_read_b128 v[168:171], v251
	ds_write_b128 v112, v[172:175]
	ds_write_b128 v112, v[176:179] offset:1024
	ds_write_b128 v112, v[180:183] offset:2048
	ds_write_b128 v112, v[184:187] offset:3072
	s_waitcnt lgkmcnt(4)
	v_mfma_f32_32x32x16_bf16 v[188:203], v[156:159], v[48:51], v[188:203]
	v_exp_f32_e32 v32, v32
	v_exp_f32_e32 v33, v33
	v_exp_f32_e32 v34, v34
	v_exp_f32_e32 v35, v35
	v_mfma_f32_32x32x16_bf16 v[188:203], v[160:163], v[52:55], v[188:203]
	v_exp_f32_e32 v36, v36
	v_exp_f32_e32 v37, v37
	v_exp_f32_e32 v38, v38
	v_exp_f32_e32 v39, v39
	v_mfma_f32_32x32x16_bf16 v[188:203], v[164:167], v[56:59], v[188:203]
	v_exp_f32_e32 v40, v40
	v_exp_f32_e32 v41, v41
	v_exp_f32_e32 v42, v42
	v_exp_f32_e32 v43, v43
	v_mfma_f32_32x32x16_bf16 v[188:203], v[168:171], v[60:63], v[188:203]
	v_exp_f32_e32 v44, v44
	v_exp_f32_e32 v45, v45
	v_exp_f32_e32 v46, v46
	v_exp_f32_e32 v47, v47
	v_cvt_pk_bf16_f32 v64, v32, v33
	v_cvt_pk_bf16_f32 v65, v34, v35
	v_cvt_pk_bf16_f32 v66, v36, v37
	v_cvt_pk_bf16_f32 v67, v38, v39
	v_cvt_pk_bf16_f32 v68, v40, v41
	v_cvt_pk_bf16_f32 v69, v42, v43
	v_cvt_pk_bf16_f32 v70, v44, v45
	v_cvt_pk_bf16_f32 v71, v46, v47
	v_pk_add_f32 v[232:233], v[232:233], v[32:33]
	v_pk_add_f32 v[232:233], v[232:233], v[34:35]
	v_pk_add_f32 v[232:233], v[232:233], v[36:37]
	v_pk_add_f32 v[232:233], v[232:233], v[38:39]
	v_pk_add_f32 v[232:233], v[232:233], v[40:41]
	v_pk_add_f32 v[232:233], v[232:233], v[42:43]
	v_pk_add_f32 v[232:233], v[232:233], v[44:45]
	v_pk_add_f32 v[232:233], v[232:233], v[46:47]
	ds_read2_b32 v[32:33], v115 offset0:102 offset1:103
	ds_read2_b32 v[34:35], v115 offset0:104 offset1:105
	ds_read2_b32 v[36:37], v115 offset0:110 offset1:111
	ds_read2_b32 v[38:39], v115 offset0:112 offset1:113
	ds_read2_b32 v[40:41], v115 offset0:119 offset1:120
	ds_read2_b32 v[42:43], v115 offset0:121 offset1:122
	ds_read2_b32 v[44:45], v115 offset0:127 offset1:128
	ds_read2_b32 v[46:47], v115 offset0:129 offset1:130
	v_mfma_f32_32x32x16_bf16 v[0:15], v[64:67], v[72:75], v[0:15]
	v_mfma_f32_32x32x16_bf16 v[16:31], v[64:67], v[76:79], v[16:31]
	v_mfma_f32_32x32x16_bf16 v[0:15], v[68:71], v[220:223], v[0:15]
	v_mfma_f32_32x32x16_bf16 v[16:31], v[68:71], v[224:227], v[16:31]
	global_load_dwordx4 v[156:159], v235, s[84:85]
	global_load_dwordx4 v[160:163], v236, s[84:85]
	global_load_dwordx4 v[164:167], v237, s[84:85]
	global_load_dwordx4 v[168:171], v238, s[84:85]
	global_load_dwordx4 v[172:175], v100, s[84:85] offset:768
	global_load_dwordx4 v[176:179], v149, s[84:85] offset:768
	global_load_dwordx4 v[180:183], v100, s[84:85] offset:832
	global_load_dwordx4 v[184:187], v149, s[84:85] offset:832
	s_add_u32 s84, s84, 0x30000
	s_addc_u32 s85, s85, 0
	ds_read_b64_tr_b16 v[72:73], v231
	ds_read_b64_tr_b16 v[74:75], v231 offset:512
	ds_read_b64_tr_b16 v[76:77], v231 offset:2048
	ds_read_b64_tr_b16 v[78:79], v231 offset:2560
	ds_read_b64_tr_b16 v[220:221], v231 offset:1024
	ds_read_b64_tr_b16 v[222:223], v231 offset:1536
	ds_read_b64_tr_b16 v[224:225], v231 offset:3072
	ds_read_b64_tr_b16 v[226:227], v231 offset:3584
	s_waitcnt vmcnt(8)
	ds_write_b128 v247, v[116:119]
	ds_write_b128 v247, v[120:123] offset:1024
	ds_write_b128 v247, v[124:127] offset:2048
	ds_write_b128 v247, v[128:131] offset:3072
	ds_read_b128 v[116:119], v248
	ds_read_b128 v[120:123], v249
	ds_read_b128 v[124:127], v250
	ds_read_b128 v[128:131], v251
	ds_write_b128 v112, v[132:135]
	ds_write_b128 v112, v[136:139] offset:1024
	ds_write_b128 v112, v[140:143] offset:2048
	ds_write_b128 v112, v[144:147] offset:3072
	s_waitcnt lgkmcnt(4)
	v_mfma_f32_32x32x16_bf16 v[32:47], v[116:119], v[48:51], v[32:47]
	v_exp_f32_e32 v188, v188
	v_exp_f32_e32 v189, v189
	v_exp_f32_e32 v190, v190
	v_exp_f32_e32 v191, v191
	v_mfma_f32_32x32x16_bf16 v[32:47], v[120:123], v[52:55], v[32:47]
	v_exp_f32_e32 v192, v192
	v_exp_f32_e32 v193, v193
	v_exp_f32_e32 v194, v194
	v_exp_f32_e32 v195, v195
	v_mfma_f32_32x32x16_bf16 v[32:47], v[124:127], v[56:59], v[32:47]
	v_exp_f32_e32 v196, v196
	v_exp_f32_e32 v197, v197
	v_exp_f32_e32 v198, v198
	v_exp_f32_e32 v199, v199
	v_mfma_f32_32x32x16_bf16 v[32:47], v[128:131], v[60:63], v[32:47]
	v_exp_f32_e32 v200, v200
	v_exp_f32_e32 v201, v201
	v_exp_f32_e32 v202, v202
	v_exp_f32_e32 v203, v203
	v_cvt_pk_bf16_f32 v64, v188, v189
	v_cvt_pk_bf16_f32 v65, v190, v191
	v_cvt_pk_bf16_f32 v66, v192, v193
	v_cvt_pk_bf16_f32 v67, v194, v195
	v_cvt_pk_bf16_f32 v68, v196, v197
	v_cvt_pk_bf16_f32 v69, v198, v199
	v_cvt_pk_bf16_f32 v70, v200, v201
	v_cvt_pk_bf16_f32 v71, v202, v203
	v_pk_add_f32 v[232:233], v[232:233], v[188:189]
	v_pk_add_f32 v[232:233], v[232:233], v[190:191]
	v_pk_add_f32 v[232:233], v[232:233], v[192:193]
	v_pk_add_f32 v[232:233], v[232:233], v[194:195]
	v_pk_add_f32 v[232:233], v[232:233], v[196:197]
	v_pk_add_f32 v[232:233], v[232:233], v[198:199]
	v_pk_add_f32 v[232:233], v[232:233], v[200:201]
	v_pk_add_f32 v[232:233], v[232:233], v[202:203]
	ds_read2_b32 v[188:189], v115 offset0:136 offset1:137
	ds_read2_b32 v[190:191], v115 offset0:138 offset1:139
	ds_read2_b32 v[192:193], v115 offset0:144 offset1:145
	ds_read2_b32 v[194:195], v115 offset0:146 offset1:147
	ds_read2_b32 v[196:197], v115 offset0:153 offset1:154
	ds_read2_b32 v[198:199], v115 offset0:155 offset1:156
	ds_read2_b32 v[200:201], v115 offset0:161 offset1:162
	ds_read2_b32 v[202:203], v115 offset0:163 offset1:164
	v_mfma_f32_32x32x16_bf16 v[0:15], v[64:67], v[72:75], v[0:15]
	v_mfma_f32_32x32x16_bf16 v[16:31], v[64:67], v[76:79], v[16:31]
	v_mfma_f32_32x32x16_bf16 v[0:15], v[68:71], v[220:223], v[0:15]
	v_mfma_f32_32x32x16_bf16 v[16:31], v[68:71], v[224:227], v[16:31]
	global_load_dwordx4 v[116:119], v235, s[84:85]
	global_load_dwordx4 v[120:123], v236, s[84:85]
	global_load_dwordx4 v[124:127], v237, s[84:85]
	global_load_dwordx4 v[128:131], v238, s[84:85]
	global_load_dwordx4 v[132:135], v100, s[84:85] offset:768
	global_load_dwordx4 v[136:139], v149, s[84:85] offset:768
	global_load_dwordx4 v[140:143], v100, s[84:85] offset:832
	global_load_dwordx4 v[144:147], v149, s[84:85] offset:832
	s_add_u32 s84, s84, 0x30000
	s_addc_u32 s85, s85, 0
	ds_read_b64_tr_b16 v[72:73], v231
	ds_read_b64_tr_b16 v[74:75], v231 offset:512
	ds_read_b64_tr_b16 v[76:77], v231 offset:2048
	ds_read_b64_tr_b16 v[78:79], v231 offset:2560
	ds_read_b64_tr_b16 v[220:221], v231 offset:1024
	ds_read_b64_tr_b16 v[222:223], v231 offset:1536
	ds_read_b64_tr_b16 v[224:225], v231 offset:3072
	ds_read_b64_tr_b16 v[226:227], v231 offset:3584
	s_waitcnt vmcnt(8)
	ds_write_b128 v247, v[156:159]
	ds_write_b128 v247, v[160:163] offset:1024
	ds_write_b128 v247, v[164:167] offset:2048
	ds_write_b128 v247, v[168:171] offset:3072
	ds_read_b128 v[156:159], v248
	ds_read_b128 v[160:163], v249
	ds_read_b128 v[164:167], v250
	ds_read_b128 v[168:171], v251
	ds_write_b128 v112, v[172:175]
	ds_write_b128 v112, v[176:179] offset:1024
	ds_write_b128 v112, v[180:183] offset:2048
	ds_write_b128 v112, v[184:187] offset:3072
	s_waitcnt lgkmcnt(4)
	v_mfma_f32_32x32x16_bf16 v[188:203], v[156:159], v[48:51], v[188:203]
	v_exp_f32_e32 v32, v32
	v_exp_f32_e32 v33, v33
	v_exp_f32_e32 v34, v34
	v_exp_f32_e32 v35, v35
	v_mfma_f32_32x32x16_bf16 v[188:203], v[160:163], v[52:55], v[188:203]
	v_exp_f32_e32 v36, v36
	v_exp_f32_e32 v37, v37
	v_exp_f32_e32 v38, v38
	v_exp_f32_e32 v39, v39
	v_mfma_f32_32x32x16_bf16 v[188:203], v[164:167], v[56:59], v[188:203]
	v_exp_f32_e32 v40, v40
	v_exp_f32_e32 v41, v41
	v_exp_f32_e32 v42, v42
	v_exp_f32_e32 v43, v43
	v_mfma_f32_32x32x16_bf16 v[188:203], v[168:171], v[60:63], v[188:203]
	v_exp_f32_e32 v44, v44
	v_exp_f32_e32 v45, v45
	v_exp_f32_e32 v46, v46
	v_exp_f32_e32 v47, v47
	v_cvt_pk_bf16_f32 v64, v32, v33
	v_cvt_pk_bf16_f32 v65, v34, v35
	v_cvt_pk_bf16_f32 v66, v36, v37
	v_cvt_pk_bf16_f32 v67, v38, v39
	v_cvt_pk_bf16_f32 v68, v40, v41
	v_cvt_pk_bf16_f32 v69, v42, v43
	v_cvt_pk_bf16_f32 v70, v44, v45
	v_cvt_pk_bf16_f32 v71, v46, v47
	v_pk_add_f32 v[232:233], v[232:233], v[32:33]
	v_pk_add_f32 v[232:233], v[232:233], v[34:35]
	v_pk_add_f32 v[232:233], v[232:233], v[36:37]
	v_pk_add_f32 v[232:233], v[232:233], v[38:39]
	v_pk_add_f32 v[232:233], v[232:233], v[40:41]
	v_pk_add_f32 v[232:233], v[232:233], v[42:43]
	v_pk_add_f32 v[232:233], v[232:233], v[44:45]
	v_pk_add_f32 v[232:233], v[232:233], v[46:47]
	ds_read2_b32 v[32:33], v115 offset0:170 offset1:171
	ds_read2_b32 v[34:35], v115 offset0:172 offset1:173
	ds_read2_b32 v[36:37], v115 offset0:178 offset1:179
	ds_read2_b32 v[38:39], v115 offset0:180 offset1:181
	ds_read2_b32 v[40:41], v115 offset0:187 offset1:188
	ds_read2_b32 v[42:43], v115 offset0:189 offset1:190
	ds_read2_b32 v[44:45], v115 offset0:195 offset1:196
	ds_read2_b32 v[46:47], v115 offset0:197 offset1:198
	v_mfma_f32_32x32x16_bf16 v[0:15], v[64:67], v[72:75], v[0:15]
	v_mfma_f32_32x32x16_bf16 v[16:31], v[64:67], v[76:79], v[16:31]
	v_mfma_f32_32x32x16_bf16 v[0:15], v[68:71], v[220:223], v[0:15]
	v_mfma_f32_32x32x16_bf16 v[16:31], v[68:71], v[224:227], v[16:31]
	global_load_dwordx4 v[156:159], v235, s[84:85]
	global_load_dwordx4 v[160:163], v236, s[84:85]
	global_load_dwordx4 v[164:167], v237, s[84:85]
	global_load_dwordx4 v[168:171], v238, s[84:85]
	global_load_dwordx4 v[172:175], v100, s[84:85] offset:768
	global_load_dwordx4 v[176:179], v149, s[84:85] offset:768
	global_load_dwordx4 v[180:183], v100, s[84:85] offset:832
	global_load_dwordx4 v[184:187], v149, s[84:85] offset:832
	s_add_u32 s84, s84, 0x30000
	s_addc_u32 s85, s85, 0
	ds_read_b64_tr_b16 v[72:73], v231
	ds_read_b64_tr_b16 v[74:75], v231 offset:512
	ds_read_b64_tr_b16 v[76:77], v231 offset:2048
	ds_read_b64_tr_b16 v[78:79], v231 offset:2560
	ds_read_b64_tr_b16 v[220:221], v231 offset:1024
	ds_read_b64_tr_b16 v[222:223], v231 offset:1536
	ds_read_b64_tr_b16 v[224:225], v231 offset:3072
	ds_read_b64_tr_b16 v[226:227], v231 offset:3584
	s_waitcnt vmcnt(8)
	ds_write_b128 v247, v[116:119]
	ds_write_b128 v247, v[120:123] offset:1024
	ds_write_b128 v247, v[124:127] offset:2048
	ds_write_b128 v247, v[128:131] offset:3072
	ds_read_b128 v[116:119], v248
	ds_read_b128 v[120:123], v249
	ds_read_b128 v[124:127], v250
	ds_read_b128 v[128:131], v251
	ds_write_b128 v112, v[132:135]
	ds_write_b128 v112, v[136:139] offset:1024
	ds_write_b128 v112, v[140:143] offset:2048
	ds_write_b128 v112, v[144:147] offset:3072
	s_waitcnt lgkmcnt(4)
	v_mfma_f32_32x32x16_bf16 v[32:47], v[116:119], v[48:51], v[32:47]
	v_exp_f32_e32 v188, v188
	v_exp_f32_e32 v189, v189
	v_exp_f32_e32 v190, v190
	v_exp_f32_e32 v191, v191
	v_mfma_f32_32x32x16_bf16 v[32:47], v[120:123], v[52:55], v[32:47]
	v_exp_f32_e32 v192, v192
	v_exp_f32_e32 v193, v193
	v_exp_f32_e32 v194, v194
	v_exp_f32_e32 v195, v195
	v_mfma_f32_32x32x16_bf16 v[32:47], v[124:127], v[56:59], v[32:47]
	v_exp_f32_e32 v196, v196
	v_exp_f32_e32 v197, v197
	v_exp_f32_e32 v198, v198
	v_exp_f32_e32 v199, v199
	v_mfma_f32_32x32x16_bf16 v[32:47], v[128:131], v[60:63], v[32:47]
	v_exp_f32_e32 v200, v200
	v_exp_f32_e32 v201, v201
	v_exp_f32_e32 v202, v202
	v_exp_f32_e32 v203, v203
	v_cvt_pk_bf16_f32 v64, v188, v189
	v_cvt_pk_bf16_f32 v65, v190, v191
	v_cvt_pk_bf16_f32 v66, v192, v193
	v_cvt_pk_bf16_f32 v67, v194, v195
	v_cvt_pk_bf16_f32 v68, v196, v197
	v_cvt_pk_bf16_f32 v69, v198, v199
	v_cvt_pk_bf16_f32 v70, v200, v201
	v_cvt_pk_bf16_f32 v71, v202, v203
	v_pk_add_f32 v[232:233], v[232:233], v[188:189]
	v_pk_add_f32 v[232:233], v[232:233], v[190:191]
	v_pk_add_f32 v[232:233], v[232:233], v[192:193]
	v_pk_add_f32 v[232:233], v[232:233], v[194:195]
	v_pk_add_f32 v[232:233], v[232:233], v[196:197]
	v_pk_add_f32 v[232:233], v[232:233], v[198:199]
	v_pk_add_f32 v[232:233], v[232:233], v[200:201]
	v_pk_add_f32 v[232:233], v[232:233], v[202:203]
	ds_read2_b32 v[188:189], v115 offset0:204 offset1:205
	ds_read2_b32 v[190:191], v115 offset0:206 offset1:207
	ds_read2_b32 v[192:193], v115 offset0:212 offset1:213
	ds_read2_b32 v[194:195], v115 offset0:214 offset1:215
	ds_read2_b32 v[196:197], v115 offset0:221 offset1:222
	ds_read2_b32 v[198:199], v115 offset0:223 offset1:224
	ds_read2_b32 v[200:201], v115 offset0:229 offset1:230
	ds_read2_b32 v[202:203], v115 offset0:231 offset1:232
	v_mfma_f32_32x32x16_bf16 v[0:15], v[64:67], v[72:75], v[0:15]
	v_mfma_f32_32x32x16_bf16 v[16:31], v[64:67], v[76:79], v[16:31]
	v_mfma_f32_32x32x16_bf16 v[0:15], v[68:71], v[220:223], v[0:15]
	v_mfma_f32_32x32x16_bf16 v[16:31], v[68:71], v[224:227], v[16:31]
	global_load_dwordx4 v[116:119], v235, s[84:85]
	global_load_dwordx4 v[120:123], v236, s[84:85]
	global_load_dwordx4 v[124:127], v237, s[84:85]
	global_load_dwordx4 v[128:131], v238, s[84:85]
	global_load_dwordx4 v[132:135], v100, s[84:85] offset:768
	global_load_dwordx4 v[136:139], v149, s[84:85] offset:768
	global_load_dwordx4 v[140:143], v100, s[84:85] offset:832
	global_load_dwordx4 v[144:147], v149, s[84:85] offset:832
	s_add_u32 s84, s84, 0x30000
	s_addc_u32 s85, s85, 0
	ds_read_b64_tr_b16 v[72:73], v231
	ds_read_b64_tr_b16 v[74:75], v231 offset:512
	ds_read_b64_tr_b16 v[76:77], v231 offset:2048
	ds_read_b64_tr_b16 v[78:79], v231 offset:2560
	ds_read_b64_tr_b16 v[220:221], v231 offset:1024
	ds_read_b64_tr_b16 v[222:223], v231 offset:1536
	ds_read_b64_tr_b16 v[224:225], v231 offset:3072
	ds_read_b64_tr_b16 v[226:227], v231 offset:3584
	s_waitcnt vmcnt(8)
	ds_write_b128 v247, v[156:159]
	ds_write_b128 v247, v[160:163] offset:1024
	ds_write_b128 v247, v[164:167] offset:2048
	ds_write_b128 v247, v[168:171] offset:3072
	ds_read_b128 v[156:159], v248
	ds_read_b128 v[160:163], v249
	ds_read_b128 v[164:167], v250
	ds_read_b128 v[168:171], v251
	ds_write_b128 v112, v[172:175]
	ds_write_b128 v112, v[176:179] offset:1024
	ds_write_b128 v112, v[180:183] offset:2048
	ds_write_b128 v112, v[184:187] offset:3072
	s_waitcnt lgkmcnt(4)
	v_mfma_f32_32x32x16_bf16 v[188:203], v[156:159], v[48:51], v[188:203]
	v_exp_f32_e32 v32, v32
	v_exp_f32_e32 v33, v33
	v_exp_f32_e32 v34, v34
	v_exp_f32_e32 v35, v35
	v_mfma_f32_32x32x16_bf16 v[188:203], v[160:163], v[52:55], v[188:203]
	v_exp_f32_e32 v36, v36
	v_exp_f32_e32 v37, v37
	v_exp_f32_e32 v38, v38
	v_exp_f32_e32 v39, v39
	v_mfma_f32_32x32x16_bf16 v[188:203], v[164:167], v[56:59], v[188:203]
	v_exp_f32_e32 v40, v40
	v_exp_f32_e32 v41, v41
	v_exp_f32_e32 v42, v42
	v_exp_f32_e32 v43, v43
	v_mfma_f32_32x32x16_bf16 v[188:203], v[168:171], v[60:63], v[188:203]
	v_exp_f32_e32 v44, v44
	v_exp_f32_e32 v45, v45
	v_exp_f32_e32 v46, v46
	v_exp_f32_e32 v47, v47
	v_cvt_pk_bf16_f32 v64, v32, v33
	v_cvt_pk_bf16_f32 v65, v34, v35
	v_cvt_pk_bf16_f32 v66, v36, v37
	v_cvt_pk_bf16_f32 v67, v38, v39
	v_cvt_pk_bf16_f32 v68, v40, v41
	v_cvt_pk_bf16_f32 v69, v42, v43
	v_cvt_pk_bf16_f32 v70, v44, v45
	v_cvt_pk_bf16_f32 v71, v46, v47
	v_pk_add_f32 v[232:233], v[232:233], v[32:33]
	v_pk_add_f32 v[232:233], v[232:233], v[34:35]
	v_pk_add_f32 v[232:233], v[232:233], v[36:37]
	v_pk_add_f32 v[232:233], v[232:233], v[38:39]
	v_pk_add_f32 v[232:233], v[232:233], v[40:41]
	v_pk_add_f32 v[232:233], v[232:233], v[42:43]
	v_pk_add_f32 v[232:233], v[232:233], v[44:45]
	v_pk_add_f32 v[232:233], v[232:233], v[46:47]
	v_add_u32_e32 v115, 952, v115
	ds_read2_b32 v[32:33], v115 offset0:0 offset1:1
	ds_read2_b32 v[34:35], v115 offset0:2 offset1:3
	ds_read2_b32 v[36:37], v115 offset0:8 offset1:9
	ds_read2_b32 v[38:39], v115 offset0:10 offset1:11
	ds_read2_b32 v[40:41], v115 offset0:17 offset1:18
	ds_read2_b32 v[42:43], v115 offset0:19 offset1:20
	ds_read2_b32 v[44:45], v115 offset0:25 offset1:26
	ds_read2_b32 v[46:47], v115 offset0:27 offset1:28
	v_mfma_f32_32x32x16_bf16 v[0:15], v[64:67], v[72:75], v[0:15]
	v_mfma_f32_32x32x16_bf16 v[16:31], v[64:67], v[76:79], v[16:31]
	v_mfma_f32_32x32x16_bf16 v[0:15], v[68:71], v[220:223], v[0:15]
	v_mfma_f32_32x32x16_bf16 v[16:31], v[68:71], v[224:227], v[16:31]
	global_load_dwordx4 v[156:159], v235, s[84:85]
	global_load_dwordx4 v[160:163], v236, s[84:85]
	global_load_dwordx4 v[164:167], v237, s[84:85]
	global_load_dwordx4 v[168:171], v238, s[84:85]
	global_load_dwordx4 v[172:175], v100, s[84:85] offset:768
	global_load_dwordx4 v[176:179], v149, s[84:85] offset:768
	global_load_dwordx4 v[180:183], v100, s[84:85] offset:832
	global_load_dwordx4 v[184:187], v149, s[84:85] offset:832
	s_add_u32 s84, s84, 0x30000
	s_addc_u32 s85, s85, 0
	ds_read_b64_tr_b16 v[72:73], v231
	ds_read_b64_tr_b16 v[74:75], v231 offset:512
	ds_read_b64_tr_b16 v[76:77], v231 offset:2048
	ds_read_b64_tr_b16 v[78:79], v231 offset:2560
	ds_read_b64_tr_b16 v[220:221], v231 offset:1024
	ds_read_b64_tr_b16 v[222:223], v231 offset:1536
	ds_read_b64_tr_b16 v[224:225], v231 offset:3072
	ds_read_b64_tr_b16 v[226:227], v231 offset:3584
	s_waitcnt vmcnt(8)
	ds_write_b128 v247, v[116:119]
	ds_write_b128 v247, v[120:123] offset:1024
	ds_write_b128 v247, v[124:127] offset:2048
	ds_write_b128 v247, v[128:131] offset:3072
	ds_read_b128 v[116:119], v248
	ds_read_b128 v[120:123], v249
	ds_read_b128 v[124:127], v250
	ds_read_b128 v[128:131], v251
	ds_write_b128 v112, v[132:135]
	ds_write_b128 v112, v[136:139] offset:1024
	ds_write_b128 v112, v[140:143] offset:2048
	ds_write_b128 v112, v[144:147] offset:3072
	s_waitcnt lgkmcnt(4)
	v_mfma_f32_32x32x16_bf16 v[32:47], v[116:119], v[48:51], v[32:47]
	v_exp_f32_e32 v188, v188
	v_exp_f32_e32 v189, v189
	v_exp_f32_e32 v190, v190
	v_exp_f32_e32 v191, v191
	v_mfma_f32_32x32x16_bf16 v[32:47], v[120:123], v[52:55], v[32:47]
	v_exp_f32_e32 v192, v192
	v_exp_f32_e32 v193, v193
	v_exp_f32_e32 v194, v194
	v_exp_f32_e32 v195, v195
	v_mfma_f32_32x32x16_bf16 v[32:47], v[124:127], v[56:59], v[32:47]
	v_exp_f32_e32 v196, v196
	v_exp_f32_e32 v197, v197
	v_exp_f32_e32 v198, v198
	v_exp_f32_e32 v199, v199
	v_mfma_f32_32x32x16_bf16 v[32:47], v[128:131], v[60:63], v[32:47]
	v_exp_f32_e32 v200, v200
	v_exp_f32_e32 v201, v201
	v_exp_f32_e32 v202, v202
	v_exp_f32_e32 v203, v203
	v_cvt_pk_bf16_f32 v64, v188, v189
	v_cvt_pk_bf16_f32 v65, v190, v191
	v_cvt_pk_bf16_f32 v66, v192, v193
	v_cvt_pk_bf16_f32 v67, v194, v195
	v_cvt_pk_bf16_f32 v68, v196, v197
	v_cvt_pk_bf16_f32 v69, v198, v199
	v_cvt_pk_bf16_f32 v70, v200, v201
	v_cvt_pk_bf16_f32 v71, v202, v203
	v_pk_add_f32 v[232:233], v[232:233], v[188:189]
	v_pk_add_f32 v[232:233], v[232:233], v[190:191]
	v_pk_add_f32 v[232:233], v[232:233], v[192:193]
	v_pk_add_f32 v[232:233], v[232:233], v[194:195]
	v_pk_add_f32 v[232:233], v[232:233], v[196:197]
	v_pk_add_f32 v[232:233], v[232:233], v[198:199]
	v_pk_add_f32 v[232:233], v[232:233], v[200:201]
	v_pk_add_f32 v[232:233], v[232:233], v[202:203]
	ds_read2_b32 v[188:189], v115 offset0:34 offset1:35
	ds_read2_b32 v[190:191], v115 offset0:36 offset1:37
	ds_read2_b32 v[192:193], v115 offset0:42 offset1:43
	ds_read2_b32 v[194:195], v115 offset0:44 offset1:45
	ds_read2_b32 v[196:197], v115 offset0:51 offset1:52
	ds_read2_b32 v[198:199], v115 offset0:53 offset1:54
	ds_read2_b32 v[200:201], v115 offset0:59 offset1:60
	ds_read2_b32 v[202:203], v115 offset0:61 offset1:62
	v_mfma_f32_32x32x16_bf16 v[0:15], v[64:67], v[72:75], v[0:15]
	v_mfma_f32_32x32x16_bf16 v[16:31], v[64:67], v[76:79], v[16:31]
	v_mfma_f32_32x32x16_bf16 v[0:15], v[68:71], v[220:223], v[0:15]
	v_mfma_f32_32x32x16_bf16 v[16:31], v[68:71], v[224:227], v[16:31]
	global_load_dwordx4 v[116:119], v235, s[84:85]
	global_load_dwordx4 v[120:123], v236, s[84:85]
	global_load_dwordx4 v[124:127], v237, s[84:85]
	global_load_dwordx4 v[128:131], v238, s[84:85]
	global_load_dwordx4 v[132:135], v100, s[84:85] offset:768
	global_load_dwordx4 v[136:139], v149, s[84:85] offset:768
	global_load_dwordx4 v[140:143], v100, s[84:85] offset:832
	global_load_dwordx4 v[144:147], v149, s[84:85] offset:832
	s_add_u32 s84, s84, 0x30000
	s_addc_u32 s85, s85, 0
	ds_read_b64_tr_b16 v[72:73], v231
	ds_read_b64_tr_b16 v[74:75], v231 offset:512
	ds_read_b64_tr_b16 v[76:77], v231 offset:2048
	ds_read_b64_tr_b16 v[78:79], v231 offset:2560
	ds_read_b64_tr_b16 v[220:221], v231 offset:1024
	ds_read_b64_tr_b16 v[222:223], v231 offset:1536
	ds_read_b64_tr_b16 v[224:225], v231 offset:3072
	ds_read_b64_tr_b16 v[226:227], v231 offset:3584
	s_waitcnt vmcnt(8)
	ds_write_b128 v247, v[156:159]
	ds_write_b128 v247, v[160:163] offset:1024
	ds_write_b128 v247, v[164:167] offset:2048
	ds_write_b128 v247, v[168:171] offset:3072
	ds_read_b128 v[156:159], v248
	ds_read_b128 v[160:163], v249
	ds_read_b128 v[164:167], v250
	ds_read_b128 v[168:171], v251
	ds_write_b128 v112, v[172:175]
	ds_write_b128 v112, v[176:179] offset:1024
	ds_write_b128 v112, v[180:183] offset:2048
	ds_write_b128 v112, v[184:187] offset:3072
	s_waitcnt lgkmcnt(4)
	v_mfma_f32_32x32x16_bf16 v[188:203], v[156:159], v[48:51], v[188:203]
	v_exp_f32_e32 v32, v32
	v_exp_f32_e32 v33, v33
	v_exp_f32_e32 v34, v34
	v_exp_f32_e32 v35, v35
	v_mfma_f32_32x32x16_bf16 v[188:203], v[160:163], v[52:55], v[188:203]
	v_exp_f32_e32 v36, v36
	v_exp_f32_e32 v37, v37
	v_exp_f32_e32 v38, v38
	v_exp_f32_e32 v39, v39
	v_mfma_f32_32x32x16_bf16 v[188:203], v[164:167], v[56:59], v[188:203]
	v_exp_f32_e32 v40, v40
	v_exp_f32_e32 v41, v41
	v_exp_f32_e32 v42, v42
	v_exp_f32_e32 v43, v43
	v_mfma_f32_32x32x16_bf16 v[188:203], v[168:171], v[60:63], v[188:203]
	v_exp_f32_e32 v44, v44
	v_exp_f32_e32 v45, v45
	v_exp_f32_e32 v46, v46
	v_exp_f32_e32 v47, v47
	v_cvt_pk_bf16_f32 v64, v32, v33
	v_cvt_pk_bf16_f32 v65, v34, v35
	v_cvt_pk_bf16_f32 v66, v36, v37
	v_cvt_pk_bf16_f32 v67, v38, v39
	v_cvt_pk_bf16_f32 v68, v40, v41
	v_cvt_pk_bf16_f32 v69, v42, v43
	v_cvt_pk_bf16_f32 v70, v44, v45
	v_cvt_pk_bf16_f32 v71, v46, v47
	v_pk_add_f32 v[232:233], v[232:233], v[32:33]
	v_pk_add_f32 v[232:233], v[232:233], v[34:35]
	v_pk_add_f32 v[232:233], v[232:233], v[36:37]
	v_pk_add_f32 v[232:233], v[232:233], v[38:39]
	v_pk_add_f32 v[232:233], v[232:233], v[40:41]
	v_pk_add_f32 v[232:233], v[232:233], v[42:43]
	v_pk_add_f32 v[232:233], v[232:233], v[44:45]
	v_pk_add_f32 v[232:233], v[232:233], v[46:47]
	ds_read2_b32 v[32:33], v115 offset0:68 offset1:69
	ds_read2_b32 v[34:35], v115 offset0:70 offset1:71
	ds_read2_b32 v[36:37], v115 offset0:76 offset1:77
	ds_read2_b32 v[38:39], v115 offset0:78 offset1:79
	ds_read2_b32 v[40:41], v115 offset0:85 offset1:86
	ds_read2_b32 v[42:43], v115 offset0:87 offset1:88
	ds_read2_b32 v[44:45], v115 offset0:93 offset1:94
	ds_read2_b32 v[46:47], v115 offset0:95 offset1:96
	v_mfma_f32_32x32x16_bf16 v[0:15], v[64:67], v[72:75], v[0:15]
	v_mfma_f32_32x32x16_bf16 v[16:31], v[64:67], v[76:79], v[16:31]
	v_mfma_f32_32x32x16_bf16 v[0:15], v[68:71], v[220:223], v[0:15]
	v_mfma_f32_32x32x16_bf16 v[16:31], v[68:71], v[224:227], v[16:31]
	global_load_dwordx4 v[156:159], v235, s[84:85]
	global_load_dwordx4 v[160:163], v236, s[84:85]
	global_load_dwordx4 v[164:167], v237, s[84:85]
	global_load_dwordx4 v[168:171], v238, s[84:85]
	global_load_dwordx4 v[172:175], v100, s[84:85] offset:768
	global_load_dwordx4 v[176:179], v149, s[84:85] offset:768
	global_load_dwordx4 v[180:183], v100, s[84:85] offset:832
	global_load_dwordx4 v[184:187], v149, s[84:85] offset:832
	s_add_u32 s84, s84, 0x30000
	s_addc_u32 s85, s85, 0
	ds_read_b64_tr_b16 v[72:73], v231
	ds_read_b64_tr_b16 v[74:75], v231 offset:512
	ds_read_b64_tr_b16 v[76:77], v231 offset:2048
	ds_read_b64_tr_b16 v[78:79], v231 offset:2560
	ds_read_b64_tr_b16 v[220:221], v231 offset:1024
	ds_read_b64_tr_b16 v[222:223], v231 offset:1536
	ds_read_b64_tr_b16 v[224:225], v231 offset:3072
	ds_read_b64_tr_b16 v[226:227], v231 offset:3584
	s_waitcnt vmcnt(8)
	ds_write_b128 v247, v[116:119]
	ds_write_b128 v247, v[120:123] offset:1024
	ds_write_b128 v247, v[124:127] offset:2048
	ds_write_b128 v247, v[128:131] offset:3072
	ds_read_b128 v[116:119], v248
	ds_read_b128 v[120:123], v249
	ds_read_b128 v[124:127], v250
	ds_read_b128 v[128:131], v251
	ds_write_b128 v112, v[132:135]
	ds_write_b128 v112, v[136:139] offset:1024
	ds_write_b128 v112, v[140:143] offset:2048
	ds_write_b128 v112, v[144:147] offset:3072
	s_waitcnt lgkmcnt(4)
	v_mfma_f32_32x32x16_bf16 v[32:47], v[116:119], v[48:51], v[32:47]
	v_exp_f32_e32 v188, v188
	v_exp_f32_e32 v189, v189
	v_exp_f32_e32 v190, v190
	v_exp_f32_e32 v191, v191
	v_mfma_f32_32x32x16_bf16 v[32:47], v[120:123], v[52:55], v[32:47]
	v_exp_f32_e32 v192, v192
	v_exp_f32_e32 v193, v193
	v_exp_f32_e32 v194, v194
	v_exp_f32_e32 v195, v195
	v_mfma_f32_32x32x16_bf16 v[32:47], v[124:127], v[56:59], v[32:47]
	v_exp_f32_e32 v196, v196
	v_exp_f32_e32 v197, v197
	v_exp_f32_e32 v198, v198
	v_exp_f32_e32 v199, v199
	v_mfma_f32_32x32x16_bf16 v[32:47], v[128:131], v[60:63], v[32:47]
	v_exp_f32_e32 v200, v200
	v_exp_f32_e32 v201, v201
	v_exp_f32_e32 v202, v202
	v_exp_f32_e32 v203, v203
	v_cvt_pk_bf16_f32 v64, v188, v189
	v_cvt_pk_bf16_f32 v65, v190, v191
	v_cvt_pk_bf16_f32 v66, v192, v193
	v_cvt_pk_bf16_f32 v67, v194, v195
	v_cvt_pk_bf16_f32 v68, v196, v197
	v_cvt_pk_bf16_f32 v69, v198, v199
	v_cvt_pk_bf16_f32 v70, v200, v201
	v_cvt_pk_bf16_f32 v71, v202, v203
	v_pk_add_f32 v[232:233], v[232:233], v[188:189]
	v_pk_add_f32 v[232:233], v[232:233], v[190:191]
	v_pk_add_f32 v[232:233], v[232:233], v[192:193]
	v_pk_add_f32 v[232:233], v[232:233], v[194:195]
	v_pk_add_f32 v[232:233], v[232:233], v[196:197]
	v_pk_add_f32 v[232:233], v[232:233], v[198:199]
	v_pk_add_f32 v[232:233], v[232:233], v[200:201]
	v_pk_add_f32 v[232:233], v[232:233], v[202:203]
	ds_read2_b32 v[188:189], v115 offset0:102 offset1:103
	ds_read2_b32 v[190:191], v115 offset0:104 offset1:105
	ds_read2_b32 v[192:193], v115 offset0:110 offset1:111
	ds_read2_b32 v[194:195], v115 offset0:112 offset1:113
	ds_read2_b32 v[196:197], v115 offset0:119 offset1:120
	ds_read2_b32 v[198:199], v115 offset0:121 offset1:122
	ds_read2_b32 v[200:201], v115 offset0:127 offset1:128
	ds_read2_b32 v[202:203], v115 offset0:129 offset1:130
	v_mfma_f32_32x32x16_bf16 v[0:15], v[64:67], v[72:75], v[0:15]
	v_mfma_f32_32x32x16_bf16 v[16:31], v[64:67], v[76:79], v[16:31]
	v_mfma_f32_32x32x16_bf16 v[0:15], v[68:71], v[220:223], v[0:15]
	v_mfma_f32_32x32x16_bf16 v[16:31], v[68:71], v[224:227], v[16:31]
	global_load_dwordx4 v[116:119], v235, s[84:85]
	global_load_dwordx4 v[120:123], v236, s[84:85]
	global_load_dwordx4 v[124:127], v237, s[84:85]
	global_load_dwordx4 v[128:131], v238, s[84:85]
	global_load_dwordx4 v[132:135], v100, s[84:85] offset:768
	global_load_dwordx4 v[136:139], v149, s[84:85] offset:768
	global_load_dwordx4 v[140:143], v100, s[84:85] offset:832
	global_load_dwordx4 v[144:147], v149, s[84:85] offset:832
	s_add_u32 s84, s84, 0x30000
	s_addc_u32 s85, s85, 0
	ds_read_b64_tr_b16 v[72:73], v231
	ds_read_b64_tr_b16 v[74:75], v231 offset:512
	ds_read_b64_tr_b16 v[76:77], v231 offset:2048
	ds_read_b64_tr_b16 v[78:79], v231 offset:2560
	ds_read_b64_tr_b16 v[220:221], v231 offset:1024
	ds_read_b64_tr_b16 v[222:223], v231 offset:1536
	ds_read_b64_tr_b16 v[224:225], v231 offset:3072
	ds_read_b64_tr_b16 v[226:227], v231 offset:3584
	s_waitcnt vmcnt(8)
	ds_write_b128 v247, v[156:159]
	ds_write_b128 v247, v[160:163] offset:1024
	ds_write_b128 v247, v[164:167] offset:2048
	ds_write_b128 v247, v[168:171] offset:3072
	ds_read_b128 v[156:159], v248
	ds_read_b128 v[160:163], v249
	ds_read_b128 v[164:167], v250
	ds_read_b128 v[168:171], v251
	ds_write_b128 v112, v[172:175]
	ds_write_b128 v112, v[176:179] offset:1024
	ds_write_b128 v112, v[180:183] offset:2048
	ds_write_b128 v112, v[184:187] offset:3072
	s_waitcnt lgkmcnt(4)
	v_mfma_f32_32x32x16_bf16 v[188:203], v[156:159], v[48:51], v[188:203]
	v_exp_f32_e32 v32, v32
	v_exp_f32_e32 v33, v33
	v_exp_f32_e32 v34, v34
	v_exp_f32_e32 v35, v35
	v_mfma_f32_32x32x16_bf16 v[188:203], v[160:163], v[52:55], v[188:203]
	v_exp_f32_e32 v36, v36
	v_exp_f32_e32 v37, v37
	v_exp_f32_e32 v38, v38
	v_exp_f32_e32 v39, v39
	v_mfma_f32_32x32x16_bf16 v[188:203], v[164:167], v[56:59], v[188:203]
	v_exp_f32_e32 v40, v40
	v_exp_f32_e32 v41, v41
	v_exp_f32_e32 v42, v42
	v_exp_f32_e32 v43, v43
	v_mfma_f32_32x32x16_bf16 v[188:203], v[168:171], v[60:63], v[188:203]
	v_exp_f32_e32 v44, v44
	v_exp_f32_e32 v45, v45
	v_exp_f32_e32 v46, v46
	v_exp_f32_e32 v47, v47
	v_cvt_pk_bf16_f32 v64, v32, v33
	v_cvt_pk_bf16_f32 v65, v34, v35
	v_cvt_pk_bf16_f32 v66, v36, v37
	v_cvt_pk_bf16_f32 v67, v38, v39
	v_cvt_pk_bf16_f32 v68, v40, v41
	v_cvt_pk_bf16_f32 v69, v42, v43
	v_cvt_pk_bf16_f32 v70, v44, v45
	v_cvt_pk_bf16_f32 v71, v46, v47
	v_pk_add_f32 v[232:233], v[232:233], v[32:33]
	v_pk_add_f32 v[232:233], v[232:233], v[34:35]
	v_pk_add_f32 v[232:233], v[232:233], v[36:37]
	v_pk_add_f32 v[232:233], v[232:233], v[38:39]
	v_pk_add_f32 v[232:233], v[232:233], v[40:41]
	v_pk_add_f32 v[232:233], v[232:233], v[42:43]
	v_pk_add_f32 v[232:233], v[232:233], v[44:45]
	v_pk_add_f32 v[232:233], v[232:233], v[46:47]
	ds_read2_b32 v[32:33], v115 offset0:136 offset1:137
	ds_read2_b32 v[34:35], v115 offset0:138 offset1:139
	ds_read2_b32 v[36:37], v115 offset0:144 offset1:145
	ds_read2_b32 v[38:39], v115 offset0:146 offset1:147
	ds_read2_b32 v[40:41], v115 offset0:153 offset1:154
	ds_read2_b32 v[42:43], v115 offset0:155 offset1:156
	ds_read2_b32 v[44:45], v115 offset0:161 offset1:162
	ds_read2_b32 v[46:47], v115 offset0:163 offset1:164
	v_mfma_f32_32x32x16_bf16 v[0:15], v[64:67], v[72:75], v[0:15]
	v_mfma_f32_32x32x16_bf16 v[16:31], v[64:67], v[76:79], v[16:31]
	v_mfma_f32_32x32x16_bf16 v[0:15], v[68:71], v[220:223], v[0:15]
	v_mfma_f32_32x32x16_bf16 v[16:31], v[68:71], v[224:227], v[16:31]
	global_load_dwordx4 v[156:159], v235, s[84:85]
	global_load_dwordx4 v[160:163], v236, s[84:85]
	global_load_dwordx4 v[164:167], v237, s[84:85]
	global_load_dwordx4 v[168:171], v238, s[84:85]
	global_load_dwordx4 v[172:175], v100, s[84:85] offset:768
	global_load_dwordx4 v[176:179], v149, s[84:85] offset:768
	global_load_dwordx4 v[180:183], v100, s[84:85] offset:832
	global_load_dwordx4 v[184:187], v149, s[84:85] offset:832
	ds_read_b64_tr_b16 v[72:73], v231
	ds_read_b64_tr_b16 v[74:75], v231 offset:512
	ds_read_b64_tr_b16 v[76:77], v231 offset:2048
	ds_read_b64_tr_b16 v[78:79], v231 offset:2560
	ds_read_b64_tr_b16 v[220:221], v231 offset:1024
	ds_read_b64_tr_b16 v[222:223], v231 offset:1536
	ds_read_b64_tr_b16 v[224:225], v231 offset:3072
	ds_read_b64_tr_b16 v[226:227], v231 offset:3584
	s_waitcnt vmcnt(8)
	ds_write_b128 v247, v[116:119]
	ds_write_b128 v247, v[120:123] offset:1024
	ds_write_b128 v247, v[124:127] offset:2048
	ds_write_b128 v247, v[128:131] offset:3072
	ds_read_b128 v[116:119], v248
	ds_read_b128 v[120:123], v249
	ds_read_b128 v[124:127], v250
	ds_read_b128 v[128:131], v251
	ds_write_b128 v112, v[132:135]
	ds_write_b128 v112, v[136:139] offset:1024
	ds_write_b128 v112, v[140:143] offset:2048
	ds_write_b128 v112, v[144:147] offset:3072
	s_waitcnt lgkmcnt(4)
	v_mfma_f32_32x32x16_bf16 v[32:47], v[116:119], v[48:51], v[32:47]
	v_exp_f32_e32 v188, v188
	v_exp_f32_e32 v189, v189
	v_exp_f32_e32 v190, v190
	v_exp_f32_e32 v191, v191
	v_mfma_f32_32x32x16_bf16 v[32:47], v[120:123], v[52:55], v[32:47]
	v_exp_f32_e32 v192, v192
	v_exp_f32_e32 v193, v193
	v_exp_f32_e32 v194, v194
	v_exp_f32_e32 v195, v195
	v_mfma_f32_32x32x16_bf16 v[32:47], v[124:127], v[56:59], v[32:47]
	v_exp_f32_e32 v196, v196
	v_exp_f32_e32 v197, v197
	v_exp_f32_e32 v198, v198
	v_exp_f32_e32 v199, v199
	v_mfma_f32_32x32x16_bf16 v[32:47], v[128:131], v[60:63], v[32:47]
	v_exp_f32_e32 v200, v200
	v_exp_f32_e32 v201, v201
	v_exp_f32_e32 v202, v202
	v_exp_f32_e32 v203, v203
	v_cvt_pk_bf16_f32 v64, v188, v189
	v_cvt_pk_bf16_f32 v65, v190, v191
	v_cvt_pk_bf16_f32 v66, v192, v193
	v_cvt_pk_bf16_f32 v67, v194, v195
	v_cvt_pk_bf16_f32 v68, v196, v197
	v_cvt_pk_bf16_f32 v69, v198, v199
	v_cvt_pk_bf16_f32 v70, v200, v201
	v_cvt_pk_bf16_f32 v71, v202, v203
	v_pk_add_f32 v[232:233], v[232:233], v[188:189]
	v_pk_add_f32 v[232:233], v[232:233], v[190:191]
	v_pk_add_f32 v[232:233], v[232:233], v[192:193]
	v_pk_add_f32 v[232:233], v[232:233], v[194:195]
	v_pk_add_f32 v[232:233], v[232:233], v[196:197]
	v_pk_add_f32 v[232:233], v[232:233], v[198:199]
	v_pk_add_f32 v[232:233], v[232:233], v[200:201]
	v_pk_add_f32 v[232:233], v[232:233], v[202:203]
	ds_read2_b32 v[188:189], v115 offset0:170 offset1:171
	ds_read2_b32 v[190:191], v115 offset0:172 offset1:173
	ds_read2_b32 v[192:193], v115 offset0:178 offset1:179
	ds_read2_b32 v[194:195], v115 offset0:180 offset1:181
	ds_read2_b32 v[196:197], v115 offset0:187 offset1:188
	ds_read2_b32 v[198:199], v115 offset0:189 offset1:190
	ds_read2_b32 v[200:201], v115 offset0:195 offset1:196
	ds_read2_b32 v[202:203], v115 offset0:197 offset1:198
	v_mfma_f32_32x32x16_bf16 v[0:15], v[64:67], v[72:75], v[0:15]
	v_mfma_f32_32x32x16_bf16 v[16:31], v[64:67], v[76:79], v[16:31]
	v_mfma_f32_32x32x16_bf16 v[0:15], v[68:71], v[220:223], v[0:15]
	v_mfma_f32_32x32x16_bf16 v[16:31], v[68:71], v[224:227], v[16:31]
	global_load_dwordx4 v[116:119], v239, s[86:87]
	global_load_dwordx4 v[120:123], v240, s[86:87]
	global_load_dwordx4 v[124:127], v241, s[86:87]
	global_load_dwordx4 v[128:131], v242, s[86:87]
	global_load_dwordx4 v[132:135], v101, s[86:87] offset:768
	global_load_dwordx4 v[136:139], v150, s[86:87] offset:768
	global_load_dwordx4 v[140:143], v101, s[86:87] offset:832
	global_load_dwordx4 v[144:147], v150, s[86:87] offset:832
	s_add_u32 s86, s86, 0xc0000
	s_addc_u32 s87, s87, 0
	ds_read_b64_tr_b16 v[72:73], v231
	ds_read_b64_tr_b16 v[74:75], v231 offset:512
	ds_read_b64_tr_b16 v[76:77], v231 offset:2048
	ds_read_b64_tr_b16 v[78:79], v231 offset:2560
	ds_read_b64_tr_b16 v[220:221], v231 offset:1024
	ds_read_b64_tr_b16 v[222:223], v231 offset:1536
	ds_read_b64_tr_b16 v[224:225], v231 offset:3072
	ds_read_b64_tr_b16 v[226:227], v231 offset:3584
	s_waitcnt vmcnt(8)
	ds_write_b128 v247, v[156:159]
	ds_write_b128 v247, v[160:163] offset:1024
	ds_write_b128 v247, v[164:167] offset:2048
	ds_write_b128 v247, v[168:171] offset:3072
	ds_read_b128 v[156:159], v248
	ds_read_b128 v[160:163], v249
	ds_read_b128 v[164:167], v250
	ds_read_b128 v[168:171], v251
	ds_write_b128 v112, v[172:175]
	ds_write_b128 v112, v[176:179] offset:1024
	ds_write_b128 v112, v[180:183] offset:2048
	ds_write_b128 v112, v[184:187] offset:3072
	s_waitcnt lgkmcnt(4)
	v_mfma_f32_32x32x16_bf16 v[188:203], v[156:159], v[48:51], v[188:203]
	v_exp_f32_e32 v32, v32
	v_exp_f32_e32 v33, v33
	v_exp_f32_e32 v34, v34
	v_exp_f32_e32 v35, v35
	v_mfma_f32_32x32x16_bf16 v[188:203], v[160:163], v[52:55], v[188:203]
	v_exp_f32_e32 v36, v36
	v_exp_f32_e32 v37, v37
	v_exp_f32_e32 v38, v38
	v_exp_f32_e32 v39, v39
	v_mfma_f32_32x32x16_bf16 v[188:203], v[164:167], v[56:59], v[188:203]
	v_exp_f32_e32 v40, v40
	v_exp_f32_e32 v41, v41
	v_exp_f32_e32 v42, v42
	v_exp_f32_e32 v43, v43
	v_mfma_f32_32x32x16_bf16 v[188:203], v[168:171], v[60:63], v[188:203]
	v_exp_f32_e32 v44, v44
	v_exp_f32_e32 v45, v45
	v_exp_f32_e32 v46, v46
	v_exp_f32_e32 v47, v47
	v_cvt_pk_bf16_f32 v64, v32, v33
	v_cvt_pk_bf16_f32 v65, v34, v35
	v_cvt_pk_bf16_f32 v66, v36, v37
	v_cvt_pk_bf16_f32 v67, v38, v39
	v_cvt_pk_bf16_f32 v68, v40, v41
	v_cvt_pk_bf16_f32 v69, v42, v43
	v_cvt_pk_bf16_f32 v70, v44, v45
	v_cvt_pk_bf16_f32 v71, v46, v47
	v_pk_add_f32 v[232:233], v[232:233], v[32:33]
	v_pk_add_f32 v[232:233], v[232:233], v[34:35]
	v_pk_add_f32 v[232:233], v[232:233], v[36:37]
	v_pk_add_f32 v[232:233], v[232:233], v[38:39]
	v_pk_add_f32 v[232:233], v[232:233], v[40:41]
	v_pk_add_f32 v[232:233], v[232:233], v[42:43]
	v_pk_add_f32 v[232:233], v[232:233], v[44:45]
	v_pk_add_f32 v[232:233], v[232:233], v[46:47]
	v_mov_b32_e32 v115, v229
	ds_read2_b32 v[32:33], v115 offset0:0 offset1:1
	ds_read2_b32 v[34:35], v115 offset0:2 offset1:3
	ds_read2_b32 v[36:37], v115 offset0:8 offset1:9
	ds_read2_b32 v[38:39], v115 offset0:10 offset1:11
	ds_read2_b32 v[40:41], v115 offset0:16 offset1:17
	ds_read2_b32 v[42:43], v115 offset0:18 offset1:19
	ds_read2_b32 v[44:45], v115 offset0:24 offset1:25
	ds_read2_b32 v[46:47], v115 offset0:26 offset1:27
	v_mfma_f32_32x32x16_bf16 v[0:15], v[64:67], v[72:75], v[0:15]
	v_mfma_f32_32x32x16_bf16 v[16:31], v[64:67], v[76:79], v[16:31]
	v_mfma_f32_32x32x16_bf16 v[0:15], v[68:71], v[220:223], v[0:15]
	v_mfma_f32_32x32x16_bf16 v[16:31], v[68:71], v[224:227], v[16:31]
	global_load_dwordx4 v[156:159], v239, s[86:87]
	global_load_dwordx4 v[160:163], v240, s[86:87]
	global_load_dwordx4 v[164:167], v241, s[86:87]
	global_load_dwordx4 v[168:171], v242, s[86:87]
	global_load_dwordx4 v[172:175], v101, s[86:87] offset:768
	global_load_dwordx4 v[176:179], v150, s[86:87] offset:768
	global_load_dwordx4 v[180:183], v101, s[86:87] offset:832
	global_load_dwordx4 v[184:187], v150, s[86:87] offset:832
	s_add_u32 s86, s86, 0xc0000
	s_addc_u32 s87, s87, 0
	ds_read_b64_tr_b16 v[72:73], v231
	ds_read_b64_tr_b16 v[74:75], v231 offset:512
	ds_read_b64_tr_b16 v[76:77], v231 offset:2048
	ds_read_b64_tr_b16 v[78:79], v231 offset:2560
	ds_read_b64_tr_b16 v[220:221], v231 offset:1024
	ds_read_b64_tr_b16 v[222:223], v231 offset:1536
	ds_read_b64_tr_b16 v[224:225], v231 offset:3072
	ds_read_b64_tr_b16 v[226:227], v231 offset:3584
	s_waitcnt vmcnt(8)
	ds_write_b128 v247, v[116:119]
	ds_write_b128 v247, v[120:123] offset:1024
	ds_write_b128 v247, v[124:127] offset:2048
	ds_write_b128 v247, v[128:131] offset:3072
	ds_read_b128 v[116:119], v248
	ds_read_b128 v[120:123], v249
	ds_read_b128 v[124:127], v250
	ds_read_b128 v[128:131], v251
	ds_write_b128 v112, v[132:135]
	ds_write_b128 v112, v[136:139] offset:1024
	ds_write_b128 v112, v[140:143] offset:2048
	ds_write_b128 v112, v[144:147] offset:3072
	s_waitcnt lgkmcnt(4)
	v_mfma_f32_32x32x16_bf16 v[32:47], v[116:119], v[48:51], v[32:47]
	v_exp_f32_e32 v188, v188
	v_exp_f32_e32 v189, v189
	v_exp_f32_e32 v190, v190
	v_exp_f32_e32 v191, v191
	v_mfma_f32_32x32x16_bf16 v[32:47], v[120:123], v[52:55], v[32:47]
	v_exp_f32_e32 v192, v192
	v_exp_f32_e32 v193, v193
	v_exp_f32_e32 v194, v194
	v_exp_f32_e32 v195, v195
	v_mfma_f32_32x32x16_bf16 v[32:47], v[124:127], v[56:59], v[32:47]
	v_exp_f32_e32 v196, v196
	v_exp_f32_e32 v197, v197
	v_exp_f32_e32 v198, v198
	v_exp_f32_e32 v199, v199
	v_mfma_f32_32x32x16_bf16 v[32:47], v[128:131], v[60:63], v[32:47]
	v_exp_f32_e32 v200, v200
	v_exp_f32_e32 v201, v201
	v_exp_f32_e32 v202, v202
	v_exp_f32_e32 v203, v203
	v_cvt_pk_bf16_f32 v64, v188, v189
	v_cvt_pk_bf16_f32 v65, v190, v191
	v_cvt_pk_bf16_f32 v66, v192, v193
	v_cvt_pk_bf16_f32 v67, v194, v195
	v_cvt_pk_bf16_f32 v68, v196, v197
	v_cvt_pk_bf16_f32 v69, v198, v199
	v_cvt_pk_bf16_f32 v70, v200, v201
	v_cvt_pk_bf16_f32 v71, v202, v203
	v_pk_add_f32 v[232:233], v[232:233], v[188:189]
	v_pk_add_f32 v[232:233], v[232:233], v[190:191]
	v_pk_add_f32 v[232:233], v[232:233], v[192:193]
	v_pk_add_f32 v[232:233], v[232:233], v[194:195]
	v_pk_add_f32 v[232:233], v[232:233], v[196:197]
	v_pk_add_f32 v[232:233], v[232:233], v[198:199]
	v_pk_add_f32 v[232:233], v[232:233], v[200:201]
	v_pk_add_f32 v[232:233], v[232:233], v[202:203]
	ds_read2_b32 v[188:189], v115 offset0:32 offset1:33
	ds_read2_b32 v[190:191], v115 offset0:34 offset1:35
	ds_read2_b32 v[192:193], v115 offset0:40 offset1:41
	ds_read2_b32 v[194:195], v115 offset0:42 offset1:43
	ds_read2_b32 v[196:197], v115 offset0:48 offset1:49
	ds_read2_b32 v[198:199], v115 offset0:50 offset1:51
	ds_read2_b32 v[200:201], v115 offset0:56 offset1:57
	ds_read2_b32 v[202:203], v115 offset0:58 offset1:59
	v_mfma_f32_32x32x16_bf16 v[0:15], v[64:67], v[72:75], v[0:15]
	v_mfma_f32_32x32x16_bf16 v[16:31], v[64:67], v[76:79], v[16:31]
	v_mfma_f32_32x32x16_bf16 v[0:15], v[68:71], v[220:223], v[0:15]
	v_mfma_f32_32x32x16_bf16 v[16:31], v[68:71], v[224:227], v[16:31]
	global_load_dwordx4 v[116:119], v239, s[86:87]
	global_load_dwordx4 v[120:123], v240, s[86:87]
	global_load_dwordx4 v[124:127], v241, s[86:87]
	global_load_dwordx4 v[128:131], v242, s[86:87]
	global_load_dwordx4 v[132:135], v101, s[86:87] offset:768
	global_load_dwordx4 v[136:139], v150, s[86:87] offset:768
	global_load_dwordx4 v[140:143], v101, s[86:87] offset:832
	global_load_dwordx4 v[144:147], v150, s[86:87] offset:832
	s_add_u32 s86, s86, 0xc0000
	s_addc_u32 s87, s87, 0
	ds_read_b64_tr_b16 v[72:73], v231
	ds_read_b64_tr_b16 v[74:75], v231 offset:512
	ds_read_b64_tr_b16 v[76:77], v231 offset:2048
	ds_read_b64_tr_b16 v[78:79], v231 offset:2560
	ds_read_b64_tr_b16 v[220:221], v231 offset:1024
	ds_read_b64_tr_b16 v[222:223], v231 offset:1536
	ds_read_b64_tr_b16 v[224:225], v231 offset:3072
	ds_read_b64_tr_b16 v[226:227], v231 offset:3584
	s_waitcnt vmcnt(8)
	ds_write_b128 v247, v[156:159]
	ds_write_b128 v247, v[160:163] offset:1024
	ds_write_b128 v247, v[164:167] offset:2048
	ds_write_b128 v247, v[168:171] offset:3072
	ds_read_b128 v[156:159], v248
	ds_read_b128 v[160:163], v249
	ds_read_b128 v[164:167], v250
	ds_read_b128 v[168:171], v251
	ds_write_b128 v112, v[172:175]
	ds_write_b128 v112, v[176:179] offset:1024
	ds_write_b128 v112, v[180:183] offset:2048
	ds_write_b128 v112, v[184:187] offset:3072
	s_waitcnt lgkmcnt(4)
	v_mfma_f32_32x32x16_bf16 v[188:203], v[156:159], v[48:51], v[188:203]
	v_exp_f32_e32 v32, v32
	v_exp_f32_e32 v33, v33
	v_exp_f32_e32 v34, v34
	v_exp_f32_e32 v35, v35
	v_mfma_f32_32x32x16_bf16 v[188:203], v[160:163], v[52:55], v[188:203]
	v_exp_f32_e32 v36, v36
	v_exp_f32_e32 v37, v37
	v_exp_f32_e32 v38, v38
	v_exp_f32_e32 v39, v39
	v_mfma_f32_32x32x16_bf16 v[188:203], v[164:167], v[56:59], v[188:203]
	v_exp_f32_e32 v40, v40
	v_exp_f32_e32 v41, v41
	v_exp_f32_e32 v42, v42
	v_exp_f32_e32 v43, v43
	v_mfma_f32_32x32x16_bf16 v[188:203], v[168:171], v[60:63], v[188:203]
	v_exp_f32_e32 v44, v44
	v_exp_f32_e32 v45, v45
	v_exp_f32_e32 v46, v46
	v_exp_f32_e32 v47, v47
	v_cvt_pk_bf16_f32 v64, v32, v33
	v_cvt_pk_bf16_f32 v65, v34, v35
	v_cvt_pk_bf16_f32 v66, v36, v37
	v_cvt_pk_bf16_f32 v67, v38, v39
	v_cvt_pk_bf16_f32 v68, v40, v41
	v_cvt_pk_bf16_f32 v69, v42, v43
	v_cvt_pk_bf16_f32 v70, v44, v45
	v_cvt_pk_bf16_f32 v71, v46, v47
	v_pk_add_f32 v[232:233], v[232:233], v[32:33]
	v_pk_add_f32 v[232:233], v[232:233], v[34:35]
	v_pk_add_f32 v[232:233], v[232:233], v[36:37]
	v_pk_add_f32 v[232:233], v[232:233], v[38:39]
	v_pk_add_f32 v[232:233], v[232:233], v[40:41]
	v_pk_add_f32 v[232:233], v[232:233], v[42:43]
	v_pk_add_f32 v[232:233], v[232:233], v[44:45]
	v_pk_add_f32 v[232:233], v[232:233], v[46:47]
	ds_read2_b32 v[32:33], v115 offset0:64 offset1:65
	ds_read2_b32 v[34:35], v115 offset0:66 offset1:67
	ds_read2_b32 v[36:37], v115 offset0:72 offset1:73
	ds_read2_b32 v[38:39], v115 offset0:74 offset1:75
	ds_read2_b32 v[40:41], v115 offset0:80 offset1:81
	ds_read2_b32 v[42:43], v115 offset0:82 offset1:83
	ds_read2_b32 v[44:45], v115 offset0:88 offset1:89
	ds_read2_b32 v[46:47], v115 offset0:90 offset1:91
	v_mfma_f32_32x32x16_bf16 v[0:15], v[64:67], v[72:75], v[0:15]
	v_mfma_f32_32x32x16_bf16 v[16:31], v[64:67], v[76:79], v[16:31]
	v_mfma_f32_32x32x16_bf16 v[0:15], v[68:71], v[220:223], v[0:15]
	v_mfma_f32_32x32x16_bf16 v[16:31], v[68:71], v[224:227], v[16:31]
	global_load_dwordx4 v[156:159], v239, s[86:87]
	global_load_dwordx4 v[160:163], v240, s[86:87]
	global_load_dwordx4 v[164:167], v241, s[86:87]
	global_load_dwordx4 v[168:171], v242, s[86:87]
	global_load_dwordx4 v[172:175], v101, s[86:87] offset:768
	global_load_dwordx4 v[176:179], v150, s[86:87] offset:768
	global_load_dwordx4 v[180:183], v101, s[86:87] offset:832
	global_load_dwordx4 v[184:187], v150, s[86:87] offset:832
	s_add_u32 s86, s86, 0xc0000
	s_addc_u32 s87, s87, 0
	ds_read_b64_tr_b16 v[72:73], v231
	ds_read_b64_tr_b16 v[74:75], v231 offset:512
	ds_read_b64_tr_b16 v[76:77], v231 offset:2048
	ds_read_b64_tr_b16 v[78:79], v231 offset:2560
	ds_read_b64_tr_b16 v[220:221], v231 offset:1024
	ds_read_b64_tr_b16 v[222:223], v231 offset:1536
	ds_read_b64_tr_b16 v[224:225], v231 offset:3072
	ds_read_b64_tr_b16 v[226:227], v231 offset:3584
	s_waitcnt vmcnt(8)
	ds_write_b128 v247, v[116:119]
	ds_write_b128 v247, v[120:123] offset:1024
	ds_write_b128 v247, v[124:127] offset:2048
	ds_write_b128 v247, v[128:131] offset:3072
	ds_read_b128 v[116:119], v248
	ds_read_b128 v[120:123], v249
	ds_read_b128 v[124:127], v250
	ds_read_b128 v[128:131], v251
	ds_write_b128 v112, v[132:135]
	ds_write_b128 v112, v[136:139] offset:1024
	ds_write_b128 v112, v[140:143] offset:2048
	ds_write_b128 v112, v[144:147] offset:3072
	s_waitcnt lgkmcnt(4)
	v_mfma_f32_32x32x16_bf16 v[32:47], v[116:119], v[48:51], v[32:47]
	v_exp_f32_e32 v188, v188
	v_exp_f32_e32 v189, v189
	v_exp_f32_e32 v190, v190
	v_exp_f32_e32 v191, v191
	v_mfma_f32_32x32x16_bf16 v[32:47], v[120:123], v[52:55], v[32:47]
	v_exp_f32_e32 v192, v192
	v_exp_f32_e32 v193, v193
	v_exp_f32_e32 v194, v194
	v_exp_f32_e32 v195, v195
	v_mfma_f32_32x32x16_bf16 v[32:47], v[124:127], v[56:59], v[32:47]
	v_exp_f32_e32 v196, v196
	v_exp_f32_e32 v197, v197
	v_exp_f32_e32 v198, v198
	v_exp_f32_e32 v199, v199
	v_mfma_f32_32x32x16_bf16 v[32:47], v[128:131], v[60:63], v[32:47]
	v_exp_f32_e32 v200, v200
	v_exp_f32_e32 v201, v201
	v_exp_f32_e32 v202, v202
	v_exp_f32_e32 v203, v203
	v_cvt_pk_bf16_f32 v64, v188, v189
	v_cvt_pk_bf16_f32 v65, v190, v191
	v_cvt_pk_bf16_f32 v66, v192, v193
	v_cvt_pk_bf16_f32 v67, v194, v195
	v_cvt_pk_bf16_f32 v68, v196, v197
	v_cvt_pk_bf16_f32 v69, v198, v199
	v_cvt_pk_bf16_f32 v70, v200, v201
	v_cvt_pk_bf16_f32 v71, v202, v203
	v_pk_add_f32 v[232:233], v[232:233], v[188:189]
	v_pk_add_f32 v[232:233], v[232:233], v[190:191]
	v_pk_add_f32 v[232:233], v[232:233], v[192:193]
	v_pk_add_f32 v[232:233], v[232:233], v[194:195]
	v_pk_add_f32 v[232:233], v[232:233], v[196:197]
	v_pk_add_f32 v[232:233], v[232:233], v[198:199]
	v_pk_add_f32 v[232:233], v[232:233], v[200:201]
	v_pk_add_f32 v[232:233], v[232:233], v[202:203]
	ds_read2_b32 v[188:189], v115 offset0:96 offset1:97
	ds_read2_b32 v[190:191], v115 offset0:98 offset1:99
	ds_read2_b32 v[192:193], v115 offset0:104 offset1:105
	ds_read2_b32 v[194:195], v115 offset0:106 offset1:107
	ds_read2_b32 v[196:197], v115 offset0:112 offset1:113
	ds_read2_b32 v[198:199], v115 offset0:114 offset1:115
	ds_read2_b32 v[200:201], v115 offset0:120 offset1:121
	ds_read2_b32 v[202:203], v115 offset0:122 offset1:123
	v_mfma_f32_32x32x16_bf16 v[0:15], v[64:67], v[72:75], v[0:15]
	v_mfma_f32_32x32x16_bf16 v[16:31], v[64:67], v[76:79], v[16:31]
	v_mfma_f32_32x32x16_bf16 v[0:15], v[68:71], v[220:223], v[0:15]
	v_mfma_f32_32x32x16_bf16 v[16:31], v[68:71], v[224:227], v[16:31]
	global_load_dwordx4 v[116:119], v239, s[86:87]
	global_load_dwordx4 v[120:123], v240, s[86:87]
	global_load_dwordx4 v[124:127], v241, s[86:87]
	global_load_dwordx4 v[128:131], v242, s[86:87]
	global_load_dwordx4 v[132:135], v101, s[86:87] offset:768
	global_load_dwordx4 v[136:139], v150, s[86:87] offset:768
	global_load_dwordx4 v[140:143], v101, s[86:87] offset:832
	global_load_dwordx4 v[144:147], v150, s[86:87] offset:832
	s_add_u32 s86, s86, 0xc0000
	s_addc_u32 s87, s87, 0
	ds_read_b64_tr_b16 v[72:73], v231
	ds_read_b64_tr_b16 v[74:75], v231 offset:512
	ds_read_b64_tr_b16 v[76:77], v231 offset:2048
	ds_read_b64_tr_b16 v[78:79], v231 offset:2560
	ds_read_b64_tr_b16 v[220:221], v231 offset:1024
	ds_read_b64_tr_b16 v[222:223], v231 offset:1536
	ds_read_b64_tr_b16 v[224:225], v231 offset:3072
	ds_read_b64_tr_b16 v[226:227], v231 offset:3584
	s_waitcnt vmcnt(8)
	ds_write_b128 v247, v[156:159]
	ds_write_b128 v247, v[160:163] offset:1024
	ds_write_b128 v247, v[164:167] offset:2048
	ds_write_b128 v247, v[168:171] offset:3072
	ds_read_b128 v[156:159], v248
	ds_read_b128 v[160:163], v249
	ds_read_b128 v[164:167], v250
	ds_read_b128 v[168:171], v251
	ds_write_b128 v112, v[172:175]
	ds_write_b128 v112, v[176:179] offset:1024
	ds_write_b128 v112, v[180:183] offset:2048
	ds_write_b128 v112, v[184:187] offset:3072
	s_waitcnt lgkmcnt(4)
	v_mfma_f32_32x32x16_bf16 v[188:203], v[156:159], v[48:51], v[188:203]
	v_exp_f32_e32 v32, v32
	v_exp_f32_e32 v33, v33
	v_exp_f32_e32 v34, v34
	v_exp_f32_e32 v35, v35
	v_mfma_f32_32x32x16_bf16 v[188:203], v[160:163], v[52:55], v[188:203]
	v_exp_f32_e32 v36, v36
	v_exp_f32_e32 v37, v37
	v_exp_f32_e32 v38, v38
	v_exp_f32_e32 v39, v39
	v_mfma_f32_32x32x16_bf16 v[188:203], v[164:167], v[56:59], v[188:203]
	v_exp_f32_e32 v40, v40
	v_exp_f32_e32 v41, v41
	v_exp_f32_e32 v42, v42
	v_exp_f32_e32 v43, v43
	v_mfma_f32_32x32x16_bf16 v[188:203], v[168:171], v[60:63], v[188:203]
	v_exp_f32_e32 v44, v44
	v_exp_f32_e32 v45, v45
	v_exp_f32_e32 v46, v46
	v_exp_f32_e32 v47, v47
	v_cvt_pk_bf16_f32 v64, v32, v33
	v_cvt_pk_bf16_f32 v65, v34, v35
	v_cvt_pk_bf16_f32 v66, v36, v37
	v_cvt_pk_bf16_f32 v67, v38, v39
	v_cvt_pk_bf16_f32 v68, v40, v41
	v_cvt_pk_bf16_f32 v69, v42, v43
	v_cvt_pk_bf16_f32 v70, v44, v45
	v_cvt_pk_bf16_f32 v71, v46, v47
	v_pk_add_f32 v[232:233], v[232:233], v[32:33]
	v_pk_add_f32 v[232:233], v[232:233], v[34:35]
	v_pk_add_f32 v[232:233], v[232:233], v[36:37]
	v_pk_add_f32 v[232:233], v[232:233], v[38:39]
	v_pk_add_f32 v[232:233], v[232:233], v[40:41]
	v_pk_add_f32 v[232:233], v[232:233], v[42:43]
	v_pk_add_f32 v[232:233], v[232:233], v[44:45]
	v_pk_add_f32 v[232:233], v[232:233], v[46:47]
	ds_read2_b32 v[32:33], v115 offset0:128 offset1:129
	ds_read2_b32 v[34:35], v115 offset0:130 offset1:131
	ds_read2_b32 v[36:37], v115 offset0:136 offset1:137
	ds_read2_b32 v[38:39], v115 offset0:138 offset1:139
	ds_read2_b32 v[40:41], v115 offset0:144 offset1:145
	ds_read2_b32 v[42:43], v115 offset0:146 offset1:147
	ds_read2_b32 v[44:45], v115 offset0:152 offset1:153
	ds_read2_b32 v[46:47], v115 offset0:154 offset1:155
	v_mfma_f32_32x32x16_bf16 v[0:15], v[64:67], v[72:75], v[0:15]
	v_mfma_f32_32x32x16_bf16 v[16:31], v[64:67], v[76:79], v[16:31]
	v_mfma_f32_32x32x16_bf16 v[0:15], v[68:71], v[220:223], v[0:15]
	v_mfma_f32_32x32x16_bf16 v[16:31], v[68:71], v[224:227], v[16:31]
	global_load_dwordx4 v[156:159], v239, s[86:87]
	global_load_dwordx4 v[160:163], v240, s[86:87]
	global_load_dwordx4 v[164:167], v241, s[86:87]
	global_load_dwordx4 v[168:171], v242, s[86:87]
	global_load_dwordx4 v[172:175], v101, s[86:87] offset:768
	global_load_dwordx4 v[176:179], v150, s[86:87] offset:768
	global_load_dwordx4 v[180:183], v101, s[86:87] offset:832
	global_load_dwordx4 v[184:187], v150, s[86:87] offset:832
	s_add_u32 s86, s86, 0xc0000
	s_addc_u32 s87, s87, 0
	ds_read_b64_tr_b16 v[72:73], v231
	ds_read_b64_tr_b16 v[74:75], v231 offset:512
	ds_read_b64_tr_b16 v[76:77], v231 offset:2048
	ds_read_b64_tr_b16 v[78:79], v231 offset:2560
	ds_read_b64_tr_b16 v[220:221], v231 offset:1024
	ds_read_b64_tr_b16 v[222:223], v231 offset:1536
	ds_read_b64_tr_b16 v[224:225], v231 offset:3072
	ds_read_b64_tr_b16 v[226:227], v231 offset:3584
	s_waitcnt vmcnt(8)
	ds_write_b128 v247, v[116:119]
	ds_write_b128 v247, v[120:123] offset:1024
	ds_write_b128 v247, v[124:127] offset:2048
	ds_write_b128 v247, v[128:131] offset:3072
	ds_read_b128 v[116:119], v248
	ds_read_b128 v[120:123], v249
	ds_read_b128 v[124:127], v250
	ds_read_b128 v[128:131], v251
	ds_write_b128 v112, v[132:135]
	ds_write_b128 v112, v[136:139] offset:1024
	ds_write_b128 v112, v[140:143] offset:2048
	ds_write_b128 v112, v[144:147] offset:3072
	s_waitcnt lgkmcnt(4)
	v_mfma_f32_32x32x16_bf16 v[32:47], v[116:119], v[48:51], v[32:47]
	v_exp_f32_e32 v188, v188
	v_exp_f32_e32 v189, v189
	v_exp_f32_e32 v190, v190
	v_exp_f32_e32 v191, v191
	v_mfma_f32_32x32x16_bf16 v[32:47], v[120:123], v[52:55], v[32:47]
	v_exp_f32_e32 v192, v192
	v_exp_f32_e32 v193, v193
	v_exp_f32_e32 v194, v194
	v_exp_f32_e32 v195, v195
	v_mfma_f32_32x32x16_bf16 v[32:47], v[124:127], v[56:59], v[32:47]
	v_exp_f32_e32 v196, v196
	v_exp_f32_e32 v197, v197
	v_exp_f32_e32 v198, v198
	v_exp_f32_e32 v199, v199
	v_mfma_f32_32x32x16_bf16 v[32:47], v[128:131], v[60:63], v[32:47]
	v_exp_f32_e32 v200, v200
	v_exp_f32_e32 v201, v201
	v_exp_f32_e32 v202, v202
	v_exp_f32_e32 v203, v203
	v_cvt_pk_bf16_f32 v64, v188, v189
	v_cvt_pk_bf16_f32 v65, v190, v191
	v_cvt_pk_bf16_f32 v66, v192, v193
	v_cvt_pk_bf16_f32 v67, v194, v195
	v_cvt_pk_bf16_f32 v68, v196, v197
	v_cvt_pk_bf16_f32 v69, v198, v199
	v_cvt_pk_bf16_f32 v70, v200, v201
	v_cvt_pk_bf16_f32 v71, v202, v203
	v_pk_add_f32 v[232:233], v[232:233], v[188:189]
	v_pk_add_f32 v[232:233], v[232:233], v[190:191]
	v_pk_add_f32 v[232:233], v[232:233], v[192:193]
	v_pk_add_f32 v[232:233], v[232:233], v[194:195]
	v_pk_add_f32 v[232:233], v[232:233], v[196:197]
	v_pk_add_f32 v[232:233], v[232:233], v[198:199]
	v_pk_add_f32 v[232:233], v[232:233], v[200:201]
	v_pk_add_f32 v[232:233], v[232:233], v[202:203]
	ds_read2_b32 v[188:189], v115 offset0:160 offset1:161
	ds_read2_b32 v[190:191], v115 offset0:162 offset1:163
	ds_read2_b32 v[192:193], v115 offset0:168 offset1:169
	ds_read2_b32 v[194:195], v115 offset0:170 offset1:171
	ds_read2_b32 v[196:197], v115 offset0:176 offset1:177
	ds_read2_b32 v[198:199], v115 offset0:178 offset1:179
	ds_read2_b32 v[200:201], v115 offset0:184 offset1:185
	ds_read2_b32 v[202:203], v115 offset0:186 offset1:187
	v_mfma_f32_32x32x16_bf16 v[0:15], v[64:67], v[72:75], v[0:15]
	v_mfma_f32_32x32x16_bf16 v[16:31], v[64:67], v[76:79], v[16:31]
	v_mfma_f32_32x32x16_bf16 v[0:15], v[68:71], v[220:223], v[0:15]
	v_mfma_f32_32x32x16_bf16 v[16:31], v[68:71], v[224:227], v[16:31]
	global_load_dwordx4 v[116:119], v239, s[86:87]
	global_load_dwordx4 v[120:123], v240, s[86:87]
	global_load_dwordx4 v[124:127], v241, s[86:87]
	global_load_dwordx4 v[128:131], v242, s[86:87]
	global_load_dwordx4 v[132:135], v101, s[86:87] offset:768
	global_load_dwordx4 v[136:139], v150, s[86:87] offset:768
	global_load_dwordx4 v[140:143], v101, s[86:87] offset:832
	global_load_dwordx4 v[144:147], v150, s[86:87] offset:832
	s_add_u32 s86, s86, 0xc0000
	s_addc_u32 s87, s87, 0
	ds_read_b64_tr_b16 v[72:73], v231
	ds_read_b64_tr_b16 v[74:75], v231 offset:512
	ds_read_b64_tr_b16 v[76:77], v231 offset:2048
	ds_read_b64_tr_b16 v[78:79], v231 offset:2560
	ds_read_b64_tr_b16 v[220:221], v231 offset:1024
	ds_read_b64_tr_b16 v[222:223], v231 offset:1536
	ds_read_b64_tr_b16 v[224:225], v231 offset:3072
	ds_read_b64_tr_b16 v[226:227], v231 offset:3584
	s_waitcnt vmcnt(8)
	ds_write_b128 v247, v[156:159]
	ds_write_b128 v247, v[160:163] offset:1024
	ds_write_b128 v247, v[164:167] offset:2048
	ds_write_b128 v247, v[168:171] offset:3072
	ds_read_b128 v[156:159], v248
	ds_read_b128 v[160:163], v249
	ds_read_b128 v[164:167], v250
	ds_read_b128 v[168:171], v251
	ds_write_b128 v112, v[172:175]
	ds_write_b128 v112, v[176:179] offset:1024
	ds_write_b128 v112, v[180:183] offset:2048
	ds_write_b128 v112, v[184:187] offset:3072
	s_waitcnt lgkmcnt(4)
	v_mfma_f32_32x32x16_bf16 v[188:203], v[156:159], v[48:51], v[188:203]
	v_exp_f32_e32 v32, v32
	v_exp_f32_e32 v33, v33
	v_exp_f32_e32 v34, v34
	v_exp_f32_e32 v35, v35
	v_mfma_f32_32x32x16_bf16 v[188:203], v[160:163], v[52:55], v[188:203]
	v_exp_f32_e32 v36, v36
	v_exp_f32_e32 v37, v37
	v_exp_f32_e32 v38, v38
	v_exp_f32_e32 v39, v39
	v_mfma_f32_32x32x16_bf16 v[188:203], v[164:167], v[56:59], v[188:203]
	v_exp_f32_e32 v40, v40
	v_exp_f32_e32 v41, v41
	v_exp_f32_e32 v42, v42
	v_exp_f32_e32 v43, v43
	v_mfma_f32_32x32x16_bf16 v[188:203], v[168:171], v[60:63], v[188:203]
	v_exp_f32_e32 v44, v44
	v_exp_f32_e32 v45, v45
	v_exp_f32_e32 v46, v46
	v_exp_f32_e32 v47, v47
	v_cvt_pk_bf16_f32 v64, v32, v33
	v_cvt_pk_bf16_f32 v65, v34, v35
	v_cvt_pk_bf16_f32 v66, v36, v37
	v_cvt_pk_bf16_f32 v67, v38, v39
	v_cvt_pk_bf16_f32 v68, v40, v41
	v_cvt_pk_bf16_f32 v69, v42, v43
	v_cvt_pk_bf16_f32 v70, v44, v45
	v_cvt_pk_bf16_f32 v71, v46, v47
	v_pk_add_f32 v[232:233], v[232:233], v[32:33]
	v_pk_add_f32 v[232:233], v[232:233], v[34:35]
	v_pk_add_f32 v[232:233], v[232:233], v[36:37]
	v_pk_add_f32 v[232:233], v[232:233], v[38:39]
	v_pk_add_f32 v[232:233], v[232:233], v[40:41]
	v_pk_add_f32 v[232:233], v[232:233], v[42:43]
	v_pk_add_f32 v[232:233], v[232:233], v[44:45]
	v_pk_add_f32 v[232:233], v[232:233], v[46:47]
	ds_read2_b32 v[32:33], v115 offset0:192 offset1:193
	ds_read2_b32 v[34:35], v115 offset0:194 offset1:195
	ds_read2_b32 v[36:37], v115 offset0:200 offset1:201
	ds_read2_b32 v[38:39], v115 offset0:202 offset1:203
	ds_read2_b32 v[40:41], v115 offset0:208 offset1:209
	ds_read2_b32 v[42:43], v115 offset0:210 offset1:211
	ds_read2_b32 v[44:45], v115 offset0:216 offset1:217
	ds_read2_b32 v[46:47], v115 offset0:218 offset1:219
	v_mfma_f32_32x32x16_bf16 v[0:15], v[64:67], v[72:75], v[0:15]
	v_mfma_f32_32x32x16_bf16 v[16:31], v[64:67], v[76:79], v[16:31]
	v_mfma_f32_32x32x16_bf16 v[0:15], v[68:71], v[220:223], v[0:15]
	v_mfma_f32_32x32x16_bf16 v[16:31], v[68:71], v[224:227], v[16:31]
	global_load_dwordx4 v[156:159], v239, s[86:87]
	global_load_dwordx4 v[160:163], v240, s[86:87]
	global_load_dwordx4 v[164:167], v241, s[86:87]
	global_load_dwordx4 v[168:171], v242, s[86:87]
	global_load_dwordx4 v[172:175], v101, s[86:87] offset:768
	global_load_dwordx4 v[176:179], v150, s[86:87] offset:768
	global_load_dwordx4 v[180:183], v101, s[86:87] offset:832
	global_load_dwordx4 v[184:187], v150, s[86:87] offset:832
	ds_read_b64_tr_b16 v[72:73], v231
	ds_read_b64_tr_b16 v[74:75], v231 offset:512
	ds_read_b64_tr_b16 v[76:77], v231 offset:2048
	ds_read_b64_tr_b16 v[78:79], v231 offset:2560
	ds_read_b64_tr_b16 v[220:221], v231 offset:1024
	ds_read_b64_tr_b16 v[222:223], v231 offset:1536
	ds_read_b64_tr_b16 v[224:225], v231 offset:3072
	ds_read_b64_tr_b16 v[226:227], v231 offset:3584
	s_waitcnt vmcnt(8)
	ds_write_b128 v247, v[116:119]
	ds_write_b128 v247, v[120:123] offset:1024
	ds_write_b128 v247, v[124:127] offset:2048
	ds_write_b128 v247, v[128:131] offset:3072
	ds_read_b128 v[116:119], v248
	ds_read_b128 v[120:123], v249
	ds_read_b128 v[124:127], v250
	ds_read_b128 v[128:131], v251
	ds_write_b128 v112, v[132:135]
	ds_write_b128 v112, v[136:139] offset:1024
	ds_write_b128 v112, v[140:143] offset:2048
	ds_write_b128 v112, v[144:147] offset:3072
	s_waitcnt lgkmcnt(4)
	v_mfma_f32_32x32x16_bf16 v[32:47], v[116:119], v[48:51], v[32:47]
	v_exp_f32_e32 v188, v188
	v_exp_f32_e32 v189, v189
	v_exp_f32_e32 v190, v190
	v_exp_f32_e32 v191, v191
	v_mfma_f32_32x32x16_bf16 v[32:47], v[120:123], v[52:55], v[32:47]
	v_exp_f32_e32 v192, v192
	v_exp_f32_e32 v193, v193
	v_exp_f32_e32 v194, v194
	v_exp_f32_e32 v195, v195
	v_mfma_f32_32x32x16_bf16 v[32:47], v[124:127], v[56:59], v[32:47]
	v_exp_f32_e32 v196, v196
	v_exp_f32_e32 v197, v197
	v_exp_f32_e32 v198, v198
	v_exp_f32_e32 v199, v199
	v_mfma_f32_32x32x16_bf16 v[32:47], v[128:131], v[60:63], v[32:47]
	v_exp_f32_e32 v200, v200
	v_exp_f32_e32 v201, v201
	v_exp_f32_e32 v202, v202
	v_exp_f32_e32 v203, v203
	v_cvt_pk_bf16_f32 v64, v188, v189
	v_cvt_pk_bf16_f32 v65, v190, v191
	v_cvt_pk_bf16_f32 v66, v192, v193
	v_cvt_pk_bf16_f32 v67, v194, v195
	v_cvt_pk_bf16_f32 v68, v196, v197
	v_cvt_pk_bf16_f32 v69, v198, v199
	v_cvt_pk_bf16_f32 v70, v200, v201
	v_cvt_pk_bf16_f32 v71, v202, v203
	v_pk_add_f32 v[232:233], v[232:233], v[188:189]
	v_pk_add_f32 v[232:233], v[232:233], v[190:191]
	v_pk_add_f32 v[232:233], v[232:233], v[192:193]
	v_pk_add_f32 v[232:233], v[232:233], v[194:195]
	v_pk_add_f32 v[232:233], v[232:233], v[196:197]
	v_pk_add_f32 v[232:233], v[232:233], v[198:199]
	v_pk_add_f32 v[232:233], v[232:233], v[200:201]
	v_pk_add_f32 v[232:233], v[232:233], v[202:203]
	ds_read2_b32 v[188:189], v115 offset0:224 offset1:225
	ds_read2_b32 v[190:191], v115 offset0:226 offset1:227
	ds_read2_b32 v[192:193], v115 offset0:232 offset1:233
	ds_read2_b32 v[194:195], v115 offset0:234 offset1:235
	ds_read2_b32 v[196:197], v115 offset0:240 offset1:241
	ds_read2_b32 v[198:199], v115 offset0:242 offset1:243
	ds_read2_b32 v[200:201], v115 offset0:248 offset1:249
	ds_read2_b32 v[202:203], v115 offset0:250 offset1:251
	v_mfma_f32_32x32x16_bf16 v[0:15], v[64:67], v[72:75], v[0:15]
	v_mfma_f32_32x32x16_bf16 v[16:31], v[64:67], v[76:79], v[16:31]
	v_mfma_f32_32x32x16_bf16 v[0:15], v[68:71], v[220:223], v[0:15]
	v_mfma_f32_32x32x16_bf16 v[16:31], v[68:71], v[224:227], v[16:31]
	global_load_dwordx4 v[116:119], v243, s[88:89]
	global_load_dwordx4 v[120:123], v244, s[88:89]
	global_load_dwordx4 v[124:127], v245, s[88:89]
	global_load_dwordx4 v[128:131], v246, s[88:89]
	global_load_dwordx4 v[132:135], v148, s[88:89] offset:768
	global_load_dwordx4 v[136:139], v151, s[88:89] offset:768
	global_load_dwordx4 v[140:143], v148, s[88:89] offset:832
	global_load_dwordx4 v[144:147], v151, s[88:89] offset:832
	s_add_u32 s88, s88, 0x300000
	s_addc_u32 s89, s89, 0
	ds_read_b64_tr_b16 v[72:73], v231
	ds_read_b64_tr_b16 v[74:75], v231 offset:512
	ds_read_b64_tr_b16 v[76:77], v231 offset:2048
	ds_read_b64_tr_b16 v[78:79], v231 offset:2560
	ds_read_b64_tr_b16 v[220:221], v231 offset:1024
	ds_read_b64_tr_b16 v[222:223], v231 offset:1536
	ds_read_b64_tr_b16 v[224:225], v231 offset:3072
	ds_read_b64_tr_b16 v[226:227], v231 offset:3584
	s_waitcnt vmcnt(8)
	ds_write_b128 v247, v[156:159]
	ds_write_b128 v247, v[160:163] offset:1024
	ds_write_b128 v247, v[164:167] offset:2048
	ds_write_b128 v247, v[168:171] offset:3072
	ds_read_b128 v[156:159], v248
	ds_read_b128 v[160:163], v249
	ds_read_b128 v[164:167], v250
	ds_read_b128 v[168:171], v251
	ds_write_b128 v112, v[172:175]
	ds_write_b128 v112, v[176:179] offset:1024
	ds_write_b128 v112, v[180:183] offset:2048
	ds_write_b128 v112, v[184:187] offset:3072
	s_waitcnt lgkmcnt(4)
	v_mfma_f32_32x32x16_bf16 v[188:203], v[156:159], v[48:51], v[188:203]
	v_exp_f32_e32 v32, v32
	v_exp_f32_e32 v33, v33
	v_exp_f32_e32 v34, v34
	v_exp_f32_e32 v35, v35
	v_mfma_f32_32x32x16_bf16 v[188:203], v[160:163], v[52:55], v[188:203]
	v_exp_f32_e32 v36, v36
	v_exp_f32_e32 v37, v37
	v_exp_f32_e32 v38, v38
	v_exp_f32_e32 v39, v39
	v_mfma_f32_32x32x16_bf16 v[188:203], v[164:167], v[56:59], v[188:203]
	v_exp_f32_e32 v40, v40
	v_exp_f32_e32 v41, v41
	v_exp_f32_e32 v42, v42
	v_exp_f32_e32 v43, v43
	v_mfma_f32_32x32x16_bf16 v[188:203], v[168:171], v[60:63], v[188:203]
	v_exp_f32_e32 v44, v44
	v_exp_f32_e32 v45, v45
	v_exp_f32_e32 v46, v46
	v_exp_f32_e32 v47, v47
	v_cvt_pk_bf16_f32 v64, v32, v33
	v_cvt_pk_bf16_f32 v65, v34, v35
	v_cvt_pk_bf16_f32 v66, v36, v37
	v_cvt_pk_bf16_f32 v67, v38, v39
	v_cvt_pk_bf16_f32 v68, v40, v41
	v_cvt_pk_bf16_f32 v69, v42, v43
	v_cvt_pk_bf16_f32 v70, v44, v45
	v_cvt_pk_bf16_f32 v71, v46, v47
	v_pk_add_f32 v[232:233], v[232:233], v[32:33]
	v_pk_add_f32 v[232:233], v[232:233], v[34:35]
	v_pk_add_f32 v[232:233], v[232:233], v[36:37]
	v_pk_add_f32 v[232:233], v[232:233], v[38:39]
	v_pk_add_f32 v[232:233], v[232:233], v[40:41]
	v_pk_add_f32 v[232:233], v[232:233], v[42:43]
	v_pk_add_f32 v[232:233], v[232:233], v[44:45]
	v_pk_add_f32 v[232:233], v[232:233], v[46:47]
	v_mov_b32_e32 v115, v230
	ds_read2_b32 v[32:33], v115 offset0:0 offset1:1
	ds_read2_b32 v[34:35], v115 offset0:2 offset1:3
	ds_read2_b32 v[36:37], v115 offset0:8 offset1:9
	ds_read2_b32 v[38:39], v115 offset0:10 offset1:11
	ds_read2_b32 v[40:41], v115 offset0:16 offset1:17
	ds_read2_b32 v[42:43], v115 offset0:18 offset1:19
	ds_read2_b32 v[44:45], v115 offset0:24 offset1:25
	ds_read2_b32 v[46:47], v115 offset0:26 offset1:27
	v_mfma_f32_32x32x16_bf16 v[0:15], v[64:67], v[72:75], v[0:15]
	v_mfma_f32_32x32x16_bf16 v[16:31], v[64:67], v[76:79], v[16:31]
	v_mfma_f32_32x32x16_bf16 v[0:15], v[68:71], v[220:223], v[0:15]
	v_mfma_f32_32x32x16_bf16 v[16:31], v[68:71], v[224:227], v[16:31]
	global_load_dwordx4 v[156:159], v243, s[88:89]
	global_load_dwordx4 v[160:163], v244, s[88:89]
	global_load_dwordx4 v[164:167], v245, s[88:89]
	global_load_dwordx4 v[168:171], v246, s[88:89]
	global_load_dwordx4 v[172:175], v148, s[88:89] offset:768
	global_load_dwordx4 v[176:179], v151, s[88:89] offset:768
	global_load_dwordx4 v[180:183], v148, s[88:89] offset:832
	global_load_dwordx4 v[184:187], v151, s[88:89] offset:832
	s_add_u32 s88, s88, 0x300000
	s_addc_u32 s89, s89, 0
	ds_read_b64_tr_b16 v[72:73], v231
	ds_read_b64_tr_b16 v[74:75], v231 offset:512
	ds_read_b64_tr_b16 v[76:77], v231 offset:2048
	ds_read_b64_tr_b16 v[78:79], v231 offset:2560
	ds_read_b64_tr_b16 v[220:221], v231 offset:1024
	ds_read_b64_tr_b16 v[222:223], v231 offset:1536
	ds_read_b64_tr_b16 v[224:225], v231 offset:3072
	ds_read_b64_tr_b16 v[226:227], v231 offset:3584
	s_waitcnt vmcnt(8)
	ds_write_b128 v247, v[116:119]
	ds_write_b128 v247, v[120:123] offset:1024
	ds_write_b128 v247, v[124:127] offset:2048
	ds_write_b128 v247, v[128:131] offset:3072
	ds_read_b128 v[116:119], v248
	ds_read_b128 v[120:123], v249
	ds_read_b128 v[124:127], v250
	ds_read_b128 v[128:131], v251
	ds_write_b128 v112, v[132:135]
	ds_write_b128 v112, v[136:139] offset:1024
	ds_write_b128 v112, v[140:143] offset:2048
	ds_write_b128 v112, v[144:147] offset:3072
	s_waitcnt lgkmcnt(4)
	v_mfma_f32_32x32x16_bf16 v[32:47], v[116:119], v[48:51], v[32:47]
	v_exp_f32_e32 v188, v188
	v_exp_f32_e32 v189, v189
	v_exp_f32_e32 v190, v190
	v_exp_f32_e32 v191, v191
	v_mfma_f32_32x32x16_bf16 v[32:47], v[120:123], v[52:55], v[32:47]
	v_exp_f32_e32 v192, v192
	v_exp_f32_e32 v193, v193
	v_exp_f32_e32 v194, v194
	v_exp_f32_e32 v195, v195
	v_mfma_f32_32x32x16_bf16 v[32:47], v[124:127], v[56:59], v[32:47]
	v_exp_f32_e32 v196, v196
	v_exp_f32_e32 v197, v197
	v_exp_f32_e32 v198, v198
	v_exp_f32_e32 v199, v199
	v_mfma_f32_32x32x16_bf16 v[32:47], v[128:131], v[60:63], v[32:47]
	v_exp_f32_e32 v200, v200
	v_exp_f32_e32 v201, v201
	v_exp_f32_e32 v202, v202
	v_exp_f32_e32 v203, v203
	v_cvt_pk_bf16_f32 v64, v188, v189
	v_cvt_pk_bf16_f32 v65, v190, v191
	v_cvt_pk_bf16_f32 v66, v192, v193
	v_cvt_pk_bf16_f32 v67, v194, v195
	v_cvt_pk_bf16_f32 v68, v196, v197
	v_cvt_pk_bf16_f32 v69, v198, v199
	v_cvt_pk_bf16_f32 v70, v200, v201
	v_cvt_pk_bf16_f32 v71, v202, v203
	v_pk_add_f32 v[232:233], v[232:233], v[188:189]
	v_pk_add_f32 v[232:233], v[232:233], v[190:191]
	v_pk_add_f32 v[232:233], v[232:233], v[192:193]
	v_pk_add_f32 v[232:233], v[232:233], v[194:195]
	v_pk_add_f32 v[232:233], v[232:233], v[196:197]
	v_pk_add_f32 v[232:233], v[232:233], v[198:199]
	v_pk_add_f32 v[232:233], v[232:233], v[200:201]
	v_pk_add_f32 v[232:233], v[232:233], v[202:203]
	ds_read2_b32 v[188:189], v115 offset0:32 offset1:33
	ds_read2_b32 v[190:191], v115 offset0:34 offset1:35
	ds_read2_b32 v[192:193], v115 offset0:40 offset1:41
	ds_read2_b32 v[194:195], v115 offset0:42 offset1:43
	ds_read2_b32 v[196:197], v115 offset0:48 offset1:49
	ds_read2_b32 v[198:199], v115 offset0:50 offset1:51
	ds_read2_b32 v[200:201], v115 offset0:56 offset1:57
	ds_read2_b32 v[202:203], v115 offset0:58 offset1:59
	v_mfma_f32_32x32x16_bf16 v[0:15], v[64:67], v[72:75], v[0:15]
	v_mfma_f32_32x32x16_bf16 v[16:31], v[64:67], v[76:79], v[16:31]
	v_mfma_f32_32x32x16_bf16 v[0:15], v[68:71], v[220:223], v[0:15]
	v_mfma_f32_32x32x16_bf16 v[16:31], v[68:71], v[224:227], v[16:31]
	global_load_dwordx4 v[116:119], v243, s[88:89]
	global_load_dwordx4 v[120:123], v244, s[88:89]
	global_load_dwordx4 v[124:127], v245, s[88:89]
	global_load_dwordx4 v[128:131], v246, s[88:89]
	global_load_dwordx4 v[132:135], v148, s[88:89] offset:768
	global_load_dwordx4 v[136:139], v151, s[88:89] offset:768
	global_load_dwordx4 v[140:143], v148, s[88:89] offset:832
	global_load_dwordx4 v[144:147], v151, s[88:89] offset:832
	s_add_u32 s88, s88, 0x300000
	s_addc_u32 s89, s89, 0
	ds_read_b64_tr_b16 v[72:73], v231
	ds_read_b64_tr_b16 v[74:75], v231 offset:512
	ds_read_b64_tr_b16 v[76:77], v231 offset:2048
	ds_read_b64_tr_b16 v[78:79], v231 offset:2560
	ds_read_b64_tr_b16 v[220:221], v231 offset:1024
	ds_read_b64_tr_b16 v[222:223], v231 offset:1536
	ds_read_b64_tr_b16 v[224:225], v231 offset:3072
	ds_read_b64_tr_b16 v[226:227], v231 offset:3584
	s_waitcnt vmcnt(8)
	ds_write_b128 v247, v[156:159]
	ds_write_b128 v247, v[160:163] offset:1024
	ds_write_b128 v247, v[164:167] offset:2048
	ds_write_b128 v247, v[168:171] offset:3072
	ds_read_b128 v[156:159], v248
	ds_read_b128 v[160:163], v249
	ds_read_b128 v[164:167], v250
	ds_read_b128 v[168:171], v251
	ds_write_b128 v112, v[172:175]
	ds_write_b128 v112, v[176:179] offset:1024
	ds_write_b128 v112, v[180:183] offset:2048
	ds_write_b128 v112, v[184:187] offset:3072
	s_waitcnt lgkmcnt(4)
	v_mfma_f32_32x32x16_bf16 v[188:203], v[156:159], v[48:51], v[188:203]
	v_exp_f32_e32 v32, v32
	v_exp_f32_e32 v33, v33
	v_exp_f32_e32 v34, v34
	v_exp_f32_e32 v35, v35
	v_mfma_f32_32x32x16_bf16 v[188:203], v[160:163], v[52:55], v[188:203]
	v_exp_f32_e32 v36, v36
	v_exp_f32_e32 v37, v37
	v_exp_f32_e32 v38, v38
	v_exp_f32_e32 v39, v39
	v_mfma_f32_32x32x16_bf16 v[188:203], v[164:167], v[56:59], v[188:203]
	v_exp_f32_e32 v40, v40
	v_exp_f32_e32 v41, v41
	v_exp_f32_e32 v42, v42
	v_exp_f32_e32 v43, v43
	v_mfma_f32_32x32x16_bf16 v[188:203], v[168:171], v[60:63], v[188:203]
	v_exp_f32_e32 v44, v44
	v_exp_f32_e32 v45, v45
	v_exp_f32_e32 v46, v46
	v_exp_f32_e32 v47, v47
	v_cvt_pk_bf16_f32 v64, v32, v33
	v_cvt_pk_bf16_f32 v65, v34, v35
	v_cvt_pk_bf16_f32 v66, v36, v37
	v_cvt_pk_bf16_f32 v67, v38, v39
	v_cvt_pk_bf16_f32 v68, v40, v41
	v_cvt_pk_bf16_f32 v69, v42, v43
	v_cvt_pk_bf16_f32 v70, v44, v45
	v_cvt_pk_bf16_f32 v71, v46, v47
	v_pk_add_f32 v[232:233], v[232:233], v[32:33]
	v_pk_add_f32 v[232:233], v[232:233], v[34:35]
	v_pk_add_f32 v[232:233], v[232:233], v[36:37]
	v_pk_add_f32 v[232:233], v[232:233], v[38:39]
	v_pk_add_f32 v[232:233], v[232:233], v[40:41]
	v_pk_add_f32 v[232:233], v[232:233], v[42:43]
	v_pk_add_f32 v[232:233], v[232:233], v[44:45]
	v_pk_add_f32 v[232:233], v[232:233], v[46:47]
	ds_read2_b32 v[32:33], v115 offset0:64 offset1:65
	ds_read2_b32 v[34:35], v115 offset0:66 offset1:67
	ds_read2_b32 v[36:37], v115 offset0:72 offset1:73
	ds_read2_b32 v[38:39], v115 offset0:74 offset1:75
	ds_read2_b32 v[40:41], v115 offset0:80 offset1:81
	ds_read2_b32 v[42:43], v115 offset0:82 offset1:83
	ds_read2_b32 v[44:45], v115 offset0:88 offset1:89
	ds_read2_b32 v[46:47], v115 offset0:90 offset1:91
	v_mfma_f32_32x32x16_bf16 v[0:15], v[64:67], v[72:75], v[0:15]
	v_mfma_f32_32x32x16_bf16 v[16:31], v[64:67], v[76:79], v[16:31]
	v_mfma_f32_32x32x16_bf16 v[0:15], v[68:71], v[220:223], v[0:15]
	v_mfma_f32_32x32x16_bf16 v[16:31], v[68:71], v[224:227], v[16:31]
	global_load_dwordx4 v[156:159], v243, s[88:89]
	global_load_dwordx4 v[160:163], v244, s[88:89]
	global_load_dwordx4 v[164:167], v245, s[88:89]
	global_load_dwordx4 v[168:171], v246, s[88:89]
	global_load_dwordx4 v[172:175], v148, s[88:89] offset:768
	global_load_dwordx4 v[176:179], v151, s[88:89] offset:768
	global_load_dwordx4 v[180:183], v148, s[88:89] offset:832
	global_load_dwordx4 v[184:187], v151, s[88:89] offset:832
	s_add_u32 s88, s88, 0x300000
	s_addc_u32 s89, s89, 0
	ds_read_b64_tr_b16 v[72:73], v231
	ds_read_b64_tr_b16 v[74:75], v231 offset:512
	ds_read_b64_tr_b16 v[76:77], v231 offset:2048
	ds_read_b64_tr_b16 v[78:79], v231 offset:2560
	ds_read_b64_tr_b16 v[220:221], v231 offset:1024
	ds_read_b64_tr_b16 v[222:223], v231 offset:1536
	ds_read_b64_tr_b16 v[224:225], v231 offset:3072
	ds_read_b64_tr_b16 v[226:227], v231 offset:3584
	s_waitcnt vmcnt(8)
	ds_write_b128 v247, v[116:119]
	ds_write_b128 v247, v[120:123] offset:1024
	ds_write_b128 v247, v[124:127] offset:2048
	ds_write_b128 v247, v[128:131] offset:3072
	ds_read_b128 v[116:119], v248
	ds_read_b128 v[120:123], v249
	ds_read_b128 v[124:127], v250
	ds_read_b128 v[128:131], v251
	ds_write_b128 v112, v[132:135]
	ds_write_b128 v112, v[136:139] offset:1024
	ds_write_b128 v112, v[140:143] offset:2048
	ds_write_b128 v112, v[144:147] offset:3072
	s_waitcnt lgkmcnt(4)
	v_mfma_f32_32x32x16_bf16 v[32:47], v[116:119], v[48:51], v[32:47]
	v_exp_f32_e32 v188, v188
	v_exp_f32_e32 v189, v189
	v_exp_f32_e32 v190, v190
	v_exp_f32_e32 v191, v191
	v_mfma_f32_32x32x16_bf16 v[32:47], v[120:123], v[52:55], v[32:47]
	v_exp_f32_e32 v192, v192
	v_exp_f32_e32 v193, v193
	v_exp_f32_e32 v194, v194
	v_exp_f32_e32 v195, v195
	v_mfma_f32_32x32x16_bf16 v[32:47], v[124:127], v[56:59], v[32:47]
	v_exp_f32_e32 v196, v196
	v_exp_f32_e32 v197, v197
	v_exp_f32_e32 v198, v198
	v_exp_f32_e32 v199, v199
	v_mfma_f32_32x32x16_bf16 v[32:47], v[128:131], v[60:63], v[32:47]
	v_exp_f32_e32 v200, v200
	v_exp_f32_e32 v201, v201
	v_exp_f32_e32 v202, v202
	v_exp_f32_e32 v203, v203
	v_cvt_pk_bf16_f32 v64, v188, v189
	v_cvt_pk_bf16_f32 v65, v190, v191
	v_cvt_pk_bf16_f32 v66, v192, v193
	v_cvt_pk_bf16_f32 v67, v194, v195
	v_cvt_pk_bf16_f32 v68, v196, v197
	v_cvt_pk_bf16_f32 v69, v198, v199
	v_cvt_pk_bf16_f32 v70, v200, v201
	v_cvt_pk_bf16_f32 v71, v202, v203
	v_pk_add_f32 v[232:233], v[232:233], v[188:189]
	v_pk_add_f32 v[232:233], v[232:233], v[190:191]
	v_pk_add_f32 v[232:233], v[232:233], v[192:193]
	v_pk_add_f32 v[232:233], v[232:233], v[194:195]
	v_pk_add_f32 v[232:233], v[232:233], v[196:197]
	v_pk_add_f32 v[232:233], v[232:233], v[198:199]
	v_pk_add_f32 v[232:233], v[232:233], v[200:201]
	v_pk_add_f32 v[232:233], v[232:233], v[202:203]
	ds_read2_b32 v[188:189], v115 offset0:96 offset1:97
	ds_read2_b32 v[190:191], v115 offset0:98 offset1:99
	ds_read2_b32 v[192:193], v115 offset0:104 offset1:105
	ds_read2_b32 v[194:195], v115 offset0:106 offset1:107
	ds_read2_b32 v[196:197], v115 offset0:112 offset1:113
	ds_read2_b32 v[198:199], v115 offset0:114 offset1:115
	ds_read2_b32 v[200:201], v115 offset0:120 offset1:121
	ds_read2_b32 v[202:203], v115 offset0:122 offset1:123
	v_mfma_f32_32x32x16_bf16 v[0:15], v[64:67], v[72:75], v[0:15]
	v_mfma_f32_32x32x16_bf16 v[16:31], v[64:67], v[76:79], v[16:31]
	v_mfma_f32_32x32x16_bf16 v[0:15], v[68:71], v[220:223], v[0:15]
	v_mfma_f32_32x32x16_bf16 v[16:31], v[68:71], v[224:227], v[16:31]
	global_load_dwordx4 v[116:119], v243, s[88:89]
	global_load_dwordx4 v[120:123], v244, s[88:89]
	global_load_dwordx4 v[124:127], v245, s[88:89]
	global_load_dwordx4 v[128:131], v246, s[88:89]
	global_load_dwordx4 v[132:135], v148, s[88:89] offset:768
	global_load_dwordx4 v[136:139], v151, s[88:89] offset:768
	global_load_dwordx4 v[140:143], v148, s[88:89] offset:832
	global_load_dwordx4 v[144:147], v151, s[88:89] offset:832
	ds_read_b64_tr_b16 v[72:73], v231
	ds_read_b64_tr_b16 v[74:75], v231 offset:512
	ds_read_b64_tr_b16 v[76:77], v231 offset:2048
	ds_read_b64_tr_b16 v[78:79], v231 offset:2560
	ds_read_b64_tr_b16 v[220:221], v231 offset:1024
	ds_read_b64_tr_b16 v[222:223], v231 offset:1536
	ds_read_b64_tr_b16 v[224:225], v231 offset:3072
	ds_read_b64_tr_b16 v[226:227], v231 offset:3584
	s_waitcnt vmcnt(8)
	ds_write_b128 v247, v[156:159]
	ds_write_b128 v247, v[160:163] offset:1024
	ds_write_b128 v247, v[164:167] offset:2048
	ds_write_b128 v247, v[168:171] offset:3072
	ds_read_b128 v[156:159], v248
	ds_read_b128 v[160:163], v249
	ds_read_b128 v[164:167], v250
	ds_read_b128 v[168:171], v251
	ds_write_b128 v112, v[172:175]
	ds_write_b128 v112, v[176:179] offset:1024
	ds_write_b128 v112, v[180:183] offset:2048
	ds_write_b128 v112, v[184:187] offset:3072
	s_waitcnt lgkmcnt(4)
	v_mfma_f32_32x32x16_bf16 v[188:203], v[156:159], v[48:51], v[188:203]
	v_exp_f32_e32 v32, v32
	v_exp_f32_e32 v33, v33
	v_exp_f32_e32 v34, v34
	v_exp_f32_e32 v35, v35
	v_mfma_f32_32x32x16_bf16 v[188:203], v[160:163], v[52:55], v[188:203]
	v_exp_f32_e32 v36, v36
	v_exp_f32_e32 v37, v37
	v_exp_f32_e32 v38, v38
	v_exp_f32_e32 v39, v39
	v_mfma_f32_32x32x16_bf16 v[188:203], v[164:167], v[56:59], v[188:203]
	v_exp_f32_e32 v40, v40
	v_exp_f32_e32 v41, v41
	v_exp_f32_e32 v42, v42
	v_exp_f32_e32 v43, v43
	v_mfma_f32_32x32x16_bf16 v[188:203], v[168:171], v[60:63], v[188:203]
	v_exp_f32_e32 v44, v44
	v_exp_f32_e32 v45, v45
	v_exp_f32_e32 v46, v46
	v_exp_f32_e32 v47, v47
	v_cvt_pk_bf16_f32 v64, v32, v33
	v_cvt_pk_bf16_f32 v65, v34, v35
	v_cvt_pk_bf16_f32 v66, v36, v37
	v_cvt_pk_bf16_f32 v67, v38, v39
	v_cvt_pk_bf16_f32 v68, v40, v41
	v_cvt_pk_bf16_f32 v69, v42, v43
	v_cvt_pk_bf16_f32 v70, v44, v45
	v_cvt_pk_bf16_f32 v71, v46, v47
	v_pk_add_f32 v[232:233], v[232:233], v[32:33]
	v_pk_add_f32 v[232:233], v[232:233], v[34:35]
	v_pk_add_f32 v[232:233], v[232:233], v[36:37]
	v_pk_add_f32 v[232:233], v[232:233], v[38:39]
	v_pk_add_f32 v[232:233], v[232:233], v[40:41]
	v_pk_add_f32 v[232:233], v[232:233], v[42:43]
	v_pk_add_f32 v[232:233], v[232:233], v[44:45]
	v_pk_add_f32 v[232:233], v[232:233], v[46:47]
	ds_read2_b32 v[32:33], v115 offset0:128 offset1:129
	ds_read2_b32 v[34:35], v115 offset0:130 offset1:131
	ds_read2_b32 v[36:37], v115 offset0:136 offset1:137
	ds_read2_b32 v[38:39], v115 offset0:138 offset1:139
	ds_read2_b32 v[40:41], v115 offset0:144 offset1:145
	ds_read2_b32 v[42:43], v115 offset0:146 offset1:147
	ds_read2_b32 v[44:45], v115 offset0:152 offset1:153
	ds_read2_b32 v[46:47], v115 offset0:154 offset1:155
	v_mfma_f32_32x32x16_bf16 v[0:15], v[64:67], v[72:75], v[0:15]
	v_mfma_f32_32x32x16_bf16 v[16:31], v[64:67], v[76:79], v[16:31]
	v_mfma_f32_32x32x16_bf16 v[0:15], v[68:71], v[220:223], v[0:15]
	v_mfma_f32_32x32x16_bf16 v[16:31], v[68:71], v[224:227], v[16:31]
	ds_read_b64_tr_b16 v[72:73], v231
	ds_read_b64_tr_b16 v[74:75], v231 offset:512
	ds_read_b64_tr_b16 v[76:77], v231 offset:2048
	ds_read_b64_tr_b16 v[78:79], v231 offset:2560
	ds_read_b64_tr_b16 v[220:221], v231 offset:1024
	ds_read_b64_tr_b16 v[222:223], v231 offset:1536
	ds_read_b64_tr_b16 v[224:225], v231 offset:3072
	ds_read_b64_tr_b16 v[226:227], v231 offset:3584
	s_waitcnt vmcnt(0)
; __device__ __forceinline__ void dil_unit(LAS unsigned char* lds, bf16_t* proj, int seq, int hd, int T0, int rho) {
;     ...
;     if (bound) DIL_LOOP(true); else DIL_LOOP(false);
	ds_write_b128 v247, v[116:119]
	ds_write_b128 v247, v[120:123] offset:1024
	ds_write_b128 v247, v[124:127] offset:2048
	ds_write_b128 v247, v[128:131] offset:3072
	ds_read_b128 v[116:119], v248
	ds_read_b128 v[120:123], v249
	ds_read_b128 v[124:127], v250
	ds_read_b128 v[128:131], v251
	ds_write_b128 v112, v[132:135]
	ds_write_b128 v112, v[136:139] offset:1024
	ds_write_b128 v112, v[140:143] offset:2048
	ds_write_b128 v112, v[144:147] offset:3072
	s_waitcnt lgkmcnt(4)
	v_mfma_f32_32x32x16_bf16 v[32:47], v[116:119], v[48:51], v[32:47]
	v_exp_f32_e32 v188, v188
	v_exp_f32_e32 v189, v189
	v_exp_f32_e32 v190, v190
	v_exp_f32_e32 v191, v191
	v_mfma_f32_32x32x16_bf16 v[32:47], v[120:123], v[52:55], v[32:47]
	v_exp_f32_e32 v192, v192
	v_exp_f32_e32 v193, v193
	v_exp_f32_e32 v194, v194
	v_exp_f32_e32 v195, v195
	v_mfma_f32_32x32x16_bf16 v[32:47], v[124:127], v[56:59], v[32:47]
	v_exp_f32_e32 v196, v196
	v_exp_f32_e32 v197, v197
	v_exp_f32_e32 v198, v198
	v_exp_f32_e32 v199, v199
	v_mfma_f32_32x32x16_bf16 v[32:47], v[128:131], v[60:63], v[32:47]
	v_exp_f32_e32 v200, v200
	v_exp_f32_e32 v201, v201
	v_exp_f32_e32 v202, v202
	v_exp_f32_e32 v203, v203
	v_cvt_pk_bf16_f32 v64, v188, v189
	v_cvt_pk_bf16_f32 v65, v190, v191
	v_cvt_pk_bf16_f32 v66, v192, v193
	v_cvt_pk_bf16_f32 v67, v194, v195
	v_cvt_pk_bf16_f32 v68, v196, v197
	v_cvt_pk_bf16_f32 v69, v198, v199
	v_cvt_pk_bf16_f32 v70, v200, v201
	v_cvt_pk_bf16_f32 v71, v202, v203
	v_pk_add_f32 v[232:233], v[232:233], v[188:189]
	v_pk_add_f32 v[232:233], v[232:233], v[190:191]
	v_pk_add_f32 v[232:233], v[232:233], v[192:193]
	v_pk_add_f32 v[232:233], v[232:233], v[194:195]
	v_pk_add_f32 v[232:233], v[232:233], v[196:197]
	v_pk_add_f32 v[232:233], v[232:233], v[198:199]
	v_pk_add_f32 v[232:233], v[232:233], v[200:201]
	v_pk_add_f32 v[232:233], v[232:233], v[202:203]
	v_mfma_f32_32x32x16_bf16 v[0:15], v[64:67], v[72:75], v[0:15]
	v_mfma_f32_32x32x16_bf16 v[16:31], v[64:67], v[76:79], v[16:31]
	v_mfma_f32_32x32x16_bf16 v[0:15], v[68:71], v[220:223], v[0:15]
	v_mfma_f32_32x32x16_bf16 v[16:31], v[68:71], v[224:227], v[16:31]
	ds_read_b64_tr_b16 v[72:73], v231
	ds_read_b64_tr_b16 v[74:75], v231 offset:512
	ds_read_b64_tr_b16 v[76:77], v231 offset:2048
	ds_read_b64_tr_b16 v[78:79], v231 offset:2560
	ds_read_b64_tr_b16 v[220:221], v231 offset:1024
	ds_read_b64_tr_b16 v[222:223], v231 offset:1536
	ds_read_b64_tr_b16 v[224:225], v231 offset:3072
	ds_read_b64_tr_b16 v[226:227], v231 offset:3584
	s_waitcnt lgkmcnt(0)
	v_exp_f32_e32 v32, v32
	v_exp_f32_e32 v33, v33
	v_exp_f32_e32 v34, v34
	v_exp_f32_e32 v35, v35
	v_exp_f32_e32 v36, v36
	v_exp_f32_e32 v37, v37
	v_exp_f32_e32 v38, v38
	v_exp_f32_e32 v39, v39
	v_exp_f32_e32 v40, v40
	v_exp_f32_e32 v41, v41
	v_exp_f32_e32 v42, v42
	v_exp_f32_e32 v43, v43
	v_exp_f32_e32 v44, v44
	v_exp_f32_e32 v45, v45
	v_exp_f32_e32 v46, v46
	v_exp_f32_e32 v47, v47
	v_cvt_pk_bf16_f32 v64, v32, v33
	v_cvt_pk_bf16_f32 v65, v34, v35
	v_cvt_pk_bf16_f32 v66, v36, v37
	v_cvt_pk_bf16_f32 v67, v38, v39
	v_cvt_pk_bf16_f32 v68, v40, v41
	v_cvt_pk_bf16_f32 v69, v42, v43
	v_cvt_pk_bf16_f32 v70, v44, v45
	v_cvt_pk_bf16_f32 v71, v46, v47
	v_pk_add_f32 v[232:233], v[232:233], v[32:33]
	v_pk_add_f32 v[232:233], v[232:233], v[34:35]
	v_pk_add_f32 v[232:233], v[232:233], v[36:37]
	v_pk_add_f32 v[232:233], v[232:233], v[38:39]
	v_pk_add_f32 v[232:233], v[232:233], v[40:41]
	v_pk_add_f32 v[232:233], v[232:233], v[42:43]
	v_pk_add_f32 v[232:233], v[232:233], v[44:45]
	v_pk_add_f32 v[232:233], v[232:233], v[46:47]
	v_mfma_f32_32x32x16_bf16 v[0:15], v[64:67], v[72:75], v[0:15]
	v_mfma_f32_32x32x16_bf16 v[16:31], v[64:67], v[76:79], v[16:31]
	v_mfma_f32_32x32x16_bf16 v[0:15], v[68:71], v[220:223], v[0:15]
	v_mfma_f32_32x32x16_bf16 v[16:31], v[68:71], v[224:227], v[16:31]
	v_add_f32_e32 v113, v232, v233
	v_or_b32_e32 v114, 1, v107
	v_or_b32_e32 v97, 2, v107
	v_or_b32_e32 v96, 3, v107
	v_or_b32_e32 v95, 8, v107
	v_or_b32_e32 v94, 9, v107
	v_or_b32_e32 v93, 10, v107
	v_or_b32_e32 v92, 11, v107
	v_or_b32_e32 v91, 16, v107
	v_or_b32_e32 v90, 17, v107
	v_or_b32_e32 v89, 18, v107
	v_or_b32_e32 v88, 19, v107
	v_or_b32_e32 v87, 24, v107
	v_or_b32_e32 v86, 25, v107
	v_or_b32_e32 v85, 26, v107
	v_or_b32_e32 v84, 27, v107
	s_nop 11
	s_branch .LBB0_1265
; #define LAS __attribute__((address_space(3)))
; #define GAS __attribute__((address_space(1)))
; __device__ __forceinline__ void dil_unit(LAS unsigned char* lds, bf16_t* proj, int seq, int hd, int T0, int rho) {
;     ...
;     bf16_t* base = proj + (size_t)seq * SEQ * NIN;
;     LAS unsigned char* wbuf = lds + wid * 4096;
;     const LAS unsigned char* vp = wbuf + ((lane >> 4) & 1) * 32 + (lane & 3) * 8 + (4 * hi + ((lane & 15) >> 2)) * 64;
;     const int P0 = T0 + rho;
;     bf16x8 qr[4];
; #pragma unroll
;     for (int ks = 0; ks < 4; ++ks) qr[ks] = *(const GAS bf16x8*)(base + (size_t)(P0 + 16 * r32) * NIN + PC_LQ + hd * 64 + 16 * ks + 8 * hi);
;     f32x16 o0 = {}, o1 = {}; float l = 0.f;
;     const bool bound = (T0 < 1024) || (T0 >= 15360);
.LBB0_1270:
	s_movk_i32 s100, 0x1800
	s_add_i32 s101, s8, 0x15c00
	s_lshl_b32 s90, s54, 1
	s_add_u32 s82, s52, s90
	s_addc_u32 s83, s53, 0
	s_add_u32 s82, s82, 0x1200
	s_addc_u32 s83, s83, 0
	s_sub_i32 s90, s67, 64
	s_mul_i32 s90, s90, 0x1800
	s_add_u32 s84, s82, s90
	s_addc_u32 s85, s83, 0
	s_sub_i32 s90, s67, 256
	s_mul_i32 s90, s90, 0x1800
	s_add_u32 s86, s82, s90
	s_addc_u32 s87, s83, 0
	s_sub_i32 s90, s67, 1024
	s_mul_i32 s90, s90, 0x1800
	s_add_u32 s88, s82, s90
	s_addc_u32 s89, s83, 0
	v_lshlrev_b32_e32 v153, 1, v98
	v_mad_u32_u24 v80, v105, s100, v82
	v_mad_u32_u24 v100, v110, s100, v153
	v_add_u32_e32 v149, 0x18000, v100
	v_lshlrev_b32_e32 v83, 2, v105
	v_mad_u32_u24 v83, v83, s100, v82
	v_lshlrev_b32_e32 v101, 2, v110
	v_mad_u32_u24 v101, v101, s100, v153
	v_add_u32_e32 v150, 0x60000, v101
	v_lshlrev_b32_e32 v99, 4, v105
	v_mad_u32_u24 v99, v99, s100, v82
	v_lshlrev_b32_e32 v148, 4, v110
	v_mad_u32_u24 v148, v148, s100, v153
	v_add_u32_e32 v151, 0x180000, v148
	v_lshrrev_b32_e32 v249, 3, v103
	v_and_b32_e32 v250, 7, v103
	v_lshlrev_b32_e32 v250, 4, v250
	v_add_u32_e32 v235, 0, v249
	v_add_u32_e32 v236, 8, v249
	v_add_u32_e32 v237, 16, v249
	v_add_u32_e32 v238, 24, v249
	v_add_u32_e32 v239, 0, v249
	v_lshlrev_b32_e32 v239, 2, v239
	v_add_u32_e32 v240, 8, v249
	v_lshlrev_b32_e32 v240, 2, v240
	v_add_u32_e32 v241, 16, v249
	v_lshlrev_b32_e32 v241, 2, v241
	v_add_u32_e32 v242, 24, v249
	v_lshlrev_b32_e32 v242, 2, v242
	v_add_u32_e32 v243, 0, v249
	v_lshlrev_b32_e32 v243, 4, v243
	v_add_u32_e32 v244, 8, v249
	v_lshlrev_b32_e32 v244, 4, v244
	v_add_u32_e32 v245, 16, v249
	v_lshlrev_b32_e32 v245, 4, v245
	v_add_u32_e32 v246, 24, v249
	v_lshlrev_b32_e32 v246, 4, v246
	v_mov_b32_e32 v252, v250
	v_mov_b32_e32 v100, v110
	v_add_u32_e32 v149, 16, v100
	v_lshlrev_b32_e32 v101, 2, v110
	v_add_u32_e32 v150, 64, v101
	v_lshlrev_b32_e32 v148, 4, v110
	v_add_u32_e32 v151, 256, v148
	s_mov_b32 s98, 0x4000
	s_mov_b32 s99, 0x3fff
	v_and_b32_e32 v247, 7, v249
	v_lshlrev_b32_e32 v247, 4, v247
	v_xor_b32_e32 v247, v247, v112
	v_and_b32_e32 v153, 7, v105
	v_or_b32_e32 v248, 0, v106
	v_xor_b32_e32 v248, v248, v153
	v_lshlrev_b32_e32 v248, 4, v248
	v_lshl_add_u32 v248, v105, 7, v248
	v_add_u32_e32 v248, s69, v248
	v_or_b32_e32 v249, 2, v106
	v_xor_b32_e32 v249, v249, v153
	v_lshlrev_b32_e32 v249, 4, v249
	v_lshl_add_u32 v249, v105, 7, v249
	v_add_u32_e32 v249, s69, v249
	v_or_b32_e32 v250, 4, v106
	v_xor_b32_e32 v250, v250, v153
	v_lshlrev_b32_e32 v250, 4, v250
	v_lshl_add_u32 v250, v105, 7, v250
	v_add_u32_e32 v250, s69, v250
	v_or_b32_e32 v251, 6, v106
	v_xor_b32_e32 v251, v251, v153
	v_lshlrev_b32_e32 v251, 4, v251
	v_lshl_add_u32 v251, v105, 7, v251
	v_add_u32_e32 v251, s69, v251
	v_lshlrev_b32_e32 v153, 1, v98
	v_mul_u32_u24_e32 v228, 17, v105
	v_sub_u32_e32 v228, v107, v228
	s_mul_i32 s90, s54, 153
	s_lshr_b32 s90, s90, 1
	s_add_i32 s90, s90, 34876
	v_lshl_add_u32 v228, v228, 2, s90
	v_lshlrev_b32_e32 v229, 2, v105
	v_sub_u32_e32 v229, v107, v229
	s_add_i32 s90, s101, 5104
	v_lshl_add_u32 v229, v229, 2, s90
	v_sub_u32_e32 v230, v107, v105
	s_add_i32 s90, s101, 6364
	v_lshl_add_u32 v230, v230, 2, s90
	v_add_u32_e32 v231, v109, v108
	v_mov_b64_e32 v[232:233], 0
	v_mov_b64_e32 v[0:1], 0
	v_mov_b64_e32 v[2:3], 0
	v_mov_b64_e32 v[4:5], 0
	v_mov_b64_e32 v[6:7], 0
	v_mov_b64_e32 v[8:9], 0
	v_mov_b64_e32 v[10:11], 0
	v_mov_b64_e32 v[12:13], 0
	v_mov_b64_e32 v[14:15], 0
	v_mov_b64_e32 v[16:17], 0
	v_mov_b64_e32 v[18:19], 0
	v_mov_b64_e32 v[20:21], 0
	v_mov_b64_e32 v[22:23], 0
	v_mov_b64_e32 v[24:25], 0
	v_mov_b64_e32 v[26:27], 0
	v_mov_b64_e32 v[28:29], 0
	v_mov_b64_e32 v[30:31], 0
	s_add_i32 s90, s67, -64
	v_add_u32_e32 v80, s90, v235
	v_add_u32_e32 v83, s90, v236
	v_add_u32_e32 v99, s90, v237
	v_add_u32_e32 v253, s90, v238
	v_add_u32_e32 v254, s90, v100
	v_add_u32_e32 v255, s90, v149
	v_med3_i32 v80, v80, 0, s99
	v_med3_i32 v83, v83, 0, s99
	v_med3_i32 v99, v99, 0, s99
	v_med3_i32 v253, v253, 0, s99
	v_med3_i32 v254, v254, 0, s99
	v_med3_i32 v255, v255, 0, s99
	v_mad_u32_u24 v80, v80, s100, v252
	v_mad_u32_u24 v83, v83, s100, v252
	v_mad_u32_u24 v99, v99, s100, v252
	v_mad_u32_u24 v253, v253, s100, v252
	v_mad_u32_u24 v254, v254, s100, v153
	v_mad_u32_u24 v255, v255, s100, v153
	global_load_dwordx4 v[116:119], v80, s[82:83]
	global_load_dwordx4 v[120:123], v83, s[82:83]
	global_load_dwordx4 v[124:127], v99, s[82:83]
	global_load_dwordx4 v[128:131], v253, s[82:83]
	global_load_dwordx4 v[132:135], v254, s[82:83] offset:768
	global_load_dwordx4 v[136:139], v255, s[82:83] offset:768
	global_load_dwordx4 v[140:143], v254, s[82:83] offset:832
	global_load_dwordx4 v[144:147], v255, s[82:83] offset:832
	s_add_i32 s90, s67, -32
	v_add_u32_e32 v80, s90, v235
	v_add_u32_e32 v83, s90, v236
	v_add_u32_e32 v99, s90, v237
	v_add_u32_e32 v253, s90, v238
	v_add_u32_e32 v254, s90, v100
	v_add_u32_e32 v255, s90, v149
	v_med3_i32 v80, v80, 0, s99
	v_med3_i32 v83, v83, 0, s99
	v_med3_i32 v99, v99, 0, s99
	v_med3_i32 v253, v253, 0, s99
	v_med3_i32 v254, v254, 0, s99
	v_med3_i32 v255, v255, 0, s99
	v_mad_u32_u24 v80, v80, s100, v252
	v_mad_u32_u24 v83, v83, s100, v252
	v_mad_u32_u24 v99, v99, s100, v252
	v_mad_u32_u24 v253, v253, s100, v252
	v_mad_u32_u24 v254, v254, s100, v153
	v_mad_u32_u24 v255, v255, s100, v153
	global_load_dwordx4 v[156:159], v80, s[82:83]
	global_load_dwordx4 v[160:163], v83, s[82:83]
	global_load_dwordx4 v[164:167], v99, s[82:83]
	global_load_dwordx4 v[168:171], v253, s[82:83]
	global_load_dwordx4 v[172:175], v254, s[82:83] offset:768
	global_load_dwordx4 v[176:179], v255, s[82:83] offset:768
	global_load_dwordx4 v[180:183], v254, s[82:83] offset:832
	global_load_dwordx4 v[184:187], v255, s[82:83] offset:832
	v_mov_b32_e32 v115, v228
	ds_read2_b32 v[32:33], v115 offset0:0 offset1:1
	ds_read2_b32 v[34:35], v115 offset0:2 offset1:3
	ds_read2_b32 v[36:37], v115 offset0:8 offset1:9
	ds_read2_b32 v[38:39], v115 offset0:10 offset1:11
	ds_read2_b32 v[40:41], v115 offset0:17 offset1:18
	ds_read2_b32 v[42:43], v115 offset0:19 offset1:20
	ds_read2_b32 v[44:45], v115 offset0:25 offset1:26
	ds_read2_b32 v[46:47], v115 offset0:27 offset1:28
	s_waitcnt vmcnt(8)
	ds_write_b128 v247, v[116:119]
	ds_write_b128 v247, v[120:123] offset:1024
	ds_write_b128 v247, v[124:127] offset:2048
	ds_write_b128 v247, v[128:131] offset:3072
	ds_read_b128 v[116:119], v248
	ds_read_b128 v[120:123], v249
	ds_read_b128 v[124:127], v250
	ds_read_b128 v[128:131], v251
	ds_write_b128 v112, v[132:135]
	ds_write_b128 v112, v[136:139] offset:1024
	ds_write_b128 v112, v[140:143] offset:2048
	ds_write_b128 v112, v[144:147] offset:3072
	s_waitcnt lgkmcnt(4)
	v_mfma_f32_32x32x16_bf16 v[32:47], v[116:119], v[48:51], v[32:47]
	v_mfma_f32_32x32x16_bf16 v[32:47], v[120:123], v[52:55], v[32:47]
	v_mfma_f32_32x32x16_bf16 v[32:47], v[124:127], v[56:59], v[32:47]
	v_mfma_f32_32x32x16_bf16 v[32:47], v[128:131], v[60:63], v[32:47]
	ds_read2_b32 v[188:189], v115 offset0:34 offset1:35
	ds_read2_b32 v[190:191], v115 offset0:36 offset1:37
	ds_read2_b32 v[192:193], v115 offset0:42 offset1:43
	ds_read2_b32 v[194:195], v115 offset0:44 offset1:45
	ds_read2_b32 v[196:197], v115 offset0:51 offset1:52
	ds_read2_b32 v[198:199], v115 offset0:53 offset1:54
	ds_read2_b32 v[200:201], v115 offset0:59 offset1:60
	ds_read2_b32 v[202:203], v115 offset0:61 offset1:62
	s_add_i32 s90, s67, 0
	v_add_u32_e32 v80, s90, v235
	v_add_u32_e32 v83, s90, v236
	v_add_u32_e32 v99, s90, v237
	v_add_u32_e32 v253, s90, v238
	v_add_u32_e32 v254, s90, v100
	v_add_u32_e32 v255, s90, v149
	v_med3_i32 v80, v80, 0, s99
	v_med3_i32 v83, v83, 0, s99
	v_med3_i32 v99, v99, 0, s99
	v_med3_i32 v253, v253, 0, s99
	v_med3_i32 v254, v254, 0, s99
	v_med3_i32 v255, v255, 0, s99
	v_mad_u32_u24 v80, v80, s100, v252
	v_mad_u32_u24 v83, v83, s100, v252
	v_mad_u32_u24 v99, v99, s100, v252
	v_mad_u32_u24 v253, v253, s100, v252
	v_mad_u32_u24 v254, v254, s100, v153
	v_mad_u32_u24 v255, v255, s100, v153
	global_load_dwordx4 v[116:119], v80, s[82:83]
	global_load_dwordx4 v[120:123], v83, s[82:83]
	global_load_dwordx4 v[124:127], v99, s[82:83]
	global_load_dwordx4 v[128:131], v253, s[82:83]
	global_load_dwordx4 v[132:135], v254, s[82:83] offset:768
	global_load_dwordx4 v[136:139], v255, s[82:83] offset:768
	global_load_dwordx4 v[140:143], v254, s[82:83] offset:832
	global_load_dwordx4 v[144:147], v255, s[82:83] offset:832
	ds_read_b64_tr_b16 v[72:73], v231
	ds_read_b64_tr_b16 v[74:75], v231 offset:512
	ds_read_b64_tr_b16 v[76:77], v231 offset:2048
	ds_read_b64_tr_b16 v[78:79], v231 offset:2560
	ds_read_b64_tr_b16 v[220:221], v231 offset:1024
	ds_read_b64_tr_b16 v[222:223], v231 offset:1536
	ds_read_b64_tr_b16 v[224:225], v231 offset:3072
	ds_read_b64_tr_b16 v[226:227], v231 offset:3584
	s_waitcnt vmcnt(8)
	ds_write_b128 v247, v[156:159]
	ds_write_b128 v247, v[160:163] offset:1024
	ds_write_b128 v247, v[164:167] offset:2048
	ds_write_b128 v247, v[168:171] offset:3072
	ds_read_b128 v[156:159], v248
	ds_read_b128 v[160:163], v249
	ds_read_b128 v[164:167], v250
	ds_read_b128 v[168:171], v251
	ds_write_b128 v112, v[172:175]
	ds_write_b128 v112, v[176:179] offset:1024
	ds_write_b128 v112, v[180:183] offset:2048
	ds_write_b128 v112, v[184:187] offset:3072
	s_waitcnt lgkmcnt(4)
	v_mfma_f32_32x32x16_bf16 v[188:203], v[156:159], v[48:51], v[188:203]
	v_exp_f32_e32 v32, v32
	v_exp_f32_e32 v33, v33
	v_exp_f32_e32 v34, v34
	v_exp_f32_e32 v35, v35
	v_mfma_f32_32x32x16_bf16 v[188:203], v[160:163], v[52:55], v[188:203]
	v_exp_f32_e32 v36, v36
	v_exp_f32_e32 v37, v37
	v_exp_f32_e32 v38, v38
	v_exp_f32_e32 v39, v39
	v_mfma_f32_32x32x16_bf16 v[188:203], v[164:167], v[56:59], v[188:203]
	v_exp_f32_e32 v40, v40
	v_exp_f32_e32 v41, v41
	v_exp_f32_e32 v42, v42
	v_exp_f32_e32 v43, v43
	v_mfma_f32_32x32x16_bf16 v[188:203], v[168:171], v[60:63], v[188:203]
	v_exp_f32_e32 v44, v44
	v_exp_f32_e32 v45, v45
	v_exp_f32_e32 v46, v46
	v_exp_f32_e32 v47, v47
	s_add_i32 s90, s67, -64
	v_add_u32_e32 v84, s90, v107
	v_add_u32_e32 v85, 0, v84
	v_add_u32_e32 v86, 1, v84
	v_add_u32_e32 v87, 2, v84
	v_add_u32_e32 v88, 3, v84
	v_cmp_gt_u32_e64 s[30:31], s98, v85
	v_cmp_gt_u32_e64 s[36:37], s98, v86
	v_cmp_gt_u32_e64 s[78:79], s98, v87
	v_cmp_gt_u32_e64 s[50:51], s98, v88
	v_cndmask_b32_e64 v32, 0, v32, s[30:31]
	v_add_u32_e32 v85, 8, v84
	v_cmp_gt_u32_e64 s[30:31], s98, v85
	v_cndmask_b32_e64 v33, 0, v33, s[36:37]
	v_add_u32_e32 v86, 9, v84
	v_cmp_gt_u32_e64 s[36:37], s98, v86
	v_cndmask_b32_e64 v34, 0, v34, s[78:79]
	v_add_u32_e32 v87, 10, v84
	v_cmp_gt_u32_e64 s[78:79], s98, v87
	v_cndmask_b32_e64 v35, 0, v35, s[50:51]
	v_add_u32_e32 v88, 11, v84
	v_cmp_gt_u32_e64 s[50:51], s98, v88
	v_cndmask_b32_e64 v36, 0, v36, s[30:31]
	v_add_u32_e32 v85, 16, v84
	v_cmp_gt_u32_e64 s[30:31], s98, v85
	v_cndmask_b32_e64 v37, 0, v37, s[36:37]
	v_add_u32_e32 v86, 17, v84
	v_cmp_gt_u32_e64 s[36:37], s98, v86
	v_cndmask_b32_e64 v38, 0, v38, s[78:79]
	v_add_u32_e32 v87, 18, v84
	v_cmp_gt_u32_e64 s[78:79], s98, v87
	v_cndmask_b32_e64 v39, 0, v39, s[50:51]
	v_add_u32_e32 v88, 19, v84
	v_cmp_gt_u32_e64 s[50:51], s98, v88
	v_cndmask_b32_e64 v40, 0, v40, s[30:31]
	v_add_u32_e32 v85, 24, v84
	v_cmp_gt_u32_e64 s[30:31], s98, v85
	v_cndmask_b32_e64 v41, 0, v41, s[36:37]
	v_add_u32_e32 v86, 25, v84
	v_cmp_gt_u32_e64 s[36:37], s98, v86
	v_cndmask_b32_e64 v42, 0, v42, s[78:79]
	v_add_u32_e32 v87, 26, v84
	v_cmp_gt_u32_e64 s[78:79], s98, v87
	v_cndmask_b32_e64 v43, 0, v43, s[50:51]
	v_add_u32_e32 v88, 27, v84
	v_cmp_gt_u32_e64 s[50:51], s98, v88
	v_nop
	v_cndmask_b32_e64 v44, 0, v44, s[30:31]
	v_cndmask_b32_e64 v45, 0, v45, s[36:37]
	v_cndmask_b32_e64 v46, 0, v46, s[78:79]
	v_cndmask_b32_e64 v47, 0, v47, s[50:51]
	v_cvt_pk_bf16_f32 v64, v32, v33
	v_cvt_pk_bf16_f32 v65, v34, v35
	v_cvt_pk_bf16_f32 v66, v36, v37
	v_cvt_pk_bf16_f32 v67, v38, v39
	v_cvt_pk_bf16_f32 v68, v40, v41
	v_cvt_pk_bf16_f32 v69, v42, v43
	v_cvt_pk_bf16_f32 v70, v44, v45
	v_cvt_pk_bf16_f32 v71, v46, v47
	v_pk_add_f32 v[232:233], v[232:233], v[32:33]
	v_pk_add_f32 v[232:233], v[232:233], v[34:35]
	v_pk_add_f32 v[232:233], v[232:233], v[36:37]
	v_pk_add_f32 v[232:233], v[232:233], v[38:39]
	v_pk_add_f32 v[232:233], v[232:233], v[40:41]
	v_pk_add_f32 v[232:233], v[232:233], v[42:43]
	v_pk_add_f32 v[232:233], v[232:233], v[44:45]
	v_pk_add_f32 v[232:233], v[232:233], v[46:47]
	ds_read2_b32 v[32:33], v115 offset0:68 offset1:69
	ds_read2_b32 v[34:35], v115 offset0:70 offset1:71
	ds_read2_b32 v[36:37], v115 offset0:76 offset1:77
	ds_read2_b32 v[38:39], v115 offset0:78 offset1:79
	ds_read2_b32 v[40:41], v115 offset0:85 offset1:86
	ds_read2_b32 v[42:43], v115 offset0:87 offset1:88
	ds_read2_b32 v[44:45], v115 offset0:93 offset1:94
	ds_read2_b32 v[46:47], v115 offset0:95 offset1:96
	v_mfma_f32_32x32x16_bf16 v[0:15], v[64:67], v[72:75], v[0:15]
	v_mfma_f32_32x32x16_bf16 v[16:31], v[64:67], v[76:79], v[16:31]
	v_mfma_f32_32x32x16_bf16 v[0:15], v[68:71], v[220:223], v[0:15]
	v_mfma_f32_32x32x16_bf16 v[16:31], v[68:71], v[224:227], v[16:31]
	s_add_i32 s90, s67, 32
	v_add_u32_e32 v80, s90, v235
	v_add_u32_e32 v83, s90, v236
	v_add_u32_e32 v99, s90, v237
	v_add_u32_e32 v253, s90, v238
	v_add_u32_e32 v254, s90, v100
	v_add_u32_e32 v255, s90, v149
	v_med3_i32 v80, v80, 0, s99
	v_med3_i32 v83, v83, 0, s99
	v_med3_i32 v99, v99, 0, s99
	v_med3_i32 v253, v253, 0, s99
	v_med3_i32 v254, v254, 0, s99
	v_med3_i32 v255, v255, 0, s99
	v_mad_u32_u24 v80, v80, s100, v252
	v_mad_u32_u24 v83, v83, s100, v252
	v_mad_u32_u24 v99, v99, s100, v252
	v_mad_u32_u24 v253, v253, s100, v252
	v_mad_u32_u24 v254, v254, s100, v153
	v_mad_u32_u24 v255, v255, s100, v153
	global_load_dwordx4 v[156:159], v80, s[82:83]
	global_load_dwordx4 v[160:163], v83, s[82:83]
	global_load_dwordx4 v[164:167], v99, s[82:83]
	global_load_dwordx4 v[168:171], v253, s[82:83]
	global_load_dwordx4 v[172:175], v254, s[82:83] offset:768
	global_load_dwordx4 v[176:179], v255, s[82:83] offset:768
	global_load_dwordx4 v[180:183], v254, s[82:83] offset:832
	global_load_dwordx4 v[184:187], v255, s[82:83] offset:832
	ds_read_b64_tr_b16 v[72:73], v231
	ds_read_b64_tr_b16 v[74:75], v231 offset:512
	ds_read_b64_tr_b16 v[76:77], v231 offset:2048
	ds_read_b64_tr_b16 v[78:79], v231 offset:2560
	ds_read_b64_tr_b16 v[220:221], v231 offset:1024
	ds_read_b64_tr_b16 v[222:223], v231 offset:1536
	ds_read_b64_tr_b16 v[224:225], v231 offset:3072
	ds_read_b64_tr_b16 v[226:227], v231 offset:3584
	s_waitcnt vmcnt(8)
	ds_write_b128 v247, v[116:119]
	ds_write_b128 v247, v[120:123] offset:1024
	ds_write_b128 v247, v[124:127] offset:2048
	ds_write_b128 v247, v[128:131] offset:3072
	ds_read_b128 v[116:119], v248
	ds_read_b128 v[120:123], v249
	ds_read_b128 v[124:127], v250
	ds_read_b128 v[128:131], v251
	ds_write_b128 v112, v[132:135]
	ds_write_b128 v112, v[136:139] offset:1024
	ds_write_b128 v112, v[140:143] offset:2048
	ds_write_b128 v112, v[144:147] offset:3072
	s_waitcnt lgkmcnt(4)
	v_mfma_f32_32x32x16_bf16 v[32:47], v[116:119], v[48:51], v[32:47]
	v_exp_f32_e32 v188, v188
	v_exp_f32_e32 v189, v189
	v_exp_f32_e32 v190, v190
	v_exp_f32_e32 v191, v191
	v_mfma_f32_32x32x16_bf16 v[32:47], v[120:123], v[52:55], v[32:47]
	v_exp_f32_e32 v192, v192
	v_exp_f32_e32 v193, v193
	v_exp_f32_e32 v194, v194
	v_exp_f32_e32 v195, v195
	v_mfma_f32_32x32x16_bf16 v[32:47], v[124:127], v[56:59], v[32:47]
	v_exp_f32_e32 v196, v196
	v_exp_f32_e32 v197, v197
	v_exp_f32_e32 v198, v198
	v_exp_f32_e32 v199, v199
	v_mfma_f32_32x32x16_bf16 v[32:47], v[128:131], v[60:63], v[32:47]
	v_exp_f32_e32 v200, v200
	v_exp_f32_e32 v201, v201
	v_exp_f32_e32 v202, v202
	v_exp_f32_e32 v203, v203
	s_add_i32 s90, s67, -32
	v_add_u32_e32 v84, s90, v107
	v_add_u32_e32 v85, 0, v84
	v_add_u32_e32 v86, 1, v84
	v_add_u32_e32 v87, 2, v84
	v_add_u32_e32 v88, 3, v84
	v_cmp_gt_u32_e64 s[30:31], s98, v85
	v_cmp_gt_u32_e64 s[36:37], s98, v86
	v_cmp_gt_u32_e64 s[78:79], s98, v87
	v_cmp_gt_u32_e64 s[50:51], s98, v88
	v_cndmask_b32_e64 v188, 0, v188, s[30:31]
	v_add_u32_e32 v85, 8, v84
	v_cmp_gt_u32_e64 s[30:31], s98, v85
	v_cndmask_b32_e64 v189, 0, v189, s[36:37]
	v_add_u32_e32 v86, 9, v84
	v_cmp_gt_u32_e64 s[36:37], s98, v86
	v_cndmask_b32_e64 v190, 0, v190, s[78:79]
	v_add_u32_e32 v87, 10, v84
	v_cmp_gt_u32_e64 s[78:79], s98, v87
	v_cndmask_b32_e64 v191, 0, v191, s[50:51]
	v_add_u32_e32 v88, 11, v84
	v_cmp_gt_u32_e64 s[50:51], s98, v88
	v_cndmask_b32_e64 v192, 0, v192, s[30:31]
	v_add_u32_e32 v85, 16, v84
	v_cmp_gt_u32_e64 s[30:31], s98, v85
	v_cndmask_b32_e64 v193, 0, v193, s[36:37]
	v_add_u32_e32 v86, 17, v84
	v_cmp_gt_u32_e64 s[36:37], s98, v86
	v_cndmask_b32_e64 v194, 0, v194, s[78:79]
	v_add_u32_e32 v87, 18, v84
	v_cmp_gt_u32_e64 s[78:79], s98, v87
	v_cndmask_b32_e64 v195, 0, v195, s[50:51]
	v_add_u32_e32 v88, 19, v84
	v_cmp_gt_u32_e64 s[50:51], s98, v88
	v_cndmask_b32_e64 v196, 0, v196, s[30:31]
	v_add_u32_e32 v85, 24, v84
	v_cmp_gt_u32_e64 s[30:31], s98, v85
	v_cndmask_b32_e64 v197, 0, v197, s[36:37]
	v_add_u32_e32 v86, 25, v84
	v_cmp_gt_u32_e64 s[36:37], s98, v86
	v_cndmask_b32_e64 v198, 0, v198, s[78:79]
	v_add_u32_e32 v87, 26, v84
	v_cmp_gt_u32_e64 s[78:79], s98, v87
	v_cndmask_b32_e64 v199, 0, v199, s[50:51]
	v_add_u32_e32 v88, 27, v84
	v_cmp_gt_u32_e64 s[50:51], s98, v88
	v_nop
	v_cndmask_b32_e64 v200, 0, v200, s[30:31]
	v_cndmask_b32_e64 v201, 0, v201, s[36:37]
	v_cndmask_b32_e64 v202, 0, v202, s[78:79]
	v_cndmask_b32_e64 v203, 0, v203, s[50:51]
	v_cvt_pk_bf16_f32 v64, v188, v189
	v_cvt_pk_bf16_f32 v65, v190, v191
	v_cvt_pk_bf16_f32 v66, v192, v193
	v_cvt_pk_bf16_f32 v67, v194, v195
	v_cvt_pk_bf16_f32 v68, v196, v197
	v_cvt_pk_bf16_f32 v69, v198, v199
	v_cvt_pk_bf16_f32 v70, v200, v201
	v_cvt_pk_bf16_f32 v71, v202, v203
	v_pk_add_f32 v[232:233], v[232:233], v[188:189]
	v_pk_add_f32 v[232:233], v[232:233], v[190:191]
	v_pk_add_f32 v[232:233], v[232:233], v[192:193]
	v_pk_add_f32 v[232:233], v[232:233], v[194:195]
	v_pk_add_f32 v[232:233], v[232:233], v[196:197]
	v_pk_add_f32 v[232:233], v[232:233], v[198:199]
	v_pk_add_f32 v[232:233], v[232:233], v[200:201]
	v_pk_add_f32 v[232:233], v[232:233], v[202:203]
	ds_read2_b32 v[188:189], v115 offset0:102 offset1:103
	ds_read2_b32 v[190:191], v115 offset0:104 offset1:105
	ds_read2_b32 v[192:193], v115 offset0:110 offset1:111
	ds_read2_b32 v[194:195], v115 offset0:112 offset1:113
	ds_read2_b32 v[196:197], v115 offset0:119 offset1:120
	ds_read2_b32 v[198:199], v115 offset0:121 offset1:122
	ds_read2_b32 v[200:201], v115 offset0:127 offset1:128
	ds_read2_b32 v[202:203], v115 offset0:129 offset1:130
	v_mfma_f32_32x32x16_bf16 v[0:15], v[64:67], v[72:75], v[0:15]
	v_mfma_f32_32x32x16_bf16 v[16:31], v[64:67], v[76:79], v[16:31]
	v_mfma_f32_32x32x16_bf16 v[0:15], v[68:71], v[220:223], v[0:15]
	v_mfma_f32_32x32x16_bf16 v[16:31], v[68:71], v[224:227], v[16:31]
	s_add_i32 s90, s67, 64
	v_add_u32_e32 v80, s90, v235
	v_add_u32_e32 v83, s90, v236
	v_add_u32_e32 v99, s90, v237
	v_add_u32_e32 v253, s90, v238
	v_add_u32_e32 v254, s90, v100
	v_add_u32_e32 v255, s90, v149
	v_med3_i32 v80, v80, 0, s99
	v_med3_i32 v83, v83, 0, s99
	v_med3_i32 v99, v99, 0, s99
	v_med3_i32 v253, v253, 0, s99
	v_med3_i32 v254, v254, 0, s99
	v_med3_i32 v255, v255, 0, s99
	v_mad_u32_u24 v80, v80, s100, v252
	v_mad_u32_u24 v83, v83, s100, v252
	v_mad_u32_u24 v99, v99, s100, v252
	v_mad_u32_u24 v253, v253, s100, v252
	v_mad_u32_u24 v254, v254, s100, v153
	v_mad_u32_u24 v255, v255, s100, v153
	global_load_dwordx4 v[116:119], v80, s[82:83]
	global_load_dwordx4 v[120:123], v83, s[82:83]
	global_load_dwordx4 v[124:127], v99, s[82:83]
	global_load_dwordx4 v[128:131], v253, s[82:83]
	global_load_dwordx4 v[132:135], v254, s[82:83] offset:768
	global_load_dwordx4 v[136:139], v255, s[82:83] offset:768
	global_load_dwordx4 v[140:143], v254, s[82:83] offset:832
	global_load_dwordx4 v[144:147], v255, s[82:83] offset:832
	ds_read_b64_tr_b16 v[72:73], v231
	ds_read_b64_tr_b16 v[74:75], v231 offset:512
	ds_read_b64_tr_b16 v[76:77], v231 offset:2048
	ds_read_b64_tr_b16 v[78:79], v231 offset:2560
	ds_read_b64_tr_b16 v[220:221], v231 offset:1024
	ds_read_b64_tr_b16 v[222:223], v231 offset:1536
	ds_read_b64_tr_b16 v[224:225], v231 offset:3072
	ds_read_b64_tr_b16 v[226:227], v231 offset:3584
	s_waitcnt vmcnt(8)
	ds_write_b128 v247, v[156:159]
	ds_write_b128 v247, v[160:163] offset:1024
	ds_write_b128 v247, v[164:167] offset:2048
	ds_write_b128 v247, v[168:171] offset:3072
	ds_read_b128 v[156:159], v248
	ds_read_b128 v[160:163], v249
	ds_read_b128 v[164:167], v250
	ds_read_b128 v[168:171], v251
	ds_write_b128 v112, v[172:175]
	ds_write_b128 v112, v[176:179] offset:1024
	ds_write_b128 v112, v[180:183] offset:2048
	ds_write_b128 v112, v[184:187] offset:3072
	s_waitcnt lgkmcnt(4)
	v_mfma_f32_32x32x16_bf16 v[188:203], v[156:159], v[48:51], v[188:203]
	v_exp_f32_e32 v32, v32
	v_exp_f32_e32 v33, v33
	v_exp_f32_e32 v34, v34
	v_exp_f32_e32 v35, v35
	v_mfma_f32_32x32x16_bf16 v[188:203], v[160:163], v[52:55], v[188:203]
	v_exp_f32_e32 v36, v36
	v_exp_f32_e32 v37, v37
	v_exp_f32_e32 v38, v38
	v_exp_f32_e32 v39, v39
	v_mfma_f32_32x32x16_bf16 v[188:203], v[164:167], v[56:59], v[188:203]
	v_exp_f32_e32 v40, v40
	v_exp_f32_e32 v41, v41
	v_exp_f32_e32 v42, v42
	v_exp_f32_e32 v43, v43
	v_mfma_f32_32x32x16_bf16 v[188:203], v[168:171], v[60:63], v[188:203]
	v_exp_f32_e32 v44, v44
	v_exp_f32_e32 v45, v45
	v_exp_f32_e32 v46, v46
	v_exp_f32_e32 v47, v47
	s_add_i32 s90, s67, 0
	v_add_u32_e32 v84, s90, v107
	v_add_u32_e32 v85, 0, v84
	v_add_u32_e32 v86, 1, v84
	v_add_u32_e32 v87, 2, v84
	v_add_u32_e32 v88, 3, v84
	v_cmp_gt_u32_e64 s[30:31], s98, v85
	v_cmp_gt_u32_e64 s[36:37], s98, v86
	v_cmp_gt_u32_e64 s[78:79], s98, v87
	v_cmp_gt_u32_e64 s[50:51], s98, v88
	v_cndmask_b32_e64 v32, 0, v32, s[30:31]
	v_add_u32_e32 v85, 8, v84
	v_cmp_gt_u32_e64 s[30:31], s98, v85
	v_cndmask_b32_e64 v33, 0, v33, s[36:37]
	v_add_u32_e32 v86, 9, v84
	v_cmp_gt_u32_e64 s[36:37], s98, v86
	v_cndmask_b32_e64 v34, 0, v34, s[78:79]
	v_add_u32_e32 v87, 10, v84
	v_cmp_gt_u32_e64 s[78:79], s98, v87
	v_cndmask_b32_e64 v35, 0, v35, s[50:51]
	v_add_u32_e32 v88, 11, v84
	v_cmp_gt_u32_e64 s[50:51], s98, v88
	v_cndmask_b32_e64 v36, 0, v36, s[30:31]
	v_add_u32_e32 v85, 16, v84
	v_cmp_gt_u32_e64 s[30:31], s98, v85
	v_cndmask_b32_e64 v37, 0, v37, s[36:37]
	v_add_u32_e32 v86, 17, v84
	v_cmp_gt_u32_e64 s[36:37], s98, v86
	v_cndmask_b32_e64 v38, 0, v38, s[78:79]
	v_add_u32_e32 v87, 18, v84
	v_cmp_gt_u32_e64 s[78:79], s98, v87
	v_cndmask_b32_e64 v39, 0, v39, s[50:51]
	v_add_u32_e32 v88, 19, v84
	v_cmp_gt_u32_e64 s[50:51], s98, v88
	v_cndmask_b32_e64 v40, 0, v40, s[30:31]
	v_add_u32_e32 v85, 24, v84
	v_cmp_gt_u32_e64 s[30:31], s98, v85
	v_cndmask_b32_e64 v41, 0, v41, s[36:37]
	v_add_u32_e32 v86, 25, v84
	v_cmp_gt_u32_e64 s[36:37], s98, v86
	v_cndmask_b32_e64 v42, 0, v42, s[78:79]
	v_add_u32_e32 v87, 26, v84
	v_cmp_gt_u32_e64 s[78:79], s98, v87
	v_cndmask_b32_e64 v43, 0, v43, s[50:51]
	v_add_u32_e32 v88, 27, v84
	v_cmp_gt_u32_e64 s[50:51], s98, v88
	v_nop
	v_cndmask_b32_e64 v44, 0, v44, s[30:31]
	v_cndmask_b32_e64 v45, 0, v45, s[36:37]
	v_cndmask_b32_e64 v46, 0, v46, s[78:79]
	v_cndmask_b32_e64 v47, 0, v47, s[50:51]
	v_cvt_pk_bf16_f32 v64, v32, v33
	v_cvt_pk_bf16_f32 v65, v34, v35
	v_cvt_pk_bf16_f32 v66, v36, v37
	v_cvt_pk_bf16_f32 v67, v38, v39
	v_cvt_pk_bf16_f32 v68, v40, v41
	v_cvt_pk_bf16_f32 v69, v42, v43
	v_cvt_pk_bf16_f32 v70, v44, v45
	v_cvt_pk_bf16_f32 v71, v46, v47
	v_pk_add_f32 v[232:233], v[232:233], v[32:33]
	v_pk_add_f32 v[232:233], v[232:233], v[34:35]
	v_pk_add_f32 v[232:233], v[232:233], v[36:37]
	v_pk_add_f32 v[232:233], v[232:233], v[38:39]
	v_pk_add_f32 v[232:233], v[232:233], v[40:41]
	v_pk_add_f32 v[232:233], v[232:233], v[42:43]
	v_pk_add_f32 v[232:233], v[232:233], v[44:45]
	v_pk_add_f32 v[232:233], v[232:233], v[46:47]
	ds_read2_b32 v[32:33], v115 offset0:136 offset1:137
	ds_read2_b32 v[34:35], v115 offset0:138 offset1:139
	ds_read2_b32 v[36:37], v115 offset0:144 offset1:145
	ds_read2_b32 v[38:39], v115 offset0:146 offset1:147
	ds_read2_b32 v[40:41], v115 offset0:153 offset1:154
	ds_read2_b32 v[42:43], v115 offset0:155 offset1:156
	ds_read2_b32 v[44:45], v115 offset0:161 offset1:162
	ds_read2_b32 v[46:47], v115 offset0:163 offset1:164
	v_mfma_f32_32x32x16_bf16 v[0:15], v[64:67], v[72:75], v[0:15]
	v_mfma_f32_32x32x16_bf16 v[16:31], v[64:67], v[76:79], v[16:31]
	v_mfma_f32_32x32x16_bf16 v[0:15], v[68:71], v[220:223], v[0:15]
	v_mfma_f32_32x32x16_bf16 v[16:31], v[68:71], v[224:227], v[16:31]
	s_add_i32 s90, s67, 96
	v_add_u32_e32 v80, s90, v235
	v_add_u32_e32 v83, s90, v236
	v_add_u32_e32 v99, s90, v237
	v_add_u32_e32 v253, s90, v238
	v_add_u32_e32 v254, s90, v100
	v_add_u32_e32 v255, s90, v149
	v_med3_i32 v80, v80, 0, s99
	v_med3_i32 v83, v83, 0, s99
	v_med3_i32 v99, v99, 0, s99
	v_med3_i32 v253, v253, 0, s99
	v_med3_i32 v254, v254, 0, s99
	v_med3_i32 v255, v255, 0, s99
	v_mad_u32_u24 v80, v80, s100, v252
	v_mad_u32_u24 v83, v83, s100, v252
	v_mad_u32_u24 v99, v99, s100, v252
	v_mad_u32_u24 v253, v253, s100, v252
	v_mad_u32_u24 v254, v254, s100, v153
	v_mad_u32_u24 v255, v255, s100, v153
	global_load_dwordx4 v[156:159], v80, s[82:83]
	global_load_dwordx4 v[160:163], v83, s[82:83]
	global_load_dwordx4 v[164:167], v99, s[82:83]
	global_load_dwordx4 v[168:171], v253, s[82:83]
	global_load_dwordx4 v[172:175], v254, s[82:83] offset:768
	global_load_dwordx4 v[176:179], v255, s[82:83] offset:768
	global_load_dwordx4 v[180:183], v254, s[82:83] offset:832
	global_load_dwordx4 v[184:187], v255, s[82:83] offset:832
	ds_read_b64_tr_b16 v[72:73], v231
	ds_read_b64_tr_b16 v[74:75], v231 offset:512
	ds_read_b64_tr_b16 v[76:77], v231 offset:2048
	ds_read_b64_tr_b16 v[78:79], v231 offset:2560
	ds_read_b64_tr_b16 v[220:221], v231 offset:1024
	ds_read_b64_tr_b16 v[222:223], v231 offset:1536
	ds_read_b64_tr_b16 v[224:225], v231 offset:3072
	ds_read_b64_tr_b16 v[226:227], v231 offset:3584
	s_waitcnt vmcnt(8)
	ds_write_b128 v247, v[116:119]
	ds_write_b128 v247, v[120:123] offset:1024
	ds_write_b128 v247, v[124:127] offset:2048
	ds_write_b128 v247, v[128:131] offset:3072
	ds_read_b128 v[116:119], v248
	ds_read_b128 v[120:123], v249
	ds_read_b128 v[124:127], v250
	ds_read_b128 v[128:131], v251
	ds_write_b128 v112, v[132:135]
	ds_write_b128 v112, v[136:139] offset:1024
	ds_write_b128 v112, v[140:143] offset:2048
	ds_write_b128 v112, v[144:147] offset:3072
	s_waitcnt lgkmcnt(4)
	v_mfma_f32_32x32x16_bf16 v[32:47], v[116:119], v[48:51], v[32:47]
	v_exp_f32_e32 v188, v188
	v_exp_f32_e32 v189, v189
	v_exp_f32_e32 v190, v190
	v_exp_f32_e32 v191, v191
	v_mfma_f32_32x32x16_bf16 v[32:47], v[120:123], v[52:55], v[32:47]
	v_exp_f32_e32 v192, v192
	v_exp_f32_e32 v193, v193
	v_exp_f32_e32 v194, v194
	v_exp_f32_e32 v195, v195
	v_mfma_f32_32x32x16_bf16 v[32:47], v[124:127], v[56:59], v[32:47]
	v_exp_f32_e32 v196, v196
	v_exp_f32_e32 v197, v197
	v_exp_f32_e32 v198, v198
	v_exp_f32_e32 v199, v199
	v_mfma_f32_32x32x16_bf16 v[32:47], v[128:131], v[60:63], v[32:47]
	v_exp_f32_e32 v200, v200
	v_exp_f32_e32 v201, v201
	v_exp_f32_e32 v202, v202
	v_exp_f32_e32 v203, v203
	s_add_i32 s90, s67, 32
	v_add_u32_e32 v84, s90, v107
	v_add_u32_e32 v85, 0, v84
	v_add_u32_e32 v86, 1, v84
	v_add_u32_e32 v87, 2, v84
	v_add_u32_e32 v88, 3, v84
	v_cmp_gt_u32_e64 s[30:31], s98, v85
	v_cmp_gt_u32_e64 s[36:37], s98, v86
	v_cmp_gt_u32_e64 s[78:79], s98, v87
	v_cmp_gt_u32_e64 s[50:51], s98, v88
	v_cndmask_b32_e64 v188, 0, v188, s[30:31]
	v_add_u32_e32 v85, 8, v84
	v_cmp_gt_u32_e64 s[30:31], s98, v85
	v_cndmask_b32_e64 v189, 0, v189, s[36:37]
	v_add_u32_e32 v86, 9, v84
	v_cmp_gt_u32_e64 s[36:37], s98, v86
	v_cndmask_b32_e64 v190, 0, v190, s[78:79]
	v_add_u32_e32 v87, 10, v84
	v_cmp_gt_u32_e64 s[78:79], s98, v87
	v_cndmask_b32_e64 v191, 0, v191, s[50:51]
	v_add_u32_e32 v88, 11, v84
	v_cmp_gt_u32_e64 s[50:51], s98, v88
	v_cndmask_b32_e64 v192, 0, v192, s[30:31]
	v_add_u32_e32 v85, 16, v84
	v_cmp_gt_u32_e64 s[30:31], s98, v85
	v_cndmask_b32_e64 v193, 0, v193, s[36:37]
	v_add_u32_e32 v86, 17, v84
	v_cmp_gt_u32_e64 s[36:37], s98, v86
	v_cndmask_b32_e64 v194, 0, v194, s[78:79]
	v_add_u32_e32 v87, 18, v84
	v_cmp_gt_u32_e64 s[78:79], s98, v87
	v_cndmask_b32_e64 v195, 0, v195, s[50:51]
	v_add_u32_e32 v88, 19, v84
	v_cmp_gt_u32_e64 s[50:51], s98, v88
	v_cndmask_b32_e64 v196, 0, v196, s[30:31]
	v_add_u32_e32 v85, 24, v84
	v_cmp_gt_u32_e64 s[30:31], s98, v85
	v_cndmask_b32_e64 v197, 0, v197, s[36:37]
	v_add_u32_e32 v86, 25, v84
	v_cmp_gt_u32_e64 s[36:37], s98, v86
	v_cndmask_b32_e64 v198, 0, v198, s[78:79]
	v_add_u32_e32 v87, 26, v84
	v_cmp_gt_u32_e64 s[78:79], s98, v87
	v_cndmask_b32_e64 v199, 0, v199, s[50:51]
	v_add_u32_e32 v88, 27, v84
	v_cmp_gt_u32_e64 s[50:51], s98, v88
	v_nop
	v_cndmask_b32_e64 v200, 0, v200, s[30:31]
	v_cndmask_b32_e64 v201, 0, v201, s[36:37]
	v_cndmask_b32_e64 v202, 0, v202, s[78:79]
	v_cndmask_b32_e64 v203, 0, v203, s[50:51]
	v_cvt_pk_bf16_f32 v64, v188, v189
	v_cvt_pk_bf16_f32 v65, v190, v191
	v_cvt_pk_bf16_f32 v66, v192, v193
	v_cvt_pk_bf16_f32 v67, v194, v195
	v_cvt_pk_bf16_f32 v68, v196, v197
	v_cvt_pk_bf16_f32 v69, v198, v199
	v_cvt_pk_bf16_f32 v70, v200, v201
	v_cvt_pk_bf16_f32 v71, v202, v203
	v_pk_add_f32 v[232:233], v[232:233], v[188:189]
	v_pk_add_f32 v[232:233], v[232:233], v[190:191]
	v_pk_add_f32 v[232:233], v[232:233], v[192:193]
	v_pk_add_f32 v[232:233], v[232:233], v[194:195]
	v_pk_add_f32 v[232:233], v[232:233], v[196:197]
	v_pk_add_f32 v[232:233], v[232:233], v[198:199]
	v_pk_add_f32 v[232:233], v[232:233], v[200:201]
	v_pk_add_f32 v[232:233], v[232:233], v[202:203]
	ds_read2_b32 v[188:189], v115 offset0:170 offset1:171
	ds_read2_b32 v[190:191], v115 offset0:172 offset1:173
	ds_read2_b32 v[192:193], v115 offset0:178 offset1:179
	ds_read2_b32 v[194:195], v115 offset0:180 offset1:181
	ds_read2_b32 v[196:197], v115 offset0:187 offset1:188
	ds_read2_b32 v[198:199], v115 offset0:189 offset1:190
	ds_read2_b32 v[200:201], v115 offset0:195 offset1:196
	ds_read2_b32 v[202:203], v115 offset0:197 offset1:198
	v_mfma_f32_32x32x16_bf16 v[0:15], v[64:67], v[72:75], v[0:15]
	v_mfma_f32_32x32x16_bf16 v[16:31], v[64:67], v[76:79], v[16:31]
	v_mfma_f32_32x32x16_bf16 v[0:15], v[68:71], v[220:223], v[0:15]
	v_mfma_f32_32x32x16_bf16 v[16:31], v[68:71], v[224:227], v[16:31]
	s_add_i32 s90, s67, 128
	v_add_u32_e32 v80, s90, v235
	v_add_u32_e32 v83, s90, v236
	v_add_u32_e32 v99, s90, v237
	v_add_u32_e32 v253, s90, v238
	v_add_u32_e32 v254, s90, v100
	v_add_u32_e32 v255, s90, v149
	v_med3_i32 v80, v80, 0, s99
	v_med3_i32 v83, v83, 0, s99
	v_med3_i32 v99, v99, 0, s99
	v_med3_i32 v253, v253, 0, s99
	v_med3_i32 v254, v254, 0, s99
	v_med3_i32 v255, v255, 0, s99
	v_mad_u32_u24 v80, v80, s100, v252
	v_mad_u32_u24 v83, v83, s100, v252
	v_mad_u32_u24 v99, v99, s100, v252
	v_mad_u32_u24 v253, v253, s100, v252
	v_mad_u32_u24 v254, v254, s100, v153
	v_mad_u32_u24 v255, v255, s100, v153
	global_load_dwordx4 v[116:119], v80, s[82:83]
	global_load_dwordx4 v[120:123], v83, s[82:83]
	global_load_dwordx4 v[124:127], v99, s[82:83]
	global_load_dwordx4 v[128:131], v253, s[82:83]
	global_load_dwordx4 v[132:135], v254, s[82:83] offset:768
	global_load_dwordx4 v[136:139], v255, s[82:83] offset:768
	global_load_dwordx4 v[140:143], v254, s[82:83] offset:832
	global_load_dwordx4 v[144:147], v255, s[82:83] offset:832
	ds_read_b64_tr_b16 v[72:73], v231
	ds_read_b64_tr_b16 v[74:75], v231 offset:512
	ds_read_b64_tr_b16 v[76:77], v231 offset:2048
	ds_read_b64_tr_b16 v[78:79], v231 offset:2560
	ds_read_b64_tr_b16 v[220:221], v231 offset:1024
	ds_read_b64_tr_b16 v[222:223], v231 offset:1536
	ds_read_b64_tr_b16 v[224:225], v231 offset:3072
	ds_read_b64_tr_b16 v[226:227], v231 offset:3584
	s_waitcnt vmcnt(8)
	ds_write_b128 v247, v[156:159]
	ds_write_b128 v247, v[160:163] offset:1024
	ds_write_b128 v247, v[164:167] offset:2048
	ds_write_b128 v247, v[168:171] offset:3072
	ds_read_b128 v[156:159], v248
	ds_read_b128 v[160:163], v249
	ds_read_b128 v[164:167], v250
	ds_read_b128 v[168:171], v251
	ds_write_b128 v112, v[172:175]
	ds_write_b128 v112, v[176:179] offset:1024
	ds_write_b128 v112, v[180:183] offset:2048
	ds_write_b128 v112, v[184:187] offset:3072
	s_waitcnt lgkmcnt(4)
	v_mfma_f32_32x32x16_bf16 v[188:203], v[156:159], v[48:51], v[188:203]
	v_exp_f32_e32 v32, v32
	v_exp_f32_e32 v33, v33
	v_exp_f32_e32 v34, v34
	v_exp_f32_e32 v35, v35
	v_mfma_f32_32x32x16_bf16 v[188:203], v[160:163], v[52:55], v[188:203]
	v_exp_f32_e32 v36, v36
	v_exp_f32_e32 v37, v37
	v_exp_f32_e32 v38, v38
	v_exp_f32_e32 v39, v39
	v_mfma_f32_32x32x16_bf16 v[188:203], v[164:167], v[56:59], v[188:203]
	v_exp_f32_e32 v40, v40
	v_exp_f32_e32 v41, v41
	v_exp_f32_e32 v42, v42
	v_exp_f32_e32 v43, v43
	v_mfma_f32_32x32x16_bf16 v[188:203], v[168:171], v[60:63], v[188:203]
	v_exp_f32_e32 v44, v44
	v_exp_f32_e32 v45, v45
	v_exp_f32_e32 v46, v46
	v_exp_f32_e32 v47, v47
	s_add_i32 s90, s67, 64
	v_add_u32_e32 v84, s90, v107
	v_add_u32_e32 v85, 0, v84
	v_add_u32_e32 v86, 1, v84
	v_add_u32_e32 v87, 2, v84
	v_add_u32_e32 v88, 3, v84
	v_cmp_gt_u32_e64 s[30:31], s98, v85
	v_cmp_gt_u32_e64 s[36:37], s98, v86
	v_cmp_gt_u32_e64 s[78:79], s98, v87
	v_cmp_gt_u32_e64 s[50:51], s98, v88
	v_cndmask_b32_e64 v32, 0, v32, s[30:31]
	v_add_u32_e32 v85, 8, v84
	v_cmp_gt_u32_e64 s[30:31], s98, v85
	v_cndmask_b32_e64 v33, 0, v33, s[36:37]
	v_add_u32_e32 v86, 9, v84
	v_cmp_gt_u32_e64 s[36:37], s98, v86
	v_cndmask_b32_e64 v34, 0, v34, s[78:79]
	v_add_u32_e32 v87, 10, v84
	v_cmp_gt_u32_e64 s[78:79], s98, v87
	v_cndmask_b32_e64 v35, 0, v35, s[50:51]
	v_add_u32_e32 v88, 11, v84
	v_cmp_gt_u32_e64 s[50:51], s98, v88
	v_cndmask_b32_e64 v36, 0, v36, s[30:31]
	v_add_u32_e32 v85, 16, v84
	v_cmp_gt_u32_e64 s[30:31], s98, v85
	v_cndmask_b32_e64 v37, 0, v37, s[36:37]
	v_add_u32_e32 v86, 17, v84
	v_cmp_gt_u32_e64 s[36:37], s98, v86
	v_cndmask_b32_e64 v38, 0, v38, s[78:79]
	v_add_u32_e32 v87, 18, v84
	v_cmp_gt_u32_e64 s[78:79], s98, v87
	v_cndmask_b32_e64 v39, 0, v39, s[50:51]
	v_add_u32_e32 v88, 19, v84
	v_cmp_gt_u32_e64 s[50:51], s98, v88
	v_cndmask_b32_e64 v40, 0, v40, s[30:31]
	v_add_u32_e32 v85, 24, v84
	v_cmp_gt_u32_e64 s[30:31], s98, v85
	v_cndmask_b32_e64 v41, 0, v41, s[36:37]
	v_add_u32_e32 v86, 25, v84
	v_cmp_gt_u32_e64 s[36:37], s98, v86
	v_cndmask_b32_e64 v42, 0, v42, s[78:79]
	v_add_u32_e32 v87, 26, v84
	v_cmp_gt_u32_e64 s[78:79], s98, v87
	v_cndmask_b32_e64 v43, 0, v43, s[50:51]
	v_add_u32_e32 v88, 27, v84
	v_cmp_gt_u32_e64 s[50:51], s98, v88
	v_nop
	v_cndmask_b32_e64 v44, 0, v44, s[30:31]
	v_cndmask_b32_e64 v45, 0, v45, s[36:37]
	v_cndmask_b32_e64 v46, 0, v46, s[78:79]
	v_cndmask_b32_e64 v47, 0, v47, s[50:51]
	v_cvt_pk_bf16_f32 v64, v32, v33
	v_cvt_pk_bf16_f32 v65, v34, v35
	v_cvt_pk_bf16_f32 v66, v36, v37
	v_cvt_pk_bf16_f32 v67, v38, v39
	v_cvt_pk_bf16_f32 v68, v40, v41
	v_cvt_pk_bf16_f32 v69, v42, v43
	v_cvt_pk_bf16_f32 v70, v44, v45
	v_cvt_pk_bf16_f32 v71, v46, v47
	v_pk_add_f32 v[232:233], v[232:233], v[32:33]
	v_pk_add_f32 v[232:233], v[232:233], v[34:35]
	v_pk_add_f32 v[232:233], v[232:233], v[36:37]
	v_pk_add_f32 v[232:233], v[232:233], v[38:39]
	v_pk_add_f32 v[232:233], v[232:233], v[40:41]
	v_pk_add_f32 v[232:233], v[232:233], v[42:43]
	v_pk_add_f32 v[232:233], v[232:233], v[44:45]
	v_pk_add_f32 v[232:233], v[232:233], v[46:47]
	ds_read2_b32 v[32:33], v115 offset0:204 offset1:205
	ds_read2_b32 v[34:35], v115 offset0:206 offset1:207
	ds_read2_b32 v[36:37], v115 offset0:212 offset1:213
	ds_read2_b32 v[38:39], v115 offset0:214 offset1:215
	ds_read2_b32 v[40:41], v115 offset0:221 offset1:222
	ds_read2_b32 v[42:43], v115 offset0:223 offset1:224
	ds_read2_b32 v[44:45], v115 offset0:229 offset1:230
	ds_read2_b32 v[46:47], v115 offset0:231 offset1:232
	v_mfma_f32_32x32x16_bf16 v[0:15], v[64:67], v[72:75], v[0:15]
	v_mfma_f32_32x32x16_bf16 v[16:31], v[64:67], v[76:79], v[16:31]
	v_mfma_f32_32x32x16_bf16 v[0:15], v[68:71], v[220:223], v[0:15]
	v_mfma_f32_32x32x16_bf16 v[16:31], v[68:71], v[224:227], v[16:31]
	s_add_i32 s90, s67, 160
	v_add_u32_e32 v80, s90, v235
	v_add_u32_e32 v83, s90, v236
	v_add_u32_e32 v99, s90, v237
	v_add_u32_e32 v253, s90, v238
	v_add_u32_e32 v254, s90, v100
	v_add_u32_e32 v255, s90, v149
	v_med3_i32 v80, v80, 0, s99
	v_med3_i32 v83, v83, 0, s99
	v_med3_i32 v99, v99, 0, s99
	v_med3_i32 v253, v253, 0, s99
	v_med3_i32 v254, v254, 0, s99
	v_med3_i32 v255, v255, 0, s99
	v_mad_u32_u24 v80, v80, s100, v252
	v_mad_u32_u24 v83, v83, s100, v252
	v_mad_u32_u24 v99, v99, s100, v252
	v_mad_u32_u24 v253, v253, s100, v252
	v_mad_u32_u24 v254, v254, s100, v153
	v_mad_u32_u24 v255, v255, s100, v153
	global_load_dwordx4 v[156:159], v80, s[82:83]
	global_load_dwordx4 v[160:163], v83, s[82:83]
	global_load_dwordx4 v[164:167], v99, s[82:83]
	global_load_dwordx4 v[168:171], v253, s[82:83]
	global_load_dwordx4 v[172:175], v254, s[82:83] offset:768
	global_load_dwordx4 v[176:179], v255, s[82:83] offset:768
	global_load_dwordx4 v[180:183], v254, s[82:83] offset:832
	global_load_dwordx4 v[184:187], v255, s[82:83] offset:832
	ds_read_b64_tr_b16 v[72:73], v231
	ds_read_b64_tr_b16 v[74:75], v231 offset:512
	ds_read_b64_tr_b16 v[76:77], v231 offset:2048
	ds_read_b64_tr_b16 v[78:79], v231 offset:2560
	ds_read_b64_tr_b16 v[220:221], v231 offset:1024
	ds_read_b64_tr_b16 v[222:223], v231 offset:1536
	ds_read_b64_tr_b16 v[224:225], v231 offset:3072
	ds_read_b64_tr_b16 v[226:227], v231 offset:3584
	s_waitcnt vmcnt(8)
	ds_write_b128 v247, v[116:119]
	ds_write_b128 v247, v[120:123] offset:1024
	ds_write_b128 v247, v[124:127] offset:2048
	ds_write_b128 v247, v[128:131] offset:3072
	ds_read_b128 v[116:119], v248
	ds_read_b128 v[120:123], v249
	ds_read_b128 v[124:127], v250
	ds_read_b128 v[128:131], v251
	ds_write_b128 v112, v[132:135]
	ds_write_b128 v112, v[136:139] offset:1024
	ds_write_b128 v112, v[140:143] offset:2048
	ds_write_b128 v112, v[144:147] offset:3072
	s_waitcnt lgkmcnt(4)
	v_mfma_f32_32x32x16_bf16 v[32:47], v[116:119], v[48:51], v[32:47]
	v_exp_f32_e32 v188, v188
	v_exp_f32_e32 v189, v189
	v_exp_f32_e32 v190, v190
	v_exp_f32_e32 v191, v191
	v_mfma_f32_32x32x16_bf16 v[32:47], v[120:123], v[52:55], v[32:47]
	v_exp_f32_e32 v192, v192
	v_exp_f32_e32 v193, v193
	v_exp_f32_e32 v194, v194
	v_exp_f32_e32 v195, v195
	v_mfma_f32_32x32x16_bf16 v[32:47], v[124:127], v[56:59], v[32:47]
	v_exp_f32_e32 v196, v196
	v_exp_f32_e32 v197, v197
	v_exp_f32_e32 v198, v198
	v_exp_f32_e32 v199, v199
	v_mfma_f32_32x32x16_bf16 v[32:47], v[128:131], v[60:63], v[32:47]
	v_exp_f32_e32 v200, v200
	v_exp_f32_e32 v201, v201
	v_exp_f32_e32 v202, v202
	v_exp_f32_e32 v203, v203
	s_add_i32 s90, s67, 96
	v_add_u32_e32 v84, s90, v107
	v_add_u32_e32 v85, 0, v84
	v_add_u32_e32 v86, 1, v84
	v_add_u32_e32 v87, 2, v84
	v_add_u32_e32 v88, 3, v84
	v_cmp_gt_u32_e64 s[30:31], s98, v85
	v_cmp_gt_u32_e64 s[36:37], s98, v86
	v_cmp_gt_u32_e64 s[78:79], s98, v87
	v_cmp_gt_u32_e64 s[50:51], s98, v88
	v_cndmask_b32_e64 v188, 0, v188, s[30:31]
	v_add_u32_e32 v85, 8, v84
	v_cmp_gt_u32_e64 s[30:31], s98, v85
	v_cndmask_b32_e64 v189, 0, v189, s[36:37]
	v_add_u32_e32 v86, 9, v84
	v_cmp_gt_u32_e64 s[36:37], s98, v86
	v_cndmask_b32_e64 v190, 0, v190, s[78:79]
	v_add_u32_e32 v87, 10, v84
	v_cmp_gt_u32_e64 s[78:79], s98, v87
	v_cndmask_b32_e64 v191, 0, v191, s[50:51]
	v_add_u32_e32 v88, 11, v84
	v_cmp_gt_u32_e64 s[50:51], s98, v88
	v_cndmask_b32_e64 v192, 0, v192, s[30:31]
	v_add_u32_e32 v85, 16, v84
	v_cmp_gt_u32_e64 s[30:31], s98, v85
	v_cndmask_b32_e64 v193, 0, v193, s[36:37]
	v_add_u32_e32 v86, 17, v84
	v_cmp_gt_u32_e64 s[36:37], s98, v86
	v_cndmask_b32_e64 v194, 0, v194, s[78:79]
	v_add_u32_e32 v87, 18, v84
	v_cmp_gt_u32_e64 s[78:79], s98, v87
	v_cndmask_b32_e64 v195, 0, v195, s[50:51]
	v_add_u32_e32 v88, 19, v84
	v_cmp_gt_u32_e64 s[50:51], s98, v88
	v_cndmask_b32_e64 v196, 0, v196, s[30:31]
	v_add_u32_e32 v85, 24, v84
	v_cmp_gt_u32_e64 s[30:31], s98, v85
	v_cndmask_b32_e64 v197, 0, v197, s[36:37]
	v_add_u32_e32 v86, 25, v84
	v_cmp_gt_u32_e64 s[36:37], s98, v86
	v_cndmask_b32_e64 v198, 0, v198, s[78:79]
	v_add_u32_e32 v87, 26, v84
	v_cmp_gt_u32_e64 s[78:79], s98, v87
	v_cndmask_b32_e64 v199, 0, v199, s[50:51]
	v_add_u32_e32 v88, 27, v84
	v_cmp_gt_u32_e64 s[50:51], s98, v88
	v_nop
	v_cndmask_b32_e64 v200, 0, v200, s[30:31]
	v_cndmask_b32_e64 v201, 0, v201, s[36:37]
	v_cndmask_b32_e64 v202, 0, v202, s[78:79]
	v_cndmask_b32_e64 v203, 0, v203, s[50:51]
	v_cvt_pk_bf16_f32 v64, v188, v189
	v_cvt_pk_bf16_f32 v65, v190, v191
	v_cvt_pk_bf16_f32 v66, v192, v193
	v_cvt_pk_bf16_f32 v67, v194, v195
	v_cvt_pk_bf16_f32 v68, v196, v197
	v_cvt_pk_bf16_f32 v69, v198, v199
	v_cvt_pk_bf16_f32 v70, v200, v201
	v_cvt_pk_bf16_f32 v71, v202, v203
	v_pk_add_f32 v[232:233], v[232:233], v[188:189]
	v_pk_add_f32 v[232:233], v[232:233], v[190:191]
	v_pk_add_f32 v[232:233], v[232:233], v[192:193]
	v_pk_add_f32 v[232:233], v[232:233], v[194:195]
	v_pk_add_f32 v[232:233], v[232:233], v[196:197]
	v_pk_add_f32 v[232:233], v[232:233], v[198:199]
	v_pk_add_f32 v[232:233], v[232:233], v[200:201]
	v_pk_add_f32 v[232:233], v[232:233], v[202:203]
	v_add_u32_e32 v115, 952, v115
	ds_read2_b32 v[188:189], v115 offset0:0 offset1:1
	ds_read2_b32 v[190:191], v115 offset0:2 offset1:3
	ds_read2_b32 v[192:193], v115 offset0:8 offset1:9
	ds_read2_b32 v[194:195], v115 offset0:10 offset1:11
	ds_read2_b32 v[196:197], v115 offset0:17 offset1:18
	ds_read2_b32 v[198:199], v115 offset0:19 offset1:20
	ds_read2_b32 v[200:201], v115 offset0:25 offset1:26
	ds_read2_b32 v[202:203], v115 offset0:27 offset1:28
	v_mfma_f32_32x32x16_bf16 v[0:15], v[64:67], v[72:75], v[0:15]
	v_mfma_f32_32x32x16_bf16 v[16:31], v[64:67], v[76:79], v[16:31]
	v_mfma_f32_32x32x16_bf16 v[0:15], v[68:71], v[220:223], v[0:15]
	v_mfma_f32_32x32x16_bf16 v[16:31], v[68:71], v[224:227], v[16:31]
	s_add_i32 s90, s67, 192
	v_add_u32_e32 v80, s90, v235
	v_add_u32_e32 v83, s90, v236
	v_add_u32_e32 v99, s90, v237
	v_add_u32_e32 v253, s90, v238
	v_add_u32_e32 v254, s90, v100
	v_add_u32_e32 v255, s90, v149
	v_med3_i32 v80, v80, 0, s99
	v_med3_i32 v83, v83, 0, s99
	v_med3_i32 v99, v99, 0, s99
	v_med3_i32 v253, v253, 0, s99
	v_med3_i32 v254, v254, 0, s99
	v_med3_i32 v255, v255, 0, s99
	v_mad_u32_u24 v80, v80, s100, v252
	v_mad_u32_u24 v83, v83, s100, v252
	v_mad_u32_u24 v99, v99, s100, v252
	v_mad_u32_u24 v253, v253, s100, v252
	v_mad_u32_u24 v254, v254, s100, v153
	v_mad_u32_u24 v255, v255, s100, v153
	global_load_dwordx4 v[116:119], v80, s[82:83]
	global_load_dwordx4 v[120:123], v83, s[82:83]
	global_load_dwordx4 v[124:127], v99, s[82:83]
	global_load_dwordx4 v[128:131], v253, s[82:83]
	global_load_dwordx4 v[132:135], v254, s[82:83] offset:768
	global_load_dwordx4 v[136:139], v255, s[82:83] offset:768
	global_load_dwordx4 v[140:143], v254, s[82:83] offset:832
	global_load_dwordx4 v[144:147], v255, s[82:83] offset:832
	ds_read_b64_tr_b16 v[72:73], v231
	ds_read_b64_tr_b16 v[74:75], v231 offset:512
	ds_read_b64_tr_b16 v[76:77], v231 offset:2048
	ds_read_b64_tr_b16 v[78:79], v231 offset:2560
	ds_read_b64_tr_b16 v[220:221], v231 offset:1024
	ds_read_b64_tr_b16 v[222:223], v231 offset:1536
	ds_read_b64_tr_b16 v[224:225], v231 offset:3072
	ds_read_b64_tr_b16 v[226:227], v231 offset:3584
	s_waitcnt vmcnt(8)
	ds_write_b128 v247, v[156:159]
	ds_write_b128 v247, v[160:163] offset:1024
	ds_write_b128 v247, v[164:167] offset:2048
	ds_write_b128 v247, v[168:171] offset:3072
	ds_read_b128 v[156:159], v248
	ds_read_b128 v[160:163], v249
	ds_read_b128 v[164:167], v250
	ds_read_b128 v[168:171], v251
	ds_write_b128 v112, v[172:175]
	ds_write_b128 v112, v[176:179] offset:1024
	ds_write_b128 v112, v[180:183] offset:2048
	ds_write_b128 v112, v[184:187] offset:3072
	s_waitcnt lgkmcnt(4)
	v_mfma_f32_32x32x16_bf16 v[188:203], v[156:159], v[48:51], v[188:203]
	v_exp_f32_e32 v32, v32
	v_exp_f32_e32 v33, v33
	v_exp_f32_e32 v34, v34
	v_exp_f32_e32 v35, v35
	v_mfma_f32_32x32x16_bf16 v[188:203], v[160:163], v[52:55], v[188:203]
	v_exp_f32_e32 v36, v36
	v_exp_f32_e32 v37, v37
	v_exp_f32_e32 v38, v38
	v_exp_f32_e32 v39, v39
	v_mfma_f32_32x32x16_bf16 v[188:203], v[164:167], v[56:59], v[188:203]
	v_exp_f32_e32 v40, v40
	v_exp_f32_e32 v41, v41
	v_exp_f32_e32 v42, v42
	v_exp_f32_e32 v43, v43
	v_mfma_f32_32x32x16_bf16 v[188:203], v[168:171], v[60:63], v[188:203]
	v_exp_f32_e32 v44, v44
	v_exp_f32_e32 v45, v45
	v_exp_f32_e32 v46, v46
	v_exp_f32_e32 v47, v47
	s_add_i32 s90, s67, 128
	v_add_u32_e32 v84, s90, v107
	v_add_u32_e32 v85, 0, v84
	v_add_u32_e32 v86, 1, v84
	v_add_u32_e32 v87, 2, v84
	v_add_u32_e32 v88, 3, v84
	v_cmp_gt_u32_e64 s[30:31], s98, v85
	v_cmp_gt_u32_e64 s[36:37], s98, v86
	v_cmp_gt_u32_e64 s[78:79], s98, v87
	v_cmp_gt_u32_e64 s[50:51], s98, v88
	v_cndmask_b32_e64 v32, 0, v32, s[30:31]
	v_add_u32_e32 v85, 8, v84
	v_cmp_gt_u32_e64 s[30:31], s98, v85
	v_cndmask_b32_e64 v33, 0, v33, s[36:37]
	v_add_u32_e32 v86, 9, v84
	v_cmp_gt_u32_e64 s[36:37], s98, v86
	v_cndmask_b32_e64 v34, 0, v34, s[78:79]
	v_add_u32_e32 v87, 10, v84
	v_cmp_gt_u32_e64 s[78:79], s98, v87
	v_cndmask_b32_e64 v35, 0, v35, s[50:51]
	v_add_u32_e32 v88, 11, v84
	v_cmp_gt_u32_e64 s[50:51], s98, v88
	v_cndmask_b32_e64 v36, 0, v36, s[30:31]
	v_add_u32_e32 v85, 16, v84
	v_cmp_gt_u32_e64 s[30:31], s98, v85
	v_cndmask_b32_e64 v37, 0, v37, s[36:37]
	v_add_u32_e32 v86, 17, v84
	v_cmp_gt_u32_e64 s[36:37], s98, v86
	v_cndmask_b32_e64 v38, 0, v38, s[78:79]
	v_add_u32_e32 v87, 18, v84
	v_cmp_gt_u32_e64 s[78:79], s98, v87
	v_cndmask_b32_e64 v39, 0, v39, s[50:51]
	v_add_u32_e32 v88, 19, v84
	v_cmp_gt_u32_e64 s[50:51], s98, v88
	v_cndmask_b32_e64 v40, 0, v40, s[30:31]
	v_add_u32_e32 v85, 24, v84
	v_cmp_gt_u32_e64 s[30:31], s98, v85
	v_cndmask_b32_e64 v41, 0, v41, s[36:37]
	v_add_u32_e32 v86, 25, v84
	v_cmp_gt_u32_e64 s[36:37], s98, v86
	v_cndmask_b32_e64 v42, 0, v42, s[78:79]
	v_add_u32_e32 v87, 26, v84
	v_cmp_gt_u32_e64 s[78:79], s98, v87
	v_cndmask_b32_e64 v43, 0, v43, s[50:51]
	v_add_u32_e32 v88, 27, v84
	v_cmp_gt_u32_e64 s[50:51], s98, v88
	v_nop
	v_cndmask_b32_e64 v44, 0, v44, s[30:31]
	v_cndmask_b32_e64 v45, 0, v45, s[36:37]
	v_cndmask_b32_e64 v46, 0, v46, s[78:79]
	v_cndmask_b32_e64 v47, 0, v47, s[50:51]
	v_cvt_pk_bf16_f32 v64, v32, v33
	v_cvt_pk_bf16_f32 v65, v34, v35
	v_cvt_pk_bf16_f32 v66, v36, v37
	v_cvt_pk_bf16_f32 v67, v38, v39
	v_cvt_pk_bf16_f32 v68, v40, v41
	v_cvt_pk_bf16_f32 v69, v42, v43
	v_cvt_pk_bf16_f32 v70, v44, v45
	v_cvt_pk_bf16_f32 v71, v46, v47
	v_pk_add_f32 v[232:233], v[232:233], v[32:33]
	v_pk_add_f32 v[232:233], v[232:233], v[34:35]
	v_pk_add_f32 v[232:233], v[232:233], v[36:37]
	v_pk_add_f32 v[232:233], v[232:233], v[38:39]
	v_pk_add_f32 v[232:233], v[232:233], v[40:41]
	v_pk_add_f32 v[232:233], v[232:233], v[42:43]
	v_pk_add_f32 v[232:233], v[232:233], v[44:45]
	v_pk_add_f32 v[232:233], v[232:233], v[46:47]
	ds_read2_b32 v[32:33], v115 offset0:34 offset1:35
	ds_read2_b32 v[34:35], v115 offset0:36 offset1:37
	ds_read2_b32 v[36:37], v115 offset0:42 offset1:43
	ds_read2_b32 v[38:39], v115 offset0:44 offset1:45
	ds_read2_b32 v[40:41], v115 offset0:51 offset1:52
	ds_read2_b32 v[42:43], v115 offset0:53 offset1:54
	ds_read2_b32 v[44:45], v115 offset0:59 offset1:60
	ds_read2_b32 v[46:47], v115 offset0:61 offset1:62
	v_mfma_f32_32x32x16_bf16 v[0:15], v[64:67], v[72:75], v[0:15]
	v_mfma_f32_32x32x16_bf16 v[16:31], v[64:67], v[76:79], v[16:31]
	v_mfma_f32_32x32x16_bf16 v[0:15], v[68:71], v[220:223], v[0:15]
	v_mfma_f32_32x32x16_bf16 v[16:31], v[68:71], v[224:227], v[16:31]
	s_add_i32 s90, s67, 224
	v_add_u32_e32 v80, s90, v235
	v_add_u32_e32 v83, s90, v236
	v_add_u32_e32 v99, s90, v237
	v_add_u32_e32 v253, s90, v238
	v_add_u32_e32 v254, s90, v100
	v_add_u32_e32 v255, s90, v149
	v_med3_i32 v80, v80, 0, s99
	v_med3_i32 v83, v83, 0, s99
	v_med3_i32 v99, v99, 0, s99
	v_med3_i32 v253, v253, 0, s99
	v_med3_i32 v254, v254, 0, s99
	v_med3_i32 v255, v255, 0, s99
	v_mad_u32_u24 v80, v80, s100, v252
	v_mad_u32_u24 v83, v83, s100, v252
	v_mad_u32_u24 v99, v99, s100, v252
	v_mad_u32_u24 v253, v253, s100, v252
	v_mad_u32_u24 v254, v254, s100, v153
	v_mad_u32_u24 v255, v255, s100, v153
	global_load_dwordx4 v[156:159], v80, s[82:83]
	global_load_dwordx4 v[160:163], v83, s[82:83]
	global_load_dwordx4 v[164:167], v99, s[82:83]
	global_load_dwordx4 v[168:171], v253, s[82:83]
	global_load_dwordx4 v[172:175], v254, s[82:83] offset:768
	global_load_dwordx4 v[176:179], v255, s[82:83] offset:768
	global_load_dwordx4 v[180:183], v254, s[82:83] offset:832
	global_load_dwordx4 v[184:187], v255, s[82:83] offset:832
	ds_read_b64_tr_b16 v[72:73], v231
	ds_read_b64_tr_b16 v[74:75], v231 offset:512
	ds_read_b64_tr_b16 v[76:77], v231 offset:2048
	ds_read_b64_tr_b16 v[78:79], v231 offset:2560
	ds_read_b64_tr_b16 v[220:221], v231 offset:1024
	ds_read_b64_tr_b16 v[222:223], v231 offset:1536
	ds_read_b64_tr_b16 v[224:225], v231 offset:3072
	ds_read_b64_tr_b16 v[226:227], v231 offset:3584
	s_waitcnt vmcnt(8)
	ds_write_b128 v247, v[116:119]
	ds_write_b128 v247, v[120:123] offset:1024
	ds_write_b128 v247, v[124:127] offset:2048
	ds_write_b128 v247, v[128:131] offset:3072
	ds_read_b128 v[116:119], v248
	ds_read_b128 v[120:123], v249
	ds_read_b128 v[124:127], v250
	ds_read_b128 v[128:131], v251
	ds_write_b128 v112, v[132:135]
	ds_write_b128 v112, v[136:139] offset:1024
	ds_write_b128 v112, v[140:143] offset:2048
	ds_write_b128 v112, v[144:147] offset:3072
	s_waitcnt lgkmcnt(4)
	v_mfma_f32_32x32x16_bf16 v[32:47], v[116:119], v[48:51], v[32:47]
	v_exp_f32_e32 v188, v188
	v_exp_f32_e32 v189, v189
	v_exp_f32_e32 v190, v190
	v_exp_f32_e32 v191, v191
	v_mfma_f32_32x32x16_bf16 v[32:47], v[120:123], v[52:55], v[32:47]
	v_exp_f32_e32 v192, v192
	v_exp_f32_e32 v193, v193
	v_exp_f32_e32 v194, v194
	v_exp_f32_e32 v195, v195
	v_mfma_f32_32x32x16_bf16 v[32:47], v[124:127], v[56:59], v[32:47]
	v_exp_f32_e32 v196, v196
	v_exp_f32_e32 v197, v197
	v_exp_f32_e32 v198, v198
	v_exp_f32_e32 v199, v199
	v_mfma_f32_32x32x16_bf16 v[32:47], v[128:131], v[60:63], v[32:47]
	v_exp_f32_e32 v200, v200
	v_exp_f32_e32 v201, v201
	v_exp_f32_e32 v202, v202
	v_exp_f32_e32 v203, v203
	s_add_i32 s90, s67, 160
	v_add_u32_e32 v84, s90, v107
	v_add_u32_e32 v85, 0, v84
	v_add_u32_e32 v86, 1, v84
	v_add_u32_e32 v87, 2, v84
	v_add_u32_e32 v88, 3, v84
	v_cmp_gt_u32_e64 s[30:31], s98, v85
	v_cmp_gt_u32_e64 s[36:37], s98, v86
	v_cmp_gt_u32_e64 s[78:79], s98, v87
	v_cmp_gt_u32_e64 s[50:51], s98, v88
	v_cndmask_b32_e64 v188, 0, v188, s[30:31]
	v_add_u32_e32 v85, 8, v84
	v_cmp_gt_u32_e64 s[30:31], s98, v85
	v_cndmask_b32_e64 v189, 0, v189, s[36:37]
	v_add_u32_e32 v86, 9, v84
	v_cmp_gt_u32_e64 s[36:37], s98, v86
	v_cndmask_b32_e64 v190, 0, v190, s[78:79]
	v_add_u32_e32 v87, 10, v84
	v_cmp_gt_u32_e64 s[78:79], s98, v87
	v_cndmask_b32_e64 v191, 0, v191, s[50:51]
	v_add_u32_e32 v88, 11, v84
	v_cmp_gt_u32_e64 s[50:51], s98, v88
	v_cndmask_b32_e64 v192, 0, v192, s[30:31]
	v_add_u32_e32 v85, 16, v84
	v_cmp_gt_u32_e64 s[30:31], s98, v85
	v_cndmask_b32_e64 v193, 0, v193, s[36:37]
	v_add_u32_e32 v86, 17, v84
	v_cmp_gt_u32_e64 s[36:37], s98, v86
	v_cndmask_b32_e64 v194, 0, v194, s[78:79]
	v_add_u32_e32 v87, 18, v84
	v_cmp_gt_u32_e64 s[78:79], s98, v87
	v_cndmask_b32_e64 v195, 0, v195, s[50:51]
	v_add_u32_e32 v88, 19, v84
	v_cmp_gt_u32_e64 s[50:51], s98, v88
	v_cndmask_b32_e64 v196, 0, v196, s[30:31]
	v_add_u32_e32 v85, 24, v84
	v_cmp_gt_u32_e64 s[30:31], s98, v85
	v_cndmask_b32_e64 v197, 0, v197, s[36:37]
	v_add_u32_e32 v86, 25, v84
	v_cmp_gt_u32_e64 s[36:37], s98, v86
	v_cndmask_b32_e64 v198, 0, v198, s[78:79]
	v_add_u32_e32 v87, 26, v84
	v_cmp_gt_u32_e64 s[78:79], s98, v87
	v_cndmask_b32_e64 v199, 0, v199, s[50:51]
	v_add_u32_e32 v88, 27, v84
	v_cmp_gt_u32_e64 s[50:51], s98, v88
	v_nop
	v_cndmask_b32_e64 v200, 0, v200, s[30:31]
	v_cndmask_b32_e64 v201, 0, v201, s[36:37]
	v_cndmask_b32_e64 v202, 0, v202, s[78:79]
	v_cndmask_b32_e64 v203, 0, v203, s[50:51]
	v_cvt_pk_bf16_f32 v64, v188, v189
	v_cvt_pk_bf16_f32 v65, v190, v191
	v_cvt_pk_bf16_f32 v66, v192, v193
	v_cvt_pk_bf16_f32 v67, v194, v195
	v_cvt_pk_bf16_f32 v68, v196, v197
	v_cvt_pk_bf16_f32 v69, v198, v199
	v_cvt_pk_bf16_f32 v70, v200, v201
	v_cvt_pk_bf16_f32 v71, v202, v203
	v_pk_add_f32 v[232:233], v[232:233], v[188:189]
	v_pk_add_f32 v[232:233], v[232:233], v[190:191]
	v_pk_add_f32 v[232:233], v[232:233], v[192:193]
	v_pk_add_f32 v[232:233], v[232:233], v[194:195]
	v_pk_add_f32 v[232:233], v[232:233], v[196:197]
	v_pk_add_f32 v[232:233], v[232:233], v[198:199]
	v_pk_add_f32 v[232:233], v[232:233], v[200:201]
	v_pk_add_f32 v[232:233], v[232:233], v[202:203]
	ds_read2_b32 v[188:189], v115 offset0:68 offset1:69
	ds_read2_b32 v[190:191], v115 offset0:70 offset1:71
	ds_read2_b32 v[192:193], v115 offset0:76 offset1:77
	ds_read2_b32 v[194:195], v115 offset0:78 offset1:79
	ds_read2_b32 v[196:197], v115 offset0:85 offset1:86
	ds_read2_b32 v[198:199], v115 offset0:87 offset1:88
	ds_read2_b32 v[200:201], v115 offset0:93 offset1:94
	ds_read2_b32 v[202:203], v115 offset0:95 offset1:96
	v_mfma_f32_32x32x16_bf16 v[0:15], v[64:67], v[72:75], v[0:15]
	v_mfma_f32_32x32x16_bf16 v[16:31], v[64:67], v[76:79], v[16:31]
	v_mfma_f32_32x32x16_bf16 v[0:15], v[68:71], v[220:223], v[0:15]
	v_mfma_f32_32x32x16_bf16 v[16:31], v[68:71], v[224:227], v[16:31]
	s_add_i32 s90, s67, 256
	v_add_u32_e32 v80, s90, v235
	v_add_u32_e32 v83, s90, v236
	v_add_u32_e32 v99, s90, v237
	v_add_u32_e32 v253, s90, v238
	v_add_u32_e32 v254, s90, v100
	v_add_u32_e32 v255, s90, v149
	v_med3_i32 v80, v80, 0, s99
	v_med3_i32 v83, v83, 0, s99
	v_med3_i32 v99, v99, 0, s99
	v_med3_i32 v253, v253, 0, s99
	v_med3_i32 v254, v254, 0, s99
	v_med3_i32 v255, v255, 0, s99
	v_mad_u32_u24 v80, v80, s100, v252
	v_mad_u32_u24 v83, v83, s100, v252
	v_mad_u32_u24 v99, v99, s100, v252
	v_mad_u32_u24 v253, v253, s100, v252
	v_mad_u32_u24 v254, v254, s100, v153
	v_mad_u32_u24 v255, v255, s100, v153
	global_load_dwordx4 v[116:119], v80, s[82:83]
	global_load_dwordx4 v[120:123], v83, s[82:83]
	global_load_dwordx4 v[124:127], v99, s[82:83]
	global_load_dwordx4 v[128:131], v253, s[82:83]
	global_load_dwordx4 v[132:135], v254, s[82:83] offset:768
	global_load_dwordx4 v[136:139], v255, s[82:83] offset:768
	global_load_dwordx4 v[140:143], v254, s[82:83] offset:832
	global_load_dwordx4 v[144:147], v255, s[82:83] offset:832
	ds_read_b64_tr_b16 v[72:73], v231
	ds_read_b64_tr_b16 v[74:75], v231 offset:512
	ds_read_b64_tr_b16 v[76:77], v231 offset:2048
	ds_read_b64_tr_b16 v[78:79], v231 offset:2560
	ds_read_b64_tr_b16 v[220:221], v231 offset:1024
	ds_read_b64_tr_b16 v[222:223], v231 offset:1536
	ds_read_b64_tr_b16 v[224:225], v231 offset:3072
	ds_read_b64_tr_b16 v[226:227], v231 offset:3584
	s_waitcnt vmcnt(8)
	ds_write_b128 v247, v[156:159]
	ds_write_b128 v247, v[160:163] offset:1024
	ds_write_b128 v247, v[164:167] offset:2048
	ds_write_b128 v247, v[168:171] offset:3072
	ds_read_b128 v[156:159], v248
	ds_read_b128 v[160:163], v249
	ds_read_b128 v[164:167], v250
	ds_read_b128 v[168:171], v251
	ds_write_b128 v112, v[172:175]
	ds_write_b128 v112, v[176:179] offset:1024
	ds_write_b128 v112, v[180:183] offset:2048
	ds_write_b128 v112, v[184:187] offset:3072
	s_waitcnt lgkmcnt(4)
	v_mfma_f32_32x32x16_bf16 v[188:203], v[156:159], v[48:51], v[188:203]
	v_exp_f32_e32 v32, v32
	v_exp_f32_e32 v33, v33
	v_exp_f32_e32 v34, v34
	v_exp_f32_e32 v35, v35
	v_mfma_f32_32x32x16_bf16 v[188:203], v[160:163], v[52:55], v[188:203]
	v_exp_f32_e32 v36, v36
	v_exp_f32_e32 v37, v37
	v_exp_f32_e32 v38, v38
	v_exp_f32_e32 v39, v39
	v_mfma_f32_32x32x16_bf16 v[188:203], v[164:167], v[56:59], v[188:203]
	v_exp_f32_e32 v40, v40
	v_exp_f32_e32 v41, v41
	v_exp_f32_e32 v42, v42
	v_exp_f32_e32 v43, v43
	v_mfma_f32_32x32x16_bf16 v[188:203], v[168:171], v[60:63], v[188:203]
	v_exp_f32_e32 v44, v44
	v_exp_f32_e32 v45, v45
	v_exp_f32_e32 v46, v46
	v_exp_f32_e32 v47, v47
	s_add_i32 s90, s67, 192
	v_add_u32_e32 v84, s90, v107
	v_add_u32_e32 v85, 0, v84
	v_add_u32_e32 v86, 1, v84
	v_add_u32_e32 v87, 2, v84
	v_add_u32_e32 v88, 3, v84
	v_cmp_gt_u32_e64 s[30:31], s98, v85
	v_cmp_gt_u32_e64 s[36:37], s98, v86
	v_cmp_gt_u32_e64 s[78:79], s98, v87
	v_cmp_gt_u32_e64 s[50:51], s98, v88
	v_cndmask_b32_e64 v32, 0, v32, s[30:31]
	v_add_u32_e32 v85, 8, v84
	v_cmp_gt_u32_e64 s[30:31], s98, v85
	v_cndmask_b32_e64 v33, 0, v33, s[36:37]
	v_add_u32_e32 v86, 9, v84
	v_cmp_gt_u32_e64 s[36:37], s98, v86
	v_cndmask_b32_e64 v34, 0, v34, s[78:79]
	v_add_u32_e32 v87, 10, v84
	v_cmp_gt_u32_e64 s[78:79], s98, v87
	v_cndmask_b32_e64 v35, 0, v35, s[50:51]
	v_add_u32_e32 v88, 11, v84
	v_cmp_gt_u32_e64 s[50:51], s98, v88
	v_cndmask_b32_e64 v36, 0, v36, s[30:31]
	v_add_u32_e32 v85, 16, v84
	v_cmp_gt_u32_e64 s[30:31], s98, v85
	v_cndmask_b32_e64 v37, 0, v37, s[36:37]
	v_add_u32_e32 v86, 17, v84
	v_cmp_gt_u32_e64 s[36:37], s98, v86
	v_cndmask_b32_e64 v38, 0, v38, s[78:79]
	v_add_u32_e32 v87, 18, v84
	v_cmp_gt_u32_e64 s[78:79], s98, v87
	v_cndmask_b32_e64 v39, 0, v39, s[50:51]
	v_add_u32_e32 v88, 19, v84
	v_cmp_gt_u32_e64 s[50:51], s98, v88
	v_cndmask_b32_e64 v40, 0, v40, s[30:31]
	v_add_u32_e32 v85, 24, v84
	v_cmp_gt_u32_e64 s[30:31], s98, v85
	v_cndmask_b32_e64 v41, 0, v41, s[36:37]
	v_add_u32_e32 v86, 25, v84
	v_cmp_gt_u32_e64 s[36:37], s98, v86
	v_cndmask_b32_e64 v42, 0, v42, s[78:79]
	v_add_u32_e32 v87, 26, v84
	v_cmp_gt_u32_e64 s[78:79], s98, v87
	v_cndmask_b32_e64 v43, 0, v43, s[50:51]
	v_add_u32_e32 v88, 27, v84
	v_cmp_gt_u32_e64 s[50:51], s98, v88
	v_nop
	v_cndmask_b32_e64 v44, 0, v44, s[30:31]
	v_cndmask_b32_e64 v45, 0, v45, s[36:37]
	v_cndmask_b32_e64 v46, 0, v46, s[78:79]
	v_cndmask_b32_e64 v47, 0, v47, s[50:51]
	v_cvt_pk_bf16_f32 v64, v32, v33
	v_cvt_pk_bf16_f32 v65, v34, v35
	v_cvt_pk_bf16_f32 v66, v36, v37
	v_cvt_pk_bf16_f32 v67, v38, v39
	v_cvt_pk_bf16_f32 v68, v40, v41
	v_cvt_pk_bf16_f32 v69, v42, v43
	v_cvt_pk_bf16_f32 v70, v44, v45
	v_cvt_pk_bf16_f32 v71, v46, v47
	v_pk_add_f32 v[232:233], v[232:233], v[32:33]
	v_pk_add_f32 v[232:233], v[232:233], v[34:35]
	v_pk_add_f32 v[232:233], v[232:233], v[36:37]
	v_pk_add_f32 v[232:233], v[232:233], v[38:39]
	v_pk_add_f32 v[232:233], v[232:233], v[40:41]
	v_pk_add_f32 v[232:233], v[232:233], v[42:43]
	v_pk_add_f32 v[232:233], v[232:233], v[44:45]
	v_pk_add_f32 v[232:233], v[232:233], v[46:47]
	ds_read2_b32 v[32:33], v115 offset0:102 offset1:103
	ds_read2_b32 v[34:35], v115 offset0:104 offset1:105
	ds_read2_b32 v[36:37], v115 offset0:110 offset1:111
	ds_read2_b32 v[38:39], v115 offset0:112 offset1:113
	ds_read2_b32 v[40:41], v115 offset0:119 offset1:120
	ds_read2_b32 v[42:43], v115 offset0:121 offset1:122
	ds_read2_b32 v[44:45], v115 offset0:127 offset1:128
	ds_read2_b32 v[46:47], v115 offset0:129 offset1:130
	v_mfma_f32_32x32x16_bf16 v[0:15], v[64:67], v[72:75], v[0:15]
	v_mfma_f32_32x32x16_bf16 v[16:31], v[64:67], v[76:79], v[16:31]
	v_mfma_f32_32x32x16_bf16 v[0:15], v[68:71], v[220:223], v[0:15]
	v_mfma_f32_32x32x16_bf16 v[16:31], v[68:71], v[224:227], v[16:31]
	s_add_i32 s90, s67, 288
	v_add_u32_e32 v80, s90, v235
	v_add_u32_e32 v83, s90, v236
	v_add_u32_e32 v99, s90, v237
	v_add_u32_e32 v253, s90, v238
	v_add_u32_e32 v254, s90, v100
	v_add_u32_e32 v255, s90, v149
	v_med3_i32 v80, v80, 0, s99
	v_med3_i32 v83, v83, 0, s99
	v_med3_i32 v99, v99, 0, s99
	v_med3_i32 v253, v253, 0, s99
	v_med3_i32 v254, v254, 0, s99
	v_med3_i32 v255, v255, 0, s99
	v_mad_u32_u24 v80, v80, s100, v252
	v_mad_u32_u24 v83, v83, s100, v252
	v_mad_u32_u24 v99, v99, s100, v252
	v_mad_u32_u24 v253, v253, s100, v252
	v_mad_u32_u24 v254, v254, s100, v153
	v_mad_u32_u24 v255, v255, s100, v153
	global_load_dwordx4 v[156:159], v80, s[82:83]
	global_load_dwordx4 v[160:163], v83, s[82:83]
	global_load_dwordx4 v[164:167], v99, s[82:83]
	global_load_dwordx4 v[168:171], v253, s[82:83]
	global_load_dwordx4 v[172:175], v254, s[82:83] offset:768
	global_load_dwordx4 v[176:179], v255, s[82:83] offset:768
	global_load_dwordx4 v[180:183], v254, s[82:83] offset:832
	global_load_dwordx4 v[184:187], v255, s[82:83] offset:832
	ds_read_b64_tr_b16 v[72:73], v231
	ds_read_b64_tr_b16 v[74:75], v231 offset:512
	ds_read_b64_tr_b16 v[76:77], v231 offset:2048
	ds_read_b64_tr_b16 v[78:79], v231 offset:2560
	ds_read_b64_tr_b16 v[220:221], v231 offset:1024
	ds_read_b64_tr_b16 v[222:223], v231 offset:1536
	ds_read_b64_tr_b16 v[224:225], v231 offset:3072
	ds_read_b64_tr_b16 v[226:227], v231 offset:3584
	s_waitcnt vmcnt(8)
	ds_write_b128 v247, v[116:119]
	ds_write_b128 v247, v[120:123] offset:1024
	ds_write_b128 v247, v[124:127] offset:2048
	ds_write_b128 v247, v[128:131] offset:3072
	ds_read_b128 v[116:119], v248
	ds_read_b128 v[120:123], v249
	ds_read_b128 v[124:127], v250
	ds_read_b128 v[128:131], v251
	ds_write_b128 v112, v[132:135]
	ds_write_b128 v112, v[136:139] offset:1024
	ds_write_b128 v112, v[140:143] offset:2048
	ds_write_b128 v112, v[144:147] offset:3072
	s_waitcnt lgkmcnt(4)
	v_mfma_f32_32x32x16_bf16 v[32:47], v[116:119], v[48:51], v[32:47]
	v_exp_f32_e32 v188, v188
	v_exp_f32_e32 v189, v189
	v_exp_f32_e32 v190, v190
	v_exp_f32_e32 v191, v191
	v_mfma_f32_32x32x16_bf16 v[32:47], v[120:123], v[52:55], v[32:47]
	v_exp_f32_e32 v192, v192
	v_exp_f32_e32 v193, v193
	v_exp_f32_e32 v194, v194
	v_exp_f32_e32 v195, v195
	v_mfma_f32_32x32x16_bf16 v[32:47], v[124:127], v[56:59], v[32:47]
	v_exp_f32_e32 v196, v196
	v_exp_f32_e32 v197, v197
	v_exp_f32_e32 v198, v198
	v_exp_f32_e32 v199, v199
	v_mfma_f32_32x32x16_bf16 v[32:47], v[128:131], v[60:63], v[32:47]
	v_exp_f32_e32 v200, v200
	v_exp_f32_e32 v201, v201
	v_exp_f32_e32 v202, v202
	v_exp_f32_e32 v203, v203
	s_add_i32 s90, s67, 224
	v_add_u32_e32 v84, s90, v107
	v_add_u32_e32 v85, 0, v84
	v_add_u32_e32 v86, 1, v84
	v_add_u32_e32 v87, 2, v84
	v_add_u32_e32 v88, 3, v84
	v_cmp_gt_u32_e64 s[30:31], s98, v85
	v_cmp_gt_u32_e64 s[36:37], s98, v86
	v_cmp_gt_u32_e64 s[78:79], s98, v87
	v_cmp_gt_u32_e64 s[50:51], s98, v88
	v_cndmask_b32_e64 v188, 0, v188, s[30:31]
	v_add_u32_e32 v85, 8, v84
	v_cmp_gt_u32_e64 s[30:31], s98, v85
	v_cndmask_b32_e64 v189, 0, v189, s[36:37]
	v_add_u32_e32 v86, 9, v84
	v_cmp_gt_u32_e64 s[36:37], s98, v86
	v_cndmask_b32_e64 v190, 0, v190, s[78:79]
	v_add_u32_e32 v87, 10, v84
	v_cmp_gt_u32_e64 s[78:79], s98, v87
	v_cndmask_b32_e64 v191, 0, v191, s[50:51]
	v_add_u32_e32 v88, 11, v84
	v_cmp_gt_u32_e64 s[50:51], s98, v88
	v_cndmask_b32_e64 v192, 0, v192, s[30:31]
	v_add_u32_e32 v85, 16, v84
	v_cmp_gt_u32_e64 s[30:31], s98, v85
	v_cndmask_b32_e64 v193, 0, v193, s[36:37]
	v_add_u32_e32 v86, 17, v84
	v_cmp_gt_u32_e64 s[36:37], s98, v86
	v_cndmask_b32_e64 v194, 0, v194, s[78:79]
	v_add_u32_e32 v87, 18, v84
	v_cmp_gt_u32_e64 s[78:79], s98, v87
	v_cndmask_b32_e64 v195, 0, v195, s[50:51]
	v_add_u32_e32 v88, 19, v84
	v_cmp_gt_u32_e64 s[50:51], s98, v88
	v_cndmask_b32_e64 v196, 0, v196, s[30:31]
	v_add_u32_e32 v85, 24, v84
	v_cmp_gt_u32_e64 s[30:31], s98, v85
	v_cndmask_b32_e64 v197, 0, v197, s[36:37]
	v_add_u32_e32 v86, 25, v84
	v_cmp_gt_u32_e64 s[36:37], s98, v86
	v_cndmask_b32_e64 v198, 0, v198, s[78:79]
	v_add_u32_e32 v87, 26, v84
	v_cmp_gt_u32_e64 s[78:79], s98, v87
	v_cndmask_b32_e64 v199, 0, v199, s[50:51]
	v_add_u32_e32 v88, 27, v84
	v_cmp_gt_u32_e64 s[50:51], s98, v88
	v_nop
	v_cndmask_b32_e64 v200, 0, v200, s[30:31]
	v_cndmask_b32_e64 v201, 0, v201, s[36:37]
	v_cndmask_b32_e64 v202, 0, v202, s[78:79]
	v_cndmask_b32_e64 v203, 0, v203, s[50:51]
	v_cvt_pk_bf16_f32 v64, v188, v189
	v_cvt_pk_bf16_f32 v65, v190, v191
	v_cvt_pk_bf16_f32 v66, v192, v193
	v_cvt_pk_bf16_f32 v67, v194, v195
	v_cvt_pk_bf16_f32 v68, v196, v197
	v_cvt_pk_bf16_f32 v69, v198, v199
	v_cvt_pk_bf16_f32 v70, v200, v201
	v_cvt_pk_bf16_f32 v71, v202, v203
	v_pk_add_f32 v[232:233], v[232:233], v[188:189]
	v_pk_add_f32 v[232:233], v[232:233], v[190:191]
	v_pk_add_f32 v[232:233], v[232:233], v[192:193]
	v_pk_add_f32 v[232:233], v[232:233], v[194:195]
	v_pk_add_f32 v[232:233], v[232:233], v[196:197]
	v_pk_add_f32 v[232:233], v[232:233], v[198:199]
	v_pk_add_f32 v[232:233], v[232:233], v[200:201]
	v_pk_add_f32 v[232:233], v[232:233], v[202:203]
	ds_read2_b32 v[188:189], v115 offset0:136 offset1:137
	ds_read2_b32 v[190:191], v115 offset0:138 offset1:139
	ds_read2_b32 v[192:193], v115 offset0:144 offset1:145
	ds_read2_b32 v[194:195], v115 offset0:146 offset1:147
	ds_read2_b32 v[196:197], v115 offset0:153 offset1:154
	ds_read2_b32 v[198:199], v115 offset0:155 offset1:156
	ds_read2_b32 v[200:201], v115 offset0:161 offset1:162
	ds_read2_b32 v[202:203], v115 offset0:163 offset1:164
	v_mfma_f32_32x32x16_bf16 v[0:15], v[64:67], v[72:75], v[0:15]
	v_mfma_f32_32x32x16_bf16 v[16:31], v[64:67], v[76:79], v[16:31]
	v_mfma_f32_32x32x16_bf16 v[0:15], v[68:71], v[220:223], v[0:15]
	v_mfma_f32_32x32x16_bf16 v[16:31], v[68:71], v[224:227], v[16:31]
	s_add_i32 s90, s67, 320
	v_add_u32_e32 v80, s90, v235
	v_add_u32_e32 v83, s90, v236
	v_add_u32_e32 v99, s90, v237
	v_add_u32_e32 v253, s90, v238
	v_add_u32_e32 v254, s90, v100
	v_add_u32_e32 v255, s90, v149
	v_med3_i32 v80, v80, 0, s99
	v_med3_i32 v83, v83, 0, s99
	v_med3_i32 v99, v99, 0, s99
	v_med3_i32 v253, v253, 0, s99
	v_med3_i32 v254, v254, 0, s99
	v_med3_i32 v255, v255, 0, s99
	v_mad_u32_u24 v80, v80, s100, v252
	v_mad_u32_u24 v83, v83, s100, v252
	v_mad_u32_u24 v99, v99, s100, v252
	v_mad_u32_u24 v253, v253, s100, v252
	v_mad_u32_u24 v254, v254, s100, v153
	v_mad_u32_u24 v255, v255, s100, v153
	global_load_dwordx4 v[116:119], v80, s[82:83]
	global_load_dwordx4 v[120:123], v83, s[82:83]
	global_load_dwordx4 v[124:127], v99, s[82:83]
	global_load_dwordx4 v[128:131], v253, s[82:83]
	global_load_dwordx4 v[132:135], v254, s[82:83] offset:768
	global_load_dwordx4 v[136:139], v255, s[82:83] offset:768
	global_load_dwordx4 v[140:143], v254, s[82:83] offset:832
	global_load_dwordx4 v[144:147], v255, s[82:83] offset:832
	ds_read_b64_tr_b16 v[72:73], v231
	ds_read_b64_tr_b16 v[74:75], v231 offset:512
	ds_read_b64_tr_b16 v[76:77], v231 offset:2048
	ds_read_b64_tr_b16 v[78:79], v231 offset:2560
	ds_read_b64_tr_b16 v[220:221], v231 offset:1024
	ds_read_b64_tr_b16 v[222:223], v231 offset:1536
	ds_read_b64_tr_b16 v[224:225], v231 offset:3072
	ds_read_b64_tr_b16 v[226:227], v231 offset:3584
	s_waitcnt vmcnt(8)
	ds_write_b128 v247, v[156:159]
	ds_write_b128 v247, v[160:163] offset:1024
	ds_write_b128 v247, v[164:167] offset:2048
	ds_write_b128 v247, v[168:171] offset:3072
	ds_read_b128 v[156:159], v248
	ds_read_b128 v[160:163], v249
	ds_read_b128 v[164:167], v250
	ds_read_b128 v[168:171], v251
	ds_write_b128 v112, v[172:175]
	ds_write_b128 v112, v[176:179] offset:1024
	ds_write_b128 v112, v[180:183] offset:2048
	ds_write_b128 v112, v[184:187] offset:3072
	s_waitcnt lgkmcnt(4)
	v_mfma_f32_32x32x16_bf16 v[188:203], v[156:159], v[48:51], v[188:203]
	v_exp_f32_e32 v32, v32
	v_exp_f32_e32 v33, v33
	v_exp_f32_e32 v34, v34
	v_exp_f32_e32 v35, v35
	v_mfma_f32_32x32x16_bf16 v[188:203], v[160:163], v[52:55], v[188:203]
	v_exp_f32_e32 v36, v36
	v_exp_f32_e32 v37, v37
	v_exp_f32_e32 v38, v38
	v_exp_f32_e32 v39, v39
	v_mfma_f32_32x32x16_bf16 v[188:203], v[164:167], v[56:59], v[188:203]
	v_exp_f32_e32 v40, v40
	v_exp_f32_e32 v41, v41
	v_exp_f32_e32 v42, v42
	v_exp_f32_e32 v43, v43
	v_mfma_f32_32x32x16_bf16 v[188:203], v[168:171], v[60:63], v[188:203]
	v_exp_f32_e32 v44, v44
	v_exp_f32_e32 v45, v45
	v_exp_f32_e32 v46, v46
	v_exp_f32_e32 v47, v47
	s_add_i32 s90, s67, 256
	v_add_u32_e32 v84, s90, v107
	v_add_u32_e32 v85, 0, v84
	v_add_u32_e32 v86, 1, v84
	v_add_u32_e32 v87, 2, v84
	v_add_u32_e32 v88, 3, v84
	v_cmp_gt_u32_e64 s[30:31], s98, v85
	v_cmp_gt_u32_e64 s[36:37], s98, v86
	v_cmp_gt_u32_e64 s[78:79], s98, v87
	v_cmp_gt_u32_e64 s[50:51], s98, v88
	v_cndmask_b32_e64 v32, 0, v32, s[30:31]
	v_add_u32_e32 v85, 8, v84
	v_cmp_gt_u32_e64 s[30:31], s98, v85
	v_cndmask_b32_e64 v33, 0, v33, s[36:37]
	v_add_u32_e32 v86, 9, v84
	v_cmp_gt_u32_e64 s[36:37], s98, v86
	v_cndmask_b32_e64 v34, 0, v34, s[78:79]
	v_add_u32_e32 v87, 10, v84
	v_cmp_gt_u32_e64 s[78:79], s98, v87
	v_cndmask_b32_e64 v35, 0, v35, s[50:51]
	v_add_u32_e32 v88, 11, v84
	v_cmp_gt_u32_e64 s[50:51], s98, v88
	v_cndmask_b32_e64 v36, 0, v36, s[30:31]
	v_add_u32_e32 v85, 16, v84
	v_cmp_gt_u32_e64 s[30:31], s98, v85
	v_cndmask_b32_e64 v37, 0, v37, s[36:37]
	v_add_u32_e32 v86, 17, v84
	v_cmp_gt_u32_e64 s[36:37], s98, v86
	v_cndmask_b32_e64 v38, 0, v38, s[78:79]
	v_add_u32_e32 v87, 18, v84
	v_cmp_gt_u32_e64 s[78:79], s98, v87
	v_cndmask_b32_e64 v39, 0, v39, s[50:51]
	v_add_u32_e32 v88, 19, v84
	v_cmp_gt_u32_e64 s[50:51], s98, v88
	v_cndmask_b32_e64 v40, 0, v40, s[30:31]
	v_add_u32_e32 v85, 24, v84
	v_cmp_gt_u32_e64 s[30:31], s98, v85
	v_cndmask_b32_e64 v41, 0, v41, s[36:37]
	v_add_u32_e32 v86, 25, v84
	v_cmp_gt_u32_e64 s[36:37], s98, v86
	v_cndmask_b32_e64 v42, 0, v42, s[78:79]
	v_add_u32_e32 v87, 26, v84
	v_cmp_gt_u32_e64 s[78:79], s98, v87
	v_cndmask_b32_e64 v43, 0, v43, s[50:51]
	v_add_u32_e32 v88, 27, v84
	v_cmp_gt_u32_e64 s[50:51], s98, v88
	v_nop
	v_cndmask_b32_e64 v44, 0, v44, s[30:31]
	v_cndmask_b32_e64 v45, 0, v45, s[36:37]
	v_cndmask_b32_e64 v46, 0, v46, s[78:79]
	v_cndmask_b32_e64 v47, 0, v47, s[50:51]
	v_cvt_pk_bf16_f32 v64, v32, v33
	v_cvt_pk_bf16_f32 v65, v34, v35
	v_cvt_pk_bf16_f32 v66, v36, v37
	v_cvt_pk_bf16_f32 v67, v38, v39
	v_cvt_pk_bf16_f32 v68, v40, v41
	v_cvt_pk_bf16_f32 v69, v42, v43
	v_cvt_pk_bf16_f32 v70, v44, v45
	v_cvt_pk_bf16_f32 v71, v46, v47
	v_pk_add_f32 v[232:233], v[232:233], v[32:33]
	v_pk_add_f32 v[232:233], v[232:233], v[34:35]
	v_pk_add_f32 v[232:233], v[232:233], v[36:37]
	v_pk_add_f32 v[232:233], v[232:233], v[38:39]
	v_pk_add_f32 v[232:233], v[232:233], v[40:41]
	v_pk_add_f32 v[232:233], v[232:233], v[42:43]
	v_pk_add_f32 v[232:233], v[232:233], v[44:45]
	v_pk_add_f32 v[232:233], v[232:233], v[46:47]
	ds_read2_b32 v[32:33], v115 offset0:170 offset1:171
	ds_read2_b32 v[34:35], v115 offset0:172 offset1:173
	ds_read2_b32 v[36:37], v115 offset0:178 offset1:179
	ds_read2_b32 v[38:39], v115 offset0:180 offset1:181
	ds_read2_b32 v[40:41], v115 offset0:187 offset1:188
	ds_read2_b32 v[42:43], v115 offset0:189 offset1:190
	ds_read2_b32 v[44:45], v115 offset0:195 offset1:196
	ds_read2_b32 v[46:47], v115 offset0:197 offset1:198
	v_mfma_f32_32x32x16_bf16 v[0:15], v[64:67], v[72:75], v[0:15]
	v_mfma_f32_32x32x16_bf16 v[16:31], v[64:67], v[76:79], v[16:31]
	v_mfma_f32_32x32x16_bf16 v[0:15], v[68:71], v[220:223], v[0:15]
	v_mfma_f32_32x32x16_bf16 v[16:31], v[68:71], v[224:227], v[16:31]
	s_add_i32 s90, s67, 352
	v_add_u32_e32 v80, s90, v235
	v_add_u32_e32 v83, s90, v236
	v_add_u32_e32 v99, s90, v237
	v_add_u32_e32 v253, s90, v238
	v_add_u32_e32 v254, s90, v100
	v_add_u32_e32 v255, s90, v149
	v_med3_i32 v80, v80, 0, s99
	v_med3_i32 v83, v83, 0, s99
	v_med3_i32 v99, v99, 0, s99
	v_med3_i32 v253, v253, 0, s99
	v_med3_i32 v254, v254, 0, s99
	v_med3_i32 v255, v255, 0, s99
	v_mad_u32_u24 v80, v80, s100, v252
	v_mad_u32_u24 v83, v83, s100, v252
	v_mad_u32_u24 v99, v99, s100, v252
	v_mad_u32_u24 v253, v253, s100, v252
	v_mad_u32_u24 v254, v254, s100, v153
	v_mad_u32_u24 v255, v255, s100, v153
	global_load_dwordx4 v[156:159], v80, s[82:83]
	global_load_dwordx4 v[160:163], v83, s[82:83]
	global_load_dwordx4 v[164:167], v99, s[82:83]
	global_load_dwordx4 v[168:171], v253, s[82:83]
	global_load_dwordx4 v[172:175], v254, s[82:83] offset:768
	global_load_dwordx4 v[176:179], v255, s[82:83] offset:768
	global_load_dwordx4 v[180:183], v254, s[82:83] offset:832
	global_load_dwordx4 v[184:187], v255, s[82:83] offset:832
	ds_read_b64_tr_b16 v[72:73], v231
	ds_read_b64_tr_b16 v[74:75], v231 offset:512
	ds_read_b64_tr_b16 v[76:77], v231 offset:2048
	ds_read_b64_tr_b16 v[78:79], v231 offset:2560
	ds_read_b64_tr_b16 v[220:221], v231 offset:1024
	ds_read_b64_tr_b16 v[222:223], v231 offset:1536
	ds_read_b64_tr_b16 v[224:225], v231 offset:3072
	ds_read_b64_tr_b16 v[226:227], v231 offset:3584
	s_waitcnt vmcnt(8)
	ds_write_b128 v247, v[116:119]
	ds_write_b128 v247, v[120:123] offset:1024
	ds_write_b128 v247, v[124:127] offset:2048
	ds_write_b128 v247, v[128:131] offset:3072
	ds_read_b128 v[116:119], v248
	ds_read_b128 v[120:123], v249
	ds_read_b128 v[124:127], v250
	ds_read_b128 v[128:131], v251
	ds_write_b128 v112, v[132:135]
	ds_write_b128 v112, v[136:139] offset:1024
	ds_write_b128 v112, v[140:143] offset:2048
	ds_write_b128 v112, v[144:147] offset:3072
	s_waitcnt lgkmcnt(4)
	v_mfma_f32_32x32x16_bf16 v[32:47], v[116:119], v[48:51], v[32:47]
	v_exp_f32_e32 v188, v188
	v_exp_f32_e32 v189, v189
	v_exp_f32_e32 v190, v190
	v_exp_f32_e32 v191, v191
	v_mfma_f32_32x32x16_bf16 v[32:47], v[120:123], v[52:55], v[32:47]
	v_exp_f32_e32 v192, v192
	v_exp_f32_e32 v193, v193
	v_exp_f32_e32 v194, v194
	v_exp_f32_e32 v195, v195
	v_mfma_f32_32x32x16_bf16 v[32:47], v[124:127], v[56:59], v[32:47]
	v_exp_f32_e32 v196, v196
	v_exp_f32_e32 v197, v197
	v_exp_f32_e32 v198, v198
	v_exp_f32_e32 v199, v199
	v_mfma_f32_32x32x16_bf16 v[32:47], v[128:131], v[60:63], v[32:47]
	v_exp_f32_e32 v200, v200
	v_exp_f32_e32 v201, v201
	v_exp_f32_e32 v202, v202
	v_exp_f32_e32 v203, v203
	s_add_i32 s90, s67, 288
	v_add_u32_e32 v84, s90, v107
	v_add_u32_e32 v85, 0, v84
	v_add_u32_e32 v86, 1, v84
	v_add_u32_e32 v87, 2, v84
	v_add_u32_e32 v88, 3, v84
	v_cmp_gt_u32_e64 s[30:31], s98, v85
	v_cmp_gt_u32_e64 s[36:37], s98, v86
	v_cmp_gt_u32_e64 s[78:79], s98, v87
	v_cmp_gt_u32_e64 s[50:51], s98, v88
	v_cndmask_b32_e64 v188, 0, v188, s[30:31]
	v_add_u32_e32 v85, 8, v84
	v_cmp_gt_u32_e64 s[30:31], s98, v85
	v_cndmask_b32_e64 v189, 0, v189, s[36:37]
	v_add_u32_e32 v86, 9, v84
	v_cmp_gt_u32_e64 s[36:37], s98, v86
	v_cndmask_b32_e64 v190, 0, v190, s[78:79]
	v_add_u32_e32 v87, 10, v84
	v_cmp_gt_u32_e64 s[78:79], s98, v87
	v_cndmask_b32_e64 v191, 0, v191, s[50:51]
	v_add_u32_e32 v88, 11, v84
	v_cmp_gt_u32_e64 s[50:51], s98, v88
	v_cndmask_b32_e64 v192, 0, v192, s[30:31]
	v_add_u32_e32 v85, 16, v84
	v_cmp_gt_u32_e64 s[30:31], s98, v85
	v_cndmask_b32_e64 v193, 0, v193, s[36:37]
	v_add_u32_e32 v86, 17, v84
	v_cmp_gt_u32_e64 s[36:37], s98, v86
	v_cndmask_b32_e64 v194, 0, v194, s[78:79]
	v_add_u32_e32 v87, 18, v84
	v_cmp_gt_u32_e64 s[78:79], s98, v87
	v_cndmask_b32_e64 v195, 0, v195, s[50:51]
	v_add_u32_e32 v88, 19, v84
	v_cmp_gt_u32_e64 s[50:51], s98, v88
	v_cndmask_b32_e64 v196, 0, v196, s[30:31]
	v_add_u32_e32 v85, 24, v84
	v_cmp_gt_u32_e64 s[30:31], s98, v85
	v_cndmask_b32_e64 v197, 0, v197, s[36:37]
	v_add_u32_e32 v86, 25, v84
	v_cmp_gt_u32_e64 s[36:37], s98, v86
	v_cndmask_b32_e64 v198, 0, v198, s[78:79]
	v_add_u32_e32 v87, 26, v84
	v_cmp_gt_u32_e64 s[78:79], s98, v87
	v_cndmask_b32_e64 v199, 0, v199, s[50:51]
	v_add_u32_e32 v88, 27, v84
	v_cmp_gt_u32_e64 s[50:51], s98, v88
	v_nop
	v_cndmask_b32_e64 v200, 0, v200, s[30:31]
	v_cndmask_b32_e64 v201, 0, v201, s[36:37]
	v_cndmask_b32_e64 v202, 0, v202, s[78:79]
	v_cndmask_b32_e64 v203, 0, v203, s[50:51]
	v_cvt_pk_bf16_f32 v64, v188, v189
	v_cvt_pk_bf16_f32 v65, v190, v191
	v_cvt_pk_bf16_f32 v66, v192, v193
	v_cvt_pk_bf16_f32 v67, v194, v195
	v_cvt_pk_bf16_f32 v68, v196, v197
	v_cvt_pk_bf16_f32 v69, v198, v199
	v_cvt_pk_bf16_f32 v70, v200, v201
	v_cvt_pk_bf16_f32 v71, v202, v203
	v_pk_add_f32 v[232:233], v[232:233], v[188:189]
	v_pk_add_f32 v[232:233], v[232:233], v[190:191]
	v_pk_add_f32 v[232:233], v[232:233], v[192:193]
	v_pk_add_f32 v[232:233], v[232:233], v[194:195]
	v_pk_add_f32 v[232:233], v[232:233], v[196:197]
	v_pk_add_f32 v[232:233], v[232:233], v[198:199]
	v_pk_add_f32 v[232:233], v[232:233], v[200:201]
	v_pk_add_f32 v[232:233], v[232:233], v[202:203]
	ds_read2_b32 v[188:189], v115 offset0:204 offset1:205
	ds_read2_b32 v[190:191], v115 offset0:206 offset1:207
	ds_read2_b32 v[192:193], v115 offset0:212 offset1:213
	ds_read2_b32 v[194:195], v115 offset0:214 offset1:215
	ds_read2_b32 v[196:197], v115 offset0:221 offset1:222
	ds_read2_b32 v[198:199], v115 offset0:223 offset1:224
	ds_read2_b32 v[200:201], v115 offset0:229 offset1:230
	ds_read2_b32 v[202:203], v115 offset0:231 offset1:232
	v_mfma_f32_32x32x16_bf16 v[0:15], v[64:67], v[72:75], v[0:15]
	v_mfma_f32_32x32x16_bf16 v[16:31], v[64:67], v[76:79], v[16:31]
	v_mfma_f32_32x32x16_bf16 v[0:15], v[68:71], v[220:223], v[0:15]
	v_mfma_f32_32x32x16_bf16 v[16:31], v[68:71], v[224:227], v[16:31]
	s_add_i32 s90, s67, 384
	v_add_u32_e32 v80, s90, v235
	v_add_u32_e32 v83, s90, v236
	v_add_u32_e32 v99, s90, v237
	v_add_u32_e32 v253, s90, v238
	v_add_u32_e32 v254, s90, v100
	v_add_u32_e32 v255, s90, v149
	v_med3_i32 v80, v80, 0, s99
	v_med3_i32 v83, v83, 0, s99
	v_med3_i32 v99, v99, 0, s99
	v_med3_i32 v253, v253, 0, s99
	v_med3_i32 v254, v254, 0, s99
	v_med3_i32 v255, v255, 0, s99
	v_mad_u32_u24 v80, v80, s100, v252
	v_mad_u32_u24 v83, v83, s100, v252
	v_mad_u32_u24 v99, v99, s100, v252
	v_mad_u32_u24 v253, v253, s100, v252
	v_mad_u32_u24 v254, v254, s100, v153
	v_mad_u32_u24 v255, v255, s100, v153
	global_load_dwordx4 v[116:119], v80, s[82:83]
	global_load_dwordx4 v[120:123], v83, s[82:83]
	global_load_dwordx4 v[124:127], v99, s[82:83]
	global_load_dwordx4 v[128:131], v253, s[82:83]
	global_load_dwordx4 v[132:135], v254, s[82:83] offset:768
	global_load_dwordx4 v[136:139], v255, s[82:83] offset:768
	global_load_dwordx4 v[140:143], v254, s[82:83] offset:832
	global_load_dwordx4 v[144:147], v255, s[82:83] offset:832
	ds_read_b64_tr_b16 v[72:73], v231
	ds_read_b64_tr_b16 v[74:75], v231 offset:512
	ds_read_b64_tr_b16 v[76:77], v231 offset:2048
	ds_read_b64_tr_b16 v[78:79], v231 offset:2560
	ds_read_b64_tr_b16 v[220:221], v231 offset:1024
	ds_read_b64_tr_b16 v[222:223], v231 offset:1536
	ds_read_b64_tr_b16 v[224:225], v231 offset:3072
	ds_read_b64_tr_b16 v[226:227], v231 offset:3584
	s_waitcnt vmcnt(8)
	ds_write_b128 v247, v[156:159]
	ds_write_b128 v247, v[160:163] offset:1024
	ds_write_b128 v247, v[164:167] offset:2048
	ds_write_b128 v247, v[168:171] offset:3072
	ds_read_b128 v[156:159], v248
	ds_read_b128 v[160:163], v249
	ds_read_b128 v[164:167], v250
	ds_read_b128 v[168:171], v251
	ds_write_b128 v112, v[172:175]
	ds_write_b128 v112, v[176:179] offset:1024
	ds_write_b128 v112, v[180:183] offset:2048
	ds_write_b128 v112, v[184:187] offset:3072
	s_waitcnt lgkmcnt(4)
	v_mfma_f32_32x32x16_bf16 v[188:203], v[156:159], v[48:51], v[188:203]
	v_exp_f32_e32 v32, v32
	v_exp_f32_e32 v33, v33
	v_exp_f32_e32 v34, v34
	v_exp_f32_e32 v35, v35
	v_mfma_f32_32x32x16_bf16 v[188:203], v[160:163], v[52:55], v[188:203]
	v_exp_f32_e32 v36, v36
	v_exp_f32_e32 v37, v37
	v_exp_f32_e32 v38, v38
	v_exp_f32_e32 v39, v39
	v_mfma_f32_32x32x16_bf16 v[188:203], v[164:167], v[56:59], v[188:203]
	v_exp_f32_e32 v40, v40
	v_exp_f32_e32 v41, v41
	v_exp_f32_e32 v42, v42
	v_exp_f32_e32 v43, v43
	v_mfma_f32_32x32x16_bf16 v[188:203], v[168:171], v[60:63], v[188:203]
	v_exp_f32_e32 v44, v44
	v_exp_f32_e32 v45, v45
	v_exp_f32_e32 v46, v46
	v_exp_f32_e32 v47, v47
	s_add_i32 s90, s67, 320
	v_add_u32_e32 v84, s90, v107
	v_add_u32_e32 v85, 0, v84
	v_add_u32_e32 v86, 1, v84
	v_add_u32_e32 v87, 2, v84
	v_add_u32_e32 v88, 3, v84
	v_cmp_gt_u32_e64 s[30:31], s98, v85
	v_cmp_gt_u32_e64 s[36:37], s98, v86
	v_cmp_gt_u32_e64 s[78:79], s98, v87
	v_cmp_gt_u32_e64 s[50:51], s98, v88
	v_cndmask_b32_e64 v32, 0, v32, s[30:31]
	v_add_u32_e32 v85, 8, v84
	v_cmp_gt_u32_e64 s[30:31], s98, v85
	v_cndmask_b32_e64 v33, 0, v33, s[36:37]
	v_add_u32_e32 v86, 9, v84
	v_cmp_gt_u32_e64 s[36:37], s98, v86
	v_cndmask_b32_e64 v34, 0, v34, s[78:79]
	v_add_u32_e32 v87, 10, v84
	v_cmp_gt_u32_e64 s[78:79], s98, v87
	v_cndmask_b32_e64 v35, 0, v35, s[50:51]
	v_add_u32_e32 v88, 11, v84
	v_cmp_gt_u32_e64 s[50:51], s98, v88
	v_cndmask_b32_e64 v36, 0, v36, s[30:31]
	v_add_u32_e32 v85, 16, v84
	v_cmp_gt_u32_e64 s[30:31], s98, v85
	v_cndmask_b32_e64 v37, 0, v37, s[36:37]
	v_add_u32_e32 v86, 17, v84
	v_cmp_gt_u32_e64 s[36:37], s98, v86
	v_cndmask_b32_e64 v38, 0, v38, s[78:79]
	v_add_u32_e32 v87, 18, v84
	v_cmp_gt_u32_e64 s[78:79], s98, v87
	v_cndmask_b32_e64 v39, 0, v39, s[50:51]
	v_add_u32_e32 v88, 19, v84
	v_cmp_gt_u32_e64 s[50:51], s98, v88
	v_cndmask_b32_e64 v40, 0, v40, s[30:31]
	v_add_u32_e32 v85, 24, v84
	v_cmp_gt_u32_e64 s[30:31], s98, v85
	v_cndmask_b32_e64 v41, 0, v41, s[36:37]
	v_add_u32_e32 v86, 25, v84
	v_cmp_gt_u32_e64 s[36:37], s98, v86
	v_cndmask_b32_e64 v42, 0, v42, s[78:79]
	v_add_u32_e32 v87, 26, v84
	v_cmp_gt_u32_e64 s[78:79], s98, v87
	v_cndmask_b32_e64 v43, 0, v43, s[50:51]
	v_add_u32_e32 v88, 27, v84
	v_cmp_gt_u32_e64 s[50:51], s98, v88
	v_nop
	v_cndmask_b32_e64 v44, 0, v44, s[30:31]
	v_cndmask_b32_e64 v45, 0, v45, s[36:37]
	v_cndmask_b32_e64 v46, 0, v46, s[78:79]
	v_cndmask_b32_e64 v47, 0, v47, s[50:51]
	v_cvt_pk_bf16_f32 v64, v32, v33
	v_cvt_pk_bf16_f32 v65, v34, v35
	v_cvt_pk_bf16_f32 v66, v36, v37
	v_cvt_pk_bf16_f32 v67, v38, v39
	v_cvt_pk_bf16_f32 v68, v40, v41
	v_cvt_pk_bf16_f32 v69, v42, v43
	v_cvt_pk_bf16_f32 v70, v44, v45
	v_cvt_pk_bf16_f32 v71, v46, v47
	v_pk_add_f32 v[232:233], v[232:233], v[32:33]
	v_pk_add_f32 v[232:233], v[232:233], v[34:35]
	v_pk_add_f32 v[232:233], v[232:233], v[36:37]
	v_pk_add_f32 v[232:233], v[232:233], v[38:39]
	v_pk_add_f32 v[232:233], v[232:233], v[40:41]
	v_pk_add_f32 v[232:233], v[232:233], v[42:43]
	v_pk_add_f32 v[232:233], v[232:233], v[44:45]
	v_pk_add_f32 v[232:233], v[232:233], v[46:47]
	v_add_u32_e32 v115, 952, v115
	ds_read2_b32 v[32:33], v115 offset0:0 offset1:1
	ds_read2_b32 v[34:35], v115 offset0:2 offset1:3
	ds_read2_b32 v[36:37], v115 offset0:8 offset1:9
	ds_read2_b32 v[38:39], v115 offset0:10 offset1:11
	ds_read2_b32 v[40:41], v115 offset0:17 offset1:18
	ds_read2_b32 v[42:43], v115 offset0:19 offset1:20
	ds_read2_b32 v[44:45], v115 offset0:25 offset1:26
	ds_read2_b32 v[46:47], v115 offset0:27 offset1:28
	v_mfma_f32_32x32x16_bf16 v[0:15], v[64:67], v[72:75], v[0:15]
	v_mfma_f32_32x32x16_bf16 v[16:31], v[64:67], v[76:79], v[16:31]
	v_mfma_f32_32x32x16_bf16 v[0:15], v[68:71], v[220:223], v[0:15]
	v_mfma_f32_32x32x16_bf16 v[16:31], v[68:71], v[224:227], v[16:31]
	s_add_i32 s90, s67, 416
	v_add_u32_e32 v80, s90, v235
	v_add_u32_e32 v83, s90, v236
	v_add_u32_e32 v99, s90, v237
	v_add_u32_e32 v253, s90, v238
	v_add_u32_e32 v254, s90, v100
	v_add_u32_e32 v255, s90, v149
	v_med3_i32 v80, v80, 0, s99
	v_med3_i32 v83, v83, 0, s99
	v_med3_i32 v99, v99, 0, s99
	v_med3_i32 v253, v253, 0, s99
	v_med3_i32 v254, v254, 0, s99
	v_med3_i32 v255, v255, 0, s99
	v_mad_u32_u24 v80, v80, s100, v252
	v_mad_u32_u24 v83, v83, s100, v252
	v_mad_u32_u24 v99, v99, s100, v252
	v_mad_u32_u24 v253, v253, s100, v252
	v_mad_u32_u24 v254, v254, s100, v153
	v_mad_u32_u24 v255, v255, s100, v153
	global_load_dwordx4 v[156:159], v80, s[82:83]
	global_load_dwordx4 v[160:163], v83, s[82:83]
	global_load_dwordx4 v[164:167], v99, s[82:83]
	global_load_dwordx4 v[168:171], v253, s[82:83]
	global_load_dwordx4 v[172:175], v254, s[82:83] offset:768
	global_load_dwordx4 v[176:179], v255, s[82:83] offset:768
	global_load_dwordx4 v[180:183], v254, s[82:83] offset:832
	global_load_dwordx4 v[184:187], v255, s[82:83] offset:832
	ds_read_b64_tr_b16 v[72:73], v231
	ds_read_b64_tr_b16 v[74:75], v231 offset:512
	ds_read_b64_tr_b16 v[76:77], v231 offset:2048
	ds_read_b64_tr_b16 v[78:79], v231 offset:2560
	ds_read_b64_tr_b16 v[220:221], v231 offset:1024
	ds_read_b64_tr_b16 v[222:223], v231 offset:1536
	ds_read_b64_tr_b16 v[224:225], v231 offset:3072
	ds_read_b64_tr_b16 v[226:227], v231 offset:3584
	s_waitcnt vmcnt(8)
	ds_write_b128 v247, v[116:119]
	ds_write_b128 v247, v[120:123] offset:1024
	ds_write_b128 v247, v[124:127] offset:2048
	ds_write_b128 v247, v[128:131] offset:3072
	ds_read_b128 v[116:119], v248
	ds_read_b128 v[120:123], v249
	ds_read_b128 v[124:127], v250
	ds_read_b128 v[128:131], v251
	ds_write_b128 v112, v[132:135]
	ds_write_b128 v112, v[136:139] offset:1024
	ds_write_b128 v112, v[140:143] offset:2048
	ds_write_b128 v112, v[144:147] offset:3072
	s_waitcnt lgkmcnt(4)
	v_mfma_f32_32x32x16_bf16 v[32:47], v[116:119], v[48:51], v[32:47]
	v_exp_f32_e32 v188, v188
	v_exp_f32_e32 v189, v189
	v_exp_f32_e32 v190, v190
	v_exp_f32_e32 v191, v191
	v_mfma_f32_32x32x16_bf16 v[32:47], v[120:123], v[52:55], v[32:47]
	v_exp_f32_e32 v192, v192
	v_exp_f32_e32 v193, v193
	v_exp_f32_e32 v194, v194
	v_exp_f32_e32 v195, v195
	v_mfma_f32_32x32x16_bf16 v[32:47], v[124:127], v[56:59], v[32:47]
	v_exp_f32_e32 v196, v196
	v_exp_f32_e32 v197, v197
	v_exp_f32_e32 v198, v198
	v_exp_f32_e32 v199, v199
	v_mfma_f32_32x32x16_bf16 v[32:47], v[128:131], v[60:63], v[32:47]
	v_exp_f32_e32 v200, v200
	v_exp_f32_e32 v201, v201
	v_exp_f32_e32 v202, v202
	v_exp_f32_e32 v203, v203
	s_add_i32 s90, s67, 352
	v_add_u32_e32 v84, s90, v107
	v_add_u32_e32 v85, 0, v84
	v_add_u32_e32 v86, 1, v84
	v_add_u32_e32 v87, 2, v84
	v_add_u32_e32 v88, 3, v84
	v_cmp_gt_u32_e64 s[30:31], s98, v85
	v_cmp_gt_u32_e64 s[36:37], s98, v86
	v_cmp_gt_u32_e64 s[78:79], s98, v87
	v_cmp_gt_u32_e64 s[50:51], s98, v88
	v_cndmask_b32_e64 v188, 0, v188, s[30:31]
	v_add_u32_e32 v85, 8, v84
	v_cmp_gt_u32_e64 s[30:31], s98, v85
	v_cndmask_b32_e64 v189, 0, v189, s[36:37]
	v_add_u32_e32 v86, 9, v84
	v_cmp_gt_u32_e64 s[36:37], s98, v86
	v_cndmask_b32_e64 v190, 0, v190, s[78:79]
	v_add_u32_e32 v87, 10, v84
	v_cmp_gt_u32_e64 s[78:79], s98, v87
	v_cndmask_b32_e64 v191, 0, v191, s[50:51]
	v_add_u32_e32 v88, 11, v84
	v_cmp_gt_u32_e64 s[50:51], s98, v88
	v_cndmask_b32_e64 v192, 0, v192, s[30:31]
	v_add_u32_e32 v85, 16, v84
	v_cmp_gt_u32_e64 s[30:31], s98, v85
	v_cndmask_b32_e64 v193, 0, v193, s[36:37]
	v_add_u32_e32 v86, 17, v84
	v_cmp_gt_u32_e64 s[36:37], s98, v86
	v_cndmask_b32_e64 v194, 0, v194, s[78:79]
	v_add_u32_e32 v87, 18, v84
	v_cmp_gt_u32_e64 s[78:79], s98, v87
	v_cndmask_b32_e64 v195, 0, v195, s[50:51]
	v_add_u32_e32 v88, 19, v84
	v_cmp_gt_u32_e64 s[50:51], s98, v88
	v_cndmask_b32_e64 v196, 0, v196, s[30:31]
	v_add_u32_e32 v85, 24, v84
	v_cmp_gt_u32_e64 s[30:31], s98, v85
	v_cndmask_b32_e64 v197, 0, v197, s[36:37]
	v_add_u32_e32 v86, 25, v84
	v_cmp_gt_u32_e64 s[36:37], s98, v86
	v_cndmask_b32_e64 v198, 0, v198, s[78:79]
	v_add_u32_e32 v87, 26, v84
	v_cmp_gt_u32_e64 s[78:79], s98, v87
	v_cndmask_b32_e64 v199, 0, v199, s[50:51]
	v_add_u32_e32 v88, 27, v84
	v_cmp_gt_u32_e64 s[50:51], s98, v88
	v_nop
	v_cndmask_b32_e64 v200, 0, v200, s[30:31]
	v_cndmask_b32_e64 v201, 0, v201, s[36:37]
	v_cndmask_b32_e64 v202, 0, v202, s[78:79]
	v_cndmask_b32_e64 v203, 0, v203, s[50:51]
	v_cvt_pk_bf16_f32 v64, v188, v189
	v_cvt_pk_bf16_f32 v65, v190, v191
	v_cvt_pk_bf16_f32 v66, v192, v193
	v_cvt_pk_bf16_f32 v67, v194, v195
	v_cvt_pk_bf16_f32 v68, v196, v197
	v_cvt_pk_bf16_f32 v69, v198, v199
	v_cvt_pk_bf16_f32 v70, v200, v201
	v_cvt_pk_bf16_f32 v71, v202, v203
	v_pk_add_f32 v[232:233], v[232:233], v[188:189]
	v_pk_add_f32 v[232:233], v[232:233], v[190:191]
	v_pk_add_f32 v[232:233], v[232:233], v[192:193]
	v_pk_add_f32 v[232:233], v[232:233], v[194:195]
	v_pk_add_f32 v[232:233], v[232:233], v[196:197]
	v_pk_add_f32 v[232:233], v[232:233], v[198:199]
	v_pk_add_f32 v[232:233], v[232:233], v[200:201]
	v_pk_add_f32 v[232:233], v[232:233], v[202:203]
	ds_read2_b32 v[188:189], v115 offset0:34 offset1:35
	ds_read2_b32 v[190:191], v115 offset0:36 offset1:37
	ds_read2_b32 v[192:193], v115 offset0:42 offset1:43
	ds_read2_b32 v[194:195], v115 offset0:44 offset1:45
	ds_read2_b32 v[196:197], v115 offset0:51 offset1:52
	ds_read2_b32 v[198:199], v115 offset0:53 offset1:54
	ds_read2_b32 v[200:201], v115 offset0:59 offset1:60
	ds_read2_b32 v[202:203], v115 offset0:61 offset1:62
	v_mfma_f32_32x32x16_bf16 v[0:15], v[64:67], v[72:75], v[0:15]
	v_mfma_f32_32x32x16_bf16 v[16:31], v[64:67], v[76:79], v[16:31]
	v_mfma_f32_32x32x16_bf16 v[0:15], v[68:71], v[220:223], v[0:15]
	v_mfma_f32_32x32x16_bf16 v[16:31], v[68:71], v[224:227], v[16:31]
	s_add_i32 s90, s67, 448
	v_add_u32_e32 v80, s90, v235
	v_add_u32_e32 v83, s90, v236
	v_add_u32_e32 v99, s90, v237
	v_add_u32_e32 v253, s90, v238
	v_add_u32_e32 v254, s90, v100
	v_add_u32_e32 v255, s90, v149
	v_med3_i32 v80, v80, 0, s99
	v_med3_i32 v83, v83, 0, s99
	v_med3_i32 v99, v99, 0, s99
	v_med3_i32 v253, v253, 0, s99
	v_med3_i32 v254, v254, 0, s99
	v_med3_i32 v255, v255, 0, s99
	v_mad_u32_u24 v80, v80, s100, v252
	v_mad_u32_u24 v83, v83, s100, v252
	v_mad_u32_u24 v99, v99, s100, v252
	v_mad_u32_u24 v253, v253, s100, v252
	v_mad_u32_u24 v254, v254, s100, v153
	v_mad_u32_u24 v255, v255, s100, v153
	global_load_dwordx4 v[116:119], v80, s[82:83]
	global_load_dwordx4 v[120:123], v83, s[82:83]
	global_load_dwordx4 v[124:127], v99, s[82:83]
	global_load_dwordx4 v[128:131], v253, s[82:83]
	global_load_dwordx4 v[132:135], v254, s[82:83] offset:768
	global_load_dwordx4 v[136:139], v255, s[82:83] offset:768
	global_load_dwordx4 v[140:143], v254, s[82:83] offset:832
	global_load_dwordx4 v[144:147], v255, s[82:83] offset:832
	ds_read_b64_tr_b16 v[72:73], v231
	ds_read_b64_tr_b16 v[74:75], v231 offset:512
	ds_read_b64_tr_b16 v[76:77], v231 offset:2048
	ds_read_b64_tr_b16 v[78:79], v231 offset:2560
	ds_read_b64_tr_b16 v[220:221], v231 offset:1024
	ds_read_b64_tr_b16 v[222:223], v231 offset:1536
	ds_read_b64_tr_b16 v[224:225], v231 offset:3072
	ds_read_b64_tr_b16 v[226:227], v231 offset:3584
	s_waitcnt vmcnt(8)
	ds_write_b128 v247, v[156:159]
	ds_write_b128 v247, v[160:163] offset:1024
	ds_write_b128 v247, v[164:167] offset:2048
	ds_write_b128 v247, v[168:171] offset:3072
	ds_read_b128 v[156:159], v248
	ds_read_b128 v[160:163], v249
	ds_read_b128 v[164:167], v250
	ds_read_b128 v[168:171], v251
	ds_write_b128 v112, v[172:175]
	ds_write_b128 v112, v[176:179] offset:1024
	ds_write_b128 v112, v[180:183] offset:2048
	ds_write_b128 v112, v[184:187] offset:3072
	s_waitcnt lgkmcnt(4)
	v_mfma_f32_32x32x16_bf16 v[188:203], v[156:159], v[48:51], v[188:203]
	v_exp_f32_e32 v32, v32
	v_exp_f32_e32 v33, v33
	v_exp_f32_e32 v34, v34
	v_exp_f32_e32 v35, v35
	v_mfma_f32_32x32x16_bf16 v[188:203], v[160:163], v[52:55], v[188:203]
	v_exp_f32_e32 v36, v36
	v_exp_f32_e32 v37, v37
	v_exp_f32_e32 v38, v38
	v_exp_f32_e32 v39, v39
	v_mfma_f32_32x32x16_bf16 v[188:203], v[164:167], v[56:59], v[188:203]
	v_exp_f32_e32 v40, v40
	v_exp_f32_e32 v41, v41
	v_exp_f32_e32 v42, v42
	v_exp_f32_e32 v43, v43
	v_mfma_f32_32x32x16_bf16 v[188:203], v[168:171], v[60:63], v[188:203]
	v_exp_f32_e32 v44, v44
	v_exp_f32_e32 v45, v45
	v_exp_f32_e32 v46, v46
	v_exp_f32_e32 v47, v47
	s_add_i32 s90, s67, 384
	v_add_u32_e32 v84, s90, v107
	v_add_u32_e32 v85, 0, v84
	v_add_u32_e32 v86, 1, v84
	v_add_u32_e32 v87, 2, v84
	v_add_u32_e32 v88, 3, v84
	v_cmp_gt_u32_e64 s[30:31], s98, v85
	v_cmp_gt_u32_e64 s[36:37], s98, v86
	v_cmp_gt_u32_e64 s[78:79], s98, v87
	v_cmp_gt_u32_e64 s[50:51], s98, v88
	v_cndmask_b32_e64 v32, 0, v32, s[30:31]
	v_add_u32_e32 v85, 8, v84
	v_cmp_gt_u32_e64 s[30:31], s98, v85
	v_cndmask_b32_e64 v33, 0, v33, s[36:37]
	v_add_u32_e32 v86, 9, v84
	v_cmp_gt_u32_e64 s[36:37], s98, v86
	v_cndmask_b32_e64 v34, 0, v34, s[78:79]
	v_add_u32_e32 v87, 10, v84
	v_cmp_gt_u32_e64 s[78:79], s98, v87
	v_cndmask_b32_e64 v35, 0, v35, s[50:51]
	v_add_u32_e32 v88, 11, v84
	v_cmp_gt_u32_e64 s[50:51], s98, v88
	v_cndmask_b32_e64 v36, 0, v36, s[30:31]
	v_add_u32_e32 v85, 16, v84
	v_cmp_gt_u32_e64 s[30:31], s98, v85
	v_cndmask_b32_e64 v37, 0, v37, s[36:37]
	v_add_u32_e32 v86, 17, v84
	v_cmp_gt_u32_e64 s[36:37], s98, v86
	v_cndmask_b32_e64 v38, 0, v38, s[78:79]
	v_add_u32_e32 v87, 18, v84
	v_cmp_gt_u32_e64 s[78:79], s98, v87
	v_cndmask_b32_e64 v39, 0, v39, s[50:51]
	v_add_u32_e32 v88, 19, v84
	v_cmp_gt_u32_e64 s[50:51], s98, v88
	v_cndmask_b32_e64 v40, 0, v40, s[30:31]
	v_add_u32_e32 v85, 24, v84
	v_cmp_gt_u32_e64 s[30:31], s98, v85
	v_cndmask_b32_e64 v41, 0, v41, s[36:37]
	v_add_u32_e32 v86, 25, v84
	v_cmp_gt_u32_e64 s[36:37], s98, v86
	v_cndmask_b32_e64 v42, 0, v42, s[78:79]
	v_add_u32_e32 v87, 26, v84
	v_cmp_gt_u32_e64 s[78:79], s98, v87
	v_cndmask_b32_e64 v43, 0, v43, s[50:51]
	v_add_u32_e32 v88, 27, v84
	v_cmp_gt_u32_e64 s[50:51], s98, v88
	v_nop
	v_cndmask_b32_e64 v44, 0, v44, s[30:31]
	v_cndmask_b32_e64 v45, 0, v45, s[36:37]
	v_cndmask_b32_e64 v46, 0, v46, s[78:79]
	v_cndmask_b32_e64 v47, 0, v47, s[50:51]
	v_cvt_pk_bf16_f32 v64, v32, v33
	v_cvt_pk_bf16_f32 v65, v34, v35
	v_cvt_pk_bf16_f32 v66, v36, v37
	v_cvt_pk_bf16_f32 v67, v38, v39
	v_cvt_pk_bf16_f32 v68, v40, v41
	v_cvt_pk_bf16_f32 v69, v42, v43
	v_cvt_pk_bf16_f32 v70, v44, v45
	v_cvt_pk_bf16_f32 v71, v46, v47
	v_pk_add_f32 v[232:233], v[232:233], v[32:33]
	v_pk_add_f32 v[232:233], v[232:233], v[34:35]
	v_pk_add_f32 v[232:233], v[232:233], v[36:37]
	v_pk_add_f32 v[232:233], v[232:233], v[38:39]
	v_pk_add_f32 v[232:233], v[232:233], v[40:41]
	v_pk_add_f32 v[232:233], v[232:233], v[42:43]
	v_pk_add_f32 v[232:233], v[232:233], v[44:45]
	v_pk_add_f32 v[232:233], v[232:233], v[46:47]
	ds_read2_b32 v[32:33], v115 offset0:68 offset1:69
	ds_read2_b32 v[34:35], v115 offset0:70 offset1:71
	ds_read2_b32 v[36:37], v115 offset0:76 offset1:77
	ds_read2_b32 v[38:39], v115 offset0:78 offset1:79
	ds_read2_b32 v[40:41], v115 offset0:85 offset1:86
	ds_read2_b32 v[42:43], v115 offset0:87 offset1:88
	ds_read2_b32 v[44:45], v115 offset0:93 offset1:94
	ds_read2_b32 v[46:47], v115 offset0:95 offset1:96
	v_mfma_f32_32x32x16_bf16 v[0:15], v[64:67], v[72:75], v[0:15]
	v_mfma_f32_32x32x16_bf16 v[16:31], v[64:67], v[76:79], v[16:31]
	v_mfma_f32_32x32x16_bf16 v[0:15], v[68:71], v[220:223], v[0:15]
	v_mfma_f32_32x32x16_bf16 v[16:31], v[68:71], v[224:227], v[16:31]
	s_add_i32 s90, s67, 480
	v_add_u32_e32 v80, s90, v235
	v_add_u32_e32 v83, s90, v236
	v_add_u32_e32 v99, s90, v237
	v_add_u32_e32 v253, s90, v238
	v_add_u32_e32 v254, s90, v100
	v_add_u32_e32 v255, s90, v149
	v_med3_i32 v80, v80, 0, s99
	v_med3_i32 v83, v83, 0, s99
	v_med3_i32 v99, v99, 0, s99
	v_med3_i32 v253, v253, 0, s99
	v_med3_i32 v254, v254, 0, s99
	v_med3_i32 v255, v255, 0, s99
	v_mad_u32_u24 v80, v80, s100, v252
	v_mad_u32_u24 v83, v83, s100, v252
	v_mad_u32_u24 v99, v99, s100, v252
	v_mad_u32_u24 v253, v253, s100, v252
	v_mad_u32_u24 v254, v254, s100, v153
	v_mad_u32_u24 v255, v255, s100, v153
	global_load_dwordx4 v[156:159], v80, s[82:83]
	global_load_dwordx4 v[160:163], v83, s[82:83]
	global_load_dwordx4 v[164:167], v99, s[82:83]
	global_load_dwordx4 v[168:171], v253, s[82:83]
	global_load_dwordx4 v[172:175], v254, s[82:83] offset:768
	global_load_dwordx4 v[176:179], v255, s[82:83] offset:768
	global_load_dwordx4 v[180:183], v254, s[82:83] offset:832
	global_load_dwordx4 v[184:187], v255, s[82:83] offset:832
	ds_read_b64_tr_b16 v[72:73], v231
	ds_read_b64_tr_b16 v[74:75], v231 offset:512
	ds_read_b64_tr_b16 v[76:77], v231 offset:2048
	ds_read_b64_tr_b16 v[78:79], v231 offset:2560
	ds_read_b64_tr_b16 v[220:221], v231 offset:1024
	ds_read_b64_tr_b16 v[222:223], v231 offset:1536
	ds_read_b64_tr_b16 v[224:225], v231 offset:3072
	ds_read_b64_tr_b16 v[226:227], v231 offset:3584
	s_waitcnt vmcnt(8)
	ds_write_b128 v247, v[116:119]
	ds_write_b128 v247, v[120:123] offset:1024
	ds_write_b128 v247, v[124:127] offset:2048
	ds_write_b128 v247, v[128:131] offset:3072
	ds_read_b128 v[116:119], v248
	ds_read_b128 v[120:123], v249
	ds_read_b128 v[124:127], v250
	ds_read_b128 v[128:131], v251
	ds_write_b128 v112, v[132:135]
	ds_write_b128 v112, v[136:139] offset:1024
	ds_write_b128 v112, v[140:143] offset:2048
	ds_write_b128 v112, v[144:147] offset:3072
	s_waitcnt lgkmcnt(4)
	v_mfma_f32_32x32x16_bf16 v[32:47], v[116:119], v[48:51], v[32:47]
	v_exp_f32_e32 v188, v188
	v_exp_f32_e32 v189, v189
	v_exp_f32_e32 v190, v190
	v_exp_f32_e32 v191, v191
	v_mfma_f32_32x32x16_bf16 v[32:47], v[120:123], v[52:55], v[32:47]
	v_exp_f32_e32 v192, v192
	v_exp_f32_e32 v193, v193
	v_exp_f32_e32 v194, v194
	v_exp_f32_e32 v195, v195
	v_mfma_f32_32x32x16_bf16 v[32:47], v[124:127], v[56:59], v[32:47]
	v_exp_f32_e32 v196, v196
	v_exp_f32_e32 v197, v197
	v_exp_f32_e32 v198, v198
	v_exp_f32_e32 v199, v199
	v_mfma_f32_32x32x16_bf16 v[32:47], v[128:131], v[60:63], v[32:47]
	v_exp_f32_e32 v200, v200
	v_exp_f32_e32 v201, v201
	v_exp_f32_e32 v202, v202
	v_exp_f32_e32 v203, v203
	s_add_i32 s90, s67, 416
	v_add_u32_e32 v84, s90, v107
	v_add_u32_e32 v85, 0, v84
	v_add_u32_e32 v86, 1, v84
	v_add_u32_e32 v87, 2, v84
	v_add_u32_e32 v88, 3, v84
	v_cmp_gt_u32_e64 s[30:31], s98, v85
	v_cmp_gt_u32_e64 s[36:37], s98, v86
	v_cmp_gt_u32_e64 s[78:79], s98, v87
	v_cmp_gt_u32_e64 s[50:51], s98, v88
	v_cndmask_b32_e64 v188, 0, v188, s[30:31]
	v_add_u32_e32 v85, 8, v84
	v_cmp_gt_u32_e64 s[30:31], s98, v85
	v_cndmask_b32_e64 v189, 0, v189, s[36:37]
	v_add_u32_e32 v86, 9, v84
	v_cmp_gt_u32_e64 s[36:37], s98, v86
	v_cndmask_b32_e64 v190, 0, v190, s[78:79]
	v_add_u32_e32 v87, 10, v84
	v_cmp_gt_u32_e64 s[78:79], s98, v87
	v_cndmask_b32_e64 v191, 0, v191, s[50:51]
	v_add_u32_e32 v88, 11, v84
	v_cmp_gt_u32_e64 s[50:51], s98, v88
	v_cndmask_b32_e64 v192, 0, v192, s[30:31]
	v_add_u32_e32 v85, 16, v84
	v_cmp_gt_u32_e64 s[30:31], s98, v85
	v_cndmask_b32_e64 v193, 0, v193, s[36:37]
	v_add_u32_e32 v86, 17, v84
	v_cmp_gt_u32_e64 s[36:37], s98, v86
	v_cndmask_b32_e64 v194, 0, v194, s[78:79]
	v_add_u32_e32 v87, 18, v84
	v_cmp_gt_u32_e64 s[78:79], s98, v87
	v_cndmask_b32_e64 v195, 0, v195, s[50:51]
	v_add_u32_e32 v88, 19, v84
	v_cmp_gt_u32_e64 s[50:51], s98, v88
	v_cndmask_b32_e64 v196, 0, v196, s[30:31]
	v_add_u32_e32 v85, 24, v84
	v_cmp_gt_u32_e64 s[30:31], s98, v85
	v_cndmask_b32_e64 v197, 0, v197, s[36:37]
	v_add_u32_e32 v86, 25, v84
	v_cmp_gt_u32_e64 s[36:37], s98, v86
	v_cndmask_b32_e64 v198, 0, v198, s[78:79]
	v_add_u32_e32 v87, 26, v84
	v_cmp_gt_u32_e64 s[78:79], s98, v87
	v_cndmask_b32_e64 v199, 0, v199, s[50:51]
	v_add_u32_e32 v88, 27, v84
	v_cmp_gt_u32_e64 s[50:51], s98, v88
	v_nop
	v_cndmask_b32_e64 v200, 0, v200, s[30:31]
	v_cndmask_b32_e64 v201, 0, v201, s[36:37]
	v_cndmask_b32_e64 v202, 0, v202, s[78:79]
	v_cndmask_b32_e64 v203, 0, v203, s[50:51]
	v_cvt_pk_bf16_f32 v64, v188, v189
	v_cvt_pk_bf16_f32 v65, v190, v191
	v_cvt_pk_bf16_f32 v66, v192, v193
	v_cvt_pk_bf16_f32 v67, v194, v195
	v_cvt_pk_bf16_f32 v68, v196, v197
	v_cvt_pk_bf16_f32 v69, v198, v199
	v_cvt_pk_bf16_f32 v70, v200, v201
	v_cvt_pk_bf16_f32 v71, v202, v203
	v_pk_add_f32 v[232:233], v[232:233], v[188:189]
	v_pk_add_f32 v[232:233], v[232:233], v[190:191]
	v_pk_add_f32 v[232:233], v[232:233], v[192:193]
	v_pk_add_f32 v[232:233], v[232:233], v[194:195]
	v_pk_add_f32 v[232:233], v[232:233], v[196:197]
	v_pk_add_f32 v[232:233], v[232:233], v[198:199]
	v_pk_add_f32 v[232:233], v[232:233], v[200:201]
	v_pk_add_f32 v[232:233], v[232:233], v[202:203]
	ds_read2_b32 v[188:189], v115 offset0:102 offset1:103
	ds_read2_b32 v[190:191], v115 offset0:104 offset1:105
	ds_read2_b32 v[192:193], v115 offset0:110 offset1:111
	ds_read2_b32 v[194:195], v115 offset0:112 offset1:113
	ds_read2_b32 v[196:197], v115 offset0:119 offset1:120
	ds_read2_b32 v[198:199], v115 offset0:121 offset1:122
	ds_read2_b32 v[200:201], v115 offset0:127 offset1:128
	ds_read2_b32 v[202:203], v115 offset0:129 offset1:130
	v_mfma_f32_32x32x16_bf16 v[0:15], v[64:67], v[72:75], v[0:15]
	v_mfma_f32_32x32x16_bf16 v[16:31], v[64:67], v[76:79], v[16:31]
	v_mfma_f32_32x32x16_bf16 v[0:15], v[68:71], v[220:223], v[0:15]
	v_mfma_f32_32x32x16_bf16 v[16:31], v[68:71], v[224:227], v[16:31]
	s_add_i32 s90, s67, 512
	v_add_u32_e32 v80, s90, v235
	v_add_u32_e32 v83, s90, v236
	v_add_u32_e32 v99, s90, v237
	v_add_u32_e32 v253, s90, v238
	v_add_u32_e32 v254, s90, v100
	v_add_u32_e32 v255, s90, v149
	v_med3_i32 v80, v80, 0, s99
	v_med3_i32 v83, v83, 0, s99
	v_med3_i32 v99, v99, 0, s99
	v_med3_i32 v253, v253, 0, s99
	v_med3_i32 v254, v254, 0, s99
	v_med3_i32 v255, v255, 0, s99
	v_mad_u32_u24 v80, v80, s100, v252
	v_mad_u32_u24 v83, v83, s100, v252
	v_mad_u32_u24 v99, v99, s100, v252
	v_mad_u32_u24 v253, v253, s100, v252
	v_mad_u32_u24 v254, v254, s100, v153
	v_mad_u32_u24 v255, v255, s100, v153
	global_load_dwordx4 v[116:119], v80, s[82:83]
	global_load_dwordx4 v[120:123], v83, s[82:83]
	global_load_dwordx4 v[124:127], v99, s[82:83]
	global_load_dwordx4 v[128:131], v253, s[82:83]
	global_load_dwordx4 v[132:135], v254, s[82:83] offset:768
	global_load_dwordx4 v[136:139], v255, s[82:83] offset:768
	global_load_dwordx4 v[140:143], v254, s[82:83] offset:832
	global_load_dwordx4 v[144:147], v255, s[82:83] offset:832
	ds_read_b64_tr_b16 v[72:73], v231
	ds_read_b64_tr_b16 v[74:75], v231 offset:512
	ds_read_b64_tr_b16 v[76:77], v231 offset:2048
	ds_read_b64_tr_b16 v[78:79], v231 offset:2560
	ds_read_b64_tr_b16 v[220:221], v231 offset:1024
	ds_read_b64_tr_b16 v[222:223], v231 offset:1536
	ds_read_b64_tr_b16 v[224:225], v231 offset:3072
	ds_read_b64_tr_b16 v[226:227], v231 offset:3584
	s_waitcnt vmcnt(8)
	ds_write_b128 v247, v[156:159]
	ds_write_b128 v247, v[160:163] offset:1024
	ds_write_b128 v247, v[164:167] offset:2048
	ds_write_b128 v247, v[168:171] offset:3072
	ds_read_b128 v[156:159], v248
	ds_read_b128 v[160:163], v249
	ds_read_b128 v[164:167], v250
	ds_read_b128 v[168:171], v251
	ds_write_b128 v112, v[172:175]
	ds_write_b128 v112, v[176:179] offset:1024
	ds_write_b128 v112, v[180:183] offset:2048
	ds_write_b128 v112, v[184:187] offset:3072
	s_waitcnt lgkmcnt(4)
	v_mfma_f32_32x32x16_bf16 v[188:203], v[156:159], v[48:51], v[188:203]
	v_exp_f32_e32 v32, v32
	v_exp_f32_e32 v33, v33
	v_exp_f32_e32 v34, v34
	v_exp_f32_e32 v35, v35
	v_mfma_f32_32x32x16_bf16 v[188:203], v[160:163], v[52:55], v[188:203]
	v_exp_f32_e32 v36, v36
	v_exp_f32_e32 v37, v37
	v_exp_f32_e32 v38, v38
	v_exp_f32_e32 v39, v39
	v_mfma_f32_32x32x16_bf16 v[188:203], v[164:167], v[56:59], v[188:203]
	v_exp_f32_e32 v40, v40
	v_exp_f32_e32 v41, v41
	v_exp_f32_e32 v42, v42
	v_exp_f32_e32 v43, v43
	v_mfma_f32_32x32x16_bf16 v[188:203], v[168:171], v[60:63], v[188:203]
	v_exp_f32_e32 v44, v44
	v_exp_f32_e32 v45, v45
	v_exp_f32_e32 v46, v46
	v_exp_f32_e32 v47, v47
	s_add_i32 s90, s67, 448
	v_add_u32_e32 v84, s90, v107
	v_add_u32_e32 v85, 0, v84
	v_add_u32_e32 v86, 1, v84
	v_add_u32_e32 v87, 2, v84
	v_add_u32_e32 v88, 3, v84
	v_cmp_gt_u32_e64 s[30:31], s98, v85
	v_cmp_gt_u32_e64 s[36:37], s98, v86
	v_cmp_gt_u32_e64 s[78:79], s98, v87
	v_cmp_gt_u32_e64 s[50:51], s98, v88
	v_cndmask_b32_e64 v32, 0, v32, s[30:31]
	v_add_u32_e32 v85, 8, v84
	v_cmp_gt_u32_e64 s[30:31], s98, v85
	v_cndmask_b32_e64 v33, 0, v33, s[36:37]
	v_add_u32_e32 v86, 9, v84
	v_cmp_gt_u32_e64 s[36:37], s98, v86
	v_cndmask_b32_e64 v34, 0, v34, s[78:79]
	v_add_u32_e32 v87, 10, v84
	v_cmp_gt_u32_e64 s[78:79], s98, v87
	v_cndmask_b32_e64 v35, 0, v35, s[50:51]
	v_add_u32_e32 v88, 11, v84
	v_cmp_gt_u32_e64 s[50:51], s98, v88
	v_cndmask_b32_e64 v36, 0, v36, s[30:31]
	v_add_u32_e32 v85, 16, v84
	v_cmp_gt_u32_e64 s[30:31], s98, v85
	v_cndmask_b32_e64 v37, 0, v37, s[36:37]
	v_add_u32_e32 v86, 17, v84
	v_cmp_gt_u32_e64 s[36:37], s98, v86
	v_cndmask_b32_e64 v38, 0, v38, s[78:79]
	v_add_u32_e32 v87, 18, v84
	v_cmp_gt_u32_e64 s[78:79], s98, v87
	v_cndmask_b32_e64 v39, 0, v39, s[50:51]
	v_add_u32_e32 v88, 19, v84
	v_cmp_gt_u32_e64 s[50:51], s98, v88
	v_cndmask_b32_e64 v40, 0, v40, s[30:31]
	v_add_u32_e32 v85, 24, v84
	v_cmp_gt_u32_e64 s[30:31], s98, v85
	v_cndmask_b32_e64 v41, 0, v41, s[36:37]
	v_add_u32_e32 v86, 25, v84
	v_cmp_gt_u32_e64 s[36:37], s98, v86
	v_cndmask_b32_e64 v42, 0, v42, s[78:79]
	v_add_u32_e32 v87, 26, v84
	v_cmp_gt_u32_e64 s[78:79], s98, v87
	v_cndmask_b32_e64 v43, 0, v43, s[50:51]
	v_add_u32_e32 v88, 27, v84
	v_cmp_gt_u32_e64 s[50:51], s98, v88
	v_nop
	v_cndmask_b32_e64 v44, 0, v44, s[30:31]
	v_cndmask_b32_e64 v45, 0, v45, s[36:37]
	v_cndmask_b32_e64 v46, 0, v46, s[78:79]
	v_cndmask_b32_e64 v47, 0, v47, s[50:51]
	v_cvt_pk_bf16_f32 v64, v32, v33
	v_cvt_pk_bf16_f32 v65, v34, v35
	v_cvt_pk_bf16_f32 v66, v36, v37
	v_cvt_pk_bf16_f32 v67, v38, v39
	v_cvt_pk_bf16_f32 v68, v40, v41
	v_cvt_pk_bf16_f32 v69, v42, v43
	v_cvt_pk_bf16_f32 v70, v44, v45
	v_cvt_pk_bf16_f32 v71, v46, v47
	v_pk_add_f32 v[232:233], v[232:233], v[32:33]
	v_pk_add_f32 v[232:233], v[232:233], v[34:35]
	v_pk_add_f32 v[232:233], v[232:233], v[36:37]
	v_pk_add_f32 v[232:233], v[232:233], v[38:39]
	v_pk_add_f32 v[232:233], v[232:233], v[40:41]
	v_pk_add_f32 v[232:233], v[232:233], v[42:43]
	v_pk_add_f32 v[232:233], v[232:233], v[44:45]
	v_pk_add_f32 v[232:233], v[232:233], v[46:47]
	ds_read2_b32 v[32:33], v115 offset0:136 offset1:137
	ds_read2_b32 v[34:35], v115 offset0:138 offset1:139
	ds_read2_b32 v[36:37], v115 offset0:144 offset1:145
	ds_read2_b32 v[38:39], v115 offset0:146 offset1:147
	ds_read2_b32 v[40:41], v115 offset0:153 offset1:154
	ds_read2_b32 v[42:43], v115 offset0:155 offset1:156
	ds_read2_b32 v[44:45], v115 offset0:161 offset1:162
	ds_read2_b32 v[46:47], v115 offset0:163 offset1:164
	v_mfma_f32_32x32x16_bf16 v[0:15], v[64:67], v[72:75], v[0:15]
	v_mfma_f32_32x32x16_bf16 v[16:31], v[64:67], v[76:79], v[16:31]
	v_mfma_f32_32x32x16_bf16 v[0:15], v[68:71], v[220:223], v[0:15]
	v_mfma_f32_32x32x16_bf16 v[16:31], v[68:71], v[224:227], v[16:31]
	s_add_i32 s90, s67, 544
	v_add_u32_e32 v80, s90, v235
	v_add_u32_e32 v83, s90, v236
	v_add_u32_e32 v99, s90, v237
	v_add_u32_e32 v253, s90, v238
	v_add_u32_e32 v254, s90, v100
	v_add_u32_e32 v255, s90, v149
	v_med3_i32 v80, v80, 0, s99
	v_med3_i32 v83, v83, 0, s99
	v_med3_i32 v99, v99, 0, s99
	v_med3_i32 v253, v253, 0, s99
	v_med3_i32 v254, v254, 0, s99
	v_med3_i32 v255, v255, 0, s99
	v_mad_u32_u24 v80, v80, s100, v252
	v_mad_u32_u24 v83, v83, s100, v252
	v_mad_u32_u24 v99, v99, s100, v252
	v_mad_u32_u24 v253, v253, s100, v252
	v_mad_u32_u24 v254, v254, s100, v153
	v_mad_u32_u24 v255, v255, s100, v153
	global_load_dwordx4 v[156:159], v80, s[82:83]
	global_load_dwordx4 v[160:163], v83, s[82:83]
	global_load_dwordx4 v[164:167], v99, s[82:83]
	global_load_dwordx4 v[168:171], v253, s[82:83]
	global_load_dwordx4 v[172:175], v254, s[82:83] offset:768
	global_load_dwordx4 v[176:179], v255, s[82:83] offset:768
	global_load_dwordx4 v[180:183], v254, s[82:83] offset:832
	global_load_dwordx4 v[184:187], v255, s[82:83] offset:832
	ds_read_b64_tr_b16 v[72:73], v231
	ds_read_b64_tr_b16 v[74:75], v231 offset:512
	ds_read_b64_tr_b16 v[76:77], v231 offset:2048
	ds_read_b64_tr_b16 v[78:79], v231 offset:2560
	ds_read_b64_tr_b16 v[220:221], v231 offset:1024
	ds_read_b64_tr_b16 v[222:223], v231 offset:1536
	ds_read_b64_tr_b16 v[224:225], v231 offset:3072
	ds_read_b64_tr_b16 v[226:227], v231 offset:3584
	s_waitcnt vmcnt(8)
	ds_write_b128 v247, v[116:119]
	ds_write_b128 v247, v[120:123] offset:1024
	ds_write_b128 v247, v[124:127] offset:2048
	ds_write_b128 v247, v[128:131] offset:3072
	ds_read_b128 v[116:119], v248
	ds_read_b128 v[120:123], v249
	ds_read_b128 v[124:127], v250
	ds_read_b128 v[128:131], v251
	ds_write_b128 v112, v[132:135]
	ds_write_b128 v112, v[136:139] offset:1024
	ds_write_b128 v112, v[140:143] offset:2048
	ds_write_b128 v112, v[144:147] offset:3072
	s_waitcnt lgkmcnt(4)
	v_mfma_f32_32x32x16_bf16 v[32:47], v[116:119], v[48:51], v[32:47]
	v_exp_f32_e32 v188, v188
	v_exp_f32_e32 v189, v189
	v_exp_f32_e32 v190, v190
	v_exp_f32_e32 v191, v191
	v_mfma_f32_32x32x16_bf16 v[32:47], v[120:123], v[52:55], v[32:47]
	v_exp_f32_e32 v192, v192
	v_exp_f32_e32 v193, v193
	v_exp_f32_e32 v194, v194
	v_exp_f32_e32 v195, v195
	v_mfma_f32_32x32x16_bf16 v[32:47], v[124:127], v[56:59], v[32:47]
	v_exp_f32_e32 v196, v196
	v_exp_f32_e32 v197, v197
	v_exp_f32_e32 v198, v198
	v_exp_f32_e32 v199, v199
	v_mfma_f32_32x32x16_bf16 v[32:47], v[128:131], v[60:63], v[32:47]
	v_exp_f32_e32 v200, v200
	v_exp_f32_e32 v201, v201
	v_exp_f32_e32 v202, v202
	v_exp_f32_e32 v203, v203
	s_add_i32 s90, s67, 480
	v_add_u32_e32 v84, s90, v107
	v_add_u32_e32 v85, 0, v84
	v_add_u32_e32 v86, 1, v84
	v_add_u32_e32 v87, 2, v84
	v_add_u32_e32 v88, 3, v84
	v_cmp_gt_u32_e64 s[30:31], s98, v85
	v_cmp_gt_u32_e64 s[36:37], s98, v86
	v_cmp_gt_u32_e64 s[78:79], s98, v87
	v_cmp_gt_u32_e64 s[50:51], s98, v88
	v_cndmask_b32_e64 v188, 0, v188, s[30:31]
	v_add_u32_e32 v85, 8, v84
	v_cmp_gt_u32_e64 s[30:31], s98, v85
	v_cndmask_b32_e64 v189, 0, v189, s[36:37]
	v_add_u32_e32 v86, 9, v84
	v_cmp_gt_u32_e64 s[36:37], s98, v86
	v_cndmask_b32_e64 v190, 0, v190, s[78:79]
	v_add_u32_e32 v87, 10, v84
	v_cmp_gt_u32_e64 s[78:79], s98, v87
	v_cndmask_b32_e64 v191, 0, v191, s[50:51]
	v_add_u32_e32 v88, 11, v84
	v_cmp_gt_u32_e64 s[50:51], s98, v88
	v_cndmask_b32_e64 v192, 0, v192, s[30:31]
	v_add_u32_e32 v85, 16, v84
	v_cmp_gt_u32_e64 s[30:31], s98, v85
	v_cndmask_b32_e64 v193, 0, v193, s[36:37]
	v_add_u32_e32 v86, 17, v84
	v_cmp_gt_u32_e64 s[36:37], s98, v86
	v_cndmask_b32_e64 v194, 0, v194, s[78:79]
	v_add_u32_e32 v87, 18, v84
	v_cmp_gt_u32_e64 s[78:79], s98, v87
	v_cndmask_b32_e64 v195, 0, v195, s[50:51]
	v_add_u32_e32 v88, 19, v84
	v_cmp_gt_u32_e64 s[50:51], s98, v88
	v_cndmask_b32_e64 v196, 0, v196, s[30:31]
	v_add_u32_e32 v85, 24, v84
	v_cmp_gt_u32_e64 s[30:31], s98, v85
	v_cndmask_b32_e64 v197, 0, v197, s[36:37]
	v_add_u32_e32 v86, 25, v84
	v_cmp_gt_u32_e64 s[36:37], s98, v86
	v_cndmask_b32_e64 v198, 0, v198, s[78:79]
	v_add_u32_e32 v87, 26, v84
	v_cmp_gt_u32_e64 s[78:79], s98, v87
	v_cndmask_b32_e64 v199, 0, v199, s[50:51]
	v_add_u32_e32 v88, 27, v84
	v_cmp_gt_u32_e64 s[50:51], s98, v88
	v_nop
	v_cndmask_b32_e64 v200, 0, v200, s[30:31]
	v_cndmask_b32_e64 v201, 0, v201, s[36:37]
	v_cndmask_b32_e64 v202, 0, v202, s[78:79]
	v_cndmask_b32_e64 v203, 0, v203, s[50:51]
	v_cvt_pk_bf16_f32 v64, v188, v189
	v_cvt_pk_bf16_f32 v65, v190, v191
	v_cvt_pk_bf16_f32 v66, v192, v193
	v_cvt_pk_bf16_f32 v67, v194, v195
	v_cvt_pk_bf16_f32 v68, v196, v197
	v_cvt_pk_bf16_f32 v69, v198, v199
	v_cvt_pk_bf16_f32 v70, v200, v201
	v_cvt_pk_bf16_f32 v71, v202, v203
	v_pk_add_f32 v[232:233], v[232:233], v[188:189]
	v_pk_add_f32 v[232:233], v[232:233], v[190:191]
	v_pk_add_f32 v[232:233], v[232:233], v[192:193]
	v_pk_add_f32 v[232:233], v[232:233], v[194:195]
	v_pk_add_f32 v[232:233], v[232:233], v[196:197]
	v_pk_add_f32 v[232:233], v[232:233], v[198:199]
	v_pk_add_f32 v[232:233], v[232:233], v[200:201]
	v_pk_add_f32 v[232:233], v[232:233], v[202:203]
	ds_read2_b32 v[188:189], v115 offset0:170 offset1:171
	ds_read2_b32 v[190:191], v115 offset0:172 offset1:173
	ds_read2_b32 v[192:193], v115 offset0:178 offset1:179
	ds_read2_b32 v[194:195], v115 offset0:180 offset1:181
	ds_read2_b32 v[196:197], v115 offset0:187 offset1:188
	ds_read2_b32 v[198:199], v115 offset0:189 offset1:190
	ds_read2_b32 v[200:201], v115 offset0:195 offset1:196
	ds_read2_b32 v[202:203], v115 offset0:197 offset1:198
	v_mfma_f32_32x32x16_bf16 v[0:15], v[64:67], v[72:75], v[0:15]
	v_mfma_f32_32x32x16_bf16 v[16:31], v[64:67], v[76:79], v[16:31]
	v_mfma_f32_32x32x16_bf16 v[0:15], v[68:71], v[220:223], v[0:15]
	v_mfma_f32_32x32x16_bf16 v[16:31], v[68:71], v[224:227], v[16:31]
	s_add_i32 s90, s67, -256
	v_add_u32_e32 v80, s90, v239
	v_add_u32_e32 v83, s90, v240
	v_add_u32_e32 v99, s90, v241
	v_add_u32_e32 v253, s90, v242
	v_add_u32_e32 v254, s90, v101
	v_add_u32_e32 v255, s90, v150
	v_med3_i32 v80, v80, 0, s99
	v_med3_i32 v83, v83, 0, s99
	v_med3_i32 v99, v99, 0, s99
	v_med3_i32 v253, v253, 0, s99
	v_med3_i32 v254, v254, 0, s99
	v_med3_i32 v255, v255, 0, s99
	v_mad_u32_u24 v80, v80, s100, v252
	v_mad_u32_u24 v83, v83, s100, v252
	v_mad_u32_u24 v99, v99, s100, v252
	v_mad_u32_u24 v253, v253, s100, v252
	v_mad_u32_u24 v254, v254, s100, v153
	v_mad_u32_u24 v255, v255, s100, v153
	global_load_dwordx4 v[116:119], v80, s[82:83]
	global_load_dwordx4 v[120:123], v83, s[82:83]
	global_load_dwordx4 v[124:127], v99, s[82:83]
	global_load_dwordx4 v[128:131], v253, s[82:83]
	global_load_dwordx4 v[132:135], v254, s[82:83] offset:768
	global_load_dwordx4 v[136:139], v255, s[82:83] offset:768
	global_load_dwordx4 v[140:143], v254, s[82:83] offset:832
	global_load_dwordx4 v[144:147], v255, s[82:83] offset:832
	ds_read_b64_tr_b16 v[72:73], v231
	ds_read_b64_tr_b16 v[74:75], v231 offset:512
	ds_read_b64_tr_b16 v[76:77], v231 offset:2048
	ds_read_b64_tr_b16 v[78:79], v231 offset:2560
	ds_read_b64_tr_b16 v[220:221], v231 offset:1024
	ds_read_b64_tr_b16 v[222:223], v231 offset:1536
	ds_read_b64_tr_b16 v[224:225], v231 offset:3072
	ds_read_b64_tr_b16 v[226:227], v231 offset:3584
	s_waitcnt vmcnt(8)
	ds_write_b128 v247, v[156:159]
	ds_write_b128 v247, v[160:163] offset:1024
	ds_write_b128 v247, v[164:167] offset:2048
	ds_write_b128 v247, v[168:171] offset:3072
	ds_read_b128 v[156:159], v248
	ds_read_b128 v[160:163], v249
	ds_read_b128 v[164:167], v250
	ds_read_b128 v[168:171], v251
	ds_write_b128 v112, v[172:175]
	ds_write_b128 v112, v[176:179] offset:1024
	ds_write_b128 v112, v[180:183] offset:2048
	ds_write_b128 v112, v[184:187] offset:3072
	s_waitcnt lgkmcnt(4)
	v_mfma_f32_32x32x16_bf16 v[188:203], v[156:159], v[48:51], v[188:203]
	v_exp_f32_e32 v32, v32
	v_exp_f32_e32 v33, v33
	v_exp_f32_e32 v34, v34
	v_exp_f32_e32 v35, v35
	v_mfma_f32_32x32x16_bf16 v[188:203], v[160:163], v[52:55], v[188:203]
	v_exp_f32_e32 v36, v36
	v_exp_f32_e32 v37, v37
	v_exp_f32_e32 v38, v38
	v_exp_f32_e32 v39, v39
	v_mfma_f32_32x32x16_bf16 v[188:203], v[164:167], v[56:59], v[188:203]
	v_exp_f32_e32 v40, v40
	v_exp_f32_e32 v41, v41
	v_exp_f32_e32 v42, v42
	v_exp_f32_e32 v43, v43
	v_mfma_f32_32x32x16_bf16 v[188:203], v[168:171], v[60:63], v[188:203]
	v_exp_f32_e32 v44, v44
	v_exp_f32_e32 v45, v45
	v_exp_f32_e32 v46, v46
	v_exp_f32_e32 v47, v47
	s_add_i32 s90, s67, 512
	v_add_u32_e32 v84, s90, v107
	v_add_u32_e32 v85, 0, v84
	v_add_u32_e32 v86, 1, v84
	v_add_u32_e32 v87, 2, v84
	v_add_u32_e32 v88, 3, v84
	v_cmp_gt_u32_e64 s[30:31], s98, v85
	v_cmp_gt_u32_e64 s[36:37], s98, v86
	v_cmp_gt_u32_e64 s[78:79], s98, v87
	v_cmp_gt_u32_e64 s[50:51], s98, v88
	v_cndmask_b32_e64 v32, 0, v32, s[30:31]
	v_add_u32_e32 v85, 8, v84
	v_cmp_gt_u32_e64 s[30:31], s98, v85
	v_cndmask_b32_e64 v33, 0, v33, s[36:37]
	v_add_u32_e32 v86, 9, v84
	v_cmp_gt_u32_e64 s[36:37], s98, v86
	v_cndmask_b32_e64 v34, 0, v34, s[78:79]
	v_add_u32_e32 v87, 10, v84
	v_cmp_gt_u32_e64 s[78:79], s98, v87
	v_cndmask_b32_e64 v35, 0, v35, s[50:51]
	v_add_u32_e32 v88, 11, v84
	v_cmp_gt_u32_e64 s[50:51], s98, v88
	v_cndmask_b32_e64 v36, 0, v36, s[30:31]
	v_add_u32_e32 v85, 16, v84
	v_cmp_gt_u32_e64 s[30:31], s98, v85
	v_cndmask_b32_e64 v37, 0, v37, s[36:37]
	v_add_u32_e32 v86, 17, v84
	v_cmp_gt_u32_e64 s[36:37], s98, v86
	v_cndmask_b32_e64 v38, 0, v38, s[78:79]
	v_add_u32_e32 v87, 18, v84
	v_cmp_gt_u32_e64 s[78:79], s98, v87
	v_cndmask_b32_e64 v39, 0, v39, s[50:51]
	v_add_u32_e32 v88, 19, v84
	v_cmp_gt_u32_e64 s[50:51], s98, v88
	v_cndmask_b32_e64 v40, 0, v40, s[30:31]
	v_add_u32_e32 v85, 24, v84
	v_cmp_gt_u32_e64 s[30:31], s98, v85
	v_cndmask_b32_e64 v41, 0, v41, s[36:37]
	v_add_u32_e32 v86, 25, v84
	v_cmp_gt_u32_e64 s[36:37], s98, v86
	v_cndmask_b32_e64 v42, 0, v42, s[78:79]
	v_add_u32_e32 v87, 26, v84
	v_cmp_gt_u32_e64 s[78:79], s98, v87
	v_cndmask_b32_e64 v43, 0, v43, s[50:51]
	v_add_u32_e32 v88, 27, v84
	v_cmp_gt_u32_e64 s[50:51], s98, v88
	v_nop
	v_cndmask_b32_e64 v44, 0, v44, s[30:31]
	v_cndmask_b32_e64 v45, 0, v45, s[36:37]
	v_cndmask_b32_e64 v46, 0, v46, s[78:79]
	v_cndmask_b32_e64 v47, 0, v47, s[50:51]
	v_cvt_pk_bf16_f32 v64, v32, v33
	v_cvt_pk_bf16_f32 v65, v34, v35
	v_cvt_pk_bf16_f32 v66, v36, v37
	v_cvt_pk_bf16_f32 v67, v38, v39
	v_cvt_pk_bf16_f32 v68, v40, v41
	v_cvt_pk_bf16_f32 v69, v42, v43
	v_cvt_pk_bf16_f32 v70, v44, v45
	v_cvt_pk_bf16_f32 v71, v46, v47
	v_pk_add_f32 v[232:233], v[232:233], v[32:33]
	v_pk_add_f32 v[232:233], v[232:233], v[34:35]
	v_pk_add_f32 v[232:233], v[232:233], v[36:37]
	v_pk_add_f32 v[232:233], v[232:233], v[38:39]
	v_pk_add_f32 v[232:233], v[232:233], v[40:41]
	v_pk_add_f32 v[232:233], v[232:233], v[42:43]
	v_pk_add_f32 v[232:233], v[232:233], v[44:45]
	v_pk_add_f32 v[232:233], v[232:233], v[46:47]
	v_mov_b32_e32 v115, v229
	ds_read2_b32 v[32:33], v115 offset0:0 offset1:1
	ds_read2_b32 v[34:35], v115 offset0:2 offset1:3
	ds_read2_b32 v[36:37], v115 offset0:8 offset1:9
	ds_read2_b32 v[38:39], v115 offset0:10 offset1:11
	ds_read2_b32 v[40:41], v115 offset0:16 offset1:17
	ds_read2_b32 v[42:43], v115 offset0:18 offset1:19
	ds_read2_b32 v[44:45], v115 offset0:24 offset1:25
	ds_read2_b32 v[46:47], v115 offset0:26 offset1:27
	v_mfma_f32_32x32x16_bf16 v[0:15], v[64:67], v[72:75], v[0:15]
	v_mfma_f32_32x32x16_bf16 v[16:31], v[64:67], v[76:79], v[16:31]
	v_mfma_f32_32x32x16_bf16 v[0:15], v[68:71], v[220:223], v[0:15]
	v_mfma_f32_32x32x16_bf16 v[16:31], v[68:71], v[224:227], v[16:31]
	s_add_i32 s90, s67, -128
	v_add_u32_e32 v80, s90, v239
	v_add_u32_e32 v83, s90, v240
	v_add_u32_e32 v99, s90, v241
	v_add_u32_e32 v253, s90, v242
	v_add_u32_e32 v254, s90, v101
	v_add_u32_e32 v255, s90, v150
	v_med3_i32 v80, v80, 0, s99
	v_med3_i32 v83, v83, 0, s99
	v_med3_i32 v99, v99, 0, s99
	v_med3_i32 v253, v253, 0, s99
	v_med3_i32 v254, v254, 0, s99
	v_med3_i32 v255, v255, 0, s99
	v_mad_u32_u24 v80, v80, s100, v252
	v_mad_u32_u24 v83, v83, s100, v252
	v_mad_u32_u24 v99, v99, s100, v252
	v_mad_u32_u24 v253, v253, s100, v252
	v_mad_u32_u24 v254, v254, s100, v153
	v_mad_u32_u24 v255, v255, s100, v153
	global_load_dwordx4 v[156:159], v80, s[82:83]
	global_load_dwordx4 v[160:163], v83, s[82:83]
	global_load_dwordx4 v[164:167], v99, s[82:83]
	global_load_dwordx4 v[168:171], v253, s[82:83]
	global_load_dwordx4 v[172:175], v254, s[82:83] offset:768
	global_load_dwordx4 v[176:179], v255, s[82:83] offset:768
	global_load_dwordx4 v[180:183], v254, s[82:83] offset:832
	global_load_dwordx4 v[184:187], v255, s[82:83] offset:832
	ds_read_b64_tr_b16 v[72:73], v231
	ds_read_b64_tr_b16 v[74:75], v231 offset:512
	ds_read_b64_tr_b16 v[76:77], v231 offset:2048
	ds_read_b64_tr_b16 v[78:79], v231 offset:2560
	ds_read_b64_tr_b16 v[220:221], v231 offset:1024
	ds_read_b64_tr_b16 v[222:223], v231 offset:1536
	ds_read_b64_tr_b16 v[224:225], v231 offset:3072
	ds_read_b64_tr_b16 v[226:227], v231 offset:3584
	s_waitcnt vmcnt(8)
	ds_write_b128 v247, v[116:119]
	ds_write_b128 v247, v[120:123] offset:1024
	ds_write_b128 v247, v[124:127] offset:2048
	ds_write_b128 v247, v[128:131] offset:3072
	ds_read_b128 v[116:119], v248
	ds_read_b128 v[120:123], v249
	ds_read_b128 v[124:127], v250
	ds_read_b128 v[128:131], v251
	ds_write_b128 v112, v[132:135]
	ds_write_b128 v112, v[136:139] offset:1024
	ds_write_b128 v112, v[140:143] offset:2048
	ds_write_b128 v112, v[144:147] offset:3072
	s_waitcnt lgkmcnt(4)
	v_mfma_f32_32x32x16_bf16 v[32:47], v[116:119], v[48:51], v[32:47]
	v_exp_f32_e32 v188, v188
	v_exp_f32_e32 v189, v189
	v_exp_f32_e32 v190, v190
	v_exp_f32_e32 v191, v191
	v_mfma_f32_32x32x16_bf16 v[32:47], v[120:123], v[52:55], v[32:47]
	v_exp_f32_e32 v192, v192
	v_exp_f32_e32 v193, v193
	v_exp_f32_e32 v194, v194
	v_exp_f32_e32 v195, v195
	v_mfma_f32_32x32x16_bf16 v[32:47], v[124:127], v[56:59], v[32:47]
	v_exp_f32_e32 v196, v196
	v_exp_f32_e32 v197, v197
	v_exp_f32_e32 v198, v198
	v_exp_f32_e32 v199, v199
	v_mfma_f32_32x32x16_bf16 v[32:47], v[128:131], v[60:63], v[32:47]
	v_exp_f32_e32 v200, v200
	v_exp_f32_e32 v201, v201
	v_exp_f32_e32 v202, v202
	v_exp_f32_e32 v203, v203
	s_add_i32 s90, s67, 544
	v_add_u32_e32 v84, s90, v107
	v_add_u32_e32 v85, 0, v84
	v_add_u32_e32 v86, 1, v84
	v_add_u32_e32 v87, 2, v84
	v_add_u32_e32 v88, 3, v84
	v_cmp_gt_u32_e64 s[30:31], s98, v85
	v_cmp_gt_u32_e64 s[36:37], s98, v86
	v_cmp_gt_u32_e64 s[78:79], s98, v87
	v_cmp_gt_u32_e64 s[50:51], s98, v88
	v_cndmask_b32_e64 v188, 0, v188, s[30:31]
	v_add_u32_e32 v85, 8, v84
	v_cmp_gt_u32_e64 s[30:31], s98, v85
	v_cndmask_b32_e64 v189, 0, v189, s[36:37]
	v_add_u32_e32 v86, 9, v84
	v_cmp_gt_u32_e64 s[36:37], s98, v86
	v_cndmask_b32_e64 v190, 0, v190, s[78:79]
	v_add_u32_e32 v87, 10, v84
	v_cmp_gt_u32_e64 s[78:79], s98, v87
	v_cndmask_b32_e64 v191, 0, v191, s[50:51]
	v_add_u32_e32 v88, 11, v84
	v_cmp_gt_u32_e64 s[50:51], s98, v88
	v_cndmask_b32_e64 v192, 0, v192, s[30:31]
	v_add_u32_e32 v85, 16, v84
	v_cmp_gt_u32_e64 s[30:31], s98, v85
	v_cndmask_b32_e64 v193, 0, v193, s[36:37]
	v_add_u32_e32 v86, 17, v84
	v_cmp_gt_u32_e64 s[36:37], s98, v86
	v_cndmask_b32_e64 v194, 0, v194, s[78:79]
	v_add_u32_e32 v87, 18, v84
	v_cmp_gt_u32_e64 s[78:79], s98, v87
	v_cndmask_b32_e64 v195, 0, v195, s[50:51]
	v_add_u32_e32 v88, 19, v84
	v_cmp_gt_u32_e64 s[50:51], s98, v88
	v_cndmask_b32_e64 v196, 0, v196, s[30:31]
	v_add_u32_e32 v85, 24, v84
	v_cmp_gt_u32_e64 s[30:31], s98, v85
	v_cndmask_b32_e64 v197, 0, v197, s[36:37]
	v_add_u32_e32 v86, 25, v84
	v_cmp_gt_u32_e64 s[36:37], s98, v86
	v_cndmask_b32_e64 v198, 0, v198, s[78:79]
	v_add_u32_e32 v87, 26, v84
	v_cmp_gt_u32_e64 s[78:79], s98, v87
	v_cndmask_b32_e64 v199, 0, v199, s[50:51]
	v_add_u32_e32 v88, 27, v84
	v_cmp_gt_u32_e64 s[50:51], s98, v88
	v_nop
	v_cndmask_b32_e64 v200, 0, v200, s[30:31]
	v_cndmask_b32_e64 v201, 0, v201, s[36:37]
	v_cndmask_b32_e64 v202, 0, v202, s[78:79]
	v_cndmask_b32_e64 v203, 0, v203, s[50:51]
	v_cvt_pk_bf16_f32 v64, v188, v189
	v_cvt_pk_bf16_f32 v65, v190, v191
	v_cvt_pk_bf16_f32 v66, v192, v193
	v_cvt_pk_bf16_f32 v67, v194, v195
	v_cvt_pk_bf16_f32 v68, v196, v197
	v_cvt_pk_bf16_f32 v69, v198, v199
	v_cvt_pk_bf16_f32 v70, v200, v201
	v_cvt_pk_bf16_f32 v71, v202, v203
	v_pk_add_f32 v[232:233], v[232:233], v[188:189]
	v_pk_add_f32 v[232:233], v[232:233], v[190:191]
	v_pk_add_f32 v[232:233], v[232:233], v[192:193]
	v_pk_add_f32 v[232:233], v[232:233], v[194:195]
	v_pk_add_f32 v[232:233], v[232:233], v[196:197]
	v_pk_add_f32 v[232:233], v[232:233], v[198:199]
	v_pk_add_f32 v[232:233], v[232:233], v[200:201]
	v_pk_add_f32 v[232:233], v[232:233], v[202:203]
	ds_read2_b32 v[188:189], v115 offset0:32 offset1:33
	ds_read2_b32 v[190:191], v115 offset0:34 offset1:35
	ds_read2_b32 v[192:193], v115 offset0:40 offset1:41
	ds_read2_b32 v[194:195], v115 offset0:42 offset1:43
	ds_read2_b32 v[196:197], v115 offset0:48 offset1:49
	ds_read2_b32 v[198:199], v115 offset0:50 offset1:51
	ds_read2_b32 v[200:201], v115 offset0:56 offset1:57
	ds_read2_b32 v[202:203], v115 offset0:58 offset1:59
	v_mfma_f32_32x32x16_bf16 v[0:15], v[64:67], v[72:75], v[0:15]
	v_mfma_f32_32x32x16_bf16 v[16:31], v[64:67], v[76:79], v[16:31]
	v_mfma_f32_32x32x16_bf16 v[0:15], v[68:71], v[220:223], v[0:15]
	v_mfma_f32_32x32x16_bf16 v[16:31], v[68:71], v[224:227], v[16:31]
	s_add_i32 s90, s67, 0
	v_add_u32_e32 v80, s90, v239
	v_add_u32_e32 v83, s90, v240
	v_add_u32_e32 v99, s90, v241
	v_add_u32_e32 v253, s90, v242
	v_add_u32_e32 v254, s90, v101
	v_add_u32_e32 v255, s90, v150
	v_med3_i32 v80, v80, 0, s99
	v_med3_i32 v83, v83, 0, s99
	v_med3_i32 v99, v99, 0, s99
	v_med3_i32 v253, v253, 0, s99
	v_med3_i32 v254, v254, 0, s99
	v_med3_i32 v255, v255, 0, s99
	v_mad_u32_u24 v80, v80, s100, v252
	v_mad_u32_u24 v83, v83, s100, v252
	v_mad_u32_u24 v99, v99, s100, v252
	v_mad_u32_u24 v253, v253, s100, v252
	v_mad_u32_u24 v254, v254, s100, v153
	v_mad_u32_u24 v255, v255, s100, v153
	global_load_dwordx4 v[116:119], v80, s[82:83]
	global_load_dwordx4 v[120:123], v83, s[82:83]
	global_load_dwordx4 v[124:127], v99, s[82:83]
	global_load_dwordx4 v[128:131], v253, s[82:83]
	global_load_dwordx4 v[132:135], v254, s[82:83] offset:768
	global_load_dwordx4 v[136:139], v255, s[82:83] offset:768
	global_load_dwordx4 v[140:143], v254, s[82:83] offset:832
	global_load_dwordx4 v[144:147], v255, s[82:83] offset:832
	ds_read_b64_tr_b16 v[72:73], v231
	ds_read_b64_tr_b16 v[74:75], v231 offset:512
	ds_read_b64_tr_b16 v[76:77], v231 offset:2048
	ds_read_b64_tr_b16 v[78:79], v231 offset:2560
	ds_read_b64_tr_b16 v[220:221], v231 offset:1024
	ds_read_b64_tr_b16 v[222:223], v231 offset:1536
	ds_read_b64_tr_b16 v[224:225], v231 offset:3072
	ds_read_b64_tr_b16 v[226:227], v231 offset:3584
	s_waitcnt vmcnt(8)
	ds_write_b128 v247, v[156:159]
	ds_write_b128 v247, v[160:163] offset:1024
	ds_write_b128 v247, v[164:167] offset:2048
	ds_write_b128 v247, v[168:171] offset:3072
	ds_read_b128 v[156:159], v248
	ds_read_b128 v[160:163], v249
	ds_read_b128 v[164:167], v250
	ds_read_b128 v[168:171], v251
	ds_write_b128 v112, v[172:175]
	ds_write_b128 v112, v[176:179] offset:1024
	ds_write_b128 v112, v[180:183] offset:2048
	ds_write_b128 v112, v[184:187] offset:3072
	s_waitcnt lgkmcnt(4)
	v_mfma_f32_32x32x16_bf16 v[188:203], v[156:159], v[48:51], v[188:203]
	v_exp_f32_e32 v32, v32
	v_exp_f32_e32 v33, v33
	v_exp_f32_e32 v34, v34
	v_exp_f32_e32 v35, v35
	v_mfma_f32_32x32x16_bf16 v[188:203], v[160:163], v[52:55], v[188:203]
	v_exp_f32_e32 v36, v36
	v_exp_f32_e32 v37, v37
	v_exp_f32_e32 v38, v38
	v_exp_f32_e32 v39, v39
	v_mfma_f32_32x32x16_bf16 v[188:203], v[164:167], v[56:59], v[188:203]
	v_exp_f32_e32 v40, v40
	v_exp_f32_e32 v41, v41
	v_exp_f32_e32 v42, v42
	v_exp_f32_e32 v43, v43
	v_mfma_f32_32x32x16_bf16 v[188:203], v[168:171], v[60:63], v[188:203]
	v_exp_f32_e32 v44, v44
	v_exp_f32_e32 v45, v45
	v_exp_f32_e32 v46, v46
	v_exp_f32_e32 v47, v47
	s_add_i32 s90, s67, -256
	v_lshlrev_b32_e32 v84, 2, v107
	v_add_u32_e32 v84, s90, v84
	v_add_u32_e32 v85, 0, v84
	v_add_u32_e32 v86, 4, v84
	v_add_u32_e32 v87, 8, v84
	v_add_u32_e32 v88, 12, v84
	v_cmp_gt_u32_e64 s[30:31], s98, v85
	v_cmp_gt_u32_e64 s[36:37], s98, v86
	v_cmp_gt_u32_e64 s[78:79], s98, v87
	v_cmp_gt_u32_e64 s[50:51], s98, v88
	v_cndmask_b32_e64 v32, 0, v32, s[30:31]
	v_add_u32_e32 v85, 32, v84
	v_cmp_gt_u32_e64 s[30:31], s98, v85
	v_cndmask_b32_e64 v33, 0, v33, s[36:37]
	v_add_u32_e32 v86, 36, v84
	v_cmp_gt_u32_e64 s[36:37], s98, v86
	v_cndmask_b32_e64 v34, 0, v34, s[78:79]
	v_add_u32_e32 v87, 40, v84
	v_cmp_gt_u32_e64 s[78:79], s98, v87
	v_cndmask_b32_e64 v35, 0, v35, s[50:51]
	v_add_u32_e32 v88, 44, v84
	v_cmp_gt_u32_e64 s[50:51], s98, v88
	v_cndmask_b32_e64 v36, 0, v36, s[30:31]
	v_add_u32_e32 v85, 64, v84
	v_cmp_gt_u32_e64 s[30:31], s98, v85
	v_cndmask_b32_e64 v37, 0, v37, s[36:37]
	v_add_u32_e32 v86, 68, v84
	v_cmp_gt_u32_e64 s[36:37], s98, v86
	v_cndmask_b32_e64 v38, 0, v38, s[78:79]
	v_add_u32_e32 v87, 72, v84
	v_cmp_gt_u32_e64 s[78:79], s98, v87
	v_cndmask_b32_e64 v39, 0, v39, s[50:51]
	v_add_u32_e32 v88, 76, v84
	v_cmp_gt_u32_e64 s[50:51], s98, v88
	v_cndmask_b32_e64 v40, 0, v40, s[30:31]
	v_add_u32_e32 v85, 96, v84
	v_cmp_gt_u32_e64 s[30:31], s98, v85
	v_cndmask_b32_e64 v41, 0, v41, s[36:37]
	v_add_u32_e32 v86, 100, v84
	v_cmp_gt_u32_e64 s[36:37], s98, v86
	v_cndmask_b32_e64 v42, 0, v42, s[78:79]
	v_add_u32_e32 v87, 104, v84
	v_cmp_gt_u32_e64 s[78:79], s98, v87
	v_cndmask_b32_e64 v43, 0, v43, s[50:51]
	v_add_u32_e32 v88, 108, v84
	v_cmp_gt_u32_e64 s[50:51], s98, v88
	v_nop
	v_cndmask_b32_e64 v44, 0, v44, s[30:31]
	v_cndmask_b32_e64 v45, 0, v45, s[36:37]
	v_cndmask_b32_e64 v46, 0, v46, s[78:79]
	v_cndmask_b32_e64 v47, 0, v47, s[50:51]
	v_cvt_pk_bf16_f32 v64, v32, v33
	v_cvt_pk_bf16_f32 v65, v34, v35
	v_cvt_pk_bf16_f32 v66, v36, v37
	v_cvt_pk_bf16_f32 v67, v38, v39
	v_cvt_pk_bf16_f32 v68, v40, v41
	v_cvt_pk_bf16_f32 v69, v42, v43
	v_cvt_pk_bf16_f32 v70, v44, v45
	v_cvt_pk_bf16_f32 v71, v46, v47
	v_pk_add_f32 v[232:233], v[232:233], v[32:33]
	v_pk_add_f32 v[232:233], v[232:233], v[34:35]
	v_pk_add_f32 v[232:233], v[232:233], v[36:37]
	v_pk_add_f32 v[232:233], v[232:233], v[38:39]
	v_pk_add_f32 v[232:233], v[232:233], v[40:41]
	v_pk_add_f32 v[232:233], v[232:233], v[42:43]
	v_pk_add_f32 v[232:233], v[232:233], v[44:45]
	v_pk_add_f32 v[232:233], v[232:233], v[46:47]
	ds_read2_b32 v[32:33], v115 offset0:64 offset1:65
	ds_read2_b32 v[34:35], v115 offset0:66 offset1:67
	ds_read2_b32 v[36:37], v115 offset0:72 offset1:73
	ds_read2_b32 v[38:39], v115 offset0:74 offset1:75
	ds_read2_b32 v[40:41], v115 offset0:80 offset1:81
	ds_read2_b32 v[42:43], v115 offset0:82 offset1:83
	ds_read2_b32 v[44:45], v115 offset0:88 offset1:89
	ds_read2_b32 v[46:47], v115 offset0:90 offset1:91
	v_mfma_f32_32x32x16_bf16 v[0:15], v[64:67], v[72:75], v[0:15]
	v_mfma_f32_32x32x16_bf16 v[16:31], v[64:67], v[76:79], v[16:31]
	v_mfma_f32_32x32x16_bf16 v[0:15], v[68:71], v[220:223], v[0:15]
	v_mfma_f32_32x32x16_bf16 v[16:31], v[68:71], v[224:227], v[16:31]
	s_add_i32 s90, s67, 128
	v_add_u32_e32 v80, s90, v239
	v_add_u32_e32 v83, s90, v240
	v_add_u32_e32 v99, s90, v241
	v_add_u32_e32 v253, s90, v242
	v_add_u32_e32 v254, s90, v101
	v_add_u32_e32 v255, s90, v150
	v_med3_i32 v80, v80, 0, s99
	v_med3_i32 v83, v83, 0, s99
	v_med3_i32 v99, v99, 0, s99
	v_med3_i32 v253, v253, 0, s99
	v_med3_i32 v254, v254, 0, s99
	v_med3_i32 v255, v255, 0, s99
	v_mad_u32_u24 v80, v80, s100, v252
	v_mad_u32_u24 v83, v83, s100, v252
	v_mad_u32_u24 v99, v99, s100, v252
	v_mad_u32_u24 v253, v253, s100, v252
	v_mad_u32_u24 v254, v254, s100, v153
	v_mad_u32_u24 v255, v255, s100, v153
	global_load_dwordx4 v[156:159], v80, s[82:83]
	global_load_dwordx4 v[160:163], v83, s[82:83]
	global_load_dwordx4 v[164:167], v99, s[82:83]
	global_load_dwordx4 v[168:171], v253, s[82:83]
	global_load_dwordx4 v[172:175], v254, s[82:83] offset:768
	global_load_dwordx4 v[176:179], v255, s[82:83] offset:768
	global_load_dwordx4 v[180:183], v254, s[82:83] offset:832
	global_load_dwordx4 v[184:187], v255, s[82:83] offset:832
	ds_read_b64_tr_b16 v[72:73], v231
	ds_read_b64_tr_b16 v[74:75], v231 offset:512
	ds_read_b64_tr_b16 v[76:77], v231 offset:2048
	ds_read_b64_tr_b16 v[78:79], v231 offset:2560
	ds_read_b64_tr_b16 v[220:221], v231 offset:1024
	ds_read_b64_tr_b16 v[222:223], v231 offset:1536
	ds_read_b64_tr_b16 v[224:225], v231 offset:3072
	ds_read_b64_tr_b16 v[226:227], v231 offset:3584
	s_waitcnt vmcnt(8)
	ds_write_b128 v247, v[116:119]
	ds_write_b128 v247, v[120:123] offset:1024
	ds_write_b128 v247, v[124:127] offset:2048
	ds_write_b128 v247, v[128:131] offset:3072
	ds_read_b128 v[116:119], v248
	ds_read_b128 v[120:123], v249
	ds_read_b128 v[124:127], v250
	ds_read_b128 v[128:131], v251
	ds_write_b128 v112, v[132:135]
	ds_write_b128 v112, v[136:139] offset:1024
	ds_write_b128 v112, v[140:143] offset:2048
	ds_write_b128 v112, v[144:147] offset:3072
	s_waitcnt lgkmcnt(4)
	v_mfma_f32_32x32x16_bf16 v[32:47], v[116:119], v[48:51], v[32:47]
	v_exp_f32_e32 v188, v188
	v_exp_f32_e32 v189, v189
	v_exp_f32_e32 v190, v190
	v_exp_f32_e32 v191, v191
	v_mfma_f32_32x32x16_bf16 v[32:47], v[120:123], v[52:55], v[32:47]
	v_exp_f32_e32 v192, v192
	v_exp_f32_e32 v193, v193
	v_exp_f32_e32 v194, v194
	v_exp_f32_e32 v195, v195
	v_mfma_f32_32x32x16_bf16 v[32:47], v[124:127], v[56:59], v[32:47]
	v_exp_f32_e32 v196, v196
	v_exp_f32_e32 v197, v197
	v_exp_f32_e32 v198, v198
	v_exp_f32_e32 v199, v199
	v_mfma_f32_32x32x16_bf16 v[32:47], v[128:131], v[60:63], v[32:47]
	v_exp_f32_e32 v200, v200
	v_exp_f32_e32 v201, v201
	v_exp_f32_e32 v202, v202
	v_exp_f32_e32 v203, v203
	s_add_i32 s90, s67, -128
	v_lshlrev_b32_e32 v84, 2, v107
	v_add_u32_e32 v84, s90, v84
	v_add_u32_e32 v85, 0, v84
	v_add_u32_e32 v86, 4, v84
	v_add_u32_e32 v87, 8, v84
	v_add_u32_e32 v88, 12, v84
	v_cmp_gt_u32_e64 s[30:31], s98, v85
	v_cmp_gt_u32_e64 s[36:37], s98, v86
	v_cmp_gt_u32_e64 s[78:79], s98, v87
	v_cmp_gt_u32_e64 s[50:51], s98, v88
	v_cndmask_b32_e64 v188, 0, v188, s[30:31]
	v_add_u32_e32 v85, 32, v84
	v_cmp_gt_u32_e64 s[30:31], s98, v85
	v_cndmask_b32_e64 v189, 0, v189, s[36:37]
	v_add_u32_e32 v86, 36, v84
	v_cmp_gt_u32_e64 s[36:37], s98, v86
	v_cndmask_b32_e64 v190, 0, v190, s[78:79]
	v_add_u32_e32 v87, 40, v84
	v_cmp_gt_u32_e64 s[78:79], s98, v87
	v_cndmask_b32_e64 v191, 0, v191, s[50:51]
	v_add_u32_e32 v88, 44, v84
	v_cmp_gt_u32_e64 s[50:51], s98, v88
	v_cndmask_b32_e64 v192, 0, v192, s[30:31]
	v_add_u32_e32 v85, 64, v84
	v_cmp_gt_u32_e64 s[30:31], s98, v85
	v_cndmask_b32_e64 v193, 0, v193, s[36:37]
	v_add_u32_e32 v86, 68, v84
	v_cmp_gt_u32_e64 s[36:37], s98, v86
	v_cndmask_b32_e64 v194, 0, v194, s[78:79]
	v_add_u32_e32 v87, 72, v84
	v_cmp_gt_u32_e64 s[78:79], s98, v87
	v_cndmask_b32_e64 v195, 0, v195, s[50:51]
	v_add_u32_e32 v88, 76, v84
	v_cmp_gt_u32_e64 s[50:51], s98, v88
	v_cndmask_b32_e64 v196, 0, v196, s[30:31]
	v_add_u32_e32 v85, 96, v84
	v_cmp_gt_u32_e64 s[30:31], s98, v85
	v_cndmask_b32_e64 v197, 0, v197, s[36:37]
	v_add_u32_e32 v86, 100, v84
	v_cmp_gt_u32_e64 s[36:37], s98, v86
	v_cndmask_b32_e64 v198, 0, v198, s[78:79]
	v_add_u32_e32 v87, 104, v84
	v_cmp_gt_u32_e64 s[78:79], s98, v87
	v_cndmask_b32_e64 v199, 0, v199, s[50:51]
	v_add_u32_e32 v88, 108, v84
	v_cmp_gt_u32_e64 s[50:51], s98, v88
	v_nop
	v_cndmask_b32_e64 v200, 0, v200, s[30:31]
	v_cndmask_b32_e64 v201, 0, v201, s[36:37]
	v_cndmask_b32_e64 v202, 0, v202, s[78:79]
	v_cndmask_b32_e64 v203, 0, v203, s[50:51]
	v_cvt_pk_bf16_f32 v64, v188, v189
	v_cvt_pk_bf16_f32 v65, v190, v191
	v_cvt_pk_bf16_f32 v66, v192, v193
	v_cvt_pk_bf16_f32 v67, v194, v195
	v_cvt_pk_bf16_f32 v68, v196, v197
	v_cvt_pk_bf16_f32 v69, v198, v199
	v_cvt_pk_bf16_f32 v70, v200, v201
	v_cvt_pk_bf16_f32 v71, v202, v203
	v_pk_add_f32 v[232:233], v[232:233], v[188:189]
	v_pk_add_f32 v[232:233], v[232:233], v[190:191]
	v_pk_add_f32 v[232:233], v[232:233], v[192:193]
	v_pk_add_f32 v[232:233], v[232:233], v[194:195]
	v_pk_add_f32 v[232:233], v[232:233], v[196:197]
	v_pk_add_f32 v[232:233], v[232:233], v[198:199]
	v_pk_add_f32 v[232:233], v[232:233], v[200:201]
	v_pk_add_f32 v[232:233], v[232:233], v[202:203]
	ds_read2_b32 v[188:189], v115 offset0:96 offset1:97
	ds_read2_b32 v[190:191], v115 offset0:98 offset1:99
	ds_read2_b32 v[192:193], v115 offset0:104 offset1:105
	ds_read2_b32 v[194:195], v115 offset0:106 offset1:107
	ds_read2_b32 v[196:197], v115 offset0:112 offset1:113
	ds_read2_b32 v[198:199], v115 offset0:114 offset1:115
	ds_read2_b32 v[200:201], v115 offset0:120 offset1:121
	ds_read2_b32 v[202:203], v115 offset0:122 offset1:123
	v_mfma_f32_32x32x16_bf16 v[0:15], v[64:67], v[72:75], v[0:15]
	v_mfma_f32_32x32x16_bf16 v[16:31], v[64:67], v[76:79], v[16:31]
	v_mfma_f32_32x32x16_bf16 v[0:15], v[68:71], v[220:223], v[0:15]
	v_mfma_f32_32x32x16_bf16 v[16:31], v[68:71], v[224:227], v[16:31]
	s_add_i32 s90, s67, 256
	v_add_u32_e32 v80, s90, v239
	v_add_u32_e32 v83, s90, v240
	v_add_u32_e32 v99, s90, v241
	v_add_u32_e32 v253, s90, v242
	v_add_u32_e32 v254, s90, v101
	v_add_u32_e32 v255, s90, v150
	v_med3_i32 v80, v80, 0, s99
	v_med3_i32 v83, v83, 0, s99
	v_med3_i32 v99, v99, 0, s99
	v_med3_i32 v253, v253, 0, s99
	v_med3_i32 v254, v254, 0, s99
	v_med3_i32 v255, v255, 0, s99
	v_mad_u32_u24 v80, v80, s100, v252
	v_mad_u32_u24 v83, v83, s100, v252
	v_mad_u32_u24 v99, v99, s100, v252
	v_mad_u32_u24 v253, v253, s100, v252
	v_mad_u32_u24 v254, v254, s100, v153
	v_mad_u32_u24 v255, v255, s100, v153
	global_load_dwordx4 v[116:119], v80, s[82:83]
	global_load_dwordx4 v[120:123], v83, s[82:83]
	global_load_dwordx4 v[124:127], v99, s[82:83]
	global_load_dwordx4 v[128:131], v253, s[82:83]
	global_load_dwordx4 v[132:135], v254, s[82:83] offset:768
	global_load_dwordx4 v[136:139], v255, s[82:83] offset:768
	global_load_dwordx4 v[140:143], v254, s[82:83] offset:832
	global_load_dwordx4 v[144:147], v255, s[82:83] offset:832
	ds_read_b64_tr_b16 v[72:73], v231
	ds_read_b64_tr_b16 v[74:75], v231 offset:512
	ds_read_b64_tr_b16 v[76:77], v231 offset:2048
	ds_read_b64_tr_b16 v[78:79], v231 offset:2560
	ds_read_b64_tr_b16 v[220:221], v231 offset:1024
	ds_read_b64_tr_b16 v[222:223], v231 offset:1536
	ds_read_b64_tr_b16 v[224:225], v231 offset:3072
	ds_read_b64_tr_b16 v[226:227], v231 offset:3584
	s_waitcnt vmcnt(8)
	ds_write_b128 v247, v[156:159]
	ds_write_b128 v247, v[160:163] offset:1024
	ds_write_b128 v247, v[164:167] offset:2048
	ds_write_b128 v247, v[168:171] offset:3072
	ds_read_b128 v[156:159], v248
	ds_read_b128 v[160:163], v249
	ds_read_b128 v[164:167], v250
	ds_read_b128 v[168:171], v251
	ds_write_b128 v112, v[172:175]
	ds_write_b128 v112, v[176:179] offset:1024
	ds_write_b128 v112, v[180:183] offset:2048
	ds_write_b128 v112, v[184:187] offset:3072
	s_waitcnt lgkmcnt(4)
	v_mfma_f32_32x32x16_bf16 v[188:203], v[156:159], v[48:51], v[188:203]
	v_exp_f32_e32 v32, v32
	v_exp_f32_e32 v33, v33
	v_exp_f32_e32 v34, v34
	v_exp_f32_e32 v35, v35
	v_mfma_f32_32x32x16_bf16 v[188:203], v[160:163], v[52:55], v[188:203]
	v_exp_f32_e32 v36, v36
	v_exp_f32_e32 v37, v37
	v_exp_f32_e32 v38, v38
	v_exp_f32_e32 v39, v39
	v_mfma_f32_32x32x16_bf16 v[188:203], v[164:167], v[56:59], v[188:203]
	v_exp_f32_e32 v40, v40
	v_exp_f32_e32 v41, v41
	v_exp_f32_e32 v42, v42
	v_exp_f32_e32 v43, v43
	v_mfma_f32_32x32x16_bf16 v[188:203], v[168:171], v[60:63], v[188:203]
	v_exp_f32_e32 v44, v44
	v_exp_f32_e32 v45, v45
	v_exp_f32_e32 v46, v46
	v_exp_f32_e32 v47, v47
	s_add_i32 s90, s67, 0
	v_lshlrev_b32_e32 v84, 2, v107
	v_add_u32_e32 v84, s90, v84
	v_add_u32_e32 v85, 0, v84
	v_add_u32_e32 v86, 4, v84
	v_add_u32_e32 v87, 8, v84
	v_add_u32_e32 v88, 12, v84
	v_cmp_gt_u32_e64 s[30:31], s98, v85
	v_cmp_gt_u32_e64 s[36:37], s98, v86
	v_cmp_gt_u32_e64 s[78:79], s98, v87
	v_cmp_gt_u32_e64 s[50:51], s98, v88
	v_cndmask_b32_e64 v32, 0, v32, s[30:31]
	v_add_u32_e32 v85, 32, v84
	v_cmp_gt_u32_e64 s[30:31], s98, v85
	v_cndmask_b32_e64 v33, 0, v33, s[36:37]
	v_add_u32_e32 v86, 36, v84
	v_cmp_gt_u32_e64 s[36:37], s98, v86
	v_cndmask_b32_e64 v34, 0, v34, s[78:79]
	v_add_u32_e32 v87, 40, v84
	v_cmp_gt_u32_e64 s[78:79], s98, v87
	v_cndmask_b32_e64 v35, 0, v35, s[50:51]
	v_add_u32_e32 v88, 44, v84
	v_cmp_gt_u32_e64 s[50:51], s98, v88
	v_cndmask_b32_e64 v36, 0, v36, s[30:31]
	v_add_u32_e32 v85, 64, v84
	v_cmp_gt_u32_e64 s[30:31], s98, v85
	v_cndmask_b32_e64 v37, 0, v37, s[36:37]
	v_add_u32_e32 v86, 68, v84
	v_cmp_gt_u32_e64 s[36:37], s98, v86
	v_cndmask_b32_e64 v38, 0, v38, s[78:79]
	v_add_u32_e32 v87, 72, v84
	v_cmp_gt_u32_e64 s[78:79], s98, v87
	v_cndmask_b32_e64 v39, 0, v39, s[50:51]
	v_add_u32_e32 v88, 76, v84
	v_cmp_gt_u32_e64 s[50:51], s98, v88
	v_cndmask_b32_e64 v40, 0, v40, s[30:31]
	v_add_u32_e32 v85, 96, v84
	v_cmp_gt_u32_e64 s[30:31], s98, v85
	v_cndmask_b32_e64 v41, 0, v41, s[36:37]
	v_add_u32_e32 v86, 100, v84
	v_cmp_gt_u32_e64 s[36:37], s98, v86
	v_cndmask_b32_e64 v42, 0, v42, s[78:79]
	v_add_u32_e32 v87, 104, v84
	v_cmp_gt_u32_e64 s[78:79], s98, v87
	v_cndmask_b32_e64 v43, 0, v43, s[50:51]
	v_add_u32_e32 v88, 108, v84
	v_cmp_gt_u32_e64 s[50:51], s98, v88
	v_nop
	v_cndmask_b32_e64 v44, 0, v44, s[30:31]
	v_cndmask_b32_e64 v45, 0, v45, s[36:37]
	v_cndmask_b32_e64 v46, 0, v46, s[78:79]
	v_cndmask_b32_e64 v47, 0, v47, s[50:51]
	v_cvt_pk_bf16_f32 v64, v32, v33
	v_cvt_pk_bf16_f32 v65, v34, v35
	v_cvt_pk_bf16_f32 v66, v36, v37
	v_cvt_pk_bf16_f32 v67, v38, v39
	v_cvt_pk_bf16_f32 v68, v40, v41
	v_cvt_pk_bf16_f32 v69, v42, v43
	v_cvt_pk_bf16_f32 v70, v44, v45
	v_cvt_pk_bf16_f32 v71, v46, v47
	v_pk_add_f32 v[232:233], v[232:233], v[32:33]
	v_pk_add_f32 v[232:233], v[232:233], v[34:35]
	v_pk_add_f32 v[232:233], v[232:233], v[36:37]
	v_pk_add_f32 v[232:233], v[232:233], v[38:39]
	v_pk_add_f32 v[232:233], v[232:233], v[40:41]
	v_pk_add_f32 v[232:233], v[232:233], v[42:43]
	v_pk_add_f32 v[232:233], v[232:233], v[44:45]
	v_pk_add_f32 v[232:233], v[232:233], v[46:47]
	ds_read2_b32 v[32:33], v115 offset0:128 offset1:129
	ds_read2_b32 v[34:35], v115 offset0:130 offset1:131
	ds_read2_b32 v[36:37], v115 offset0:136 offset1:137
	ds_read2_b32 v[38:39], v115 offset0:138 offset1:139
	ds_read2_b32 v[40:41], v115 offset0:144 offset1:145
	ds_read2_b32 v[42:43], v115 offset0:146 offset1:147
	ds_read2_b32 v[44:45], v115 offset0:152 offset1:153
	ds_read2_b32 v[46:47], v115 offset0:154 offset1:155
	v_mfma_f32_32x32x16_bf16 v[0:15], v[64:67], v[72:75], v[0:15]
	v_mfma_f32_32x32x16_bf16 v[16:31], v[64:67], v[76:79], v[16:31]
	v_mfma_f32_32x32x16_bf16 v[0:15], v[68:71], v[220:223], v[0:15]
	v_mfma_f32_32x32x16_bf16 v[16:31], v[68:71], v[224:227], v[16:31]
	s_add_i32 s90, s67, 384
	v_add_u32_e32 v80, s90, v239
	v_add_u32_e32 v83, s90, v240
	v_add_u32_e32 v99, s90, v241
	v_add_u32_e32 v253, s90, v242
	v_add_u32_e32 v254, s90, v101
	v_add_u32_e32 v255, s90, v150
	v_med3_i32 v80, v80, 0, s99
	v_med3_i32 v83, v83, 0, s99
	v_med3_i32 v99, v99, 0, s99
	v_med3_i32 v253, v253, 0, s99
	v_med3_i32 v254, v254, 0, s99
	v_med3_i32 v255, v255, 0, s99
	v_mad_u32_u24 v80, v80, s100, v252
	v_mad_u32_u24 v83, v83, s100, v252
	v_mad_u32_u24 v99, v99, s100, v252
	v_mad_u32_u24 v253, v253, s100, v252
	v_mad_u32_u24 v254, v254, s100, v153
	v_mad_u32_u24 v255, v255, s100, v153
	global_load_dwordx4 v[156:159], v80, s[82:83]
	global_load_dwordx4 v[160:163], v83, s[82:83]
	global_load_dwordx4 v[164:167], v99, s[82:83]
	global_load_dwordx4 v[168:171], v253, s[82:83]
	global_load_dwordx4 v[172:175], v254, s[82:83] offset:768
	global_load_dwordx4 v[176:179], v255, s[82:83] offset:768
	global_load_dwordx4 v[180:183], v254, s[82:83] offset:832
	global_load_dwordx4 v[184:187], v255, s[82:83] offset:832
	ds_read_b64_tr_b16 v[72:73], v231
	ds_read_b64_tr_b16 v[74:75], v231 offset:512
	ds_read_b64_tr_b16 v[76:77], v231 offset:2048
	ds_read_b64_tr_b16 v[78:79], v231 offset:2560
	ds_read_b64_tr_b16 v[220:221], v231 offset:1024
	ds_read_b64_tr_b16 v[222:223], v231 offset:1536
	ds_read_b64_tr_b16 v[224:225], v231 offset:3072
	ds_read_b64_tr_b16 v[226:227], v231 offset:3584
	s_waitcnt vmcnt(8)
	ds_write_b128 v247, v[116:119]
	ds_write_b128 v247, v[120:123] offset:1024
	ds_write_b128 v247, v[124:127] offset:2048
	ds_write_b128 v247, v[128:131] offset:3072
	ds_read_b128 v[116:119], v248
	ds_read_b128 v[120:123], v249
	ds_read_b128 v[124:127], v250
	ds_read_b128 v[128:131], v251
	ds_write_b128 v112, v[132:135]
	ds_write_b128 v112, v[136:139] offset:1024
	ds_write_b128 v112, v[140:143] offset:2048
	ds_write_b128 v112, v[144:147] offset:3072
	s_waitcnt lgkmcnt(4)
	v_mfma_f32_32x32x16_bf16 v[32:47], v[116:119], v[48:51], v[32:47]
	v_exp_f32_e32 v188, v188
	v_exp_f32_e32 v189, v189
	v_exp_f32_e32 v190, v190
	v_exp_f32_e32 v191, v191
	v_mfma_f32_32x32x16_bf16 v[32:47], v[120:123], v[52:55], v[32:47]
	v_exp_f32_e32 v192, v192
	v_exp_f32_e32 v193, v193
	v_exp_f32_e32 v194, v194
	v_exp_f32_e32 v195, v195
	v_mfma_f32_32x32x16_bf16 v[32:47], v[124:127], v[56:59], v[32:47]
	v_exp_f32_e32 v196, v196
	v_exp_f32_e32 v197, v197
	v_exp_f32_e32 v198, v198
	v_exp_f32_e32 v199, v199
	v_mfma_f32_32x32x16_bf16 v[32:47], v[128:131], v[60:63], v[32:47]
	v_exp_f32_e32 v200, v200
	v_exp_f32_e32 v201, v201
	v_exp_f32_e32 v202, v202
	v_exp_f32_e32 v203, v203
	s_add_i32 s90, s67, 128
	v_lshlrev_b32_e32 v84, 2, v107
	v_add_u32_e32 v84, s90, v84
	v_add_u32_e32 v85, 0, v84
	v_add_u32_e32 v86, 4, v84
	v_add_u32_e32 v87, 8, v84
	v_add_u32_e32 v88, 12, v84
	v_cmp_gt_u32_e64 s[30:31], s98, v85
	v_cmp_gt_u32_e64 s[36:37], s98, v86
	v_cmp_gt_u32_e64 s[78:79], s98, v87
	v_cmp_gt_u32_e64 s[50:51], s98, v88
	v_cndmask_b32_e64 v188, 0, v188, s[30:31]
	v_add_u32_e32 v85, 32, v84
	v_cmp_gt_u32_e64 s[30:31], s98, v85
	v_cndmask_b32_e64 v189, 0, v189, s[36:37]
	v_add_u32_e32 v86, 36, v84
	v_cmp_gt_u32_e64 s[36:37], s98, v86
	v_cndmask_b32_e64 v190, 0, v190, s[78:79]
	v_add_u32_e32 v87, 40, v84
	v_cmp_gt_u32_e64 s[78:79], s98, v87
	v_cndmask_b32_e64 v191, 0, v191, s[50:51]
	v_add_u32_e32 v88, 44, v84
	v_cmp_gt_u32_e64 s[50:51], s98, v88
	v_cndmask_b32_e64 v192, 0, v192, s[30:31]
	v_add_u32_e32 v85, 64, v84
	v_cmp_gt_u32_e64 s[30:31], s98, v85
	v_cndmask_b32_e64 v193, 0, v193, s[36:37]
	v_add_u32_e32 v86, 68, v84
	v_cmp_gt_u32_e64 s[36:37], s98, v86
	v_cndmask_b32_e64 v194, 0, v194, s[78:79]
	v_add_u32_e32 v87, 72, v84
	v_cmp_gt_u32_e64 s[78:79], s98, v87
	v_cndmask_b32_e64 v195, 0, v195, s[50:51]
	v_add_u32_e32 v88, 76, v84
	v_cmp_gt_u32_e64 s[50:51], s98, v88
	v_cndmask_b32_e64 v196, 0, v196, s[30:31]
	v_add_u32_e32 v85, 96, v84
	v_cmp_gt_u32_e64 s[30:31], s98, v85
	v_cndmask_b32_e64 v197, 0, v197, s[36:37]
	v_add_u32_e32 v86, 100, v84
	v_cmp_gt_u32_e64 s[36:37], s98, v86
	v_cndmask_b32_e64 v198, 0, v198, s[78:79]
	v_add_u32_e32 v87, 104, v84
	v_cmp_gt_u32_e64 s[78:79], s98, v87
	v_cndmask_b32_e64 v199, 0, v199, s[50:51]
	v_add_u32_e32 v88, 108, v84
	v_cmp_gt_u32_e64 s[50:51], s98, v88
	v_nop
	v_cndmask_b32_e64 v200, 0, v200, s[30:31]
	v_cndmask_b32_e64 v201, 0, v201, s[36:37]
	v_cndmask_b32_e64 v202, 0, v202, s[78:79]
	v_cndmask_b32_e64 v203, 0, v203, s[50:51]
	v_cvt_pk_bf16_f32 v64, v188, v189
	v_cvt_pk_bf16_f32 v65, v190, v191
	v_cvt_pk_bf16_f32 v66, v192, v193
	v_cvt_pk_bf16_f32 v67, v194, v195
	v_cvt_pk_bf16_f32 v68, v196, v197
	v_cvt_pk_bf16_f32 v69, v198, v199
	v_cvt_pk_bf16_f32 v70, v200, v201
	v_cvt_pk_bf16_f32 v71, v202, v203
	v_pk_add_f32 v[232:233], v[232:233], v[188:189]
	v_pk_add_f32 v[232:233], v[232:233], v[190:191]
	v_pk_add_f32 v[232:233], v[232:233], v[192:193]
	v_pk_add_f32 v[232:233], v[232:233], v[194:195]
	v_pk_add_f32 v[232:233], v[232:233], v[196:197]
	v_pk_add_f32 v[232:233], v[232:233], v[198:199]
	v_pk_add_f32 v[232:233], v[232:233], v[200:201]
	v_pk_add_f32 v[232:233], v[232:233], v[202:203]
	ds_read2_b32 v[188:189], v115 offset0:160 offset1:161
	ds_read2_b32 v[190:191], v115 offset0:162 offset1:163
	ds_read2_b32 v[192:193], v115 offset0:168 offset1:169
	ds_read2_b32 v[194:195], v115 offset0:170 offset1:171
	ds_read2_b32 v[196:197], v115 offset0:176 offset1:177
	ds_read2_b32 v[198:199], v115 offset0:178 offset1:179
	ds_read2_b32 v[200:201], v115 offset0:184 offset1:185
	ds_read2_b32 v[202:203], v115 offset0:186 offset1:187
	v_mfma_f32_32x32x16_bf16 v[0:15], v[64:67], v[72:75], v[0:15]
	v_mfma_f32_32x32x16_bf16 v[16:31], v[64:67], v[76:79], v[16:31]
	v_mfma_f32_32x32x16_bf16 v[0:15], v[68:71], v[220:223], v[0:15]
	v_mfma_f32_32x32x16_bf16 v[16:31], v[68:71], v[224:227], v[16:31]
	s_add_i32 s90, s67, 512
	v_add_u32_e32 v80, s90, v239
	v_add_u32_e32 v83, s90, v240
	v_add_u32_e32 v99, s90, v241
	v_add_u32_e32 v253, s90, v242
	v_add_u32_e32 v254, s90, v101
	v_add_u32_e32 v255, s90, v150
	v_med3_i32 v80, v80, 0, s99
	v_med3_i32 v83, v83, 0, s99
	v_med3_i32 v99, v99, 0, s99
	v_med3_i32 v253, v253, 0, s99
	v_med3_i32 v254, v254, 0, s99
	v_med3_i32 v255, v255, 0, s99
	v_mad_u32_u24 v80, v80, s100, v252
	v_mad_u32_u24 v83, v83, s100, v252
	v_mad_u32_u24 v99, v99, s100, v252
	v_mad_u32_u24 v253, v253, s100, v252
	v_mad_u32_u24 v254, v254, s100, v153
	v_mad_u32_u24 v255, v255, s100, v153
	global_load_dwordx4 v[116:119], v80, s[82:83]
	global_load_dwordx4 v[120:123], v83, s[82:83]
	global_load_dwordx4 v[124:127], v99, s[82:83]
	global_load_dwordx4 v[128:131], v253, s[82:83]
	global_load_dwordx4 v[132:135], v254, s[82:83] offset:768
	global_load_dwordx4 v[136:139], v255, s[82:83] offset:768
	global_load_dwordx4 v[140:143], v254, s[82:83] offset:832
	global_load_dwordx4 v[144:147], v255, s[82:83] offset:832
	ds_read_b64_tr_b16 v[72:73], v231
	ds_read_b64_tr_b16 v[74:75], v231 offset:512
	ds_read_b64_tr_b16 v[76:77], v231 offset:2048
	ds_read_b64_tr_b16 v[78:79], v231 offset:2560
	ds_read_b64_tr_b16 v[220:221], v231 offset:1024
	ds_read_b64_tr_b16 v[222:223], v231 offset:1536
	ds_read_b64_tr_b16 v[224:225], v231 offset:3072
	ds_read_b64_tr_b16 v[226:227], v231 offset:3584
	s_waitcnt vmcnt(8)
	ds_write_b128 v247, v[156:159]
	ds_write_b128 v247, v[160:163] offset:1024
	ds_write_b128 v247, v[164:167] offset:2048
	ds_write_b128 v247, v[168:171] offset:3072
	ds_read_b128 v[156:159], v248
	ds_read_b128 v[160:163], v249
	ds_read_b128 v[164:167], v250
	ds_read_b128 v[168:171], v251
	ds_write_b128 v112, v[172:175]
	ds_write_b128 v112, v[176:179] offset:1024
	ds_write_b128 v112, v[180:183] offset:2048
	ds_write_b128 v112, v[184:187] offset:3072
	s_waitcnt lgkmcnt(4)
	v_mfma_f32_32x32x16_bf16 v[188:203], v[156:159], v[48:51], v[188:203]
	v_exp_f32_e32 v32, v32
	v_exp_f32_e32 v33, v33
	v_exp_f32_e32 v34, v34
	v_exp_f32_e32 v35, v35
	v_mfma_f32_32x32x16_bf16 v[188:203], v[160:163], v[52:55], v[188:203]
	v_exp_f32_e32 v36, v36
	v_exp_f32_e32 v37, v37
	v_exp_f32_e32 v38, v38
	v_exp_f32_e32 v39, v39
	v_mfma_f32_32x32x16_bf16 v[188:203], v[164:167], v[56:59], v[188:203]
	v_exp_f32_e32 v40, v40
	v_exp_f32_e32 v41, v41
	v_exp_f32_e32 v42, v42
	v_exp_f32_e32 v43, v43
	v_mfma_f32_32x32x16_bf16 v[188:203], v[168:171], v[60:63], v[188:203]
	v_exp_f32_e32 v44, v44
	v_exp_f32_e32 v45, v45
	v_exp_f32_e32 v46, v46
	v_exp_f32_e32 v47, v47
	s_add_i32 s90, s67, 256
	v_lshlrev_b32_e32 v84, 2, v107
	v_add_u32_e32 v84, s90, v84
	v_add_u32_e32 v85, 0, v84
	v_add_u32_e32 v86, 4, v84
	v_add_u32_e32 v87, 8, v84
	v_add_u32_e32 v88, 12, v84
	v_cmp_gt_u32_e64 s[30:31], s98, v85
	v_cmp_gt_u32_e64 s[36:37], s98, v86
	v_cmp_gt_u32_e64 s[78:79], s98, v87
	v_cmp_gt_u32_e64 s[50:51], s98, v88
	v_cndmask_b32_e64 v32, 0, v32, s[30:31]
	v_add_u32_e32 v85, 32, v84
	v_cmp_gt_u32_e64 s[30:31], s98, v85
	v_cndmask_b32_e64 v33, 0, v33, s[36:37]
	v_add_u32_e32 v86, 36, v84
	v_cmp_gt_u32_e64 s[36:37], s98, v86
	v_cndmask_b32_e64 v34, 0, v34, s[78:79]
	v_add_u32_e32 v87, 40, v84
	v_cmp_gt_u32_e64 s[78:79], s98, v87
	v_cndmask_b32_e64 v35, 0, v35, s[50:51]
	v_add_u32_e32 v88, 44, v84
	v_cmp_gt_u32_e64 s[50:51], s98, v88
	v_cndmask_b32_e64 v36, 0, v36, s[30:31]
	v_add_u32_e32 v85, 64, v84
	v_cmp_gt_u32_e64 s[30:31], s98, v85
	v_cndmask_b32_e64 v37, 0, v37, s[36:37]
	v_add_u32_e32 v86, 68, v84
	v_cmp_gt_u32_e64 s[36:37], s98, v86
	v_cndmask_b32_e64 v38, 0, v38, s[78:79]
	v_add_u32_e32 v87, 72, v84
	v_cmp_gt_u32_e64 s[78:79], s98, v87
	v_cndmask_b32_e64 v39, 0, v39, s[50:51]
	v_add_u32_e32 v88, 76, v84
	v_cmp_gt_u32_e64 s[50:51], s98, v88
	v_cndmask_b32_e64 v40, 0, v40, s[30:31]
	v_add_u32_e32 v85, 96, v84
	v_cmp_gt_u32_e64 s[30:31], s98, v85
	v_cndmask_b32_e64 v41, 0, v41, s[36:37]
	v_add_u32_e32 v86, 100, v84
	v_cmp_gt_u32_e64 s[36:37], s98, v86
	v_cndmask_b32_e64 v42, 0, v42, s[78:79]
	v_add_u32_e32 v87, 104, v84
	v_cmp_gt_u32_e64 s[78:79], s98, v87
	v_cndmask_b32_e64 v43, 0, v43, s[50:51]
	v_add_u32_e32 v88, 108, v84
	v_cmp_gt_u32_e64 s[50:51], s98, v88
	v_nop
	v_cndmask_b32_e64 v44, 0, v44, s[30:31]
	v_cndmask_b32_e64 v45, 0, v45, s[36:37]
	v_cndmask_b32_e64 v46, 0, v46, s[78:79]
	v_cndmask_b32_e64 v47, 0, v47, s[50:51]
	v_cvt_pk_bf16_f32 v64, v32, v33
	v_cvt_pk_bf16_f32 v65, v34, v35
	v_cvt_pk_bf16_f32 v66, v36, v37
	v_cvt_pk_bf16_f32 v67, v38, v39
	v_cvt_pk_bf16_f32 v68, v40, v41
	v_cvt_pk_bf16_f32 v69, v42, v43
	v_cvt_pk_bf16_f32 v70, v44, v45
	v_cvt_pk_bf16_f32 v71, v46, v47
	v_pk_add_f32 v[232:233], v[232:233], v[32:33]
	v_pk_add_f32 v[232:233], v[232:233], v[34:35]
	v_pk_add_f32 v[232:233], v[232:233], v[36:37]
	v_pk_add_f32 v[232:233], v[232:233], v[38:39]
	v_pk_add_f32 v[232:233], v[232:233], v[40:41]
	v_pk_add_f32 v[232:233], v[232:233], v[42:43]
	v_pk_add_f32 v[232:233], v[232:233], v[44:45]
	v_pk_add_f32 v[232:233], v[232:233], v[46:47]
	ds_read2_b32 v[32:33], v115 offset0:192 offset1:193
	ds_read2_b32 v[34:35], v115 offset0:194 offset1:195
	ds_read2_b32 v[36:37], v115 offset0:200 offset1:201
	ds_read2_b32 v[38:39], v115 offset0:202 offset1:203
	ds_read2_b32 v[40:41], v115 offset0:208 offset1:209
	ds_read2_b32 v[42:43], v115 offset0:210 offset1:211
	ds_read2_b32 v[44:45], v115 offset0:216 offset1:217
	ds_read2_b32 v[46:47], v115 offset0:218 offset1:219
	v_mfma_f32_32x32x16_bf16 v[0:15], v[64:67], v[72:75], v[0:15]
	v_mfma_f32_32x32x16_bf16 v[16:31], v[64:67], v[76:79], v[16:31]
	v_mfma_f32_32x32x16_bf16 v[0:15], v[68:71], v[220:223], v[0:15]
	v_mfma_f32_32x32x16_bf16 v[16:31], v[68:71], v[224:227], v[16:31]
	s_add_i32 s90, s67, 640
	v_add_u32_e32 v80, s90, v239
	v_add_u32_e32 v83, s90, v240
	v_add_u32_e32 v99, s90, v241
	v_add_u32_e32 v253, s90, v242
	v_add_u32_e32 v254, s90, v101
	v_add_u32_e32 v255, s90, v150
	v_med3_i32 v80, v80, 0, s99
	v_med3_i32 v83, v83, 0, s99
	v_med3_i32 v99, v99, 0, s99
	v_med3_i32 v253, v253, 0, s99
	v_med3_i32 v254, v254, 0, s99
	v_med3_i32 v255, v255, 0, s99
	v_mad_u32_u24 v80, v80, s100, v252
	v_mad_u32_u24 v83, v83, s100, v252
	v_mad_u32_u24 v99, v99, s100, v252
	v_mad_u32_u24 v253, v253, s100, v252
	v_mad_u32_u24 v254, v254, s100, v153
	v_mad_u32_u24 v255, v255, s100, v153
	global_load_dwordx4 v[156:159], v80, s[82:83]
	global_load_dwordx4 v[160:163], v83, s[82:83]
	global_load_dwordx4 v[164:167], v99, s[82:83]
	global_load_dwordx4 v[168:171], v253, s[82:83]
	global_load_dwordx4 v[172:175], v254, s[82:83] offset:768
	global_load_dwordx4 v[176:179], v255, s[82:83] offset:768
	global_load_dwordx4 v[180:183], v254, s[82:83] offset:832
	global_load_dwordx4 v[184:187], v255, s[82:83] offset:832
	ds_read_b64_tr_b16 v[72:73], v231
	ds_read_b64_tr_b16 v[74:75], v231 offset:512
	ds_read_b64_tr_b16 v[76:77], v231 offset:2048
	ds_read_b64_tr_b16 v[78:79], v231 offset:2560
	ds_read_b64_tr_b16 v[220:221], v231 offset:1024
	ds_read_b64_tr_b16 v[222:223], v231 offset:1536
	ds_read_b64_tr_b16 v[224:225], v231 offset:3072
	ds_read_b64_tr_b16 v[226:227], v231 offset:3584
	s_waitcnt vmcnt(8)
	ds_write_b128 v247, v[116:119]
	ds_write_b128 v247, v[120:123] offset:1024
	ds_write_b128 v247, v[124:127] offset:2048
	ds_write_b128 v247, v[128:131] offset:3072
	ds_read_b128 v[116:119], v248
	ds_read_b128 v[120:123], v249
	ds_read_b128 v[124:127], v250
	ds_read_b128 v[128:131], v251
	ds_write_b128 v112, v[132:135]
	ds_write_b128 v112, v[136:139] offset:1024
	ds_write_b128 v112, v[140:143] offset:2048
	ds_write_b128 v112, v[144:147] offset:3072
	s_waitcnt lgkmcnt(4)
	v_mfma_f32_32x32x16_bf16 v[32:47], v[116:119], v[48:51], v[32:47]
	v_exp_f32_e32 v188, v188
	v_exp_f32_e32 v189, v189
	v_exp_f32_e32 v190, v190
	v_exp_f32_e32 v191, v191
	v_mfma_f32_32x32x16_bf16 v[32:47], v[120:123], v[52:55], v[32:47]
	v_exp_f32_e32 v192, v192
	v_exp_f32_e32 v193, v193
	v_exp_f32_e32 v194, v194
	v_exp_f32_e32 v195, v195
	v_mfma_f32_32x32x16_bf16 v[32:47], v[124:127], v[56:59], v[32:47]
	v_exp_f32_e32 v196, v196
	v_exp_f32_e32 v197, v197
	v_exp_f32_e32 v198, v198
	v_exp_f32_e32 v199, v199
	v_mfma_f32_32x32x16_bf16 v[32:47], v[128:131], v[60:63], v[32:47]
	v_exp_f32_e32 v200, v200
	v_exp_f32_e32 v201, v201
	v_exp_f32_e32 v202, v202
	v_exp_f32_e32 v203, v203
	s_add_i32 s90, s67, 384
	v_lshlrev_b32_e32 v84, 2, v107
	v_add_u32_e32 v84, s90, v84
	v_add_u32_e32 v85, 0, v84
	v_add_u32_e32 v86, 4, v84
	v_add_u32_e32 v87, 8, v84
	v_add_u32_e32 v88, 12, v84
	v_cmp_gt_u32_e64 s[30:31], s98, v85
	v_cmp_gt_u32_e64 s[36:37], s98, v86
	v_cmp_gt_u32_e64 s[78:79], s98, v87
	v_cmp_gt_u32_e64 s[50:51], s98, v88
	v_cndmask_b32_e64 v188, 0, v188, s[30:31]
	v_add_u32_e32 v85, 32, v84
	v_cmp_gt_u32_e64 s[30:31], s98, v85
	v_cndmask_b32_e64 v189, 0, v189, s[36:37]
	v_add_u32_e32 v86, 36, v84
	v_cmp_gt_u32_e64 s[36:37], s98, v86
	v_cndmask_b32_e64 v190, 0, v190, s[78:79]
	v_add_u32_e32 v87, 40, v84
	v_cmp_gt_u32_e64 s[78:79], s98, v87
	v_cndmask_b32_e64 v191, 0, v191, s[50:51]
	v_add_u32_e32 v88, 44, v84
	v_cmp_gt_u32_e64 s[50:51], s98, v88
	v_cndmask_b32_e64 v192, 0, v192, s[30:31]
	v_add_u32_e32 v85, 64, v84
	v_cmp_gt_u32_e64 s[30:31], s98, v85
	v_cndmask_b32_e64 v193, 0, v193, s[36:37]
	v_add_u32_e32 v86, 68, v84
	v_cmp_gt_u32_e64 s[36:37], s98, v86
	v_cndmask_b32_e64 v194, 0, v194, s[78:79]
	v_add_u32_e32 v87, 72, v84
	v_cmp_gt_u32_e64 s[78:79], s98, v87
	v_cndmask_b32_e64 v195, 0, v195, s[50:51]
	v_add_u32_e32 v88, 76, v84
	v_cmp_gt_u32_e64 s[50:51], s98, v88
	v_cndmask_b32_e64 v196, 0, v196, s[30:31]
	v_add_u32_e32 v85, 96, v84
	v_cmp_gt_u32_e64 s[30:31], s98, v85
	v_cndmask_b32_e64 v197, 0, v197, s[36:37]
	v_add_u32_e32 v86, 100, v84
	v_cmp_gt_u32_e64 s[36:37], s98, v86
	v_cndmask_b32_e64 v198, 0, v198, s[78:79]
	v_add_u32_e32 v87, 104, v84
	v_cmp_gt_u32_e64 s[78:79], s98, v87
	v_cndmask_b32_e64 v199, 0, v199, s[50:51]
	v_add_u32_e32 v88, 108, v84
	v_cmp_gt_u32_e64 s[50:51], s98, v88
	v_nop
	v_cndmask_b32_e64 v200, 0, v200, s[30:31]
	v_cndmask_b32_e64 v201, 0, v201, s[36:37]
	v_cndmask_b32_e64 v202, 0, v202, s[78:79]
	v_cndmask_b32_e64 v203, 0, v203, s[50:51]
	v_cvt_pk_bf16_f32 v64, v188, v189
	v_cvt_pk_bf16_f32 v65, v190, v191
	v_cvt_pk_bf16_f32 v66, v192, v193
	v_cvt_pk_bf16_f32 v67, v194, v195
	v_cvt_pk_bf16_f32 v68, v196, v197
	v_cvt_pk_bf16_f32 v69, v198, v199
	v_cvt_pk_bf16_f32 v70, v200, v201
	v_cvt_pk_bf16_f32 v71, v202, v203
	v_pk_add_f32 v[232:233], v[232:233], v[188:189]
	v_pk_add_f32 v[232:233], v[232:233], v[190:191]
	v_pk_add_f32 v[232:233], v[232:233], v[192:193]
	v_pk_add_f32 v[232:233], v[232:233], v[194:195]
	v_pk_add_f32 v[232:233], v[232:233], v[196:197]
	v_pk_add_f32 v[232:233], v[232:233], v[198:199]
	v_pk_add_f32 v[232:233], v[232:233], v[200:201]
	v_pk_add_f32 v[232:233], v[232:233], v[202:203]
	ds_read2_b32 v[188:189], v115 offset0:224 offset1:225
	ds_read2_b32 v[190:191], v115 offset0:226 offset1:227
	ds_read2_b32 v[192:193], v115 offset0:232 offset1:233
	ds_read2_b32 v[194:195], v115 offset0:234 offset1:235
	ds_read2_b32 v[196:197], v115 offset0:240 offset1:241
	ds_read2_b32 v[198:199], v115 offset0:242 offset1:243
	ds_read2_b32 v[200:201], v115 offset0:248 offset1:249
	ds_read2_b32 v[202:203], v115 offset0:250 offset1:251
	v_mfma_f32_32x32x16_bf16 v[0:15], v[64:67], v[72:75], v[0:15]
	v_mfma_f32_32x32x16_bf16 v[16:31], v[64:67], v[76:79], v[16:31]
	v_mfma_f32_32x32x16_bf16 v[0:15], v[68:71], v[220:223], v[0:15]
	v_mfma_f32_32x32x16_bf16 v[16:31], v[68:71], v[224:227], v[16:31]
	s_add_i32 s90, s67, -1024
	v_add_u32_e32 v80, s90, v243
	v_add_u32_e32 v83, s90, v244
	v_add_u32_e32 v99, s90, v245
	v_add_u32_e32 v253, s90, v246
	v_add_u32_e32 v254, s90, v148
	v_add_u32_e32 v255, s90, v151
	v_med3_i32 v80, v80, 0, s99
	v_med3_i32 v83, v83, 0, s99
	v_med3_i32 v99, v99, 0, s99
	v_med3_i32 v253, v253, 0, s99
	v_med3_i32 v254, v254, 0, s99
	v_med3_i32 v255, v255, 0, s99
	v_mad_u32_u24 v80, v80, s100, v252
	v_mad_u32_u24 v83, v83, s100, v252
	v_mad_u32_u24 v99, v99, s100, v252
	v_mad_u32_u24 v253, v253, s100, v252
	v_mad_u32_u24 v254, v254, s100, v153
	v_mad_u32_u24 v255, v255, s100, v153
	global_load_dwordx4 v[116:119], v80, s[82:83]
	global_load_dwordx4 v[120:123], v83, s[82:83]
	global_load_dwordx4 v[124:127], v99, s[82:83]
	global_load_dwordx4 v[128:131], v253, s[82:83]
	global_load_dwordx4 v[132:135], v254, s[82:83] offset:768
	global_load_dwordx4 v[136:139], v255, s[82:83] offset:768
	global_load_dwordx4 v[140:143], v254, s[82:83] offset:832
	global_load_dwordx4 v[144:147], v255, s[82:83] offset:832
	ds_read_b64_tr_b16 v[72:73], v231
	ds_read_b64_tr_b16 v[74:75], v231 offset:512
	ds_read_b64_tr_b16 v[76:77], v231 offset:2048
	ds_read_b64_tr_b16 v[78:79], v231 offset:2560
	ds_read_b64_tr_b16 v[220:221], v231 offset:1024
	ds_read_b64_tr_b16 v[222:223], v231 offset:1536
	ds_read_b64_tr_b16 v[224:225], v231 offset:3072
	ds_read_b64_tr_b16 v[226:227], v231 offset:3584
	s_waitcnt vmcnt(8)
	ds_write_b128 v247, v[156:159]
	ds_write_b128 v247, v[160:163] offset:1024
	ds_write_b128 v247, v[164:167] offset:2048
	ds_write_b128 v247, v[168:171] offset:3072
	ds_read_b128 v[156:159], v248
	ds_read_b128 v[160:163], v249
	ds_read_b128 v[164:167], v250
	ds_read_b128 v[168:171], v251
	ds_write_b128 v112, v[172:175]
	ds_write_b128 v112, v[176:179] offset:1024
	ds_write_b128 v112, v[180:183] offset:2048
	ds_write_b128 v112, v[184:187] offset:3072
	s_waitcnt lgkmcnt(4)
	v_mfma_f32_32x32x16_bf16 v[188:203], v[156:159], v[48:51], v[188:203]
	v_exp_f32_e32 v32, v32
	v_exp_f32_e32 v33, v33
	v_exp_f32_e32 v34, v34
	v_exp_f32_e32 v35, v35
	v_mfma_f32_32x32x16_bf16 v[188:203], v[160:163], v[52:55], v[188:203]
	v_exp_f32_e32 v36, v36
	v_exp_f32_e32 v37, v37
	v_exp_f32_e32 v38, v38
	v_exp_f32_e32 v39, v39
	v_mfma_f32_32x32x16_bf16 v[188:203], v[164:167], v[56:59], v[188:203]
	v_exp_f32_e32 v40, v40
	v_exp_f32_e32 v41, v41
	v_exp_f32_e32 v42, v42
	v_exp_f32_e32 v43, v43
	v_mfma_f32_32x32x16_bf16 v[188:203], v[168:171], v[60:63], v[188:203]
	v_exp_f32_e32 v44, v44
	v_exp_f32_e32 v45, v45
	v_exp_f32_e32 v46, v46
	v_exp_f32_e32 v47, v47
	s_add_i32 s90, s67, 512
	v_lshlrev_b32_e32 v84, 2, v107
	v_add_u32_e32 v84, s90, v84
	v_add_u32_e32 v85, 0, v84
	v_add_u32_e32 v86, 4, v84
	v_add_u32_e32 v87, 8, v84
	v_add_u32_e32 v88, 12, v84
	v_cmp_gt_u32_e64 s[30:31], s98, v85
	v_cmp_gt_u32_e64 s[36:37], s98, v86
	v_cmp_gt_u32_e64 s[78:79], s98, v87
	v_cmp_gt_u32_e64 s[50:51], s98, v88
	v_cndmask_b32_e64 v32, 0, v32, s[30:31]
	v_add_u32_e32 v85, 32, v84
	v_cmp_gt_u32_e64 s[30:31], s98, v85
	v_cndmask_b32_e64 v33, 0, v33, s[36:37]
	v_add_u32_e32 v86, 36, v84
	v_cmp_gt_u32_e64 s[36:37], s98, v86
	v_cndmask_b32_e64 v34, 0, v34, s[78:79]
	v_add_u32_e32 v87, 40, v84
	v_cmp_gt_u32_e64 s[78:79], s98, v87
	v_cndmask_b32_e64 v35, 0, v35, s[50:51]
	v_add_u32_e32 v88, 44, v84
	v_cmp_gt_u32_e64 s[50:51], s98, v88
	v_cndmask_b32_e64 v36, 0, v36, s[30:31]
	v_add_u32_e32 v85, 64, v84
	v_cmp_gt_u32_e64 s[30:31], s98, v85
	v_cndmask_b32_e64 v37, 0, v37, s[36:37]
	v_add_u32_e32 v86, 68, v84
	v_cmp_gt_u32_e64 s[36:37], s98, v86
	v_cndmask_b32_e64 v38, 0, v38, s[78:79]
	v_add_u32_e32 v87, 72, v84
	v_cmp_gt_u32_e64 s[78:79], s98, v87
	v_cndmask_b32_e64 v39, 0, v39, s[50:51]
	v_add_u32_e32 v88, 76, v84
	v_cmp_gt_u32_e64 s[50:51], s98, v88
	v_cndmask_b32_e64 v40, 0, v40, s[30:31]
	v_add_u32_e32 v85, 96, v84
	v_cmp_gt_u32_e64 s[30:31], s98, v85
	v_cndmask_b32_e64 v41, 0, v41, s[36:37]
	v_add_u32_e32 v86, 100, v84
	v_cmp_gt_u32_e64 s[36:37], s98, v86
	v_cndmask_b32_e64 v42, 0, v42, s[78:79]
	v_add_u32_e32 v87, 104, v84
	v_cmp_gt_u32_e64 s[78:79], s98, v87
	v_cndmask_b32_e64 v43, 0, v43, s[50:51]
	v_add_u32_e32 v88, 108, v84
	v_cmp_gt_u32_e64 s[50:51], s98, v88
	v_nop
	v_cndmask_b32_e64 v44, 0, v44, s[30:31]
	v_cndmask_b32_e64 v45, 0, v45, s[36:37]
	v_cndmask_b32_e64 v46, 0, v46, s[78:79]
	v_cndmask_b32_e64 v47, 0, v47, s[50:51]
	v_cvt_pk_bf16_f32 v64, v32, v33
	v_cvt_pk_bf16_f32 v65, v34, v35
	v_cvt_pk_bf16_f32 v66, v36, v37
	v_cvt_pk_bf16_f32 v67, v38, v39
	v_cvt_pk_bf16_f32 v68, v40, v41
	v_cvt_pk_bf16_f32 v69, v42, v43
	v_cvt_pk_bf16_f32 v70, v44, v45
	v_cvt_pk_bf16_f32 v71, v46, v47
	v_pk_add_f32 v[232:233], v[232:233], v[32:33]
	v_pk_add_f32 v[232:233], v[232:233], v[34:35]
	v_pk_add_f32 v[232:233], v[232:233], v[36:37]
	v_pk_add_f32 v[232:233], v[232:233], v[38:39]
	v_pk_add_f32 v[232:233], v[232:233], v[40:41]
	v_pk_add_f32 v[232:233], v[232:233], v[42:43]
	v_pk_add_f32 v[232:233], v[232:233], v[44:45]
	v_pk_add_f32 v[232:233], v[232:233], v[46:47]
	v_mov_b32_e32 v115, v230
	ds_read2_b32 v[32:33], v115 offset0:0 offset1:1
	ds_read2_b32 v[34:35], v115 offset0:2 offset1:3
	ds_read2_b32 v[36:37], v115 offset0:8 offset1:9
	ds_read2_b32 v[38:39], v115 offset0:10 offset1:11
	ds_read2_b32 v[40:41], v115 offset0:16 offset1:17
	ds_read2_b32 v[42:43], v115 offset0:18 offset1:19
	ds_read2_b32 v[44:45], v115 offset0:24 offset1:25
	ds_read2_b32 v[46:47], v115 offset0:26 offset1:27
	v_mfma_f32_32x32x16_bf16 v[0:15], v[64:67], v[72:75], v[0:15]
	v_mfma_f32_32x32x16_bf16 v[16:31], v[64:67], v[76:79], v[16:31]
	v_mfma_f32_32x32x16_bf16 v[0:15], v[68:71], v[220:223], v[0:15]
	v_mfma_f32_32x32x16_bf16 v[16:31], v[68:71], v[224:227], v[16:31]
	s_add_i32 s90, s67, -512
	v_add_u32_e32 v80, s90, v243
	v_add_u32_e32 v83, s90, v244
	v_add_u32_e32 v99, s90, v245
	v_add_u32_e32 v253, s90, v246
	v_add_u32_e32 v254, s90, v148
	v_add_u32_e32 v255, s90, v151
	v_med3_i32 v80, v80, 0, s99
	v_med3_i32 v83, v83, 0, s99
	v_med3_i32 v99, v99, 0, s99
	v_med3_i32 v253, v253, 0, s99
	v_med3_i32 v254, v254, 0, s99
	v_med3_i32 v255, v255, 0, s99
	v_mad_u32_u24 v80, v80, s100, v252
	v_mad_u32_u24 v83, v83, s100, v252
	v_mad_u32_u24 v99, v99, s100, v252
	v_mad_u32_u24 v253, v253, s100, v252
	v_mad_u32_u24 v254, v254, s100, v153
	v_mad_u32_u24 v255, v255, s100, v153
	global_load_dwordx4 v[156:159], v80, s[82:83]
	global_load_dwordx4 v[160:163], v83, s[82:83]
	global_load_dwordx4 v[164:167], v99, s[82:83]
	global_load_dwordx4 v[168:171], v253, s[82:83]
	global_load_dwordx4 v[172:175], v254, s[82:83] offset:768
	global_load_dwordx4 v[176:179], v255, s[82:83] offset:768
	global_load_dwordx4 v[180:183], v254, s[82:83] offset:832
	global_load_dwordx4 v[184:187], v255, s[82:83] offset:832
	ds_read_b64_tr_b16 v[72:73], v231
	ds_read_b64_tr_b16 v[74:75], v231 offset:512
	ds_read_b64_tr_b16 v[76:77], v231 offset:2048
	ds_read_b64_tr_b16 v[78:79], v231 offset:2560
	ds_read_b64_tr_b16 v[220:221], v231 offset:1024
	ds_read_b64_tr_b16 v[222:223], v231 offset:1536
	ds_read_b64_tr_b16 v[224:225], v231 offset:3072
	ds_read_b64_tr_b16 v[226:227], v231 offset:3584
	s_waitcnt vmcnt(8)
	ds_write_b128 v247, v[116:119]
	ds_write_b128 v247, v[120:123] offset:1024
	ds_write_b128 v247, v[124:127] offset:2048
	ds_write_b128 v247, v[128:131] offset:3072
	ds_read_b128 v[116:119], v248
	ds_read_b128 v[120:123], v249
	ds_read_b128 v[124:127], v250
	ds_read_b128 v[128:131], v251
	ds_write_b128 v112, v[132:135]
	ds_write_b128 v112, v[136:139] offset:1024
	ds_write_b128 v112, v[140:143] offset:2048
	ds_write_b128 v112, v[144:147] offset:3072
	s_waitcnt lgkmcnt(4)
	v_mfma_f32_32x32x16_bf16 v[32:47], v[116:119], v[48:51], v[32:47]
	v_exp_f32_e32 v188, v188
	v_exp_f32_e32 v189, v189
	v_exp_f32_e32 v190, v190
	v_exp_f32_e32 v191, v191
	v_mfma_f32_32x32x16_bf16 v[32:47], v[120:123], v[52:55], v[32:47]
	v_exp_f32_e32 v192, v192
	v_exp_f32_e32 v193, v193
	v_exp_f32_e32 v194, v194
	v_exp_f32_e32 v195, v195
	v_mfma_f32_32x32x16_bf16 v[32:47], v[124:127], v[56:59], v[32:47]
	v_exp_f32_e32 v196, v196
	v_exp_f32_e32 v197, v197
	v_exp_f32_e32 v198, v198
	v_exp_f32_e32 v199, v199
	v_mfma_f32_32x32x16_bf16 v[32:47], v[128:131], v[60:63], v[32:47]
	v_exp_f32_e32 v200, v200
	v_exp_f32_e32 v201, v201
	v_exp_f32_e32 v202, v202
	v_exp_f32_e32 v203, v203
	s_add_i32 s90, s67, 640
	v_lshlrev_b32_e32 v84, 2, v107
	v_add_u32_e32 v84, s90, v84
	v_add_u32_e32 v85, 0, v84
	v_add_u32_e32 v86, 4, v84
	v_add_u32_e32 v87, 8, v84
	v_add_u32_e32 v88, 12, v84
	v_cmp_gt_u32_e64 s[30:31], s98, v85
	v_cmp_gt_u32_e64 s[36:37], s98, v86
	v_cmp_gt_u32_e64 s[78:79], s98, v87
	v_cmp_gt_u32_e64 s[50:51], s98, v88
	v_cndmask_b32_e64 v188, 0, v188, s[30:31]
	v_add_u32_e32 v85, 32, v84
	v_cmp_gt_u32_e64 s[30:31], s98, v85
	v_cndmask_b32_e64 v189, 0, v189, s[36:37]
	v_add_u32_e32 v86, 36, v84
	v_cmp_gt_u32_e64 s[36:37], s98, v86
	v_cndmask_b32_e64 v190, 0, v190, s[78:79]
	v_add_u32_e32 v87, 40, v84
	v_cmp_gt_u32_e64 s[78:79], s98, v87
	v_cndmask_b32_e64 v191, 0, v191, s[50:51]
	v_add_u32_e32 v88, 44, v84
	v_cmp_gt_u32_e64 s[50:51], s98, v88
	v_cndmask_b32_e64 v192, 0, v192, s[30:31]
	v_add_u32_e32 v85, 64, v84
	v_cmp_gt_u32_e64 s[30:31], s98, v85
	v_cndmask_b32_e64 v193, 0, v193, s[36:37]
	v_add_u32_e32 v86, 68, v84
	v_cmp_gt_u32_e64 s[36:37], s98, v86
	v_cndmask_b32_e64 v194, 0, v194, s[78:79]
	v_add_u32_e32 v87, 72, v84
	v_cmp_gt_u32_e64 s[78:79], s98, v87
	v_cndmask_b32_e64 v195, 0, v195, s[50:51]
	v_add_u32_e32 v88, 76, v84
	v_cmp_gt_u32_e64 s[50:51], s98, v88
	v_cndmask_b32_e64 v196, 0, v196, s[30:31]
	v_add_u32_e32 v85, 96, v84
	v_cmp_gt_u32_e64 s[30:31], s98, v85
	v_cndmask_b32_e64 v197, 0, v197, s[36:37]
	v_add_u32_e32 v86, 100, v84
	v_cmp_gt_u32_e64 s[36:37], s98, v86
	v_cndmask_b32_e64 v198, 0, v198, s[78:79]
	v_add_u32_e32 v87, 104, v84
	v_cmp_gt_u32_e64 s[78:79], s98, v87
	v_cndmask_b32_e64 v199, 0, v199, s[50:51]
	v_add_u32_e32 v88, 108, v84
	v_cmp_gt_u32_e64 s[50:51], s98, v88
	v_nop
	v_cndmask_b32_e64 v200, 0, v200, s[30:31]
	v_cndmask_b32_e64 v201, 0, v201, s[36:37]
	v_cndmask_b32_e64 v202, 0, v202, s[78:79]
	v_cndmask_b32_e64 v203, 0, v203, s[50:51]
	v_cvt_pk_bf16_f32 v64, v188, v189
	v_cvt_pk_bf16_f32 v65, v190, v191
	v_cvt_pk_bf16_f32 v66, v192, v193
	v_cvt_pk_bf16_f32 v67, v194, v195
	v_cvt_pk_bf16_f32 v68, v196, v197
	v_cvt_pk_bf16_f32 v69, v198, v199
	v_cvt_pk_bf16_f32 v70, v200, v201
	v_cvt_pk_bf16_f32 v71, v202, v203
	v_pk_add_f32 v[232:233], v[232:233], v[188:189]
	v_pk_add_f32 v[232:233], v[232:233], v[190:191]
	v_pk_add_f32 v[232:233], v[232:233], v[192:193]
	v_pk_add_f32 v[232:233], v[232:233], v[194:195]
	v_pk_add_f32 v[232:233], v[232:233], v[196:197]
	v_pk_add_f32 v[232:233], v[232:233], v[198:199]
	v_pk_add_f32 v[232:233], v[232:233], v[200:201]
	v_pk_add_f32 v[232:233], v[232:233], v[202:203]
	ds_read2_b32 v[188:189], v115 offset0:32 offset1:33
	ds_read2_b32 v[190:191], v115 offset0:34 offset1:35
	ds_read2_b32 v[192:193], v115 offset0:40 offset1:41
	ds_read2_b32 v[194:195], v115 offset0:42 offset1:43
	ds_read2_b32 v[196:197], v115 offset0:48 offset1:49
	ds_read2_b32 v[198:199], v115 offset0:50 offset1:51
	ds_read2_b32 v[200:201], v115 offset0:56 offset1:57
	ds_read2_b32 v[202:203], v115 offset0:58 offset1:59
	v_mfma_f32_32x32x16_bf16 v[0:15], v[64:67], v[72:75], v[0:15]
	v_mfma_f32_32x32x16_bf16 v[16:31], v[64:67], v[76:79], v[16:31]
	v_mfma_f32_32x32x16_bf16 v[0:15], v[68:71], v[220:223], v[0:15]
	v_mfma_f32_32x32x16_bf16 v[16:31], v[68:71], v[224:227], v[16:31]
	s_add_i32 s90, s67, 0
	v_add_u32_e32 v80, s90, v243
	v_add_u32_e32 v83, s90, v244
	v_add_u32_e32 v99, s90, v245
	v_add_u32_e32 v253, s90, v246
	v_add_u32_e32 v254, s90, v148
	v_add_u32_e32 v255, s90, v151
	v_med3_i32 v80, v80, 0, s99
	v_med3_i32 v83, v83, 0, s99
	v_med3_i32 v99, v99, 0, s99
	v_med3_i32 v253, v253, 0, s99
	v_med3_i32 v254, v254, 0, s99
	v_med3_i32 v255, v255, 0, s99
	v_mad_u32_u24 v80, v80, s100, v252
	v_mad_u32_u24 v83, v83, s100, v252
	v_mad_u32_u24 v99, v99, s100, v252
	v_mad_u32_u24 v253, v253, s100, v252
	v_mad_u32_u24 v254, v254, s100, v153
	v_mad_u32_u24 v255, v255, s100, v153
	global_load_dwordx4 v[116:119], v80, s[82:83]
	global_load_dwordx4 v[120:123], v83, s[82:83]
	global_load_dwordx4 v[124:127], v99, s[82:83]
	global_load_dwordx4 v[128:131], v253, s[82:83]
	global_load_dwordx4 v[132:135], v254, s[82:83] offset:768
	global_load_dwordx4 v[136:139], v255, s[82:83] offset:768
	global_load_dwordx4 v[140:143], v254, s[82:83] offset:832
	global_load_dwordx4 v[144:147], v255, s[82:83] offset:832
	ds_read_b64_tr_b16 v[72:73], v231
	ds_read_b64_tr_b16 v[74:75], v231 offset:512
	ds_read_b64_tr_b16 v[76:77], v231 offset:2048
	ds_read_b64_tr_b16 v[78:79], v231 offset:2560
	ds_read_b64_tr_b16 v[220:221], v231 offset:1024
	ds_read_b64_tr_b16 v[222:223], v231 offset:1536
	ds_read_b64_tr_b16 v[224:225], v231 offset:3072
	ds_read_b64_tr_b16 v[226:227], v231 offset:3584
	s_waitcnt vmcnt(8)
	ds_write_b128 v247, v[156:159]
	ds_write_b128 v247, v[160:163] offset:1024
	ds_write_b128 v247, v[164:167] offset:2048
	ds_write_b128 v247, v[168:171] offset:3072
	ds_read_b128 v[156:159], v248
	ds_read_b128 v[160:163], v249
	ds_read_b128 v[164:167], v250
	ds_read_b128 v[168:171], v251
	ds_write_b128 v112, v[172:175]
	ds_write_b128 v112, v[176:179] offset:1024
	ds_write_b128 v112, v[180:183] offset:2048
	ds_write_b128 v112, v[184:187] offset:3072
	s_waitcnt lgkmcnt(4)
	v_mfma_f32_32x32x16_bf16 v[188:203], v[156:159], v[48:51], v[188:203]
	v_exp_f32_e32 v32, v32
	v_exp_f32_e32 v33, v33
	v_exp_f32_e32 v34, v34
	v_exp_f32_e32 v35, v35
	v_mfma_f32_32x32x16_bf16 v[188:203], v[160:163], v[52:55], v[188:203]
	v_exp_f32_e32 v36, v36
	v_exp_f32_e32 v37, v37
	v_exp_f32_e32 v38, v38
	v_exp_f32_e32 v39, v39
	v_mfma_f32_32x32x16_bf16 v[188:203], v[164:167], v[56:59], v[188:203]
	v_exp_f32_e32 v40, v40
	v_exp_f32_e32 v41, v41
	v_exp_f32_e32 v42, v42
	v_exp_f32_e32 v43, v43
	v_mfma_f32_32x32x16_bf16 v[188:203], v[168:171], v[60:63], v[188:203]
	v_exp_f32_e32 v44, v44
	v_exp_f32_e32 v45, v45
	v_exp_f32_e32 v46, v46
	v_exp_f32_e32 v47, v47
	s_add_i32 s90, s67, -1024
	v_lshlrev_b32_e32 v84, 4, v107
	v_add_u32_e32 v84, s90, v84
	v_add_u32_e32 v85, 0, v84
	v_add_u32_e32 v86, 16, v84
	v_add_u32_e32 v87, 32, v84
	v_add_u32_e32 v88, 48, v84
	v_cmp_gt_u32_e64 s[30:31], s98, v85
	v_cmp_gt_u32_e64 s[36:37], s98, v86
	v_cmp_gt_u32_e64 s[78:79], s98, v87
	v_cmp_gt_u32_e64 s[50:51], s98, v88
	v_cndmask_b32_e64 v32, 0, v32, s[30:31]
	v_add_u32_e32 v85, 128, v84
	v_cmp_gt_u32_e64 s[30:31], s98, v85
	v_cndmask_b32_e64 v33, 0, v33, s[36:37]
	v_add_u32_e32 v86, 144, v84
	v_cmp_gt_u32_e64 s[36:37], s98, v86
	v_cndmask_b32_e64 v34, 0, v34, s[78:79]
	v_add_u32_e32 v87, 160, v84
	v_cmp_gt_u32_e64 s[78:79], s98, v87
	v_cndmask_b32_e64 v35, 0, v35, s[50:51]
	v_add_u32_e32 v88, 176, v84
	v_cmp_gt_u32_e64 s[50:51], s98, v88
	v_cndmask_b32_e64 v36, 0, v36, s[30:31]
	v_add_u32_e32 v85, 256, v84
	v_cmp_gt_u32_e64 s[30:31], s98, v85
	v_cndmask_b32_e64 v37, 0, v37, s[36:37]
	v_add_u32_e32 v86, 272, v84
	v_cmp_gt_u32_e64 s[36:37], s98, v86
	v_cndmask_b32_e64 v38, 0, v38, s[78:79]
	v_add_u32_e32 v87, 288, v84
	v_cmp_gt_u32_e64 s[78:79], s98, v87
	v_cndmask_b32_e64 v39, 0, v39, s[50:51]
	v_add_u32_e32 v88, 304, v84
	v_cmp_gt_u32_e64 s[50:51], s98, v88
	v_cndmask_b32_e64 v40, 0, v40, s[30:31]
	v_add_u32_e32 v85, 384, v84
	v_cmp_gt_u32_e64 s[30:31], s98, v85
	v_cndmask_b32_e64 v41, 0, v41, s[36:37]
	v_add_u32_e32 v86, 400, v84
	v_cmp_gt_u32_e64 s[36:37], s98, v86
	v_cndmask_b32_e64 v42, 0, v42, s[78:79]
	v_add_u32_e32 v87, 416, v84
	v_cmp_gt_u32_e64 s[78:79], s98, v87
	v_cndmask_b32_e64 v43, 0, v43, s[50:51]
	v_add_u32_e32 v88, 432, v84
	v_cmp_gt_u32_e64 s[50:51], s98, v88
	v_nop
	v_cndmask_b32_e64 v44, 0, v44, s[30:31]
	v_cndmask_b32_e64 v45, 0, v45, s[36:37]
	v_cndmask_b32_e64 v46, 0, v46, s[78:79]
	v_cndmask_b32_e64 v47, 0, v47, s[50:51]
	v_cvt_pk_bf16_f32 v64, v32, v33
	v_cvt_pk_bf16_f32 v65, v34, v35
	v_cvt_pk_bf16_f32 v66, v36, v37
	v_cvt_pk_bf16_f32 v67, v38, v39
	v_cvt_pk_bf16_f32 v68, v40, v41
	v_cvt_pk_bf16_f32 v69, v42, v43
	v_cvt_pk_bf16_f32 v70, v44, v45
	v_cvt_pk_bf16_f32 v71, v46, v47
	v_pk_add_f32 v[232:233], v[232:233], v[32:33]
	v_pk_add_f32 v[232:233], v[232:233], v[34:35]
	v_pk_add_f32 v[232:233], v[232:233], v[36:37]
	v_pk_add_f32 v[232:233], v[232:233], v[38:39]
	v_pk_add_f32 v[232:233], v[232:233], v[40:41]
	v_pk_add_f32 v[232:233], v[232:233], v[42:43]
	v_pk_add_f32 v[232:233], v[232:233], v[44:45]
	v_pk_add_f32 v[232:233], v[232:233], v[46:47]
	ds_read2_b32 v[32:33], v115 offset0:64 offset1:65
	ds_read2_b32 v[34:35], v115 offset0:66 offset1:67
	ds_read2_b32 v[36:37], v115 offset0:72 offset1:73
	ds_read2_b32 v[38:39], v115 offset0:74 offset1:75
	ds_read2_b32 v[40:41], v115 offset0:80 offset1:81
	ds_read2_b32 v[42:43], v115 offset0:82 offset1:83
	ds_read2_b32 v[44:45], v115 offset0:88 offset1:89
	ds_read2_b32 v[46:47], v115 offset0:90 offset1:91
	v_mfma_f32_32x32x16_bf16 v[0:15], v[64:67], v[72:75], v[0:15]
	v_mfma_f32_32x32x16_bf16 v[16:31], v[64:67], v[76:79], v[16:31]
	v_mfma_f32_32x32x16_bf16 v[0:15], v[68:71], v[220:223], v[0:15]
	v_mfma_f32_32x32x16_bf16 v[16:31], v[68:71], v[224:227], v[16:31]
	s_add_i32 s90, s67, 512
	v_add_u32_e32 v80, s90, v243
	v_add_u32_e32 v83, s90, v244
	v_add_u32_e32 v99, s90, v245
	v_add_u32_e32 v253, s90, v246
	v_add_u32_e32 v254, s90, v148
	v_add_u32_e32 v255, s90, v151
	v_med3_i32 v80, v80, 0, s99
	v_med3_i32 v83, v83, 0, s99
	v_med3_i32 v99, v99, 0, s99
	v_med3_i32 v253, v253, 0, s99
	v_med3_i32 v254, v254, 0, s99
	v_med3_i32 v255, v255, 0, s99
	v_mad_u32_u24 v80, v80, s100, v252
	v_mad_u32_u24 v83, v83, s100, v252
	v_mad_u32_u24 v99, v99, s100, v252
	v_mad_u32_u24 v253, v253, s100, v252
	v_mad_u32_u24 v254, v254, s100, v153
	v_mad_u32_u24 v255, v255, s100, v153
	global_load_dwordx4 v[156:159], v80, s[82:83]
	global_load_dwordx4 v[160:163], v83, s[82:83]
	global_load_dwordx4 v[164:167], v99, s[82:83]
	global_load_dwordx4 v[168:171], v253, s[82:83]
	global_load_dwordx4 v[172:175], v254, s[82:83] offset:768
	global_load_dwordx4 v[176:179], v255, s[82:83] offset:768
	global_load_dwordx4 v[180:183], v254, s[82:83] offset:832
	global_load_dwordx4 v[184:187], v255, s[82:83] offset:832
	ds_read_b64_tr_b16 v[72:73], v231
	ds_read_b64_tr_b16 v[74:75], v231 offset:512
	ds_read_b64_tr_b16 v[76:77], v231 offset:2048
	ds_read_b64_tr_b16 v[78:79], v231 offset:2560
	ds_read_b64_tr_b16 v[220:221], v231 offset:1024
	ds_read_b64_tr_b16 v[222:223], v231 offset:1536
	ds_read_b64_tr_b16 v[224:225], v231 offset:3072
	ds_read_b64_tr_b16 v[226:227], v231 offset:3584
	s_waitcnt vmcnt(8)
	ds_write_b128 v247, v[116:119]
	ds_write_b128 v247, v[120:123] offset:1024
	ds_write_b128 v247, v[124:127] offset:2048
	ds_write_b128 v247, v[128:131] offset:3072
	ds_read_b128 v[116:119], v248
	ds_read_b128 v[120:123], v249
	ds_read_b128 v[124:127], v250
	ds_read_b128 v[128:131], v251
	ds_write_b128 v112, v[132:135]
	ds_write_b128 v112, v[136:139] offset:1024
	ds_write_b128 v112, v[140:143] offset:2048
	ds_write_b128 v112, v[144:147] offset:3072
	s_waitcnt lgkmcnt(4)
	v_mfma_f32_32x32x16_bf16 v[32:47], v[116:119], v[48:51], v[32:47]
	v_exp_f32_e32 v188, v188
	v_exp_f32_e32 v189, v189
	v_exp_f32_e32 v190, v190
	v_exp_f32_e32 v191, v191
	v_mfma_f32_32x32x16_bf16 v[32:47], v[120:123], v[52:55], v[32:47]
	v_exp_f32_e32 v192, v192
	v_exp_f32_e32 v193, v193
	v_exp_f32_e32 v194, v194
	v_exp_f32_e32 v195, v195
	v_mfma_f32_32x32x16_bf16 v[32:47], v[124:127], v[56:59], v[32:47]
	v_exp_f32_e32 v196, v196
	v_exp_f32_e32 v197, v197
	v_exp_f32_e32 v198, v198
	v_exp_f32_e32 v199, v199
	v_mfma_f32_32x32x16_bf16 v[32:47], v[128:131], v[60:63], v[32:47]
	v_exp_f32_e32 v200, v200
	v_exp_f32_e32 v201, v201
	v_exp_f32_e32 v202, v202
	v_exp_f32_e32 v203, v203
	s_add_i32 s90, s67, -512
	v_lshlrev_b32_e32 v84, 4, v107
	v_add_u32_e32 v84, s90, v84
	v_add_u32_e32 v85, 0, v84
	v_add_u32_e32 v86, 16, v84
	v_add_u32_e32 v87, 32, v84
	v_add_u32_e32 v88, 48, v84
	v_cmp_gt_u32_e64 s[30:31], s98, v85
	v_cmp_gt_u32_e64 s[36:37], s98, v86
	v_cmp_gt_u32_e64 s[78:79], s98, v87
	v_cmp_gt_u32_e64 s[50:51], s98, v88
	v_cndmask_b32_e64 v188, 0, v188, s[30:31]
	v_add_u32_e32 v85, 128, v84
	v_cmp_gt_u32_e64 s[30:31], s98, v85
	v_cndmask_b32_e64 v189, 0, v189, s[36:37]
	v_add_u32_e32 v86, 144, v84
	v_cmp_gt_u32_e64 s[36:37], s98, v86
	v_cndmask_b32_e64 v190, 0, v190, s[78:79]
	v_add_u32_e32 v87, 160, v84
	v_cmp_gt_u32_e64 s[78:79], s98, v87
	v_cndmask_b32_e64 v191, 0, v191, s[50:51]
	v_add_u32_e32 v88, 176, v84
	v_cmp_gt_u32_e64 s[50:51], s98, v88
	v_cndmask_b32_e64 v192, 0, v192, s[30:31]
	v_add_u32_e32 v85, 256, v84
	v_cmp_gt_u32_e64 s[30:31], s98, v85
	v_cndmask_b32_e64 v193, 0, v193, s[36:37]
	v_add_u32_e32 v86, 272, v84
	v_cmp_gt_u32_e64 s[36:37], s98, v86
	v_cndmask_b32_e64 v194, 0, v194, s[78:79]
	v_add_u32_e32 v87, 288, v84
	v_cmp_gt_u32_e64 s[78:79], s98, v87
	v_cndmask_b32_e64 v195, 0, v195, s[50:51]
	v_add_u32_e32 v88, 304, v84
	v_cmp_gt_u32_e64 s[50:51], s98, v88
	v_cndmask_b32_e64 v196, 0, v196, s[30:31]
	v_add_u32_e32 v85, 384, v84
	v_cmp_gt_u32_e64 s[30:31], s98, v85
	v_cndmask_b32_e64 v197, 0, v197, s[36:37]
	v_add_u32_e32 v86, 400, v84
	v_cmp_gt_u32_e64 s[36:37], s98, v86
	v_cndmask_b32_e64 v198, 0, v198, s[78:79]
	v_add_u32_e32 v87, 416, v84
	v_cmp_gt_u32_e64 s[78:79], s98, v87
	v_cndmask_b32_e64 v199, 0, v199, s[50:51]
	v_add_u32_e32 v88, 432, v84
	v_cmp_gt_u32_e64 s[50:51], s98, v88
	v_nop
	v_cndmask_b32_e64 v200, 0, v200, s[30:31]
	v_cndmask_b32_e64 v201, 0, v201, s[36:37]
	v_cndmask_b32_e64 v202, 0, v202, s[78:79]
	v_cndmask_b32_e64 v203, 0, v203, s[50:51]
	v_cvt_pk_bf16_f32 v64, v188, v189
	v_cvt_pk_bf16_f32 v65, v190, v191
	v_cvt_pk_bf16_f32 v66, v192, v193
	v_cvt_pk_bf16_f32 v67, v194, v195
	v_cvt_pk_bf16_f32 v68, v196, v197
	v_cvt_pk_bf16_f32 v69, v198, v199
	v_cvt_pk_bf16_f32 v70, v200, v201
	v_cvt_pk_bf16_f32 v71, v202, v203
	v_pk_add_f32 v[232:233], v[232:233], v[188:189]
	v_pk_add_f32 v[232:233], v[232:233], v[190:191]
	v_pk_add_f32 v[232:233], v[232:233], v[192:193]
	v_pk_add_f32 v[232:233], v[232:233], v[194:195]
	v_pk_add_f32 v[232:233], v[232:233], v[196:197]
	v_pk_add_f32 v[232:233], v[232:233], v[198:199]
	v_pk_add_f32 v[232:233], v[232:233], v[200:201]
	v_pk_add_f32 v[232:233], v[232:233], v[202:203]
	ds_read2_b32 v[188:189], v115 offset0:96 offset1:97
	ds_read2_b32 v[190:191], v115 offset0:98 offset1:99
	ds_read2_b32 v[192:193], v115 offset0:104 offset1:105
	ds_read2_b32 v[194:195], v115 offset0:106 offset1:107
	ds_read2_b32 v[196:197], v115 offset0:112 offset1:113
	ds_read2_b32 v[198:199], v115 offset0:114 offset1:115
	ds_read2_b32 v[200:201], v115 offset0:120 offset1:121
	ds_read2_b32 v[202:203], v115 offset0:122 offset1:123
	v_mfma_f32_32x32x16_bf16 v[0:15], v[64:67], v[72:75], v[0:15]
	v_mfma_f32_32x32x16_bf16 v[16:31], v[64:67], v[76:79], v[16:31]
	v_mfma_f32_32x32x16_bf16 v[0:15], v[68:71], v[220:223], v[0:15]
	v_mfma_f32_32x32x16_bf16 v[16:31], v[68:71], v[224:227], v[16:31]
	s_add_i32 s90, s67, 1024
	v_add_u32_e32 v80, s90, v243
	v_add_u32_e32 v83, s90, v244
	v_add_u32_e32 v99, s90, v245
	v_add_u32_e32 v253, s90, v246
	v_add_u32_e32 v254, s90, v148
	v_add_u32_e32 v255, s90, v151
	v_med3_i32 v80, v80, 0, s99
	v_med3_i32 v83, v83, 0, s99
	v_med3_i32 v99, v99, 0, s99
	v_med3_i32 v253, v253, 0, s99
	v_med3_i32 v254, v254, 0, s99
	v_med3_i32 v255, v255, 0, s99
	v_mad_u32_u24 v80, v80, s100, v252
	v_mad_u32_u24 v83, v83, s100, v252
	v_mad_u32_u24 v99, v99, s100, v252
	v_mad_u32_u24 v253, v253, s100, v252
	v_mad_u32_u24 v254, v254, s100, v153
	v_mad_u32_u24 v255, v255, s100, v153
	global_load_dwordx4 v[116:119], v80, s[82:83]
	global_load_dwordx4 v[120:123], v83, s[82:83]
	global_load_dwordx4 v[124:127], v99, s[82:83]
	global_load_dwordx4 v[128:131], v253, s[82:83]
	global_load_dwordx4 v[132:135], v254, s[82:83] offset:768
	global_load_dwordx4 v[136:139], v255, s[82:83] offset:768
	global_load_dwordx4 v[140:143], v254, s[82:83] offset:832
	global_load_dwordx4 v[144:147], v255, s[82:83] offset:832
	ds_read_b64_tr_b16 v[72:73], v231
	ds_read_b64_tr_b16 v[74:75], v231 offset:512
	ds_read_b64_tr_b16 v[76:77], v231 offset:2048
	ds_read_b64_tr_b16 v[78:79], v231 offset:2560
	ds_read_b64_tr_b16 v[220:221], v231 offset:1024
	ds_read_b64_tr_b16 v[222:223], v231 offset:1536
	ds_read_b64_tr_b16 v[224:225], v231 offset:3072
	ds_read_b64_tr_b16 v[226:227], v231 offset:3584
	s_waitcnt vmcnt(8)
	ds_write_b128 v247, v[156:159]
	ds_write_b128 v247, v[160:163] offset:1024
	ds_write_b128 v247, v[164:167] offset:2048
	ds_write_b128 v247, v[168:171] offset:3072
	ds_read_b128 v[156:159], v248
	ds_read_b128 v[160:163], v249
	ds_read_b128 v[164:167], v250
	ds_read_b128 v[168:171], v251
	ds_write_b128 v112, v[172:175]
	ds_write_b128 v112, v[176:179] offset:1024
	ds_write_b128 v112, v[180:183] offset:2048
	ds_write_b128 v112, v[184:187] offset:3072
	s_waitcnt lgkmcnt(4)
	v_mfma_f32_32x32x16_bf16 v[188:203], v[156:159], v[48:51], v[188:203]
	v_exp_f32_e32 v32, v32
	v_exp_f32_e32 v33, v33
	v_exp_f32_e32 v34, v34
	v_exp_f32_e32 v35, v35
	v_mfma_f32_32x32x16_bf16 v[188:203], v[160:163], v[52:55], v[188:203]
	v_exp_f32_e32 v36, v36
	v_exp_f32_e32 v37, v37
	v_exp_f32_e32 v38, v38
	v_exp_f32_e32 v39, v39
	v_mfma_f32_32x32x16_bf16 v[188:203], v[164:167], v[56:59], v[188:203]
	v_exp_f32_e32 v40, v40
	v_exp_f32_e32 v41, v41
	v_exp_f32_e32 v42, v42
	v_exp_f32_e32 v43, v43
	v_mfma_f32_32x32x16_bf16 v[188:203], v[168:171], v[60:63], v[188:203]
	v_exp_f32_e32 v44, v44
	v_exp_f32_e32 v45, v45
	v_exp_f32_e32 v46, v46
	v_exp_f32_e32 v47, v47
	s_add_i32 s90, s67, 0
	v_lshlrev_b32_e32 v84, 4, v107
	v_add_u32_e32 v84, s90, v84
	v_add_u32_e32 v85, 0, v84
	v_add_u32_e32 v86, 16, v84
	v_add_u32_e32 v87, 32, v84
	v_add_u32_e32 v88, 48, v84
	v_cmp_gt_u32_e64 s[30:31], s98, v85
	v_cmp_gt_u32_e64 s[36:37], s98, v86
	v_cmp_gt_u32_e64 s[78:79], s98, v87
	v_cmp_gt_u32_e64 s[50:51], s98, v88
	v_cndmask_b32_e64 v32, 0, v32, s[30:31]
	v_add_u32_e32 v85, 128, v84
	v_cmp_gt_u32_e64 s[30:31], s98, v85
	v_cndmask_b32_e64 v33, 0, v33, s[36:37]
	v_add_u32_e32 v86, 144, v84
	v_cmp_gt_u32_e64 s[36:37], s98, v86
	v_cndmask_b32_e64 v34, 0, v34, s[78:79]
	v_add_u32_e32 v87, 160, v84
	v_cmp_gt_u32_e64 s[78:79], s98, v87
	v_cndmask_b32_e64 v35, 0, v35, s[50:51]
	v_add_u32_e32 v88, 176, v84
	v_cmp_gt_u32_e64 s[50:51], s98, v88
	v_cndmask_b32_e64 v36, 0, v36, s[30:31]
	v_add_u32_e32 v85, 256, v84
	v_cmp_gt_u32_e64 s[30:31], s98, v85
	v_cndmask_b32_e64 v37, 0, v37, s[36:37]
	v_add_u32_e32 v86, 272, v84
	v_cmp_gt_u32_e64 s[36:37], s98, v86
	v_cndmask_b32_e64 v38, 0, v38, s[78:79]
	v_add_u32_e32 v87, 288, v84
	v_cmp_gt_u32_e64 s[78:79], s98, v87
	v_cndmask_b32_e64 v39, 0, v39, s[50:51]
	v_add_u32_e32 v88, 304, v84
	v_cmp_gt_u32_e64 s[50:51], s98, v88
	v_cndmask_b32_e64 v40, 0, v40, s[30:31]
	v_add_u32_e32 v85, 384, v84
	v_cmp_gt_u32_e64 s[30:31], s98, v85
	v_cndmask_b32_e64 v41, 0, v41, s[36:37]
	v_add_u32_e32 v86, 400, v84
	v_cmp_gt_u32_e64 s[36:37], s98, v86
	v_cndmask_b32_e64 v42, 0, v42, s[78:79]
	v_add_u32_e32 v87, 416, v84
	v_cmp_gt_u32_e64 s[78:79], s98, v87
	v_cndmask_b32_e64 v43, 0, v43, s[50:51]
	v_add_u32_e32 v88, 432, v84
	v_cmp_gt_u32_e64 s[50:51], s98, v88
	v_nop
	v_cndmask_b32_e64 v44, 0, v44, s[30:31]
	v_cndmask_b32_e64 v45, 0, v45, s[36:37]
	v_cndmask_b32_e64 v46, 0, v46, s[78:79]
	v_cndmask_b32_e64 v47, 0, v47, s[50:51]
	v_cvt_pk_bf16_f32 v64, v32, v33
	v_cvt_pk_bf16_f32 v65, v34, v35
	v_cvt_pk_bf16_f32 v66, v36, v37
	v_cvt_pk_bf16_f32 v67, v38, v39
	v_cvt_pk_bf16_f32 v68, v40, v41
	v_cvt_pk_bf16_f32 v69, v42, v43
	v_cvt_pk_bf16_f32 v70, v44, v45
	v_cvt_pk_bf16_f32 v71, v46, v47
	v_pk_add_f32 v[232:233], v[232:233], v[32:33]
	v_pk_add_f32 v[232:233], v[232:233], v[34:35]
	v_pk_add_f32 v[232:233], v[232:233], v[36:37]
	v_pk_add_f32 v[232:233], v[232:233], v[38:39]
	v_pk_add_f32 v[232:233], v[232:233], v[40:41]
	v_pk_add_f32 v[232:233], v[232:233], v[42:43]
	v_pk_add_f32 v[232:233], v[232:233], v[44:45]
	v_pk_add_f32 v[232:233], v[232:233], v[46:47]
	ds_read2_b32 v[32:33], v115 offset0:128 offset1:129
	ds_read2_b32 v[34:35], v115 offset0:130 offset1:131
	ds_read2_b32 v[36:37], v115 offset0:136 offset1:137
	ds_read2_b32 v[38:39], v115 offset0:138 offset1:139
	ds_read2_b32 v[40:41], v115 offset0:144 offset1:145
	ds_read2_b32 v[42:43], v115 offset0:146 offset1:147
	ds_read2_b32 v[44:45], v115 offset0:152 offset1:153
	ds_read2_b32 v[46:47], v115 offset0:154 offset1:155
	v_mfma_f32_32x32x16_bf16 v[0:15], v[64:67], v[72:75], v[0:15]
	v_mfma_f32_32x32x16_bf16 v[16:31], v[64:67], v[76:79], v[16:31]
	v_mfma_f32_32x32x16_bf16 v[0:15], v[68:71], v[220:223], v[0:15]
	v_mfma_f32_32x32x16_bf16 v[16:31], v[68:71], v[224:227], v[16:31]
	ds_read_b64_tr_b16 v[72:73], v231
	ds_read_b64_tr_b16 v[74:75], v231 offset:512
	ds_read_b64_tr_b16 v[76:77], v231 offset:2048
	ds_read_b64_tr_b16 v[78:79], v231 offset:2560
	ds_read_b64_tr_b16 v[220:221], v231 offset:1024
	ds_read_b64_tr_b16 v[222:223], v231 offset:1536
	ds_read_b64_tr_b16 v[224:225], v231 offset:3072
	ds_read_b64_tr_b16 v[226:227], v231 offset:3584
	s_waitcnt vmcnt(0)
	ds_write_b128 v247, v[116:119]
	ds_write_b128 v247, v[120:123] offset:1024
	ds_write_b128 v247, v[124:127] offset:2048
	ds_write_b128 v247, v[128:131] offset:3072
	ds_read_b128 v[116:119], v248
	ds_read_b128 v[120:123], v249
	ds_read_b128 v[124:127], v250
	ds_read_b128 v[128:131], v251
	ds_write_b128 v112, v[132:135]
	ds_write_b128 v112, v[136:139] offset:1024
	ds_write_b128 v112, v[140:143] offset:2048
	ds_write_b128 v112, v[144:147] offset:3072
	s_waitcnt lgkmcnt(4)
	v_mfma_f32_32x32x16_bf16 v[32:47], v[116:119], v[48:51], v[32:47]
	v_exp_f32_e32 v188, v188
	v_exp_f32_e32 v189, v189
	v_exp_f32_e32 v190, v190
	v_exp_f32_e32 v191, v191
	v_mfma_f32_32x32x16_bf16 v[32:47], v[120:123], v[52:55], v[32:47]
	v_exp_f32_e32 v192, v192
	v_exp_f32_e32 v193, v193
	v_exp_f32_e32 v194, v194
	v_exp_f32_e32 v195, v195
	v_mfma_f32_32x32x16_bf16 v[32:47], v[124:127], v[56:59], v[32:47]
	v_exp_f32_e32 v196, v196
	v_exp_f32_e32 v197, v197
	v_exp_f32_e32 v198, v198
	v_exp_f32_e32 v199, v199
	v_mfma_f32_32x32x16_bf16 v[32:47], v[128:131], v[60:63], v[32:47]
	v_exp_f32_e32 v200, v200
	v_exp_f32_e32 v201, v201
	v_exp_f32_e32 v202, v202
	v_exp_f32_e32 v203, v203
	s_add_i32 s90, s67, 512
	v_lshlrev_b32_e32 v84, 4, v107
	v_add_u32_e32 v84, s90, v84
	v_add_u32_e32 v85, 0, v84
	v_add_u32_e32 v86, 16, v84
	v_add_u32_e32 v87, 32, v84
	v_add_u32_e32 v88, 48, v84
	v_cmp_gt_u32_e64 s[30:31], s98, v85
	v_cmp_gt_u32_e64 s[36:37], s98, v86
	v_cmp_gt_u32_e64 s[78:79], s98, v87
	v_cmp_gt_u32_e64 s[50:51], s98, v88
	v_cndmask_b32_e64 v188, 0, v188, s[30:31]
	v_add_u32_e32 v85, 128, v84
	v_cmp_gt_u32_e64 s[30:31], s98, v85
	v_cndmask_b32_e64 v189, 0, v189, s[36:37]
	v_add_u32_e32 v86, 144, v84
	v_cmp_gt_u32_e64 s[36:37], s98, v86
	v_cndmask_b32_e64 v190, 0, v190, s[78:79]
	v_add_u32_e32 v87, 160, v84
	v_cmp_gt_u32_e64 s[78:79], s98, v87
	v_cndmask_b32_e64 v191, 0, v191, s[50:51]
	v_add_u32_e32 v88, 176, v84
	v_cmp_gt_u32_e64 s[50:51], s98, v88
	v_cndmask_b32_e64 v192, 0, v192, s[30:31]
	v_add_u32_e32 v85, 256, v84
	v_cmp_gt_u32_e64 s[30:31], s98, v85
	v_cndmask_b32_e64 v193, 0, v193, s[36:37]
	v_add_u32_e32 v86, 272, v84
	v_cmp_gt_u32_e64 s[36:37], s98, v86
	v_cndmask_b32_e64 v194, 0, v194, s[78:79]
	v_add_u32_e32 v87, 288, v84
	v_cmp_gt_u32_e64 s[78:79], s98, v87
	v_cndmask_b32_e64 v195, 0, v195, s[50:51]
	v_add_u32_e32 v88, 304, v84
	v_cmp_gt_u32_e64 s[50:51], s98, v88
	v_cndmask_b32_e64 v196, 0, v196, s[30:31]
	v_add_u32_e32 v85, 384, v84
	v_cmp_gt_u32_e64 s[30:31], s98, v85
	v_cndmask_b32_e64 v197, 0, v197, s[36:37]
	v_add_u32_e32 v86, 400, v84
	v_cmp_gt_u32_e64 s[36:37], s98, v86
	v_cndmask_b32_e64 v198, 0, v198, s[78:79]
	v_add_u32_e32 v87, 416, v84
	v_cmp_gt_u32_e64 s[78:79], s98, v87
	v_cndmask_b32_e64 v199, 0, v199, s[50:51]
	v_add_u32_e32 v88, 432, v84
	v_cmp_gt_u32_e64 s[50:51], s98, v88
	v_nop
	v_cndmask_b32_e64 v200, 0, v200, s[30:31]
	v_cndmask_b32_e64 v201, 0, v201, s[36:37]
	v_cndmask_b32_e64 v202, 0, v202, s[78:79]
	v_cndmask_b32_e64 v203, 0, v203, s[50:51]
	v_cvt_pk_bf16_f32 v64, v188, v189
	v_cvt_pk_bf16_f32 v65, v190, v191
	v_cvt_pk_bf16_f32 v66, v192, v193
	v_cvt_pk_bf16_f32 v67, v194, v195
	v_cvt_pk_bf16_f32 v68, v196, v197
	v_cvt_pk_bf16_f32 v69, v198, v199
	v_cvt_pk_bf16_f32 v70, v200, v201
	v_cvt_pk_bf16_f32 v71, v202, v203
	v_pk_add_f32 v[232:233], v[232:233], v[188:189]
	v_pk_add_f32 v[232:233], v[232:233], v[190:191]
	v_pk_add_f32 v[232:233], v[232:233], v[192:193]
	v_pk_add_f32 v[232:233], v[232:233], v[194:195]
	v_pk_add_f32 v[232:233], v[232:233], v[196:197]
	v_pk_add_f32 v[232:233], v[232:233], v[198:199]
	v_pk_add_f32 v[232:233], v[232:233], v[200:201]
	v_pk_add_f32 v[232:233], v[232:233], v[202:203]
	v_mfma_f32_32x32x16_bf16 v[0:15], v[64:67], v[72:75], v[0:15]
	v_mfma_f32_32x32x16_bf16 v[16:31], v[64:67], v[76:79], v[16:31]
	v_mfma_f32_32x32x16_bf16 v[0:15], v[68:71], v[220:223], v[0:15]
	v_mfma_f32_32x32x16_bf16 v[16:31], v[68:71], v[224:227], v[16:31]
	ds_read_b64_tr_b16 v[72:73], v231
	ds_read_b64_tr_b16 v[74:75], v231 offset:512
	ds_read_b64_tr_b16 v[76:77], v231 offset:2048
	ds_read_b64_tr_b16 v[78:79], v231 offset:2560
	ds_read_b64_tr_b16 v[220:221], v231 offset:1024
	ds_read_b64_tr_b16 v[222:223], v231 offset:1536
	ds_read_b64_tr_b16 v[224:225], v231 offset:3072
	ds_read_b64_tr_b16 v[226:227], v231 offset:3584
	s_waitcnt lgkmcnt(0)
; __device__ __forceinline__ int crow(int r, int hi) { return (r & 3) + 8 * (r >> 2) + 4 * hi; }
; __device__ __forceinline__ void dil_unit(LAS unsigned char* lds, bf16_t* proj, int seq, int hd, int T0, int rho) {
;     ...
;     l += __shfl_xor(l, 32);
; #pragma unroll
;     for (int rr = 0; rr < 16; ++rr) {
;         const int j = crow(rr, hi);
	v_exp_f32_e32 v32, v32
	v_exp_f32_e32 v33, v33
	v_exp_f32_e32 v34, v34
	v_exp_f32_e32 v35, v35
	v_exp_f32_e32 v36, v36
	v_exp_f32_e32 v37, v37
	v_exp_f32_e32 v38, v38
	v_exp_f32_e32 v39, v39
	v_exp_f32_e32 v40, v40
	v_exp_f32_e32 v41, v41
	v_exp_f32_e32 v42, v42
	v_exp_f32_e32 v43, v43
	v_exp_f32_e32 v44, v44
	v_exp_f32_e32 v45, v45
	v_exp_f32_e32 v46, v46
	v_exp_f32_e32 v47, v47
	s_add_i32 s90, s67, 1024
	v_lshlrev_b32_e32 v84, 4, v107
	v_add_u32_e32 v84, s90, v84
	v_add_u32_e32 v85, 0, v84
	v_add_u32_e32 v86, 16, v84
	v_add_u32_e32 v87, 32, v84
	v_add_u32_e32 v88, 48, v84
	v_cmp_gt_u32_e64 s[30:31], s98, v85
	v_cmp_gt_u32_e64 s[36:37], s98, v86
	v_cmp_gt_u32_e64 s[78:79], s98, v87
	v_cmp_gt_u32_e64 s[50:51], s98, v88
	v_cndmask_b32_e64 v32, 0, v32, s[30:31]
	v_add_u32_e32 v85, 128, v84
	v_cmp_gt_u32_e64 s[30:31], s98, v85
	v_cndmask_b32_e64 v33, 0, v33, s[36:37]
	v_add_u32_e32 v86, 144, v84
	v_cmp_gt_u32_e64 s[36:37], s98, v86
	v_cndmask_b32_e64 v34, 0, v34, s[78:79]
	v_add_u32_e32 v87, 160, v84
	v_cmp_gt_u32_e64 s[78:79], s98, v87
	v_cndmask_b32_e64 v35, 0, v35, s[50:51]
	v_add_u32_e32 v88, 176, v84
	v_cmp_gt_u32_e64 s[50:51], s98, v88
	v_cndmask_b32_e64 v36, 0, v36, s[30:31]
	v_add_u32_e32 v85, 256, v84
	v_cmp_gt_u32_e64 s[30:31], s98, v85
	v_cndmask_b32_e64 v37, 0, v37, s[36:37]
	v_add_u32_e32 v86, 272, v84
	v_cmp_gt_u32_e64 s[36:37], s98, v86
	v_cndmask_b32_e64 v38, 0, v38, s[78:79]
	v_add_u32_e32 v87, 288, v84
	v_cmp_gt_u32_e64 s[78:79], s98, v87
	v_cndmask_b32_e64 v39, 0, v39, s[50:51]
	v_add_u32_e32 v88, 304, v84
	v_cmp_gt_u32_e64 s[50:51], s98, v88
	v_cndmask_b32_e64 v40, 0, v40, s[30:31]
	v_add_u32_e32 v85, 384, v84
	v_cmp_gt_u32_e64 s[30:31], s98, v85
	v_cndmask_b32_e64 v41, 0, v41, s[36:37]
	v_add_u32_e32 v86, 400, v84
	v_cmp_gt_u32_e64 s[36:37], s98, v86
	v_cndmask_b32_e64 v42, 0, v42, s[78:79]
	v_add_u32_e32 v87, 416, v84
	v_cmp_gt_u32_e64 s[78:79], s98, v87
	v_cndmask_b32_e64 v43, 0, v43, s[50:51]
	v_add_u32_e32 v88, 432, v84
	v_cmp_gt_u32_e64 s[50:51], s98, v88
	v_nop
	v_cndmask_b32_e64 v44, 0, v44, s[30:31]
	v_cndmask_b32_e64 v45, 0, v45, s[36:37]
	v_cndmask_b32_e64 v46, 0, v46, s[78:79]
	v_cndmask_b32_e64 v47, 0, v47, s[50:51]
	v_cvt_pk_bf16_f32 v64, v32, v33
	v_cvt_pk_bf16_f32 v65, v34, v35
	v_cvt_pk_bf16_f32 v66, v36, v37
	v_cvt_pk_bf16_f32 v67, v38, v39
	v_cvt_pk_bf16_f32 v68, v40, v41
	v_cvt_pk_bf16_f32 v69, v42, v43
	v_cvt_pk_bf16_f32 v70, v44, v45
	v_cvt_pk_bf16_f32 v71, v46, v47
	v_pk_add_f32 v[232:233], v[232:233], v[32:33]
	v_pk_add_f32 v[232:233], v[232:233], v[34:35]
	v_pk_add_f32 v[232:233], v[232:233], v[36:37]
	v_pk_add_f32 v[232:233], v[232:233], v[38:39]
	v_pk_add_f32 v[232:233], v[232:233], v[40:41]
	v_pk_add_f32 v[232:233], v[232:233], v[42:43]
	v_pk_add_f32 v[232:233], v[232:233], v[44:45]
	v_pk_add_f32 v[232:233], v[232:233], v[46:47]
	v_mfma_f32_32x32x16_bf16 v[0:15], v[64:67], v[72:75], v[0:15]
	v_mfma_f32_32x32x16_bf16 v[16:31], v[64:67], v[76:79], v[16:31]
	v_mfma_f32_32x32x16_bf16 v[0:15], v[68:71], v[220:223], v[0:15]
	v_mfma_f32_32x32x16_bf16 v[16:31], v[68:71], v[224:227], v[16:31]
	v_add_f32_e32 v113, v232, v233
	v_or_b32_e32 v114, 1, v107
	v_or_b32_e32 v97, 2, v107
	v_or_b32_e32 v96, 3, v107
	v_or_b32_e32 v95, 8, v107
	v_or_b32_e32 v94, 9, v107
	v_or_b32_e32 v93, 10, v107
	v_or_b32_e32 v92, 11, v107
	v_or_b32_e32 v91, 16, v107
	v_or_b32_e32 v90, 17, v107
	v_or_b32_e32 v89, 18, v107
	v_or_b32_e32 v88, 19, v107
	v_or_b32_e32 v87, 24, v107
	v_or_b32_e32 v86, 25, v107
	v_or_b32_e32 v85, 26, v107
	v_or_b32_e32 v84, 27, v107
	s_nop 11
	s_branch .LBB0_1265
